# final output stores written through (sc1 instead of nt): nothing of d_out left dirty in L2 for the end-of-kernel write-back
# baseline (speedup 1.0000x reference)
; #define LAS __attribute__((address_space(3)))
; #define TR4(p_) __builtin_amdgcn_ds_read_tr4_b64_v2i32((LAS v2i*)(p_))
; __device__ __forceinline__ void peer_v_tokens(int j, const LAS unsigned short* EL, const LAS unsigned char* AL  , const LAS float* ASC  , const LAS int* SAL  , ...
;     ...
;     const int BUF[3] = {vslot(3 * wave), vslot(3 * wave + 1), vslot(3 * wave + 2)};
;     const int g = lane >> 3, j8 = lane & 7, s16 = lane & 15, grp = lane >> 4;
;     *(LAS unsigned long long*)(ldsb + BUF[0] + 8 * s16) = 0xFEDCBA9876543210ull;
;     CFENCE();
;     const v2i cal = TR4(ldsb + BUF[0] + 8 * s16);
;     const int pc = cal.x & 15;
;     asm volatile("s_waitcnt lgkmcnt(0)" ::: "memory");
;     const unsigned cx0 = 16u * (unsigned)(j8 ^ (g >> 1)), cx1 = 16u * (unsigned)(j8 ^ (4 + (g >> 1)));
;     const int fr = (4 * (s16 >> 3) + ((s16 & 7) >> 1)) & 7;
;     int roff[4];
; #pragma unroll
;     for (int r = 0; r < 4; ++r) roff[r] = 128 * s16 + 16 * ((((grp >> 1) + 2 * r)) ^ fr) + 8 * (grp & 1);
;     ...
; #pragma unroll 1
;     for (int it = 0; it < 8; ++it) {
;         const int tl = it * 8 + wave, t = j * 64 + tl;
;         unsigned E[8];
;         { const LAS v4u* ep = (const LAS v4u*)(EL + tl * 128 + 16 * g); const v4u e0 = ep[0], e1 = ep[1];
;           E[0] = e0.x; E[1] = e0.y; E[2] = e0.z; E[3] = e0.w; E[4] = e1.x; E[5] = e1.y; E[6] = e1.z; E[7] = e1.w; }
;         uint2 hv[4]; float4 gv[4];
;         { unsigned ho = (unsigned)t * (D / 4) + (unsigned)lane; asm volatile("" : "+v"(ho)); const uint2* hp = (const uint2*)HB + ho; const float4* gp = (const float4*)fng + lane;
; #pragma unroll
;           for (int jq = 0; jq < 4; ++jq) { hv[jq] = hp[64 * jq]; gv[jq] = gp[64 * jq]; } }
;         VDMA(0, 0); VDMA(1, 1);
; #pragma unroll
;         for (int m = 0; m < 2; ++m) {
;             const int idx = lane + 64 * m, tau = idx >> 4, sr = idx & 15, k = 16 * (sr & 7) + 2 * tau + (sr >> 3);
;             const int aq = (int)*(const LAS signed char*)(AL + tl * 128 + k); const int tq = aq + 8;
;             const unsigned lo = (((unsigned)tq & 15u) ^ 8u) * 0x11111111u, hi = ((unsigned)(tq >> 4) & 15u) * 0x11111111u;
;             typedef unsigned u2v __attribute__((ext_vector_type(2)));
;             u2v l2; l2.x = lo; l2.y = lo; u2v h2; h2.x = hi; h2.y = hi;
;             *(LAS u2v*)(ATL + 8 * idx) = l2; *(LAS u2v*)(ATL + 1024 + 8 * idx) = h2;
;         }
.LBB0_691:
	s_or_b64 exec, exec, s[10:11]
	v_mov_b32_e32 v18, v1
	s_waitcnt lgkmcnt(0)
	s_barrier
	v_readlane_b32 s70, v235, 50
	v_and_b32_e32 v19, 15, v18
	v_lshlrev_b32_e32 v58, 3, v19
	v_add_u32_e32 v20, s60, v58
	ds_write_b64 v20, v[84:85]
	v_lshrrev_b32_e32 v23, 1, v18
	v_ashrrev_i32_e32 v24, 5, v18
	v_and_b32_e32 v25, 8, v23
	ds_read_b64_tr_b4 v[20:21], v20
	v_lshl_or_b32 v19, v19, 7, v25
	v_bitop3_b32 v25, v23, v24, 7 bitop3:0x6c
	v_lshl_add_u32 v59, v25, 4, v19
	v_add_u32_e32 v25, 2, v24
	v_bitop3_b32 v25, v25, v23, 7 bitop3:0x78
	v_lshl_add_u32 v60, v25, 4, v19
	v_add_u32_e32 v25, 4, v24
	v_add_u32_e32 v24, 6, v24
	s_waitcnt lgkmcnt(0)
	v_ashrrev_i32_e32 v21, 4, v18
	v_bitop3_b32 v25, v25, v23, 7 bitop3:0x78
	v_bitop3_b32 v23, v24, v23, 7 bitop3:0x78
	v_bitop3_b32 v22, v18, v21, 7 bitop3:0x6c
	v_add_u32_e32 v21, 4, v21
	v_lshl_add_u32 v61, v25, 4, v19
	v_lshl_add_u32 v62, v23, 4, v19
	v_and_b32_e32 v19, 15, v20
	v_bitop3_b32 v21, v21, v18, 7 bitop3:0x78
	v_lshlrev_b32_e32 v63, 4, v22
	v_lshlrev_b32_e32 v22, 1, v19
	v_ashrrev_i32_e32 v19, 31, v18
	v_lshlrev_b32_e32 v64, 4, v21
	v_lshlrev_b64 v[20:21], 4, v[18:19]
	v_and_b32_e32 v25, 0x7ffffff0, v18
	v_lshl_add_u64 v[34:35], s[86:87], 0, v[20:21]
	v_lshlrev_b32_e32 v19, 4, v18
	v_lshlrev_b32_e32 v25, 1, v25
	v_lshl_add_u64 v[36:37], s[88:89], 0, v[20:21]
	v_add_u32_e32 v21, 64, v18
	s_waitcnt lgkmcnt(0)
	v_and_b32_e32 v19, 0x70, v19
	v_add3_u32 v65, s58, v22, v25
	v_ashrrev_i32_e32 v20, 3, v18
	v_ashrrev_i32_e32 v22, 3, v21
	v_lshrrev_b32_e32 v23, 3, v18
	v_bfe_u32 v24, v18, 3, 1
	v_and_b32_e32 v20, -2, v20
	v_and_b32_e32 v22, -2, v22
	v_lshlrev_b32_e32 v21, 3, v21
	v_add_u32_e32 v19, s72, v19
	v_lshlrev_b32_e32 v66, 3, v18
	v_add_u32_e32 v67, 0x200000, v63
	v_add_u32_e32 v68, 0x200000, v64
	v_add_u32_e32 v69, 0x400000, v63
	v_add_u32_e32 v70, 0x400000, v64
	v_add_u32_e32 v71, 0x600000, v63
	v_add_u32_e32 v72, 0x600000, v64
	v_add3_u32 v73, v19, v22, v24
	v_add3_u32 v74, v19, v20, v24
	v_lshl_add_u32 v75, v23, 5, s65
	v_add_u32_e32 v76, s73, v18
	s_mov_b32 s12, 0
	v_add_u32_e32 v77, s59, v21
	s_mov_b32 s13, s67
	v_readlane_b32 s71, v235, 51
	s_mov_b32 s76, s60
	s_add_i32 s77, s60, 0x800
	s_mov_b32 s78, s61
	s_add_i32 s79, s61, 0x800
	s_mov_b32 s98, s62
	s_add_i32 s99, s62, 0x800
	v_add_u32_e32 v159, s59, v66
	v_add_u32_e32 v160, s59, v58
	v_add_u32_e32 v154, s58, v66
	v_add_u32_e32 v227, 0x12000, v75
	v_lshlrev_b32_e32 v138, 1, v66
	v_add_u32_e32 v155, 0x11200, v138
	v_add_u32_e32 v156, 0x27400, v138
	global_load_dwordx4 v[210:213], v[34:35], off
	global_load_dwordx4 v[214:217], v[34:35], off offset:1024
	global_load_dwordx4 v[218:221], v[34:35], off offset:2048
	global_load_dwordx4 v[222:225], v[34:35], off offset:3072
	ds_read_b128 v[18:21], v227
	ds_read_b128 v[22:25], v227 offset:16
	v_mov_b32_e32 v138, v74
	ds_read_u8 v139, v138
	v_mov_b32_e32 v141, v73
	ds_read_u8 v140, v141
	v_mov_b32_e32 v150, v63
	v_mov_b32_e32 v151, v64
	s_waitcnt lgkmcnt(0)
	v_and_b32_e32 v78, 0xffff, v18
	v_lshrrev_b32_e32 v79, 16, v18
	v_lshl_add_u32 v78, v78, 7, v150
	v_lshl_add_u32 v79, v79, 7, v151
	s_mov_b32 m0, s76
	s_add_i32 s43, s76, 0x400
	global_load_lds_dwordx4 v78, s[50:51]
	s_mov_b32 m0, s43
	s_nop 0
	global_load_lds_dwordx4 v79, s[50:51]
	v_and_b32_e32 v78, 0xffff, v19
	v_lshrrev_b32_e32 v79, 16, v19
	v_lshl_add_u32 v78, v78, 7, v150
	v_lshl_add_u32 v79, v79, 7, v151
	s_mov_b32 m0, s77
	s_add_i32 s43, s77, 0x400
	global_load_lds_dwordx4 v78, s[50:51]
	s_mov_b32 m0, s43
	s_nop 0
	global_load_lds_dwordx4 v79, s[50:51]
	v_and_b32_e32 v78, 0xffff, v20
	v_lshrrev_b32_e32 v79, 16, v20
	v_lshl_add_u32 v78, v78, 7, v150
	v_lshl_add_u32 v79, v79, 7, v151
	s_mov_b32 m0, s78
	s_add_i32 s43, s78, 0x400
	global_load_lds_dwordx4 v78, s[50:51]
	s_mov_b32 m0, s43
	s_nop 0
	global_load_lds_dwordx4 v79, s[50:51]
	v_and_b32_e32 v78, 0xffff, v21
	v_lshrrev_b32_e32 v79, 16, v21
	v_lshl_add_u32 v78, v78, 7, v150
	v_lshl_add_u32 v79, v79, 7, v151
	s_mov_b32 m0, s79
	s_add_i32 s43, s79, 0x400
	global_load_lds_dwordx4 v78, s[50:51]
	s_mov_b32 m0, s43
	s_nop 0
	global_load_lds_dwordx4 v79, s[50:51]
	v_and_b32_e32 v78, 0xffff, v22
	v_lshrrev_b32_e32 v79, 16, v22
	v_lshl_add_u32 v78, v78, 7, v150
	v_lshl_add_u32 v79, v79, 7, v151
	s_mov_b32 m0, s98
	s_add_i32 s43, s98, 0x400
	global_load_lds_dwordx4 v78, s[50:51]
	s_mov_b32 m0, s43
	s_nop 0
	global_load_lds_dwordx4 v79, s[50:51]
	v_add_u32_e32 v143, 8, v139
	v_and_b32_e32 v142, 15, v143
	v_xor_b32_e32 v142, 8, v142
	v_bfe_u32 v144, v143, 4, 4
	v_mul_lo_u32 v142, v142, s92
	v_mul_lo_u32 v144, v144, s92
	v_mov_b32_e32 v143, v142
	v_mov_b32_e32 v145, v144
	ds_write2st64_b64 v159, v[142:143], v[144:145] offset1:2
	s_waitcnt vmcnt(10)
	ds_write_b128 v155, v[210:213]
	ds_write_b128 v155, v[214:217] offset:1024
	ds_write_b128 v156, v[218:221]
	ds_write_b128 v156, v[222:225] offset:1024
	s_waitcnt vmcnt(8)
	v_add_u32_e32 v54, s76, v59
	v_add_u32_e32 v55, s76, v60
	v_add_u32_e32 v56, s76, v61
	v_add_u32_e32 v57, s76, v62
	ds_read_b64_tr_b4 v[46:47], v160
	ds_read_b64_tr_b4 v[48:49], v160 offset:1024
	ds_read_b64_tr_b4 v[122:123], v54
	ds_read_b64_tr_b4 v[124:125], v55
	ds_read_b64_tr_b4 v[126:127], v56
	ds_read_b64_tr_b4 v[128:129], v57
	v_add_u32_e32 v147, 8, v140
	v_and_b32_e32 v146, 15, v147
	v_xor_b32_e32 v146, 8, v146
	v_bfe_u32 v148, v147, 4, 4
	v_mul_lo_u32 v146, v146, s92
	v_mul_lo_u32 v148, v148, s92
	v_mov_b32_e32 v147, v146
	v_mov_b32_e32 v149, v148
	ds_write2st64_b64 v77, v[146:147], v[148:149] offset1:2
	v_add_u32_e32 v138, 0x400, v74
	ds_read_u8 v139, v138
	v_add_u32_e32 v141, 0x400, v73
	ds_read_u8 v140, v141
	s_mov_b32 s43, s67
	v_mov_b32_e32 v138, s43
	ds_read2st64_b32 v[228:229], v138 offset1:1
	ds_read_b128 v[26:29], v227 offset:2048
	ds_read_b128 v[30:33], v227 offset:2064
	v_mov_b32_e32 v38, 0
	v_mov_b32_e32 v39, 0
	v_mov_b32_e32 v40, 0
	v_mov_b32_e32 v41, 0
	v_mov_b32_e32 v42, 0
	v_mov_b32_e32 v43, 0
	v_mov_b32_e32 v44, 0
	v_mov_b32_e32 v45, 0
	v_and_b32_e32 v78, 0xffff, v23
	v_lshrrev_b32_e32 v79, 16, v23
	v_lshl_add_u32 v78, v78, 7, v150
	v_lshl_add_u32 v79, v79, 7, v151
	s_mov_b32 m0, s99
	s_add_i32 s43, s99, 0x400
	global_load_lds_dwordx4 v78, s[50:51]
	s_mov_b32 m0, s43
	s_nop 0
	global_load_lds_dwordx4 v79, s[50:51]
	s_waitcnt vmcnt(8)
; __device__ __forceinline__ bf16 f2bf(float f) { return (bf16)f2bfu(f); }
; #define TR4(p_) __builtin_amdgcn_ds_read_tr4_b64_v2i32((LAS v2i*)(p_))
; #define VDMA(st_, k_) do { _Pragma("unroll") for (int i_ = 0; i_ < 4; ++i_) { \
;         const unsigned off_ = (unsigned)((st_) >> 2) * (16384u * 128u) + (PE_ID(E, 4 * ((st_) & 3) + i_) << 7) + ((i_ & 1) ? cx1 : cx0); \
;         __builtin_amdgcn_global_load_lds((const unsigned*)(V4 + off_), (LAS unsigned*)(ldsb + BUF[k_] + 1024 * i_), 16, 0, 0); } } while (0)
; __device__ __forceinline__ void peer_v_tokens(int j, const LAS unsigned short* EL, const LAS unsigned char* AL  , const LAS float* ASC  , const LAS int* SAL  , ...
;     ...
;         for (int st = 0; st < 16; ++st) {
;             const int p = st >> 2, q = st & 3;
;             if (st < 14) VDMA(st + 2, (st + 2) % 3);
;             if (st < 14) asm volatile("s_waitcnt vmcnt(8)" ::: "memory");
;             else if (st == 14) asm volatile("s_waitcnt vmcnt(4)" ::: "memory");
;             else asm volatile("s_waitcnt vmcnt(0)" ::: "memory");
;             if (q == 0) {
; #pragma unroll
;                 for (int r = 0; r < 4; ++r) { accH[r] = 0; accL[r] = 0; } }
; #pragma unroll
;             for (int tp = 0; tp < 2; ++tp) {
;                 const v2i ao = TR4(ATL + (2 * q + tp) * 128 + 8 * s16), ah = TR4(ATL + 1024 + (2 * q + tp) * 128 + 8 * s16);
; #pragma unroll
;                 for (int r = 0; r < 4; ++r) {
;                     const v2i d = TR4(ldsb + BUF[st % 3] + 2048 * tp + roff[r]);
;                     accH[r] = __builtin_amdgcn_sdot8(d.x, ah.x, accH[r], false); accH[r] = __builtin_amdgcn_sdot8(d.y, ah.y, accH[r], false);
;                     accL[r] = __builtin_amdgcn_sdot8(d.x, ao.x, accL[r], false); accL[r] = __builtin_amdgcn_sdot8(d.y, ao.y, accL[r], false);
;                 }
;             }
;             asm volatile("s_waitcnt lgkmcnt(0)" ::: "memory");
;             if (q == 3) {
; #pragma unroll
;                 for (int r = 0; r < 4; ++r) STASH[256 * p + 16 * (grp + 4 * r) + pc] = f2bf(asc * (float)(2 * ((accH[r] << 4) + accL[r]) + sa));
;             }
;         }
	v_add_u32_e32 v54, s77, v59
	v_add_u32_e32 v55, s77, v60
	v_add_u32_e32 v56, s77, v61
	v_add_u32_e32 v57, s77, v62
	ds_read_b64_tr_b4 v[50:51], v160 offset:128
	ds_read_b64_tr_b4 v[52:53], v160 offset:1152
	ds_read_b64_tr_b4 v[130:131], v54
	ds_read_b64_tr_b4 v[132:133], v55
	ds_read_b64_tr_b4 v[134:135], v56
	ds_read_b64_tr_b4 v[136:137], v57
	s_waitcnt lgkmcnt(12)
	v_dot8c_i32_i4_e32 v38, v122, v48
	v_dot8c_i32_i4_e32 v39, v122, v46
	v_dot8c_i32_i4_e32 v40, v124, v48
	v_dot8c_i32_i4_e32 v41, v124, v46
	v_dot8c_i32_i4_e32 v42, v126, v48
	v_dot8c_i32_i4_e32 v43, v126, v46
	v_dot8c_i32_i4_e32 v44, v128, v48
	v_dot8c_i32_i4_e32 v45, v128, v46
	v_dot8c_i32_i4_e32 v38, v123, v49
	v_dot8c_i32_i4_e32 v39, v123, v47
	v_dot8c_i32_i4_e32 v40, v125, v49
	v_dot8c_i32_i4_e32 v41, v125, v47
	v_dot8c_i32_i4_e32 v42, v127, v49
	v_dot8c_i32_i4_e32 v43, v127, v47
	v_dot8c_i32_i4_e32 v44, v129, v49
	v_dot8c_i32_i4_e32 v45, v129, v47
	v_and_b32_e32 v78, 0xffff, v24
	v_lshrrev_b32_e32 v79, 16, v24
	v_lshl_add_u32 v78, v78, 7, v150
	v_lshl_add_u32 v79, v79, 7, v151
	s_mov_b32 m0, s76
	s_add_i32 s43, s76, 0x400
	global_load_lds_dwordx4 v78, s[50:51]
	s_mov_b32 m0, s43
	s_nop 0
	global_load_lds_dwordx4 v79, s[50:51]
	s_waitcnt vmcnt(8)
	v_add_u32_e32 v54, s78, v59
	v_add_u32_e32 v55, s78, v60
	v_add_u32_e32 v56, s78, v61
	v_add_u32_e32 v57, s78, v62
	ds_read_b64_tr_b4 v[46:47], v160 offset:256
	ds_read_b64_tr_b4 v[48:49], v160 offset:1280
	ds_read_b64_tr_b4 v[122:123], v54
	ds_read_b64_tr_b4 v[124:125], v55
	ds_read_b64_tr_b4 v[126:127], v56
	ds_read_b64_tr_b4 v[128:129], v57
	s_waitcnt lgkmcnt(6)
	v_dot8c_i32_i4_e32 v38, v130, v52
	v_dot8c_i32_i4_e32 v39, v130, v50
	v_dot8c_i32_i4_e32 v40, v132, v52
	v_dot8c_i32_i4_e32 v41, v132, v50
	v_dot8c_i32_i4_e32 v42, v134, v52
	v_dot8c_i32_i4_e32 v43, v134, v50
	v_dot8c_i32_i4_e32 v44, v136, v52
	v_dot8c_i32_i4_e32 v45, v136, v50
	v_dot8c_i32_i4_e32 v38, v131, v53
	v_dot8c_i32_i4_e32 v39, v131, v51
	v_dot8c_i32_i4_e32 v40, v133, v53
	v_dot8c_i32_i4_e32 v41, v133, v51
	v_dot8c_i32_i4_e32 v42, v135, v53
	v_dot8c_i32_i4_e32 v43, v135, v51
	v_dot8c_i32_i4_e32 v44, v137, v53
	v_dot8c_i32_i4_e32 v45, v137, v51
	v_and_b32_e32 v78, 0xffff, v25
	v_lshrrev_b32_e32 v79, 16, v25
	v_lshl_add_u32 v78, v78, 7, v150
	v_lshl_add_u32 v79, v79, 7, v151
	s_mov_b32 m0, s77
	s_add_i32 s43, s77, 0x400
	global_load_lds_dwordx4 v78, s[50:51]
	s_mov_b32 m0, s43
	s_nop 0
	global_load_lds_dwordx4 v79, s[50:51]
	s_waitcnt vmcnt(8)
	v_add_u32_e32 v54, s79, v59
	v_add_u32_e32 v55, s79, v60
	v_add_u32_e32 v56, s79, v61
	v_add_u32_e32 v57, s79, v62
	ds_read_b64_tr_b4 v[50:51], v160 offset:384
	ds_read_b64_tr_b4 v[52:53], v160 offset:1408
	ds_read_b64_tr_b4 v[130:131], v54
	ds_read_b64_tr_b4 v[132:133], v55
	ds_read_b64_tr_b4 v[134:135], v56
	ds_read_b64_tr_b4 v[136:137], v57
	s_waitcnt lgkmcnt(6)
	v_dot8c_i32_i4_e32 v38, v122, v48
	v_dot8c_i32_i4_e32 v39, v122, v46
	v_dot8c_i32_i4_e32 v40, v124, v48
	v_dot8c_i32_i4_e32 v41, v124, v46
	v_dot8c_i32_i4_e32 v42, v126, v48
	v_dot8c_i32_i4_e32 v43, v126, v46
	v_dot8c_i32_i4_e32 v44, v128, v48
	v_dot8c_i32_i4_e32 v45, v128, v46
	v_dot8c_i32_i4_e32 v38, v123, v49
	v_dot8c_i32_i4_e32 v39, v123, v47
	v_dot8c_i32_i4_e32 v40, v125, v49
	v_dot8c_i32_i4_e32 v41, v125, v47
	v_dot8c_i32_i4_e32 v42, v127, v49
	v_dot8c_i32_i4_e32 v43, v127, v47
	v_dot8c_i32_i4_e32 v44, v129, v49
	v_dot8c_i32_i4_e32 v45, v129, v47
	s_waitcnt lgkmcnt(15)
	v_and_b32_e32 v78, 0xffff, v26
	v_lshrrev_b32_e32 v79, 16, v26
	v_lshl_add_u32 v78, v78, 7, v150
	v_lshl_add_u32 v79, v79, 7, v151
	s_mov_b32 m0, s78
	s_add_i32 s43, s78, 0x400
	global_load_lds_dwordx4 v78, s[50:51]
	s_mov_b32 m0, s43
	s_nop 0
	global_load_lds_dwordx4 v79, s[50:51]
	s_waitcnt vmcnt(8)
	v_add_u32_e32 v54, s98, v59
	v_add_u32_e32 v55, s98, v60
	v_add_u32_e32 v56, s98, v61
	v_add_u32_e32 v57, s98, v62
	ds_read_b64_tr_b4 v[46:47], v160 offset:512
	ds_read_b64_tr_b4 v[48:49], v160 offset:1536
	ds_read_b64_tr_b4 v[122:123], v54
	ds_read_b64_tr_b4 v[124:125], v55
	ds_read_b64_tr_b4 v[126:127], v56
	ds_read_b64_tr_b4 v[128:129], v57
	s_waitcnt lgkmcnt(6)
	v_dot8c_i32_i4_e32 v38, v130, v52
	v_dot8c_i32_i4_e32 v39, v130, v50
	v_dot8c_i32_i4_e32 v40, v132, v52
	v_dot8c_i32_i4_e32 v41, v132, v50
	v_dot8c_i32_i4_e32 v42, v134, v52
	v_dot8c_i32_i4_e32 v43, v134, v50
	v_dot8c_i32_i4_e32 v44, v136, v52
	v_dot8c_i32_i4_e32 v45, v136, v50
	v_dot8c_i32_i4_e32 v38, v131, v53
	v_dot8c_i32_i4_e32 v39, v131, v51
	v_dot8c_i32_i4_e32 v40, v133, v53
	v_dot8c_i32_i4_e32 v41, v133, v51
	v_dot8c_i32_i4_e32 v42, v135, v53
	v_dot8c_i32_i4_e32 v43, v135, v51
	v_dot8c_i32_i4_e32 v44, v137, v53
	v_dot8c_i32_i4_e32 v45, v137, v51
	v_and_b32_e32 v78, 0xffff, v27
	v_lshrrev_b32_e32 v79, 16, v27
	v_lshl_add_u32 v78, v78, 7, v150
	v_lshl_add_u32 v79, v79, 7, v151
	s_mov_b32 m0, s79
	s_add_i32 s43, s79, 0x400
	global_load_lds_dwordx4 v78, s[50:51]
	s_mov_b32 m0, s43
	s_nop 0
	global_load_lds_dwordx4 v79, s[50:51]
	s_waitcnt vmcnt(8)
	v_add_u32_e32 v54, s99, v59
	v_add_u32_e32 v55, s99, v60
	v_add_u32_e32 v56, s99, v61
	v_add_u32_e32 v57, s99, v62
	ds_read_b64_tr_b4 v[50:51], v160 offset:640
	ds_read_b64_tr_b4 v[52:53], v160 offset:1664
	ds_read_b64_tr_b4 v[130:131], v54
	ds_read_b64_tr_b4 v[132:133], v55
	ds_read_b64_tr_b4 v[134:135], v56
	ds_read_b64_tr_b4 v[136:137], v57
	s_waitcnt lgkmcnt(6)
	v_dot8c_i32_i4_e32 v38, v122, v48
	v_dot8c_i32_i4_e32 v39, v122, v46
	v_dot8c_i32_i4_e32 v40, v124, v48
	v_dot8c_i32_i4_e32 v41, v124, v46
	v_dot8c_i32_i4_e32 v42, v126, v48
	v_dot8c_i32_i4_e32 v43, v126, v46
	v_dot8c_i32_i4_e32 v44, v128, v48
	v_dot8c_i32_i4_e32 v45, v128, v46
	v_dot8c_i32_i4_e32 v38, v123, v49
	v_dot8c_i32_i4_e32 v39, v123, v47
	v_dot8c_i32_i4_e32 v40, v125, v49
	v_dot8c_i32_i4_e32 v41, v125, v47
	v_dot8c_i32_i4_e32 v42, v127, v49
	v_dot8c_i32_i4_e32 v43, v127, v47
	v_dot8c_i32_i4_e32 v44, v129, v49
	v_dot8c_i32_i4_e32 v45, v129, v47
	s_waitcnt lgkmcnt(15)
; __device__ __forceinline__ void peer_v_tokens(int j, const LAS unsigned short* EL, const LAS unsigned char* AL  , const LAS float* ASC  , const LAS int* SAL  , ...
;     ...
;         { const LAS v4u* ep = (const LAS v4u*)(EL + tl * 128 + 16 * g); const v4u e0 = ep[0], e1 = ep[1];
;           E[0] = e0.x; E[1] = e0.y; E[2] = e0.z; E[3] = e0.w; E[4] = e1.x; E[5] = e1.y; E[6] = e1.z; E[7] = e1.w; }
;         uint2 hv[4]; float4 gv[4];
;         { unsigned ho = (unsigned)t * (D / 4) + (unsigned)lane; asm volatile("" : "+v"(ho)); const uint2* hp = (const uint2*)HB + ho; const float4* gp = (const float4*)fng + lane;
; #pragma unroll
;           for (int jq = 0; jq < 4; ++jq) { hv[jq] = hp[64 * jq]; gv[jq] = gp[64 * jq]; } }
;         VDMA(0, 0); VDMA(1, 1);
; #pragma unroll
;         for (int m = 0; m < 2; ++m) {
;             const int idx = lane + 64 * m, tau = idx >> 4, sr = idx & 15, k = 16 * (sr & 7) + 2 * tau + (sr >> 3);
;             const int aq = (int)*(const LAS signed char*)(AL + tl * 128 + k); const int tq = aq + 8;
;             const unsigned lo = (((unsigned)tq & 15u) ^ 8u) * 0x11111111u, hi = ((unsigned)(tq >> 4) & 15u) * 0x11111111u;
;             typedef unsigned u2v __attribute__((ext_vector_type(2)));
;             u2v l2; l2.x = lo; l2.y = lo; u2v h2; h2.x = hi; h2.y = hi;
;             *(LAS u2v*)(ATL + 8 * idx) = l2; *(LAS u2v*)(ATL + 1024 + 8 * idx) = h2;
;         }
;         const float asc = ASC[tl]; const int sa = SAL[tl];
;         CFENCE();
;         int accH[4], accL[4];
; #pragma unroll
;         for (int st = 0; st < 16; ++st) {
;             const int p = st >> 2, q = st & 3;
;             if (st < 14) VDMA(st + 2, (st + 2) % 3);
;             if (st < 14) asm volatile("s_waitcnt vmcnt(8)" ::: "memory");
;             else if (st == 14) asm volatile("s_waitcnt vmcnt(4)" ::: "memory");
;             else asm volatile("s_waitcnt vmcnt(0)" ::: "memory");
;             if (q == 0) {
; #pragma unroll
;                 for (int r = 0; r < 4; ++r) { accH[r] = 0; accL[r] = 0; } }
; #pragma unroll
;             for (int tp = 0; tp < 2; ++tp) {
;                 const v2i ao = TR4(ATL + (2 * q + tp) * 128 + 8 * s16), ah = TR4(ATL + 1024 + (2 * q + tp) * 128 + 8 * s16);
; #pragma unroll
;                 for (int r = 0; r < 4; ++r) {
;                     const v2i d = TR4(ldsb + BUF[st % 3] + 2048 * tp + roff[r]);
	v_add_u32_e32 v143, 8, v139
	v_and_b32_e32 v142, 15, v143
	v_xor_b32_e32 v142, 8, v142
	v_bfe_u32 v144, v143, 4, 4
	v_mul_lo_u32 v142, v142, s92
	v_mul_lo_u32 v144, v144, s92
	v_mov_b32_e32 v143, v142
	v_mov_b32_e32 v145, v144
	ds_write2st64_b64 v159, v[142:143], v[144:145] offset1:2
	v_and_b32_e32 v78, 0xffff, v28
	v_lshrrev_b32_e32 v79, 16, v28
	v_lshl_add_u32 v78, v78, 7, v150
	v_lshl_add_u32 v79, v79, 7, v151
	s_mov_b32 m0, s98
	s_add_i32 s43, s98, 0x400
	global_load_lds_dwordx4 v78, s[50:51]
	s_mov_b32 m0, s43
	s_nop 0
	global_load_lds_dwordx4 v79, s[50:51]
	s_waitcnt vmcnt(8)
	v_add_u32_e32 v54, s76, v59
	v_add_u32_e32 v55, s76, v60
	v_add_u32_e32 v56, s76, v61
	v_add_u32_e32 v57, s76, v62
	ds_read_b64_tr_b4 v[46:47], v160 offset:768
	ds_read_b64_tr_b4 v[48:49], v160 offset:1792
	ds_read_b64_tr_b4 v[122:123], v54
	ds_read_b64_tr_b4 v[124:125], v55
	ds_read_b64_tr_b4 v[126:127], v56
	ds_read_b64_tr_b4 v[128:129], v57
	s_waitcnt lgkmcnt(7)
	v_dot8c_i32_i4_e32 v38, v130, v52
	v_dot8c_i32_i4_e32 v39, v130, v50
	v_dot8c_i32_i4_e32 v40, v132, v52
	v_dot8c_i32_i4_e32 v41, v132, v50
	v_dot8c_i32_i4_e32 v42, v134, v52
	v_dot8c_i32_i4_e32 v43, v134, v50
	v_dot8c_i32_i4_e32 v44, v136, v52
	v_dot8c_i32_i4_e32 v45, v136, v50
	v_dot8c_i32_i4_e32 v38, v131, v53
	v_dot8c_i32_i4_e32 v39, v131, v51
	v_dot8c_i32_i4_e32 v40, v133, v53
	v_dot8c_i32_i4_e32 v41, v133, v51
	v_dot8c_i32_i4_e32 v42, v135, v53
	v_dot8c_i32_i4_e32 v43, v135, v51
	v_dot8c_i32_i4_e32 v44, v137, v53
	v_dot8c_i32_i4_e32 v45, v137, v51
	v_and_b32_e32 v78, 0xffff, v29
	v_lshrrev_b32_e32 v79, 16, v29
	v_lshl_add_u32 v78, v78, 7, v150
	v_lshl_add_u32 v79, v79, 7, v151
	s_mov_b32 m0, s99
	s_add_i32 s43, s99, 0x400
	global_load_lds_dwordx4 v78, s[50:51]
	s_mov_b32 m0, s43
	s_nop 0
	global_load_lds_dwordx4 v79, s[50:51]
	s_waitcnt vmcnt(8)
	v_add_u32_e32 v54, s77, v59
	v_add_u32_e32 v55, s77, v60
	v_add_u32_e32 v56, s77, v61
	v_add_u32_e32 v57, s77, v62
	ds_read_b64_tr_b4 v[50:51], v160 offset:896
	ds_read_b64_tr_b4 v[52:53], v160 offset:1920
	ds_read_b64_tr_b4 v[130:131], v54
	ds_read_b64_tr_b4 v[132:133], v55
	ds_read_b64_tr_b4 v[134:135], v56
	ds_read_b64_tr_b4 v[136:137], v57
	s_waitcnt lgkmcnt(6)
	v_dot8c_i32_i4_e32 v38, v122, v48
	v_dot8c_i32_i4_e32 v39, v122, v46
	v_dot8c_i32_i4_e32 v40, v124, v48
	v_dot8c_i32_i4_e32 v41, v124, v46
	v_dot8c_i32_i4_e32 v42, v126, v48
	v_dot8c_i32_i4_e32 v43, v126, v46
	v_dot8c_i32_i4_e32 v44, v128, v48
	v_dot8c_i32_i4_e32 v45, v128, v46
	v_dot8c_i32_i4_e32 v38, v123, v49
	v_dot8c_i32_i4_e32 v39, v123, v47
	v_dot8c_i32_i4_e32 v40, v125, v49
	v_dot8c_i32_i4_e32 v41, v125, v47
	v_dot8c_i32_i4_e32 v42, v127, v49
	v_dot8c_i32_i4_e32 v43, v127, v47
	v_dot8c_i32_i4_e32 v44, v129, v49
	v_dot8c_i32_i4_e32 v45, v129, v47
	v_and_b32_e32 v78, 0xffff, v30
	v_lshrrev_b32_e32 v79, 16, v30
	v_lshl_add_u32 v78, v78, 7, v150
	v_lshl_add_u32 v79, v79, 7, v151
	s_mov_b32 m0, s76
	s_add_i32 s43, s76, 0x400
	global_load_lds_dwordx4 v78, s[50:51]
	s_mov_b32 m0, s43
	s_nop 0
	global_load_lds_dwordx4 v79, s[50:51]
	s_waitcnt vmcnt(8)
	v_add_u32_e32 v54, s78, v59
	v_add_u32_e32 v55, s78, v60
	v_add_u32_e32 v56, s78, v61
	v_add_u32_e32 v57, s78, v62
	ds_read_b64_tr_b4 v[46:47], v160
	ds_read_b64_tr_b4 v[48:49], v160 offset:1024
	ds_read_b64_tr_b4 v[122:123], v54
	ds_read_b64_tr_b4 v[124:125], v55
	ds_read_b64_tr_b4 v[126:127], v56
	ds_read_b64_tr_b4 v[128:129], v57
	s_waitcnt lgkmcnt(6)
	v_dot8c_i32_i4_e32 v38, v130, v52
	v_dot8c_i32_i4_e32 v39, v130, v50
	v_dot8c_i32_i4_e32 v40, v132, v52
	v_dot8c_i32_i4_e32 v41, v132, v50
	v_dot8c_i32_i4_e32 v42, v134, v52
	v_dot8c_i32_i4_e32 v43, v134, v50
	v_dot8c_i32_i4_e32 v44, v136, v52
	v_dot8c_i32_i4_e32 v45, v136, v50
	v_dot8c_i32_i4_e32 v38, v131, v53
	v_dot8c_i32_i4_e32 v39, v131, v51
	v_dot8c_i32_i4_e32 v40, v133, v53
	v_dot8c_i32_i4_e32 v41, v133, v51
	v_dot8c_i32_i4_e32 v42, v135, v53
	v_dot8c_i32_i4_e32 v43, v135, v51
	v_dot8c_i32_i4_e32 v44, v137, v53
	v_dot8c_i32_i4_e32 v45, v137, v51
	s_nop 3
	s_waitcnt lgkmcnt(15)
	v_lshlrev_b32_e32 v38, 5, v38
	v_lshlrev_b32_e32 v39, 1, v39
	v_add3_u32 v38, v39, v229, v38
	v_cvt_f32_i32_e32 v38, v38
	v_mul_f32_e32 v38, v228, v38
	v_lshlrev_b32_e32 v40, 5, v40
	v_lshlrev_b32_e32 v41, 1, v41
	v_add3_u32 v40, v41, v229, v40
	v_cvt_f32_i32_e32 v40, v40
	v_mul_f32_e32 v40, v228, v40
	v_lshlrev_b32_e32 v42, 5, v42
	v_lshlrev_b32_e32 v43, 1, v43
	v_add3_u32 v42, v43, v229, v42
	v_cvt_f32_i32_e32 v42, v42
	v_mul_f32_e32 v42, v228, v42
	v_lshlrev_b32_e32 v44, 5, v44
	v_lshlrev_b32_e32 v45, 1, v45
	v_add3_u32 v44, v45, v229, v44
	v_cvt_f32_i32_e32 v44, v44
	v_mul_f32_e32 v44, v228, v44
	v_cvt_pk_bf16_f32 v162, v38, v40
	v_cvt_pk_bf16_f32 v163, v42, v44
	v_add_u32_e32 v147, 8, v140
	v_and_b32_e32 v146, 15, v147
	v_xor_b32_e32 v146, 8, v146
	v_bfe_u32 v148, v147, 4, 4
	v_mul_lo_u32 v146, v146, s92
	v_mul_lo_u32 v148, v148, s92
	v_mov_b32_e32 v147, v146
	v_mov_b32_e32 v149, v148
	ds_write2st64_b64 v77, v[146:147], v[148:149] offset1:2
	v_mov_b32_e32 v138, v74
	ds_read_u8 v139, v138
	v_mov_b32_e32 v141, v73
	ds_read_u8 v140, v141
	s_add_i32 s43, s67, 32
	v_mov_b32_e32 v138, s43
	ds_read2st64_b32 v[228:229], v138 offset1:1
	ds_read_b128 v[18:21], v227
	ds_read_b128 v[22:25], v227 offset:16
	v_add_u32_e32 v152, 0x200000, v63
	v_add_u32_e32 v153, 0x200000, v64
	v_mov_b32_e32 v38, 0
	v_mov_b32_e32 v39, 0
	v_mov_b32_e32 v40, 0
	v_mov_b32_e32 v41, 0
	v_mov_b32_e32 v42, 0
	v_mov_b32_e32 v43, 0
	v_mov_b32_e32 v44, 0
	v_mov_b32_e32 v45, 0
	v_and_b32_e32 v78, 0xffff, v31
	v_lshrrev_b32_e32 v79, 16, v31
	v_lshl_add_u32 v78, v78, 7, v150
	v_lshl_add_u32 v79, v79, 7, v151
	s_mov_b32 m0, s77
	s_add_i32 s43, s77, 0x400
	global_load_lds_dwordx4 v78, s[50:51]
	s_mov_b32 m0, s43
	s_nop 0
	global_load_lds_dwordx4 v79, s[50:51]
	s_waitcnt vmcnt(8)
; __device__ __forceinline__ bf16 f2bf(float f) { return (bf16)f2bfu(f); }
; #define TR4(p_) __builtin_amdgcn_ds_read_tr4_b64_v2i32((LAS v2i*)(p_))
; #define VDMA(st_, k_) do { _Pragma("unroll") for (int i_ = 0; i_ < 4; ++i_) { \
;         const unsigned off_ = (unsigned)((st_) >> 2) * (16384u * 128u) + (PE_ID(E, 4 * ((st_) & 3) + i_) << 7) + ((i_ & 1) ? cx1 : cx0); \
;         __builtin_amdgcn_global_load_lds((const unsigned*)(V4 + off_), (LAS unsigned*)(ldsb + BUF[k_] + 1024 * i_), 16, 0, 0); } } while (0)
; __device__ __forceinline__ void peer_v_tokens(int j, const LAS unsigned short* EL, const LAS unsigned char* AL  , const LAS float* ASC  , const LAS int* SAL  , ...
;     ...
;         for (int st = 0; st < 16; ++st) {
;             const int p = st >> 2, q = st & 3;
;             if (st < 14) VDMA(st + 2, (st + 2) % 3);
;             if (st < 14) asm volatile("s_waitcnt vmcnt(8)" ::: "memory");
;             else if (st == 14) asm volatile("s_waitcnt vmcnt(4)" ::: "memory");
;             else asm volatile("s_waitcnt vmcnt(0)" ::: "memory");
;             if (q == 0) {
; #pragma unroll
;                 for (int r = 0; r < 4; ++r) { accH[r] = 0; accL[r] = 0; } }
; #pragma unroll
;             for (int tp = 0; tp < 2; ++tp) {
;                 const v2i ao = TR4(ATL + (2 * q + tp) * 128 + 8 * s16), ah = TR4(ATL + 1024 + (2 * q + tp) * 128 + 8 * s16);
; #pragma unroll
;                 for (int r = 0; r < 4; ++r) {
;                     const v2i d = TR4(ldsb + BUF[st % 3] + 2048 * tp + roff[r]);
;                     accH[r] = __builtin_amdgcn_sdot8(d.x, ah.x, accH[r], false); accH[r] = __builtin_amdgcn_sdot8(d.y, ah.y, accH[r], false);
;                     accL[r] = __builtin_amdgcn_sdot8(d.x, ao.x, accL[r], false); accL[r] = __builtin_amdgcn_sdot8(d.y, ao.y, accL[r], false);
;                 }
;             }
;             asm volatile("s_waitcnt lgkmcnt(0)" ::: "memory");
;             if (q == 3) {
; #pragma unroll
;                 for (int r = 0; r < 4; ++r) STASH[256 * p + 16 * (grp + 4 * r) + pc] = f2bf(asc * (float)(2 * ((accH[r] << 4) + accL[r]) + sa));
;             }
;         }
	v_add_u32_e32 v54, s79, v59
	v_add_u32_e32 v55, s79, v60
	v_add_u32_e32 v56, s79, v61
	v_add_u32_e32 v57, s79, v62
	ds_read_b64_tr_b4 v[50:51], v160 offset:128
	ds_read_b64_tr_b4 v[52:53], v160 offset:1152
	ds_read_b64_tr_b4 v[130:131], v54
	ds_read_b64_tr_b4 v[132:133], v55
	ds_read_b64_tr_b4 v[134:135], v56
	ds_read_b64_tr_b4 v[136:137], v57
	s_waitcnt lgkmcnt(12)
	v_dot8c_i32_i4_e32 v38, v122, v48
	v_dot8c_i32_i4_e32 v39, v122, v46
	v_dot8c_i32_i4_e32 v40, v124, v48
	v_dot8c_i32_i4_e32 v41, v124, v46
	v_dot8c_i32_i4_e32 v42, v126, v48
	v_dot8c_i32_i4_e32 v43, v126, v46
	v_dot8c_i32_i4_e32 v44, v128, v48
	v_dot8c_i32_i4_e32 v45, v128, v46
	v_dot8c_i32_i4_e32 v38, v123, v49
	v_dot8c_i32_i4_e32 v39, v123, v47
	v_dot8c_i32_i4_e32 v40, v125, v49
	v_dot8c_i32_i4_e32 v41, v125, v47
	v_dot8c_i32_i4_e32 v42, v127, v49
	v_dot8c_i32_i4_e32 v43, v127, v47
	v_dot8c_i32_i4_e32 v44, v129, v49
	v_dot8c_i32_i4_e32 v45, v129, v47
	v_and_b32_e32 v78, 0xffff, v32
	v_lshrrev_b32_e32 v79, 16, v32
	v_lshl_add_u32 v78, v78, 7, v150
	v_lshl_add_u32 v79, v79, 7, v151
	s_mov_b32 m0, s78
	s_add_i32 s43, s78, 0x400
	global_load_lds_dwordx4 v78, s[50:51]
	s_mov_b32 m0, s43
	s_nop 0
	global_load_lds_dwordx4 v79, s[50:51]
	s_waitcnt vmcnt(8)
	v_add_u32_e32 v54, s98, v59
	v_add_u32_e32 v55, s98, v60
	v_add_u32_e32 v56, s98, v61
	v_add_u32_e32 v57, s98, v62
	ds_read_b64_tr_b4 v[46:47], v160 offset:256
	ds_read_b64_tr_b4 v[48:49], v160 offset:1280
	ds_read_b64_tr_b4 v[122:123], v54
	ds_read_b64_tr_b4 v[124:125], v55
	ds_read_b64_tr_b4 v[126:127], v56
	ds_read_b64_tr_b4 v[128:129], v57
	s_waitcnt lgkmcnt(6)
	v_dot8c_i32_i4_e32 v38, v130, v52
	v_dot8c_i32_i4_e32 v39, v130, v50
	v_dot8c_i32_i4_e32 v40, v132, v52
	v_dot8c_i32_i4_e32 v41, v132, v50
	v_dot8c_i32_i4_e32 v42, v134, v52
	v_dot8c_i32_i4_e32 v43, v134, v50
	v_dot8c_i32_i4_e32 v44, v136, v52
	v_dot8c_i32_i4_e32 v45, v136, v50
	v_dot8c_i32_i4_e32 v38, v131, v53
	v_dot8c_i32_i4_e32 v39, v131, v51
	v_dot8c_i32_i4_e32 v40, v133, v53
	v_dot8c_i32_i4_e32 v41, v133, v51
	v_dot8c_i32_i4_e32 v42, v135, v53
	v_dot8c_i32_i4_e32 v43, v135, v51
	v_dot8c_i32_i4_e32 v44, v137, v53
	v_dot8c_i32_i4_e32 v45, v137, v51
	v_and_b32_e32 v78, 0xffff, v33
	v_lshrrev_b32_e32 v79, 16, v33
	v_lshl_add_u32 v78, v78, 7, v150
	v_lshl_add_u32 v79, v79, 7, v151
	s_mov_b32 m0, s79
	s_add_i32 s43, s79, 0x400
	global_load_lds_dwordx4 v78, s[50:51]
	s_mov_b32 m0, s43
	s_nop 0
	global_load_lds_dwordx4 v79, s[50:51]
	s_waitcnt vmcnt(8)
	v_add_u32_e32 v54, s99, v59
	v_add_u32_e32 v55, s99, v60
	v_add_u32_e32 v56, s99, v61
	v_add_u32_e32 v57, s99, v62
	ds_read_b64_tr_b4 v[50:51], v160 offset:384
	ds_read_b64_tr_b4 v[52:53], v160 offset:1408
	ds_read_b64_tr_b4 v[130:131], v54
	ds_read_b64_tr_b4 v[132:133], v55
	ds_read_b64_tr_b4 v[134:135], v56
	ds_read_b64_tr_b4 v[136:137], v57
	s_waitcnt lgkmcnt(6)
	v_dot8c_i32_i4_e32 v38, v122, v48
	v_dot8c_i32_i4_e32 v39, v122, v46
	v_dot8c_i32_i4_e32 v40, v124, v48
	v_dot8c_i32_i4_e32 v41, v124, v46
	v_dot8c_i32_i4_e32 v42, v126, v48
	v_dot8c_i32_i4_e32 v43, v126, v46
	v_dot8c_i32_i4_e32 v44, v128, v48
	v_dot8c_i32_i4_e32 v45, v128, v46
	v_dot8c_i32_i4_e32 v38, v123, v49
	v_dot8c_i32_i4_e32 v39, v123, v47
	v_dot8c_i32_i4_e32 v40, v125, v49
	v_dot8c_i32_i4_e32 v41, v125, v47
	v_dot8c_i32_i4_e32 v42, v127, v49
	v_dot8c_i32_i4_e32 v43, v127, v47
	v_dot8c_i32_i4_e32 v44, v129, v49
	v_dot8c_i32_i4_e32 v45, v129, v47
	s_waitcnt lgkmcnt(15)
	v_and_b32_e32 v78, 0xffff, v18
	v_lshrrev_b32_e32 v79, 16, v18
	v_lshl_add_u32 v78, v78, 7, v152
	v_lshl_add_u32 v79, v79, 7, v153
	s_mov_b32 m0, s98
	s_add_i32 s43, s98, 0x400
	global_load_lds_dwordx4 v78, s[50:51]
	s_mov_b32 m0, s43
	s_nop 0
	global_load_lds_dwordx4 v79, s[50:51]
	s_waitcnt vmcnt(8)
	v_add_u32_e32 v54, s76, v59
	v_add_u32_e32 v55, s76, v60
	v_add_u32_e32 v56, s76, v61
	v_add_u32_e32 v57, s76, v62
	ds_read_b64_tr_b4 v[46:47], v160 offset:512
	ds_read_b64_tr_b4 v[48:49], v160 offset:1536
	ds_read_b64_tr_b4 v[122:123], v54
	ds_read_b64_tr_b4 v[124:125], v55
	ds_read_b64_tr_b4 v[126:127], v56
	ds_read_b64_tr_b4 v[128:129], v57
	s_waitcnt lgkmcnt(6)
	v_dot8c_i32_i4_e32 v38, v130, v52
	v_dot8c_i32_i4_e32 v39, v130, v50
	v_dot8c_i32_i4_e32 v40, v132, v52
	v_dot8c_i32_i4_e32 v41, v132, v50
	v_dot8c_i32_i4_e32 v42, v134, v52
	v_dot8c_i32_i4_e32 v43, v134, v50
	v_dot8c_i32_i4_e32 v44, v136, v52
	v_dot8c_i32_i4_e32 v45, v136, v50
	v_dot8c_i32_i4_e32 v38, v131, v53
	v_dot8c_i32_i4_e32 v39, v131, v51
	v_dot8c_i32_i4_e32 v40, v133, v53
	v_dot8c_i32_i4_e32 v41, v133, v51
	v_dot8c_i32_i4_e32 v42, v135, v53
	v_dot8c_i32_i4_e32 v43, v135, v51
	v_dot8c_i32_i4_e32 v44, v137, v53
	v_dot8c_i32_i4_e32 v45, v137, v51
	v_and_b32_e32 v78, 0xffff, v19
	v_lshrrev_b32_e32 v79, 16, v19
	v_lshl_add_u32 v78, v78, 7, v152
	v_lshl_add_u32 v79, v79, 7, v153
	s_mov_b32 m0, s99
	s_add_i32 s43, s99, 0x400
	global_load_lds_dwordx4 v78, s[50:51]
	s_mov_b32 m0, s43
	s_nop 0
	global_load_lds_dwordx4 v79, s[50:51]
	s_waitcnt vmcnt(8)
	v_add_u32_e32 v54, s77, v59
	v_add_u32_e32 v55, s77, v60
	v_add_u32_e32 v56, s77, v61
	v_add_u32_e32 v57, s77, v62
	ds_read_b64_tr_b4 v[50:51], v160 offset:640
	ds_read_b64_tr_b4 v[52:53], v160 offset:1664
	ds_read_b64_tr_b4 v[130:131], v54
	ds_read_b64_tr_b4 v[132:133], v55
	ds_read_b64_tr_b4 v[134:135], v56
	ds_read_b64_tr_b4 v[136:137], v57
	s_waitcnt lgkmcnt(6)
	v_dot8c_i32_i4_e32 v38, v122, v48
	v_dot8c_i32_i4_e32 v39, v122, v46
	v_dot8c_i32_i4_e32 v40, v124, v48
	v_dot8c_i32_i4_e32 v41, v124, v46
	v_dot8c_i32_i4_e32 v42, v126, v48
	v_dot8c_i32_i4_e32 v43, v126, v46
	v_dot8c_i32_i4_e32 v44, v128, v48
	v_dot8c_i32_i4_e32 v45, v128, v46
	v_dot8c_i32_i4_e32 v38, v123, v49
	v_dot8c_i32_i4_e32 v39, v123, v47
	v_dot8c_i32_i4_e32 v40, v125, v49
	v_dot8c_i32_i4_e32 v41, v125, v47
	v_dot8c_i32_i4_e32 v42, v127, v49
	v_dot8c_i32_i4_e32 v43, v127, v47
	v_dot8c_i32_i4_e32 v44, v129, v49
	v_dot8c_i32_i4_e32 v45, v129, v47
	s_waitcnt lgkmcnt(15)
; __device__ __forceinline__ void peer_v_tokens(int j, const LAS unsigned short* EL, const LAS unsigned char* AL  , const LAS float* ASC  , const LAS int* SAL  , ...
;     ...
;         { const LAS v4u* ep = (const LAS v4u*)(EL + tl * 128 + 16 * g); const v4u e0 = ep[0], e1 = ep[1];
;           E[0] = e0.x; E[1] = e0.y; E[2] = e0.z; E[3] = e0.w; E[4] = e1.x; E[5] = e1.y; E[6] = e1.z; E[7] = e1.w; }
;         uint2 hv[4]; float4 gv[4];
;         { unsigned ho = (unsigned)t * (D / 4) + (unsigned)lane; asm volatile("" : "+v"(ho)); const uint2* hp = (const uint2*)HB + ho; const float4* gp = (const float4*)fng + lane;
; #pragma unroll
;           for (int jq = 0; jq < 4; ++jq) { hv[jq] = hp[64 * jq]; gv[jq] = gp[64 * jq]; } }
;         VDMA(0, 0); VDMA(1, 1);
; #pragma unroll
;         for (int m = 0; m < 2; ++m) {
;             const int idx = lane + 64 * m, tau = idx >> 4, sr = idx & 15, k = 16 * (sr & 7) + 2 * tau + (sr >> 3);
;             const int aq = (int)*(const LAS signed char*)(AL + tl * 128 + k); const int tq = aq + 8;
;             const unsigned lo = (((unsigned)tq & 15u) ^ 8u) * 0x11111111u, hi = ((unsigned)(tq >> 4) & 15u) * 0x11111111u;
;             typedef unsigned u2v __attribute__((ext_vector_type(2)));
;             u2v l2; l2.x = lo; l2.y = lo; u2v h2; h2.x = hi; h2.y = hi;
;             *(LAS u2v*)(ATL + 8 * idx) = l2; *(LAS u2v*)(ATL + 1024 + 8 * idx) = h2;
;         }
;         const float asc = ASC[tl]; const int sa = SAL[tl];
;         CFENCE();
;         int accH[4], accL[4];
; #pragma unroll
;         for (int st = 0; st < 16; ++st) {
;             const int p = st >> 2, q = st & 3;
;             if (st < 14) VDMA(st + 2, (st + 2) % 3);
;             if (st < 14) asm volatile("s_waitcnt vmcnt(8)" ::: "memory");
;             else if (st == 14) asm volatile("s_waitcnt vmcnt(4)" ::: "memory");
;             else asm volatile("s_waitcnt vmcnt(0)" ::: "memory");
;             if (q == 0) {
; #pragma unroll
;                 for (int r = 0; r < 4; ++r) { accH[r] = 0; accL[r] = 0; } }
; #pragma unroll
;             for (int tp = 0; tp < 2; ++tp) {
;                 const v2i ao = TR4(ATL + (2 * q + tp) * 128 + 8 * s16), ah = TR4(ATL + 1024 + (2 * q + tp) * 128 + 8 * s16);
; #pragma unroll
;                 for (int r = 0; r < 4; ++r) {
;                     const v2i d = TR4(ldsb + BUF[st % 3] + 2048 * tp + roff[r]);
	v_add_u32_e32 v143, 8, v139
	v_and_b32_e32 v142, 15, v143
	v_xor_b32_e32 v142, 8, v142
	v_bfe_u32 v144, v143, 4, 4
	v_mul_lo_u32 v142, v142, s92
	v_mul_lo_u32 v144, v144, s92
	v_mov_b32_e32 v143, v142
	v_mov_b32_e32 v145, v144
	ds_write2st64_b64 v159, v[142:143], v[144:145] offset1:2
	v_and_b32_e32 v78, 0xffff, v20
	v_lshrrev_b32_e32 v79, 16, v20
	v_lshl_add_u32 v78, v78, 7, v152
	v_lshl_add_u32 v79, v79, 7, v153
	s_mov_b32 m0, s76
	s_add_i32 s43, s76, 0x400
	global_load_lds_dwordx4 v78, s[50:51]
	s_mov_b32 m0, s43
	s_nop 0
	global_load_lds_dwordx4 v79, s[50:51]
	s_waitcnt vmcnt(8)
	v_add_u32_e32 v54, s78, v59
	v_add_u32_e32 v55, s78, v60
	v_add_u32_e32 v56, s78, v61
	v_add_u32_e32 v57, s78, v62
	ds_read_b64_tr_b4 v[46:47], v160 offset:768
	ds_read_b64_tr_b4 v[48:49], v160 offset:1792
	ds_read_b64_tr_b4 v[122:123], v54
	ds_read_b64_tr_b4 v[124:125], v55
	ds_read_b64_tr_b4 v[126:127], v56
	ds_read_b64_tr_b4 v[128:129], v57
	s_waitcnt lgkmcnt(7)
	v_dot8c_i32_i4_e32 v38, v130, v52
	v_dot8c_i32_i4_e32 v39, v130, v50
	v_dot8c_i32_i4_e32 v40, v132, v52
	v_dot8c_i32_i4_e32 v41, v132, v50
	v_dot8c_i32_i4_e32 v42, v134, v52
	v_dot8c_i32_i4_e32 v43, v134, v50
	v_dot8c_i32_i4_e32 v44, v136, v52
	v_dot8c_i32_i4_e32 v45, v136, v50
	v_dot8c_i32_i4_e32 v38, v131, v53
	v_dot8c_i32_i4_e32 v39, v131, v51
	v_dot8c_i32_i4_e32 v40, v133, v53
	v_dot8c_i32_i4_e32 v41, v133, v51
	v_dot8c_i32_i4_e32 v42, v135, v53
	v_dot8c_i32_i4_e32 v43, v135, v51
	v_dot8c_i32_i4_e32 v44, v137, v53
	v_dot8c_i32_i4_e32 v45, v137, v51
	v_and_b32_e32 v78, 0xffff, v21
	v_lshrrev_b32_e32 v79, 16, v21
	v_lshl_add_u32 v78, v78, 7, v152
	v_lshl_add_u32 v79, v79, 7, v153
	s_mov_b32 m0, s77
	s_add_i32 s43, s77, 0x400
	global_load_lds_dwordx4 v78, s[50:51]
	s_mov_b32 m0, s43
	s_nop 0
	global_load_lds_dwordx4 v79, s[50:51]
	s_waitcnt vmcnt(8)
	v_add_u32_e32 v54, s79, v59
	v_add_u32_e32 v55, s79, v60
	v_add_u32_e32 v56, s79, v61
	v_add_u32_e32 v57, s79, v62
	ds_read_b64_tr_b4 v[50:51], v160 offset:896
	ds_read_b64_tr_b4 v[52:53], v160 offset:1920
	ds_read_b64_tr_b4 v[130:131], v54
	ds_read_b64_tr_b4 v[132:133], v55
	ds_read_b64_tr_b4 v[134:135], v56
	ds_read_b64_tr_b4 v[136:137], v57
	s_waitcnt lgkmcnt(6)
	v_dot8c_i32_i4_e32 v38, v122, v48
	v_dot8c_i32_i4_e32 v39, v122, v46
	v_dot8c_i32_i4_e32 v40, v124, v48
	v_dot8c_i32_i4_e32 v41, v124, v46
	v_dot8c_i32_i4_e32 v42, v126, v48
	v_dot8c_i32_i4_e32 v43, v126, v46
	v_dot8c_i32_i4_e32 v44, v128, v48
	v_dot8c_i32_i4_e32 v45, v128, v46
	v_dot8c_i32_i4_e32 v38, v123, v49
	v_dot8c_i32_i4_e32 v39, v123, v47
	v_dot8c_i32_i4_e32 v40, v125, v49
	v_dot8c_i32_i4_e32 v41, v125, v47
	v_dot8c_i32_i4_e32 v42, v127, v49
	v_dot8c_i32_i4_e32 v43, v127, v47
	v_dot8c_i32_i4_e32 v44, v129, v49
	v_dot8c_i32_i4_e32 v45, v129, v47
	v_and_b32_e32 v78, 0xffff, v22
	v_lshrrev_b32_e32 v79, 16, v22
	v_lshl_add_u32 v78, v78, 7, v152
	v_lshl_add_u32 v79, v79, 7, v153
	s_mov_b32 m0, s78
	s_add_i32 s43, s78, 0x400
	global_load_lds_dwordx4 v78, s[50:51]
	s_mov_b32 m0, s43
	s_nop 0
	global_load_lds_dwordx4 v79, s[50:51]
	s_waitcnt vmcnt(8)
	v_add_u32_e32 v54, s98, v59
	v_add_u32_e32 v55, s98, v60
	v_add_u32_e32 v56, s98, v61
	v_add_u32_e32 v57, s98, v62
	ds_read_b64_tr_b4 v[46:47], v160
	ds_read_b64_tr_b4 v[48:49], v160 offset:1024
	ds_read_b64_tr_b4 v[122:123], v54
	ds_read_b64_tr_b4 v[124:125], v55
	ds_read_b64_tr_b4 v[126:127], v56
	ds_read_b64_tr_b4 v[128:129], v57
	s_waitcnt lgkmcnt(6)
	v_dot8c_i32_i4_e32 v38, v130, v52
	v_dot8c_i32_i4_e32 v39, v130, v50
	v_dot8c_i32_i4_e32 v40, v132, v52
	v_dot8c_i32_i4_e32 v41, v132, v50
	v_dot8c_i32_i4_e32 v42, v134, v52
	v_dot8c_i32_i4_e32 v43, v134, v50
	v_dot8c_i32_i4_e32 v44, v136, v52
	v_dot8c_i32_i4_e32 v45, v136, v50
	v_dot8c_i32_i4_e32 v38, v131, v53
	v_dot8c_i32_i4_e32 v39, v131, v51
	v_dot8c_i32_i4_e32 v40, v133, v53
	v_dot8c_i32_i4_e32 v41, v133, v51
	v_dot8c_i32_i4_e32 v42, v135, v53
	v_dot8c_i32_i4_e32 v43, v135, v51
	v_dot8c_i32_i4_e32 v44, v137, v53
	v_dot8c_i32_i4_e32 v45, v137, v51
	s_nop 3
	s_waitcnt lgkmcnt(15)
	v_lshlrev_b32_e32 v38, 5, v38
	v_lshlrev_b32_e32 v39, 1, v39
	v_add3_u32 v38, v39, v229, v38
	v_cvt_f32_i32_e32 v38, v38
	v_mul_f32_e32 v38, v228, v38
	v_lshlrev_b32_e32 v40, 5, v40
	v_lshlrev_b32_e32 v41, 1, v41
	v_add3_u32 v40, v41, v229, v40
	v_cvt_f32_i32_e32 v40, v40
	v_mul_f32_e32 v40, v228, v40
	v_lshlrev_b32_e32 v42, 5, v42
	v_lshlrev_b32_e32 v43, 1, v43
	v_add3_u32 v42, v43, v229, v42
	v_cvt_f32_i32_e32 v42, v42
	v_mul_f32_e32 v42, v228, v42
	v_lshlrev_b32_e32 v44, 5, v44
	v_lshlrev_b32_e32 v45, 1, v45
	v_add3_u32 v44, v45, v229, v44
	v_cvt_f32_i32_e32 v44, v44
	v_mul_f32_e32 v44, v228, v44
	v_cvt_pk_bf16_f32 v170, v38, v40
	v_cvt_pk_bf16_f32 v171, v42, v44
	v_add_u32_e32 v147, 8, v140
	v_and_b32_e32 v146, 15, v147
	v_xor_b32_e32 v146, 8, v146
	v_bfe_u32 v148, v147, 4, 4
	v_mul_lo_u32 v146, v146, s92
	v_mul_lo_u32 v148, v148, s92
	v_mov_b32_e32 v147, v146
	v_mov_b32_e32 v149, v148
	ds_write2st64_b64 v77, v[146:147], v[148:149] offset1:2
	v_add_u32_e32 v138, 0x400, v74
	ds_read_u8 v139, v138
	v_add_u32_e32 v141, 0x400, v73
	ds_read_u8 v140, v141
	s_mov_b32 s43, s67
	v_mov_b32_e32 v138, s43
	ds_read2st64_b32 v[228:229], v138 offset1:1
	ds_read_b128 v[26:29], v227 offset:2048
	ds_read_b128 v[30:33], v227 offset:2064
	v_mov_b32_e32 v38, 0
	v_mov_b32_e32 v39, 0
	v_mov_b32_e32 v40, 0
	v_mov_b32_e32 v41, 0
	v_mov_b32_e32 v42, 0
	v_mov_b32_e32 v43, 0
	v_mov_b32_e32 v44, 0
	v_mov_b32_e32 v45, 0
	v_and_b32_e32 v78, 0xffff, v23
	v_lshrrev_b32_e32 v79, 16, v23
	v_lshl_add_u32 v78, v78, 7, v152
	v_lshl_add_u32 v79, v79, 7, v153
	s_mov_b32 m0, s79
	s_add_i32 s43, s79, 0x400
	global_load_lds_dwordx4 v78, s[50:51]
	s_mov_b32 m0, s43
	s_nop 0
	global_load_lds_dwordx4 v79, s[50:51]
	s_waitcnt vmcnt(8)
; __device__ __forceinline__ bf16 f2bf(float f) { return (bf16)f2bfu(f); }
; #define TR4(p_) __builtin_amdgcn_ds_read_tr4_b64_v2i32((LAS v2i*)(p_))
; #define VDMA(st_, k_) do { _Pragma("unroll") for (int i_ = 0; i_ < 4; ++i_) { \
;         const unsigned off_ = (unsigned)((st_) >> 2) * (16384u * 128u) + (PE_ID(E, 4 * ((st_) & 3) + i_) << 7) + ((i_ & 1) ? cx1 : cx0); \
;         __builtin_amdgcn_global_load_lds((const unsigned*)(V4 + off_), (LAS unsigned*)(ldsb + BUF[k_] + 1024 * i_), 16, 0, 0); } } while (0)
; __device__ __forceinline__ void peer_v_tokens(int j, const LAS unsigned short* EL, const LAS unsigned char* AL  , const LAS float* ASC  , const LAS int* SAL  , ...
;     ...
;         for (int st = 0; st < 16; ++st) {
;             const int p = st >> 2, q = st & 3;
;             if (st < 14) VDMA(st + 2, (st + 2) % 3);
;             if (st < 14) asm volatile("s_waitcnt vmcnt(8)" ::: "memory");
;             else if (st == 14) asm volatile("s_waitcnt vmcnt(4)" ::: "memory");
;             else asm volatile("s_waitcnt vmcnt(0)" ::: "memory");
;             if (q == 0) {
; #pragma unroll
;                 for (int r = 0; r < 4; ++r) { accH[r] = 0; accL[r] = 0; } }
; #pragma unroll
;             for (int tp = 0; tp < 2; ++tp) {
;                 const v2i ao = TR4(ATL + (2 * q + tp) * 128 + 8 * s16), ah = TR4(ATL + 1024 + (2 * q + tp) * 128 + 8 * s16);
; #pragma unroll
;                 for (int r = 0; r < 4; ++r) {
;                     const v2i d = TR4(ldsb + BUF[st % 3] + 2048 * tp + roff[r]);
;                     accH[r] = __builtin_amdgcn_sdot8(d.x, ah.x, accH[r], false); accH[r] = __builtin_amdgcn_sdot8(d.y, ah.y, accH[r], false);
;                     accL[r] = __builtin_amdgcn_sdot8(d.x, ao.x, accL[r], false); accL[r] = __builtin_amdgcn_sdot8(d.y, ao.y, accL[r], false);
;                 }
;             }
;             asm volatile("s_waitcnt lgkmcnt(0)" ::: "memory");
;             if (q == 3) {
; #pragma unroll
;                 for (int r = 0; r < 4; ++r) STASH[256 * p + 16 * (grp + 4 * r) + pc] = f2bf(asc * (float)(2 * ((accH[r] << 4) + accL[r]) + sa));
;             }
;         }
	v_add_u32_e32 v54, s99, v59
	v_add_u32_e32 v55, s99, v60
	v_add_u32_e32 v56, s99, v61
	v_add_u32_e32 v57, s99, v62
	ds_read_b64_tr_b4 v[50:51], v160 offset:128
	ds_read_b64_tr_b4 v[52:53], v160 offset:1152
	ds_read_b64_tr_b4 v[130:131], v54
	ds_read_b64_tr_b4 v[132:133], v55
	ds_read_b64_tr_b4 v[134:135], v56
	ds_read_b64_tr_b4 v[136:137], v57
	s_waitcnt lgkmcnt(12)
	v_dot8c_i32_i4_e32 v38, v122, v48
	v_dot8c_i32_i4_e32 v39, v122, v46
	v_dot8c_i32_i4_e32 v40, v124, v48
	v_dot8c_i32_i4_e32 v41, v124, v46
	v_dot8c_i32_i4_e32 v42, v126, v48
	v_dot8c_i32_i4_e32 v43, v126, v46
	v_dot8c_i32_i4_e32 v44, v128, v48
	v_dot8c_i32_i4_e32 v45, v128, v46
	v_dot8c_i32_i4_e32 v38, v123, v49
	v_dot8c_i32_i4_e32 v39, v123, v47
	v_dot8c_i32_i4_e32 v40, v125, v49
	v_dot8c_i32_i4_e32 v41, v125, v47
	v_dot8c_i32_i4_e32 v42, v127, v49
	v_dot8c_i32_i4_e32 v43, v127, v47
	v_dot8c_i32_i4_e32 v44, v129, v49
	v_dot8c_i32_i4_e32 v45, v129, v47
	v_and_b32_e32 v78, 0xffff, v24
	v_lshrrev_b32_e32 v79, 16, v24
	v_lshl_add_u32 v78, v78, 7, v152
	v_lshl_add_u32 v79, v79, 7, v153
	s_mov_b32 m0, s98
	s_add_i32 s43, s98, 0x400
	global_load_lds_dwordx4 v78, s[50:51]
	s_mov_b32 m0, s43
	s_nop 0
	global_load_lds_dwordx4 v79, s[50:51]
	s_waitcnt vmcnt(8)
	v_add_u32_e32 v54, s76, v59
	v_add_u32_e32 v55, s76, v60
	v_add_u32_e32 v56, s76, v61
	v_add_u32_e32 v57, s76, v62
	ds_read_b64_tr_b4 v[46:47], v160 offset:256
	ds_read_b64_tr_b4 v[48:49], v160 offset:1280
	ds_read_b64_tr_b4 v[122:123], v54
	ds_read_b64_tr_b4 v[124:125], v55
	ds_read_b64_tr_b4 v[126:127], v56
	ds_read_b64_tr_b4 v[128:129], v57
	s_waitcnt lgkmcnt(6)
	v_dot8c_i32_i4_e32 v38, v130, v52
	v_dot8c_i32_i4_e32 v39, v130, v50
	v_dot8c_i32_i4_e32 v40, v132, v52
	v_dot8c_i32_i4_e32 v41, v132, v50
	v_dot8c_i32_i4_e32 v42, v134, v52
	v_dot8c_i32_i4_e32 v43, v134, v50
	v_dot8c_i32_i4_e32 v44, v136, v52
	v_dot8c_i32_i4_e32 v45, v136, v50
	v_dot8c_i32_i4_e32 v38, v131, v53
	v_dot8c_i32_i4_e32 v39, v131, v51
	v_dot8c_i32_i4_e32 v40, v133, v53
	v_dot8c_i32_i4_e32 v41, v133, v51
	v_dot8c_i32_i4_e32 v42, v135, v53
	v_dot8c_i32_i4_e32 v43, v135, v51
	v_dot8c_i32_i4_e32 v44, v137, v53
	v_dot8c_i32_i4_e32 v45, v137, v51
	v_and_b32_e32 v78, 0xffff, v25
	v_lshrrev_b32_e32 v79, 16, v25
	v_lshl_add_u32 v78, v78, 7, v152
	v_lshl_add_u32 v79, v79, 7, v153
	s_mov_b32 m0, s99
	s_add_i32 s43, s99, 0x400
	global_load_lds_dwordx4 v78, s[50:51]
	s_mov_b32 m0, s43
	s_nop 0
	global_load_lds_dwordx4 v79, s[50:51]
	s_waitcnt vmcnt(8)
	v_add_u32_e32 v54, s77, v59
	v_add_u32_e32 v55, s77, v60
	v_add_u32_e32 v56, s77, v61
	v_add_u32_e32 v57, s77, v62
	ds_read_b64_tr_b4 v[50:51], v160 offset:384
	ds_read_b64_tr_b4 v[52:53], v160 offset:1408
	ds_read_b64_tr_b4 v[130:131], v54
	ds_read_b64_tr_b4 v[132:133], v55
	ds_read_b64_tr_b4 v[134:135], v56
	ds_read_b64_tr_b4 v[136:137], v57
	s_waitcnt lgkmcnt(6)
	v_dot8c_i32_i4_e32 v38, v122, v48
	v_dot8c_i32_i4_e32 v39, v122, v46
	v_dot8c_i32_i4_e32 v40, v124, v48
	v_dot8c_i32_i4_e32 v41, v124, v46
	v_dot8c_i32_i4_e32 v42, v126, v48
	v_dot8c_i32_i4_e32 v43, v126, v46
	v_dot8c_i32_i4_e32 v44, v128, v48
	v_dot8c_i32_i4_e32 v45, v128, v46
	v_dot8c_i32_i4_e32 v38, v123, v49
	v_dot8c_i32_i4_e32 v39, v123, v47
	v_dot8c_i32_i4_e32 v40, v125, v49
	v_dot8c_i32_i4_e32 v41, v125, v47
	v_dot8c_i32_i4_e32 v42, v127, v49
	v_dot8c_i32_i4_e32 v43, v127, v47
	v_dot8c_i32_i4_e32 v44, v129, v49
	v_dot8c_i32_i4_e32 v45, v129, v47
	s_waitcnt lgkmcnt(15)
	v_and_b32_e32 v78, 0xffff, v26
	v_lshrrev_b32_e32 v79, 16, v26
	v_lshl_add_u32 v78, v78, 7, v152
	v_lshl_add_u32 v79, v79, 7, v153
	s_mov_b32 m0, s76
	s_add_i32 s43, s76, 0x400
	global_load_lds_dwordx4 v78, s[50:51]
	s_mov_b32 m0, s43
	s_nop 0
	global_load_lds_dwordx4 v79, s[50:51]
	s_waitcnt vmcnt(8)
	v_add_u32_e32 v54, s78, v59
	v_add_u32_e32 v55, s78, v60
	v_add_u32_e32 v56, s78, v61
	v_add_u32_e32 v57, s78, v62
	ds_read_b64_tr_b4 v[46:47], v160 offset:512
	ds_read_b64_tr_b4 v[48:49], v160 offset:1536
	ds_read_b64_tr_b4 v[122:123], v54
	ds_read_b64_tr_b4 v[124:125], v55
	ds_read_b64_tr_b4 v[126:127], v56
	ds_read_b64_tr_b4 v[128:129], v57
	s_waitcnt lgkmcnt(6)
	v_dot8c_i32_i4_e32 v38, v130, v52
	v_dot8c_i32_i4_e32 v39, v130, v50
	v_dot8c_i32_i4_e32 v40, v132, v52
	v_dot8c_i32_i4_e32 v41, v132, v50
	v_dot8c_i32_i4_e32 v42, v134, v52
	v_dot8c_i32_i4_e32 v43, v134, v50
	v_dot8c_i32_i4_e32 v44, v136, v52
	v_dot8c_i32_i4_e32 v45, v136, v50
	v_dot8c_i32_i4_e32 v38, v131, v53
	v_dot8c_i32_i4_e32 v39, v131, v51
	v_dot8c_i32_i4_e32 v40, v133, v53
	v_dot8c_i32_i4_e32 v41, v133, v51
	v_dot8c_i32_i4_e32 v42, v135, v53
	v_dot8c_i32_i4_e32 v43, v135, v51
	v_dot8c_i32_i4_e32 v44, v137, v53
	v_dot8c_i32_i4_e32 v45, v137, v51
	v_and_b32_e32 v78, 0xffff, v27
	v_lshrrev_b32_e32 v79, 16, v27
	v_lshl_add_u32 v78, v78, 7, v152
	v_lshl_add_u32 v79, v79, 7, v153
	s_mov_b32 m0, s77
	s_add_i32 s43, s77, 0x400
	global_load_lds_dwordx4 v78, s[50:51]
	s_mov_b32 m0, s43
	s_nop 0
	global_load_lds_dwordx4 v79, s[50:51]
	s_waitcnt vmcnt(8)
	v_add_u32_e32 v54, s79, v59
	v_add_u32_e32 v55, s79, v60
	v_add_u32_e32 v56, s79, v61
	v_add_u32_e32 v57, s79, v62
	ds_read_b64_tr_b4 v[50:51], v160 offset:640
	ds_read_b64_tr_b4 v[52:53], v160 offset:1664
	ds_read_b64_tr_b4 v[130:131], v54
	ds_read_b64_tr_b4 v[132:133], v55
	ds_read_b64_tr_b4 v[134:135], v56
	ds_read_b64_tr_b4 v[136:137], v57
	s_waitcnt lgkmcnt(6)
	v_dot8c_i32_i4_e32 v38, v122, v48
	v_dot8c_i32_i4_e32 v39, v122, v46
	v_dot8c_i32_i4_e32 v40, v124, v48
	v_dot8c_i32_i4_e32 v41, v124, v46
	v_dot8c_i32_i4_e32 v42, v126, v48
	v_dot8c_i32_i4_e32 v43, v126, v46
	v_dot8c_i32_i4_e32 v44, v128, v48
	v_dot8c_i32_i4_e32 v45, v128, v46
	v_dot8c_i32_i4_e32 v38, v123, v49
	v_dot8c_i32_i4_e32 v39, v123, v47
	v_dot8c_i32_i4_e32 v40, v125, v49
	v_dot8c_i32_i4_e32 v41, v125, v47
	v_dot8c_i32_i4_e32 v42, v127, v49
	v_dot8c_i32_i4_e32 v43, v127, v47
	v_dot8c_i32_i4_e32 v44, v129, v49
	v_dot8c_i32_i4_e32 v45, v129, v47
	s_waitcnt lgkmcnt(15)
; __device__ __forceinline__ void peer_v_tokens(int j, const LAS unsigned short* EL, const LAS unsigned char* AL  , const LAS float* ASC  , const LAS int* SAL  , ...
;     ...
;         { const LAS v4u* ep = (const LAS v4u*)(EL + tl * 128 + 16 * g); const v4u e0 = ep[0], e1 = ep[1];
;           E[0] = e0.x; E[1] = e0.y; E[2] = e0.z; E[3] = e0.w; E[4] = e1.x; E[5] = e1.y; E[6] = e1.z; E[7] = e1.w; }
;         uint2 hv[4]; float4 gv[4];
;         { unsigned ho = (unsigned)t * (D / 4) + (unsigned)lane; asm volatile("" : "+v"(ho)); const uint2* hp = (const uint2*)HB + ho; const float4* gp = (const float4*)fng + lane;
; #pragma unroll
;           for (int jq = 0; jq < 4; ++jq) { hv[jq] = hp[64 * jq]; gv[jq] = gp[64 * jq]; } }
;         VDMA(0, 0); VDMA(1, 1);
; #pragma unroll
;         for (int m = 0; m < 2; ++m) {
;             const int idx = lane + 64 * m, tau = idx >> 4, sr = idx & 15, k = 16 * (sr & 7) + 2 * tau + (sr >> 3);
;             const int aq = (int)*(const LAS signed char*)(AL + tl * 128 + k); const int tq = aq + 8;
;             const unsigned lo = (((unsigned)tq & 15u) ^ 8u) * 0x11111111u, hi = ((unsigned)(tq >> 4) & 15u) * 0x11111111u;
;             typedef unsigned u2v __attribute__((ext_vector_type(2)));
;             u2v l2; l2.x = lo; l2.y = lo; u2v h2; h2.x = hi; h2.y = hi;
;             *(LAS u2v*)(ATL + 8 * idx) = l2; *(LAS u2v*)(ATL + 1024 + 8 * idx) = h2;
;         }
;         const float asc = ASC[tl]; const int sa = SAL[tl];
;         CFENCE();
;         int accH[4], accL[4];
; #pragma unroll
;         for (int st = 0; st < 16; ++st) {
;             const int p = st >> 2, q = st & 3;
;             if (st < 14) VDMA(st + 2, (st + 2) % 3);
;             if (st < 14) asm volatile("s_waitcnt vmcnt(8)" ::: "memory");
;             else if (st == 14) asm volatile("s_waitcnt vmcnt(4)" ::: "memory");
;             else asm volatile("s_waitcnt vmcnt(0)" ::: "memory");
;             if (q == 0) {
; #pragma unroll
;                 for (int r = 0; r < 4; ++r) { accH[r] = 0; accL[r] = 0; } }
; #pragma unroll
;             for (int tp = 0; tp < 2; ++tp) {
;                 const v2i ao = TR4(ATL + (2 * q + tp) * 128 + 8 * s16), ah = TR4(ATL + 1024 + (2 * q + tp) * 128 + 8 * s16);
; #pragma unroll
;                 for (int r = 0; r < 4; ++r) {
;                     const v2i d = TR4(ldsb + BUF[st % 3] + 2048 * tp + roff[r]);
	v_add_u32_e32 v143, 8, v139
	v_and_b32_e32 v142, 15, v143
	v_xor_b32_e32 v142, 8, v142
	v_bfe_u32 v144, v143, 4, 4
	v_mul_lo_u32 v142, v142, s92
	v_mul_lo_u32 v144, v144, s92
	v_mov_b32_e32 v143, v142
	v_mov_b32_e32 v145, v144
	ds_write2st64_b64 v159, v[142:143], v[144:145] offset1:2
	v_and_b32_e32 v78, 0xffff, v28
	v_lshrrev_b32_e32 v79, 16, v28
	v_lshl_add_u32 v78, v78, 7, v152
	v_lshl_add_u32 v79, v79, 7, v153
	s_mov_b32 m0, s78
	s_add_i32 s43, s78, 0x400
	global_load_lds_dwordx4 v78, s[50:51]
	s_mov_b32 m0, s43
	s_nop 0
	global_load_lds_dwordx4 v79, s[50:51]
	s_waitcnt vmcnt(8)
	v_add_u32_e32 v54, s98, v59
	v_add_u32_e32 v55, s98, v60
	v_add_u32_e32 v56, s98, v61
	v_add_u32_e32 v57, s98, v62
	ds_read_b64_tr_b4 v[46:47], v160 offset:768
	ds_read_b64_tr_b4 v[48:49], v160 offset:1792
	ds_read_b64_tr_b4 v[122:123], v54
	ds_read_b64_tr_b4 v[124:125], v55
	ds_read_b64_tr_b4 v[126:127], v56
	ds_read_b64_tr_b4 v[128:129], v57
	s_waitcnt lgkmcnt(7)
	v_dot8c_i32_i4_e32 v38, v130, v52
	v_dot8c_i32_i4_e32 v39, v130, v50
	v_dot8c_i32_i4_e32 v40, v132, v52
	v_dot8c_i32_i4_e32 v41, v132, v50
	v_dot8c_i32_i4_e32 v42, v134, v52
	v_dot8c_i32_i4_e32 v43, v134, v50
	v_dot8c_i32_i4_e32 v44, v136, v52
	v_dot8c_i32_i4_e32 v45, v136, v50
	v_dot8c_i32_i4_e32 v38, v131, v53
	v_dot8c_i32_i4_e32 v39, v131, v51
	v_dot8c_i32_i4_e32 v40, v133, v53
	v_dot8c_i32_i4_e32 v41, v133, v51
	v_dot8c_i32_i4_e32 v42, v135, v53
	v_dot8c_i32_i4_e32 v43, v135, v51
	v_dot8c_i32_i4_e32 v44, v137, v53
	v_dot8c_i32_i4_e32 v45, v137, v51
	v_and_b32_e32 v78, 0xffff, v29
	v_lshrrev_b32_e32 v79, 16, v29
	v_lshl_add_u32 v78, v78, 7, v152
	v_lshl_add_u32 v79, v79, 7, v153
	s_mov_b32 m0, s79
	s_add_i32 s43, s79, 0x400
	global_load_lds_dwordx4 v78, s[50:51]
	s_mov_b32 m0, s43
	s_nop 0
	global_load_lds_dwordx4 v79, s[50:51]
	s_waitcnt vmcnt(8)
	v_add_u32_e32 v54, s99, v59
	v_add_u32_e32 v55, s99, v60
	v_add_u32_e32 v56, s99, v61
	v_add_u32_e32 v57, s99, v62
	ds_read_b64_tr_b4 v[50:51], v160 offset:896
	ds_read_b64_tr_b4 v[52:53], v160 offset:1920
	ds_read_b64_tr_b4 v[130:131], v54
	ds_read_b64_tr_b4 v[132:133], v55
	ds_read_b64_tr_b4 v[134:135], v56
	ds_read_b64_tr_b4 v[136:137], v57
	s_waitcnt lgkmcnt(6)
	v_dot8c_i32_i4_e32 v38, v122, v48
	v_dot8c_i32_i4_e32 v39, v122, v46
	v_dot8c_i32_i4_e32 v40, v124, v48
	v_dot8c_i32_i4_e32 v41, v124, v46
	v_dot8c_i32_i4_e32 v42, v126, v48
	v_dot8c_i32_i4_e32 v43, v126, v46
	v_dot8c_i32_i4_e32 v44, v128, v48
	v_dot8c_i32_i4_e32 v45, v128, v46
	v_dot8c_i32_i4_e32 v38, v123, v49
	v_dot8c_i32_i4_e32 v39, v123, v47
	v_dot8c_i32_i4_e32 v40, v125, v49
	v_dot8c_i32_i4_e32 v41, v125, v47
	v_dot8c_i32_i4_e32 v42, v127, v49
	v_dot8c_i32_i4_e32 v43, v127, v47
	v_dot8c_i32_i4_e32 v44, v129, v49
	v_dot8c_i32_i4_e32 v45, v129, v47
	v_and_b32_e32 v78, 0xffff, v30
	v_lshrrev_b32_e32 v79, 16, v30
	v_lshl_add_u32 v78, v78, 7, v152
	v_lshl_add_u32 v79, v79, 7, v153
	s_mov_b32 m0, s98
	s_add_i32 s43, s98, 0x400
	global_load_lds_dwordx4 v78, s[50:51]
	s_mov_b32 m0, s43
	s_nop 0
	global_load_lds_dwordx4 v79, s[50:51]
	s_waitcnt vmcnt(8)
	v_add_u32_e32 v54, s76, v59
	v_add_u32_e32 v55, s76, v60
	v_add_u32_e32 v56, s76, v61
	v_add_u32_e32 v57, s76, v62
	ds_read_b64_tr_b4 v[46:47], v160
	ds_read_b64_tr_b4 v[48:49], v160 offset:1024
	ds_read_b64_tr_b4 v[122:123], v54
	ds_read_b64_tr_b4 v[124:125], v55
	ds_read_b64_tr_b4 v[126:127], v56
	ds_read_b64_tr_b4 v[128:129], v57
	s_waitcnt lgkmcnt(6)
	v_dot8c_i32_i4_e32 v38, v130, v52
	v_dot8c_i32_i4_e32 v39, v130, v50
	v_dot8c_i32_i4_e32 v40, v132, v52
	v_dot8c_i32_i4_e32 v41, v132, v50
	v_dot8c_i32_i4_e32 v42, v134, v52
	v_dot8c_i32_i4_e32 v43, v134, v50
	v_dot8c_i32_i4_e32 v44, v136, v52
	v_dot8c_i32_i4_e32 v45, v136, v50
	v_dot8c_i32_i4_e32 v38, v131, v53
	v_dot8c_i32_i4_e32 v39, v131, v51
	v_dot8c_i32_i4_e32 v40, v133, v53
	v_dot8c_i32_i4_e32 v41, v133, v51
	v_dot8c_i32_i4_e32 v42, v135, v53
	v_dot8c_i32_i4_e32 v43, v135, v51
	v_dot8c_i32_i4_e32 v44, v137, v53
	v_dot8c_i32_i4_e32 v45, v137, v51
	s_nop 3
	s_waitcnt lgkmcnt(15)
	v_lshlrev_b32_e32 v38, 5, v38
	v_lshlrev_b32_e32 v39, 1, v39
	v_add3_u32 v38, v39, v229, v38
	v_cvt_f32_i32_e32 v38, v38
	v_mul_f32_e32 v38, v228, v38
	v_lshlrev_b32_e32 v40, 5, v40
	v_lshlrev_b32_e32 v41, 1, v41
	v_add3_u32 v40, v41, v229, v40
	v_cvt_f32_i32_e32 v40, v40
	v_mul_f32_e32 v40, v228, v40
	v_lshlrev_b32_e32 v42, 5, v42
	v_lshlrev_b32_e32 v43, 1, v43
	v_add3_u32 v42, v43, v229, v42
	v_cvt_f32_i32_e32 v42, v42
	v_mul_f32_e32 v42, v228, v42
	v_lshlrev_b32_e32 v44, 5, v44
	v_lshlrev_b32_e32 v45, 1, v45
	v_add3_u32 v44, v45, v229, v44
	v_cvt_f32_i32_e32 v44, v44
	v_mul_f32_e32 v44, v228, v44
	v_cvt_pk_bf16_f32 v164, v38, v40
	v_cvt_pk_bf16_f32 v165, v42, v44
	v_add_u32_e32 v147, 8, v140
	v_and_b32_e32 v146, 15, v147
	v_xor_b32_e32 v146, 8, v146
	v_bfe_u32 v148, v147, 4, 4
	v_mul_lo_u32 v146, v146, s92
	v_mul_lo_u32 v148, v148, s92
	v_mov_b32_e32 v147, v146
	v_mov_b32_e32 v149, v148
	ds_write2st64_b64 v77, v[146:147], v[148:149] offset1:2
	v_mov_b32_e32 v138, v74
	ds_read_u8 v139, v138
	v_mov_b32_e32 v141, v73
	ds_read_u8 v140, v141
	s_add_i32 s43, s67, 32
	v_mov_b32_e32 v138, s43
	ds_read2st64_b32 v[228:229], v138 offset1:1
	ds_read_b128 v[18:21], v227
	ds_read_b128 v[22:25], v227 offset:16
	v_add_u32_e32 v150, 0x400000, v63
	v_add_u32_e32 v151, 0x400000, v64
	v_mov_b32_e32 v38, 0
	v_mov_b32_e32 v39, 0
	v_mov_b32_e32 v40, 0
	v_mov_b32_e32 v41, 0
	v_mov_b32_e32 v42, 0
	v_mov_b32_e32 v43, 0
	v_mov_b32_e32 v44, 0
	v_mov_b32_e32 v45, 0
	v_and_b32_e32 v78, 0xffff, v31
	v_lshrrev_b32_e32 v79, 16, v31
	v_lshl_add_u32 v78, v78, 7, v152
	v_lshl_add_u32 v79, v79, 7, v153
	s_mov_b32 m0, s99
	s_add_i32 s43, s99, 0x400
	global_load_lds_dwordx4 v78, s[50:51]
	s_mov_b32 m0, s43
	s_nop 0
	global_load_lds_dwordx4 v79, s[50:51]
	s_waitcnt vmcnt(8)
; __device__ __forceinline__ bf16 f2bf(float f) { return (bf16)f2bfu(f); }
; #define TR4(p_) __builtin_amdgcn_ds_read_tr4_b64_v2i32((LAS v2i*)(p_))
; #define VDMA(st_, k_) do { _Pragma("unroll") for (int i_ = 0; i_ < 4; ++i_) { \
;         const unsigned off_ = (unsigned)((st_) >> 2) * (16384u * 128u) + (PE_ID(E, 4 * ((st_) & 3) + i_) << 7) + ((i_ & 1) ? cx1 : cx0); \
;         __builtin_amdgcn_global_load_lds((const unsigned*)(V4 + off_), (LAS unsigned*)(ldsb + BUF[k_] + 1024 * i_), 16, 0, 0); } } while (0)
; __device__ __forceinline__ void peer_v_tokens(int j, const LAS unsigned short* EL, const LAS unsigned char* AL  , const LAS float* ASC  , const LAS int* SAL  , ...
;     ...
;         for (int st = 0; st < 16; ++st) {
;             const int p = st >> 2, q = st & 3;
;             if (st < 14) VDMA(st + 2, (st + 2) % 3);
;             if (st < 14) asm volatile("s_waitcnt vmcnt(8)" ::: "memory");
;             else if (st == 14) asm volatile("s_waitcnt vmcnt(4)" ::: "memory");
;             else asm volatile("s_waitcnt vmcnt(0)" ::: "memory");
;             if (q == 0) {
; #pragma unroll
;                 for (int r = 0; r < 4; ++r) { accH[r] = 0; accL[r] = 0; } }
; #pragma unroll
;             for (int tp = 0; tp < 2; ++tp) {
;                 const v2i ao = TR4(ATL + (2 * q + tp) * 128 + 8 * s16), ah = TR4(ATL + 1024 + (2 * q + tp) * 128 + 8 * s16);
; #pragma unroll
;                 for (int r = 0; r < 4; ++r) {
;                     const v2i d = TR4(ldsb + BUF[st % 3] + 2048 * tp + roff[r]);
;                     accH[r] = __builtin_amdgcn_sdot8(d.x, ah.x, accH[r], false); accH[r] = __builtin_amdgcn_sdot8(d.y, ah.y, accH[r], false);
;                     accL[r] = __builtin_amdgcn_sdot8(d.x, ao.x, accL[r], false); accL[r] = __builtin_amdgcn_sdot8(d.y, ao.y, accL[r], false);
;                 }
;             }
;             asm volatile("s_waitcnt lgkmcnt(0)" ::: "memory");
;             if (q == 3) {
; #pragma unroll
;                 for (int r = 0; r < 4; ++r) STASH[256 * p + 16 * (grp + 4 * r) + pc] = f2bf(asc * (float)(2 * ((accH[r] << 4) + accL[r]) + sa));
;             }
;         }
	v_add_u32_e32 v54, s77, v59
	v_add_u32_e32 v55, s77, v60
	v_add_u32_e32 v56, s77, v61
	v_add_u32_e32 v57, s77, v62
	ds_read_b64_tr_b4 v[50:51], v160 offset:128
	ds_read_b64_tr_b4 v[52:53], v160 offset:1152
	ds_read_b64_tr_b4 v[130:131], v54
	ds_read_b64_tr_b4 v[132:133], v55
	ds_read_b64_tr_b4 v[134:135], v56
	ds_read_b64_tr_b4 v[136:137], v57
	s_waitcnt lgkmcnt(12)
	v_dot8c_i32_i4_e32 v38, v122, v48
	v_dot8c_i32_i4_e32 v39, v122, v46
	v_dot8c_i32_i4_e32 v40, v124, v48
	v_dot8c_i32_i4_e32 v41, v124, v46
	v_dot8c_i32_i4_e32 v42, v126, v48
	v_dot8c_i32_i4_e32 v43, v126, v46
	v_dot8c_i32_i4_e32 v44, v128, v48
	v_dot8c_i32_i4_e32 v45, v128, v46
	v_dot8c_i32_i4_e32 v38, v123, v49
	v_dot8c_i32_i4_e32 v39, v123, v47
	v_dot8c_i32_i4_e32 v40, v125, v49
	v_dot8c_i32_i4_e32 v41, v125, v47
	v_dot8c_i32_i4_e32 v42, v127, v49
	v_dot8c_i32_i4_e32 v43, v127, v47
	v_dot8c_i32_i4_e32 v44, v129, v49
	v_dot8c_i32_i4_e32 v45, v129, v47
	v_and_b32_e32 v78, 0xffff, v32
	v_lshrrev_b32_e32 v79, 16, v32
	v_lshl_add_u32 v78, v78, 7, v152
	v_lshl_add_u32 v79, v79, 7, v153
	s_mov_b32 m0, s76
	s_add_i32 s43, s76, 0x400
	global_load_lds_dwordx4 v78, s[50:51]
	s_mov_b32 m0, s43
	s_nop 0
	global_load_lds_dwordx4 v79, s[50:51]
	s_waitcnt vmcnt(8)
	v_add_u32_e32 v54, s78, v59
	v_add_u32_e32 v55, s78, v60
	v_add_u32_e32 v56, s78, v61
	v_add_u32_e32 v57, s78, v62
	ds_read_b64_tr_b4 v[46:47], v160 offset:256
	ds_read_b64_tr_b4 v[48:49], v160 offset:1280
	ds_read_b64_tr_b4 v[122:123], v54
	ds_read_b64_tr_b4 v[124:125], v55
	ds_read_b64_tr_b4 v[126:127], v56
	ds_read_b64_tr_b4 v[128:129], v57
	s_waitcnt lgkmcnt(6)
	v_dot8c_i32_i4_e32 v38, v130, v52
	v_dot8c_i32_i4_e32 v39, v130, v50
	v_dot8c_i32_i4_e32 v40, v132, v52
	v_dot8c_i32_i4_e32 v41, v132, v50
	v_dot8c_i32_i4_e32 v42, v134, v52
	v_dot8c_i32_i4_e32 v43, v134, v50
	v_dot8c_i32_i4_e32 v44, v136, v52
	v_dot8c_i32_i4_e32 v45, v136, v50
	v_dot8c_i32_i4_e32 v38, v131, v53
	v_dot8c_i32_i4_e32 v39, v131, v51
	v_dot8c_i32_i4_e32 v40, v133, v53
	v_dot8c_i32_i4_e32 v41, v133, v51
	v_dot8c_i32_i4_e32 v42, v135, v53
	v_dot8c_i32_i4_e32 v43, v135, v51
	v_dot8c_i32_i4_e32 v44, v137, v53
	v_dot8c_i32_i4_e32 v45, v137, v51
	v_and_b32_e32 v78, 0xffff, v33
	v_lshrrev_b32_e32 v79, 16, v33
	v_lshl_add_u32 v78, v78, 7, v152
	v_lshl_add_u32 v79, v79, 7, v153
	s_mov_b32 m0, s77
	s_add_i32 s43, s77, 0x400
	global_load_lds_dwordx4 v78, s[50:51]
	s_mov_b32 m0, s43
	s_nop 0
	global_load_lds_dwordx4 v79, s[50:51]
	s_waitcnt vmcnt(8)
	v_add_u32_e32 v54, s79, v59
	v_add_u32_e32 v55, s79, v60
	v_add_u32_e32 v56, s79, v61
	v_add_u32_e32 v57, s79, v62
	ds_read_b64_tr_b4 v[50:51], v160 offset:384
	ds_read_b64_tr_b4 v[52:53], v160 offset:1408
	ds_read_b64_tr_b4 v[130:131], v54
	ds_read_b64_tr_b4 v[132:133], v55
	ds_read_b64_tr_b4 v[134:135], v56
	ds_read_b64_tr_b4 v[136:137], v57
	s_waitcnt lgkmcnt(6)
	v_dot8c_i32_i4_e32 v38, v122, v48
	v_dot8c_i32_i4_e32 v39, v122, v46
	v_dot8c_i32_i4_e32 v40, v124, v48
	v_dot8c_i32_i4_e32 v41, v124, v46
	v_dot8c_i32_i4_e32 v42, v126, v48
	v_dot8c_i32_i4_e32 v43, v126, v46
	v_dot8c_i32_i4_e32 v44, v128, v48
	v_dot8c_i32_i4_e32 v45, v128, v46
	v_dot8c_i32_i4_e32 v38, v123, v49
	v_dot8c_i32_i4_e32 v39, v123, v47
	v_dot8c_i32_i4_e32 v40, v125, v49
	v_dot8c_i32_i4_e32 v41, v125, v47
	v_dot8c_i32_i4_e32 v42, v127, v49
	v_dot8c_i32_i4_e32 v43, v127, v47
	v_dot8c_i32_i4_e32 v44, v129, v49
	v_dot8c_i32_i4_e32 v45, v129, v47
	s_waitcnt lgkmcnt(15)
	v_and_b32_e32 v78, 0xffff, v18
	v_lshrrev_b32_e32 v79, 16, v18
	v_lshl_add_u32 v78, v78, 7, v150
	v_lshl_add_u32 v79, v79, 7, v151
	s_mov_b32 m0, s78
	s_add_i32 s43, s78, 0x400
	global_load_lds_dwordx4 v78, s[50:51]
	s_mov_b32 m0, s43
	s_nop 0
	global_load_lds_dwordx4 v79, s[50:51]
	s_waitcnt vmcnt(8)
	v_add_u32_e32 v54, s98, v59
	v_add_u32_e32 v55, s98, v60
	v_add_u32_e32 v56, s98, v61
	v_add_u32_e32 v57, s98, v62
	ds_read_b64_tr_b4 v[46:47], v160 offset:512
	ds_read_b64_tr_b4 v[48:49], v160 offset:1536
	ds_read_b64_tr_b4 v[122:123], v54
	ds_read_b64_tr_b4 v[124:125], v55
	ds_read_b64_tr_b4 v[126:127], v56
	ds_read_b64_tr_b4 v[128:129], v57
	s_waitcnt lgkmcnt(6)
	v_dot8c_i32_i4_e32 v38, v130, v52
	v_dot8c_i32_i4_e32 v39, v130, v50
	v_dot8c_i32_i4_e32 v40, v132, v52
	v_dot8c_i32_i4_e32 v41, v132, v50
	v_dot8c_i32_i4_e32 v42, v134, v52
	v_dot8c_i32_i4_e32 v43, v134, v50
	v_dot8c_i32_i4_e32 v44, v136, v52
	v_dot8c_i32_i4_e32 v45, v136, v50
	v_dot8c_i32_i4_e32 v38, v131, v53
	v_dot8c_i32_i4_e32 v39, v131, v51
	v_dot8c_i32_i4_e32 v40, v133, v53
	v_dot8c_i32_i4_e32 v41, v133, v51
	v_dot8c_i32_i4_e32 v42, v135, v53
	v_dot8c_i32_i4_e32 v43, v135, v51
	v_dot8c_i32_i4_e32 v44, v137, v53
	v_dot8c_i32_i4_e32 v45, v137, v51
	v_and_b32_e32 v78, 0xffff, v19
	v_lshrrev_b32_e32 v79, 16, v19
	v_lshl_add_u32 v78, v78, 7, v150
	v_lshl_add_u32 v79, v79, 7, v151
	s_mov_b32 m0, s79
	s_add_i32 s43, s79, 0x400
	global_load_lds_dwordx4 v78, s[50:51]
	s_mov_b32 m0, s43
	s_nop 0
	global_load_lds_dwordx4 v79, s[50:51]
	s_waitcnt vmcnt(8)
	v_add_u32_e32 v54, s99, v59
	v_add_u32_e32 v55, s99, v60
	v_add_u32_e32 v56, s99, v61
	v_add_u32_e32 v57, s99, v62
	ds_read_b64_tr_b4 v[50:51], v160 offset:640
	ds_read_b64_tr_b4 v[52:53], v160 offset:1664
	ds_read_b64_tr_b4 v[130:131], v54
	ds_read_b64_tr_b4 v[132:133], v55
	ds_read_b64_tr_b4 v[134:135], v56
	ds_read_b64_tr_b4 v[136:137], v57
	s_waitcnt lgkmcnt(6)
	v_dot8c_i32_i4_e32 v38, v122, v48
	v_dot8c_i32_i4_e32 v39, v122, v46
	v_dot8c_i32_i4_e32 v40, v124, v48
	v_dot8c_i32_i4_e32 v41, v124, v46
	v_dot8c_i32_i4_e32 v42, v126, v48
	v_dot8c_i32_i4_e32 v43, v126, v46
	v_dot8c_i32_i4_e32 v44, v128, v48
	v_dot8c_i32_i4_e32 v45, v128, v46
	v_dot8c_i32_i4_e32 v38, v123, v49
	v_dot8c_i32_i4_e32 v39, v123, v47
	v_dot8c_i32_i4_e32 v40, v125, v49
	v_dot8c_i32_i4_e32 v41, v125, v47
	v_dot8c_i32_i4_e32 v42, v127, v49
	v_dot8c_i32_i4_e32 v43, v127, v47
	v_dot8c_i32_i4_e32 v44, v129, v49
	v_dot8c_i32_i4_e32 v45, v129, v47
	s_waitcnt lgkmcnt(15)
; __device__ __forceinline__ void peer_v_tokens(int j, const LAS unsigned short* EL, const LAS unsigned char* AL  , const LAS float* ASC  , const LAS int* SAL  , ...
;     ...
;         { const LAS v4u* ep = (const LAS v4u*)(EL + tl * 128 + 16 * g); const v4u e0 = ep[0], e1 = ep[1];
;           E[0] = e0.x; E[1] = e0.y; E[2] = e0.z; E[3] = e0.w; E[4] = e1.x; E[5] = e1.y; E[6] = e1.z; E[7] = e1.w; }
;         uint2 hv[4]; float4 gv[4];
;         { unsigned ho = (unsigned)t * (D / 4) + (unsigned)lane; asm volatile("" : "+v"(ho)); const uint2* hp = (const uint2*)HB + ho; const float4* gp = (const float4*)fng + lane;
; #pragma unroll
;           for (int jq = 0; jq < 4; ++jq) { hv[jq] = hp[64 * jq]; gv[jq] = gp[64 * jq]; } }
;         VDMA(0, 0); VDMA(1, 1);
; #pragma unroll
;         for (int m = 0; m < 2; ++m) {
;             const int idx = lane + 64 * m, tau = idx >> 4, sr = idx & 15, k = 16 * (sr & 7) + 2 * tau + (sr >> 3);
;             const int aq = (int)*(const LAS signed char*)(AL + tl * 128 + k); const int tq = aq + 8;
;             const unsigned lo = (((unsigned)tq & 15u) ^ 8u) * 0x11111111u, hi = ((unsigned)(tq >> 4) & 15u) * 0x11111111u;
;             typedef unsigned u2v __attribute__((ext_vector_type(2)));
;             u2v l2; l2.x = lo; l2.y = lo; u2v h2; h2.x = hi; h2.y = hi;
;             *(LAS u2v*)(ATL + 8 * idx) = l2; *(LAS u2v*)(ATL + 1024 + 8 * idx) = h2;
;         }
;         const float asc = ASC[tl]; const int sa = SAL[tl];
;         CFENCE();
;         int accH[4], accL[4];
; #pragma unroll
;         for (int st = 0; st < 16; ++st) {
;             const int p = st >> 2, q = st & 3;
;             if (st < 14) VDMA(st + 2, (st + 2) % 3);
;             if (st < 14) asm volatile("s_waitcnt vmcnt(8)" ::: "memory");
;             else if (st == 14) asm volatile("s_waitcnt vmcnt(4)" ::: "memory");
;             else asm volatile("s_waitcnt vmcnt(0)" ::: "memory");
;             if (q == 0) {
; #pragma unroll
;                 for (int r = 0; r < 4; ++r) { accH[r] = 0; accL[r] = 0; } }
; #pragma unroll
;             for (int tp = 0; tp < 2; ++tp) {
;                 const v2i ao = TR4(ATL + (2 * q + tp) * 128 + 8 * s16), ah = TR4(ATL + 1024 + (2 * q + tp) * 128 + 8 * s16);
; #pragma unroll
;                 for (int r = 0; r < 4; ++r) {
;                     const v2i d = TR4(ldsb + BUF[st % 3] + 2048 * tp + roff[r]);
	v_add_u32_e32 v143, 8, v139
	v_and_b32_e32 v142, 15, v143
	v_xor_b32_e32 v142, 8, v142
	v_bfe_u32 v144, v143, 4, 4
	v_mul_lo_u32 v142, v142, s92
	v_mul_lo_u32 v144, v144, s92
	v_mov_b32_e32 v143, v142
	v_mov_b32_e32 v145, v144
	ds_write2st64_b64 v159, v[142:143], v[144:145] offset1:2
	v_and_b32_e32 v78, 0xffff, v20
	v_lshrrev_b32_e32 v79, 16, v20
	v_lshl_add_u32 v78, v78, 7, v150
	v_lshl_add_u32 v79, v79, 7, v151
	s_mov_b32 m0, s98
	s_add_i32 s43, s98, 0x400
	global_load_lds_dwordx4 v78, s[50:51]
	s_mov_b32 m0, s43
	s_nop 0
	global_load_lds_dwordx4 v79, s[50:51]
	s_waitcnt vmcnt(8)
	v_add_u32_e32 v54, s76, v59
	v_add_u32_e32 v55, s76, v60
	v_add_u32_e32 v56, s76, v61
	v_add_u32_e32 v57, s76, v62
	ds_read_b64_tr_b4 v[46:47], v160 offset:768
	ds_read_b64_tr_b4 v[48:49], v160 offset:1792
	ds_read_b64_tr_b4 v[122:123], v54
	ds_read_b64_tr_b4 v[124:125], v55
	ds_read_b64_tr_b4 v[126:127], v56
	ds_read_b64_tr_b4 v[128:129], v57
	s_waitcnt lgkmcnt(7)
	v_dot8c_i32_i4_e32 v38, v130, v52
	v_dot8c_i32_i4_e32 v39, v130, v50
	v_dot8c_i32_i4_e32 v40, v132, v52
	v_dot8c_i32_i4_e32 v41, v132, v50
	v_dot8c_i32_i4_e32 v42, v134, v52
	v_dot8c_i32_i4_e32 v43, v134, v50
	v_dot8c_i32_i4_e32 v44, v136, v52
	v_dot8c_i32_i4_e32 v45, v136, v50
	v_dot8c_i32_i4_e32 v38, v131, v53
	v_dot8c_i32_i4_e32 v39, v131, v51
	v_dot8c_i32_i4_e32 v40, v133, v53
	v_dot8c_i32_i4_e32 v41, v133, v51
	v_dot8c_i32_i4_e32 v42, v135, v53
	v_dot8c_i32_i4_e32 v43, v135, v51
	v_dot8c_i32_i4_e32 v44, v137, v53
	v_dot8c_i32_i4_e32 v45, v137, v51
	v_and_b32_e32 v78, 0xffff, v21
	v_lshrrev_b32_e32 v79, 16, v21
	v_lshl_add_u32 v78, v78, 7, v150
	v_lshl_add_u32 v79, v79, 7, v151
	s_mov_b32 m0, s99
	s_add_i32 s43, s99, 0x400
	global_load_lds_dwordx4 v78, s[50:51]
	s_mov_b32 m0, s43
	s_nop 0
	global_load_lds_dwordx4 v79, s[50:51]
	s_waitcnt vmcnt(8)
	v_add_u32_e32 v54, s77, v59
	v_add_u32_e32 v55, s77, v60
	v_add_u32_e32 v56, s77, v61
	v_add_u32_e32 v57, s77, v62
	ds_read_b64_tr_b4 v[50:51], v160 offset:896
	ds_read_b64_tr_b4 v[52:53], v160 offset:1920
	ds_read_b64_tr_b4 v[130:131], v54
	ds_read_b64_tr_b4 v[132:133], v55
	ds_read_b64_tr_b4 v[134:135], v56
	ds_read_b64_tr_b4 v[136:137], v57
	s_waitcnt lgkmcnt(6)
	v_dot8c_i32_i4_e32 v38, v122, v48
	v_dot8c_i32_i4_e32 v39, v122, v46
	v_dot8c_i32_i4_e32 v40, v124, v48
	v_dot8c_i32_i4_e32 v41, v124, v46
	v_dot8c_i32_i4_e32 v42, v126, v48
	v_dot8c_i32_i4_e32 v43, v126, v46
	v_dot8c_i32_i4_e32 v44, v128, v48
	v_dot8c_i32_i4_e32 v45, v128, v46
	v_dot8c_i32_i4_e32 v38, v123, v49
	v_dot8c_i32_i4_e32 v39, v123, v47
	v_dot8c_i32_i4_e32 v40, v125, v49
	v_dot8c_i32_i4_e32 v41, v125, v47
	v_dot8c_i32_i4_e32 v42, v127, v49
	v_dot8c_i32_i4_e32 v43, v127, v47
	v_dot8c_i32_i4_e32 v44, v129, v49
	v_dot8c_i32_i4_e32 v45, v129, v47
	v_and_b32_e32 v78, 0xffff, v22
	v_lshrrev_b32_e32 v79, 16, v22
	v_lshl_add_u32 v78, v78, 7, v150
	v_lshl_add_u32 v79, v79, 7, v151
	s_mov_b32 m0, s76
	s_add_i32 s43, s76, 0x400
	global_load_lds_dwordx4 v78, s[50:51]
	s_mov_b32 m0, s43
	s_nop 0
	global_load_lds_dwordx4 v79, s[50:51]
	s_waitcnt vmcnt(8)
	v_add_u32_e32 v54, s78, v59
	v_add_u32_e32 v55, s78, v60
	v_add_u32_e32 v56, s78, v61
	v_add_u32_e32 v57, s78, v62
	ds_read_b64_tr_b4 v[46:47], v160
	ds_read_b64_tr_b4 v[48:49], v160 offset:1024
	ds_read_b64_tr_b4 v[122:123], v54
	ds_read_b64_tr_b4 v[124:125], v55
	ds_read_b64_tr_b4 v[126:127], v56
	ds_read_b64_tr_b4 v[128:129], v57
	s_waitcnt lgkmcnt(6)
	v_dot8c_i32_i4_e32 v38, v130, v52
	v_dot8c_i32_i4_e32 v39, v130, v50
	v_dot8c_i32_i4_e32 v40, v132, v52
	v_dot8c_i32_i4_e32 v41, v132, v50
	v_dot8c_i32_i4_e32 v42, v134, v52
	v_dot8c_i32_i4_e32 v43, v134, v50
	v_dot8c_i32_i4_e32 v44, v136, v52
	v_dot8c_i32_i4_e32 v45, v136, v50
	v_dot8c_i32_i4_e32 v38, v131, v53
	v_dot8c_i32_i4_e32 v39, v131, v51
	v_dot8c_i32_i4_e32 v40, v133, v53
	v_dot8c_i32_i4_e32 v41, v133, v51
	v_dot8c_i32_i4_e32 v42, v135, v53
	v_dot8c_i32_i4_e32 v43, v135, v51
	v_dot8c_i32_i4_e32 v44, v137, v53
	v_dot8c_i32_i4_e32 v45, v137, v51
	s_nop 3
	s_waitcnt lgkmcnt(15)
	v_lshlrev_b32_e32 v38, 5, v38
	v_lshlrev_b32_e32 v39, 1, v39
	v_add3_u32 v38, v39, v229, v38
	v_cvt_f32_i32_e32 v38, v38
	v_mul_f32_e32 v38, v228, v38
	v_lshlrev_b32_e32 v40, 5, v40
	v_lshlrev_b32_e32 v41, 1, v41
	v_add3_u32 v40, v41, v229, v40
	v_cvt_f32_i32_e32 v40, v40
	v_mul_f32_e32 v40, v228, v40
	v_lshlrev_b32_e32 v42, 5, v42
	v_lshlrev_b32_e32 v43, 1, v43
	v_add3_u32 v42, v43, v229, v42
	v_cvt_f32_i32_e32 v42, v42
	v_mul_f32_e32 v42, v228, v42
	v_lshlrev_b32_e32 v44, 5, v44
	v_lshlrev_b32_e32 v45, 1, v45
	v_add3_u32 v44, v45, v229, v44
	v_cvt_f32_i32_e32 v44, v44
	v_mul_f32_e32 v44, v228, v44
	v_cvt_pk_bf16_f32 v172, v38, v40
	v_cvt_pk_bf16_f32 v173, v42, v44
	v_add_u32_e32 v147, 8, v140
	v_and_b32_e32 v146, 15, v147
	v_xor_b32_e32 v146, 8, v146
	v_bfe_u32 v148, v147, 4, 4
	v_mul_lo_u32 v146, v146, s92
	v_mul_lo_u32 v148, v148, s92
	v_mov_b32_e32 v147, v146
	v_mov_b32_e32 v149, v148
	ds_write2st64_b64 v77, v[146:147], v[148:149] offset1:2
	v_add_u32_e32 v138, 0x400, v74
	ds_read_u8 v139, v138
	v_add_u32_e32 v141, 0x400, v73
	ds_read_u8 v140, v141
	s_mov_b32 s43, s67
	v_mov_b32_e32 v138, s43
	ds_read2st64_b32 v[228:229], v138 offset1:1
	ds_read_b128 v[26:29], v227 offset:2048
	ds_read_b128 v[30:33], v227 offset:2064
	v_mov_b32_e32 v38, 0
	v_mov_b32_e32 v39, 0
	v_mov_b32_e32 v40, 0
	v_mov_b32_e32 v41, 0
	v_mov_b32_e32 v42, 0
	v_mov_b32_e32 v43, 0
	v_mov_b32_e32 v44, 0
	v_mov_b32_e32 v45, 0
	v_and_b32_e32 v78, 0xffff, v23
	v_lshrrev_b32_e32 v79, 16, v23
	v_lshl_add_u32 v78, v78, 7, v150
	v_lshl_add_u32 v79, v79, 7, v151
	s_mov_b32 m0, s77
	s_add_i32 s43, s77, 0x400
	global_load_lds_dwordx4 v78, s[50:51]
	s_mov_b32 m0, s43
	s_nop 0
	global_load_lds_dwordx4 v79, s[50:51]
	s_waitcnt vmcnt(8)
; __device__ __forceinline__ bf16 f2bf(float f) { return (bf16)f2bfu(f); }
; #define TR4(p_) __builtin_amdgcn_ds_read_tr4_b64_v2i32((LAS v2i*)(p_))
; #define VDMA(st_, k_) do { _Pragma("unroll") for (int i_ = 0; i_ < 4; ++i_) { \
;         const unsigned off_ = (unsigned)((st_) >> 2) * (16384u * 128u) + (PE_ID(E, 4 * ((st_) & 3) + i_) << 7) + ((i_ & 1) ? cx1 : cx0); \
;         __builtin_amdgcn_global_load_lds((const unsigned*)(V4 + off_), (LAS unsigned*)(ldsb + BUF[k_] + 1024 * i_), 16, 0, 0); } } while (0)
; __device__ __forceinline__ void peer_v_tokens(int j, const LAS unsigned short* EL, const LAS unsigned char* AL  , const LAS float* ASC  , const LAS int* SAL  , ...
;     ...
;         for (int st = 0; st < 16; ++st) {
;             const int p = st >> 2, q = st & 3;
;             if (st < 14) VDMA(st + 2, (st + 2) % 3);
;             if (st < 14) asm volatile("s_waitcnt vmcnt(8)" ::: "memory");
;             else if (st == 14) asm volatile("s_waitcnt vmcnt(4)" ::: "memory");
;             else asm volatile("s_waitcnt vmcnt(0)" ::: "memory");
;             if (q == 0) {
; #pragma unroll
;                 for (int r = 0; r < 4; ++r) { accH[r] = 0; accL[r] = 0; } }
; #pragma unroll
;             for (int tp = 0; tp < 2; ++tp) {
;                 const v2i ao = TR4(ATL + (2 * q + tp) * 128 + 8 * s16), ah = TR4(ATL + 1024 + (2 * q + tp) * 128 + 8 * s16);
; #pragma unroll
;                 for (int r = 0; r < 4; ++r) {
;                     const v2i d = TR4(ldsb + BUF[st % 3] + 2048 * tp + roff[r]);
;                     accH[r] = __builtin_amdgcn_sdot8(d.x, ah.x, accH[r], false); accH[r] = __builtin_amdgcn_sdot8(d.y, ah.y, accH[r], false);
;                     accL[r] = __builtin_amdgcn_sdot8(d.x, ao.x, accL[r], false); accL[r] = __builtin_amdgcn_sdot8(d.y, ao.y, accL[r], false);
;                 }
;             }
;             asm volatile("s_waitcnt lgkmcnt(0)" ::: "memory");
;             if (q == 3) {
; #pragma unroll
;                 for (int r = 0; r < 4; ++r) STASH[256 * p + 16 * (grp + 4 * r) + pc] = f2bf(asc * (float)(2 * ((accH[r] << 4) + accL[r]) + sa));
;             }
;         }
	v_add_u32_e32 v54, s79, v59
	v_add_u32_e32 v55, s79, v60
	v_add_u32_e32 v56, s79, v61
	v_add_u32_e32 v57, s79, v62
	ds_read_b64_tr_b4 v[50:51], v160 offset:128
	ds_read_b64_tr_b4 v[52:53], v160 offset:1152
	ds_read_b64_tr_b4 v[130:131], v54
	ds_read_b64_tr_b4 v[132:133], v55
	ds_read_b64_tr_b4 v[134:135], v56
	ds_read_b64_tr_b4 v[136:137], v57
	s_waitcnt lgkmcnt(12)
	v_dot8c_i32_i4_e32 v38, v122, v48
	v_dot8c_i32_i4_e32 v39, v122, v46
	v_dot8c_i32_i4_e32 v40, v124, v48
	v_dot8c_i32_i4_e32 v41, v124, v46
	v_dot8c_i32_i4_e32 v42, v126, v48
	v_dot8c_i32_i4_e32 v43, v126, v46
	v_dot8c_i32_i4_e32 v44, v128, v48
	v_dot8c_i32_i4_e32 v45, v128, v46
	v_dot8c_i32_i4_e32 v38, v123, v49
	v_dot8c_i32_i4_e32 v39, v123, v47
	v_dot8c_i32_i4_e32 v40, v125, v49
	v_dot8c_i32_i4_e32 v41, v125, v47
	v_dot8c_i32_i4_e32 v42, v127, v49
	v_dot8c_i32_i4_e32 v43, v127, v47
	v_dot8c_i32_i4_e32 v44, v129, v49
	v_dot8c_i32_i4_e32 v45, v129, v47
	v_and_b32_e32 v78, 0xffff, v24
	v_lshrrev_b32_e32 v79, 16, v24
	v_lshl_add_u32 v78, v78, 7, v150
	v_lshl_add_u32 v79, v79, 7, v151
	s_mov_b32 m0, s78
	s_add_i32 s43, s78, 0x400
	global_load_lds_dwordx4 v78, s[50:51]
	s_mov_b32 m0, s43
	s_nop 0
	global_load_lds_dwordx4 v79, s[50:51]
	s_waitcnt vmcnt(8)
	v_add_u32_e32 v54, s98, v59
	v_add_u32_e32 v55, s98, v60
	v_add_u32_e32 v56, s98, v61
	v_add_u32_e32 v57, s98, v62
	ds_read_b64_tr_b4 v[46:47], v160 offset:256
	ds_read_b64_tr_b4 v[48:49], v160 offset:1280
	ds_read_b64_tr_b4 v[122:123], v54
	ds_read_b64_tr_b4 v[124:125], v55
	ds_read_b64_tr_b4 v[126:127], v56
	ds_read_b64_tr_b4 v[128:129], v57
	s_waitcnt lgkmcnt(6)
	v_dot8c_i32_i4_e32 v38, v130, v52
	v_dot8c_i32_i4_e32 v39, v130, v50
	v_dot8c_i32_i4_e32 v40, v132, v52
	v_dot8c_i32_i4_e32 v41, v132, v50
	v_dot8c_i32_i4_e32 v42, v134, v52
	v_dot8c_i32_i4_e32 v43, v134, v50
	v_dot8c_i32_i4_e32 v44, v136, v52
	v_dot8c_i32_i4_e32 v45, v136, v50
	v_dot8c_i32_i4_e32 v38, v131, v53
	v_dot8c_i32_i4_e32 v39, v131, v51
	v_dot8c_i32_i4_e32 v40, v133, v53
	v_dot8c_i32_i4_e32 v41, v133, v51
	v_dot8c_i32_i4_e32 v42, v135, v53
	v_dot8c_i32_i4_e32 v43, v135, v51
	v_dot8c_i32_i4_e32 v44, v137, v53
	v_dot8c_i32_i4_e32 v45, v137, v51
	v_and_b32_e32 v78, 0xffff, v25
	v_lshrrev_b32_e32 v79, 16, v25
	v_lshl_add_u32 v78, v78, 7, v150
	v_lshl_add_u32 v79, v79, 7, v151
	s_mov_b32 m0, s79
	s_add_i32 s43, s79, 0x400
	global_load_lds_dwordx4 v78, s[50:51]
	s_mov_b32 m0, s43
	s_nop 0
	global_load_lds_dwordx4 v79, s[50:51]
	s_waitcnt vmcnt(8)
	v_add_u32_e32 v54, s99, v59
	v_add_u32_e32 v55, s99, v60
	v_add_u32_e32 v56, s99, v61
	v_add_u32_e32 v57, s99, v62
	ds_read_b64_tr_b4 v[50:51], v160 offset:384
	ds_read_b64_tr_b4 v[52:53], v160 offset:1408
	ds_read_b64_tr_b4 v[130:131], v54
	ds_read_b64_tr_b4 v[132:133], v55
	ds_read_b64_tr_b4 v[134:135], v56
	ds_read_b64_tr_b4 v[136:137], v57
	s_waitcnt lgkmcnt(6)
	v_dot8c_i32_i4_e32 v38, v122, v48
	v_dot8c_i32_i4_e32 v39, v122, v46
	v_dot8c_i32_i4_e32 v40, v124, v48
	v_dot8c_i32_i4_e32 v41, v124, v46
	v_dot8c_i32_i4_e32 v42, v126, v48
	v_dot8c_i32_i4_e32 v43, v126, v46
	v_dot8c_i32_i4_e32 v44, v128, v48
	v_dot8c_i32_i4_e32 v45, v128, v46
	v_dot8c_i32_i4_e32 v38, v123, v49
	v_dot8c_i32_i4_e32 v39, v123, v47
	v_dot8c_i32_i4_e32 v40, v125, v49
	v_dot8c_i32_i4_e32 v41, v125, v47
	v_dot8c_i32_i4_e32 v42, v127, v49
	v_dot8c_i32_i4_e32 v43, v127, v47
	v_dot8c_i32_i4_e32 v44, v129, v49
	v_dot8c_i32_i4_e32 v45, v129, v47
	s_waitcnt lgkmcnt(15)
	v_and_b32_e32 v78, 0xffff, v26
	v_lshrrev_b32_e32 v79, 16, v26
	v_lshl_add_u32 v78, v78, 7, v150
	v_lshl_add_u32 v79, v79, 7, v151
	s_mov_b32 m0, s98
	s_add_i32 s43, s98, 0x400
	global_load_lds_dwordx4 v78, s[50:51]
	s_mov_b32 m0, s43
	s_nop 0
	global_load_lds_dwordx4 v79, s[50:51]
	s_waitcnt vmcnt(8)
	v_add_u32_e32 v54, s76, v59
	v_add_u32_e32 v55, s76, v60
	v_add_u32_e32 v56, s76, v61
	v_add_u32_e32 v57, s76, v62
	ds_read_b64_tr_b4 v[46:47], v160 offset:512
	ds_read_b64_tr_b4 v[48:49], v160 offset:1536
	ds_read_b64_tr_b4 v[122:123], v54
	ds_read_b64_tr_b4 v[124:125], v55
	ds_read_b64_tr_b4 v[126:127], v56
	ds_read_b64_tr_b4 v[128:129], v57
	s_waitcnt lgkmcnt(6)
	v_dot8c_i32_i4_e32 v38, v130, v52
	v_dot8c_i32_i4_e32 v39, v130, v50
	v_dot8c_i32_i4_e32 v40, v132, v52
	v_dot8c_i32_i4_e32 v41, v132, v50
	v_dot8c_i32_i4_e32 v42, v134, v52
	v_dot8c_i32_i4_e32 v43, v134, v50
	v_dot8c_i32_i4_e32 v44, v136, v52
	v_dot8c_i32_i4_e32 v45, v136, v50
	v_dot8c_i32_i4_e32 v38, v131, v53
	v_dot8c_i32_i4_e32 v39, v131, v51
	v_dot8c_i32_i4_e32 v40, v133, v53
	v_dot8c_i32_i4_e32 v41, v133, v51
	v_dot8c_i32_i4_e32 v42, v135, v53
	v_dot8c_i32_i4_e32 v43, v135, v51
	v_dot8c_i32_i4_e32 v44, v137, v53
	v_dot8c_i32_i4_e32 v45, v137, v51
	v_and_b32_e32 v78, 0xffff, v27
	v_lshrrev_b32_e32 v79, 16, v27
	v_lshl_add_u32 v78, v78, 7, v150
	v_lshl_add_u32 v79, v79, 7, v151
	s_mov_b32 m0, s99
	s_add_i32 s43, s99, 0x400
	global_load_lds_dwordx4 v78, s[50:51]
	s_mov_b32 m0, s43
	s_nop 0
	global_load_lds_dwordx4 v79, s[50:51]
	s_waitcnt vmcnt(8)
	v_add_u32_e32 v54, s77, v59
	v_add_u32_e32 v55, s77, v60
	v_add_u32_e32 v56, s77, v61
	v_add_u32_e32 v57, s77, v62
	ds_read_b64_tr_b4 v[50:51], v160 offset:640
	ds_read_b64_tr_b4 v[52:53], v160 offset:1664
	ds_read_b64_tr_b4 v[130:131], v54
	ds_read_b64_tr_b4 v[132:133], v55
	ds_read_b64_tr_b4 v[134:135], v56
	ds_read_b64_tr_b4 v[136:137], v57
	s_waitcnt lgkmcnt(6)
	v_dot8c_i32_i4_e32 v38, v122, v48
	v_dot8c_i32_i4_e32 v39, v122, v46
	v_dot8c_i32_i4_e32 v40, v124, v48
	v_dot8c_i32_i4_e32 v41, v124, v46
	v_dot8c_i32_i4_e32 v42, v126, v48
	v_dot8c_i32_i4_e32 v43, v126, v46
	v_dot8c_i32_i4_e32 v44, v128, v48
	v_dot8c_i32_i4_e32 v45, v128, v46
	v_dot8c_i32_i4_e32 v38, v123, v49
	v_dot8c_i32_i4_e32 v39, v123, v47
	v_dot8c_i32_i4_e32 v40, v125, v49
	v_dot8c_i32_i4_e32 v41, v125, v47
	v_dot8c_i32_i4_e32 v42, v127, v49
	v_dot8c_i32_i4_e32 v43, v127, v47
	v_dot8c_i32_i4_e32 v44, v129, v49
	v_dot8c_i32_i4_e32 v45, v129, v47
	s_waitcnt lgkmcnt(15)
; __device__ __forceinline__ void peer_v_tokens(int j, const LAS unsigned short* EL, const LAS unsigned char* AL  , const LAS float* ASC  , const LAS int* SAL  , ...
;     ...
;         { const LAS v4u* ep = (const LAS v4u*)(EL + tl * 128 + 16 * g); const v4u e0 = ep[0], e1 = ep[1];
;           E[0] = e0.x; E[1] = e0.y; E[2] = e0.z; E[3] = e0.w; E[4] = e1.x; E[5] = e1.y; E[6] = e1.z; E[7] = e1.w; }
;         uint2 hv[4]; float4 gv[4];
;         { unsigned ho = (unsigned)t * (D / 4) + (unsigned)lane; asm volatile("" : "+v"(ho)); const uint2* hp = (const uint2*)HB + ho; const float4* gp = (const float4*)fng + lane;
; #pragma unroll
;           for (int jq = 0; jq < 4; ++jq) { hv[jq] = hp[64 * jq]; gv[jq] = gp[64 * jq]; } }
;         VDMA(0, 0); VDMA(1, 1);
; #pragma unroll
;         for (int m = 0; m < 2; ++m) {
;             const int idx = lane + 64 * m, tau = idx >> 4, sr = idx & 15, k = 16 * (sr & 7) + 2 * tau + (sr >> 3);
;             const int aq = (int)*(const LAS signed char*)(AL + tl * 128 + k); const int tq = aq + 8;
;             const unsigned lo = (((unsigned)tq & 15u) ^ 8u) * 0x11111111u, hi = ((unsigned)(tq >> 4) & 15u) * 0x11111111u;
;             typedef unsigned u2v __attribute__((ext_vector_type(2)));
;             u2v l2; l2.x = lo; l2.y = lo; u2v h2; h2.x = hi; h2.y = hi;
;             *(LAS u2v*)(ATL + 8 * idx) = l2; *(LAS u2v*)(ATL + 1024 + 8 * idx) = h2;
;         }
;         const float asc = ASC[tl]; const int sa = SAL[tl];
;         CFENCE();
;         int accH[4], accL[4];
; #pragma unroll
;         for (int st = 0; st < 16; ++st) {
;             const int p = st >> 2, q = st & 3;
;             if (st < 14) VDMA(st + 2, (st + 2) % 3);
;             if (st < 14) asm volatile("s_waitcnt vmcnt(8)" ::: "memory");
;             else if (st == 14) asm volatile("s_waitcnt vmcnt(4)" ::: "memory");
;             else asm volatile("s_waitcnt vmcnt(0)" ::: "memory");
;             if (q == 0) {
; #pragma unroll
;                 for (int r = 0; r < 4; ++r) { accH[r] = 0; accL[r] = 0; } }
; #pragma unroll
;             for (int tp = 0; tp < 2; ++tp) {
;                 const v2i ao = TR4(ATL + (2 * q + tp) * 128 + 8 * s16), ah = TR4(ATL + 1024 + (2 * q + tp) * 128 + 8 * s16);
; #pragma unroll
;                 for (int r = 0; r < 4; ++r) {
;                     const v2i d = TR4(ldsb + BUF[st % 3] + 2048 * tp + roff[r]);
	v_add_u32_e32 v143, 8, v139
	v_and_b32_e32 v142, 15, v143
	v_xor_b32_e32 v142, 8, v142
	v_bfe_u32 v144, v143, 4, 4
	v_mul_lo_u32 v142, v142, s92
	v_mul_lo_u32 v144, v144, s92
	v_mov_b32_e32 v143, v142
	v_mov_b32_e32 v145, v144
	ds_write2st64_b64 v159, v[142:143], v[144:145] offset1:2
	v_and_b32_e32 v78, 0xffff, v28
	v_lshrrev_b32_e32 v79, 16, v28
	v_lshl_add_u32 v78, v78, 7, v150
	v_lshl_add_u32 v79, v79, 7, v151
	s_mov_b32 m0, s76
	s_add_i32 s43, s76, 0x400
	global_load_lds_dwordx4 v78, s[50:51]
	s_mov_b32 m0, s43
	s_nop 0
	global_load_lds_dwordx4 v79, s[50:51]
	s_waitcnt vmcnt(8)
	v_add_u32_e32 v54, s78, v59
	v_add_u32_e32 v55, s78, v60
	v_add_u32_e32 v56, s78, v61
	v_add_u32_e32 v57, s78, v62
	ds_read_b64_tr_b4 v[46:47], v160 offset:768
	ds_read_b64_tr_b4 v[48:49], v160 offset:1792
	ds_read_b64_tr_b4 v[122:123], v54
	ds_read_b64_tr_b4 v[124:125], v55
	ds_read_b64_tr_b4 v[126:127], v56
	ds_read_b64_tr_b4 v[128:129], v57
	s_waitcnt lgkmcnt(7)
	v_dot8c_i32_i4_e32 v38, v130, v52
	v_dot8c_i32_i4_e32 v39, v130, v50
	v_dot8c_i32_i4_e32 v40, v132, v52
	v_dot8c_i32_i4_e32 v41, v132, v50
	v_dot8c_i32_i4_e32 v42, v134, v52
	v_dot8c_i32_i4_e32 v43, v134, v50
	v_dot8c_i32_i4_e32 v44, v136, v52
	v_dot8c_i32_i4_e32 v45, v136, v50
	v_dot8c_i32_i4_e32 v38, v131, v53
	v_dot8c_i32_i4_e32 v39, v131, v51
	v_dot8c_i32_i4_e32 v40, v133, v53
	v_dot8c_i32_i4_e32 v41, v133, v51
	v_dot8c_i32_i4_e32 v42, v135, v53
	v_dot8c_i32_i4_e32 v43, v135, v51
	v_dot8c_i32_i4_e32 v44, v137, v53
	v_dot8c_i32_i4_e32 v45, v137, v51
	v_and_b32_e32 v78, 0xffff, v29
	v_lshrrev_b32_e32 v79, 16, v29
	v_lshl_add_u32 v78, v78, 7, v150
	v_lshl_add_u32 v79, v79, 7, v151
	s_mov_b32 m0, s77
	s_add_i32 s43, s77, 0x400
	global_load_lds_dwordx4 v78, s[50:51]
	s_mov_b32 m0, s43
	s_nop 0
	global_load_lds_dwordx4 v79, s[50:51]
	s_waitcnt vmcnt(8)
	v_add_u32_e32 v54, s79, v59
	v_add_u32_e32 v55, s79, v60
	v_add_u32_e32 v56, s79, v61
	v_add_u32_e32 v57, s79, v62
	ds_read_b64_tr_b4 v[50:51], v160 offset:896
	ds_read_b64_tr_b4 v[52:53], v160 offset:1920
	ds_read_b64_tr_b4 v[130:131], v54
	ds_read_b64_tr_b4 v[132:133], v55
	ds_read_b64_tr_b4 v[134:135], v56
	ds_read_b64_tr_b4 v[136:137], v57
	s_waitcnt lgkmcnt(6)
	v_dot8c_i32_i4_e32 v38, v122, v48
	v_dot8c_i32_i4_e32 v39, v122, v46
	v_dot8c_i32_i4_e32 v40, v124, v48
	v_dot8c_i32_i4_e32 v41, v124, v46
	v_dot8c_i32_i4_e32 v42, v126, v48
	v_dot8c_i32_i4_e32 v43, v126, v46
	v_dot8c_i32_i4_e32 v44, v128, v48
	v_dot8c_i32_i4_e32 v45, v128, v46
	v_dot8c_i32_i4_e32 v38, v123, v49
	v_dot8c_i32_i4_e32 v39, v123, v47
	v_dot8c_i32_i4_e32 v40, v125, v49
	v_dot8c_i32_i4_e32 v41, v125, v47
	v_dot8c_i32_i4_e32 v42, v127, v49
	v_dot8c_i32_i4_e32 v43, v127, v47
	v_dot8c_i32_i4_e32 v44, v129, v49
	v_dot8c_i32_i4_e32 v45, v129, v47
	v_and_b32_e32 v78, 0xffff, v30
	v_lshrrev_b32_e32 v79, 16, v30
	v_lshl_add_u32 v78, v78, 7, v150
	v_lshl_add_u32 v79, v79, 7, v151
	s_mov_b32 m0, s78
	s_add_i32 s43, s78, 0x400
	global_load_lds_dwordx4 v78, s[50:51]
	s_mov_b32 m0, s43
	s_nop 0
	global_load_lds_dwordx4 v79, s[50:51]
	s_waitcnt vmcnt(8)
	v_add_u32_e32 v54, s98, v59
	v_add_u32_e32 v55, s98, v60
	v_add_u32_e32 v56, s98, v61
	v_add_u32_e32 v57, s98, v62
	ds_read_b64_tr_b4 v[46:47], v160
	ds_read_b64_tr_b4 v[48:49], v160 offset:1024
	ds_read_b64_tr_b4 v[122:123], v54
	ds_read_b64_tr_b4 v[124:125], v55
	ds_read_b64_tr_b4 v[126:127], v56
	ds_read_b64_tr_b4 v[128:129], v57
	s_waitcnt lgkmcnt(6)
	v_dot8c_i32_i4_e32 v38, v130, v52
	v_dot8c_i32_i4_e32 v39, v130, v50
	v_dot8c_i32_i4_e32 v40, v132, v52
	v_dot8c_i32_i4_e32 v41, v132, v50
	v_dot8c_i32_i4_e32 v42, v134, v52
	v_dot8c_i32_i4_e32 v43, v134, v50
	v_dot8c_i32_i4_e32 v44, v136, v52
	v_dot8c_i32_i4_e32 v45, v136, v50
	v_dot8c_i32_i4_e32 v38, v131, v53
	v_dot8c_i32_i4_e32 v39, v131, v51
	v_dot8c_i32_i4_e32 v40, v133, v53
	v_dot8c_i32_i4_e32 v41, v133, v51
	v_dot8c_i32_i4_e32 v42, v135, v53
	v_dot8c_i32_i4_e32 v43, v135, v51
	v_dot8c_i32_i4_e32 v44, v137, v53
	v_dot8c_i32_i4_e32 v45, v137, v51
	s_nop 3
	s_waitcnt lgkmcnt(15)
	v_lshlrev_b32_e32 v38, 5, v38
	v_lshlrev_b32_e32 v39, 1, v39
	v_add3_u32 v38, v39, v229, v38
	v_cvt_f32_i32_e32 v38, v38
	v_mul_f32_e32 v38, v228, v38
	v_lshlrev_b32_e32 v40, 5, v40
	v_lshlrev_b32_e32 v41, 1, v41
	v_add3_u32 v40, v41, v229, v40
	v_cvt_f32_i32_e32 v40, v40
	v_mul_f32_e32 v40, v228, v40
	v_lshlrev_b32_e32 v42, 5, v42
	v_lshlrev_b32_e32 v43, 1, v43
	v_add3_u32 v42, v43, v229, v42
	v_cvt_f32_i32_e32 v42, v42
	v_mul_f32_e32 v42, v228, v42
	v_lshlrev_b32_e32 v44, 5, v44
	v_lshlrev_b32_e32 v45, 1, v45
	v_add3_u32 v44, v45, v229, v44
	v_cvt_f32_i32_e32 v44, v44
	v_mul_f32_e32 v44, v228, v44
	v_cvt_pk_bf16_f32 v166, v38, v40
	v_cvt_pk_bf16_f32 v167, v42, v44
	v_add_u32_e32 v147, 8, v140
	v_and_b32_e32 v146, 15, v147
	v_xor_b32_e32 v146, 8, v146
	v_bfe_u32 v148, v147, 4, 4
	v_mul_lo_u32 v146, v146, s92
	v_mul_lo_u32 v148, v148, s92
	v_mov_b32_e32 v147, v146
	v_mov_b32_e32 v149, v148
	ds_write2st64_b64 v77, v[146:147], v[148:149] offset1:2
	v_mov_b32_e32 v138, v74
	ds_read_u8 v139, v138
	v_mov_b32_e32 v141, v73
	ds_read_u8 v140, v141
	s_add_i32 s43, s67, 32
	v_mov_b32_e32 v138, s43
	ds_read2st64_b32 v[228:229], v138 offset1:1
	ds_read_b128 v[18:21], v227
	ds_read_b128 v[22:25], v227 offset:16
	v_add_u32_e32 v152, 0x600000, v63
	v_add_u32_e32 v153, 0x600000, v64
	v_mov_b32_e32 v38, 0
	v_mov_b32_e32 v39, 0
	v_mov_b32_e32 v40, 0
	v_mov_b32_e32 v41, 0
	v_mov_b32_e32 v42, 0
	v_mov_b32_e32 v43, 0
	v_mov_b32_e32 v44, 0
	v_mov_b32_e32 v45, 0
	v_and_b32_e32 v78, 0xffff, v31
	v_lshrrev_b32_e32 v79, 16, v31
	v_lshl_add_u32 v78, v78, 7, v150
	v_lshl_add_u32 v79, v79, 7, v151
	s_mov_b32 m0, s79
	s_add_i32 s43, s79, 0x400
	global_load_lds_dwordx4 v78, s[50:51]
	s_mov_b32 m0, s43
	s_nop 0
	global_load_lds_dwordx4 v79, s[50:51]
	s_waitcnt vmcnt(8)
; __device__ __forceinline__ bf16 f2bf(float f) { return (bf16)f2bfu(f); }
; #define TR4(p_) __builtin_amdgcn_ds_read_tr4_b64_v2i32((LAS v2i*)(p_))
; #define VDMA(st_, k_) do { _Pragma("unroll") for (int i_ = 0; i_ < 4; ++i_) { \
;         const unsigned off_ = (unsigned)((st_) >> 2) * (16384u * 128u) + (PE_ID(E, 4 * ((st_) & 3) + i_) << 7) + ((i_ & 1) ? cx1 : cx0); \
;         __builtin_amdgcn_global_load_lds((const unsigned*)(V4 + off_), (LAS unsigned*)(ldsb + BUF[k_] + 1024 * i_), 16, 0, 0); } } while (0)
; __device__ __forceinline__ void peer_v_tokens(int j, const LAS unsigned short* EL, const LAS unsigned char* AL  , const LAS float* ASC  , const LAS int* SAL  , ...
;     ...
;         for (int st = 0; st < 16; ++st) {
;             const int p = st >> 2, q = st & 3;
;             if (st < 14) VDMA(st + 2, (st + 2) % 3);
;             if (st < 14) asm volatile("s_waitcnt vmcnt(8)" ::: "memory");
;             else if (st == 14) asm volatile("s_waitcnt vmcnt(4)" ::: "memory");
;             else asm volatile("s_waitcnt vmcnt(0)" ::: "memory");
;             if (q == 0) {
; #pragma unroll
;                 for (int r = 0; r < 4; ++r) { accH[r] = 0; accL[r] = 0; } }
; #pragma unroll
;             for (int tp = 0; tp < 2; ++tp) {
;                 const v2i ao = TR4(ATL + (2 * q + tp) * 128 + 8 * s16), ah = TR4(ATL + 1024 + (2 * q + tp) * 128 + 8 * s16);
; #pragma unroll
;                 for (int r = 0; r < 4; ++r) {
;                     const v2i d = TR4(ldsb + BUF[st % 3] + 2048 * tp + roff[r]);
;                     accH[r] = __builtin_amdgcn_sdot8(d.x, ah.x, accH[r], false); accH[r] = __builtin_amdgcn_sdot8(d.y, ah.y, accH[r], false);
;                     accL[r] = __builtin_amdgcn_sdot8(d.x, ao.x, accL[r], false); accL[r] = __builtin_amdgcn_sdot8(d.y, ao.y, accL[r], false);
;                 }
;             }
;             asm volatile("s_waitcnt lgkmcnt(0)" ::: "memory");
;             if (q == 3) {
; #pragma unroll
;                 for (int r = 0; r < 4; ++r) STASH[256 * p + 16 * (grp + 4 * r) + pc] = f2bf(asc * (float)(2 * ((accH[r] << 4) + accL[r]) + sa));
;             }
;         }
	v_add_u32_e32 v54, s99, v59
	v_add_u32_e32 v55, s99, v60
	v_add_u32_e32 v56, s99, v61
	v_add_u32_e32 v57, s99, v62
	ds_read_b64_tr_b4 v[50:51], v160 offset:128
	ds_read_b64_tr_b4 v[52:53], v160 offset:1152
	ds_read_b64_tr_b4 v[130:131], v54
	ds_read_b64_tr_b4 v[132:133], v55
	ds_read_b64_tr_b4 v[134:135], v56
	ds_read_b64_tr_b4 v[136:137], v57
	s_waitcnt lgkmcnt(12)
	v_dot8c_i32_i4_e32 v38, v122, v48
	v_dot8c_i32_i4_e32 v39, v122, v46
	v_dot8c_i32_i4_e32 v40, v124, v48
	v_dot8c_i32_i4_e32 v41, v124, v46
	v_dot8c_i32_i4_e32 v42, v126, v48
	v_dot8c_i32_i4_e32 v43, v126, v46
	v_dot8c_i32_i4_e32 v44, v128, v48
	v_dot8c_i32_i4_e32 v45, v128, v46
	v_dot8c_i32_i4_e32 v38, v123, v49
	v_dot8c_i32_i4_e32 v39, v123, v47
	v_dot8c_i32_i4_e32 v40, v125, v49
	v_dot8c_i32_i4_e32 v41, v125, v47
	v_dot8c_i32_i4_e32 v42, v127, v49
	v_dot8c_i32_i4_e32 v43, v127, v47
	v_dot8c_i32_i4_e32 v44, v129, v49
	v_dot8c_i32_i4_e32 v45, v129, v47
	v_and_b32_e32 v78, 0xffff, v32
	v_lshrrev_b32_e32 v79, 16, v32
	v_lshl_add_u32 v78, v78, 7, v150
	v_lshl_add_u32 v79, v79, 7, v151
	s_mov_b32 m0, s98
	s_add_i32 s43, s98, 0x400
	global_load_lds_dwordx4 v78, s[50:51]
	s_mov_b32 m0, s43
	s_nop 0
	global_load_lds_dwordx4 v79, s[50:51]
	s_waitcnt vmcnt(8)
	v_add_u32_e32 v54, s76, v59
	v_add_u32_e32 v55, s76, v60
	v_add_u32_e32 v56, s76, v61
	v_add_u32_e32 v57, s76, v62
	ds_read_b64_tr_b4 v[46:47], v160 offset:256
	ds_read_b64_tr_b4 v[48:49], v160 offset:1280
	ds_read_b64_tr_b4 v[122:123], v54
	ds_read_b64_tr_b4 v[124:125], v55
	ds_read_b64_tr_b4 v[126:127], v56
	ds_read_b64_tr_b4 v[128:129], v57
	s_waitcnt lgkmcnt(6)
	v_dot8c_i32_i4_e32 v38, v130, v52
	v_dot8c_i32_i4_e32 v39, v130, v50
	v_dot8c_i32_i4_e32 v40, v132, v52
	v_dot8c_i32_i4_e32 v41, v132, v50
	v_dot8c_i32_i4_e32 v42, v134, v52
	v_dot8c_i32_i4_e32 v43, v134, v50
	v_dot8c_i32_i4_e32 v44, v136, v52
	v_dot8c_i32_i4_e32 v45, v136, v50
	v_dot8c_i32_i4_e32 v38, v131, v53
	v_dot8c_i32_i4_e32 v39, v131, v51
	v_dot8c_i32_i4_e32 v40, v133, v53
	v_dot8c_i32_i4_e32 v41, v133, v51
	v_dot8c_i32_i4_e32 v42, v135, v53
	v_dot8c_i32_i4_e32 v43, v135, v51
	v_dot8c_i32_i4_e32 v44, v137, v53
	v_dot8c_i32_i4_e32 v45, v137, v51
	v_and_b32_e32 v78, 0xffff, v33
	v_lshrrev_b32_e32 v79, 16, v33
	v_lshl_add_u32 v78, v78, 7, v150
	v_lshl_add_u32 v79, v79, 7, v151
	s_mov_b32 m0, s99
	s_add_i32 s43, s99, 0x400
	global_load_lds_dwordx4 v78, s[50:51]
	s_mov_b32 m0, s43
	s_nop 0
	global_load_lds_dwordx4 v79, s[50:51]
	s_waitcnt vmcnt(8)
	v_add_u32_e32 v54, s77, v59
	v_add_u32_e32 v55, s77, v60
	v_add_u32_e32 v56, s77, v61
	v_add_u32_e32 v57, s77, v62
	ds_read_b64_tr_b4 v[50:51], v160 offset:384
	ds_read_b64_tr_b4 v[52:53], v160 offset:1408
	ds_read_b64_tr_b4 v[130:131], v54
	ds_read_b64_tr_b4 v[132:133], v55
	ds_read_b64_tr_b4 v[134:135], v56
	ds_read_b64_tr_b4 v[136:137], v57
	s_waitcnt lgkmcnt(6)
	v_dot8c_i32_i4_e32 v38, v122, v48
	v_dot8c_i32_i4_e32 v39, v122, v46
	v_dot8c_i32_i4_e32 v40, v124, v48
	v_dot8c_i32_i4_e32 v41, v124, v46
	v_dot8c_i32_i4_e32 v42, v126, v48
	v_dot8c_i32_i4_e32 v43, v126, v46
	v_dot8c_i32_i4_e32 v44, v128, v48
	v_dot8c_i32_i4_e32 v45, v128, v46
	v_dot8c_i32_i4_e32 v38, v123, v49
	v_dot8c_i32_i4_e32 v39, v123, v47
	v_dot8c_i32_i4_e32 v40, v125, v49
	v_dot8c_i32_i4_e32 v41, v125, v47
	v_dot8c_i32_i4_e32 v42, v127, v49
	v_dot8c_i32_i4_e32 v43, v127, v47
	v_dot8c_i32_i4_e32 v44, v129, v49
	v_dot8c_i32_i4_e32 v45, v129, v47
	s_waitcnt lgkmcnt(15)
	v_and_b32_e32 v78, 0xffff, v18
	v_lshrrev_b32_e32 v79, 16, v18
	v_lshl_add_u32 v78, v78, 7, v152
	v_lshl_add_u32 v79, v79, 7, v153
	s_mov_b32 m0, s76
	s_add_i32 s43, s76, 0x400
	global_load_lds_dwordx4 v78, s[50:51]
	s_mov_b32 m0, s43
	s_nop 0
	global_load_lds_dwordx4 v79, s[50:51]
	s_waitcnt vmcnt(8)
	v_add_u32_e32 v54, s78, v59
	v_add_u32_e32 v55, s78, v60
	v_add_u32_e32 v56, s78, v61
	v_add_u32_e32 v57, s78, v62
	ds_read_b64_tr_b4 v[46:47], v160 offset:512
	ds_read_b64_tr_b4 v[48:49], v160 offset:1536
	ds_read_b64_tr_b4 v[122:123], v54
	ds_read_b64_tr_b4 v[124:125], v55
	ds_read_b64_tr_b4 v[126:127], v56
	ds_read_b64_tr_b4 v[128:129], v57
	s_waitcnt lgkmcnt(6)
	v_dot8c_i32_i4_e32 v38, v130, v52
	v_dot8c_i32_i4_e32 v39, v130, v50
	v_dot8c_i32_i4_e32 v40, v132, v52
	v_dot8c_i32_i4_e32 v41, v132, v50
	v_dot8c_i32_i4_e32 v42, v134, v52
	v_dot8c_i32_i4_e32 v43, v134, v50
	v_dot8c_i32_i4_e32 v44, v136, v52
	v_dot8c_i32_i4_e32 v45, v136, v50
	v_dot8c_i32_i4_e32 v38, v131, v53
	v_dot8c_i32_i4_e32 v39, v131, v51
	v_dot8c_i32_i4_e32 v40, v133, v53
	v_dot8c_i32_i4_e32 v41, v133, v51
	v_dot8c_i32_i4_e32 v42, v135, v53
	v_dot8c_i32_i4_e32 v43, v135, v51
	v_dot8c_i32_i4_e32 v44, v137, v53
	v_dot8c_i32_i4_e32 v45, v137, v51
	v_and_b32_e32 v78, 0xffff, v19
	v_lshrrev_b32_e32 v79, 16, v19
	v_lshl_add_u32 v78, v78, 7, v152
	v_lshl_add_u32 v79, v79, 7, v153
	s_mov_b32 m0, s77
	s_add_i32 s43, s77, 0x400
	global_load_lds_dwordx4 v78, s[50:51]
	s_mov_b32 m0, s43
	s_nop 0
	global_load_lds_dwordx4 v79, s[50:51]
	s_waitcnt vmcnt(8)
	v_add_u32_e32 v54, s79, v59
	v_add_u32_e32 v55, s79, v60
	v_add_u32_e32 v56, s79, v61
	v_add_u32_e32 v57, s79, v62
	ds_read_b64_tr_b4 v[50:51], v160 offset:640
	ds_read_b64_tr_b4 v[52:53], v160 offset:1664
	ds_read_b64_tr_b4 v[130:131], v54
	ds_read_b64_tr_b4 v[132:133], v55
	ds_read_b64_tr_b4 v[134:135], v56
	ds_read_b64_tr_b4 v[136:137], v57
	s_waitcnt lgkmcnt(6)
	v_dot8c_i32_i4_e32 v38, v122, v48
	v_dot8c_i32_i4_e32 v39, v122, v46
	v_dot8c_i32_i4_e32 v40, v124, v48
	v_dot8c_i32_i4_e32 v41, v124, v46
	v_dot8c_i32_i4_e32 v42, v126, v48
	v_dot8c_i32_i4_e32 v43, v126, v46
	v_dot8c_i32_i4_e32 v44, v128, v48
	v_dot8c_i32_i4_e32 v45, v128, v46
	v_dot8c_i32_i4_e32 v38, v123, v49
	v_dot8c_i32_i4_e32 v39, v123, v47
	v_dot8c_i32_i4_e32 v40, v125, v49
	v_dot8c_i32_i4_e32 v41, v125, v47
	v_dot8c_i32_i4_e32 v42, v127, v49
	v_dot8c_i32_i4_e32 v43, v127, v47
	v_dot8c_i32_i4_e32 v44, v129, v49
	v_dot8c_i32_i4_e32 v45, v129, v47
	s_waitcnt lgkmcnt(15)
; __device__ __forceinline__ void peer_v_tokens(int j, const LAS unsigned short* EL, const LAS unsigned char* AL  , const LAS float* ASC  , const LAS int* SAL  , ...
;     ...
;         { const LAS v4u* ep = (const LAS v4u*)(EL + tl * 128 + 16 * g); const v4u e0 = ep[0], e1 = ep[1];
;           E[0] = e0.x; E[1] = e0.y; E[2] = e0.z; E[3] = e0.w; E[4] = e1.x; E[5] = e1.y; E[6] = e1.z; E[7] = e1.w; }
;         uint2 hv[4]; float4 gv[4];
;         { unsigned ho = (unsigned)t * (D / 4) + (unsigned)lane; asm volatile("" : "+v"(ho)); const uint2* hp = (const uint2*)HB + ho; const float4* gp = (const float4*)fng + lane;
; #pragma unroll
;           for (int jq = 0; jq < 4; ++jq) { hv[jq] = hp[64 * jq]; gv[jq] = gp[64 * jq]; } }
;         VDMA(0, 0); VDMA(1, 1);
; #pragma unroll
;         for (int m = 0; m < 2; ++m) {
;             const int idx = lane + 64 * m, tau = idx >> 4, sr = idx & 15, k = 16 * (sr & 7) + 2 * tau + (sr >> 3);
;             const int aq = (int)*(const LAS signed char*)(AL + tl * 128 + k); const int tq = aq + 8;
;             const unsigned lo = (((unsigned)tq & 15u) ^ 8u) * 0x11111111u, hi = ((unsigned)(tq >> 4) & 15u) * 0x11111111u;
;             typedef unsigned u2v __attribute__((ext_vector_type(2)));
;             u2v l2; l2.x = lo; l2.y = lo; u2v h2; h2.x = hi; h2.y = hi;
;             *(LAS u2v*)(ATL + 8 * idx) = l2; *(LAS u2v*)(ATL + 1024 + 8 * idx) = h2;
;         }
;         const float asc = ASC[tl]; const int sa = SAL[tl];
;         CFENCE();
;         int accH[4], accL[4];
; #pragma unroll
;         for (int st = 0; st < 16; ++st) {
;             const int p = st >> 2, q = st & 3;
;             if (st < 14) VDMA(st + 2, (st + 2) % 3);
;             if (st < 14) asm volatile("s_waitcnt vmcnt(8)" ::: "memory");
;             else if (st == 14) asm volatile("s_waitcnt vmcnt(4)" ::: "memory");
;             else asm volatile("s_waitcnt vmcnt(0)" ::: "memory");
;             if (q == 0) {
; #pragma unroll
;                 for (int r = 0; r < 4; ++r) { accH[r] = 0; accL[r] = 0; } }
; #pragma unroll
;             for (int tp = 0; tp < 2; ++tp) {
;                 const v2i ao = TR4(ATL + (2 * q + tp) * 128 + 8 * s16), ah = TR4(ATL + 1024 + (2 * q + tp) * 128 + 8 * s16);
; #pragma unroll
;                 for (int r = 0; r < 4; ++r) {
;                     const v2i d = TR4(ldsb + BUF[st % 3] + 2048 * tp + roff[r]);
	v_add_u32_e32 v143, 8, v139
	v_and_b32_e32 v142, 15, v143
	v_xor_b32_e32 v142, 8, v142
	v_bfe_u32 v144, v143, 4, 4
	v_mul_lo_u32 v142, v142, s92
	v_mul_lo_u32 v144, v144, s92
	v_mov_b32_e32 v143, v142
	v_mov_b32_e32 v145, v144
	ds_write2st64_b64 v159, v[142:143], v[144:145] offset1:2
	v_and_b32_e32 v78, 0xffff, v20
	v_lshrrev_b32_e32 v79, 16, v20
	v_lshl_add_u32 v78, v78, 7, v152
	v_lshl_add_u32 v79, v79, 7, v153
	s_mov_b32 m0, s78
	s_add_i32 s43, s78, 0x400
	global_load_lds_dwordx4 v78, s[50:51]
	s_mov_b32 m0, s43
	s_nop 0
	global_load_lds_dwordx4 v79, s[50:51]
	s_waitcnt vmcnt(8)
	v_add_u32_e32 v54, s98, v59
	v_add_u32_e32 v55, s98, v60
	v_add_u32_e32 v56, s98, v61
	v_add_u32_e32 v57, s98, v62
	ds_read_b64_tr_b4 v[46:47], v160 offset:768
	ds_read_b64_tr_b4 v[48:49], v160 offset:1792
	ds_read_b64_tr_b4 v[122:123], v54
	ds_read_b64_tr_b4 v[124:125], v55
	ds_read_b64_tr_b4 v[126:127], v56
	ds_read_b64_tr_b4 v[128:129], v57
	s_waitcnt lgkmcnt(7)
	v_dot8c_i32_i4_e32 v38, v130, v52
	v_dot8c_i32_i4_e32 v39, v130, v50
	v_dot8c_i32_i4_e32 v40, v132, v52
	v_dot8c_i32_i4_e32 v41, v132, v50
	v_dot8c_i32_i4_e32 v42, v134, v52
	v_dot8c_i32_i4_e32 v43, v134, v50
	v_dot8c_i32_i4_e32 v44, v136, v52
	v_dot8c_i32_i4_e32 v45, v136, v50
	v_dot8c_i32_i4_e32 v38, v131, v53
	v_dot8c_i32_i4_e32 v39, v131, v51
	v_dot8c_i32_i4_e32 v40, v133, v53
	v_dot8c_i32_i4_e32 v41, v133, v51
	v_dot8c_i32_i4_e32 v42, v135, v53
	v_dot8c_i32_i4_e32 v43, v135, v51
	v_dot8c_i32_i4_e32 v44, v137, v53
	v_dot8c_i32_i4_e32 v45, v137, v51
	v_and_b32_e32 v78, 0xffff, v21
	v_lshrrev_b32_e32 v79, 16, v21
	v_lshl_add_u32 v78, v78, 7, v152
	v_lshl_add_u32 v79, v79, 7, v153
	s_mov_b32 m0, s79
	s_add_i32 s43, s79, 0x400
	global_load_lds_dwordx4 v78, s[50:51]
	s_mov_b32 m0, s43
	s_nop 0
	global_load_lds_dwordx4 v79, s[50:51]
	s_waitcnt vmcnt(8)
	v_add_u32_e32 v54, s99, v59
	v_add_u32_e32 v55, s99, v60
	v_add_u32_e32 v56, s99, v61
	v_add_u32_e32 v57, s99, v62
	ds_read_b64_tr_b4 v[50:51], v160 offset:896
	ds_read_b64_tr_b4 v[52:53], v160 offset:1920
	ds_read_b64_tr_b4 v[130:131], v54
	ds_read_b64_tr_b4 v[132:133], v55
	ds_read_b64_tr_b4 v[134:135], v56
	ds_read_b64_tr_b4 v[136:137], v57
	s_waitcnt lgkmcnt(6)
	v_dot8c_i32_i4_e32 v38, v122, v48
	v_dot8c_i32_i4_e32 v39, v122, v46
	v_dot8c_i32_i4_e32 v40, v124, v48
	v_dot8c_i32_i4_e32 v41, v124, v46
	v_dot8c_i32_i4_e32 v42, v126, v48
	v_dot8c_i32_i4_e32 v43, v126, v46
	v_dot8c_i32_i4_e32 v44, v128, v48
	v_dot8c_i32_i4_e32 v45, v128, v46
	v_dot8c_i32_i4_e32 v38, v123, v49
	v_dot8c_i32_i4_e32 v39, v123, v47
	v_dot8c_i32_i4_e32 v40, v125, v49
	v_dot8c_i32_i4_e32 v41, v125, v47
	v_dot8c_i32_i4_e32 v42, v127, v49
	v_dot8c_i32_i4_e32 v43, v127, v47
	v_dot8c_i32_i4_e32 v44, v129, v49
	v_dot8c_i32_i4_e32 v45, v129, v47
	v_and_b32_e32 v78, 0xffff, v22
	v_lshrrev_b32_e32 v79, 16, v22
	v_lshl_add_u32 v78, v78, 7, v152
	v_lshl_add_u32 v79, v79, 7, v153
	s_mov_b32 m0, s98
	s_add_i32 s43, s98, 0x400
	global_load_lds_dwordx4 v78, s[50:51]
	s_mov_b32 m0, s43
	s_nop 0
	global_load_lds_dwordx4 v79, s[50:51]
	s_waitcnt vmcnt(8)
	v_add_u32_e32 v54, s76, v59
	v_add_u32_e32 v55, s76, v60
	v_add_u32_e32 v56, s76, v61
	v_add_u32_e32 v57, s76, v62
	ds_read_b64_tr_b4 v[46:47], v160
	ds_read_b64_tr_b4 v[48:49], v160 offset:1024
	ds_read_b64_tr_b4 v[122:123], v54
	ds_read_b64_tr_b4 v[124:125], v55
	ds_read_b64_tr_b4 v[126:127], v56
	ds_read_b64_tr_b4 v[128:129], v57
	s_waitcnt lgkmcnt(6)
	v_dot8c_i32_i4_e32 v38, v130, v52
	v_dot8c_i32_i4_e32 v39, v130, v50
	v_dot8c_i32_i4_e32 v40, v132, v52
	v_dot8c_i32_i4_e32 v41, v132, v50
	v_dot8c_i32_i4_e32 v42, v134, v52
	v_dot8c_i32_i4_e32 v43, v134, v50
	v_dot8c_i32_i4_e32 v44, v136, v52
	v_dot8c_i32_i4_e32 v45, v136, v50
	v_dot8c_i32_i4_e32 v38, v131, v53
	v_dot8c_i32_i4_e32 v39, v131, v51
	v_dot8c_i32_i4_e32 v40, v133, v53
	v_dot8c_i32_i4_e32 v41, v133, v51
	v_dot8c_i32_i4_e32 v42, v135, v53
	v_dot8c_i32_i4_e32 v43, v135, v51
	v_dot8c_i32_i4_e32 v44, v137, v53
	v_dot8c_i32_i4_e32 v45, v137, v51
	s_nop 3
	s_waitcnt lgkmcnt(15)
	v_lshlrev_b32_e32 v38, 5, v38
	v_lshlrev_b32_e32 v39, 1, v39
	v_add3_u32 v38, v39, v229, v38
	v_cvt_f32_i32_e32 v38, v38
	v_mul_f32_e32 v38, v228, v38
	v_lshlrev_b32_e32 v40, 5, v40
	v_lshlrev_b32_e32 v41, 1, v41
	v_add3_u32 v40, v41, v229, v40
	v_cvt_f32_i32_e32 v40, v40
	v_mul_f32_e32 v40, v228, v40
	v_lshlrev_b32_e32 v42, 5, v42
	v_lshlrev_b32_e32 v43, 1, v43
	v_add3_u32 v42, v43, v229, v42
	v_cvt_f32_i32_e32 v42, v42
	v_mul_f32_e32 v42, v228, v42
	v_lshlrev_b32_e32 v44, 5, v44
	v_lshlrev_b32_e32 v45, 1, v45
	v_add3_u32 v44, v45, v229, v44
	v_cvt_f32_i32_e32 v44, v44
	v_mul_f32_e32 v44, v228, v44
	v_cvt_pk_bf16_f32 v174, v38, v40
	v_cvt_pk_bf16_f32 v175, v42, v44
	v_add_u32_e32 v147, 8, v140
	v_and_b32_e32 v146, 15, v147
	v_xor_b32_e32 v146, 8, v146
	v_bfe_u32 v148, v147, 4, 4
	v_mul_lo_u32 v146, v146, s92
	v_mul_lo_u32 v148, v148, s92
	v_mov_b32_e32 v147, v146
	v_mov_b32_e32 v149, v148
	ds_write2st64_b64 v77, v[146:147], v[148:149] offset1:2
	v_add_u32_e32 v138, 0x400, v74
	ds_read_u8 v139, v138
	v_add_u32_e32 v141, 0x400, v73
	ds_read_u8 v140, v141
	s_mov_b32 s43, s67
	v_mov_b32_e32 v138, s43
	ds_read2st64_b32 v[228:229], v138 offset1:1
	ds_read_b128 v[26:29], v227 offset:2048
	ds_read_b128 v[30:33], v227 offset:2064
	v_mov_b32_e32 v38, 0
	v_mov_b32_e32 v39, 0
	v_mov_b32_e32 v40, 0
	v_mov_b32_e32 v41, 0
	v_mov_b32_e32 v42, 0
	v_mov_b32_e32 v43, 0
	v_mov_b32_e32 v44, 0
	v_mov_b32_e32 v45, 0
	v_and_b32_e32 v78, 0xffff, v23
	v_lshrrev_b32_e32 v79, 16, v23
	v_lshl_add_u32 v78, v78, 7, v152
	v_lshl_add_u32 v79, v79, 7, v153
	s_mov_b32 m0, s99
	s_add_i32 s43, s99, 0x400
	global_load_lds_dwordx4 v78, s[50:51]
	s_mov_b32 m0, s43
	s_nop 0
	global_load_lds_dwordx4 v79, s[50:51]
	s_waitcnt vmcnt(8)
; __device__ __forceinline__ bf16 f2bf(float f) { return (bf16)f2bfu(f); }
; #define TR4(p_) __builtin_amdgcn_ds_read_tr4_b64_v2i32((LAS v2i*)(p_))
; #define VDMA(st_, k_) do { _Pragma("unroll") for (int i_ = 0; i_ < 4; ++i_) { \
;         const unsigned off_ = (unsigned)((st_) >> 2) * (16384u * 128u) + (PE_ID(E, 4 * ((st_) & 3) + i_) << 7) + ((i_ & 1) ? cx1 : cx0); \
;         __builtin_amdgcn_global_load_lds((const unsigned*)(V4 + off_), (LAS unsigned*)(ldsb + BUF[k_] + 1024 * i_), 16, 0, 0); } } while (0)
; __device__ __forceinline__ void peer_v_tokens(int j, const LAS unsigned short* EL, const LAS unsigned char* AL  , const LAS float* ASC  , const LAS int* SAL  , ...
;     ...
;         for (int st = 0; st < 16; ++st) {
;             const int p = st >> 2, q = st & 3;
;             if (st < 14) VDMA(st + 2, (st + 2) % 3);
;             if (st < 14) asm volatile("s_waitcnt vmcnt(8)" ::: "memory");
;             else if (st == 14) asm volatile("s_waitcnt vmcnt(4)" ::: "memory");
;             else asm volatile("s_waitcnt vmcnt(0)" ::: "memory");
;             if (q == 0) {
; #pragma unroll
;                 for (int r = 0; r < 4; ++r) { accH[r] = 0; accL[r] = 0; } }
; #pragma unroll
;             for (int tp = 0; tp < 2; ++tp) {
;                 const v2i ao = TR4(ATL + (2 * q + tp) * 128 + 8 * s16), ah = TR4(ATL + 1024 + (2 * q + tp) * 128 + 8 * s16);
; #pragma unroll
;                 for (int r = 0; r < 4; ++r) {
;                     const v2i d = TR4(ldsb + BUF[st % 3] + 2048 * tp + roff[r]);
;                     accH[r] = __builtin_amdgcn_sdot8(d.x, ah.x, accH[r], false); accH[r] = __builtin_amdgcn_sdot8(d.y, ah.y, accH[r], false);
;                     accL[r] = __builtin_amdgcn_sdot8(d.x, ao.x, accL[r], false); accL[r] = __builtin_amdgcn_sdot8(d.y, ao.y, accL[r], false);
;                 }
;             }
;             asm volatile("s_waitcnt lgkmcnt(0)" ::: "memory");
;             if (q == 3) {
; #pragma unroll
;                 for (int r = 0; r < 4; ++r) STASH[256 * p + 16 * (grp + 4 * r) + pc] = f2bf(asc * (float)(2 * ((accH[r] << 4) + accL[r]) + sa));
;             }
;         }
	v_add_u32_e32 v54, s77, v59
	v_add_u32_e32 v55, s77, v60
	v_add_u32_e32 v56, s77, v61
	v_add_u32_e32 v57, s77, v62
	ds_read_b64_tr_b4 v[50:51], v160 offset:128
	ds_read_b64_tr_b4 v[52:53], v160 offset:1152
	ds_read_b64_tr_b4 v[130:131], v54
	ds_read_b64_tr_b4 v[132:133], v55
	ds_read_b64_tr_b4 v[134:135], v56
	ds_read_b64_tr_b4 v[136:137], v57
	s_waitcnt lgkmcnt(12)
	v_dot8c_i32_i4_e32 v38, v122, v48
	v_dot8c_i32_i4_e32 v39, v122, v46
	v_dot8c_i32_i4_e32 v40, v124, v48
	v_dot8c_i32_i4_e32 v41, v124, v46
	v_dot8c_i32_i4_e32 v42, v126, v48
	v_dot8c_i32_i4_e32 v43, v126, v46
	v_dot8c_i32_i4_e32 v44, v128, v48
	v_dot8c_i32_i4_e32 v45, v128, v46
	v_dot8c_i32_i4_e32 v38, v123, v49
	v_dot8c_i32_i4_e32 v39, v123, v47
	v_dot8c_i32_i4_e32 v40, v125, v49
	v_dot8c_i32_i4_e32 v41, v125, v47
	v_dot8c_i32_i4_e32 v42, v127, v49
	v_dot8c_i32_i4_e32 v43, v127, v47
	v_dot8c_i32_i4_e32 v44, v129, v49
	v_dot8c_i32_i4_e32 v45, v129, v47
	v_and_b32_e32 v78, 0xffff, v24
	v_lshrrev_b32_e32 v79, 16, v24
	v_lshl_add_u32 v78, v78, 7, v152
	v_lshl_add_u32 v79, v79, 7, v153
	s_mov_b32 m0, s76
	s_add_i32 s43, s76, 0x400
	global_load_lds_dwordx4 v78, s[50:51]
	s_mov_b32 m0, s43
	s_nop 0
	global_load_lds_dwordx4 v79, s[50:51]
	s_waitcnt vmcnt(8)
	v_add_u32_e32 v54, s78, v59
	v_add_u32_e32 v55, s78, v60
	v_add_u32_e32 v56, s78, v61
	v_add_u32_e32 v57, s78, v62
	ds_read_b64_tr_b4 v[46:47], v160 offset:256
	ds_read_b64_tr_b4 v[48:49], v160 offset:1280
	ds_read_b64_tr_b4 v[122:123], v54
	ds_read_b64_tr_b4 v[124:125], v55
	ds_read_b64_tr_b4 v[126:127], v56
	ds_read_b64_tr_b4 v[128:129], v57
	s_waitcnt lgkmcnt(6)
	v_dot8c_i32_i4_e32 v38, v130, v52
	v_dot8c_i32_i4_e32 v39, v130, v50
	v_dot8c_i32_i4_e32 v40, v132, v52
	v_dot8c_i32_i4_e32 v41, v132, v50
	v_dot8c_i32_i4_e32 v42, v134, v52
	v_dot8c_i32_i4_e32 v43, v134, v50
	v_dot8c_i32_i4_e32 v44, v136, v52
	v_dot8c_i32_i4_e32 v45, v136, v50
	v_dot8c_i32_i4_e32 v38, v131, v53
	v_dot8c_i32_i4_e32 v39, v131, v51
	v_dot8c_i32_i4_e32 v40, v133, v53
	v_dot8c_i32_i4_e32 v41, v133, v51
	v_dot8c_i32_i4_e32 v42, v135, v53
	v_dot8c_i32_i4_e32 v43, v135, v51
	v_dot8c_i32_i4_e32 v44, v137, v53
	v_dot8c_i32_i4_e32 v45, v137, v51
	v_and_b32_e32 v78, 0xffff, v25
	v_lshrrev_b32_e32 v79, 16, v25
	v_lshl_add_u32 v78, v78, 7, v152
	v_lshl_add_u32 v79, v79, 7, v153
	s_mov_b32 m0, s77
	s_add_i32 s43, s77, 0x400
	global_load_lds_dwordx4 v78, s[50:51]
	s_mov_b32 m0, s43
	s_nop 0
	global_load_lds_dwordx4 v79, s[50:51]
	s_waitcnt vmcnt(8)
	v_add_u32_e32 v54, s79, v59
	v_add_u32_e32 v55, s79, v60
	v_add_u32_e32 v56, s79, v61
	v_add_u32_e32 v57, s79, v62
	ds_read_b64_tr_b4 v[50:51], v160 offset:384
	ds_read_b64_tr_b4 v[52:53], v160 offset:1408
	ds_read_b64_tr_b4 v[130:131], v54
	ds_read_b64_tr_b4 v[132:133], v55
	ds_read_b64_tr_b4 v[134:135], v56
	ds_read_b64_tr_b4 v[136:137], v57
	s_waitcnt lgkmcnt(6)
	v_dot8c_i32_i4_e32 v38, v122, v48
	v_dot8c_i32_i4_e32 v39, v122, v46
	v_dot8c_i32_i4_e32 v40, v124, v48
	v_dot8c_i32_i4_e32 v41, v124, v46
	v_dot8c_i32_i4_e32 v42, v126, v48
	v_dot8c_i32_i4_e32 v43, v126, v46
	v_dot8c_i32_i4_e32 v44, v128, v48
	v_dot8c_i32_i4_e32 v45, v128, v46
	v_dot8c_i32_i4_e32 v38, v123, v49
	v_dot8c_i32_i4_e32 v39, v123, v47
	v_dot8c_i32_i4_e32 v40, v125, v49
	v_dot8c_i32_i4_e32 v41, v125, v47
	v_dot8c_i32_i4_e32 v42, v127, v49
	v_dot8c_i32_i4_e32 v43, v127, v47
	v_dot8c_i32_i4_e32 v44, v129, v49
	v_dot8c_i32_i4_e32 v45, v129, v47
	s_waitcnt lgkmcnt(15)
	v_and_b32_e32 v78, 0xffff, v26
	v_lshrrev_b32_e32 v79, 16, v26
	v_lshl_add_u32 v78, v78, 7, v152
	v_lshl_add_u32 v79, v79, 7, v153
	s_mov_b32 m0, s78
	s_add_i32 s43, s78, 0x400
	global_load_lds_dwordx4 v78, s[50:51]
	s_mov_b32 m0, s43
	s_nop 0
	global_load_lds_dwordx4 v79, s[50:51]
	s_waitcnt vmcnt(8)
	v_add_u32_e32 v54, s98, v59
	v_add_u32_e32 v55, s98, v60
	v_add_u32_e32 v56, s98, v61
	v_add_u32_e32 v57, s98, v62
	ds_read_b64_tr_b4 v[46:47], v160 offset:512
	ds_read_b64_tr_b4 v[48:49], v160 offset:1536
	ds_read_b64_tr_b4 v[122:123], v54
	ds_read_b64_tr_b4 v[124:125], v55
	ds_read_b64_tr_b4 v[126:127], v56
	ds_read_b64_tr_b4 v[128:129], v57
	s_waitcnt lgkmcnt(6)
	v_dot8c_i32_i4_e32 v38, v130, v52
	v_dot8c_i32_i4_e32 v39, v130, v50
	v_dot8c_i32_i4_e32 v40, v132, v52
	v_dot8c_i32_i4_e32 v41, v132, v50
	v_dot8c_i32_i4_e32 v42, v134, v52
	v_dot8c_i32_i4_e32 v43, v134, v50
	v_dot8c_i32_i4_e32 v44, v136, v52
	v_dot8c_i32_i4_e32 v45, v136, v50
	v_dot8c_i32_i4_e32 v38, v131, v53
	v_dot8c_i32_i4_e32 v39, v131, v51
	v_dot8c_i32_i4_e32 v40, v133, v53
	v_dot8c_i32_i4_e32 v41, v133, v51
	v_dot8c_i32_i4_e32 v42, v135, v53
	v_dot8c_i32_i4_e32 v43, v135, v51
	v_dot8c_i32_i4_e32 v44, v137, v53
	v_dot8c_i32_i4_e32 v45, v137, v51
	v_and_b32_e32 v78, 0xffff, v27
	v_lshrrev_b32_e32 v79, 16, v27
	v_lshl_add_u32 v78, v78, 7, v152
	v_lshl_add_u32 v79, v79, 7, v153
	s_mov_b32 m0, s79
	s_add_i32 s43, s79, 0x400
	global_load_lds_dwordx4 v78, s[50:51]
	s_mov_b32 m0, s43
	s_nop 0
	global_load_lds_dwordx4 v79, s[50:51]
	s_waitcnt vmcnt(8)
	v_add_u32_e32 v54, s99, v59
	v_add_u32_e32 v55, s99, v60
	v_add_u32_e32 v56, s99, v61
	v_add_u32_e32 v57, s99, v62
	ds_read_b64_tr_b4 v[50:51], v160 offset:640
	ds_read_b64_tr_b4 v[52:53], v160 offset:1664
	ds_read_b64_tr_b4 v[130:131], v54
	ds_read_b64_tr_b4 v[132:133], v55
	ds_read_b64_tr_b4 v[134:135], v56
	ds_read_b64_tr_b4 v[136:137], v57
	s_waitcnt lgkmcnt(6)
	v_dot8c_i32_i4_e32 v38, v122, v48
	v_dot8c_i32_i4_e32 v39, v122, v46
	v_dot8c_i32_i4_e32 v40, v124, v48
	v_dot8c_i32_i4_e32 v41, v124, v46
	v_dot8c_i32_i4_e32 v42, v126, v48
	v_dot8c_i32_i4_e32 v43, v126, v46
	v_dot8c_i32_i4_e32 v44, v128, v48
	v_dot8c_i32_i4_e32 v45, v128, v46
	v_dot8c_i32_i4_e32 v38, v123, v49
	v_dot8c_i32_i4_e32 v39, v123, v47
	v_dot8c_i32_i4_e32 v40, v125, v49
	v_dot8c_i32_i4_e32 v41, v125, v47
	v_dot8c_i32_i4_e32 v42, v127, v49
	v_dot8c_i32_i4_e32 v43, v127, v47
	v_dot8c_i32_i4_e32 v44, v129, v49
	v_dot8c_i32_i4_e32 v45, v129, v47
	s_waitcnt lgkmcnt(15)
; __device__ __forceinline__ void peer_v_tokens(int j, const LAS unsigned short* EL, const LAS unsigned char* AL  , const LAS float* ASC  , const LAS int* SAL  , ...
;     ...
;         { const LAS v4u* ep = (const LAS v4u*)(EL + tl * 128 + 16 * g); const v4u e0 = ep[0], e1 = ep[1];
;           E[0] = e0.x; E[1] = e0.y; E[2] = e0.z; E[3] = e0.w; E[4] = e1.x; E[5] = e1.y; E[6] = e1.z; E[7] = e1.w; }
;         uint2 hv[4]; float4 gv[4];
;         { unsigned ho = (unsigned)t * (D / 4) + (unsigned)lane; asm volatile("" : "+v"(ho)); const uint2* hp = (const uint2*)HB + ho; const float4* gp = (const float4*)fng + lane;
; #pragma unroll
;           for (int jq = 0; jq < 4; ++jq) { hv[jq] = hp[64 * jq]; gv[jq] = gp[64 * jq]; } }
;         VDMA(0, 0); VDMA(1, 1);
; #pragma unroll
;         for (int m = 0; m < 2; ++m) {
;             const int idx = lane + 64 * m, tau = idx >> 4, sr = idx & 15, k = 16 * (sr & 7) + 2 * tau + (sr >> 3);
;             const int aq = (int)*(const LAS signed char*)(AL + tl * 128 + k); const int tq = aq + 8;
;             const unsigned lo = (((unsigned)tq & 15u) ^ 8u) * 0x11111111u, hi = ((unsigned)(tq >> 4) & 15u) * 0x11111111u;
;             typedef unsigned u2v __attribute__((ext_vector_type(2)));
;             u2v l2; l2.x = lo; l2.y = lo; u2v h2; h2.x = hi; h2.y = hi;
;             *(LAS u2v*)(ATL + 8 * idx) = l2; *(LAS u2v*)(ATL + 1024 + 8 * idx) = h2;
;         }
;         const float asc = ASC[tl]; const int sa = SAL[tl];
;         CFENCE();
;         int accH[4], accL[4];
; #pragma unroll
;         for (int st = 0; st < 16; ++st) {
;             const int p = st >> 2, q = st & 3;
;             if (st < 14) VDMA(st + 2, (st + 2) % 3);
;             if (st < 14) asm volatile("s_waitcnt vmcnt(8)" ::: "memory");
;             else if (st == 14) asm volatile("s_waitcnt vmcnt(4)" ::: "memory");
;             else asm volatile("s_waitcnt vmcnt(0)" ::: "memory");
;             if (q == 0) {
; #pragma unroll
;                 for (int r = 0; r < 4; ++r) { accH[r] = 0; accL[r] = 0; } }
; #pragma unroll
;             for (int tp = 0; tp < 2; ++tp) {
;                 const v2i ao = TR4(ATL + (2 * q + tp) * 128 + 8 * s16), ah = TR4(ATL + 1024 + (2 * q + tp) * 128 + 8 * s16);
; #pragma unroll
;                 for (int r = 0; r < 4; ++r) {
;                     const v2i d = TR4(ldsb + BUF[st % 3] + 2048 * tp + roff[r]);
	v_add_u32_e32 v143, 8, v139
	v_and_b32_e32 v142, 15, v143
	v_xor_b32_e32 v142, 8, v142
	v_bfe_u32 v144, v143, 4, 4
	v_mul_lo_u32 v142, v142, s92
	v_mul_lo_u32 v144, v144, s92
	v_mov_b32_e32 v143, v142
	v_mov_b32_e32 v145, v144
	ds_write2st64_b64 v159, v[142:143], v[144:145] offset1:2
	v_and_b32_e32 v78, 0xffff, v28
	v_lshrrev_b32_e32 v79, 16, v28
	v_lshl_add_u32 v78, v78, 7, v152
	v_lshl_add_u32 v79, v79, 7, v153
	s_mov_b32 m0, s98
	s_add_i32 s43, s98, 0x400
	global_load_lds_dwordx4 v78, s[50:51]
	s_mov_b32 m0, s43
	s_nop 0
	global_load_lds_dwordx4 v79, s[50:51]
	s_waitcnt vmcnt(8)
	v_add_u32_e32 v54, s76, v59
	v_add_u32_e32 v55, s76, v60
	v_add_u32_e32 v56, s76, v61
	v_add_u32_e32 v57, s76, v62
	ds_read_b64_tr_b4 v[46:47], v160 offset:768
	ds_read_b64_tr_b4 v[48:49], v160 offset:1792
	ds_read_b64_tr_b4 v[122:123], v54
	ds_read_b64_tr_b4 v[124:125], v55
	ds_read_b64_tr_b4 v[126:127], v56
	ds_read_b64_tr_b4 v[128:129], v57
	s_waitcnt lgkmcnt(7)
	v_dot8c_i32_i4_e32 v38, v130, v52
	v_dot8c_i32_i4_e32 v39, v130, v50
	v_dot8c_i32_i4_e32 v40, v132, v52
	v_dot8c_i32_i4_e32 v41, v132, v50
	v_dot8c_i32_i4_e32 v42, v134, v52
	v_dot8c_i32_i4_e32 v43, v134, v50
	v_dot8c_i32_i4_e32 v44, v136, v52
	v_dot8c_i32_i4_e32 v45, v136, v50
	v_dot8c_i32_i4_e32 v38, v131, v53
	v_dot8c_i32_i4_e32 v39, v131, v51
	v_dot8c_i32_i4_e32 v40, v133, v53
	v_dot8c_i32_i4_e32 v41, v133, v51
	v_dot8c_i32_i4_e32 v42, v135, v53
	v_dot8c_i32_i4_e32 v43, v135, v51
	v_dot8c_i32_i4_e32 v44, v137, v53
	v_dot8c_i32_i4_e32 v45, v137, v51
	v_and_b32_e32 v78, 0xffff, v29
	v_lshrrev_b32_e32 v79, 16, v29
	v_lshl_add_u32 v78, v78, 7, v152
	v_lshl_add_u32 v79, v79, 7, v153
	s_mov_b32 m0, s99
	s_add_i32 s43, s99, 0x400
	global_load_lds_dwordx4 v78, s[50:51]
	s_mov_b32 m0, s43
	s_nop 0
	global_load_lds_dwordx4 v79, s[50:51]
	s_waitcnt vmcnt(8)
	v_add_u32_e32 v54, s77, v59
	v_add_u32_e32 v55, s77, v60
	v_add_u32_e32 v56, s77, v61
	v_add_u32_e32 v57, s77, v62
	ds_read_b64_tr_b4 v[50:51], v160 offset:896
	ds_read_b64_tr_b4 v[52:53], v160 offset:1920
	ds_read_b64_tr_b4 v[130:131], v54
	ds_read_b64_tr_b4 v[132:133], v55
	ds_read_b64_tr_b4 v[134:135], v56
	ds_read_b64_tr_b4 v[136:137], v57
	s_waitcnt lgkmcnt(6)
	v_dot8c_i32_i4_e32 v38, v122, v48
	v_dot8c_i32_i4_e32 v39, v122, v46
	v_dot8c_i32_i4_e32 v40, v124, v48
	v_dot8c_i32_i4_e32 v41, v124, v46
	v_dot8c_i32_i4_e32 v42, v126, v48
	v_dot8c_i32_i4_e32 v43, v126, v46
	v_dot8c_i32_i4_e32 v44, v128, v48
	v_dot8c_i32_i4_e32 v45, v128, v46
	v_dot8c_i32_i4_e32 v38, v123, v49
	v_dot8c_i32_i4_e32 v39, v123, v47
	v_dot8c_i32_i4_e32 v40, v125, v49
	v_dot8c_i32_i4_e32 v41, v125, v47
	v_dot8c_i32_i4_e32 v42, v127, v49
	v_dot8c_i32_i4_e32 v43, v127, v47
	v_dot8c_i32_i4_e32 v44, v129, v49
	v_dot8c_i32_i4_e32 v45, v129, v47
	v_and_b32_e32 v78, 0xffff, v30
	v_lshrrev_b32_e32 v79, 16, v30
	v_lshl_add_u32 v78, v78, 7, v152
	v_lshl_add_u32 v79, v79, 7, v153
	s_mov_b32 m0, s76
	s_add_i32 s43, s76, 0x400
	global_load_lds_dwordx4 v78, s[50:51]
	s_mov_b32 m0, s43
	s_nop 0
	global_load_lds_dwordx4 v79, s[50:51]
	s_waitcnt vmcnt(8)
	v_add_u32_e32 v54, s78, v59
	v_add_u32_e32 v55, s78, v60
	v_add_u32_e32 v56, s78, v61
	v_add_u32_e32 v57, s78, v62
	ds_read_b64_tr_b4 v[46:47], v160
	ds_read_b64_tr_b4 v[48:49], v160 offset:1024
	ds_read_b64_tr_b4 v[122:123], v54
	ds_read_b64_tr_b4 v[124:125], v55
	ds_read_b64_tr_b4 v[126:127], v56
	ds_read_b64_tr_b4 v[128:129], v57
	s_waitcnt lgkmcnt(6)
	v_dot8c_i32_i4_e32 v38, v130, v52
	v_dot8c_i32_i4_e32 v39, v130, v50
	v_dot8c_i32_i4_e32 v40, v132, v52
	v_dot8c_i32_i4_e32 v41, v132, v50
	v_dot8c_i32_i4_e32 v42, v134, v52
	v_dot8c_i32_i4_e32 v43, v134, v50
	v_dot8c_i32_i4_e32 v44, v136, v52
	v_dot8c_i32_i4_e32 v45, v136, v50
	v_dot8c_i32_i4_e32 v38, v131, v53
	v_dot8c_i32_i4_e32 v39, v131, v51
	v_dot8c_i32_i4_e32 v40, v133, v53
	v_dot8c_i32_i4_e32 v41, v133, v51
	v_dot8c_i32_i4_e32 v42, v135, v53
	v_dot8c_i32_i4_e32 v43, v135, v51
	v_dot8c_i32_i4_e32 v44, v137, v53
	v_dot8c_i32_i4_e32 v45, v137, v51
	s_nop 3
	s_waitcnt lgkmcnt(15)
	v_lshlrev_b32_e32 v38, 5, v38
	v_lshlrev_b32_e32 v39, 1, v39
	v_add3_u32 v38, v39, v229, v38
	v_cvt_f32_i32_e32 v38, v38
	v_mul_f32_e32 v38, v228, v38
	v_lshlrev_b32_e32 v40, 5, v40
	v_lshlrev_b32_e32 v41, 1, v41
	v_add3_u32 v40, v41, v229, v40
	v_cvt_f32_i32_e32 v40, v40
	v_mul_f32_e32 v40, v228, v40
	v_lshlrev_b32_e32 v42, 5, v42
	v_lshlrev_b32_e32 v43, 1, v43
	v_add3_u32 v42, v43, v229, v42
	v_cvt_f32_i32_e32 v42, v42
	v_mul_f32_e32 v42, v228, v42
	v_lshlrev_b32_e32 v44, 5, v44
	v_lshlrev_b32_e32 v45, 1, v45
	v_add3_u32 v44, v45, v229, v44
	v_cvt_f32_i32_e32 v44, v44
	v_mul_f32_e32 v44, v228, v44
	v_cvt_pk_bf16_f32 v168, v38, v40
	v_cvt_pk_bf16_f32 v169, v42, v44
	s_add_i32 s43, s40, 0
	s_lshl_b32 s43, s43, 11
	v_add_u32_e32 v138, s43, v66
	global_load_dwordx2 v[194:195], v138, s[70:71]
	global_load_dwordx2 v[196:197], v138, s[70:71] offset:512
	global_load_dwordx2 v[198:199], v138, s[70:71] offset:1024
	global_load_dwordx2 v[200:201], v138, s[70:71] offset:1536
	v_add_u32_e32 v147, 8, v140
	v_and_b32_e32 v146, 15, v147
	v_xor_b32_e32 v146, 8, v146
	v_bfe_u32 v148, v147, 4, 4
	v_mul_lo_u32 v146, v146, s92
	v_mul_lo_u32 v148, v148, s92
	v_mov_b32_e32 v147, v146
	v_mov_b32_e32 v149, v148
	ds_write2st64_b64 v77, v[146:147], v[148:149] offset1:2
	v_add_u32_e32 v138, 0x800, v74
	ds_read_u8 v139, v138
	v_add_u32_e32 v141, 0x800, v73
	ds_read_u8 v140, v141
	s_add_i32 s43, s67, 32
	v_mov_b32_e32 v138, s43
	ds_read2st64_b32 v[228:229], v138 offset1:1
	ds_read_b128 v[18:21], v227 offset:4096
	ds_read_b128 v[22:25], v227 offset:4112
	v_mov_b32_e32 v150, v63
	v_mov_b32_e32 v151, v64
	v_mov_b32_e32 v38, 0
	v_mov_b32_e32 v39, 0
	v_mov_b32_e32 v40, 0
	v_mov_b32_e32 v41, 0
	v_mov_b32_e32 v42, 0
	v_mov_b32_e32 v43, 0
	v_mov_b32_e32 v44, 0
	v_mov_b32_e32 v45, 0
	v_and_b32_e32 v78, 0xffff, v31
	v_lshrrev_b32_e32 v79, 16, v31
	v_lshl_add_u32 v78, v78, 7, v152
	v_lshl_add_u32 v79, v79, 7, v153
	s_mov_b32 m0, s77
	s_add_i32 s43, s77, 0x400
	global_load_lds_dwordx4 v78, s[50:51]
	s_mov_b32 m0, s43
	s_nop 0
	global_load_lds_dwordx4 v79, s[50:51]
	s_waitcnt vmcnt(12)
; __device__ __forceinline__ bf16 f2bf(float f) { return (bf16)f2bfu(f); }
; #define TR4(p_) __builtin_amdgcn_ds_read_tr4_b64_v2i32((LAS v2i*)(p_))
; #define VDMA(st_, k_) do { _Pragma("unroll") for (int i_ = 0; i_ < 4; ++i_) { \
;         const unsigned off_ = (unsigned)((st_) >> 2) * (16384u * 128u) + (PE_ID(E, 4 * ((st_) & 3) + i_) << 7) + ((i_ & 1) ? cx1 : cx0); \
;         __builtin_amdgcn_global_load_lds((const unsigned*)(V4 + off_), (LAS unsigned*)(ldsb + BUF[k_] + 1024 * i_), 16, 0, 0); } } while (0)
; __device__ __forceinline__ void peer_v_tokens(int j, const LAS unsigned short* EL, const LAS unsigned char* AL  , const LAS float* ASC  , const LAS int* SAL  , ...
;     ...
;         for (int st = 0; st < 16; ++st) {
;             const int p = st >> 2, q = st & 3;
;             if (st < 14) VDMA(st + 2, (st + 2) % 3);
;             if (st < 14) asm volatile("s_waitcnt vmcnt(8)" ::: "memory");
;             else if (st == 14) asm volatile("s_waitcnt vmcnt(4)" ::: "memory");
;             else asm volatile("s_waitcnt vmcnt(0)" ::: "memory");
;             if (q == 0) {
; #pragma unroll
;                 for (int r = 0; r < 4; ++r) { accH[r] = 0; accL[r] = 0; } }
; #pragma unroll
;             for (int tp = 0; tp < 2; ++tp) {
;                 const v2i ao = TR4(ATL + (2 * q + tp) * 128 + 8 * s16), ah = TR4(ATL + 1024 + (2 * q + tp) * 128 + 8 * s16);
; #pragma unroll
;                 for (int r = 0; r < 4; ++r) {
;                     const v2i d = TR4(ldsb + BUF[st % 3] + 2048 * tp + roff[r]);
;                     accH[r] = __builtin_amdgcn_sdot8(d.x, ah.x, accH[r], false); accH[r] = __builtin_amdgcn_sdot8(d.y, ah.y, accH[r], false);
;                     accL[r] = __builtin_amdgcn_sdot8(d.x, ao.x, accL[r], false); accL[r] = __builtin_amdgcn_sdot8(d.y, ao.y, accL[r], false);
;                 }
;             }
;             asm volatile("s_waitcnt lgkmcnt(0)" ::: "memory");
;             if (q == 3) {
; #pragma unroll
;                 for (int r = 0; r < 4; ++r) STASH[256 * p + 16 * (grp + 4 * r) + pc] = f2bf(asc * (float)(2 * ((accH[r] << 4) + accL[r]) + sa));
;             }
;         }
	v_add_u32_e32 v54, s79, v59
	v_add_u32_e32 v55, s79, v60
	v_add_u32_e32 v56, s79, v61
	v_add_u32_e32 v57, s79, v62
	ds_read_b64_tr_b4 v[50:51], v160 offset:128
	ds_read_b64_tr_b4 v[52:53], v160 offset:1152
	ds_read_b64_tr_b4 v[130:131], v54
	ds_read_b64_tr_b4 v[132:133], v55
	ds_read_b64_tr_b4 v[134:135], v56
	ds_read_b64_tr_b4 v[136:137], v57
	s_waitcnt lgkmcnt(12)
	v_dot8c_i32_i4_e32 v38, v122, v48
	v_dot8c_i32_i4_e32 v39, v122, v46
	v_dot8c_i32_i4_e32 v40, v124, v48
	v_dot8c_i32_i4_e32 v41, v124, v46
	v_dot8c_i32_i4_e32 v42, v126, v48
	v_dot8c_i32_i4_e32 v43, v126, v46
	v_dot8c_i32_i4_e32 v44, v128, v48
	v_dot8c_i32_i4_e32 v45, v128, v46
	v_dot8c_i32_i4_e32 v38, v123, v49
	v_dot8c_i32_i4_e32 v39, v123, v47
	v_dot8c_i32_i4_e32 v40, v125, v49
	v_dot8c_i32_i4_e32 v41, v125, v47
	v_dot8c_i32_i4_e32 v42, v127, v49
	v_dot8c_i32_i4_e32 v43, v127, v47
	v_dot8c_i32_i4_e32 v44, v129, v49
	v_dot8c_i32_i4_e32 v45, v129, v47
	v_and_b32_e32 v78, 0xffff, v32
	v_lshrrev_b32_e32 v79, 16, v32
	v_lshl_add_u32 v78, v78, 7, v152
	v_lshl_add_u32 v79, v79, 7, v153
	s_mov_b32 m0, s78
	s_add_i32 s43, s78, 0x400
	global_load_lds_dwordx4 v78, s[50:51]
	s_mov_b32 m0, s43
	s_nop 0
	global_load_lds_dwordx4 v79, s[50:51]
	s_waitcnt vmcnt(12)
	v_add_u32_e32 v54, s98, v59
	v_add_u32_e32 v55, s98, v60
	v_add_u32_e32 v56, s98, v61
	v_add_u32_e32 v57, s98, v62
	ds_read_b64_tr_b4 v[46:47], v160 offset:256
	ds_read_b64_tr_b4 v[48:49], v160 offset:1280
	ds_read_b64_tr_b4 v[122:123], v54
	ds_read_b64_tr_b4 v[124:125], v55
	ds_read_b64_tr_b4 v[126:127], v56
	ds_read_b64_tr_b4 v[128:129], v57
	s_waitcnt lgkmcnt(6)
	v_dot8c_i32_i4_e32 v38, v130, v52
	v_dot8c_i32_i4_e32 v39, v130, v50
	v_dot8c_i32_i4_e32 v40, v132, v52
	v_dot8c_i32_i4_e32 v41, v132, v50
	v_dot8c_i32_i4_e32 v42, v134, v52
	v_dot8c_i32_i4_e32 v43, v134, v50
	v_dot8c_i32_i4_e32 v44, v136, v52
	v_dot8c_i32_i4_e32 v45, v136, v50
	v_dot8c_i32_i4_e32 v38, v131, v53
	v_dot8c_i32_i4_e32 v39, v131, v51
	v_dot8c_i32_i4_e32 v40, v133, v53
	v_dot8c_i32_i4_e32 v41, v133, v51
	v_dot8c_i32_i4_e32 v42, v135, v53
	v_dot8c_i32_i4_e32 v43, v135, v51
	v_dot8c_i32_i4_e32 v44, v137, v53
	v_dot8c_i32_i4_e32 v45, v137, v51
	v_and_b32_e32 v78, 0xffff, v33
	v_lshrrev_b32_e32 v79, 16, v33
	v_lshl_add_u32 v78, v78, 7, v152
	v_lshl_add_u32 v79, v79, 7, v153
	s_mov_b32 m0, s79
	s_add_i32 s43, s79, 0x400
	global_load_lds_dwordx4 v78, s[50:51]
	s_mov_b32 m0, s43
	s_nop 0
	global_load_lds_dwordx4 v79, s[50:51]
	s_waitcnt vmcnt(12)
	v_add_u32_e32 v54, s99, v59
	v_add_u32_e32 v55, s99, v60
	v_add_u32_e32 v56, s99, v61
	v_add_u32_e32 v57, s99, v62
	ds_read_b64_tr_b4 v[50:51], v160 offset:384
	ds_read_b64_tr_b4 v[52:53], v160 offset:1408
	ds_read_b64_tr_b4 v[130:131], v54
	ds_read_b64_tr_b4 v[132:133], v55
	ds_read_b64_tr_b4 v[134:135], v56
	ds_read_b64_tr_b4 v[136:137], v57
	s_waitcnt lgkmcnt(6)
	v_dot8c_i32_i4_e32 v38, v122, v48
	v_dot8c_i32_i4_e32 v39, v122, v46
	v_dot8c_i32_i4_e32 v40, v124, v48
	v_dot8c_i32_i4_e32 v41, v124, v46
	v_dot8c_i32_i4_e32 v42, v126, v48
	v_dot8c_i32_i4_e32 v43, v126, v46
	v_dot8c_i32_i4_e32 v44, v128, v48
	v_dot8c_i32_i4_e32 v45, v128, v46
	v_dot8c_i32_i4_e32 v38, v123, v49
	v_dot8c_i32_i4_e32 v39, v123, v47
	v_dot8c_i32_i4_e32 v40, v125, v49
	v_dot8c_i32_i4_e32 v41, v125, v47
	v_dot8c_i32_i4_e32 v42, v127, v49
	v_dot8c_i32_i4_e32 v43, v127, v47
	v_dot8c_i32_i4_e32 v44, v129, v49
	v_dot8c_i32_i4_e32 v45, v129, v47
	s_waitcnt lgkmcnt(15)
	v_and_b32_e32 v78, 0xffff, v18
	v_lshrrev_b32_e32 v79, 16, v18
	v_lshl_add_u32 v78, v78, 7, v150
	v_lshl_add_u32 v79, v79, 7, v151
	s_mov_b32 m0, s98
	s_add_i32 s43, s98, 0x400
	global_load_lds_dwordx4 v78, s[50:51]
	s_mov_b32 m0, s43
	s_nop 0
	global_load_lds_dwordx4 v79, s[50:51]
	s_waitcnt vmcnt(12)
	v_add_u32_e32 v54, s76, v59
	v_add_u32_e32 v55, s76, v60
	v_add_u32_e32 v56, s76, v61
	v_add_u32_e32 v57, s76, v62
	ds_read_b64_tr_b4 v[46:47], v160 offset:512
	ds_read_b64_tr_b4 v[48:49], v160 offset:1536
	ds_read_b64_tr_b4 v[122:123], v54
	ds_read_b64_tr_b4 v[124:125], v55
	ds_read_b64_tr_b4 v[126:127], v56
	ds_read_b64_tr_b4 v[128:129], v57
	s_waitcnt lgkmcnt(6)
	v_dot8c_i32_i4_e32 v38, v130, v52
	v_dot8c_i32_i4_e32 v39, v130, v50
	v_dot8c_i32_i4_e32 v40, v132, v52
	v_dot8c_i32_i4_e32 v41, v132, v50
	v_dot8c_i32_i4_e32 v42, v134, v52
	v_dot8c_i32_i4_e32 v43, v134, v50
	v_dot8c_i32_i4_e32 v44, v136, v52
	v_dot8c_i32_i4_e32 v45, v136, v50
	v_dot8c_i32_i4_e32 v38, v131, v53
	v_dot8c_i32_i4_e32 v39, v131, v51
	v_dot8c_i32_i4_e32 v40, v133, v53
	v_dot8c_i32_i4_e32 v41, v133, v51
	v_dot8c_i32_i4_e32 v42, v135, v53
	v_dot8c_i32_i4_e32 v43, v135, v51
	v_dot8c_i32_i4_e32 v44, v137, v53
	v_dot8c_i32_i4_e32 v45, v137, v51
	v_and_b32_e32 v78, 0xffff, v19
	v_lshrrev_b32_e32 v79, 16, v19
	v_lshl_add_u32 v78, v78, 7, v150
	v_lshl_add_u32 v79, v79, 7, v151
	s_mov_b32 m0, s99
	s_add_i32 s43, s99, 0x400
	global_load_lds_dwordx4 v78, s[50:51]
	s_mov_b32 m0, s43
	s_nop 0
	global_load_lds_dwordx4 v79, s[50:51]
	s_waitcnt vmcnt(8)
	v_add_u32_e32 v54, s77, v59
	v_add_u32_e32 v55, s77, v60
	v_add_u32_e32 v56, s77, v61
	v_add_u32_e32 v57, s77, v62
	ds_read_b64_tr_b4 v[50:51], v160 offset:640
	ds_read_b64_tr_b4 v[52:53], v160 offset:1664
	ds_read_b64_tr_b4 v[130:131], v54
	ds_read_b64_tr_b4 v[132:133], v55
	ds_read_b64_tr_b4 v[134:135], v56
	ds_read_b64_tr_b4 v[136:137], v57
	s_waitcnt lgkmcnt(6)
	v_dot8c_i32_i4_e32 v38, v122, v48
	v_dot8c_i32_i4_e32 v39, v122, v46
	v_dot8c_i32_i4_e32 v40, v124, v48
	v_dot8c_i32_i4_e32 v41, v124, v46
	v_dot8c_i32_i4_e32 v42, v126, v48
	v_dot8c_i32_i4_e32 v43, v126, v46
	v_dot8c_i32_i4_e32 v44, v128, v48
	v_dot8c_i32_i4_e32 v45, v128, v46
	v_dot8c_i32_i4_e32 v38, v123, v49
	v_dot8c_i32_i4_e32 v39, v123, v47
	v_dot8c_i32_i4_e32 v40, v125, v49
	v_dot8c_i32_i4_e32 v41, v125, v47
	v_dot8c_i32_i4_e32 v42, v127, v49
	v_dot8c_i32_i4_e32 v43, v127, v47
	v_dot8c_i32_i4_e32 v44, v129, v49
	v_dot8c_i32_i4_e32 v45, v129, v47
	s_waitcnt lgkmcnt(15)
; __device__ __forceinline__ void peer_v_tokens(int j, const LAS unsigned short* EL, const LAS unsigned char* AL  , const LAS float* ASC  , const LAS int* SAL  , ...
;     ...
;         { const LAS v4u* ep = (const LAS v4u*)(EL + tl * 128 + 16 * g); const v4u e0 = ep[0], e1 = ep[1];
;           E[0] = e0.x; E[1] = e0.y; E[2] = e0.z; E[3] = e0.w; E[4] = e1.x; E[5] = e1.y; E[6] = e1.z; E[7] = e1.w; }
;         uint2 hv[4]; float4 gv[4];
;         { unsigned ho = (unsigned)t * (D / 4) + (unsigned)lane; asm volatile("" : "+v"(ho)); const uint2* hp = (const uint2*)HB + ho; const float4* gp = (const float4*)fng + lane;
; #pragma unroll
;           for (int jq = 0; jq < 4; ++jq) { hv[jq] = hp[64 * jq]; gv[jq] = gp[64 * jq]; } }
;         VDMA(0, 0); VDMA(1, 1);
; #pragma unroll
;         for (int m = 0; m < 2; ++m) {
;             const int idx = lane + 64 * m, tau = idx >> 4, sr = idx & 15, k = 16 * (sr & 7) + 2 * tau + (sr >> 3);
;             const int aq = (int)*(const LAS signed char*)(AL + tl * 128 + k); const int tq = aq + 8;
;             const unsigned lo = (((unsigned)tq & 15u) ^ 8u) * 0x11111111u, hi = ((unsigned)(tq >> 4) & 15u) * 0x11111111u;
;             typedef unsigned u2v __attribute__((ext_vector_type(2)));
;             u2v l2; l2.x = lo; l2.y = lo; u2v h2; h2.x = hi; h2.y = hi;
;             *(LAS u2v*)(ATL + 8 * idx) = l2; *(LAS u2v*)(ATL + 1024 + 8 * idx) = h2;
;         }
;         const float asc = ASC[tl]; const int sa = SAL[tl];
;         CFENCE();
;         int accH[4], accL[4];
; #pragma unroll
;         for (int st = 0; st < 16; ++st) {
;             const int p = st >> 2, q = st & 3;
;             if (st < 14) VDMA(st + 2, (st + 2) % 3);
;             if (st < 14) asm volatile("s_waitcnt vmcnt(8)" ::: "memory");
;             else if (st == 14) asm volatile("s_waitcnt vmcnt(4)" ::: "memory");
;             else asm volatile("s_waitcnt vmcnt(0)" ::: "memory");
;             if (q == 0) {
; #pragma unroll
;                 for (int r = 0; r < 4; ++r) { accH[r] = 0; accL[r] = 0; } }
; #pragma unroll
;             for (int tp = 0; tp < 2; ++tp) {
;                 const v2i ao = TR4(ATL + (2 * q + tp) * 128 + 8 * s16), ah = TR4(ATL + 1024 + (2 * q + tp) * 128 + 8 * s16);
; #pragma unroll
;                 for (int r = 0; r < 4; ++r) {
;                     const v2i d = TR4(ldsb + BUF[st % 3] + 2048 * tp + roff[r]);
	v_add_u32_e32 v143, 8, v139
	v_and_b32_e32 v142, 15, v143
	v_xor_b32_e32 v142, 8, v142
	v_bfe_u32 v144, v143, 4, 4
	v_mul_lo_u32 v142, v142, s92
	v_mul_lo_u32 v144, v144, s92
	v_mov_b32_e32 v143, v142
	v_mov_b32_e32 v145, v144
	ds_write2st64_b64 v159, v[142:143], v[144:145] offset1:2
	v_and_b32_e32 v78, 0xffff, v20
	v_lshrrev_b32_e32 v79, 16, v20
	v_lshl_add_u32 v78, v78, 7, v150
	v_lshl_add_u32 v79, v79, 7, v151
	s_mov_b32 m0, s76
	s_add_i32 s43, s76, 0x400
	global_load_lds_dwordx4 v78, s[50:51]
	s_mov_b32 m0, s43
	s_nop 0
	global_load_lds_dwordx4 v79, s[50:51]
	s_waitcnt vmcnt(8)
	v_add_u32_e32 v54, s78, v59
	v_add_u32_e32 v55, s78, v60
	v_add_u32_e32 v56, s78, v61
	v_add_u32_e32 v57, s78, v62
	ds_read_b64_tr_b4 v[46:47], v160 offset:768
	ds_read_b64_tr_b4 v[48:49], v160 offset:1792
	ds_read_b64_tr_b4 v[122:123], v54
	ds_read_b64_tr_b4 v[124:125], v55
	ds_read_b64_tr_b4 v[126:127], v56
	ds_read_b64_tr_b4 v[128:129], v57
	s_waitcnt lgkmcnt(7)
	v_dot8c_i32_i4_e32 v38, v130, v52
	v_dot8c_i32_i4_e32 v39, v130, v50
	v_dot8c_i32_i4_e32 v40, v132, v52
	v_dot8c_i32_i4_e32 v41, v132, v50
	v_dot8c_i32_i4_e32 v42, v134, v52
	v_dot8c_i32_i4_e32 v43, v134, v50
	v_dot8c_i32_i4_e32 v44, v136, v52
	v_dot8c_i32_i4_e32 v45, v136, v50
	v_dot8c_i32_i4_e32 v38, v131, v53
	v_dot8c_i32_i4_e32 v39, v131, v51
	v_dot8c_i32_i4_e32 v40, v133, v53
	v_dot8c_i32_i4_e32 v41, v133, v51
	v_dot8c_i32_i4_e32 v42, v135, v53
	v_dot8c_i32_i4_e32 v43, v135, v51
	v_dot8c_i32_i4_e32 v44, v137, v53
	v_dot8c_i32_i4_e32 v45, v137, v51
	v_and_b32_e32 v78, 0xffff, v21
	v_lshrrev_b32_e32 v79, 16, v21
	v_lshl_add_u32 v78, v78, 7, v150
	v_lshl_add_u32 v79, v79, 7, v151
	s_mov_b32 m0, s77
	s_add_i32 s43, s77, 0x400
	global_load_lds_dwordx4 v78, s[50:51]
	s_mov_b32 m0, s43
	s_nop 0
	global_load_lds_dwordx4 v79, s[50:51]
	s_waitcnt vmcnt(8)
	v_add_u32_e32 v54, s79, v59
	v_add_u32_e32 v55, s79, v60
	v_add_u32_e32 v56, s79, v61
	v_add_u32_e32 v57, s79, v62
	ds_read_b64_tr_b4 v[50:51], v160 offset:896
	ds_read_b64_tr_b4 v[52:53], v160 offset:1920
	ds_read_b64_tr_b4 v[130:131], v54
	ds_read_b64_tr_b4 v[132:133], v55
	ds_read_b64_tr_b4 v[134:135], v56
	ds_read_b64_tr_b4 v[136:137], v57
	s_waitcnt lgkmcnt(6)
	v_dot8c_i32_i4_e32 v38, v122, v48
	v_dot8c_i32_i4_e32 v39, v122, v46
	v_dot8c_i32_i4_e32 v40, v124, v48
	v_dot8c_i32_i4_e32 v41, v124, v46
	v_dot8c_i32_i4_e32 v42, v126, v48
	v_dot8c_i32_i4_e32 v43, v126, v46
	v_dot8c_i32_i4_e32 v44, v128, v48
	v_dot8c_i32_i4_e32 v45, v128, v46
	v_dot8c_i32_i4_e32 v38, v123, v49
	v_dot8c_i32_i4_e32 v39, v123, v47
	v_dot8c_i32_i4_e32 v40, v125, v49
	v_dot8c_i32_i4_e32 v41, v125, v47
	v_dot8c_i32_i4_e32 v42, v127, v49
	v_dot8c_i32_i4_e32 v43, v127, v47
	v_dot8c_i32_i4_e32 v44, v129, v49
	v_dot8c_i32_i4_e32 v45, v129, v47
	v_and_b32_e32 v78, 0xffff, v22
	v_lshrrev_b32_e32 v79, 16, v22
	v_lshl_add_u32 v78, v78, 7, v150
	v_lshl_add_u32 v79, v79, 7, v151
	s_mov_b32 m0, s78
	s_add_i32 s43, s78, 0x400
	global_load_lds_dwordx4 v78, s[50:51]
	s_mov_b32 m0, s43
	s_nop 0
	global_load_lds_dwordx4 v79, s[50:51]
	s_waitcnt vmcnt(8)
	v_add_u32_e32 v54, s98, v59
	v_add_u32_e32 v55, s98, v60
	v_add_u32_e32 v56, s98, v61
	v_add_u32_e32 v57, s98, v62
	ds_read_b64_tr_b4 v[46:47], v160
	ds_read_b64_tr_b4 v[48:49], v160 offset:1024
	ds_read_b64_tr_b4 v[122:123], v54
	ds_read_b64_tr_b4 v[124:125], v55
	ds_read_b64_tr_b4 v[126:127], v56
	ds_read_b64_tr_b4 v[128:129], v57
	s_waitcnt lgkmcnt(6)
	v_dot8c_i32_i4_e32 v38, v130, v52
	v_dot8c_i32_i4_e32 v39, v130, v50
	v_dot8c_i32_i4_e32 v40, v132, v52
	v_dot8c_i32_i4_e32 v41, v132, v50
	v_dot8c_i32_i4_e32 v42, v134, v52
	v_dot8c_i32_i4_e32 v43, v134, v50
	v_dot8c_i32_i4_e32 v44, v136, v52
	v_dot8c_i32_i4_e32 v45, v136, v50
	v_dot8c_i32_i4_e32 v38, v131, v53
	v_dot8c_i32_i4_e32 v39, v131, v51
	v_dot8c_i32_i4_e32 v40, v133, v53
	v_dot8c_i32_i4_e32 v41, v133, v51
	v_dot8c_i32_i4_e32 v42, v135, v53
	v_dot8c_i32_i4_e32 v43, v135, v51
	v_dot8c_i32_i4_e32 v44, v137, v53
	v_dot8c_i32_i4_e32 v45, v137, v51
	s_nop 3
	s_waitcnt lgkmcnt(15)
	v_lshlrev_b32_e32 v38, 5, v38
	v_lshlrev_b32_e32 v39, 1, v39
	v_add3_u32 v38, v39, v229, v38
	v_cvt_f32_i32_e32 v38, v38
	v_mul_f32_e32 v38, v228, v38
	v_lshlrev_b32_e32 v40, 5, v40
	v_lshlrev_b32_e32 v41, 1, v41
	v_add3_u32 v40, v41, v229, v40
	v_cvt_f32_i32_e32 v40, v40
	v_mul_f32_e32 v40, v228, v40
	v_lshlrev_b32_e32 v42, 5, v42
	v_lshlrev_b32_e32 v43, 1, v43
	v_add3_u32 v42, v43, v229, v42
	v_cvt_f32_i32_e32 v42, v42
	v_mul_f32_e32 v42, v228, v42
	v_lshlrev_b32_e32 v44, 5, v44
	v_lshlrev_b32_e32 v45, 1, v45
	v_add3_u32 v44, v45, v229, v44
	v_cvt_f32_i32_e32 v44, v44
	v_mul_f32_e32 v44, v228, v44
	v_cvt_pk_bf16_f32 v176, v38, v40
	v_cvt_pk_bf16_f32 v177, v42, v44
	v_add_u32_e32 v147, 8, v140
	v_and_b32_e32 v146, 15, v147
	v_xor_b32_e32 v146, 8, v146
	v_bfe_u32 v148, v147, 4, 4
	v_mul_lo_u32 v146, v146, s92
	v_mul_lo_u32 v148, v148, s92
	v_mov_b32_e32 v147, v146
	v_mov_b32_e32 v149, v148
	ds_write2st64_b64 v77, v[146:147], v[148:149] offset1:2
	v_add_u32_e32 v138, 0xc00, v74
	ds_read_u8 v139, v138
	v_add_u32_e32 v141, 0xc00, v73
	ds_read_u8 v140, v141
	s_add_i32 s43, s67, 64
	v_mov_b32_e32 v138, s43
	ds_read2st64_b32 v[228:229], v138 offset1:1
	ds_read_b128 v[26:29], v227 offset:6144
	ds_read_b128 v[30:33], v227 offset:6160
	v_mov_b32_e32 v38, 0
	v_mov_b32_e32 v39, 0
	v_mov_b32_e32 v40, 0
	v_mov_b32_e32 v41, 0
	v_mov_b32_e32 v42, 0
	v_mov_b32_e32 v43, 0
	v_mov_b32_e32 v44, 0
	v_mov_b32_e32 v45, 0
	v_and_b32_e32 v78, 0xffff, v23
	v_lshrrev_b32_e32 v79, 16, v23
	v_lshl_add_u32 v78, v78, 7, v150
	v_lshl_add_u32 v79, v79, 7, v151
	s_mov_b32 m0, s79
	s_add_i32 s43, s79, 0x400
	global_load_lds_dwordx4 v78, s[50:51]
	s_mov_b32 m0, s43
	s_nop 0
	global_load_lds_dwordx4 v79, s[50:51]
	s_waitcnt vmcnt(8)
; #define LAS __attribute__((address_space(3)))
; __device__ __forceinline__ bf16 f2bf(float f) { return (bf16)f2bfu(f); }
; #define TR4(p_) __builtin_amdgcn_ds_read_tr4_b64_v2i32((LAS v2i*)(p_))
; #define CFENCE() asm volatile("" ::: "memory")
; __device__ __forceinline__ void peer_v_tokens(int j, const LAS unsigned short* EL, const LAS unsigned char* AL  , const LAS float* ASC  , const LAS int* SAL  , ...
;     ...
;         for (int st = 0; st < 16; ++st) {
;             const int p = st >> 2, q = st & 3;
;             if (st < 14) VDMA(st + 2, (st + 2) % 3);
;             if (st < 14) asm volatile("s_waitcnt vmcnt(8)" ::: "memory");
;             else if (st == 14) asm volatile("s_waitcnt vmcnt(4)" ::: "memory");
;             else asm volatile("s_waitcnt vmcnt(0)" ::: "memory");
;             if (q == 0) {
; #pragma unroll
;                 for (int r = 0; r < 4; ++r) { accH[r] = 0; accL[r] = 0; } }
; #pragma unroll
;             for (int tp = 0; tp < 2; ++tp) {
;                 const v2i ao = TR4(ATL + (2 * q + tp) * 128 + 8 * s16), ah = TR4(ATL + 1024 + (2 * q + tp) * 128 + 8 * s16);
; #pragma unroll
;                 for (int r = 0; r < 4; ++r) {
;                     const v2i d = TR4(ldsb + BUF[st % 3] + 2048 * tp + roff[r]);
;                     accH[r] = __builtin_amdgcn_sdot8(d.x, ah.x, accH[r], false); accH[r] = __builtin_amdgcn_sdot8(d.y, ah.y, accH[r], false);
;                     accL[r] = __builtin_amdgcn_sdot8(d.x, ao.x, accL[r], false); accL[r] = __builtin_amdgcn_sdot8(d.y, ao.y, accL[r], false);
;                 }
;             }
;             asm volatile("s_waitcnt lgkmcnt(0)" ::: "memory");
;             if (q == 3) {
; #pragma unroll
;                 for (int r = 0; r < 4; ++r) STASH[256 * p + 16 * (grp + 4 * r) + pc] = f2bf(asc * (float)(2 * ((accH[r] << 4) + accL[r]) + sa));
;             }
;         }
;         CFENCE();
;         {
;             float4 v[4]; float ss = 0.f;
; #pragma unroll
;             for (int jq = 0; jq < 4; ++jq) { typedef unsigned u2v __attribute__((ext_vector_type(2))); const u2v pw = *(const LAS u2v*)(STASH + 4 * lane + 256 * jq); const uint2 hw = hv[jq];
	v_add_u32_e32 v54, s99, v59
	v_add_u32_e32 v55, s99, v60
	v_add_u32_e32 v56, s99, v61
	v_add_u32_e32 v57, s99, v62
	ds_read_b64_tr_b4 v[50:51], v160 offset:128
	ds_read_b64_tr_b4 v[52:53], v160 offset:1152
	ds_read_b64_tr_b4 v[130:131], v54
	ds_read_b64_tr_b4 v[132:133], v55
	ds_read_b64_tr_b4 v[134:135], v56
	ds_read_b64_tr_b4 v[136:137], v57
	s_waitcnt lgkmcnt(12)
	v_dot8c_i32_i4_e32 v38, v122, v48
	v_dot8c_i32_i4_e32 v39, v122, v46
	v_dot8c_i32_i4_e32 v40, v124, v48
	v_dot8c_i32_i4_e32 v41, v124, v46
	v_dot8c_i32_i4_e32 v42, v126, v48
	v_dot8c_i32_i4_e32 v43, v126, v46
	v_dot8c_i32_i4_e32 v44, v128, v48
	v_dot8c_i32_i4_e32 v45, v128, v46
	v_dot8c_i32_i4_e32 v38, v123, v49
	v_dot8c_i32_i4_e32 v39, v123, v47
	v_dot8c_i32_i4_e32 v40, v125, v49
	v_dot8c_i32_i4_e32 v41, v125, v47
	v_dot8c_i32_i4_e32 v42, v127, v49
	v_dot8c_i32_i4_e32 v43, v127, v47
	v_dot8c_i32_i4_e32 v44, v129, v49
	v_dot8c_i32_i4_e32 v45, v129, v47
	v_and_b32_e32 v78, 0xffff, v24
	v_lshrrev_b32_e32 v79, 16, v24
	v_lshl_add_u32 v78, v78, 7, v150
	v_lshl_add_u32 v79, v79, 7, v151
	s_mov_b32 m0, s98
	s_add_i32 s43, s98, 0x400
	global_load_lds_dwordx4 v78, s[50:51]
	s_mov_b32 m0, s43
	s_nop 0
	global_load_lds_dwordx4 v79, s[50:51]
	s_waitcnt vmcnt(8)
	v_add_u32_e32 v54, s76, v59
	v_add_u32_e32 v55, s76, v60
	v_add_u32_e32 v56, s76, v61
	v_add_u32_e32 v57, s76, v62
	ds_read_b64_tr_b4 v[46:47], v160 offset:256
	ds_read_b64_tr_b4 v[48:49], v160 offset:1280
	ds_read_b64_tr_b4 v[122:123], v54
	ds_read_b64_tr_b4 v[124:125], v55
	ds_read_b64_tr_b4 v[126:127], v56
	ds_read_b64_tr_b4 v[128:129], v57
	s_waitcnt lgkmcnt(6)
	v_dot8c_i32_i4_e32 v38, v130, v52
	v_dot8c_i32_i4_e32 v39, v130, v50
	v_dot8c_i32_i4_e32 v40, v132, v52
	v_dot8c_i32_i4_e32 v41, v132, v50
	v_dot8c_i32_i4_e32 v42, v134, v52
	v_dot8c_i32_i4_e32 v43, v134, v50
	v_dot8c_i32_i4_e32 v44, v136, v52
	v_dot8c_i32_i4_e32 v45, v136, v50
	v_dot8c_i32_i4_e32 v38, v131, v53
	v_dot8c_i32_i4_e32 v39, v131, v51
	v_dot8c_i32_i4_e32 v40, v133, v53
	v_dot8c_i32_i4_e32 v41, v133, v51
	v_dot8c_i32_i4_e32 v42, v135, v53
	v_dot8c_i32_i4_e32 v43, v135, v51
	v_dot8c_i32_i4_e32 v44, v137, v53
	v_dot8c_i32_i4_e32 v45, v137, v51
	ds_write_b16 v65, v162
	ds_write_b16_d16_hi v65, v162 offset:128
	ds_write_b16 v65, v163 offset:256
	ds_write_b16_d16_hi v65, v163 offset:384
	ds_write_b16 v65, v164 offset:512
	ds_write_b16_d16_hi v65, v164 offset:640
	ds_write_b16 v65, v165 offset:768
	ds_write_b16_d16_hi v65, v165 offset:896
	ds_write_b16 v65, v166 offset:1024
	ds_write_b16_d16_hi v65, v166 offset:1152
	ds_write_b16 v65, v167 offset:1280
	ds_write_b16_d16_hi v65, v167 offset:1408
	ds_write_b16 v65, v168 offset:1536
	ds_write_b16_d16_hi v65, v168 offset:1664
	ds_write_b16 v65, v169 offset:1792
	ds_write_b16_d16_hi v65, v169 offset:1920
	ds_read_b64 v[202:203], v154
	ds_read_b64 v[204:205], v154 offset:512
	ds_read_b64 v[206:207], v154 offset:1024
	ds_read_b64 v[208:209], v154 offset:1536
	v_and_b32_e32 v78, 0xffff, v25
	v_lshrrev_b32_e32 v79, 16, v25
	v_lshl_add_u32 v78, v78, 7, v150
	v_lshl_add_u32 v79, v79, 7, v151
	s_mov_b32 m0, s99
	s_add_i32 s43, s99, 0x400
	global_load_lds_dwordx4 v78, s[50:51]
	s_mov_b32 m0, s43
	s_nop 0
	global_load_lds_dwordx4 v79, s[50:51]
	s_waitcnt vmcnt(8)
	v_add_u32_e32 v54, s77, v59
	v_add_u32_e32 v55, s77, v60
	v_add_u32_e32 v56, s77, v61
	v_add_u32_e32 v57, s77, v62
	ds_read_b64_tr_b4 v[50:51], v160 offset:384
	ds_read_b64_tr_b4 v[52:53], v160 offset:1408
	ds_read_b64_tr_b4 v[130:131], v54
	ds_read_b64_tr_b4 v[132:133], v55
	ds_read_b64_tr_b4 v[134:135], v56
	ds_read_b64_tr_b4 v[136:137], v57
	s_waitcnt lgkmcnt(15)
	v_dot8c_i32_i4_e32 v38, v122, v48
	v_dot8c_i32_i4_e32 v39, v122, v46
	v_dot8c_i32_i4_e32 v40, v124, v48
	v_dot8c_i32_i4_e32 v41, v124, v46
	v_dot8c_i32_i4_e32 v42, v126, v48
	v_dot8c_i32_i4_e32 v43, v126, v46
	v_dot8c_i32_i4_e32 v44, v128, v48
	v_dot8c_i32_i4_e32 v45, v128, v46
	v_dot8c_i32_i4_e32 v38, v123, v49
	v_dot8c_i32_i4_e32 v39, v123, v47
	v_dot8c_i32_i4_e32 v40, v125, v49
	v_dot8c_i32_i4_e32 v41, v125, v47
	v_dot8c_i32_i4_e32 v42, v127, v49
	v_dot8c_i32_i4_e32 v43, v127, v47
	v_dot8c_i32_i4_e32 v44, v129, v49
	v_dot8c_i32_i4_e32 v45, v129, v47
	s_waitcnt lgkmcnt(15)
	v_and_b32_e32 v78, 0xffff, v26
	v_lshrrev_b32_e32 v79, 16, v26
	v_lshl_add_u32 v78, v78, 7, v150
	v_lshl_add_u32 v79, v79, 7, v151
	s_mov_b32 m0, s76
	s_add_i32 s43, s76, 0x400
	global_load_lds_dwordx4 v78, s[50:51]
	s_mov_b32 m0, s43
	s_nop 0
	global_load_lds_dwordx4 v79, s[50:51]
	s_waitcnt vmcnt(8)
	v_add_u32_e32 v54, s78, v59
	v_add_u32_e32 v55, s78, v60
	v_add_u32_e32 v56, s78, v61
	v_add_u32_e32 v57, s78, v62
	ds_read_b64_tr_b4 v[46:47], v160 offset:512
	ds_read_b64_tr_b4 v[48:49], v160 offset:1536
	ds_read_b64_tr_b4 v[122:123], v54
	ds_read_b64_tr_b4 v[124:125], v55
	ds_read_b64_tr_b4 v[126:127], v56
	ds_read_b64_tr_b4 v[128:129], v57
	s_waitcnt lgkmcnt(6)
	v_dot8c_i32_i4_e32 v38, v130, v52
	v_dot8c_i32_i4_e32 v39, v130, v50
	v_dot8c_i32_i4_e32 v40, v132, v52
	v_dot8c_i32_i4_e32 v41, v132, v50
	v_dot8c_i32_i4_e32 v42, v134, v52
	v_dot8c_i32_i4_e32 v43, v134, v50
	v_dot8c_i32_i4_e32 v44, v136, v52
	v_dot8c_i32_i4_e32 v45, v136, v50
	v_dot8c_i32_i4_e32 v38, v131, v53
	v_dot8c_i32_i4_e32 v39, v131, v51
	v_dot8c_i32_i4_e32 v40, v133, v53
	v_dot8c_i32_i4_e32 v41, v133, v51
	v_dot8c_i32_i4_e32 v42, v135, v53
	v_dot8c_i32_i4_e32 v43, v135, v51
	v_dot8c_i32_i4_e32 v44, v137, v53
	v_dot8c_i32_i4_e32 v45, v137, v51
	v_and_b32_e32 v78, 0xffff, v27
	v_lshrrev_b32_e32 v79, 16, v27
	v_lshl_add_u32 v78, v78, 7, v150
	v_lshl_add_u32 v79, v79, 7, v151
	s_mov_b32 m0, s77
	s_add_i32 s43, s77, 0x400
	global_load_lds_dwordx4 v78, s[50:51]
	s_mov_b32 m0, s43
	s_nop 0
	global_load_lds_dwordx4 v79, s[50:51]
	s_waitcnt vmcnt(8)
; __device__ __forceinline__ bf16 f2bf(float f) { return (bf16)f2bfu(f); }
; #define TR4(p_) __builtin_amdgcn_ds_read_tr4_b64_v2i32((LAS v2i*)(p_))
; #define VDMA(st_, k_) do { _Pragma("unroll") for (int i_ = 0; i_ < 4; ++i_) { \
;         const unsigned off_ = (unsigned)((st_) >> 2) * (16384u * 128u) + (PE_ID(E, 4 * ((st_) & 3) + i_) << 7) + ((i_ & 1) ? cx1 : cx0); \
;         __builtin_amdgcn_global_load_lds((const unsigned*)(V4 + off_), (LAS unsigned*)(ldsb + BUF[k_] + 1024 * i_), 16, 0, 0); } } while (0)
; __device__ __forceinline__ void peer_v_tokens(int j, const LAS unsigned short* EL, const LAS unsigned char* AL  , const LAS float* ASC  , const LAS int* SAL  , ...
;     ...
;         for (int st = 0; st < 16; ++st) {
;             const int p = st >> 2, q = st & 3;
;             if (st < 14) VDMA(st + 2, (st + 2) % 3);
;             if (st < 14) asm volatile("s_waitcnt vmcnt(8)" ::: "memory");
;             else if (st == 14) asm volatile("s_waitcnt vmcnt(4)" ::: "memory");
;             else asm volatile("s_waitcnt vmcnt(0)" ::: "memory");
;             if (q == 0) {
; #pragma unroll
;                 for (int r = 0; r < 4; ++r) { accH[r] = 0; accL[r] = 0; } }
; #pragma unroll
;             for (int tp = 0; tp < 2; ++tp) {
;                 const v2i ao = TR4(ATL + (2 * q + tp) * 128 + 8 * s16), ah = TR4(ATL + 1024 + (2 * q + tp) * 128 + 8 * s16);
; #pragma unroll
;                 for (int r = 0; r < 4; ++r) {
;                     const v2i d = TR4(ldsb + BUF[st % 3] + 2048 * tp + roff[r]);
;                     accH[r] = __builtin_amdgcn_sdot8(d.x, ah.x, accH[r], false); accH[r] = __builtin_amdgcn_sdot8(d.y, ah.y, accH[r], false);
;                     accL[r] = __builtin_amdgcn_sdot8(d.x, ao.x, accL[r], false); accL[r] = __builtin_amdgcn_sdot8(d.y, ao.y, accL[r], false);
;                 }
;             }
;             asm volatile("s_waitcnt lgkmcnt(0)" ::: "memory");
;             if (q == 3) {
; #pragma unroll
;                 for (int r = 0; r < 4; ++r) STASH[256 * p + 16 * (grp + 4 * r) + pc] = f2bf(asc * (float)(2 * ((accH[r] << 4) + accL[r]) + sa));
;             }
;         }
	v_add_u32_e32 v54, s79, v59
	v_add_u32_e32 v55, s79, v60
	v_add_u32_e32 v56, s79, v61
	v_add_u32_e32 v57, s79, v62
	ds_read_b64_tr_b4 v[50:51], v160 offset:640
	ds_read_b64_tr_b4 v[52:53], v160 offset:1664
	ds_read_b64_tr_b4 v[130:131], v54
	ds_read_b64_tr_b4 v[132:133], v55
	ds_read_b64_tr_b4 v[134:135], v56
	ds_read_b64_tr_b4 v[136:137], v57
	s_waitcnt lgkmcnt(6)
	v_dot8c_i32_i4_e32 v38, v122, v48
	v_dot8c_i32_i4_e32 v39, v122, v46
	v_dot8c_i32_i4_e32 v40, v124, v48
	v_dot8c_i32_i4_e32 v41, v124, v46
	v_dot8c_i32_i4_e32 v42, v126, v48
	v_dot8c_i32_i4_e32 v43, v126, v46
	v_dot8c_i32_i4_e32 v44, v128, v48
	v_dot8c_i32_i4_e32 v45, v128, v46
	v_dot8c_i32_i4_e32 v38, v123, v49
	v_dot8c_i32_i4_e32 v39, v123, v47
	v_dot8c_i32_i4_e32 v40, v125, v49
	v_dot8c_i32_i4_e32 v41, v125, v47
	v_dot8c_i32_i4_e32 v42, v127, v49
	v_dot8c_i32_i4_e32 v43, v127, v47
	v_dot8c_i32_i4_e32 v44, v129, v49
	v_dot8c_i32_i4_e32 v45, v129, v47
	s_waitcnt lgkmcnt(15)
	v_add_u32_e32 v143, 8, v139
	v_and_b32_e32 v142, 15, v143
	v_xor_b32_e32 v142, 8, v142
	v_bfe_u32 v144, v143, 4, 4
	v_mul_lo_u32 v142, v142, s92
	v_mul_lo_u32 v144, v144, s92
	v_mov_b32_e32 v143, v142
	v_mov_b32_e32 v145, v144
	ds_write2st64_b64 v159, v[142:143], v[144:145] offset1:2
	v_and_b32_e32 v78, 0xffff, v28
	v_lshrrev_b32_e32 v79, 16, v28
	v_lshl_add_u32 v78, v78, 7, v150
	v_lshl_add_u32 v79, v79, 7, v151
	s_mov_b32 m0, s78
	s_add_i32 s43, s78, 0x400
	global_load_lds_dwordx4 v78, s[50:51]
	s_mov_b32 m0, s43
	s_nop 0
	global_load_lds_dwordx4 v79, s[50:51]
	s_waitcnt vmcnt(8)
	v_add_u32_e32 v54, s98, v59
	v_add_u32_e32 v55, s98, v60
	v_add_u32_e32 v56, s98, v61
	v_add_u32_e32 v57, s98, v62
	ds_read_b64_tr_b4 v[46:47], v160 offset:768
	ds_read_b64_tr_b4 v[48:49], v160 offset:1792
	ds_read_b64_tr_b4 v[122:123], v54
	ds_read_b64_tr_b4 v[124:125], v55
	ds_read_b64_tr_b4 v[126:127], v56
	ds_read_b64_tr_b4 v[128:129], v57
	s_waitcnt lgkmcnt(7)
	v_dot8c_i32_i4_e32 v38, v130, v52
	v_dot8c_i32_i4_e32 v39, v130, v50
	v_dot8c_i32_i4_e32 v40, v132, v52
	v_dot8c_i32_i4_e32 v41, v132, v50
	v_dot8c_i32_i4_e32 v42, v134, v52
	v_dot8c_i32_i4_e32 v43, v134, v50
	v_dot8c_i32_i4_e32 v44, v136, v52
	v_dot8c_i32_i4_e32 v45, v136, v50
	v_dot8c_i32_i4_e32 v38, v131, v53
	v_dot8c_i32_i4_e32 v39, v131, v51
	v_dot8c_i32_i4_e32 v40, v133, v53
	v_dot8c_i32_i4_e32 v41, v133, v51
	v_dot8c_i32_i4_e32 v42, v135, v53
	v_dot8c_i32_i4_e32 v43, v135, v51
	v_dot8c_i32_i4_e32 v44, v137, v53
	v_dot8c_i32_i4_e32 v45, v137, v51
	v_and_b32_e32 v78, 0xffff, v29
	v_lshrrev_b32_e32 v79, 16, v29
	v_lshl_add_u32 v78, v78, 7, v150
	v_lshl_add_u32 v79, v79, 7, v151
	s_mov_b32 m0, s79
	s_add_i32 s43, s79, 0x400
	global_load_lds_dwordx4 v78, s[50:51]
	s_mov_b32 m0, s43
	s_nop 0
	global_load_lds_dwordx4 v79, s[50:51]
	s_waitcnt vmcnt(8)
	v_add_u32_e32 v54, s99, v59
	v_add_u32_e32 v55, s99, v60
	v_add_u32_e32 v56, s99, v61
	v_add_u32_e32 v57, s99, v62
	ds_read_b64_tr_b4 v[50:51], v160 offset:896
	ds_read_b64_tr_b4 v[52:53], v160 offset:1920
	ds_read_b64_tr_b4 v[130:131], v54
	ds_read_b64_tr_b4 v[132:133], v55
	ds_read_b64_tr_b4 v[134:135], v56
	ds_read_b64_tr_b4 v[136:137], v57
	s_waitcnt lgkmcnt(6)
	v_dot8c_i32_i4_e32 v38, v122, v48
	v_dot8c_i32_i4_e32 v39, v122, v46
	v_dot8c_i32_i4_e32 v40, v124, v48
	v_dot8c_i32_i4_e32 v41, v124, v46
	v_dot8c_i32_i4_e32 v42, v126, v48
	v_dot8c_i32_i4_e32 v43, v126, v46
	v_dot8c_i32_i4_e32 v44, v128, v48
	v_dot8c_i32_i4_e32 v45, v128, v46
	v_dot8c_i32_i4_e32 v38, v123, v49
	v_dot8c_i32_i4_e32 v39, v123, v47
	v_dot8c_i32_i4_e32 v40, v125, v49
	v_dot8c_i32_i4_e32 v41, v125, v47
	v_dot8c_i32_i4_e32 v42, v127, v49
	v_dot8c_i32_i4_e32 v43, v127, v47
	v_dot8c_i32_i4_e32 v44, v129, v49
	v_dot8c_i32_i4_e32 v45, v129, v47
	v_and_b32_e32 v78, 0xffff, v30
	v_lshrrev_b32_e32 v79, 16, v30
	v_lshl_add_u32 v78, v78, 7, v150
	v_lshl_add_u32 v79, v79, 7, v151
	s_mov_b32 m0, s98
	s_add_i32 s43, s98, 0x400
	global_load_lds_dwordx4 v78, s[50:51]
	s_mov_b32 m0, s43
	s_nop 0
	global_load_lds_dwordx4 v79, s[50:51]
	s_waitcnt vmcnt(8)
	v_add_u32_e32 v54, s76, v59
	v_add_u32_e32 v55, s76, v60
	v_add_u32_e32 v56, s76, v61
	v_add_u32_e32 v57, s76, v62
	ds_read_b64_tr_b4 v[46:47], v160
	ds_read_b64_tr_b4 v[48:49], v160 offset:1024
	ds_read_b64_tr_b4 v[122:123], v54
	ds_read_b64_tr_b4 v[124:125], v55
	ds_read_b64_tr_b4 v[126:127], v56
	ds_read_b64_tr_b4 v[128:129], v57
	s_waitcnt lgkmcnt(6)
	v_dot8c_i32_i4_e32 v38, v130, v52
	v_dot8c_i32_i4_e32 v39, v130, v50
	v_dot8c_i32_i4_e32 v40, v132, v52
	v_dot8c_i32_i4_e32 v41, v132, v50
	v_dot8c_i32_i4_e32 v42, v134, v52
	v_dot8c_i32_i4_e32 v43, v134, v50
	v_dot8c_i32_i4_e32 v44, v136, v52
	v_dot8c_i32_i4_e32 v45, v136, v50
	v_dot8c_i32_i4_e32 v38, v131, v53
	v_dot8c_i32_i4_e32 v39, v131, v51
	v_dot8c_i32_i4_e32 v40, v133, v53
	v_dot8c_i32_i4_e32 v41, v133, v51
	v_dot8c_i32_i4_e32 v42, v135, v53
	v_dot8c_i32_i4_e32 v43, v135, v51
	v_dot8c_i32_i4_e32 v44, v137, v53
	v_dot8c_i32_i4_e32 v45, v137, v51
	s_nop 3
	s_waitcnt lgkmcnt(15)
; __device__ __forceinline__ void peer_v_tokens(int j, const LAS unsigned short* EL, const LAS unsigned char* AL  , const LAS float* ASC  , const LAS int* SAL  , ...
;     ...
;         for (int st = 0; st < 16; ++st) {
;             const int p = st >> 2, q = st & 3;
;             if (st < 14) VDMA(st + 2, (st + 2) % 3);
;             if (st < 14) asm volatile("s_waitcnt vmcnt(8)" ::: "memory");
;             else if (st == 14) asm volatile("s_waitcnt vmcnt(4)" ::: "memory");
;             else asm volatile("s_waitcnt vmcnt(0)" ::: "memory");
;             if (q == 0) {
; #pragma unroll
;                 for (int r = 0; r < 4; ++r) { accH[r] = 0; accL[r] = 0; } }
; #pragma unroll
;             for (int tp = 0; tp < 2; ++tp) {
;                 const v2i ao = TR4(ATL + (2 * q + tp) * 128 + 8 * s16), ah = TR4(ATL + 1024 + (2 * q + tp) * 128 + 8 * s16);
; #pragma unroll
;                 for (int r = 0; r < 4; ++r) {
;                     const v2i d = TR4(ldsb + BUF[st % 3] + 2048 * tp + roff[r]);
;                     accH[r] = __builtin_amdgcn_sdot8(d.x, ah.x, accH[r], false); accH[r] = __builtin_amdgcn_sdot8(d.y, ah.y, accH[r], false);
;                     accL[r] = __builtin_amdgcn_sdot8(d.x, ao.x, accL[r], false); accL[r] = __builtin_amdgcn_sdot8(d.y, ao.y, accL[r], false);
;                 }
;             }
;             asm volatile("s_waitcnt lgkmcnt(0)" ::: "memory");
;             if (q == 3) {
; #pragma unroll
;                 for (int r = 0; r < 4; ++r) STASH[256 * p + 16 * (grp + 4 * r) + pc] = f2bf(asc * (float)(2 * ((accH[r] << 4) + accL[r]) + sa));
;             }
;         }
;         CFENCE();
;         {
;             float4 v[4]; float ss = 0.f;
; #pragma unroll
;             for (int jq = 0; jq < 4; ++jq) { typedef unsigned u2v __attribute__((ext_vector_type(2))); const u2v pw = *(const LAS u2v*)(STASH + 4 * lane + 256 * jq); const uint2 hw = hv[jq];
;                 v[jq] = make_float4(__uint_as_float(hw.x << 16) + __uint_as_float(pw.x << 16), __uint_as_float(hw.x & 0xffff0000u) + __uint_as_float(pw.x & 0xffff0000u),
;                                     __uint_as_float(hw.y << 16) + __uint_as_float(pw.y << 16), __uint_as_float(hw.y & 0xffff0000u) + __uint_as_float(pw.y & 0xffff0000u));
;                 ss += v[jq].x * v[jq].x + v[jq].y * v[jq].y + v[jq].z * v[jq].z + v[jq].w * v[jq].w; }
;             ss = wave_sum(ss);
	v_lshlrev_b32_e32 v38, 5, v38
	v_lshlrev_b32_e32 v39, 1, v39
	v_add3_u32 v38, v39, v229, v38
	v_cvt_f32_i32_e32 v38, v38
	v_mul_f32_e32 v38, v228, v38
	v_lshlrev_b32_e32 v40, 5, v40
	v_lshlrev_b32_e32 v41, 1, v41
	v_add3_u32 v40, v41, v229, v40
	v_cvt_f32_i32_e32 v40, v40
	v_mul_f32_e32 v40, v228, v40
	v_lshlrev_b32_e32 v42, 5, v42
	v_lshlrev_b32_e32 v43, 1, v43
	v_add3_u32 v42, v43, v229, v42
	v_cvt_f32_i32_e32 v42, v42
	v_mul_f32_e32 v42, v228, v42
	v_lshlrev_b32_e32 v44, 5, v44
	v_lshlrev_b32_e32 v45, 1, v45
	v_add3_u32 v44, v45, v229, v44
	v_cvt_f32_i32_e32 v44, v44
	v_mul_f32_e32 v44, v228, v44
	v_cvt_pk_bf16_f32 v178, v38, v40
	v_cvt_pk_bf16_f32 v179, v42, v44
	v_add_u32_e32 v147, 8, v140
	v_and_b32_e32 v146, 15, v147
	v_xor_b32_e32 v146, 8, v146
	v_bfe_u32 v148, v147, 4, 4
	v_mul_lo_u32 v146, v146, s92
	v_mul_lo_u32 v148, v148, s92
	v_mov_b32_e32 v147, v146
	v_mov_b32_e32 v149, v148
	ds_write2st64_b64 v77, v[146:147], v[148:149] offset1:2
	v_add_u32_e32 v138, 0x800, v74
	ds_read_u8 v139, v138
	v_add_u32_e32 v141, 0x800, v73
	ds_read_u8 v140, v141
	s_add_i32 s43, s67, 96
	v_mov_b32_e32 v138, s43
	ds_read2st64_b32 v[228:229], v138 offset1:1
	ds_read_b128 v[18:21], v227 offset:4096
	ds_read_b128 v[22:25], v227 offset:4112
	v_add_u32_e32 v152, 0x200000, v63
	v_add_u32_e32 v153, 0x200000, v64
	v_mov_b32_e32 v38, 0
	v_mov_b32_e32 v39, 0
	v_mov_b32_e32 v40, 0
	v_mov_b32_e32 v41, 0
	v_mov_b32_e32 v42, 0
	v_mov_b32_e32 v43, 0
	v_mov_b32_e32 v44, 0
	v_mov_b32_e32 v45, 0
	v_and_b32_e32 v78, 0xffff, v31
	v_lshrrev_b32_e32 v79, 16, v31
	v_lshl_add_u32 v78, v78, 7, v150
	v_lshl_add_u32 v79, v79, 7, v151
	s_mov_b32 m0, s99
	s_add_i32 s43, s99, 0x400
	global_load_lds_dwordx4 v78, s[50:51]
	s_mov_b32 m0, s43
	s_nop 0
	global_load_lds_dwordx4 v79, s[50:51]
	s_waitcnt vmcnt(8)
	v_add_u32_e32 v54, s77, v59
	v_add_u32_e32 v55, s77, v60
	v_add_u32_e32 v56, s77, v61
	v_add_u32_e32 v57, s77, v62
	ds_read_b64_tr_b4 v[50:51], v160 offset:128
	ds_read_b64_tr_b4 v[52:53], v160 offset:1152
	ds_read_b64_tr_b4 v[130:131], v54
	ds_read_b64_tr_b4 v[132:133], v55
	ds_read_b64_tr_b4 v[134:135], v56
	ds_read_b64_tr_b4 v[136:137], v57
	s_waitcnt lgkmcnt(12)
	s_waitcnt vmcnt(34) lgkmcnt(15)
	v_lshlrev_b32_e32 v210, 16, v194
	v_and_b32_e32 v211, 0xffff0000, v194
	v_lshlrev_b32_e32 v142, 16, v202
	v_and_b32_e32 v143, 0xffff0000, v202
	v_add_f32_e32 v210, v210, v142
	v_add_f32_e32 v211, v211, v143
	v_lshlrev_b32_e32 v212, 16, v195
	v_and_b32_e32 v213, 0xffff0000, v195
	v_lshlrev_b32_e32 v142, 16, v203
	v_and_b32_e32 v143, 0xffff0000, v203
	v_add_f32_e32 v212, v212, v142
	v_add_f32_e32 v213, v213, v143
	v_lshlrev_b32_e32 v214, 16, v196
	v_and_b32_e32 v215, 0xffff0000, v196
	v_lshlrev_b32_e32 v142, 16, v204
	v_and_b32_e32 v143, 0xffff0000, v204
	v_add_f32_e32 v214, v214, v142
	v_add_f32_e32 v215, v215, v143
	v_lshlrev_b32_e32 v216, 16, v197
	v_and_b32_e32 v217, 0xffff0000, v197
	v_lshlrev_b32_e32 v142, 16, v205
	v_and_b32_e32 v143, 0xffff0000, v205
	v_add_f32_e32 v216, v216, v142
	v_add_f32_e32 v217, v217, v143
	v_lshlrev_b32_e32 v218, 16, v198
	v_and_b32_e32 v219, 0xffff0000, v198
	v_lshlrev_b32_e32 v142, 16, v206
	v_and_b32_e32 v143, 0xffff0000, v206
	v_add_f32_e32 v218, v218, v142
	v_add_f32_e32 v219, v219, v143
	v_lshlrev_b32_e32 v220, 16, v199
	v_and_b32_e32 v221, 0xffff0000, v199
	v_lshlrev_b32_e32 v142, 16, v207
	v_and_b32_e32 v143, 0xffff0000, v207
	v_add_f32_e32 v220, v220, v142
	v_add_f32_e32 v221, v221, v143
	v_lshlrev_b32_e32 v222, 16, v200
	v_and_b32_e32 v223, 0xffff0000, v200
	v_lshlrev_b32_e32 v142, 16, v208
	v_and_b32_e32 v143, 0xffff0000, v208
	v_add_f32_e32 v222, v222, v142
	v_add_f32_e32 v223, v223, v143
	v_lshlrev_b32_e32 v224, 16, v201
	v_and_b32_e32 v225, 0xffff0000, v201
	v_lshlrev_b32_e32 v142, 16, v209
	v_and_b32_e32 v143, 0xffff0000, v209
	v_add_f32_e32 v224, v224, v142
	v_add_f32_e32 v225, v225, v143
	v_mov_b32_e32 v144, 0
	v_mul_f32_e32 v145, v210, v210
	v_fmac_f32_e32 v145, v211, v211
	v_fmac_f32_e32 v145, v212, v212
	v_fmac_f32_e32 v145, v213, v213
	v_add_f32_e32 v144, v144, v145
	v_mul_f32_e32 v145, v214, v214
	v_fmac_f32_e32 v145, v215, v215
	v_fmac_f32_e32 v145, v216, v216
	v_fmac_f32_e32 v145, v217, v217
	v_add_f32_e32 v144, v144, v145
	v_mul_f32_e32 v145, v218, v218
	v_fmac_f32_e32 v145, v219, v219
	v_fmac_f32_e32 v145, v220, v220
	v_fmac_f32_e32 v145, v221, v221
	v_add_f32_e32 v144, v144, v145
	v_mul_f32_e32 v145, v222, v222
	v_fmac_f32_e32 v145, v223, v223
	v_fmac_f32_e32 v145, v224, v224
	v_fmac_f32_e32 v145, v225, v225
	v_add_f32_e32 v144, v144, v145
	s_nop 1
	v_add_f32_dpp v144, v144, v144 quad_perm:[1,0,3,2] row_mask:0xf bank_mask:0xf bound_ctrl:1
	s_nop 1
	v_add_f32_dpp v144, v144, v144 quad_perm:[2,3,0,1] row_mask:0xf bank_mask:0xf bound_ctrl:1
	s_nop 1
	v_add_f32_dpp v144, v144, v144 row_half_mirror row_mask:0xf bank_mask:0xf bound_ctrl:1
	s_nop 1
	v_add_f32_dpp v144, v144, v144 row_mirror row_mask:0xf bank_mask:0xf bound_ctrl:1
	s_nop 1
	v_readlane_b32 s10, v144, 0
	v_readlane_b32 s11, v144, 16
	v_readlane_b32 s14, v144, 32
	v_readlane_b32 s15, v144, 48
	s_nop 3
	v_mov_b32_e32 v144, s11
	v_mov_b32_e32 v145, s15
	v_add_f32_e32 v144, s10, v144
	v_add_f32_e32 v145, s14, v145
	v_add_f32_e32 v144, v144, v145
	v_fmamk_f32 v144, v144, 0x3a800000, v111
	v_rsq_f32_e32 v144, v144
	s_nop 0
	v_mul_f32_e32 v210, v210, v144
	v_mul_f32_e32 v211, v211, v144
	v_mul_f32_e32 v212, v212, v144
	v_mul_f32_e32 v213, v213, v144
	v_mul_f32_e32 v214, v214, v144
	v_mul_f32_e32 v215, v215, v144
	v_mul_f32_e32 v216, v216, v144
	v_mul_f32_e32 v217, v217, v144
	v_mul_f32_e32 v218, v218, v144
	v_mul_f32_e32 v219, v219, v144
	v_mul_f32_e32 v220, v220, v144
	v_mul_f32_e32 v221, v221, v144
	v_mul_f32_e32 v222, v222, v144
	v_mul_f32_e32 v223, v223, v144
	v_mul_f32_e32 v224, v224, v144
	v_mul_f32_e32 v225, v225, v144
	v_dot8c_i32_i4_e32 v38, v122, v48
	v_dot8c_i32_i4_e32 v39, v122, v46
	v_dot8c_i32_i4_e32 v40, v124, v48
	v_dot8c_i32_i4_e32 v41, v124, v46
	v_dot8c_i32_i4_e32 v42, v126, v48
	v_dot8c_i32_i4_e32 v43, v126, v46
	v_dot8c_i32_i4_e32 v44, v128, v48
	v_dot8c_i32_i4_e32 v45, v128, v46
	v_dot8c_i32_i4_e32 v38, v123, v49
	v_dot8c_i32_i4_e32 v39, v123, v47
	v_dot8c_i32_i4_e32 v40, v125, v49
	v_dot8c_i32_i4_e32 v41, v125, v47
	v_dot8c_i32_i4_e32 v42, v127, v49
	v_dot8c_i32_i4_e32 v43, v127, v47
	v_dot8c_i32_i4_e32 v44, v129, v49
	v_dot8c_i32_i4_e32 v45, v129, v47
	v_and_b32_e32 v78, 0xffff, v32
	v_lshrrev_b32_e32 v79, 16, v32
	v_lshl_add_u32 v78, v78, 7, v150
	v_lshl_add_u32 v79, v79, 7, v151
	s_mov_b32 m0, s76
	s_add_i32 s43, s76, 0x400
	global_load_lds_dwordx4 v78, s[50:51]
	s_mov_b32 m0, s43
	s_nop 0
	global_load_lds_dwordx4 v79, s[50:51]
	s_waitcnt vmcnt(8)
; #define LAS __attribute__((address_space(3)))
; #define TR4(p_) __builtin_amdgcn_ds_read_tr4_b64_v2i32((LAS v2i*)(p_))
; __device__ __forceinline__ void peer_v_tokens(int j, const LAS unsigned short* EL, const LAS unsigned char* AL  , const LAS float* ASC  , const LAS int* SAL  , ...
;     ...
;         for (int m = 0; m < 2; ++m) {
;             const int idx = lane + 64 * m, tau = idx >> 4, sr = idx & 15, k = 16 * (sr & 7) + 2 * tau + (sr >> 3);
;             const int aq = (int)*(const LAS signed char*)(AL + tl * 128 + k); const int tq = aq + 8;
;             const unsigned lo = (((unsigned)tq & 15u) ^ 8u) * 0x11111111u, hi = ((unsigned)(tq >> 4) & 15u) * 0x11111111u;
;             typedef unsigned u2v __attribute__((ext_vector_type(2)));
;             u2v l2; l2.x = lo; l2.y = lo; u2v h2; h2.x = hi; h2.y = hi;
;             *(LAS u2v*)(ATL + 8 * idx) = l2; *(LAS u2v*)(ATL + 1024 + 8 * idx) = h2;
;         }
;     ...
;         for (int st = 0; st < 16; ++st) {
;             const int p = st >> 2, q = st & 3;
;             if (st < 14) VDMA(st + 2, (st + 2) % 3);
;             if (st < 14) asm volatile("s_waitcnt vmcnt(8)" ::: "memory");
;             else if (st == 14) asm volatile("s_waitcnt vmcnt(4)" ::: "memory");
;             else asm volatile("s_waitcnt vmcnt(0)" ::: "memory");
;             if (q == 0) {
; #pragma unroll
;                 for (int r = 0; r < 4; ++r) { accH[r] = 0; accL[r] = 0; } }
; #pragma unroll
;             for (int tp = 0; tp < 2; ++tp) {
;                 const v2i ao = TR4(ATL + (2 * q + tp) * 128 + 8 * s16), ah = TR4(ATL + 1024 + (2 * q + tp) * 128 + 8 * s16);
; #pragma unroll
;                 for (int r = 0; r < 4; ++r) {
;                     const v2i d = TR4(ldsb + BUF[st % 3] + 2048 * tp + roff[r]);
;                     accH[r] = __builtin_amdgcn_sdot8(d.x, ah.x, accH[r], false); accH[r] = __builtin_amdgcn_sdot8(d.y, ah.y, accH[r], false);
;                     accL[r] = __builtin_amdgcn_sdot8(d.x, ao.x, accL[r], false); accL[r] = __builtin_amdgcn_sdot8(d.y, ao.y, accL[r], false);
;                 }
;             }
	v_add_u32_e32 v54, s78, v59
	v_add_u32_e32 v55, s78, v60
	v_add_u32_e32 v56, s78, v61
	v_add_u32_e32 v57, s78, v62
	ds_read_b64_tr_b4 v[46:47], v160 offset:256
	ds_read_b64_tr_b4 v[48:49], v160 offset:1280
	ds_read_b64_tr_b4 v[122:123], v54
	ds_read_b64_tr_b4 v[124:125], v55
	ds_read_b64_tr_b4 v[126:127], v56
	ds_read_b64_tr_b4 v[128:129], v57
	s_waitcnt lgkmcnt(6)
	v_dot8c_i32_i4_e32 v38, v130, v52
	v_dot8c_i32_i4_e32 v39, v130, v50
	v_dot8c_i32_i4_e32 v40, v132, v52
	v_dot8c_i32_i4_e32 v41, v132, v50
	v_dot8c_i32_i4_e32 v42, v134, v52
	v_dot8c_i32_i4_e32 v43, v134, v50
	v_dot8c_i32_i4_e32 v44, v136, v52
	v_dot8c_i32_i4_e32 v45, v136, v50
	v_dot8c_i32_i4_e32 v38, v131, v53
	v_dot8c_i32_i4_e32 v39, v131, v51
	v_dot8c_i32_i4_e32 v40, v133, v53
	v_dot8c_i32_i4_e32 v41, v133, v51
	v_dot8c_i32_i4_e32 v42, v135, v53
	v_dot8c_i32_i4_e32 v43, v135, v51
	v_dot8c_i32_i4_e32 v44, v137, v53
	v_dot8c_i32_i4_e32 v45, v137, v51
	v_and_b32_e32 v78, 0xffff, v33
	v_lshrrev_b32_e32 v79, 16, v33
	v_lshl_add_u32 v78, v78, 7, v150
	v_lshl_add_u32 v79, v79, 7, v151
	s_mov_b32 m0, s77
	s_add_i32 s43, s77, 0x400
	global_load_lds_dwordx4 v78, s[50:51]
	s_mov_b32 m0, s43
	s_nop 0
	global_load_lds_dwordx4 v79, s[50:51]
	s_waitcnt vmcnt(8)
	v_add_u32_e32 v54, s79, v59
	v_add_u32_e32 v55, s79, v60
	v_add_u32_e32 v56, s79, v61
	v_add_u32_e32 v57, s79, v62
	ds_read_b64_tr_b4 v[50:51], v160 offset:384
	ds_read_b64_tr_b4 v[52:53], v160 offset:1408
	ds_read_b64_tr_b4 v[130:131], v54
	ds_read_b64_tr_b4 v[132:133], v55
	ds_read_b64_tr_b4 v[134:135], v56
	ds_read_b64_tr_b4 v[136:137], v57
	s_waitcnt lgkmcnt(6)
	v_dot8c_i32_i4_e32 v38, v122, v48
	v_dot8c_i32_i4_e32 v39, v122, v46
	v_dot8c_i32_i4_e32 v40, v124, v48
	v_dot8c_i32_i4_e32 v41, v124, v46
	v_dot8c_i32_i4_e32 v42, v126, v48
	v_dot8c_i32_i4_e32 v43, v126, v46
	v_dot8c_i32_i4_e32 v44, v128, v48
	v_dot8c_i32_i4_e32 v45, v128, v46
	v_dot8c_i32_i4_e32 v38, v123, v49
	v_dot8c_i32_i4_e32 v39, v123, v47
	v_dot8c_i32_i4_e32 v40, v125, v49
	v_dot8c_i32_i4_e32 v41, v125, v47
	v_dot8c_i32_i4_e32 v42, v127, v49
	v_dot8c_i32_i4_e32 v43, v127, v47
	v_dot8c_i32_i4_e32 v44, v129, v49
	v_dot8c_i32_i4_e32 v45, v129, v47
	s_waitcnt lgkmcnt(15)
	v_and_b32_e32 v78, 0xffff, v18
	v_lshrrev_b32_e32 v79, 16, v18
	v_lshl_add_u32 v78, v78, 7, v152
	v_lshl_add_u32 v79, v79, 7, v153
	s_mov_b32 m0, s78
	s_add_i32 s43, s78, 0x400
	global_load_lds_dwordx4 v78, s[50:51]
	s_mov_b32 m0, s43
	s_nop 0
	global_load_lds_dwordx4 v79, s[50:51]
	s_waitcnt vmcnt(8)
	v_add_u32_e32 v54, s98, v59
	v_add_u32_e32 v55, s98, v60
	v_add_u32_e32 v56, s98, v61
	v_add_u32_e32 v57, s98, v62
	ds_read_b64_tr_b4 v[46:47], v160 offset:512
	ds_read_b64_tr_b4 v[48:49], v160 offset:1536
	ds_read_b64_tr_b4 v[122:123], v54
	ds_read_b64_tr_b4 v[124:125], v55
	ds_read_b64_tr_b4 v[126:127], v56
	ds_read_b64_tr_b4 v[128:129], v57
	s_waitcnt lgkmcnt(6)
	v_dot8c_i32_i4_e32 v38, v130, v52
	v_dot8c_i32_i4_e32 v39, v130, v50
	v_dot8c_i32_i4_e32 v40, v132, v52
	v_dot8c_i32_i4_e32 v41, v132, v50
	v_dot8c_i32_i4_e32 v42, v134, v52
	v_dot8c_i32_i4_e32 v43, v134, v50
	v_dot8c_i32_i4_e32 v44, v136, v52
	v_dot8c_i32_i4_e32 v45, v136, v50
	v_dot8c_i32_i4_e32 v38, v131, v53
	v_dot8c_i32_i4_e32 v39, v131, v51
	v_dot8c_i32_i4_e32 v40, v133, v53
	v_dot8c_i32_i4_e32 v41, v133, v51
	v_dot8c_i32_i4_e32 v42, v135, v53
	v_dot8c_i32_i4_e32 v43, v135, v51
	v_dot8c_i32_i4_e32 v44, v137, v53
	v_dot8c_i32_i4_e32 v45, v137, v51
	v_and_b32_e32 v78, 0xffff, v19
	v_lshrrev_b32_e32 v79, 16, v19
	v_lshl_add_u32 v78, v78, 7, v152
	v_lshl_add_u32 v79, v79, 7, v153
	s_mov_b32 m0, s79
	s_add_i32 s43, s79, 0x400
	global_load_lds_dwordx4 v78, s[50:51]
	s_mov_b32 m0, s43
	s_nop 0
	global_load_lds_dwordx4 v79, s[50:51]
	s_waitcnt vmcnt(8)
	v_add_u32_e32 v54, s99, v59
	v_add_u32_e32 v55, s99, v60
	v_add_u32_e32 v56, s99, v61
	v_add_u32_e32 v57, s99, v62
	ds_read_b64_tr_b4 v[50:51], v160 offset:640
	ds_read_b64_tr_b4 v[52:53], v160 offset:1664
	ds_read_b64_tr_b4 v[130:131], v54
	ds_read_b64_tr_b4 v[132:133], v55
	ds_read_b64_tr_b4 v[134:135], v56
	ds_read_b64_tr_b4 v[136:137], v57
	s_waitcnt lgkmcnt(6)
	v_dot8c_i32_i4_e32 v38, v122, v48
	v_dot8c_i32_i4_e32 v39, v122, v46
	v_dot8c_i32_i4_e32 v40, v124, v48
	v_dot8c_i32_i4_e32 v41, v124, v46
	v_dot8c_i32_i4_e32 v42, v126, v48
	v_dot8c_i32_i4_e32 v43, v126, v46
	v_dot8c_i32_i4_e32 v44, v128, v48
	v_dot8c_i32_i4_e32 v45, v128, v46
	v_dot8c_i32_i4_e32 v38, v123, v49
	v_dot8c_i32_i4_e32 v39, v123, v47
	v_dot8c_i32_i4_e32 v40, v125, v49
	v_dot8c_i32_i4_e32 v41, v125, v47
	v_dot8c_i32_i4_e32 v42, v127, v49
	v_dot8c_i32_i4_e32 v43, v127, v47
	v_dot8c_i32_i4_e32 v44, v129, v49
	v_dot8c_i32_i4_e32 v45, v129, v47
	s_waitcnt lgkmcnt(15)
	v_add_u32_e32 v143, 8, v139
	v_and_b32_e32 v142, 15, v143
	v_xor_b32_e32 v142, 8, v142
	v_bfe_u32 v144, v143, 4, 4
	v_mul_lo_u32 v142, v142, s92
	v_mul_lo_u32 v144, v144, s92
	v_mov_b32_e32 v143, v142
	v_mov_b32_e32 v145, v144
	ds_write2st64_b64 v159, v[142:143], v[144:145] offset1:2
	v_and_b32_e32 v78, 0xffff, v20
	v_lshrrev_b32_e32 v79, 16, v20
	v_lshl_add_u32 v78, v78, 7, v152
	v_lshl_add_u32 v79, v79, 7, v153
	s_mov_b32 m0, s98
	s_add_i32 s43, s98, 0x400
	global_load_lds_dwordx4 v78, s[50:51]
	s_mov_b32 m0, s43
	s_nop 0
	global_load_lds_dwordx4 v79, s[50:51]
	s_waitcnt vmcnt(8)
	v_add_u32_e32 v54, s76, v59
	v_add_u32_e32 v55, s76, v60
	v_add_u32_e32 v56, s76, v61
	v_add_u32_e32 v57, s76, v62
	ds_read_b64_tr_b4 v[46:47], v160 offset:768
	ds_read_b64_tr_b4 v[48:49], v160 offset:1792
	ds_read_b64_tr_b4 v[122:123], v54
	ds_read_b64_tr_b4 v[124:125], v55
	ds_read_b64_tr_b4 v[126:127], v56
	ds_read_b64_tr_b4 v[128:129], v57
	s_waitcnt lgkmcnt(7)
; #define LAS __attribute__((address_space(3)))
; __device__ __forceinline__ bf16 f2bf(float f) { return (bf16)f2bfu(f); }
; __device__ __forceinline__ void peer_v_tokens(int j, const LAS unsigned short* EL, const LAS unsigned char* AL  , const LAS float* ASC  , const LAS int* SAL  , ...
;     ...
;         uint2 hv[4]; float4 gv[4];
;         { unsigned ho = (unsigned)t * (D / 4) + (unsigned)lane; asm volatile("" : "+v"(ho)); const uint2* hp = (const uint2*)HB + ho; const float4* gp = (const float4*)fng + lane;
; #pragma unroll
;           for (int jq = 0; jq < 4; ++jq) { hv[jq] = hp[64 * jq]; gv[jq] = gp[64 * jq]; } }
;     ...
;                 for (int r = 0; r < 4; ++r) STASH[256 * p + 16 * (grp + 4 * r) + pc] = f2bf(asc * (float)(2 * ((accH[r] << 4) + accL[r]) + sa));
;     ...
;         {
;             float4 v[4]; float ss = 0.f;
; #pragma unroll
;             for (int jq = 0; jq < 4; ++jq) { typedef unsigned u2v __attribute__((ext_vector_type(2))); const u2v pw = *(const LAS u2v*)(STASH + 4 * lane + 256 * jq); const uint2 hw = hv[jq];
;                 v[jq] = make_float4(__uint_as_float(hw.x << 16) + __uint_as_float(pw.x << 16), __uint_as_float(hw.x & 0xffff0000u) + __uint_as_float(pw.x & 0xffff0000u),
;                                     __uint_as_float(hw.y << 16) + __uint_as_float(pw.y << 16), __uint_as_float(hw.y & 0xffff0000u) + __uint_as_float(pw.y & 0xffff0000u));
;                 ss += v[jq].x * v[jq].x + v[jq].y * v[jq].y + v[jq].z * v[jq].z + v[jq].w * v[jq].w; }
;             ss = wave_sum(ss);
;             const float r3 = rsqrtf(ss * (1.f / D) + EPS);
;             float4* op = (float4*)(outp + (size_t)t * D) + lane;
; #pragma unroll
;             for (int jq = 0; jq < 4; ++jq) { typedef float f4v __attribute__((ext_vector_type(4))); f4v o4; o4.x = v[jq].x * r3 * gv[jq].x; o4.y = v[jq].y * r3 * gv[jq].y; o4.z = v[jq].z * r3 * gv[jq].z; o4.w = v[jq].w * r3 * gv[jq].w;
;                 __builtin_nontemporal_store(o4, (f4v*)op + 64 * jq); }
;         }
	v_dot8c_i32_i4_e32 v38, v130, v52
	v_dot8c_i32_i4_e32 v39, v130, v50
	v_dot8c_i32_i4_e32 v40, v132, v52
	v_dot8c_i32_i4_e32 v41, v132, v50
	v_dot8c_i32_i4_e32 v42, v134, v52
	v_dot8c_i32_i4_e32 v43, v134, v50
	v_dot8c_i32_i4_e32 v44, v136, v52
	v_dot8c_i32_i4_e32 v45, v136, v50
	v_dot8c_i32_i4_e32 v38, v131, v53
	v_dot8c_i32_i4_e32 v39, v131, v51
	v_dot8c_i32_i4_e32 v40, v133, v53
	v_dot8c_i32_i4_e32 v41, v133, v51
	v_dot8c_i32_i4_e32 v42, v135, v53
	v_dot8c_i32_i4_e32 v43, v135, v51
	v_dot8c_i32_i4_e32 v44, v137, v53
	v_dot8c_i32_i4_e32 v45, v137, v51
	v_and_b32_e32 v78, 0xffff, v21
	v_lshrrev_b32_e32 v79, 16, v21
	v_lshl_add_u32 v78, v78, 7, v152
	v_lshl_add_u32 v79, v79, 7, v153
	s_mov_b32 m0, s99
	s_add_i32 s43, s99, 0x400
	global_load_lds_dwordx4 v78, s[50:51]
	s_mov_b32 m0, s43
	s_nop 0
	global_load_lds_dwordx4 v79, s[50:51]
	s_waitcnt vmcnt(8)
	v_add_u32_e32 v54, s77, v59
	v_add_u32_e32 v55, s77, v60
	v_add_u32_e32 v56, s77, v61
	v_add_u32_e32 v57, s77, v62
	ds_read_b64_tr_b4 v[50:51], v160 offset:896
	ds_read_b64_tr_b4 v[52:53], v160 offset:1920
	ds_read_b64_tr_b4 v[130:131], v54
	ds_read_b64_tr_b4 v[132:133], v55
	ds_read_b64_tr_b4 v[134:135], v56
	ds_read_b64_tr_b4 v[136:137], v57
	s_waitcnt lgkmcnt(6)
	v_dot8c_i32_i4_e32 v38, v122, v48
	v_dot8c_i32_i4_e32 v39, v122, v46
	v_dot8c_i32_i4_e32 v40, v124, v48
	v_dot8c_i32_i4_e32 v41, v124, v46
	v_dot8c_i32_i4_e32 v42, v126, v48
	v_dot8c_i32_i4_e32 v43, v126, v46
	v_dot8c_i32_i4_e32 v44, v128, v48
	v_dot8c_i32_i4_e32 v45, v128, v46
	v_dot8c_i32_i4_e32 v38, v123, v49
	v_dot8c_i32_i4_e32 v39, v123, v47
	v_dot8c_i32_i4_e32 v40, v125, v49
	v_dot8c_i32_i4_e32 v41, v125, v47
	v_dot8c_i32_i4_e32 v42, v127, v49
	v_dot8c_i32_i4_e32 v43, v127, v47
	v_dot8c_i32_i4_e32 v44, v129, v49
	v_dot8c_i32_i4_e32 v45, v129, v47
	v_and_b32_e32 v78, 0xffff, v22
	v_lshrrev_b32_e32 v79, 16, v22
	v_lshl_add_u32 v78, v78, 7, v152
	v_lshl_add_u32 v79, v79, 7, v153
	s_mov_b32 m0, s76
	s_add_i32 s43, s76, 0x400
	global_load_lds_dwordx4 v78, s[50:51]
	s_mov_b32 m0, s43
	s_nop 0
	global_load_lds_dwordx4 v79, s[50:51]
	s_waitcnt vmcnt(8)
	v_add_u32_e32 v54, s78, v59
	v_add_u32_e32 v55, s78, v60
	v_add_u32_e32 v56, s78, v61
	v_add_u32_e32 v57, s78, v62
	ds_read_b64_tr_b4 v[46:47], v160
	ds_read_b64_tr_b4 v[48:49], v160 offset:1024
	ds_read_b64_tr_b4 v[122:123], v54
	ds_read_b64_tr_b4 v[124:125], v55
	ds_read_b64_tr_b4 v[126:127], v56
	ds_read_b64_tr_b4 v[128:129], v57
	s_waitcnt lgkmcnt(6)
	v_dot8c_i32_i4_e32 v38, v130, v52
	v_dot8c_i32_i4_e32 v39, v130, v50
	v_dot8c_i32_i4_e32 v40, v132, v52
	v_dot8c_i32_i4_e32 v41, v132, v50
	v_dot8c_i32_i4_e32 v42, v134, v52
	v_dot8c_i32_i4_e32 v43, v134, v50
	v_dot8c_i32_i4_e32 v44, v136, v52
	v_dot8c_i32_i4_e32 v45, v136, v50
	v_dot8c_i32_i4_e32 v38, v131, v53
	v_dot8c_i32_i4_e32 v39, v131, v51
	v_dot8c_i32_i4_e32 v40, v133, v53
	v_dot8c_i32_i4_e32 v41, v133, v51
	v_dot8c_i32_i4_e32 v42, v135, v53
	v_dot8c_i32_i4_e32 v43, v135, v51
	v_dot8c_i32_i4_e32 v44, v137, v53
	v_dot8c_i32_i4_e32 v45, v137, v51
	s_nop 3
	s_waitcnt lgkmcnt(15)
	v_lshlrev_b32_e32 v38, 5, v38
	v_lshlrev_b32_e32 v39, 1, v39
	v_add3_u32 v38, v39, v229, v38
	v_cvt_f32_i32_e32 v38, v38
	v_mul_f32_e32 v38, v228, v38
	v_lshlrev_b32_e32 v40, 5, v40
	v_lshlrev_b32_e32 v41, 1, v41
	v_add3_u32 v40, v41, v229, v40
	v_cvt_f32_i32_e32 v40, v40
	v_mul_f32_e32 v40, v228, v40
	v_lshlrev_b32_e32 v42, 5, v42
	v_lshlrev_b32_e32 v43, 1, v43
	v_add3_u32 v42, v43, v229, v42
	v_cvt_f32_i32_e32 v42, v42
	v_mul_f32_e32 v42, v228, v42
	v_lshlrev_b32_e32 v44, 5, v44
	v_lshlrev_b32_e32 v45, 1, v45
	v_add3_u32 v44, v45, v229, v44
	v_cvt_f32_i32_e32 v44, v44
	v_mul_f32_e32 v44, v228, v44
	v_cvt_pk_bf16_f32 v186, v38, v40
	v_cvt_pk_bf16_f32 v187, v42, v44
	ds_read_b128 v[252:255], v155
	s_add_i32 s44, s40, 0
	s_ashr_i32 s45, s44, 31
	s_lshl_b64 s[44:45], s[44:45], 12
	v_lshl_add_u64 v[80:81], v[36:37], 0, s[44:45]
	s_waitcnt lgkmcnt(0)
	v_mul_f32_e32 v210, v210, v252
	v_mul_f32_e32 v211, v211, v253
	v_mul_f32_e32 v212, v212, v254
	v_mul_f32_e32 v213, v213, v255
	global_store_dwordx4 v[80:81], v[210:213], off sc1
	s_add_i32 s43, s40, 8
	s_lshl_b32 s43, s43, 11
	v_add_u32_e32 v138, s43, v66
	global_load_dwordx2 v[194:195], v138, s[70:71]
	global_load_dwordx2 v[196:197], v138, s[70:71] offset:512
	global_load_dwordx2 v[198:199], v138, s[70:71] offset:1024
	global_load_dwordx2 v[200:201], v138, s[70:71] offset:1536
	v_add_u32_e32 v147, 8, v140
	v_and_b32_e32 v146, 15, v147
	v_xor_b32_e32 v146, 8, v146
	v_bfe_u32 v148, v147, 4, 4
	v_mul_lo_u32 v146, v146, s92
	v_mul_lo_u32 v148, v148, s92
	v_mov_b32_e32 v147, v146
	v_mov_b32_e32 v149, v148
	ds_write2st64_b64 v77, v[146:147], v[148:149] offset1:2
	v_add_u32_e32 v138, 0xc00, v74
	ds_read_u8 v139, v138
	v_add_u32_e32 v141, 0xc00, v73
	ds_read_u8 v140, v141
	s_add_i32 s43, s67, 64
	v_mov_b32_e32 v138, s43
	ds_read2st64_b32 v[228:229], v138 offset1:1
	ds_read_b128 v[26:29], v227 offset:6144
	ds_read_b128 v[30:33], v227 offset:6160
	v_mov_b32_e32 v38, 0
	v_mov_b32_e32 v39, 0
	v_mov_b32_e32 v40, 0
	v_mov_b32_e32 v41, 0
	v_mov_b32_e32 v42, 0
	v_mov_b32_e32 v43, 0
	v_mov_b32_e32 v44, 0
	v_mov_b32_e32 v45, 0
	v_and_b32_e32 v78, 0xffff, v23
	v_lshrrev_b32_e32 v79, 16, v23
	v_lshl_add_u32 v78, v78, 7, v152
	v_lshl_add_u32 v79, v79, 7, v153
	s_mov_b32 m0, s77
	s_add_i32 s43, s77, 0x400
	global_load_lds_dwordx4 v78, s[50:51]
	s_mov_b32 m0, s43
	s_nop 0
	global_load_lds_dwordx4 v79, s[50:51]
	s_waitcnt vmcnt(13)
	v_add_u32_e32 v54, s79, v59
	v_add_u32_e32 v55, s79, v60
	v_add_u32_e32 v56, s79, v61
	v_add_u32_e32 v57, s79, v62
	ds_read_b64_tr_b4 v[50:51], v160 offset:128
	ds_read_b64_tr_b4 v[52:53], v160 offset:1152
	ds_read_b64_tr_b4 v[130:131], v54
	ds_read_b64_tr_b4 v[132:133], v55
	ds_read_b64_tr_b4 v[134:135], v56
	ds_read_b64_tr_b4 v[136:137], v57
	s_waitcnt lgkmcnt(13)
; #define TR4(p_) __builtin_amdgcn_ds_read_tr4_b64_v2i32((LAS v2i*)(p_))
; #define VDMA(st_, k_) do { _Pragma("unroll") for (int i_ = 0; i_ < 4; ++i_) { \
;         const unsigned off_ = (unsigned)((st_) >> 2) * (16384u * 128u) + (PE_ID(E, 4 * ((st_) & 3) + i_) << 7) + ((i_ & 1) ? cx1 : cx0); \
;         __builtin_amdgcn_global_load_lds((const unsigned*)(V4 + off_), (LAS unsigned*)(ldsb + BUF[k_] + 1024 * i_), 16, 0, 0); } } while (0)
; __device__ __forceinline__ void peer_v_tokens(int j, const LAS unsigned short* EL, const LAS unsigned char* AL  , const LAS float* ASC  , const LAS int* SAL  , ...
;     ...
;         for (int st = 0; st < 16; ++st) {
;             const int p = st >> 2, q = st & 3;
;             if (st < 14) VDMA(st + 2, (st + 2) % 3);
;             if (st < 14) asm volatile("s_waitcnt vmcnt(8)" ::: "memory");
;             else if (st == 14) asm volatile("s_waitcnt vmcnt(4)" ::: "memory");
;             else asm volatile("s_waitcnt vmcnt(0)" ::: "memory");
;             if (q == 0) {
; #pragma unroll
;                 for (int r = 0; r < 4; ++r) { accH[r] = 0; accL[r] = 0; } }
; #pragma unroll
;             for (int tp = 0; tp < 2; ++tp) {
;                 const v2i ao = TR4(ATL + (2 * q + tp) * 128 + 8 * s16), ah = TR4(ATL + 1024 + (2 * q + tp) * 128 + 8 * s16);
; #pragma unroll
;                 for (int r = 0; r < 4; ++r) {
;                     const v2i d = TR4(ldsb + BUF[st % 3] + 2048 * tp + roff[r]);
;                     accH[r] = __builtin_amdgcn_sdot8(d.x, ah.x, accH[r], false); accH[r] = __builtin_amdgcn_sdot8(d.y, ah.y, accH[r], false);
;                     accL[r] = __builtin_amdgcn_sdot8(d.x, ao.x, accL[r], false); accL[r] = __builtin_amdgcn_sdot8(d.y, ao.y, accL[r], false);
;                 }
;             }
	v_dot8c_i32_i4_e32 v38, v122, v48
	v_dot8c_i32_i4_e32 v39, v122, v46
	v_dot8c_i32_i4_e32 v40, v124, v48
	v_dot8c_i32_i4_e32 v41, v124, v46
	v_dot8c_i32_i4_e32 v42, v126, v48
	v_dot8c_i32_i4_e32 v43, v126, v46
	v_dot8c_i32_i4_e32 v44, v128, v48
	v_dot8c_i32_i4_e32 v45, v128, v46
	v_dot8c_i32_i4_e32 v38, v123, v49
	v_dot8c_i32_i4_e32 v39, v123, v47
	v_dot8c_i32_i4_e32 v40, v125, v49
	v_dot8c_i32_i4_e32 v41, v125, v47
	v_dot8c_i32_i4_e32 v42, v127, v49
	v_dot8c_i32_i4_e32 v43, v127, v47
	v_dot8c_i32_i4_e32 v44, v129, v49
	v_dot8c_i32_i4_e32 v45, v129, v47
	v_and_b32_e32 v78, 0xffff, v24
	v_lshrrev_b32_e32 v79, 16, v24
	v_lshl_add_u32 v78, v78, 7, v152
	v_lshl_add_u32 v79, v79, 7, v153
	s_mov_b32 m0, s78
	s_add_i32 s43, s78, 0x400
	global_load_lds_dwordx4 v78, s[50:51]
	s_mov_b32 m0, s43
	s_nop 0
	global_load_lds_dwordx4 v79, s[50:51]
	s_waitcnt vmcnt(13)
	v_add_u32_e32 v54, s98, v59
	v_add_u32_e32 v55, s98, v60
	v_add_u32_e32 v56, s98, v61
	v_add_u32_e32 v57, s98, v62
	ds_read_b64_tr_b4 v[46:47], v160 offset:256
	ds_read_b64_tr_b4 v[48:49], v160 offset:1280
	ds_read_b64_tr_b4 v[122:123], v54
	ds_read_b64_tr_b4 v[124:125], v55
	ds_read_b64_tr_b4 v[126:127], v56
	ds_read_b64_tr_b4 v[128:129], v57
	s_waitcnt lgkmcnt(6)
	v_dot8c_i32_i4_e32 v38, v130, v52
	v_dot8c_i32_i4_e32 v39, v130, v50
	v_dot8c_i32_i4_e32 v40, v132, v52
	v_dot8c_i32_i4_e32 v41, v132, v50
	v_dot8c_i32_i4_e32 v42, v134, v52
	v_dot8c_i32_i4_e32 v43, v134, v50
	v_dot8c_i32_i4_e32 v44, v136, v52
	v_dot8c_i32_i4_e32 v45, v136, v50
	v_dot8c_i32_i4_e32 v38, v131, v53
	v_dot8c_i32_i4_e32 v39, v131, v51
	v_dot8c_i32_i4_e32 v40, v133, v53
	v_dot8c_i32_i4_e32 v41, v133, v51
	v_dot8c_i32_i4_e32 v42, v135, v53
	v_dot8c_i32_i4_e32 v43, v135, v51
	v_dot8c_i32_i4_e32 v44, v137, v53
	v_dot8c_i32_i4_e32 v45, v137, v51
	v_and_b32_e32 v78, 0xffff, v25
	v_lshrrev_b32_e32 v79, 16, v25
	v_lshl_add_u32 v78, v78, 7, v152
	v_lshl_add_u32 v79, v79, 7, v153
	s_mov_b32 m0, s79
	s_add_i32 s43, s79, 0x400
	global_load_lds_dwordx4 v78, s[50:51]
	s_mov_b32 m0, s43
	s_nop 0
	global_load_lds_dwordx4 v79, s[50:51]
	s_waitcnt vmcnt(13)
	v_add_u32_e32 v54, s99, v59
	v_add_u32_e32 v55, s99, v60
	v_add_u32_e32 v56, s99, v61
	v_add_u32_e32 v57, s99, v62
	ds_read_b64_tr_b4 v[50:51], v160 offset:384
	ds_read_b64_tr_b4 v[52:53], v160 offset:1408
	ds_read_b64_tr_b4 v[130:131], v54
	ds_read_b64_tr_b4 v[132:133], v55
	ds_read_b64_tr_b4 v[134:135], v56
	ds_read_b64_tr_b4 v[136:137], v57
	s_waitcnt lgkmcnt(6)
	v_dot8c_i32_i4_e32 v38, v122, v48
	v_dot8c_i32_i4_e32 v39, v122, v46
	v_dot8c_i32_i4_e32 v40, v124, v48
	v_dot8c_i32_i4_e32 v41, v124, v46
	v_dot8c_i32_i4_e32 v42, v126, v48
	v_dot8c_i32_i4_e32 v43, v126, v46
	v_dot8c_i32_i4_e32 v44, v128, v48
	v_dot8c_i32_i4_e32 v45, v128, v46
	v_dot8c_i32_i4_e32 v38, v123, v49
	v_dot8c_i32_i4_e32 v39, v123, v47
	v_dot8c_i32_i4_e32 v40, v125, v49
	v_dot8c_i32_i4_e32 v41, v125, v47
	v_dot8c_i32_i4_e32 v42, v127, v49
	v_dot8c_i32_i4_e32 v43, v127, v47
	v_dot8c_i32_i4_e32 v44, v129, v49
	v_dot8c_i32_i4_e32 v45, v129, v47
	s_waitcnt lgkmcnt(15)
	v_and_b32_e32 v78, 0xffff, v26
	v_lshrrev_b32_e32 v79, 16, v26
	v_lshl_add_u32 v78, v78, 7, v152
	v_lshl_add_u32 v79, v79, 7, v153
	s_mov_b32 m0, s98
	s_add_i32 s43, s98, 0x400
	global_load_lds_dwordx4 v78, s[50:51]
	s_mov_b32 m0, s43
	s_nop 0
	global_load_lds_dwordx4 v79, s[50:51]
	s_waitcnt vmcnt(13)
	v_add_u32_e32 v54, s76, v59
	v_add_u32_e32 v55, s76, v60
	v_add_u32_e32 v56, s76, v61
	v_add_u32_e32 v57, s76, v62
	ds_read_b64_tr_b4 v[46:47], v160 offset:512
	ds_read_b64_tr_b4 v[48:49], v160 offset:1536
	ds_read_b64_tr_b4 v[122:123], v54
	ds_read_b64_tr_b4 v[124:125], v55
	ds_read_b64_tr_b4 v[126:127], v56
	ds_read_b64_tr_b4 v[128:129], v57
	s_waitcnt lgkmcnt(6)
	v_dot8c_i32_i4_e32 v38, v130, v52
	v_dot8c_i32_i4_e32 v39, v130, v50
	v_dot8c_i32_i4_e32 v40, v132, v52
	v_dot8c_i32_i4_e32 v41, v132, v50
	v_dot8c_i32_i4_e32 v42, v134, v52
	v_dot8c_i32_i4_e32 v43, v134, v50
	v_dot8c_i32_i4_e32 v44, v136, v52
	v_dot8c_i32_i4_e32 v45, v136, v50
	v_dot8c_i32_i4_e32 v38, v131, v53
	v_dot8c_i32_i4_e32 v39, v131, v51
	v_dot8c_i32_i4_e32 v40, v133, v53
	v_dot8c_i32_i4_e32 v41, v133, v51
	v_dot8c_i32_i4_e32 v42, v135, v53
	v_dot8c_i32_i4_e32 v43, v135, v51
	v_dot8c_i32_i4_e32 v44, v137, v53
	v_dot8c_i32_i4_e32 v45, v137, v51
	v_and_b32_e32 v78, 0xffff, v27
	v_lshrrev_b32_e32 v79, 16, v27
	v_lshl_add_u32 v78, v78, 7, v152
	v_lshl_add_u32 v79, v79, 7, v153
	s_mov_b32 m0, s99
	s_add_i32 s43, s99, 0x400
	global_load_lds_dwordx4 v78, s[50:51]
	s_mov_b32 m0, s43
	s_nop 0
	global_load_lds_dwordx4 v79, s[50:51]
	s_waitcnt vmcnt(8)
	v_add_u32_e32 v54, s77, v59
	v_add_u32_e32 v55, s77, v60
	v_add_u32_e32 v56, s77, v61
	v_add_u32_e32 v57, s77, v62
	ds_read_b64_tr_b4 v[50:51], v160 offset:640
	ds_read_b64_tr_b4 v[52:53], v160 offset:1664
	ds_read_b64_tr_b4 v[130:131], v54
	ds_read_b64_tr_b4 v[132:133], v55
	ds_read_b64_tr_b4 v[134:135], v56
	ds_read_b64_tr_b4 v[136:137], v57
	s_waitcnt lgkmcnt(6)
	v_dot8c_i32_i4_e32 v38, v122, v48
	v_dot8c_i32_i4_e32 v39, v122, v46
	v_dot8c_i32_i4_e32 v40, v124, v48
	v_dot8c_i32_i4_e32 v41, v124, v46
	v_dot8c_i32_i4_e32 v42, v126, v48
	v_dot8c_i32_i4_e32 v43, v126, v46
	v_dot8c_i32_i4_e32 v44, v128, v48
	v_dot8c_i32_i4_e32 v45, v128, v46
	v_dot8c_i32_i4_e32 v38, v123, v49
	v_dot8c_i32_i4_e32 v39, v123, v47
	v_dot8c_i32_i4_e32 v40, v125, v49
	v_dot8c_i32_i4_e32 v41, v125, v47
	v_dot8c_i32_i4_e32 v42, v127, v49
	v_dot8c_i32_i4_e32 v43, v127, v47
	v_dot8c_i32_i4_e32 v44, v129, v49
	v_dot8c_i32_i4_e32 v45, v129, v47
	s_waitcnt lgkmcnt(15)
; #define LAS __attribute__((address_space(3)))
; __device__ __forceinline__ bf16 f2bf(float f) { return (bf16)f2bfu(f); }
; __device__ __forceinline__ void peer_v_tokens(int j, const LAS unsigned short* EL, const LAS unsigned char* AL  , const LAS float* ASC  , const LAS int* SAL  , ...
;     ...
;         for (int m = 0; m < 2; ++m) {
;             const int idx = lane + 64 * m, tau = idx >> 4, sr = idx & 15, k = 16 * (sr & 7) + 2 * tau + (sr >> 3);
;             const int aq = (int)*(const LAS signed char*)(AL + tl * 128 + k); const int tq = aq + 8;
;             const unsigned lo = (((unsigned)tq & 15u) ^ 8u) * 0x11111111u, hi = ((unsigned)(tq >> 4) & 15u) * 0x11111111u;
;             typedef unsigned u2v __attribute__((ext_vector_type(2)));
;             u2v l2; l2.x = lo; l2.y = lo; u2v h2; h2.x = hi; h2.y = hi;
;             *(LAS u2v*)(ATL + 8 * idx) = l2; *(LAS u2v*)(ATL + 1024 + 8 * idx) = h2;
;         }
;     ...
;                 for (int r = 0; r < 4; ++r) STASH[256 * p + 16 * (grp + 4 * r) + pc] = f2bf(asc * (float)(2 * ((accH[r] << 4) + accL[r]) + sa));
;     ...
;         {
;             float4 v[4]; float ss = 0.f;
; #pragma unroll
;             for (int jq = 0; jq < 4; ++jq) { typedef unsigned u2v __attribute__((ext_vector_type(2))); const u2v pw = *(const LAS u2v*)(STASH + 4 * lane + 256 * jq); const uint2 hw = hv[jq];
;                 v[jq] = make_float4(__uint_as_float(hw.x << 16) + __uint_as_float(pw.x << 16), __uint_as_float(hw.x & 0xffff0000u) + __uint_as_float(pw.x & 0xffff0000u),
;                                     __uint_as_float(hw.y << 16) + __uint_as_float(pw.y << 16), __uint_as_float(hw.y & 0xffff0000u) + __uint_as_float(pw.y & 0xffff0000u));
;                 ss += v[jq].x * v[jq].x + v[jq].y * v[jq].y + v[jq].z * v[jq].z + v[jq].w * v[jq].w; }
;             ss = wave_sum(ss);
;             const float r3 = rsqrtf(ss * (1.f / D) + EPS);
;             float4* op = (float4*)(outp + (size_t)t * D) + lane;
; #pragma unroll
;             for (int jq = 0; jq < 4; ++jq) { typedef float f4v __attribute__((ext_vector_type(4))); f4v o4; o4.x = v[jq].x * r3 * gv[jq].x; o4.y = v[jq].y * r3 * gv[jq].y; o4.z = v[jq].z * r3 * gv[jq].z; o4.w = v[jq].w * r3 * gv[jq].w;
;                 __builtin_nontemporal_store(o4, (f4v*)op + 64 * jq); }
;         }
	v_add_u32_e32 v143, 8, v139
	v_and_b32_e32 v142, 15, v143
	v_xor_b32_e32 v142, 8, v142
	v_bfe_u32 v144, v143, 4, 4
	v_mul_lo_u32 v142, v142, s92
	v_mul_lo_u32 v144, v144, s92
	v_mov_b32_e32 v143, v142
	v_mov_b32_e32 v145, v144
	ds_write2st64_b64 v159, v[142:143], v[144:145] offset1:2
	v_and_b32_e32 v78, 0xffff, v28
	v_lshrrev_b32_e32 v79, 16, v28
	v_lshl_add_u32 v78, v78, 7, v152
	v_lshl_add_u32 v79, v79, 7, v153
	s_mov_b32 m0, s76
	s_add_i32 s43, s76, 0x400
	global_load_lds_dwordx4 v78, s[50:51]
	s_mov_b32 m0, s43
	s_nop 0
	global_load_lds_dwordx4 v79, s[50:51]
	s_waitcnt vmcnt(8)
	v_add_u32_e32 v54, s78, v59
	v_add_u32_e32 v55, s78, v60
	v_add_u32_e32 v56, s78, v61
	v_add_u32_e32 v57, s78, v62
	ds_read_b64_tr_b4 v[46:47], v160 offset:768
	ds_read_b64_tr_b4 v[48:49], v160 offset:1792
	ds_read_b64_tr_b4 v[122:123], v54
	ds_read_b64_tr_b4 v[124:125], v55
	ds_read_b64_tr_b4 v[126:127], v56
	ds_read_b64_tr_b4 v[128:129], v57
	s_waitcnt lgkmcnt(7)
	v_dot8c_i32_i4_e32 v38, v130, v52
	v_dot8c_i32_i4_e32 v39, v130, v50
	v_dot8c_i32_i4_e32 v40, v132, v52
	v_dot8c_i32_i4_e32 v41, v132, v50
	v_dot8c_i32_i4_e32 v42, v134, v52
	v_dot8c_i32_i4_e32 v43, v134, v50
	v_dot8c_i32_i4_e32 v44, v136, v52
	v_dot8c_i32_i4_e32 v45, v136, v50
	v_dot8c_i32_i4_e32 v38, v131, v53
	v_dot8c_i32_i4_e32 v39, v131, v51
	v_dot8c_i32_i4_e32 v40, v133, v53
	v_dot8c_i32_i4_e32 v41, v133, v51
	v_dot8c_i32_i4_e32 v42, v135, v53
	v_dot8c_i32_i4_e32 v43, v135, v51
	v_dot8c_i32_i4_e32 v44, v137, v53
	v_dot8c_i32_i4_e32 v45, v137, v51
	v_and_b32_e32 v78, 0xffff, v29
	v_lshrrev_b32_e32 v79, 16, v29
	v_lshl_add_u32 v78, v78, 7, v152
	v_lshl_add_u32 v79, v79, 7, v153
	s_mov_b32 m0, s77
	s_add_i32 s43, s77, 0x400
	global_load_lds_dwordx4 v78, s[50:51]
	s_mov_b32 m0, s43
	s_nop 0
	global_load_lds_dwordx4 v79, s[50:51]
	s_waitcnt vmcnt(8)
	v_add_u32_e32 v54, s79, v59
	v_add_u32_e32 v55, s79, v60
	v_add_u32_e32 v56, s79, v61
	v_add_u32_e32 v57, s79, v62
	ds_read_b64_tr_b4 v[50:51], v160 offset:896
	ds_read_b64_tr_b4 v[52:53], v160 offset:1920
	ds_read_b64_tr_b4 v[130:131], v54
	ds_read_b64_tr_b4 v[132:133], v55
	ds_read_b64_tr_b4 v[134:135], v56
	ds_read_b64_tr_b4 v[136:137], v57
	s_waitcnt lgkmcnt(6)
	v_dot8c_i32_i4_e32 v38, v122, v48
	v_dot8c_i32_i4_e32 v39, v122, v46
	v_dot8c_i32_i4_e32 v40, v124, v48
	v_dot8c_i32_i4_e32 v41, v124, v46
	v_dot8c_i32_i4_e32 v42, v126, v48
	v_dot8c_i32_i4_e32 v43, v126, v46
	v_dot8c_i32_i4_e32 v44, v128, v48
	v_dot8c_i32_i4_e32 v45, v128, v46
	v_dot8c_i32_i4_e32 v38, v123, v49
	v_dot8c_i32_i4_e32 v39, v123, v47
	v_dot8c_i32_i4_e32 v40, v125, v49
	v_dot8c_i32_i4_e32 v41, v125, v47
	v_dot8c_i32_i4_e32 v42, v127, v49
	v_dot8c_i32_i4_e32 v43, v127, v47
	v_dot8c_i32_i4_e32 v44, v129, v49
	v_dot8c_i32_i4_e32 v45, v129, v47
	v_and_b32_e32 v78, 0xffff, v30
	v_lshrrev_b32_e32 v79, 16, v30
	v_lshl_add_u32 v78, v78, 7, v152
	v_lshl_add_u32 v79, v79, 7, v153
	s_mov_b32 m0, s78
	s_add_i32 s43, s78, 0x400
	global_load_lds_dwordx4 v78, s[50:51]
	s_mov_b32 m0, s43
	s_nop 0
	global_load_lds_dwordx4 v79, s[50:51]
	s_waitcnt vmcnt(8)
	v_add_u32_e32 v54, s98, v59
	v_add_u32_e32 v55, s98, v60
	v_add_u32_e32 v56, s98, v61
	v_add_u32_e32 v57, s98, v62
	ds_read_b64_tr_b4 v[46:47], v160
	ds_read_b64_tr_b4 v[48:49], v160 offset:1024
	ds_read_b64_tr_b4 v[122:123], v54
	ds_read_b64_tr_b4 v[124:125], v55
	ds_read_b64_tr_b4 v[126:127], v56
	ds_read_b64_tr_b4 v[128:129], v57
	s_waitcnt lgkmcnt(6)
	v_dot8c_i32_i4_e32 v38, v130, v52
	v_dot8c_i32_i4_e32 v39, v130, v50
	v_dot8c_i32_i4_e32 v40, v132, v52
	v_dot8c_i32_i4_e32 v41, v132, v50
	v_dot8c_i32_i4_e32 v42, v134, v52
	v_dot8c_i32_i4_e32 v43, v134, v50
	v_dot8c_i32_i4_e32 v44, v136, v52
	v_dot8c_i32_i4_e32 v45, v136, v50
	v_dot8c_i32_i4_e32 v38, v131, v53
	v_dot8c_i32_i4_e32 v39, v131, v51
	v_dot8c_i32_i4_e32 v40, v133, v53
	v_dot8c_i32_i4_e32 v41, v133, v51
	v_dot8c_i32_i4_e32 v42, v135, v53
	v_dot8c_i32_i4_e32 v43, v135, v51
	v_dot8c_i32_i4_e32 v44, v137, v53
	v_dot8c_i32_i4_e32 v45, v137, v51
	s_nop 3
	s_waitcnt lgkmcnt(15)
	v_lshlrev_b32_e32 v38, 5, v38
	v_lshlrev_b32_e32 v39, 1, v39
	v_add3_u32 v38, v39, v229, v38
	v_cvt_f32_i32_e32 v38, v38
	v_mul_f32_e32 v38, v228, v38
	v_lshlrev_b32_e32 v40, 5, v40
	v_lshlrev_b32_e32 v41, 1, v41
	v_add3_u32 v40, v41, v229, v40
	v_cvt_f32_i32_e32 v40, v40
	v_mul_f32_e32 v40, v228, v40
	v_lshlrev_b32_e32 v42, 5, v42
	v_lshlrev_b32_e32 v43, 1, v43
	v_add3_u32 v42, v43, v229, v42
	v_cvt_f32_i32_e32 v42, v42
	v_mul_f32_e32 v42, v228, v42
	v_lshlrev_b32_e32 v44, 5, v44
	v_lshlrev_b32_e32 v45, 1, v45
	v_add3_u32 v44, v45, v229, v44
	v_cvt_f32_i32_e32 v44, v44
	v_mul_f32_e32 v44, v228, v44
	v_cvt_pk_bf16_f32 v180, v38, v40
	v_cvt_pk_bf16_f32 v181, v42, v44
	ds_read_b128 v[252:255], v155 offset:1024
	s_add_i32 s44, s40, 0
	s_ashr_i32 s45, s44, 31
	s_lshl_b64 s[44:45], s[44:45], 12
	v_lshl_add_u64 v[80:81], v[36:37], 0, s[44:45]
	s_waitcnt lgkmcnt(0)
	v_mul_f32_e32 v214, v214, v252
	v_mul_f32_e32 v215, v215, v253
	v_mul_f32_e32 v216, v216, v254
	v_mul_f32_e32 v217, v217, v255
	global_store_dwordx4 v[80:81], v[214:217], off offset:1024 sc1
	v_add_u32_e32 v147, 8, v140
	v_and_b32_e32 v146, 15, v147
	v_xor_b32_e32 v146, 8, v146
	v_bfe_u32 v148, v147, 4, 4
	v_mul_lo_u32 v146, v146, s92
	v_mul_lo_u32 v148, v148, s92
	v_mov_b32_e32 v147, v146
	v_mov_b32_e32 v149, v148
	ds_write2st64_b64 v77, v[146:147], v[148:149] offset1:2
	v_add_u32_e32 v138, 0x800, v74
	ds_read_u8 v139, v138
	v_add_u32_e32 v141, 0x800, v73
	ds_read_u8 v140, v141
	s_add_i32 s43, s67, 96
	v_mov_b32_e32 v138, s43
	ds_read2st64_b32 v[228:229], v138 offset1:1
	ds_read_b128 v[18:21], v227 offset:4096
	ds_read_b128 v[22:25], v227 offset:4112
	v_add_u32_e32 v150, 0x400000, v63
	v_add_u32_e32 v151, 0x400000, v64
	v_mov_b32_e32 v38, 0
	v_mov_b32_e32 v39, 0
	v_mov_b32_e32 v40, 0
	v_mov_b32_e32 v41, 0
	v_mov_b32_e32 v42, 0
	v_mov_b32_e32 v43, 0
	v_mov_b32_e32 v44, 0
	v_mov_b32_e32 v45, 0
	v_and_b32_e32 v78, 0xffff, v31
	v_lshrrev_b32_e32 v79, 16, v31
	v_lshl_add_u32 v78, v78, 7, v152
	v_lshl_add_u32 v79, v79, 7, v153
	s_mov_b32 m0, s79
	s_add_i32 s43, s79, 0x400
	global_load_lds_dwordx4 v78, s[50:51]
	s_mov_b32 m0, s43
	s_nop 0
	global_load_lds_dwordx4 v79, s[50:51]
	s_waitcnt vmcnt(9)
; #define LAS __attribute__((address_space(3)))
; __device__ __forceinline__ bf16 f2bf(float f) { return (bf16)f2bfu(f); }
; #define TR4(p_) __builtin_amdgcn_ds_read_tr4_b64_v2i32((LAS v2i*)(p_))
; #define VDMA(st_, k_) do { _Pragma("unroll") for (int i_ = 0; i_ < 4; ++i_) { \
;         const unsigned off_ = (unsigned)((st_) >> 2) * (16384u * 128u) + (PE_ID(E, 4 * ((st_) & 3) + i_) << 7) + ((i_ & 1) ? cx1 : cx0); \
;         __builtin_amdgcn_global_load_lds((const unsigned*)(V4 + off_), (LAS unsigned*)(ldsb + BUF[k_] + 1024 * i_), 16, 0, 0); } } while (0)
; __device__ __forceinline__ void peer_v_tokens(int j, const LAS unsigned short* EL, const LAS unsigned char* AL  , const LAS float* ASC  , const LAS int* SAL  , ...
;     ...
;         for (int st = 0; st < 16; ++st) {
;             const int p = st >> 2, q = st & 3;
;             if (st < 14) VDMA(st + 2, (st + 2) % 3);
;             if (st < 14) asm volatile("s_waitcnt vmcnt(8)" ::: "memory");
;             else if (st == 14) asm volatile("s_waitcnt vmcnt(4)" ::: "memory");
;             else asm volatile("s_waitcnt vmcnt(0)" ::: "memory");
;             if (q == 0) {
; #pragma unroll
;                 for (int r = 0; r < 4; ++r) { accH[r] = 0; accL[r] = 0; } }
; #pragma unroll
;             for (int tp = 0; tp < 2; ++tp) {
;                 const v2i ao = TR4(ATL + (2 * q + tp) * 128 + 8 * s16), ah = TR4(ATL + 1024 + (2 * q + tp) * 128 + 8 * s16);
; #pragma unroll
;                 for (int r = 0; r < 4; ++r) {
;                     const v2i d = TR4(ldsb + BUF[st % 3] + 2048 * tp + roff[r]);
;                     accH[r] = __builtin_amdgcn_sdot8(d.x, ah.x, accH[r], false); accH[r] = __builtin_amdgcn_sdot8(d.y, ah.y, accH[r], false);
;                     accL[r] = __builtin_amdgcn_sdot8(d.x, ao.x, accL[r], false); accL[r] = __builtin_amdgcn_sdot8(d.y, ao.y, accL[r], false);
;                 }
;             }
;     ...
;                 for (int r = 0; r < 4; ++r) STASH[256 * p + 16 * (grp + 4 * r) + pc] = f2bf(asc * (float)(2 * ((accH[r] << 4) + accL[r]) + sa));
;     ...
;             for (int jq = 0; jq < 4; ++jq) { typedef unsigned u2v __attribute__((ext_vector_type(2))); const u2v pw = *(const LAS u2v*)(STASH + 4 * lane + 256 * jq); const uint2 hw = hv[jq];
	v_add_u32_e32 v54, s99, v59
	v_add_u32_e32 v55, s99, v60
	v_add_u32_e32 v56, s99, v61
	v_add_u32_e32 v57, s99, v62
	ds_read_b64_tr_b4 v[50:51], v160 offset:128
	ds_read_b64_tr_b4 v[52:53], v160 offset:1152
	ds_read_b64_tr_b4 v[130:131], v54
	ds_read_b64_tr_b4 v[132:133], v55
	ds_read_b64_tr_b4 v[134:135], v56
	ds_read_b64_tr_b4 v[136:137], v57
	s_waitcnt lgkmcnt(13)
	v_dot8c_i32_i4_e32 v38, v122, v48
	v_dot8c_i32_i4_e32 v39, v122, v46
	v_dot8c_i32_i4_e32 v40, v124, v48
	v_dot8c_i32_i4_e32 v41, v124, v46
	v_dot8c_i32_i4_e32 v42, v126, v48
	v_dot8c_i32_i4_e32 v43, v126, v46
	v_dot8c_i32_i4_e32 v44, v128, v48
	v_dot8c_i32_i4_e32 v45, v128, v46
	v_dot8c_i32_i4_e32 v38, v123, v49
	v_dot8c_i32_i4_e32 v39, v123, v47
	v_dot8c_i32_i4_e32 v40, v125, v49
	v_dot8c_i32_i4_e32 v41, v125, v47
	v_dot8c_i32_i4_e32 v42, v127, v49
	v_dot8c_i32_i4_e32 v43, v127, v47
	v_dot8c_i32_i4_e32 v44, v129, v49
	v_dot8c_i32_i4_e32 v45, v129, v47
	v_and_b32_e32 v78, 0xffff, v32
	v_lshrrev_b32_e32 v79, 16, v32
	v_lshl_add_u32 v78, v78, 7, v152
	v_lshl_add_u32 v79, v79, 7, v153
	s_mov_b32 m0, s98
	s_add_i32 s43, s98, 0x400
	global_load_lds_dwordx4 v78, s[50:51]
	s_mov_b32 m0, s43
	s_nop 0
	global_load_lds_dwordx4 v79, s[50:51]
	s_waitcnt vmcnt(9)
	v_add_u32_e32 v54, s76, v59
	v_add_u32_e32 v55, s76, v60
	v_add_u32_e32 v56, s76, v61
	v_add_u32_e32 v57, s76, v62
	ds_read_b64_tr_b4 v[46:47], v160 offset:256
	ds_read_b64_tr_b4 v[48:49], v160 offset:1280
	ds_read_b64_tr_b4 v[122:123], v54
	ds_read_b64_tr_b4 v[124:125], v55
	ds_read_b64_tr_b4 v[126:127], v56
	ds_read_b64_tr_b4 v[128:129], v57
	s_waitcnt lgkmcnt(6)
	v_dot8c_i32_i4_e32 v38, v130, v52
	v_dot8c_i32_i4_e32 v39, v130, v50
	v_dot8c_i32_i4_e32 v40, v132, v52
	v_dot8c_i32_i4_e32 v41, v132, v50
	v_dot8c_i32_i4_e32 v42, v134, v52
	v_dot8c_i32_i4_e32 v43, v134, v50
	v_dot8c_i32_i4_e32 v44, v136, v52
	v_dot8c_i32_i4_e32 v45, v136, v50
	v_dot8c_i32_i4_e32 v38, v131, v53
	v_dot8c_i32_i4_e32 v39, v131, v51
	v_dot8c_i32_i4_e32 v40, v133, v53
	v_dot8c_i32_i4_e32 v41, v133, v51
	v_dot8c_i32_i4_e32 v42, v135, v53
	v_dot8c_i32_i4_e32 v43, v135, v51
	v_dot8c_i32_i4_e32 v44, v137, v53
	v_dot8c_i32_i4_e32 v45, v137, v51
	ds_write_b16 v65, v170
	ds_write_b16_d16_hi v65, v170 offset:128
	ds_write_b16 v65, v171 offset:256
	ds_write_b16_d16_hi v65, v171 offset:384
	ds_write_b16 v65, v172 offset:512
	ds_write_b16_d16_hi v65, v172 offset:640
	ds_write_b16 v65, v173 offset:768
	ds_write_b16_d16_hi v65, v173 offset:896
	ds_write_b16 v65, v174 offset:1024
	ds_write_b16_d16_hi v65, v174 offset:1152
	ds_write_b16 v65, v175 offset:1280
	ds_write_b16_d16_hi v65, v175 offset:1408
	ds_write_b16 v65, v176 offset:1536
	ds_write_b16_d16_hi v65, v176 offset:1664
	ds_write_b16 v65, v177 offset:1792
	ds_write_b16_d16_hi v65, v177 offset:1920
	ds_read_b64 v[202:203], v154
	ds_read_b64 v[204:205], v154 offset:512
	ds_read_b64 v[206:207], v154 offset:1024
	ds_read_b64 v[208:209], v154 offset:1536
	v_and_b32_e32 v78, 0xffff, v33
	v_lshrrev_b32_e32 v79, 16, v33
	v_lshl_add_u32 v78, v78, 7, v152
	v_lshl_add_u32 v79, v79, 7, v153
	s_mov_b32 m0, s99
	s_add_i32 s43, s99, 0x400
	global_load_lds_dwordx4 v78, s[50:51]
	s_mov_b32 m0, s43
	s_nop 0
	global_load_lds_dwordx4 v79, s[50:51]
	s_waitcnt vmcnt(9)
	v_add_u32_e32 v54, s77, v59
	v_add_u32_e32 v55, s77, v60
	v_add_u32_e32 v56, s77, v61
	v_add_u32_e32 v57, s77, v62
	ds_read_b64_tr_b4 v[50:51], v160 offset:384
	ds_read_b64_tr_b4 v[52:53], v160 offset:1408
	ds_read_b64_tr_b4 v[130:131], v54
	ds_read_b64_tr_b4 v[132:133], v55
	ds_read_b64_tr_b4 v[134:135], v56
	ds_read_b64_tr_b4 v[136:137], v57
	s_waitcnt lgkmcnt(15)
	v_dot8c_i32_i4_e32 v38, v122, v48
	v_dot8c_i32_i4_e32 v39, v122, v46
	v_dot8c_i32_i4_e32 v40, v124, v48
	v_dot8c_i32_i4_e32 v41, v124, v46
	v_dot8c_i32_i4_e32 v42, v126, v48
	v_dot8c_i32_i4_e32 v43, v126, v46
	v_dot8c_i32_i4_e32 v44, v128, v48
	v_dot8c_i32_i4_e32 v45, v128, v46
	v_dot8c_i32_i4_e32 v38, v123, v49
	v_dot8c_i32_i4_e32 v39, v123, v47
	v_dot8c_i32_i4_e32 v40, v125, v49
	v_dot8c_i32_i4_e32 v41, v125, v47
	v_dot8c_i32_i4_e32 v42, v127, v49
	v_dot8c_i32_i4_e32 v43, v127, v47
	v_dot8c_i32_i4_e32 v44, v129, v49
	v_dot8c_i32_i4_e32 v45, v129, v47
	s_waitcnt lgkmcnt(15)
	v_and_b32_e32 v78, 0xffff, v18
	v_lshrrev_b32_e32 v79, 16, v18
	v_lshl_add_u32 v78, v78, 7, v150
	v_lshl_add_u32 v79, v79, 7, v151
	s_mov_b32 m0, s76
	s_add_i32 s43, s76, 0x400
	global_load_lds_dwordx4 v78, s[50:51]
	s_mov_b32 m0, s43
	s_nop 0
	global_load_lds_dwordx4 v79, s[50:51]
	s_waitcnt vmcnt(9)
	v_add_u32_e32 v54, s78, v59
	v_add_u32_e32 v55, s78, v60
	v_add_u32_e32 v56, s78, v61
	v_add_u32_e32 v57, s78, v62
	ds_read_b64_tr_b4 v[46:47], v160 offset:512
	ds_read_b64_tr_b4 v[48:49], v160 offset:1536
	ds_read_b64_tr_b4 v[122:123], v54
	ds_read_b64_tr_b4 v[124:125], v55
	ds_read_b64_tr_b4 v[126:127], v56
	ds_read_b64_tr_b4 v[128:129], v57
	s_waitcnt lgkmcnt(6)
	v_dot8c_i32_i4_e32 v38, v130, v52
	v_dot8c_i32_i4_e32 v39, v130, v50
	v_dot8c_i32_i4_e32 v40, v132, v52
	v_dot8c_i32_i4_e32 v41, v132, v50
	v_dot8c_i32_i4_e32 v42, v134, v52
	v_dot8c_i32_i4_e32 v43, v134, v50
	v_dot8c_i32_i4_e32 v44, v136, v52
	v_dot8c_i32_i4_e32 v45, v136, v50
	v_dot8c_i32_i4_e32 v38, v131, v53
	v_dot8c_i32_i4_e32 v39, v131, v51
	v_dot8c_i32_i4_e32 v40, v133, v53
	v_dot8c_i32_i4_e32 v41, v133, v51
	v_dot8c_i32_i4_e32 v42, v135, v53
	v_dot8c_i32_i4_e32 v43, v135, v51
	v_dot8c_i32_i4_e32 v44, v137, v53
	v_dot8c_i32_i4_e32 v45, v137, v51
	v_and_b32_e32 v78, 0xffff, v19
	v_lshrrev_b32_e32 v79, 16, v19
	v_lshl_add_u32 v78, v78, 7, v150
	v_lshl_add_u32 v79, v79, 7, v151
	s_mov_b32 m0, s77
	s_add_i32 s43, s77, 0x400
	global_load_lds_dwordx4 v78, s[50:51]
	s_mov_b32 m0, s43
	s_nop 0
	global_load_lds_dwordx4 v79, s[50:51]
	s_waitcnt vmcnt(8)
; __device__ __forceinline__ bf16 f2bf(float f) { return (bf16)f2bfu(f); }
; #define TR4(p_) __builtin_amdgcn_ds_read_tr4_b64_v2i32((LAS v2i*)(p_))
; #define VDMA(st_, k_) do { _Pragma("unroll") for (int i_ = 0; i_ < 4; ++i_) { \
;         const unsigned off_ = (unsigned)((st_) >> 2) * (16384u * 128u) + (PE_ID(E, 4 * ((st_) & 3) + i_) << 7) + ((i_ & 1) ? cx1 : cx0); \
;         __builtin_amdgcn_global_load_lds((const unsigned*)(V4 + off_), (LAS unsigned*)(ldsb + BUF[k_] + 1024 * i_), 16, 0, 0); } } while (0)
; __device__ __forceinline__ void peer_v_tokens(int j, const LAS unsigned short* EL, const LAS unsigned char* AL  , const LAS float* ASC  , const LAS int* SAL  , ...
;     ...
;         for (int st = 0; st < 16; ++st) {
;             const int p = st >> 2, q = st & 3;
;             if (st < 14) VDMA(st + 2, (st + 2) % 3);
;             if (st < 14) asm volatile("s_waitcnt vmcnt(8)" ::: "memory");
;             else if (st == 14) asm volatile("s_waitcnt vmcnt(4)" ::: "memory");
;             else asm volatile("s_waitcnt vmcnt(0)" ::: "memory");
;             if (q == 0) {
; #pragma unroll
;                 for (int r = 0; r < 4; ++r) { accH[r] = 0; accL[r] = 0; } }
; #pragma unroll
;             for (int tp = 0; tp < 2; ++tp) {
;                 const v2i ao = TR4(ATL + (2 * q + tp) * 128 + 8 * s16), ah = TR4(ATL + 1024 + (2 * q + tp) * 128 + 8 * s16);
; #pragma unroll
;                 for (int r = 0; r < 4; ++r) {
;                     const v2i d = TR4(ldsb + BUF[st % 3] + 2048 * tp + roff[r]);
;                     accH[r] = __builtin_amdgcn_sdot8(d.x, ah.x, accH[r], false); accH[r] = __builtin_amdgcn_sdot8(d.y, ah.y, accH[r], false);
;                     accL[r] = __builtin_amdgcn_sdot8(d.x, ao.x, accL[r], false); accL[r] = __builtin_amdgcn_sdot8(d.y, ao.y, accL[r], false);
;                 }
;             }
;     ...
;                 for (int r = 0; r < 4; ++r) STASH[256 * p + 16 * (grp + 4 * r) + pc] = f2bf(asc * (float)(2 * ((accH[r] << 4) + accL[r]) + sa));
	v_add_u32_e32 v54, s79, v59
	v_add_u32_e32 v55, s79, v60
	v_add_u32_e32 v56, s79, v61
	v_add_u32_e32 v57, s79, v62
	ds_read_b64_tr_b4 v[50:51], v160 offset:640
	ds_read_b64_tr_b4 v[52:53], v160 offset:1664
	ds_read_b64_tr_b4 v[130:131], v54
	ds_read_b64_tr_b4 v[132:133], v55
	ds_read_b64_tr_b4 v[134:135], v56
	ds_read_b64_tr_b4 v[136:137], v57
	s_waitcnt lgkmcnt(6)
	v_dot8c_i32_i4_e32 v38, v122, v48
	v_dot8c_i32_i4_e32 v39, v122, v46
	v_dot8c_i32_i4_e32 v40, v124, v48
	v_dot8c_i32_i4_e32 v41, v124, v46
	v_dot8c_i32_i4_e32 v42, v126, v48
	v_dot8c_i32_i4_e32 v43, v126, v46
	v_dot8c_i32_i4_e32 v44, v128, v48
	v_dot8c_i32_i4_e32 v45, v128, v46
	v_dot8c_i32_i4_e32 v38, v123, v49
	v_dot8c_i32_i4_e32 v39, v123, v47
	v_dot8c_i32_i4_e32 v40, v125, v49
	v_dot8c_i32_i4_e32 v41, v125, v47
	v_dot8c_i32_i4_e32 v42, v127, v49
	v_dot8c_i32_i4_e32 v43, v127, v47
	v_dot8c_i32_i4_e32 v44, v129, v49
	v_dot8c_i32_i4_e32 v45, v129, v47
	s_waitcnt lgkmcnt(15)
	v_add_u32_e32 v143, 8, v139
	v_and_b32_e32 v142, 15, v143
	v_xor_b32_e32 v142, 8, v142
	v_bfe_u32 v144, v143, 4, 4
	v_mul_lo_u32 v142, v142, s92
	v_mul_lo_u32 v144, v144, s92
	v_mov_b32_e32 v143, v142
	v_mov_b32_e32 v145, v144
	ds_write2st64_b64 v159, v[142:143], v[144:145] offset1:2
	v_and_b32_e32 v78, 0xffff, v20
	v_lshrrev_b32_e32 v79, 16, v20
	v_lshl_add_u32 v78, v78, 7, v150
	v_lshl_add_u32 v79, v79, 7, v151
	s_mov_b32 m0, s78
	s_add_i32 s43, s78, 0x400
	global_load_lds_dwordx4 v78, s[50:51]
	s_mov_b32 m0, s43
	s_nop 0
	global_load_lds_dwordx4 v79, s[50:51]
	s_waitcnt vmcnt(8)
	v_add_u32_e32 v54, s98, v59
	v_add_u32_e32 v55, s98, v60
	v_add_u32_e32 v56, s98, v61
	v_add_u32_e32 v57, s98, v62
	ds_read_b64_tr_b4 v[46:47], v160 offset:768
	ds_read_b64_tr_b4 v[48:49], v160 offset:1792
	ds_read_b64_tr_b4 v[122:123], v54
	ds_read_b64_tr_b4 v[124:125], v55
	ds_read_b64_tr_b4 v[126:127], v56
	ds_read_b64_tr_b4 v[128:129], v57
	s_waitcnt lgkmcnt(7)
	v_dot8c_i32_i4_e32 v38, v130, v52
	v_dot8c_i32_i4_e32 v39, v130, v50
	v_dot8c_i32_i4_e32 v40, v132, v52
	v_dot8c_i32_i4_e32 v41, v132, v50
	v_dot8c_i32_i4_e32 v42, v134, v52
	v_dot8c_i32_i4_e32 v43, v134, v50
	v_dot8c_i32_i4_e32 v44, v136, v52
	v_dot8c_i32_i4_e32 v45, v136, v50
	v_dot8c_i32_i4_e32 v38, v131, v53
	v_dot8c_i32_i4_e32 v39, v131, v51
	v_dot8c_i32_i4_e32 v40, v133, v53
	v_dot8c_i32_i4_e32 v41, v133, v51
	v_dot8c_i32_i4_e32 v42, v135, v53
	v_dot8c_i32_i4_e32 v43, v135, v51
	v_dot8c_i32_i4_e32 v44, v137, v53
	v_dot8c_i32_i4_e32 v45, v137, v51
	v_and_b32_e32 v78, 0xffff, v21
	v_lshrrev_b32_e32 v79, 16, v21
	v_lshl_add_u32 v78, v78, 7, v150
	v_lshl_add_u32 v79, v79, 7, v151
	s_mov_b32 m0, s79
	s_add_i32 s43, s79, 0x400
	global_load_lds_dwordx4 v78, s[50:51]
	s_mov_b32 m0, s43
	s_nop 0
	global_load_lds_dwordx4 v79, s[50:51]
	s_waitcnt vmcnt(8)
	v_add_u32_e32 v54, s99, v59
	v_add_u32_e32 v55, s99, v60
	v_add_u32_e32 v56, s99, v61
	v_add_u32_e32 v57, s99, v62
	ds_read_b64_tr_b4 v[50:51], v160 offset:896
	ds_read_b64_tr_b4 v[52:53], v160 offset:1920
	ds_read_b64_tr_b4 v[130:131], v54
	ds_read_b64_tr_b4 v[132:133], v55
	ds_read_b64_tr_b4 v[134:135], v56
	ds_read_b64_tr_b4 v[136:137], v57
	s_waitcnt lgkmcnt(6)
	v_dot8c_i32_i4_e32 v38, v122, v48
	v_dot8c_i32_i4_e32 v39, v122, v46
	v_dot8c_i32_i4_e32 v40, v124, v48
	v_dot8c_i32_i4_e32 v41, v124, v46
	v_dot8c_i32_i4_e32 v42, v126, v48
	v_dot8c_i32_i4_e32 v43, v126, v46
	v_dot8c_i32_i4_e32 v44, v128, v48
	v_dot8c_i32_i4_e32 v45, v128, v46
	v_dot8c_i32_i4_e32 v38, v123, v49
	v_dot8c_i32_i4_e32 v39, v123, v47
	v_dot8c_i32_i4_e32 v40, v125, v49
	v_dot8c_i32_i4_e32 v41, v125, v47
	v_dot8c_i32_i4_e32 v42, v127, v49
	v_dot8c_i32_i4_e32 v43, v127, v47
	v_dot8c_i32_i4_e32 v44, v129, v49
	v_dot8c_i32_i4_e32 v45, v129, v47
	v_and_b32_e32 v78, 0xffff, v22
	v_lshrrev_b32_e32 v79, 16, v22
	v_lshl_add_u32 v78, v78, 7, v150
	v_lshl_add_u32 v79, v79, 7, v151
	s_mov_b32 m0, s98
	s_add_i32 s43, s98, 0x400
	global_load_lds_dwordx4 v78, s[50:51]
	s_mov_b32 m0, s43
	s_nop 0
	global_load_lds_dwordx4 v79, s[50:51]
	s_waitcnt vmcnt(8)
	v_add_u32_e32 v54, s76, v59
	v_add_u32_e32 v55, s76, v60
	v_add_u32_e32 v56, s76, v61
	v_add_u32_e32 v57, s76, v62
	ds_read_b64_tr_b4 v[46:47], v160
	ds_read_b64_tr_b4 v[48:49], v160 offset:1024
	ds_read_b64_tr_b4 v[122:123], v54
	ds_read_b64_tr_b4 v[124:125], v55
	ds_read_b64_tr_b4 v[126:127], v56
	ds_read_b64_tr_b4 v[128:129], v57
	s_waitcnt lgkmcnt(6)
	v_dot8c_i32_i4_e32 v38, v130, v52
	v_dot8c_i32_i4_e32 v39, v130, v50
	v_dot8c_i32_i4_e32 v40, v132, v52
	v_dot8c_i32_i4_e32 v41, v132, v50
	v_dot8c_i32_i4_e32 v42, v134, v52
	v_dot8c_i32_i4_e32 v43, v134, v50
	v_dot8c_i32_i4_e32 v44, v136, v52
	v_dot8c_i32_i4_e32 v45, v136, v50
	v_dot8c_i32_i4_e32 v38, v131, v53
	v_dot8c_i32_i4_e32 v39, v131, v51
	v_dot8c_i32_i4_e32 v40, v133, v53
	v_dot8c_i32_i4_e32 v41, v133, v51
	v_dot8c_i32_i4_e32 v42, v135, v53
	v_dot8c_i32_i4_e32 v43, v135, v51
	v_dot8c_i32_i4_e32 v44, v137, v53
	v_dot8c_i32_i4_e32 v45, v137, v51
	s_nop 3
	s_waitcnt lgkmcnt(15)
	v_lshlrev_b32_e32 v38, 5, v38
	v_lshlrev_b32_e32 v39, 1, v39
	v_add3_u32 v38, v39, v229, v38
	v_cvt_f32_i32_e32 v38, v38
	v_mul_f32_e32 v38, v228, v38
	v_lshlrev_b32_e32 v40, 5, v40
	v_lshlrev_b32_e32 v41, 1, v41
	v_add3_u32 v40, v41, v229, v40
	v_cvt_f32_i32_e32 v40, v40
	v_mul_f32_e32 v40, v228, v40
	v_lshlrev_b32_e32 v42, 5, v42
	v_lshlrev_b32_e32 v43, 1, v43
	v_add3_u32 v42, v43, v229, v42
	v_cvt_f32_i32_e32 v42, v42
	v_mul_f32_e32 v42, v228, v42
	v_lshlrev_b32_e32 v44, 5, v44
	v_lshlrev_b32_e32 v45, 1, v45
	v_add3_u32 v44, v45, v229, v44
	v_cvt_f32_i32_e32 v44, v44
	v_mul_f32_e32 v44, v228, v44
	v_cvt_pk_bf16_f32 v188, v38, v40
	v_cvt_pk_bf16_f32 v189, v42, v44
	ds_read_b128 v[252:255], v156
	s_add_i32 s44, s40, 0
	s_ashr_i32 s45, s44, 31
	s_lshl_b64 s[44:45], s[44:45], 12
	v_lshl_add_u64 v[80:81], v[36:37], 0, s[44:45]
	s_waitcnt lgkmcnt(0)
; #define LAS __attribute__((address_space(3)))
; __device__ __forceinline__ bf16 f2bf(float f) { return (bf16)f2bfu(f); }
; __device__ __forceinline__ void peer_v_tokens(int j, const LAS unsigned short* EL, const LAS unsigned char* AL  , const LAS float* ASC  , const LAS int* SAL  , ...
;     ...
;                 for (int r = 0; r < 4; ++r) STASH[256 * p + 16 * (grp + 4 * r) + pc] = f2bf(asc * (float)(2 * ((accH[r] << 4) + accL[r]) + sa));
;     ...
;         {
;             float4 v[4]; float ss = 0.f;
; #pragma unroll
;             for (int jq = 0; jq < 4; ++jq) { typedef unsigned u2v __attribute__((ext_vector_type(2))); const u2v pw = *(const LAS u2v*)(STASH + 4 * lane + 256 * jq); const uint2 hw = hv[jq];
;                 v[jq] = make_float4(__uint_as_float(hw.x << 16) + __uint_as_float(pw.x << 16), __uint_as_float(hw.x & 0xffff0000u) + __uint_as_float(pw.x & 0xffff0000u),
;                                     __uint_as_float(hw.y << 16) + __uint_as_float(pw.y << 16), __uint_as_float(hw.y & 0xffff0000u) + __uint_as_float(pw.y & 0xffff0000u));
;                 ss += v[jq].x * v[jq].x + v[jq].y * v[jq].y + v[jq].z * v[jq].z + v[jq].w * v[jq].w; }
;             ss = wave_sum(ss);
;             const float r3 = rsqrtf(ss * (1.f / D) + EPS);
;             float4* op = (float4*)(outp + (size_t)t * D) + lane;
; #pragma unroll
;             for (int jq = 0; jq < 4; ++jq) { typedef float f4v __attribute__((ext_vector_type(4))); f4v o4; o4.x = v[jq].x * r3 * gv[jq].x; o4.y = v[jq].y * r3 * gv[jq].y; o4.z = v[jq].z * r3 * gv[jq].z; o4.w = v[jq].w * r3 * gv[jq].w;
;                 __builtin_nontemporal_store(o4, (f4v*)op + 64 * jq); }
;         }
	v_mul_f32_e32 v218, v218, v252
	v_mul_f32_e32 v219, v219, v253
	v_mul_f32_e32 v220, v220, v254
	v_mul_f32_e32 v221, v221, v255
	global_store_dwordx4 v[80:81], v[218:221], off offset:2048 sc1
	v_add_u32_e32 v147, 8, v140
	v_and_b32_e32 v146, 15, v147
	v_xor_b32_e32 v146, 8, v146
	v_bfe_u32 v148, v147, 4, 4
	v_mul_lo_u32 v146, v146, s92
	v_mul_lo_u32 v148, v148, s92
	v_mov_b32_e32 v147, v146
	v_mov_b32_e32 v149, v148
	ds_write2st64_b64 v77, v[146:147], v[148:149] offset1:2
	v_add_u32_e32 v138, 0xc00, v74
	ds_read_u8 v139, v138
	v_add_u32_e32 v141, 0xc00, v73
	ds_read_u8 v140, v141
	s_add_i32 s43, s67, 64
	v_mov_b32_e32 v138, s43
	ds_read2st64_b32 v[228:229], v138 offset1:1
	ds_read_b128 v[26:29], v227 offset:6144
	ds_read_b128 v[30:33], v227 offset:6160
	v_mov_b32_e32 v38, 0
	v_mov_b32_e32 v39, 0
	v_mov_b32_e32 v40, 0
	v_mov_b32_e32 v41, 0
	v_mov_b32_e32 v42, 0
	v_mov_b32_e32 v43, 0
	v_mov_b32_e32 v44, 0
	v_mov_b32_e32 v45, 0
	v_and_b32_e32 v78, 0xffff, v23
	v_lshrrev_b32_e32 v79, 16, v23
	v_lshl_add_u32 v78, v78, 7, v150
	v_lshl_add_u32 v79, v79, 7, v151
	s_mov_b32 m0, s99
	s_add_i32 s43, s99, 0x400
	global_load_lds_dwordx4 v78, s[50:51]
	s_mov_b32 m0, s43
	s_nop 0
	global_load_lds_dwordx4 v79, s[50:51]
	s_waitcnt vmcnt(9)
	v_add_u32_e32 v54, s77, v59
	v_add_u32_e32 v55, s77, v60
	v_add_u32_e32 v56, s77, v61
	v_add_u32_e32 v57, s77, v62
	ds_read_b64_tr_b4 v[50:51], v160 offset:128
	ds_read_b64_tr_b4 v[52:53], v160 offset:1152
	ds_read_b64_tr_b4 v[130:131], v54
	ds_read_b64_tr_b4 v[132:133], v55
	ds_read_b64_tr_b4 v[134:135], v56
	ds_read_b64_tr_b4 v[136:137], v57
	s_waitcnt lgkmcnt(13)
	s_waitcnt vmcnt(36) lgkmcnt(15)
	v_lshlrev_b32_e32 v236, 16, v194
	v_and_b32_e32 v237, 0xffff0000, v194
	v_lshlrev_b32_e32 v142, 16, v202
	v_and_b32_e32 v143, 0xffff0000, v202
	v_add_f32_e32 v236, v236, v142
	v_add_f32_e32 v237, v237, v143
	v_lshlrev_b32_e32 v238, 16, v195
	v_and_b32_e32 v239, 0xffff0000, v195
	v_lshlrev_b32_e32 v142, 16, v203
	v_and_b32_e32 v143, 0xffff0000, v203
	v_add_f32_e32 v238, v238, v142
	v_add_f32_e32 v239, v239, v143
	v_lshlrev_b32_e32 v240, 16, v196
	v_and_b32_e32 v241, 0xffff0000, v196
	v_lshlrev_b32_e32 v142, 16, v204
	v_and_b32_e32 v143, 0xffff0000, v204
	v_add_f32_e32 v240, v240, v142
	v_add_f32_e32 v241, v241, v143
	v_lshlrev_b32_e32 v242, 16, v197
	v_and_b32_e32 v243, 0xffff0000, v197
	v_lshlrev_b32_e32 v142, 16, v205
	v_and_b32_e32 v143, 0xffff0000, v205
	v_add_f32_e32 v242, v242, v142
	v_add_f32_e32 v243, v243, v143
	v_lshlrev_b32_e32 v244, 16, v198
	v_and_b32_e32 v245, 0xffff0000, v198
	v_lshlrev_b32_e32 v142, 16, v206
	v_and_b32_e32 v143, 0xffff0000, v206
	v_add_f32_e32 v244, v244, v142
	v_add_f32_e32 v245, v245, v143
	v_lshlrev_b32_e32 v246, 16, v199
	v_and_b32_e32 v247, 0xffff0000, v199
	v_lshlrev_b32_e32 v142, 16, v207
	v_and_b32_e32 v143, 0xffff0000, v207
	v_add_f32_e32 v246, v246, v142
	v_add_f32_e32 v247, v247, v143
	v_lshlrev_b32_e32 v248, 16, v200
	v_and_b32_e32 v249, 0xffff0000, v200
	v_lshlrev_b32_e32 v142, 16, v208
	v_and_b32_e32 v143, 0xffff0000, v208
	v_add_f32_e32 v248, v248, v142
	v_add_f32_e32 v249, v249, v143
	v_lshlrev_b32_e32 v250, 16, v201
	v_and_b32_e32 v251, 0xffff0000, v201
	v_lshlrev_b32_e32 v142, 16, v209
	v_and_b32_e32 v143, 0xffff0000, v209
	v_add_f32_e32 v250, v250, v142
	v_add_f32_e32 v251, v251, v143
	v_mov_b32_e32 v144, 0
	v_mul_f32_e32 v145, v236, v236
	v_fmac_f32_e32 v145, v237, v237
	v_fmac_f32_e32 v145, v238, v238
	v_fmac_f32_e32 v145, v239, v239
	v_add_f32_e32 v144, v144, v145
	v_mul_f32_e32 v145, v240, v240
	v_fmac_f32_e32 v145, v241, v241
	v_fmac_f32_e32 v145, v242, v242
	v_fmac_f32_e32 v145, v243, v243
	v_add_f32_e32 v144, v144, v145
	v_mul_f32_e32 v145, v244, v244
	v_fmac_f32_e32 v145, v245, v245
	v_fmac_f32_e32 v145, v246, v246
	v_fmac_f32_e32 v145, v247, v247
	v_add_f32_e32 v144, v144, v145
	v_mul_f32_e32 v145, v248, v248
	v_fmac_f32_e32 v145, v249, v249
	v_fmac_f32_e32 v145, v250, v250
	v_fmac_f32_e32 v145, v251, v251
	v_add_f32_e32 v144, v144, v145
	s_nop 1
	v_add_f32_dpp v144, v144, v144 quad_perm:[1,0,3,2] row_mask:0xf bank_mask:0xf bound_ctrl:1
	s_nop 1
	v_add_f32_dpp v144, v144, v144 quad_perm:[2,3,0,1] row_mask:0xf bank_mask:0xf bound_ctrl:1
	s_nop 1
	v_add_f32_dpp v144, v144, v144 row_half_mirror row_mask:0xf bank_mask:0xf bound_ctrl:1
	s_nop 1
	v_add_f32_dpp v144, v144, v144 row_mirror row_mask:0xf bank_mask:0xf bound_ctrl:1
	s_nop 1
	v_readlane_b32 s10, v144, 0
	v_readlane_b32 s11, v144, 16
	v_readlane_b32 s14, v144, 32
	v_readlane_b32 s15, v144, 48
	s_nop 3
	v_mov_b32_e32 v144, s11
	v_mov_b32_e32 v145, s15
	v_add_f32_e32 v144, s10, v144
	v_add_f32_e32 v145, s14, v145
	v_add_f32_e32 v144, v144, v145
	v_fmamk_f32 v144, v144, 0x3a800000, v111
	v_rsq_f32_e32 v144, v144
	s_nop 0
	v_mul_f32_e32 v236, v236, v144
	v_mul_f32_e32 v237, v237, v144
	v_mul_f32_e32 v238, v238, v144
	v_mul_f32_e32 v239, v239, v144
	v_mul_f32_e32 v240, v240, v144
	v_mul_f32_e32 v241, v241, v144
	v_mul_f32_e32 v242, v242, v144
	v_mul_f32_e32 v243, v243, v144
	v_mul_f32_e32 v244, v244, v144
	v_mul_f32_e32 v245, v245, v144
	v_mul_f32_e32 v246, v246, v144
	v_mul_f32_e32 v247, v247, v144
	v_mul_f32_e32 v248, v248, v144
	v_mul_f32_e32 v249, v249, v144
	v_mul_f32_e32 v250, v250, v144
	v_mul_f32_e32 v251, v251, v144
	v_dot8c_i32_i4_e32 v38, v122, v48
	v_dot8c_i32_i4_e32 v39, v122, v46
	v_dot8c_i32_i4_e32 v40, v124, v48
	v_dot8c_i32_i4_e32 v41, v124, v46
	v_dot8c_i32_i4_e32 v42, v126, v48
	v_dot8c_i32_i4_e32 v43, v126, v46
	v_dot8c_i32_i4_e32 v44, v128, v48
	v_dot8c_i32_i4_e32 v45, v128, v46
	v_dot8c_i32_i4_e32 v38, v123, v49
	v_dot8c_i32_i4_e32 v39, v123, v47
	v_dot8c_i32_i4_e32 v40, v125, v49
	v_dot8c_i32_i4_e32 v41, v125, v47
	v_dot8c_i32_i4_e32 v42, v127, v49
	v_dot8c_i32_i4_e32 v43, v127, v47
	v_dot8c_i32_i4_e32 v44, v129, v49
	v_dot8c_i32_i4_e32 v45, v129, v47
	v_and_b32_e32 v78, 0xffff, v24
	v_lshrrev_b32_e32 v79, 16, v24
	v_lshl_add_u32 v78, v78, 7, v150
	v_lshl_add_u32 v79, v79, 7, v151
	s_mov_b32 m0, s76
	s_add_i32 s43, s76, 0x400
	global_load_lds_dwordx4 v78, s[50:51]
	s_mov_b32 m0, s43
	s_nop 0
	global_load_lds_dwordx4 v79, s[50:51]
	s_waitcnt vmcnt(9)
; #define LAS __attribute__((address_space(3)))
; #define TR4(p_) __builtin_amdgcn_ds_read_tr4_b64_v2i32((LAS v2i*)(p_))
; __device__ __forceinline__ void peer_v_tokens(int j, const LAS unsigned short* EL, const LAS unsigned char* AL  , const LAS float* ASC  , const LAS int* SAL  , ...
;     ...
;         for (int m = 0; m < 2; ++m) {
;             const int idx = lane + 64 * m, tau = idx >> 4, sr = idx & 15, k = 16 * (sr & 7) + 2 * tau + (sr >> 3);
;             const int aq = (int)*(const LAS signed char*)(AL + tl * 128 + k); const int tq = aq + 8;
;             const unsigned lo = (((unsigned)tq & 15u) ^ 8u) * 0x11111111u, hi = ((unsigned)(tq >> 4) & 15u) * 0x11111111u;
;             typedef unsigned u2v __attribute__((ext_vector_type(2)));
;             u2v l2; l2.x = lo; l2.y = lo; u2v h2; h2.x = hi; h2.y = hi;
;             *(LAS u2v*)(ATL + 8 * idx) = l2; *(LAS u2v*)(ATL + 1024 + 8 * idx) = h2;
;         }
;     ...
;         for (int st = 0; st < 16; ++st) {
;             const int p = st >> 2, q = st & 3;
;             if (st < 14) VDMA(st + 2, (st + 2) % 3);
;             if (st < 14) asm volatile("s_waitcnt vmcnt(8)" ::: "memory");
;             else if (st == 14) asm volatile("s_waitcnt vmcnt(4)" ::: "memory");
;             else asm volatile("s_waitcnt vmcnt(0)" ::: "memory");
;             if (q == 0) {
; #pragma unroll
;                 for (int r = 0; r < 4; ++r) { accH[r] = 0; accL[r] = 0; } }
; #pragma unroll
;             for (int tp = 0; tp < 2; ++tp) {
;                 const v2i ao = TR4(ATL + (2 * q + tp) * 128 + 8 * s16), ah = TR4(ATL + 1024 + (2 * q + tp) * 128 + 8 * s16);
; #pragma unroll
;                 for (int r = 0; r < 4; ++r) {
;                     const v2i d = TR4(ldsb + BUF[st % 3] + 2048 * tp + roff[r]);
;                     accH[r] = __builtin_amdgcn_sdot8(d.x, ah.x, accH[r], false); accH[r] = __builtin_amdgcn_sdot8(d.y, ah.y, accH[r], false);
;                     accL[r] = __builtin_amdgcn_sdot8(d.x, ao.x, accL[r], false); accL[r] = __builtin_amdgcn_sdot8(d.y, ao.y, accL[r], false);
;                 }
;             }
	v_add_u32_e32 v54, s78, v59
	v_add_u32_e32 v55, s78, v60
	v_add_u32_e32 v56, s78, v61
	v_add_u32_e32 v57, s78, v62
	ds_read_b64_tr_b4 v[46:47], v160 offset:256
	ds_read_b64_tr_b4 v[48:49], v160 offset:1280
	ds_read_b64_tr_b4 v[122:123], v54
	ds_read_b64_tr_b4 v[124:125], v55
	ds_read_b64_tr_b4 v[126:127], v56
	ds_read_b64_tr_b4 v[128:129], v57
	s_waitcnt lgkmcnt(6)
	v_dot8c_i32_i4_e32 v38, v130, v52
	v_dot8c_i32_i4_e32 v39, v130, v50
	v_dot8c_i32_i4_e32 v40, v132, v52
	v_dot8c_i32_i4_e32 v41, v132, v50
	v_dot8c_i32_i4_e32 v42, v134, v52
	v_dot8c_i32_i4_e32 v43, v134, v50
	v_dot8c_i32_i4_e32 v44, v136, v52
	v_dot8c_i32_i4_e32 v45, v136, v50
	v_dot8c_i32_i4_e32 v38, v131, v53
	v_dot8c_i32_i4_e32 v39, v131, v51
	v_dot8c_i32_i4_e32 v40, v133, v53
	v_dot8c_i32_i4_e32 v41, v133, v51
	v_dot8c_i32_i4_e32 v42, v135, v53
	v_dot8c_i32_i4_e32 v43, v135, v51
	v_dot8c_i32_i4_e32 v44, v137, v53
	v_dot8c_i32_i4_e32 v45, v137, v51
	v_and_b32_e32 v78, 0xffff, v25
	v_lshrrev_b32_e32 v79, 16, v25
	v_lshl_add_u32 v78, v78, 7, v150
	v_lshl_add_u32 v79, v79, 7, v151
	s_mov_b32 m0, s77
	s_add_i32 s43, s77, 0x400
	global_load_lds_dwordx4 v78, s[50:51]
	s_mov_b32 m0, s43
	s_nop 0
	global_load_lds_dwordx4 v79, s[50:51]
	s_waitcnt vmcnt(9)
	v_add_u32_e32 v54, s79, v59
	v_add_u32_e32 v55, s79, v60
	v_add_u32_e32 v56, s79, v61
	v_add_u32_e32 v57, s79, v62
	ds_read_b64_tr_b4 v[50:51], v160 offset:384
	ds_read_b64_tr_b4 v[52:53], v160 offset:1408
	ds_read_b64_tr_b4 v[130:131], v54
	ds_read_b64_tr_b4 v[132:133], v55
	ds_read_b64_tr_b4 v[134:135], v56
	ds_read_b64_tr_b4 v[136:137], v57
	s_waitcnt lgkmcnt(6)
	v_dot8c_i32_i4_e32 v38, v122, v48
	v_dot8c_i32_i4_e32 v39, v122, v46
	v_dot8c_i32_i4_e32 v40, v124, v48
	v_dot8c_i32_i4_e32 v41, v124, v46
	v_dot8c_i32_i4_e32 v42, v126, v48
	v_dot8c_i32_i4_e32 v43, v126, v46
	v_dot8c_i32_i4_e32 v44, v128, v48
	v_dot8c_i32_i4_e32 v45, v128, v46
	v_dot8c_i32_i4_e32 v38, v123, v49
	v_dot8c_i32_i4_e32 v39, v123, v47
	v_dot8c_i32_i4_e32 v40, v125, v49
	v_dot8c_i32_i4_e32 v41, v125, v47
	v_dot8c_i32_i4_e32 v42, v127, v49
	v_dot8c_i32_i4_e32 v43, v127, v47
	v_dot8c_i32_i4_e32 v44, v129, v49
	v_dot8c_i32_i4_e32 v45, v129, v47
	s_waitcnt lgkmcnt(15)
	v_and_b32_e32 v78, 0xffff, v26
	v_lshrrev_b32_e32 v79, 16, v26
	v_lshl_add_u32 v78, v78, 7, v150
	v_lshl_add_u32 v79, v79, 7, v151
	s_mov_b32 m0, s78
	s_add_i32 s43, s78, 0x400
	global_load_lds_dwordx4 v78, s[50:51]
	s_mov_b32 m0, s43
	s_nop 0
	global_load_lds_dwordx4 v79, s[50:51]
	s_waitcnt vmcnt(9)
	v_add_u32_e32 v54, s98, v59
	v_add_u32_e32 v55, s98, v60
	v_add_u32_e32 v56, s98, v61
	v_add_u32_e32 v57, s98, v62
	ds_read_b64_tr_b4 v[46:47], v160 offset:512
	ds_read_b64_tr_b4 v[48:49], v160 offset:1536
	ds_read_b64_tr_b4 v[122:123], v54
	ds_read_b64_tr_b4 v[124:125], v55
	ds_read_b64_tr_b4 v[126:127], v56
	ds_read_b64_tr_b4 v[128:129], v57
	s_waitcnt lgkmcnt(6)
	v_dot8c_i32_i4_e32 v38, v130, v52
	v_dot8c_i32_i4_e32 v39, v130, v50
	v_dot8c_i32_i4_e32 v40, v132, v52
	v_dot8c_i32_i4_e32 v41, v132, v50
	v_dot8c_i32_i4_e32 v42, v134, v52
	v_dot8c_i32_i4_e32 v43, v134, v50
	v_dot8c_i32_i4_e32 v44, v136, v52
	v_dot8c_i32_i4_e32 v45, v136, v50
	v_dot8c_i32_i4_e32 v38, v131, v53
	v_dot8c_i32_i4_e32 v39, v131, v51
	v_dot8c_i32_i4_e32 v40, v133, v53
	v_dot8c_i32_i4_e32 v41, v133, v51
	v_dot8c_i32_i4_e32 v42, v135, v53
	v_dot8c_i32_i4_e32 v43, v135, v51
	v_dot8c_i32_i4_e32 v44, v137, v53
	v_dot8c_i32_i4_e32 v45, v137, v51
	v_and_b32_e32 v78, 0xffff, v27
	v_lshrrev_b32_e32 v79, 16, v27
	v_lshl_add_u32 v78, v78, 7, v150
	v_lshl_add_u32 v79, v79, 7, v151
	s_mov_b32 m0, s79
	s_add_i32 s43, s79, 0x400
	global_load_lds_dwordx4 v78, s[50:51]
	s_mov_b32 m0, s43
	s_nop 0
	global_load_lds_dwordx4 v79, s[50:51]
	s_waitcnt vmcnt(8)
	v_add_u32_e32 v54, s99, v59
	v_add_u32_e32 v55, s99, v60
	v_add_u32_e32 v56, s99, v61
	v_add_u32_e32 v57, s99, v62
	ds_read_b64_tr_b4 v[50:51], v160 offset:640
	ds_read_b64_tr_b4 v[52:53], v160 offset:1664
	ds_read_b64_tr_b4 v[130:131], v54
	ds_read_b64_tr_b4 v[132:133], v55
	ds_read_b64_tr_b4 v[134:135], v56
	ds_read_b64_tr_b4 v[136:137], v57
	s_waitcnt lgkmcnt(6)
	v_dot8c_i32_i4_e32 v38, v122, v48
	v_dot8c_i32_i4_e32 v39, v122, v46
	v_dot8c_i32_i4_e32 v40, v124, v48
	v_dot8c_i32_i4_e32 v41, v124, v46
	v_dot8c_i32_i4_e32 v42, v126, v48
	v_dot8c_i32_i4_e32 v43, v126, v46
	v_dot8c_i32_i4_e32 v44, v128, v48
	v_dot8c_i32_i4_e32 v45, v128, v46
	v_dot8c_i32_i4_e32 v38, v123, v49
	v_dot8c_i32_i4_e32 v39, v123, v47
	v_dot8c_i32_i4_e32 v40, v125, v49
	v_dot8c_i32_i4_e32 v41, v125, v47
	v_dot8c_i32_i4_e32 v42, v127, v49
	v_dot8c_i32_i4_e32 v43, v127, v47
	v_dot8c_i32_i4_e32 v44, v129, v49
	v_dot8c_i32_i4_e32 v45, v129, v47
	s_waitcnt lgkmcnt(15)
	v_add_u32_e32 v143, 8, v139
	v_and_b32_e32 v142, 15, v143
	v_xor_b32_e32 v142, 8, v142
	v_bfe_u32 v144, v143, 4, 4
	v_mul_lo_u32 v142, v142, s92
	v_mul_lo_u32 v144, v144, s92
	v_mov_b32_e32 v143, v142
	v_mov_b32_e32 v145, v144
	ds_write2st64_b64 v159, v[142:143], v[144:145] offset1:2
	v_and_b32_e32 v78, 0xffff, v28
	v_lshrrev_b32_e32 v79, 16, v28
	v_lshl_add_u32 v78, v78, 7, v150
	v_lshl_add_u32 v79, v79, 7, v151
	s_mov_b32 m0, s98
	s_add_i32 s43, s98, 0x400
	global_load_lds_dwordx4 v78, s[50:51]
	s_mov_b32 m0, s43
	s_nop 0
	global_load_lds_dwordx4 v79, s[50:51]
	s_waitcnt vmcnt(8)
	v_add_u32_e32 v54, s76, v59
	v_add_u32_e32 v55, s76, v60
	v_add_u32_e32 v56, s76, v61
	v_add_u32_e32 v57, s76, v62
	ds_read_b64_tr_b4 v[46:47], v160 offset:768
	ds_read_b64_tr_b4 v[48:49], v160 offset:1792
	ds_read_b64_tr_b4 v[122:123], v54
	ds_read_b64_tr_b4 v[124:125], v55
	ds_read_b64_tr_b4 v[126:127], v56
	ds_read_b64_tr_b4 v[128:129], v57
	s_waitcnt lgkmcnt(7)
; #define LAS __attribute__((address_space(3)))
; __device__ __forceinline__ bf16 f2bf(float f) { return (bf16)f2bfu(f); }
; __device__ __forceinline__ void peer_v_tokens(int j, const LAS unsigned short* EL, const LAS unsigned char* AL  , const LAS float* ASC  , const LAS int* SAL  , ...
;     ...
;         for (int m = 0; m < 2; ++m) {
;             const int idx = lane + 64 * m, tau = idx >> 4, sr = idx & 15, k = 16 * (sr & 7) + 2 * tau + (sr >> 3);
;             const int aq = (int)*(const LAS signed char*)(AL + tl * 128 + k); const int tq = aq + 8;
;             const unsigned lo = (((unsigned)tq & 15u) ^ 8u) * 0x11111111u, hi = ((unsigned)(tq >> 4) & 15u) * 0x11111111u;
;             typedef unsigned u2v __attribute__((ext_vector_type(2)));
;             u2v l2; l2.x = lo; l2.y = lo; u2v h2; h2.x = hi; h2.y = hi;
;             *(LAS u2v*)(ATL + 8 * idx) = l2; *(LAS u2v*)(ATL + 1024 + 8 * idx) = h2;
;         }
;     ...
;                 for (int r = 0; r < 4; ++r) STASH[256 * p + 16 * (grp + 4 * r) + pc] = f2bf(asc * (float)(2 * ((accH[r] << 4) + accL[r]) + sa));
;     ...
;         {
;             float4 v[4]; float ss = 0.f;
; #pragma unroll
;             for (int jq = 0; jq < 4; ++jq) { typedef unsigned u2v __attribute__((ext_vector_type(2))); const u2v pw = *(const LAS u2v*)(STASH + 4 * lane + 256 * jq); const uint2 hw = hv[jq];
;                 v[jq] = make_float4(__uint_as_float(hw.x << 16) + __uint_as_float(pw.x << 16), __uint_as_float(hw.x & 0xffff0000u) + __uint_as_float(pw.x & 0xffff0000u),
;                                     __uint_as_float(hw.y << 16) + __uint_as_float(pw.y << 16), __uint_as_float(hw.y & 0xffff0000u) + __uint_as_float(pw.y & 0xffff0000u));
;                 ss += v[jq].x * v[jq].x + v[jq].y * v[jq].y + v[jq].z * v[jq].z + v[jq].w * v[jq].w; }
;             ss = wave_sum(ss);
;             const float r3 = rsqrtf(ss * (1.f / D) + EPS);
;             float4* op = (float4*)(outp + (size_t)t * D) + lane;
; #pragma unroll
;             for (int jq = 0; jq < 4; ++jq) { typedef float f4v __attribute__((ext_vector_type(4))); f4v o4; o4.x = v[jq].x * r3 * gv[jq].x; o4.y = v[jq].y * r3 * gv[jq].y; o4.z = v[jq].z * r3 * gv[jq].z; o4.w = v[jq].w * r3 * gv[jq].w;
;                 __builtin_nontemporal_store(o4, (f4v*)op + 64 * jq); }
;         }
	v_dot8c_i32_i4_e32 v38, v130, v52
	v_dot8c_i32_i4_e32 v39, v130, v50
	v_dot8c_i32_i4_e32 v40, v132, v52
	v_dot8c_i32_i4_e32 v41, v132, v50
	v_dot8c_i32_i4_e32 v42, v134, v52
	v_dot8c_i32_i4_e32 v43, v134, v50
	v_dot8c_i32_i4_e32 v44, v136, v52
	v_dot8c_i32_i4_e32 v45, v136, v50
	v_dot8c_i32_i4_e32 v38, v131, v53
	v_dot8c_i32_i4_e32 v39, v131, v51
	v_dot8c_i32_i4_e32 v40, v133, v53
	v_dot8c_i32_i4_e32 v41, v133, v51
	v_dot8c_i32_i4_e32 v42, v135, v53
	v_dot8c_i32_i4_e32 v43, v135, v51
	v_dot8c_i32_i4_e32 v44, v137, v53
	v_dot8c_i32_i4_e32 v45, v137, v51
	v_and_b32_e32 v78, 0xffff, v29
	v_lshrrev_b32_e32 v79, 16, v29
	v_lshl_add_u32 v78, v78, 7, v150
	v_lshl_add_u32 v79, v79, 7, v151
	s_mov_b32 m0, s99
	s_add_i32 s43, s99, 0x400
	global_load_lds_dwordx4 v78, s[50:51]
	s_mov_b32 m0, s43
	s_nop 0
	global_load_lds_dwordx4 v79, s[50:51]
	s_waitcnt vmcnt(8)
	v_add_u32_e32 v54, s77, v59
	v_add_u32_e32 v55, s77, v60
	v_add_u32_e32 v56, s77, v61
	v_add_u32_e32 v57, s77, v62
	ds_read_b64_tr_b4 v[50:51], v160 offset:896
	ds_read_b64_tr_b4 v[52:53], v160 offset:1920
	ds_read_b64_tr_b4 v[130:131], v54
	ds_read_b64_tr_b4 v[132:133], v55
	ds_read_b64_tr_b4 v[134:135], v56
	ds_read_b64_tr_b4 v[136:137], v57
	s_waitcnt lgkmcnt(6)
	v_dot8c_i32_i4_e32 v38, v122, v48
	v_dot8c_i32_i4_e32 v39, v122, v46
	v_dot8c_i32_i4_e32 v40, v124, v48
	v_dot8c_i32_i4_e32 v41, v124, v46
	v_dot8c_i32_i4_e32 v42, v126, v48
	v_dot8c_i32_i4_e32 v43, v126, v46
	v_dot8c_i32_i4_e32 v44, v128, v48
	v_dot8c_i32_i4_e32 v45, v128, v46
	v_dot8c_i32_i4_e32 v38, v123, v49
	v_dot8c_i32_i4_e32 v39, v123, v47
	v_dot8c_i32_i4_e32 v40, v125, v49
	v_dot8c_i32_i4_e32 v41, v125, v47
	v_dot8c_i32_i4_e32 v42, v127, v49
	v_dot8c_i32_i4_e32 v43, v127, v47
	v_dot8c_i32_i4_e32 v44, v129, v49
	v_dot8c_i32_i4_e32 v45, v129, v47
	v_and_b32_e32 v78, 0xffff, v30
	v_lshrrev_b32_e32 v79, 16, v30
	v_lshl_add_u32 v78, v78, 7, v150
	v_lshl_add_u32 v79, v79, 7, v151
	s_mov_b32 m0, s76
	s_add_i32 s43, s76, 0x400
	global_load_lds_dwordx4 v78, s[50:51]
	s_mov_b32 m0, s43
	s_nop 0
	global_load_lds_dwordx4 v79, s[50:51]
	s_waitcnt vmcnt(8)
	v_add_u32_e32 v54, s78, v59
	v_add_u32_e32 v55, s78, v60
	v_add_u32_e32 v56, s78, v61
	v_add_u32_e32 v57, s78, v62
	ds_read_b64_tr_b4 v[46:47], v160
	ds_read_b64_tr_b4 v[48:49], v160 offset:1024
	ds_read_b64_tr_b4 v[122:123], v54
	ds_read_b64_tr_b4 v[124:125], v55
	ds_read_b64_tr_b4 v[126:127], v56
	ds_read_b64_tr_b4 v[128:129], v57
	s_waitcnt lgkmcnt(6)
	v_dot8c_i32_i4_e32 v38, v130, v52
	v_dot8c_i32_i4_e32 v39, v130, v50
	v_dot8c_i32_i4_e32 v40, v132, v52
	v_dot8c_i32_i4_e32 v41, v132, v50
	v_dot8c_i32_i4_e32 v42, v134, v52
	v_dot8c_i32_i4_e32 v43, v134, v50
	v_dot8c_i32_i4_e32 v44, v136, v52
	v_dot8c_i32_i4_e32 v45, v136, v50
	v_dot8c_i32_i4_e32 v38, v131, v53
	v_dot8c_i32_i4_e32 v39, v131, v51
	v_dot8c_i32_i4_e32 v40, v133, v53
	v_dot8c_i32_i4_e32 v41, v133, v51
	v_dot8c_i32_i4_e32 v42, v135, v53
	v_dot8c_i32_i4_e32 v43, v135, v51
	v_dot8c_i32_i4_e32 v44, v137, v53
	v_dot8c_i32_i4_e32 v45, v137, v51
	s_nop 3
	s_waitcnt lgkmcnt(15)
	v_lshlrev_b32_e32 v38, 5, v38
	v_lshlrev_b32_e32 v39, 1, v39
	v_add3_u32 v38, v39, v229, v38
	v_cvt_f32_i32_e32 v38, v38
	v_mul_f32_e32 v38, v228, v38
	v_lshlrev_b32_e32 v40, 5, v40
	v_lshlrev_b32_e32 v41, 1, v41
	v_add3_u32 v40, v41, v229, v40
	v_cvt_f32_i32_e32 v40, v40
	v_mul_f32_e32 v40, v228, v40
	v_lshlrev_b32_e32 v42, 5, v42
	v_lshlrev_b32_e32 v43, 1, v43
	v_add3_u32 v42, v43, v229, v42
	v_cvt_f32_i32_e32 v42, v42
	v_mul_f32_e32 v42, v228, v42
	v_lshlrev_b32_e32 v44, 5, v44
	v_lshlrev_b32_e32 v45, 1, v45
	v_add3_u32 v44, v45, v229, v44
	v_cvt_f32_i32_e32 v44, v44
	v_mul_f32_e32 v44, v228, v44
	v_cvt_pk_bf16_f32 v182, v38, v40
	v_cvt_pk_bf16_f32 v183, v42, v44
	ds_read_b128 v[252:255], v156 offset:1024
	s_add_i32 s44, s40, 0
	s_ashr_i32 s45, s44, 31
	s_lshl_b64 s[44:45], s[44:45], 12
	v_lshl_add_u64 v[80:81], v[36:37], 0, s[44:45]
	s_waitcnt lgkmcnt(0)
	v_mul_f32_e32 v222, v222, v252
	v_mul_f32_e32 v223, v223, v253
	v_mul_f32_e32 v224, v224, v254
	v_mul_f32_e32 v225, v225, v255
	global_store_dwordx4 v[80:81], v[222:225], off offset:3072 sc1
	ds_read_b128 v[252:255], v155
	s_add_i32 s44, s40, 8
	s_ashr_i32 s45, s44, 31
	s_lshl_b64 s[44:45], s[44:45], 12
	v_lshl_add_u64 v[80:81], v[36:37], 0, s[44:45]
	s_waitcnt lgkmcnt(0)
	v_mul_f32_e32 v236, v236, v252
	v_mul_f32_e32 v237, v237, v253
	v_mul_f32_e32 v238, v238, v254
	v_mul_f32_e32 v239, v239, v255
	global_store_dwordx4 v[80:81], v[236:239], off sc1
	v_add_u32_e32 v147, 8, v140
	v_and_b32_e32 v146, 15, v147
	v_xor_b32_e32 v146, 8, v146
	v_bfe_u32 v148, v147, 4, 4
	v_mul_lo_u32 v146, v146, s92
	v_mul_lo_u32 v148, v148, s92
	v_mov_b32_e32 v147, v146
	v_mov_b32_e32 v149, v148
	ds_write2st64_b64 v77, v[146:147], v[148:149] offset1:2
	v_add_u32_e32 v138, 0x800, v74
	ds_read_u8 v139, v138
	v_add_u32_e32 v141, 0x800, v73
	ds_read_u8 v140, v141
	s_add_i32 s43, s67, 96
	v_mov_b32_e32 v138, s43
	ds_read2st64_b32 v[228:229], v138 offset1:1
	ds_read_b128 v[18:21], v227 offset:4096
	ds_read_b128 v[22:25], v227 offset:4112
	v_add_u32_e32 v152, 0x600000, v63
	v_add_u32_e32 v153, 0x600000, v64
	v_mov_b32_e32 v38, 0
	v_mov_b32_e32 v39, 0
	v_mov_b32_e32 v40, 0
	v_mov_b32_e32 v41, 0
	v_mov_b32_e32 v42, 0
	v_mov_b32_e32 v43, 0
	v_mov_b32_e32 v44, 0
	v_mov_b32_e32 v45, 0
	v_and_b32_e32 v78, 0xffff, v31
	v_lshrrev_b32_e32 v79, 16, v31
	v_lshl_add_u32 v78, v78, 7, v150
	v_lshl_add_u32 v79, v79, 7, v151
	s_mov_b32 m0, s77
	s_add_i32 s43, s77, 0x400
	global_load_lds_dwordx4 v78, s[50:51]
	s_mov_b32 m0, s43
	s_nop 0
	global_load_lds_dwordx4 v79, s[50:51]
	s_waitcnt vmcnt(10)
; #define TR4(p_) __builtin_amdgcn_ds_read_tr4_b64_v2i32((LAS v2i*)(p_))
; #define VDMA(st_, k_) do { _Pragma("unroll") for (int i_ = 0; i_ < 4; ++i_) { \
;         const unsigned off_ = (unsigned)((st_) >> 2) * (16384u * 128u) + (PE_ID(E, 4 * ((st_) & 3) + i_) << 7) + ((i_ & 1) ? cx1 : cx0); \
;         __builtin_amdgcn_global_load_lds((const unsigned*)(V4 + off_), (LAS unsigned*)(ldsb + BUF[k_] + 1024 * i_), 16, 0, 0); } } while (0)
; __device__ __forceinline__ void peer_v_tokens(int j, const LAS unsigned short* EL, const LAS unsigned char* AL  , const LAS float* ASC  , const LAS int* SAL  , ...
;     ...
;         for (int st = 0; st < 16; ++st) {
;             const int p = st >> 2, q = st & 3;
;             if (st < 14) VDMA(st + 2, (st + 2) % 3);
;             if (st < 14) asm volatile("s_waitcnt vmcnt(8)" ::: "memory");
;             else if (st == 14) asm volatile("s_waitcnt vmcnt(4)" ::: "memory");
;             else asm volatile("s_waitcnt vmcnt(0)" ::: "memory");
;             if (q == 0) {
; #pragma unroll
;                 for (int r = 0; r < 4; ++r) { accH[r] = 0; accL[r] = 0; } }
; #pragma unroll
;             for (int tp = 0; tp < 2; ++tp) {
;                 const v2i ao = TR4(ATL + (2 * q + tp) * 128 + 8 * s16), ah = TR4(ATL + 1024 + (2 * q + tp) * 128 + 8 * s16);
; #pragma unroll
;                 for (int r = 0; r < 4; ++r) {
;                     const v2i d = TR4(ldsb + BUF[st % 3] + 2048 * tp + roff[r]);
;                     accH[r] = __builtin_amdgcn_sdot8(d.x, ah.x, accH[r], false); accH[r] = __builtin_amdgcn_sdot8(d.y, ah.y, accH[r], false);
;                     accL[r] = __builtin_amdgcn_sdot8(d.x, ao.x, accL[r], false); accL[r] = __builtin_amdgcn_sdot8(d.y, ao.y, accL[r], false);
;                 }
;             }
	v_add_u32_e32 v54, s79, v59
	v_add_u32_e32 v55, s79, v60
	v_add_u32_e32 v56, s79, v61
	v_add_u32_e32 v57, s79, v62
	ds_read_b64_tr_b4 v[50:51], v160 offset:128
	ds_read_b64_tr_b4 v[52:53], v160 offset:1152
	ds_read_b64_tr_b4 v[130:131], v54
	ds_read_b64_tr_b4 v[132:133], v55
	ds_read_b64_tr_b4 v[134:135], v56
	ds_read_b64_tr_b4 v[136:137], v57
	s_waitcnt lgkmcnt(14)
	v_dot8c_i32_i4_e32 v38, v122, v48
	v_dot8c_i32_i4_e32 v39, v122, v46
	v_dot8c_i32_i4_e32 v40, v124, v48
	v_dot8c_i32_i4_e32 v41, v124, v46
	v_dot8c_i32_i4_e32 v42, v126, v48
	v_dot8c_i32_i4_e32 v43, v126, v46
	v_dot8c_i32_i4_e32 v44, v128, v48
	v_dot8c_i32_i4_e32 v45, v128, v46
	v_dot8c_i32_i4_e32 v38, v123, v49
	v_dot8c_i32_i4_e32 v39, v123, v47
	v_dot8c_i32_i4_e32 v40, v125, v49
	v_dot8c_i32_i4_e32 v41, v125, v47
	v_dot8c_i32_i4_e32 v42, v127, v49
	v_dot8c_i32_i4_e32 v43, v127, v47
	v_dot8c_i32_i4_e32 v44, v129, v49
	v_dot8c_i32_i4_e32 v45, v129, v47
	v_and_b32_e32 v78, 0xffff, v32
	v_lshrrev_b32_e32 v79, 16, v32
	v_lshl_add_u32 v78, v78, 7, v150
	v_lshl_add_u32 v79, v79, 7, v151
	s_mov_b32 m0, s78
	s_add_i32 s43, s78, 0x400
	global_load_lds_dwordx4 v78, s[50:51]
	s_mov_b32 m0, s43
	s_nop 0
	global_load_lds_dwordx4 v79, s[50:51]
	s_waitcnt vmcnt(10)
	v_add_u32_e32 v54, s98, v59
	v_add_u32_e32 v55, s98, v60
	v_add_u32_e32 v56, s98, v61
	v_add_u32_e32 v57, s98, v62
	ds_read_b64_tr_b4 v[46:47], v160 offset:256
	ds_read_b64_tr_b4 v[48:49], v160 offset:1280
	ds_read_b64_tr_b4 v[122:123], v54
	ds_read_b64_tr_b4 v[124:125], v55
	ds_read_b64_tr_b4 v[126:127], v56
	ds_read_b64_tr_b4 v[128:129], v57
	s_waitcnt lgkmcnt(6)
	v_dot8c_i32_i4_e32 v38, v130, v52
	v_dot8c_i32_i4_e32 v39, v130, v50
	v_dot8c_i32_i4_e32 v40, v132, v52
	v_dot8c_i32_i4_e32 v41, v132, v50
	v_dot8c_i32_i4_e32 v42, v134, v52
	v_dot8c_i32_i4_e32 v43, v134, v50
	v_dot8c_i32_i4_e32 v44, v136, v52
	v_dot8c_i32_i4_e32 v45, v136, v50
	v_dot8c_i32_i4_e32 v38, v131, v53
	v_dot8c_i32_i4_e32 v39, v131, v51
	v_dot8c_i32_i4_e32 v40, v133, v53
	v_dot8c_i32_i4_e32 v41, v133, v51
	v_dot8c_i32_i4_e32 v42, v135, v53
	v_dot8c_i32_i4_e32 v43, v135, v51
	v_dot8c_i32_i4_e32 v44, v137, v53
	v_dot8c_i32_i4_e32 v45, v137, v51
	v_and_b32_e32 v78, 0xffff, v33
	v_lshrrev_b32_e32 v79, 16, v33
	v_lshl_add_u32 v78, v78, 7, v150
	v_lshl_add_u32 v79, v79, 7, v151
	s_mov_b32 m0, s79
	s_add_i32 s43, s79, 0x400
	global_load_lds_dwordx4 v78, s[50:51]
	s_mov_b32 m0, s43
	s_nop 0
	global_load_lds_dwordx4 v79, s[50:51]
	s_waitcnt vmcnt(10)
	v_add_u32_e32 v54, s99, v59
	v_add_u32_e32 v55, s99, v60
	v_add_u32_e32 v56, s99, v61
	v_add_u32_e32 v57, s99, v62
	ds_read_b64_tr_b4 v[50:51], v160 offset:384
	ds_read_b64_tr_b4 v[52:53], v160 offset:1408
	ds_read_b64_tr_b4 v[130:131], v54
	ds_read_b64_tr_b4 v[132:133], v55
	ds_read_b64_tr_b4 v[134:135], v56
	ds_read_b64_tr_b4 v[136:137], v57
	s_waitcnt lgkmcnt(6)
	v_dot8c_i32_i4_e32 v38, v122, v48
	v_dot8c_i32_i4_e32 v39, v122, v46
	v_dot8c_i32_i4_e32 v40, v124, v48
	v_dot8c_i32_i4_e32 v41, v124, v46
	v_dot8c_i32_i4_e32 v42, v126, v48
	v_dot8c_i32_i4_e32 v43, v126, v46
	v_dot8c_i32_i4_e32 v44, v128, v48
	v_dot8c_i32_i4_e32 v45, v128, v46
	v_dot8c_i32_i4_e32 v38, v123, v49
	v_dot8c_i32_i4_e32 v39, v123, v47
	v_dot8c_i32_i4_e32 v40, v125, v49
	v_dot8c_i32_i4_e32 v41, v125, v47
	v_dot8c_i32_i4_e32 v42, v127, v49
	v_dot8c_i32_i4_e32 v43, v127, v47
	v_dot8c_i32_i4_e32 v44, v129, v49
	v_dot8c_i32_i4_e32 v45, v129, v47
	s_waitcnt lgkmcnt(15)
	v_and_b32_e32 v78, 0xffff, v18
	v_lshrrev_b32_e32 v79, 16, v18
	v_lshl_add_u32 v78, v78, 7, v152
	v_lshl_add_u32 v79, v79, 7, v153
	s_mov_b32 m0, s98
	s_add_i32 s43, s98, 0x400
	global_load_lds_dwordx4 v78, s[50:51]
	s_mov_b32 m0, s43
	s_nop 0
	global_load_lds_dwordx4 v79, s[50:51]
	s_waitcnt vmcnt(10)
	v_add_u32_e32 v54, s76, v59
	v_add_u32_e32 v55, s76, v60
	v_add_u32_e32 v56, s76, v61
	v_add_u32_e32 v57, s76, v62
	ds_read_b64_tr_b4 v[46:47], v160 offset:512
	ds_read_b64_tr_b4 v[48:49], v160 offset:1536
	ds_read_b64_tr_b4 v[122:123], v54
	ds_read_b64_tr_b4 v[124:125], v55
	ds_read_b64_tr_b4 v[126:127], v56
	ds_read_b64_tr_b4 v[128:129], v57
	s_waitcnt lgkmcnt(6)
	v_dot8c_i32_i4_e32 v38, v130, v52
	v_dot8c_i32_i4_e32 v39, v130, v50
	v_dot8c_i32_i4_e32 v40, v132, v52
	v_dot8c_i32_i4_e32 v41, v132, v50
	v_dot8c_i32_i4_e32 v42, v134, v52
	v_dot8c_i32_i4_e32 v43, v134, v50
	v_dot8c_i32_i4_e32 v44, v136, v52
	v_dot8c_i32_i4_e32 v45, v136, v50
	v_dot8c_i32_i4_e32 v38, v131, v53
	v_dot8c_i32_i4_e32 v39, v131, v51
	v_dot8c_i32_i4_e32 v40, v133, v53
	v_dot8c_i32_i4_e32 v41, v133, v51
	v_dot8c_i32_i4_e32 v42, v135, v53
	v_dot8c_i32_i4_e32 v43, v135, v51
	v_dot8c_i32_i4_e32 v44, v137, v53
	v_dot8c_i32_i4_e32 v45, v137, v51
	v_and_b32_e32 v78, 0xffff, v19
	v_lshrrev_b32_e32 v79, 16, v19
	v_lshl_add_u32 v78, v78, 7, v152
	v_lshl_add_u32 v79, v79, 7, v153
	s_mov_b32 m0, s99
	s_add_i32 s43, s99, 0x400
	global_load_lds_dwordx4 v78, s[50:51]
	s_mov_b32 m0, s43
	s_nop 0
	global_load_lds_dwordx4 v79, s[50:51]
	s_waitcnt vmcnt(8)
	v_add_u32_e32 v54, s77, v59
	v_add_u32_e32 v55, s77, v60
	v_add_u32_e32 v56, s77, v61
	v_add_u32_e32 v57, s77, v62
	ds_read_b64_tr_b4 v[50:51], v160 offset:640
	ds_read_b64_tr_b4 v[52:53], v160 offset:1664
	ds_read_b64_tr_b4 v[130:131], v54
	ds_read_b64_tr_b4 v[132:133], v55
	ds_read_b64_tr_b4 v[134:135], v56
	ds_read_b64_tr_b4 v[136:137], v57
	s_waitcnt lgkmcnt(6)
	v_dot8c_i32_i4_e32 v38, v122, v48
	v_dot8c_i32_i4_e32 v39, v122, v46
	v_dot8c_i32_i4_e32 v40, v124, v48
	v_dot8c_i32_i4_e32 v41, v124, v46
	v_dot8c_i32_i4_e32 v42, v126, v48
	v_dot8c_i32_i4_e32 v43, v126, v46
	v_dot8c_i32_i4_e32 v44, v128, v48
	v_dot8c_i32_i4_e32 v45, v128, v46
	v_dot8c_i32_i4_e32 v38, v123, v49
	v_dot8c_i32_i4_e32 v39, v123, v47
	v_dot8c_i32_i4_e32 v40, v125, v49
	v_dot8c_i32_i4_e32 v41, v125, v47
	v_dot8c_i32_i4_e32 v42, v127, v49
	v_dot8c_i32_i4_e32 v43, v127, v47
	v_dot8c_i32_i4_e32 v44, v129, v49
	v_dot8c_i32_i4_e32 v45, v129, v47
	s_waitcnt lgkmcnt(15)
; #define LAS __attribute__((address_space(3)))
; __device__ __forceinline__ bf16 f2bf(float f) { return (bf16)f2bfu(f); }
; __device__ __forceinline__ void peer_v_tokens(int j, const LAS unsigned short* EL, const LAS unsigned char* AL  , const LAS float* ASC  , const LAS int* SAL  , ...
;     ...
;         for (int m = 0; m < 2; ++m) {
;             const int idx = lane + 64 * m, tau = idx >> 4, sr = idx & 15, k = 16 * (sr & 7) + 2 * tau + (sr >> 3);
;             const int aq = (int)*(const LAS signed char*)(AL + tl * 128 + k); const int tq = aq + 8;
;             const unsigned lo = (((unsigned)tq & 15u) ^ 8u) * 0x11111111u, hi = ((unsigned)(tq >> 4) & 15u) * 0x11111111u;
;             typedef unsigned u2v __attribute__((ext_vector_type(2)));
;             u2v l2; l2.x = lo; l2.y = lo; u2v h2; h2.x = hi; h2.y = hi;
;             *(LAS u2v*)(ATL + 8 * idx) = l2; *(LAS u2v*)(ATL + 1024 + 8 * idx) = h2;
;         }
;     ...
;                 for (int r = 0; r < 4; ++r) STASH[256 * p + 16 * (grp + 4 * r) + pc] = f2bf(asc * (float)(2 * ((accH[r] << 4) + accL[r]) + sa));
;     ...
;         {
;             float4 v[4]; float ss = 0.f;
; #pragma unroll
;             for (int jq = 0; jq < 4; ++jq) { typedef unsigned u2v __attribute__((ext_vector_type(2))); const u2v pw = *(const LAS u2v*)(STASH + 4 * lane + 256 * jq); const uint2 hw = hv[jq];
;                 v[jq] = make_float4(__uint_as_float(hw.x << 16) + __uint_as_float(pw.x << 16), __uint_as_float(hw.x & 0xffff0000u) + __uint_as_float(pw.x & 0xffff0000u),
;                                     __uint_as_float(hw.y << 16) + __uint_as_float(pw.y << 16), __uint_as_float(hw.y & 0xffff0000u) + __uint_as_float(pw.y & 0xffff0000u));
;                 ss += v[jq].x * v[jq].x + v[jq].y * v[jq].y + v[jq].z * v[jq].z + v[jq].w * v[jq].w; }
;             ss = wave_sum(ss);
;             const float r3 = rsqrtf(ss * (1.f / D) + EPS);
;             float4* op = (float4*)(outp + (size_t)t * D) + lane;
; #pragma unroll
;             for (int jq = 0; jq < 4; ++jq) { typedef float f4v __attribute__((ext_vector_type(4))); f4v o4; o4.x = v[jq].x * r3 * gv[jq].x; o4.y = v[jq].y * r3 * gv[jq].y; o4.z = v[jq].z * r3 * gv[jq].z; o4.w = v[jq].w * r3 * gv[jq].w;
;                 __builtin_nontemporal_store(o4, (f4v*)op + 64 * jq); }
;         }
	v_add_u32_e32 v143, 8, v139
	v_and_b32_e32 v142, 15, v143
	v_xor_b32_e32 v142, 8, v142
	v_bfe_u32 v144, v143, 4, 4
	v_mul_lo_u32 v142, v142, s92
	v_mul_lo_u32 v144, v144, s92
	v_mov_b32_e32 v143, v142
	v_mov_b32_e32 v145, v144
	ds_write2st64_b64 v159, v[142:143], v[144:145] offset1:2
	v_and_b32_e32 v78, 0xffff, v20
	v_lshrrev_b32_e32 v79, 16, v20
	v_lshl_add_u32 v78, v78, 7, v152
	v_lshl_add_u32 v79, v79, 7, v153
	s_mov_b32 m0, s76
	s_add_i32 s43, s76, 0x400
	global_load_lds_dwordx4 v78, s[50:51]
	s_mov_b32 m0, s43
	s_nop 0
	global_load_lds_dwordx4 v79, s[50:51]
	s_waitcnt vmcnt(8)
	v_add_u32_e32 v54, s78, v59
	v_add_u32_e32 v55, s78, v60
	v_add_u32_e32 v56, s78, v61
	v_add_u32_e32 v57, s78, v62
	ds_read_b64_tr_b4 v[46:47], v160 offset:768
	ds_read_b64_tr_b4 v[48:49], v160 offset:1792
	ds_read_b64_tr_b4 v[122:123], v54
	ds_read_b64_tr_b4 v[124:125], v55
	ds_read_b64_tr_b4 v[126:127], v56
	ds_read_b64_tr_b4 v[128:129], v57
	s_waitcnt lgkmcnt(7)
	v_dot8c_i32_i4_e32 v38, v130, v52
	v_dot8c_i32_i4_e32 v39, v130, v50
	v_dot8c_i32_i4_e32 v40, v132, v52
	v_dot8c_i32_i4_e32 v41, v132, v50
	v_dot8c_i32_i4_e32 v42, v134, v52
	v_dot8c_i32_i4_e32 v43, v134, v50
	v_dot8c_i32_i4_e32 v44, v136, v52
	v_dot8c_i32_i4_e32 v45, v136, v50
	v_dot8c_i32_i4_e32 v38, v131, v53
	v_dot8c_i32_i4_e32 v39, v131, v51
	v_dot8c_i32_i4_e32 v40, v133, v53
	v_dot8c_i32_i4_e32 v41, v133, v51
	v_dot8c_i32_i4_e32 v42, v135, v53
	v_dot8c_i32_i4_e32 v43, v135, v51
	v_dot8c_i32_i4_e32 v44, v137, v53
	v_dot8c_i32_i4_e32 v45, v137, v51
	v_and_b32_e32 v78, 0xffff, v21
	v_lshrrev_b32_e32 v79, 16, v21
	v_lshl_add_u32 v78, v78, 7, v152
	v_lshl_add_u32 v79, v79, 7, v153
	s_mov_b32 m0, s77
	s_add_i32 s43, s77, 0x400
	global_load_lds_dwordx4 v78, s[50:51]
	s_mov_b32 m0, s43
	s_nop 0
	global_load_lds_dwordx4 v79, s[50:51]
	s_waitcnt vmcnt(8)
	v_add_u32_e32 v54, s79, v59
	v_add_u32_e32 v55, s79, v60
	v_add_u32_e32 v56, s79, v61
	v_add_u32_e32 v57, s79, v62
	ds_read_b64_tr_b4 v[50:51], v160 offset:896
	ds_read_b64_tr_b4 v[52:53], v160 offset:1920
	ds_read_b64_tr_b4 v[130:131], v54
	ds_read_b64_tr_b4 v[132:133], v55
	ds_read_b64_tr_b4 v[134:135], v56
	ds_read_b64_tr_b4 v[136:137], v57
	s_waitcnt lgkmcnt(6)
	v_dot8c_i32_i4_e32 v38, v122, v48
	v_dot8c_i32_i4_e32 v39, v122, v46
	v_dot8c_i32_i4_e32 v40, v124, v48
	v_dot8c_i32_i4_e32 v41, v124, v46
	v_dot8c_i32_i4_e32 v42, v126, v48
	v_dot8c_i32_i4_e32 v43, v126, v46
	v_dot8c_i32_i4_e32 v44, v128, v48
	v_dot8c_i32_i4_e32 v45, v128, v46
	v_dot8c_i32_i4_e32 v38, v123, v49
	v_dot8c_i32_i4_e32 v39, v123, v47
	v_dot8c_i32_i4_e32 v40, v125, v49
	v_dot8c_i32_i4_e32 v41, v125, v47
	v_dot8c_i32_i4_e32 v42, v127, v49
	v_dot8c_i32_i4_e32 v43, v127, v47
	v_dot8c_i32_i4_e32 v44, v129, v49
	v_dot8c_i32_i4_e32 v45, v129, v47
	v_and_b32_e32 v78, 0xffff, v22
	v_lshrrev_b32_e32 v79, 16, v22
	v_lshl_add_u32 v78, v78, 7, v152
	v_lshl_add_u32 v79, v79, 7, v153
	s_mov_b32 m0, s78
	s_add_i32 s43, s78, 0x400
	global_load_lds_dwordx4 v78, s[50:51]
	s_mov_b32 m0, s43
	s_nop 0
	global_load_lds_dwordx4 v79, s[50:51]
	s_waitcnt vmcnt(8)
	v_add_u32_e32 v54, s98, v59
	v_add_u32_e32 v55, s98, v60
	v_add_u32_e32 v56, s98, v61
	v_add_u32_e32 v57, s98, v62
	ds_read_b64_tr_b4 v[46:47], v160
	ds_read_b64_tr_b4 v[48:49], v160 offset:1024
	ds_read_b64_tr_b4 v[122:123], v54
	ds_read_b64_tr_b4 v[124:125], v55
	ds_read_b64_tr_b4 v[126:127], v56
	ds_read_b64_tr_b4 v[128:129], v57
	s_waitcnt lgkmcnt(6)
	v_dot8c_i32_i4_e32 v38, v130, v52
	v_dot8c_i32_i4_e32 v39, v130, v50
	v_dot8c_i32_i4_e32 v40, v132, v52
	v_dot8c_i32_i4_e32 v41, v132, v50
	v_dot8c_i32_i4_e32 v42, v134, v52
	v_dot8c_i32_i4_e32 v43, v134, v50
	v_dot8c_i32_i4_e32 v44, v136, v52
	v_dot8c_i32_i4_e32 v45, v136, v50
	v_dot8c_i32_i4_e32 v38, v131, v53
	v_dot8c_i32_i4_e32 v39, v131, v51
	v_dot8c_i32_i4_e32 v40, v133, v53
	v_dot8c_i32_i4_e32 v41, v133, v51
	v_dot8c_i32_i4_e32 v42, v135, v53
	v_dot8c_i32_i4_e32 v43, v135, v51
	v_dot8c_i32_i4_e32 v44, v137, v53
	v_dot8c_i32_i4_e32 v45, v137, v51
	s_nop 3
	s_waitcnt lgkmcnt(15)
	v_lshlrev_b32_e32 v38, 5, v38
	v_lshlrev_b32_e32 v39, 1, v39
	v_add3_u32 v38, v39, v229, v38
	v_cvt_f32_i32_e32 v38, v38
	v_mul_f32_e32 v38, v228, v38
	v_lshlrev_b32_e32 v40, 5, v40
	v_lshlrev_b32_e32 v41, 1, v41
	v_add3_u32 v40, v41, v229, v40
	v_cvt_f32_i32_e32 v40, v40
	v_mul_f32_e32 v40, v228, v40
	v_lshlrev_b32_e32 v42, 5, v42
	v_lshlrev_b32_e32 v43, 1, v43
	v_add3_u32 v42, v43, v229, v42
	v_cvt_f32_i32_e32 v42, v42
	v_mul_f32_e32 v42, v228, v42
	v_lshlrev_b32_e32 v44, 5, v44
	v_lshlrev_b32_e32 v45, 1, v45
	v_add3_u32 v44, v45, v229, v44
	v_cvt_f32_i32_e32 v44, v44
	v_mul_f32_e32 v44, v228, v44
	v_cvt_pk_bf16_f32 v190, v38, v40
	v_cvt_pk_bf16_f32 v191, v42, v44
	ds_read_b128 v[252:255], v155 offset:1024
	s_add_i32 s44, s40, 8
	s_ashr_i32 s45, s44, 31
	s_lshl_b64 s[44:45], s[44:45], 12
	v_lshl_add_u64 v[80:81], v[36:37], 0, s[44:45]
	s_waitcnt lgkmcnt(0)
	v_mul_f32_e32 v240, v240, v252
	v_mul_f32_e32 v241, v241, v253
	v_mul_f32_e32 v242, v242, v254
	v_mul_f32_e32 v243, v243, v255
	global_store_dwordx4 v[80:81], v[240:243], off offset:1024 sc1
	v_add_u32_e32 v147, 8, v140
	v_and_b32_e32 v146, 15, v147
	v_xor_b32_e32 v146, 8, v146
	v_bfe_u32 v148, v147, 4, 4
	v_mul_lo_u32 v146, v146, s92
	v_mul_lo_u32 v148, v148, s92
	v_mov_b32_e32 v147, v146
	v_mov_b32_e32 v149, v148
	ds_write2st64_b64 v77, v[146:147], v[148:149] offset1:2
	v_add_u32_e32 v138, 0xc00, v74
	ds_read_u8 v139, v138
	v_add_u32_e32 v141, 0xc00, v73
	ds_read_u8 v140, v141
	s_add_i32 s43, s67, 64
	v_mov_b32_e32 v138, s43
	ds_read2st64_b32 v[228:229], v138 offset1:1
	ds_read_b128 v[26:29], v227 offset:6144
	ds_read_b128 v[30:33], v227 offset:6160
	v_mov_b32_e32 v38, 0
	v_mov_b32_e32 v39, 0
	v_mov_b32_e32 v40, 0
	v_mov_b32_e32 v41, 0
	v_mov_b32_e32 v42, 0
	v_mov_b32_e32 v43, 0
	v_mov_b32_e32 v44, 0
	v_mov_b32_e32 v45, 0
	v_and_b32_e32 v78, 0xffff, v23
	v_lshrrev_b32_e32 v79, 16, v23
	v_lshl_add_u32 v78, v78, 7, v152
	v_lshl_add_u32 v79, v79, 7, v153
	s_mov_b32 m0, s79
	s_add_i32 s43, s79, 0x400
	global_load_lds_dwordx4 v78, s[50:51]
	s_mov_b32 m0, s43
	s_nop 0
	global_load_lds_dwordx4 v79, s[50:51]
	s_waitcnt vmcnt(9)
; #define TR4(p_) __builtin_amdgcn_ds_read_tr4_b64_v2i32((LAS v2i*)(p_))
; #define VDMA(st_, k_) do { _Pragma("unroll") for (int i_ = 0; i_ < 4; ++i_) { \
;         const unsigned off_ = (unsigned)((st_) >> 2) * (16384u * 128u) + (PE_ID(E, 4 * ((st_) & 3) + i_) << 7) + ((i_ & 1) ? cx1 : cx0); \
;         __builtin_amdgcn_global_load_lds((const unsigned*)(V4 + off_), (LAS unsigned*)(ldsb + BUF[k_] + 1024 * i_), 16, 0, 0); } } while (0)
; __device__ __forceinline__ void peer_v_tokens(int j, const LAS unsigned short* EL, const LAS unsigned char* AL  , const LAS float* ASC  , const LAS int* SAL  , ...
;     ...
;         for (int st = 0; st < 16; ++st) {
;             const int p = st >> 2, q = st & 3;
;             if (st < 14) VDMA(st + 2, (st + 2) % 3);
;             if (st < 14) asm volatile("s_waitcnt vmcnt(8)" ::: "memory");
;             else if (st == 14) asm volatile("s_waitcnt vmcnt(4)" ::: "memory");
;             else asm volatile("s_waitcnt vmcnt(0)" ::: "memory");
;             if (q == 0) {
; #pragma unroll
;                 for (int r = 0; r < 4; ++r) { accH[r] = 0; accL[r] = 0; } }
; #pragma unroll
;             for (int tp = 0; tp < 2; ++tp) {
;                 const v2i ao = TR4(ATL + (2 * q + tp) * 128 + 8 * s16), ah = TR4(ATL + 1024 + (2 * q + tp) * 128 + 8 * s16);
; #pragma unroll
;                 for (int r = 0; r < 4; ++r) {
;                     const v2i d = TR4(ldsb + BUF[st % 3] + 2048 * tp + roff[r]);
;                     accH[r] = __builtin_amdgcn_sdot8(d.x, ah.x, accH[r], false); accH[r] = __builtin_amdgcn_sdot8(d.y, ah.y, accH[r], false);
;                     accL[r] = __builtin_amdgcn_sdot8(d.x, ao.x, accL[r], false); accL[r] = __builtin_amdgcn_sdot8(d.y, ao.y, accL[r], false);
;                 }
;             }
	v_add_u32_e32 v54, s99, v59
	v_add_u32_e32 v55, s99, v60
	v_add_u32_e32 v56, s99, v61
	v_add_u32_e32 v57, s99, v62
	ds_read_b64_tr_b4 v[50:51], v160 offset:128
	ds_read_b64_tr_b4 v[52:53], v160 offset:1152
	ds_read_b64_tr_b4 v[130:131], v54
	ds_read_b64_tr_b4 v[132:133], v55
	ds_read_b64_tr_b4 v[134:135], v56
	ds_read_b64_tr_b4 v[136:137], v57
	s_waitcnt lgkmcnt(13)
	v_dot8c_i32_i4_e32 v38, v122, v48
	v_dot8c_i32_i4_e32 v39, v122, v46
	v_dot8c_i32_i4_e32 v40, v124, v48
	v_dot8c_i32_i4_e32 v41, v124, v46
	v_dot8c_i32_i4_e32 v42, v126, v48
	v_dot8c_i32_i4_e32 v43, v126, v46
	v_dot8c_i32_i4_e32 v44, v128, v48
	v_dot8c_i32_i4_e32 v45, v128, v46
	v_dot8c_i32_i4_e32 v38, v123, v49
	v_dot8c_i32_i4_e32 v39, v123, v47
	v_dot8c_i32_i4_e32 v40, v125, v49
	v_dot8c_i32_i4_e32 v41, v125, v47
	v_dot8c_i32_i4_e32 v42, v127, v49
	v_dot8c_i32_i4_e32 v43, v127, v47
	v_dot8c_i32_i4_e32 v44, v129, v49
	v_dot8c_i32_i4_e32 v45, v129, v47
	v_and_b32_e32 v78, 0xffff, v24
	v_lshrrev_b32_e32 v79, 16, v24
	v_lshl_add_u32 v78, v78, 7, v152
	v_lshl_add_u32 v79, v79, 7, v153
	s_mov_b32 m0, s98
	s_add_i32 s43, s98, 0x400
	global_load_lds_dwordx4 v78, s[50:51]
	s_mov_b32 m0, s43
	s_nop 0
	global_load_lds_dwordx4 v79, s[50:51]
	s_waitcnt vmcnt(9)
	v_add_u32_e32 v54, s76, v59
	v_add_u32_e32 v55, s76, v60
	v_add_u32_e32 v56, s76, v61
	v_add_u32_e32 v57, s76, v62
	ds_read_b64_tr_b4 v[46:47], v160 offset:256
	ds_read_b64_tr_b4 v[48:49], v160 offset:1280
	ds_read_b64_tr_b4 v[122:123], v54
	ds_read_b64_tr_b4 v[124:125], v55
	ds_read_b64_tr_b4 v[126:127], v56
	ds_read_b64_tr_b4 v[128:129], v57
	s_waitcnt lgkmcnt(6)
	v_dot8c_i32_i4_e32 v38, v130, v52
	v_dot8c_i32_i4_e32 v39, v130, v50
	v_dot8c_i32_i4_e32 v40, v132, v52
	v_dot8c_i32_i4_e32 v41, v132, v50
	v_dot8c_i32_i4_e32 v42, v134, v52
	v_dot8c_i32_i4_e32 v43, v134, v50
	v_dot8c_i32_i4_e32 v44, v136, v52
	v_dot8c_i32_i4_e32 v45, v136, v50
	v_dot8c_i32_i4_e32 v38, v131, v53
	v_dot8c_i32_i4_e32 v39, v131, v51
	v_dot8c_i32_i4_e32 v40, v133, v53
	v_dot8c_i32_i4_e32 v41, v133, v51
	v_dot8c_i32_i4_e32 v42, v135, v53
	v_dot8c_i32_i4_e32 v43, v135, v51
	v_dot8c_i32_i4_e32 v44, v137, v53
	v_dot8c_i32_i4_e32 v45, v137, v51
	v_and_b32_e32 v78, 0xffff, v25
	v_lshrrev_b32_e32 v79, 16, v25
	v_lshl_add_u32 v78, v78, 7, v152
	v_lshl_add_u32 v79, v79, 7, v153
	s_mov_b32 m0, s99
	s_add_i32 s43, s99, 0x400
	global_load_lds_dwordx4 v78, s[50:51]
	s_mov_b32 m0, s43
	s_nop 0
	global_load_lds_dwordx4 v79, s[50:51]
	s_waitcnt vmcnt(9)
	v_add_u32_e32 v54, s77, v59
	v_add_u32_e32 v55, s77, v60
	v_add_u32_e32 v56, s77, v61
	v_add_u32_e32 v57, s77, v62
	ds_read_b64_tr_b4 v[50:51], v160 offset:384
	ds_read_b64_tr_b4 v[52:53], v160 offset:1408
	ds_read_b64_tr_b4 v[130:131], v54
	ds_read_b64_tr_b4 v[132:133], v55
	ds_read_b64_tr_b4 v[134:135], v56
	ds_read_b64_tr_b4 v[136:137], v57
	s_waitcnt lgkmcnt(6)
	v_dot8c_i32_i4_e32 v38, v122, v48
	v_dot8c_i32_i4_e32 v39, v122, v46
	v_dot8c_i32_i4_e32 v40, v124, v48
	v_dot8c_i32_i4_e32 v41, v124, v46
	v_dot8c_i32_i4_e32 v42, v126, v48
	v_dot8c_i32_i4_e32 v43, v126, v46
	v_dot8c_i32_i4_e32 v44, v128, v48
	v_dot8c_i32_i4_e32 v45, v128, v46
	v_dot8c_i32_i4_e32 v38, v123, v49
	v_dot8c_i32_i4_e32 v39, v123, v47
	v_dot8c_i32_i4_e32 v40, v125, v49
	v_dot8c_i32_i4_e32 v41, v125, v47
	v_dot8c_i32_i4_e32 v42, v127, v49
	v_dot8c_i32_i4_e32 v43, v127, v47
	v_dot8c_i32_i4_e32 v44, v129, v49
	v_dot8c_i32_i4_e32 v45, v129, v47
	s_waitcnt lgkmcnt(15)
	v_and_b32_e32 v78, 0xffff, v26
	v_lshrrev_b32_e32 v79, 16, v26
	v_lshl_add_u32 v78, v78, 7, v152
	v_lshl_add_u32 v79, v79, 7, v153
	s_mov_b32 m0, s76
	s_add_i32 s43, s76, 0x400
	global_load_lds_dwordx4 v78, s[50:51]
	s_mov_b32 m0, s43
	s_nop 0
	global_load_lds_dwordx4 v79, s[50:51]
	s_waitcnt vmcnt(9)
	v_add_u32_e32 v54, s78, v59
	v_add_u32_e32 v55, s78, v60
	v_add_u32_e32 v56, s78, v61
	v_add_u32_e32 v57, s78, v62
	ds_read_b64_tr_b4 v[46:47], v160 offset:512
	ds_read_b64_tr_b4 v[48:49], v160 offset:1536
	ds_read_b64_tr_b4 v[122:123], v54
	ds_read_b64_tr_b4 v[124:125], v55
	ds_read_b64_tr_b4 v[126:127], v56
	ds_read_b64_tr_b4 v[128:129], v57
	s_waitcnt lgkmcnt(6)
	v_dot8c_i32_i4_e32 v38, v130, v52
	v_dot8c_i32_i4_e32 v39, v130, v50
	v_dot8c_i32_i4_e32 v40, v132, v52
	v_dot8c_i32_i4_e32 v41, v132, v50
	v_dot8c_i32_i4_e32 v42, v134, v52
	v_dot8c_i32_i4_e32 v43, v134, v50
	v_dot8c_i32_i4_e32 v44, v136, v52
	v_dot8c_i32_i4_e32 v45, v136, v50
	v_dot8c_i32_i4_e32 v38, v131, v53
	v_dot8c_i32_i4_e32 v39, v131, v51
	v_dot8c_i32_i4_e32 v40, v133, v53
	v_dot8c_i32_i4_e32 v41, v133, v51
	v_dot8c_i32_i4_e32 v42, v135, v53
	v_dot8c_i32_i4_e32 v43, v135, v51
	v_dot8c_i32_i4_e32 v44, v137, v53
	v_dot8c_i32_i4_e32 v45, v137, v51
	v_and_b32_e32 v78, 0xffff, v27
	v_lshrrev_b32_e32 v79, 16, v27
	v_lshl_add_u32 v78, v78, 7, v152
	v_lshl_add_u32 v79, v79, 7, v153
	s_mov_b32 m0, s77
	s_add_i32 s43, s77, 0x400
	global_load_lds_dwordx4 v78, s[50:51]
	s_mov_b32 m0, s43
	s_nop 0
	global_load_lds_dwordx4 v79, s[50:51]
	s_waitcnt vmcnt(8)
	v_add_u32_e32 v54, s79, v59
	v_add_u32_e32 v55, s79, v60
	v_add_u32_e32 v56, s79, v61
	v_add_u32_e32 v57, s79, v62
	ds_read_b64_tr_b4 v[50:51], v160 offset:640
	ds_read_b64_tr_b4 v[52:53], v160 offset:1664
	ds_read_b64_tr_b4 v[130:131], v54
	ds_read_b64_tr_b4 v[132:133], v55
	ds_read_b64_tr_b4 v[134:135], v56
	ds_read_b64_tr_b4 v[136:137], v57
	s_waitcnt lgkmcnt(6)
	v_dot8c_i32_i4_e32 v38, v122, v48
	v_dot8c_i32_i4_e32 v39, v122, v46
	v_dot8c_i32_i4_e32 v40, v124, v48
	v_dot8c_i32_i4_e32 v41, v124, v46
	v_dot8c_i32_i4_e32 v42, v126, v48
	v_dot8c_i32_i4_e32 v43, v126, v46
	v_dot8c_i32_i4_e32 v44, v128, v48
	v_dot8c_i32_i4_e32 v45, v128, v46
	v_dot8c_i32_i4_e32 v38, v123, v49
	v_dot8c_i32_i4_e32 v39, v123, v47
	v_dot8c_i32_i4_e32 v40, v125, v49
	v_dot8c_i32_i4_e32 v41, v125, v47
	v_dot8c_i32_i4_e32 v42, v127, v49
	v_dot8c_i32_i4_e32 v43, v127, v47
	v_dot8c_i32_i4_e32 v44, v129, v49
	v_dot8c_i32_i4_e32 v45, v129, v47
	s_waitcnt lgkmcnt(15)
; #define LAS __attribute__((address_space(3)))
; __device__ __forceinline__ bf16 f2bf(float f) { return (bf16)f2bfu(f); }
; #define TR4(p_) __builtin_amdgcn_ds_read_tr4_b64_v2i32((LAS v2i*)(p_))
; __device__ __forceinline__ void peer_v_tokens(int j, const LAS unsigned short* EL, const LAS unsigned char* AL  , const LAS float* ASC  , const LAS int* SAL  , ...
;     ...
;         for (int m = 0; m < 2; ++m) {
;             const int idx = lane + 64 * m, tau = idx >> 4, sr = idx & 15, k = 16 * (sr & 7) + 2 * tau + (sr >> 3);
;             const int aq = (int)*(const LAS signed char*)(AL + tl * 128 + k); const int tq = aq + 8;
;             const unsigned lo = (((unsigned)tq & 15u) ^ 8u) * 0x11111111u, hi = ((unsigned)(tq >> 4) & 15u) * 0x11111111u;
;             typedef unsigned u2v __attribute__((ext_vector_type(2)));
;             u2v l2; l2.x = lo; l2.y = lo; u2v h2; h2.x = hi; h2.y = hi;
;             *(LAS u2v*)(ATL + 8 * idx) = l2; *(LAS u2v*)(ATL + 1024 + 8 * idx) = h2;
;         }
;     ...
;         for (int st = 0; st < 16; ++st) {
;             const int p = st >> 2, q = st & 3;
;             if (st < 14) VDMA(st + 2, (st + 2) % 3);
;             if (st < 14) asm volatile("s_waitcnt vmcnt(8)" ::: "memory");
;             else if (st == 14) asm volatile("s_waitcnt vmcnt(4)" ::: "memory");
;             else asm volatile("s_waitcnt vmcnt(0)" ::: "memory");
;             if (q == 0) {
; #pragma unroll
;                 for (int r = 0; r < 4; ++r) { accH[r] = 0; accL[r] = 0; } }
; #pragma unroll
;             for (int tp = 0; tp < 2; ++tp) {
;                 const v2i ao = TR4(ATL + (2 * q + tp) * 128 + 8 * s16), ah = TR4(ATL + 1024 + (2 * q + tp) * 128 + 8 * s16);
; #pragma unroll
;                 for (int r = 0; r < 4; ++r) {
;                     const v2i d = TR4(ldsb + BUF[st % 3] + 2048 * tp + roff[r]);
;                     accH[r] = __builtin_amdgcn_sdot8(d.x, ah.x, accH[r], false); accH[r] = __builtin_amdgcn_sdot8(d.y, ah.y, accH[r], false);
;                     accL[r] = __builtin_amdgcn_sdot8(d.x, ao.x, accL[r], false); accL[r] = __builtin_amdgcn_sdot8(d.y, ao.y, accL[r], false);
;                 }
;             }
;     ...
;                 for (int r = 0; r < 4; ++r) STASH[256 * p + 16 * (grp + 4 * r) + pc] = f2bf(asc * (float)(2 * ((accH[r] << 4) + accL[r]) + sa));
	v_add_u32_e32 v143, 8, v139
	v_and_b32_e32 v142, 15, v143
	v_xor_b32_e32 v142, 8, v142
	v_bfe_u32 v144, v143, 4, 4
	v_mul_lo_u32 v142, v142, s92
	v_mul_lo_u32 v144, v144, s92
	v_mov_b32_e32 v143, v142
	v_mov_b32_e32 v145, v144
	ds_write2st64_b64 v159, v[142:143], v[144:145] offset1:2
	v_and_b32_e32 v78, 0xffff, v28
	v_lshrrev_b32_e32 v79, 16, v28
	v_lshl_add_u32 v78, v78, 7, v152
	v_lshl_add_u32 v79, v79, 7, v153
	s_mov_b32 m0, s78
	s_add_i32 s43, s78, 0x400
	global_load_lds_dwordx4 v78, s[50:51]
	s_mov_b32 m0, s43
	s_nop 0
	global_load_lds_dwordx4 v79, s[50:51]
	s_waitcnt vmcnt(8)
	v_add_u32_e32 v54, s98, v59
	v_add_u32_e32 v55, s98, v60
	v_add_u32_e32 v56, s98, v61
	v_add_u32_e32 v57, s98, v62
	ds_read_b64_tr_b4 v[46:47], v160 offset:768
	ds_read_b64_tr_b4 v[48:49], v160 offset:1792
	ds_read_b64_tr_b4 v[122:123], v54
	ds_read_b64_tr_b4 v[124:125], v55
	ds_read_b64_tr_b4 v[126:127], v56
	ds_read_b64_tr_b4 v[128:129], v57
	s_waitcnt lgkmcnt(7)
	v_dot8c_i32_i4_e32 v38, v130, v52
	v_dot8c_i32_i4_e32 v39, v130, v50
	v_dot8c_i32_i4_e32 v40, v132, v52
	v_dot8c_i32_i4_e32 v41, v132, v50
	v_dot8c_i32_i4_e32 v42, v134, v52
	v_dot8c_i32_i4_e32 v43, v134, v50
	v_dot8c_i32_i4_e32 v44, v136, v52
	v_dot8c_i32_i4_e32 v45, v136, v50
	v_dot8c_i32_i4_e32 v38, v131, v53
	v_dot8c_i32_i4_e32 v39, v131, v51
	v_dot8c_i32_i4_e32 v40, v133, v53
	v_dot8c_i32_i4_e32 v41, v133, v51
	v_dot8c_i32_i4_e32 v42, v135, v53
	v_dot8c_i32_i4_e32 v43, v135, v51
	v_dot8c_i32_i4_e32 v44, v137, v53
	v_dot8c_i32_i4_e32 v45, v137, v51
	v_and_b32_e32 v78, 0xffff, v29
	v_lshrrev_b32_e32 v79, 16, v29
	v_lshl_add_u32 v78, v78, 7, v152
	v_lshl_add_u32 v79, v79, 7, v153
	s_mov_b32 m0, s79
	s_add_i32 s43, s79, 0x400
	global_load_lds_dwordx4 v78, s[50:51]
	s_mov_b32 m0, s43
	s_nop 0
	global_load_lds_dwordx4 v79, s[50:51]
	s_waitcnt vmcnt(8)
	v_add_u32_e32 v54, s99, v59
	v_add_u32_e32 v55, s99, v60
	v_add_u32_e32 v56, s99, v61
	v_add_u32_e32 v57, s99, v62
	ds_read_b64_tr_b4 v[50:51], v160 offset:896
	ds_read_b64_tr_b4 v[52:53], v160 offset:1920
	ds_read_b64_tr_b4 v[130:131], v54
	ds_read_b64_tr_b4 v[132:133], v55
	ds_read_b64_tr_b4 v[134:135], v56
	ds_read_b64_tr_b4 v[136:137], v57
	s_waitcnt lgkmcnt(6)
	v_dot8c_i32_i4_e32 v38, v122, v48
	v_dot8c_i32_i4_e32 v39, v122, v46
	v_dot8c_i32_i4_e32 v40, v124, v48
	v_dot8c_i32_i4_e32 v41, v124, v46
	v_dot8c_i32_i4_e32 v42, v126, v48
	v_dot8c_i32_i4_e32 v43, v126, v46
	v_dot8c_i32_i4_e32 v44, v128, v48
	v_dot8c_i32_i4_e32 v45, v128, v46
	v_dot8c_i32_i4_e32 v38, v123, v49
	v_dot8c_i32_i4_e32 v39, v123, v47
	v_dot8c_i32_i4_e32 v40, v125, v49
	v_dot8c_i32_i4_e32 v41, v125, v47
	v_dot8c_i32_i4_e32 v42, v127, v49
	v_dot8c_i32_i4_e32 v43, v127, v47
	v_dot8c_i32_i4_e32 v44, v129, v49
	v_dot8c_i32_i4_e32 v45, v129, v47
	v_and_b32_e32 v78, 0xffff, v30
	v_lshrrev_b32_e32 v79, 16, v30
	v_lshl_add_u32 v78, v78, 7, v152
	v_lshl_add_u32 v79, v79, 7, v153
	s_mov_b32 m0, s98
	s_add_i32 s43, s98, 0x400
	global_load_lds_dwordx4 v78, s[50:51]
	s_mov_b32 m0, s43
	s_nop 0
	global_load_lds_dwordx4 v79, s[50:51]
	s_waitcnt vmcnt(8)
	v_add_u32_e32 v54, s76, v59
	v_add_u32_e32 v55, s76, v60
	v_add_u32_e32 v56, s76, v61
	v_add_u32_e32 v57, s76, v62
	ds_read_b64_tr_b4 v[46:47], v160
	ds_read_b64_tr_b4 v[48:49], v160 offset:1024
	ds_read_b64_tr_b4 v[122:123], v54
	ds_read_b64_tr_b4 v[124:125], v55
	ds_read_b64_tr_b4 v[126:127], v56
	ds_read_b64_tr_b4 v[128:129], v57
	s_waitcnt lgkmcnt(6)
	v_dot8c_i32_i4_e32 v38, v130, v52
	v_dot8c_i32_i4_e32 v39, v130, v50
	v_dot8c_i32_i4_e32 v40, v132, v52
	v_dot8c_i32_i4_e32 v41, v132, v50
	v_dot8c_i32_i4_e32 v42, v134, v52
	v_dot8c_i32_i4_e32 v43, v134, v50
	v_dot8c_i32_i4_e32 v44, v136, v52
	v_dot8c_i32_i4_e32 v45, v136, v50
	v_dot8c_i32_i4_e32 v38, v131, v53
	v_dot8c_i32_i4_e32 v39, v131, v51
	v_dot8c_i32_i4_e32 v40, v133, v53
	v_dot8c_i32_i4_e32 v41, v133, v51
	v_dot8c_i32_i4_e32 v42, v135, v53
	v_dot8c_i32_i4_e32 v43, v135, v51
	v_dot8c_i32_i4_e32 v44, v137, v53
	v_dot8c_i32_i4_e32 v45, v137, v51
	s_nop 3
	s_waitcnt lgkmcnt(15)
	v_lshlrev_b32_e32 v38, 5, v38
	v_lshlrev_b32_e32 v39, 1, v39
	v_add3_u32 v38, v39, v229, v38
	v_cvt_f32_i32_e32 v38, v38
	v_mul_f32_e32 v38, v228, v38
	v_lshlrev_b32_e32 v40, 5, v40
	v_lshlrev_b32_e32 v41, 1, v41
	v_add3_u32 v40, v41, v229, v40
	v_cvt_f32_i32_e32 v40, v40
	v_mul_f32_e32 v40, v228, v40
	v_lshlrev_b32_e32 v42, 5, v42
	v_lshlrev_b32_e32 v43, 1, v43
	v_add3_u32 v42, v43, v229, v42
	v_cvt_f32_i32_e32 v42, v42
	v_mul_f32_e32 v42, v228, v42
	v_lshlrev_b32_e32 v44, 5, v44
	v_lshlrev_b32_e32 v45, 1, v45
	v_add3_u32 v44, v45, v229, v44
	v_cvt_f32_i32_e32 v44, v44
	v_mul_f32_e32 v44, v228, v44
	v_cvt_pk_bf16_f32 v184, v38, v40
	v_cvt_pk_bf16_f32 v185, v42, v44
	ds_read_b128 v[252:255], v156
	s_add_i32 s44, s40, 8
	s_ashr_i32 s45, s44, 31
	s_lshl_b64 s[44:45], s[44:45], 12
	v_lshl_add_u64 v[80:81], v[36:37], 0, s[44:45]
	s_waitcnt lgkmcnt(0)
; #define LAS __attribute__((address_space(3)))
; __device__ __forceinline__ void peer_v_tokens(int j, const LAS unsigned short* EL, const LAS unsigned char* AL  , const LAS float* ASC  , const LAS int* SAL  , ...
;     ...
;         uint2 hv[4]; float4 gv[4];
;         { unsigned ho = (unsigned)t * (D / 4) + (unsigned)lane; asm volatile("" : "+v"(ho)); const uint2* hp = (const uint2*)HB + ho; const float4* gp = (const float4*)fng + lane;
; #pragma unroll
;           for (int jq = 0; jq < 4; ++jq) { hv[jq] = hp[64 * jq]; gv[jq] = gp[64 * jq]; } }
;     ...
;         {
;             float4 v[4]; float ss = 0.f;
; #pragma unroll
;             for (int jq = 0; jq < 4; ++jq) { typedef unsigned u2v __attribute__((ext_vector_type(2))); const u2v pw = *(const LAS u2v*)(STASH + 4 * lane + 256 * jq); const uint2 hw = hv[jq];
;                 v[jq] = make_float4(__uint_as_float(hw.x << 16) + __uint_as_float(pw.x << 16), __uint_as_float(hw.x & 0xffff0000u) + __uint_as_float(pw.x & 0xffff0000u),
;                                     __uint_as_float(hw.y << 16) + __uint_as_float(pw.y << 16), __uint_as_float(hw.y & 0xffff0000u) + __uint_as_float(pw.y & 0xffff0000u));
;                 ss += v[jq].x * v[jq].x + v[jq].y * v[jq].y + v[jq].z * v[jq].z + v[jq].w * v[jq].w; }
;             ss = wave_sum(ss);
;             const float r3 = rsqrtf(ss * (1.f / D) + EPS);
;             float4* op = (float4*)(outp + (size_t)t * D) + lane;
; #pragma unroll
;             for (int jq = 0; jq < 4; ++jq) { typedef float f4v __attribute__((ext_vector_type(4))); f4v o4; o4.x = v[jq].x * r3 * gv[jq].x; o4.y = v[jq].y * r3 * gv[jq].y; o4.z = v[jq].z * r3 * gv[jq].z; o4.w = v[jq].w * r3 * gv[jq].w;
;                 __builtin_nontemporal_store(o4, (f4v*)op + 64 * jq); }
;         }
	v_mul_f32_e32 v244, v244, v252
	v_mul_f32_e32 v245, v245, v253
	v_mul_f32_e32 v246, v246, v254
	v_mul_f32_e32 v247, v247, v255
	global_store_dwordx4 v[80:81], v[244:247], off offset:2048 sc1
	s_add_i32 s43, s40, 16
	s_lshl_b32 s43, s43, 11
	v_add_u32_e32 v138, s43, v66
	global_load_dwordx2 v[194:195], v138, s[70:71]
	global_load_dwordx2 v[196:197], v138, s[70:71] offset:512
	global_load_dwordx2 v[198:199], v138, s[70:71] offset:1024
	global_load_dwordx2 v[200:201], v138, s[70:71] offset:1536
	v_add_u32_e32 v147, 8, v140
	v_and_b32_e32 v146, 15, v147
	v_xor_b32_e32 v146, 8, v146
	v_bfe_u32 v148, v147, 4, 4
	v_mul_lo_u32 v146, v146, s92
	v_mul_lo_u32 v148, v148, s92
	v_mov_b32_e32 v147, v146
	v_mov_b32_e32 v149, v148
	ds_write2st64_b64 v77, v[146:147], v[148:149] offset1:2
	v_add_u32_e32 v138, 0x1000, v74
	ds_read_u8 v139, v138
	v_add_u32_e32 v141, 0x1000, v73
	ds_read_u8 v140, v141
	s_add_i32 s43, s67, 96
	v_mov_b32_e32 v138, s43
	ds_read2st64_b32 v[228:229], v138 offset1:1
	ds_read_b128 v[18:21], v227 offset:8192
	ds_read_b128 v[22:25], v227 offset:8208
	v_mov_b32_e32 v150, v63
	v_mov_b32_e32 v151, v64
	v_mov_b32_e32 v38, 0
	v_mov_b32_e32 v39, 0
	v_mov_b32_e32 v40, 0
	v_mov_b32_e32 v41, 0
	v_mov_b32_e32 v42, 0
	v_mov_b32_e32 v43, 0
	v_mov_b32_e32 v44, 0
	v_mov_b32_e32 v45, 0
	v_and_b32_e32 v78, 0xffff, v31
	v_lshrrev_b32_e32 v79, 16, v31
	v_lshl_add_u32 v78, v78, 7, v152
	v_lshl_add_u32 v79, v79, 7, v153
	s_mov_b32 m0, s99
	s_add_i32 s43, s99, 0x400
	global_load_lds_dwordx4 v78, s[50:51]
	s_mov_b32 m0, s43
	s_nop 0
	global_load_lds_dwordx4 v79, s[50:51]
	s_waitcnt vmcnt(13)
	v_add_u32_e32 v54, s77, v59
	v_add_u32_e32 v55, s77, v60
	v_add_u32_e32 v56, s77, v61
	v_add_u32_e32 v57, s77, v62
	ds_read_b64_tr_b4 v[50:51], v160 offset:128
	ds_read_b64_tr_b4 v[52:53], v160 offset:1152
	ds_read_b64_tr_b4 v[130:131], v54
	ds_read_b64_tr_b4 v[132:133], v55
	ds_read_b64_tr_b4 v[134:135], v56
	ds_read_b64_tr_b4 v[136:137], v57
	s_waitcnt lgkmcnt(13)
	v_dot8c_i32_i4_e32 v38, v122, v48
	v_dot8c_i32_i4_e32 v39, v122, v46
	v_dot8c_i32_i4_e32 v40, v124, v48
	v_dot8c_i32_i4_e32 v41, v124, v46
	v_dot8c_i32_i4_e32 v42, v126, v48
	v_dot8c_i32_i4_e32 v43, v126, v46
	v_dot8c_i32_i4_e32 v44, v128, v48
	v_dot8c_i32_i4_e32 v45, v128, v46
	v_dot8c_i32_i4_e32 v38, v123, v49
	v_dot8c_i32_i4_e32 v39, v123, v47
	v_dot8c_i32_i4_e32 v40, v125, v49
	v_dot8c_i32_i4_e32 v41, v125, v47
	v_dot8c_i32_i4_e32 v42, v127, v49
	v_dot8c_i32_i4_e32 v43, v127, v47
	v_dot8c_i32_i4_e32 v44, v129, v49
	v_dot8c_i32_i4_e32 v45, v129, v47
	v_and_b32_e32 v78, 0xffff, v32
	v_lshrrev_b32_e32 v79, 16, v32
	v_lshl_add_u32 v78, v78, 7, v152
	v_lshl_add_u32 v79, v79, 7, v153
	s_mov_b32 m0, s76
	s_add_i32 s43, s76, 0x400
	global_load_lds_dwordx4 v78, s[50:51]
	s_mov_b32 m0, s43
	s_nop 0
	global_load_lds_dwordx4 v79, s[50:51]
	s_waitcnt vmcnt(13)
	v_add_u32_e32 v54, s78, v59
	v_add_u32_e32 v55, s78, v60
	v_add_u32_e32 v56, s78, v61
	v_add_u32_e32 v57, s78, v62
	ds_read_b64_tr_b4 v[46:47], v160 offset:256
	ds_read_b64_tr_b4 v[48:49], v160 offset:1280
	ds_read_b64_tr_b4 v[122:123], v54
	ds_read_b64_tr_b4 v[124:125], v55
	ds_read_b64_tr_b4 v[126:127], v56
	ds_read_b64_tr_b4 v[128:129], v57
	s_waitcnt lgkmcnt(6)
	v_dot8c_i32_i4_e32 v38, v130, v52
	v_dot8c_i32_i4_e32 v39, v130, v50
	v_dot8c_i32_i4_e32 v40, v132, v52
	v_dot8c_i32_i4_e32 v41, v132, v50
	v_dot8c_i32_i4_e32 v42, v134, v52
	v_dot8c_i32_i4_e32 v43, v134, v50
	v_dot8c_i32_i4_e32 v44, v136, v52
	v_dot8c_i32_i4_e32 v45, v136, v50
	v_dot8c_i32_i4_e32 v38, v131, v53
	v_dot8c_i32_i4_e32 v39, v131, v51
	v_dot8c_i32_i4_e32 v40, v133, v53
	v_dot8c_i32_i4_e32 v41, v133, v51
	v_dot8c_i32_i4_e32 v42, v135, v53
	v_dot8c_i32_i4_e32 v43, v135, v51
	v_dot8c_i32_i4_e32 v44, v137, v53
	v_dot8c_i32_i4_e32 v45, v137, v51
	v_and_b32_e32 v78, 0xffff, v33
	v_lshrrev_b32_e32 v79, 16, v33
	v_lshl_add_u32 v78, v78, 7, v152
	v_lshl_add_u32 v79, v79, 7, v153
	s_mov_b32 m0, s77
	s_add_i32 s43, s77, 0x400
	global_load_lds_dwordx4 v78, s[50:51]
	s_mov_b32 m0, s43
	s_nop 0
	global_load_lds_dwordx4 v79, s[50:51]
	s_waitcnt vmcnt(13)
	v_add_u32_e32 v54, s79, v59
	v_add_u32_e32 v55, s79, v60
	v_add_u32_e32 v56, s79, v61
	v_add_u32_e32 v57, s79, v62
	ds_read_b64_tr_b4 v[50:51], v160 offset:384
	ds_read_b64_tr_b4 v[52:53], v160 offset:1408
	ds_read_b64_tr_b4 v[130:131], v54
	ds_read_b64_tr_b4 v[132:133], v55
	ds_read_b64_tr_b4 v[134:135], v56
	ds_read_b64_tr_b4 v[136:137], v57
	s_waitcnt lgkmcnt(6)
	v_dot8c_i32_i4_e32 v38, v122, v48
	v_dot8c_i32_i4_e32 v39, v122, v46
	v_dot8c_i32_i4_e32 v40, v124, v48
	v_dot8c_i32_i4_e32 v41, v124, v46
	v_dot8c_i32_i4_e32 v42, v126, v48
	v_dot8c_i32_i4_e32 v43, v126, v46
	v_dot8c_i32_i4_e32 v44, v128, v48
	v_dot8c_i32_i4_e32 v45, v128, v46
	v_dot8c_i32_i4_e32 v38, v123, v49
	v_dot8c_i32_i4_e32 v39, v123, v47
	v_dot8c_i32_i4_e32 v40, v125, v49
	v_dot8c_i32_i4_e32 v41, v125, v47
	v_dot8c_i32_i4_e32 v42, v127, v49
	v_dot8c_i32_i4_e32 v43, v127, v47
	v_dot8c_i32_i4_e32 v44, v129, v49
	v_dot8c_i32_i4_e32 v45, v129, v47
	s_waitcnt lgkmcnt(15)
	v_and_b32_e32 v78, 0xffff, v18
	v_lshrrev_b32_e32 v79, 16, v18
	v_lshl_add_u32 v78, v78, 7, v150
	v_lshl_add_u32 v79, v79, 7, v151
	s_mov_b32 m0, s78
	s_add_i32 s43, s78, 0x400
	global_load_lds_dwordx4 v78, s[50:51]
	s_mov_b32 m0, s43
	s_nop 0
	global_load_lds_dwordx4 v79, s[50:51]
	s_waitcnt vmcnt(13)
	v_add_u32_e32 v54, s98, v59
	v_add_u32_e32 v55, s98, v60
	v_add_u32_e32 v56, s98, v61
	v_add_u32_e32 v57, s98, v62
	ds_read_b64_tr_b4 v[46:47], v160 offset:512
	ds_read_b64_tr_b4 v[48:49], v160 offset:1536
	ds_read_b64_tr_b4 v[122:123], v54
	ds_read_b64_tr_b4 v[124:125], v55
	ds_read_b64_tr_b4 v[126:127], v56
	ds_read_b64_tr_b4 v[128:129], v57
	s_waitcnt lgkmcnt(6)
; #define LAS __attribute__((address_space(3)))
; #define TR4(p_) __builtin_amdgcn_ds_read_tr4_b64_v2i32((LAS v2i*)(p_))
; __device__ __forceinline__ void peer_v_tokens(int j, const LAS unsigned short* EL, const LAS unsigned char* AL  , const LAS float* ASC  , const LAS int* SAL  , ...
;     ...
;         for (int m = 0; m < 2; ++m) {
;             const int idx = lane + 64 * m, tau = idx >> 4, sr = idx & 15, k = 16 * (sr & 7) + 2 * tau + (sr >> 3);
;             const int aq = (int)*(const LAS signed char*)(AL + tl * 128 + k); const int tq = aq + 8;
;             const unsigned lo = (((unsigned)tq & 15u) ^ 8u) * 0x11111111u, hi = ((unsigned)(tq >> 4) & 15u) * 0x11111111u;
;             typedef unsigned u2v __attribute__((ext_vector_type(2)));
;             u2v l2; l2.x = lo; l2.y = lo; u2v h2; h2.x = hi; h2.y = hi;
;             *(LAS u2v*)(ATL + 8 * idx) = l2; *(LAS u2v*)(ATL + 1024 + 8 * idx) = h2;
;         }
;     ...
;         for (int st = 0; st < 16; ++st) {
;             const int p = st >> 2, q = st & 3;
;             if (st < 14) VDMA(st + 2, (st + 2) % 3);
;             if (st < 14) asm volatile("s_waitcnt vmcnt(8)" ::: "memory");
;             else if (st == 14) asm volatile("s_waitcnt vmcnt(4)" ::: "memory");
;             else asm volatile("s_waitcnt vmcnt(0)" ::: "memory");
;             if (q == 0) {
; #pragma unroll
;                 for (int r = 0; r < 4; ++r) { accH[r] = 0; accL[r] = 0; } }
; #pragma unroll
;             for (int tp = 0; tp < 2; ++tp) {
;                 const v2i ao = TR4(ATL + (2 * q + tp) * 128 + 8 * s16), ah = TR4(ATL + 1024 + (2 * q + tp) * 128 + 8 * s16);
; #pragma unroll
;                 for (int r = 0; r < 4; ++r) {
;                     const v2i d = TR4(ldsb + BUF[st % 3] + 2048 * tp + roff[r]);
;                     accH[r] = __builtin_amdgcn_sdot8(d.x, ah.x, accH[r], false); accH[r] = __builtin_amdgcn_sdot8(d.y, ah.y, accH[r], false);
;                     accL[r] = __builtin_amdgcn_sdot8(d.x, ao.x, accL[r], false); accL[r] = __builtin_amdgcn_sdot8(d.y, ao.y, accL[r], false);
;                 }
;             }
	v_dot8c_i32_i4_e32 v38, v130, v52
	v_dot8c_i32_i4_e32 v39, v130, v50
	v_dot8c_i32_i4_e32 v40, v132, v52
	v_dot8c_i32_i4_e32 v41, v132, v50
	v_dot8c_i32_i4_e32 v42, v134, v52
	v_dot8c_i32_i4_e32 v43, v134, v50
	v_dot8c_i32_i4_e32 v44, v136, v52
	v_dot8c_i32_i4_e32 v45, v136, v50
	v_dot8c_i32_i4_e32 v38, v131, v53
	v_dot8c_i32_i4_e32 v39, v131, v51
	v_dot8c_i32_i4_e32 v40, v133, v53
	v_dot8c_i32_i4_e32 v41, v133, v51
	v_dot8c_i32_i4_e32 v42, v135, v53
	v_dot8c_i32_i4_e32 v43, v135, v51
	v_dot8c_i32_i4_e32 v44, v137, v53
	v_dot8c_i32_i4_e32 v45, v137, v51
	v_and_b32_e32 v78, 0xffff, v19
	v_lshrrev_b32_e32 v79, 16, v19
	v_lshl_add_u32 v78, v78, 7, v150
	v_lshl_add_u32 v79, v79, 7, v151
	s_mov_b32 m0, s79
	s_add_i32 s43, s79, 0x400
	global_load_lds_dwordx4 v78, s[50:51]
	s_mov_b32 m0, s43
	s_nop 0
	global_load_lds_dwordx4 v79, s[50:51]
	s_waitcnt vmcnt(8)
	v_add_u32_e32 v54, s99, v59
	v_add_u32_e32 v55, s99, v60
	v_add_u32_e32 v56, s99, v61
	v_add_u32_e32 v57, s99, v62
	ds_read_b64_tr_b4 v[50:51], v160 offset:640
	ds_read_b64_tr_b4 v[52:53], v160 offset:1664
	ds_read_b64_tr_b4 v[130:131], v54
	ds_read_b64_tr_b4 v[132:133], v55
	ds_read_b64_tr_b4 v[134:135], v56
	ds_read_b64_tr_b4 v[136:137], v57
	s_waitcnt lgkmcnt(6)
	v_dot8c_i32_i4_e32 v38, v122, v48
	v_dot8c_i32_i4_e32 v39, v122, v46
	v_dot8c_i32_i4_e32 v40, v124, v48
	v_dot8c_i32_i4_e32 v41, v124, v46
	v_dot8c_i32_i4_e32 v42, v126, v48
	v_dot8c_i32_i4_e32 v43, v126, v46
	v_dot8c_i32_i4_e32 v44, v128, v48
	v_dot8c_i32_i4_e32 v45, v128, v46
	v_dot8c_i32_i4_e32 v38, v123, v49
	v_dot8c_i32_i4_e32 v39, v123, v47
	v_dot8c_i32_i4_e32 v40, v125, v49
	v_dot8c_i32_i4_e32 v41, v125, v47
	v_dot8c_i32_i4_e32 v42, v127, v49
	v_dot8c_i32_i4_e32 v43, v127, v47
	v_dot8c_i32_i4_e32 v44, v129, v49
	v_dot8c_i32_i4_e32 v45, v129, v47
	s_waitcnt lgkmcnt(15)
	v_add_u32_e32 v143, 8, v139
	v_and_b32_e32 v142, 15, v143
	v_xor_b32_e32 v142, 8, v142
	v_bfe_u32 v144, v143, 4, 4
	v_mul_lo_u32 v142, v142, s92
	v_mul_lo_u32 v144, v144, s92
	v_mov_b32_e32 v143, v142
	v_mov_b32_e32 v145, v144
	ds_write2st64_b64 v159, v[142:143], v[144:145] offset1:2
	v_and_b32_e32 v78, 0xffff, v20
	v_lshrrev_b32_e32 v79, 16, v20
	v_lshl_add_u32 v78, v78, 7, v150
	v_lshl_add_u32 v79, v79, 7, v151
	s_mov_b32 m0, s98
	s_add_i32 s43, s98, 0x400
	global_load_lds_dwordx4 v78, s[50:51]
	s_mov_b32 m0, s43
	s_nop 0
	global_load_lds_dwordx4 v79, s[50:51]
	s_waitcnt vmcnt(8)
	v_add_u32_e32 v54, s76, v59
	v_add_u32_e32 v55, s76, v60
	v_add_u32_e32 v56, s76, v61
	v_add_u32_e32 v57, s76, v62
	ds_read_b64_tr_b4 v[46:47], v160 offset:768
	ds_read_b64_tr_b4 v[48:49], v160 offset:1792
	ds_read_b64_tr_b4 v[122:123], v54
	ds_read_b64_tr_b4 v[124:125], v55
	ds_read_b64_tr_b4 v[126:127], v56
	ds_read_b64_tr_b4 v[128:129], v57
	s_waitcnt lgkmcnt(7)
	v_dot8c_i32_i4_e32 v38, v130, v52
	v_dot8c_i32_i4_e32 v39, v130, v50
	v_dot8c_i32_i4_e32 v40, v132, v52
	v_dot8c_i32_i4_e32 v41, v132, v50
	v_dot8c_i32_i4_e32 v42, v134, v52
	v_dot8c_i32_i4_e32 v43, v134, v50
	v_dot8c_i32_i4_e32 v44, v136, v52
	v_dot8c_i32_i4_e32 v45, v136, v50
	v_dot8c_i32_i4_e32 v38, v131, v53
	v_dot8c_i32_i4_e32 v39, v131, v51
	v_dot8c_i32_i4_e32 v40, v133, v53
	v_dot8c_i32_i4_e32 v41, v133, v51
	v_dot8c_i32_i4_e32 v42, v135, v53
	v_dot8c_i32_i4_e32 v43, v135, v51
	v_dot8c_i32_i4_e32 v44, v137, v53
	v_dot8c_i32_i4_e32 v45, v137, v51
	v_and_b32_e32 v78, 0xffff, v21
	v_lshrrev_b32_e32 v79, 16, v21
	v_lshl_add_u32 v78, v78, 7, v150
	v_lshl_add_u32 v79, v79, 7, v151
	s_mov_b32 m0, s99
	s_add_i32 s43, s99, 0x400
	global_load_lds_dwordx4 v78, s[50:51]
	s_mov_b32 m0, s43
	s_nop 0
	global_load_lds_dwordx4 v79, s[50:51]
	s_waitcnt vmcnt(8)
	v_add_u32_e32 v54, s77, v59
	v_add_u32_e32 v55, s77, v60
	v_add_u32_e32 v56, s77, v61
	v_add_u32_e32 v57, s77, v62
	ds_read_b64_tr_b4 v[50:51], v160 offset:896
	ds_read_b64_tr_b4 v[52:53], v160 offset:1920
	ds_read_b64_tr_b4 v[130:131], v54
	ds_read_b64_tr_b4 v[132:133], v55
	ds_read_b64_tr_b4 v[134:135], v56
	ds_read_b64_tr_b4 v[136:137], v57
	s_waitcnt lgkmcnt(6)
	v_dot8c_i32_i4_e32 v38, v122, v48
	v_dot8c_i32_i4_e32 v39, v122, v46
	v_dot8c_i32_i4_e32 v40, v124, v48
	v_dot8c_i32_i4_e32 v41, v124, v46
	v_dot8c_i32_i4_e32 v42, v126, v48
	v_dot8c_i32_i4_e32 v43, v126, v46
	v_dot8c_i32_i4_e32 v44, v128, v48
	v_dot8c_i32_i4_e32 v45, v128, v46
	v_dot8c_i32_i4_e32 v38, v123, v49
	v_dot8c_i32_i4_e32 v39, v123, v47
	v_dot8c_i32_i4_e32 v40, v125, v49
	v_dot8c_i32_i4_e32 v41, v125, v47
	v_dot8c_i32_i4_e32 v42, v127, v49
	v_dot8c_i32_i4_e32 v43, v127, v47
	v_dot8c_i32_i4_e32 v44, v129, v49
	v_dot8c_i32_i4_e32 v45, v129, v47
	v_and_b32_e32 v78, 0xffff, v22
	v_lshrrev_b32_e32 v79, 16, v22
	v_lshl_add_u32 v78, v78, 7, v150
	v_lshl_add_u32 v79, v79, 7, v151
	s_mov_b32 m0, s76
	s_add_i32 s43, s76, 0x400
	global_load_lds_dwordx4 v78, s[50:51]
	s_mov_b32 m0, s43
	s_nop 0
	global_load_lds_dwordx4 v79, s[50:51]
	s_waitcnt vmcnt(8)
	v_add_u32_e32 v54, s78, v59
	v_add_u32_e32 v55, s78, v60
	v_add_u32_e32 v56, s78, v61
	v_add_u32_e32 v57, s78, v62
	ds_read_b64_tr_b4 v[46:47], v160
	ds_read_b64_tr_b4 v[48:49], v160 offset:1024
	ds_read_b64_tr_b4 v[122:123], v54
	ds_read_b64_tr_b4 v[124:125], v55
	ds_read_b64_tr_b4 v[126:127], v56
	ds_read_b64_tr_b4 v[128:129], v57
	s_waitcnt lgkmcnt(6)
	v_dot8c_i32_i4_e32 v38, v130, v52
	v_dot8c_i32_i4_e32 v39, v130, v50
	v_dot8c_i32_i4_e32 v40, v132, v52
	v_dot8c_i32_i4_e32 v41, v132, v50
	v_dot8c_i32_i4_e32 v42, v134, v52
	v_dot8c_i32_i4_e32 v43, v134, v50
	v_dot8c_i32_i4_e32 v44, v136, v52
	v_dot8c_i32_i4_e32 v45, v136, v50
	v_dot8c_i32_i4_e32 v38, v131, v53
	v_dot8c_i32_i4_e32 v39, v131, v51
	v_dot8c_i32_i4_e32 v40, v133, v53
	v_dot8c_i32_i4_e32 v41, v133, v51
	v_dot8c_i32_i4_e32 v42, v135, v53
	v_dot8c_i32_i4_e32 v43, v135, v51
	v_dot8c_i32_i4_e32 v44, v137, v53
	v_dot8c_i32_i4_e32 v45, v137, v51
	s_nop 3
	s_waitcnt lgkmcnt(15)
; #define LAS __attribute__((address_space(3)))
; __device__ __forceinline__ bf16 f2bf(float f) { return (bf16)f2bfu(f); }
; __device__ __forceinline__ void peer_v_tokens(int j, const LAS unsigned short* EL, const LAS unsigned char* AL  , const LAS float* ASC  , const LAS int* SAL  , ...
;     ...
;                 for (int r = 0; r < 4; ++r) STASH[256 * p + 16 * (grp + 4 * r) + pc] = f2bf(asc * (float)(2 * ((accH[r] << 4) + accL[r]) + sa));
;     ...
;         {
;             float4 v[4]; float ss = 0.f;
; #pragma unroll
;             for (int jq = 0; jq < 4; ++jq) { typedef unsigned u2v __attribute__((ext_vector_type(2))); const u2v pw = *(const LAS u2v*)(STASH + 4 * lane + 256 * jq); const uint2 hw = hv[jq];
;                 v[jq] = make_float4(__uint_as_float(hw.x << 16) + __uint_as_float(pw.x << 16), __uint_as_float(hw.x & 0xffff0000u) + __uint_as_float(pw.x & 0xffff0000u),
;                                     __uint_as_float(hw.y << 16) + __uint_as_float(pw.y << 16), __uint_as_float(hw.y & 0xffff0000u) + __uint_as_float(pw.y & 0xffff0000u));
;                 ss += v[jq].x * v[jq].x + v[jq].y * v[jq].y + v[jq].z * v[jq].z + v[jq].w * v[jq].w; }
;             ss = wave_sum(ss);
;             const float r3 = rsqrtf(ss * (1.f / D) + EPS);
;             float4* op = (float4*)(outp + (size_t)t * D) + lane;
; #pragma unroll
;             for (int jq = 0; jq < 4; ++jq) { typedef float f4v __attribute__((ext_vector_type(4))); f4v o4; o4.x = v[jq].x * r3 * gv[jq].x; o4.y = v[jq].y * r3 * gv[jq].y; o4.z = v[jq].z * r3 * gv[jq].z; o4.w = v[jq].w * r3 * gv[jq].w;
;                 __builtin_nontemporal_store(o4, (f4v*)op + 64 * jq); }
;         }
	v_lshlrev_b32_e32 v38, 5, v38
	v_lshlrev_b32_e32 v39, 1, v39
	v_add3_u32 v38, v39, v229, v38
	v_cvt_f32_i32_e32 v38, v38
	v_mul_f32_e32 v38, v228, v38
	v_lshlrev_b32_e32 v40, 5, v40
	v_lshlrev_b32_e32 v41, 1, v41
	v_add3_u32 v40, v41, v229, v40
	v_cvt_f32_i32_e32 v40, v40
	v_mul_f32_e32 v40, v228, v40
	v_lshlrev_b32_e32 v42, 5, v42
	v_lshlrev_b32_e32 v43, 1, v43
	v_add3_u32 v42, v43, v229, v42
	v_cvt_f32_i32_e32 v42, v42
	v_mul_f32_e32 v42, v228, v42
	v_lshlrev_b32_e32 v44, 5, v44
	v_lshlrev_b32_e32 v45, 1, v45
	v_add3_u32 v44, v45, v229, v44
	v_cvt_f32_i32_e32 v44, v44
	v_mul_f32_e32 v44, v228, v44
	v_cvt_pk_bf16_f32 v192, v38, v40
	v_cvt_pk_bf16_f32 v193, v42, v44
	ds_read_b128 v[252:255], v156 offset:1024
	s_add_i32 s44, s40, 8
	s_ashr_i32 s45, s44, 31
	s_lshl_b64 s[44:45], s[44:45], 12
	v_lshl_add_u64 v[80:81], v[36:37], 0, s[44:45]
	s_waitcnt lgkmcnt(0)
	v_mul_f32_e32 v248, v248, v252
	v_mul_f32_e32 v249, v249, v253
	v_mul_f32_e32 v250, v250, v254
	v_mul_f32_e32 v251, v251, v255
	global_store_dwordx4 v[80:81], v[248:251], off offset:3072 sc1
	v_add_u32_e32 v147, 8, v140
	v_and_b32_e32 v146, 15, v147
	v_xor_b32_e32 v146, 8, v146
	v_bfe_u32 v148, v147, 4, 4
	v_mul_lo_u32 v146, v146, s92
	v_mul_lo_u32 v148, v148, s92
	v_mov_b32_e32 v147, v146
	v_mov_b32_e32 v149, v148
	ds_write2st64_b64 v77, v[146:147], v[148:149] offset1:2
	v_add_u32_e32 v138, 0x1400, v74
	ds_read_u8 v139, v138
	v_add_u32_e32 v141, 0x1400, v73
	ds_read_u8 v140, v141
	s_add_i32 s43, s67, 128
	v_mov_b32_e32 v138, s43
	ds_read2st64_b32 v[228:229], v138 offset1:1
	ds_read_b128 v[26:29], v227 offset:10240
	ds_read_b128 v[30:33], v227 offset:10256
	v_mov_b32_e32 v38, 0
	v_mov_b32_e32 v39, 0
	v_mov_b32_e32 v40, 0
	v_mov_b32_e32 v41, 0
	v_mov_b32_e32 v42, 0
	v_mov_b32_e32 v43, 0
	v_mov_b32_e32 v44, 0
	v_mov_b32_e32 v45, 0
	v_and_b32_e32 v78, 0xffff, v23
	v_lshrrev_b32_e32 v79, 16, v23
	v_lshl_add_u32 v78, v78, 7, v150
	v_lshl_add_u32 v79, v79, 7, v151
	s_mov_b32 m0, s77
	s_add_i32 s43, s77, 0x400
	global_load_lds_dwordx4 v78, s[50:51]
	s_mov_b32 m0, s43
	s_nop 0
	global_load_lds_dwordx4 v79, s[50:51]
	s_waitcnt vmcnt(9)
	v_add_u32_e32 v54, s79, v59
	v_add_u32_e32 v55, s79, v60
	v_add_u32_e32 v56, s79, v61
	v_add_u32_e32 v57, s79, v62
	ds_read_b64_tr_b4 v[50:51], v160 offset:128
	ds_read_b64_tr_b4 v[52:53], v160 offset:1152
	ds_read_b64_tr_b4 v[130:131], v54
	ds_read_b64_tr_b4 v[132:133], v55
	ds_read_b64_tr_b4 v[134:135], v56
	ds_read_b64_tr_b4 v[136:137], v57
	s_waitcnt lgkmcnt(13)
	v_dot8c_i32_i4_e32 v38, v122, v48
	v_dot8c_i32_i4_e32 v39, v122, v46
	v_dot8c_i32_i4_e32 v40, v124, v48
	v_dot8c_i32_i4_e32 v41, v124, v46
	v_dot8c_i32_i4_e32 v42, v126, v48
	v_dot8c_i32_i4_e32 v43, v126, v46
	v_dot8c_i32_i4_e32 v44, v128, v48
	v_dot8c_i32_i4_e32 v45, v128, v46
	v_dot8c_i32_i4_e32 v38, v123, v49
	v_dot8c_i32_i4_e32 v39, v123, v47
	v_dot8c_i32_i4_e32 v40, v125, v49
	v_dot8c_i32_i4_e32 v41, v125, v47
	v_dot8c_i32_i4_e32 v42, v127, v49
	v_dot8c_i32_i4_e32 v43, v127, v47
	v_dot8c_i32_i4_e32 v44, v129, v49
	v_dot8c_i32_i4_e32 v45, v129, v47
	v_and_b32_e32 v78, 0xffff, v24
	v_lshrrev_b32_e32 v79, 16, v24
	v_lshl_add_u32 v78, v78, 7, v150
	v_lshl_add_u32 v79, v79, 7, v151
	s_mov_b32 m0, s78
	s_add_i32 s43, s78, 0x400
	global_load_lds_dwordx4 v78, s[50:51]
	s_mov_b32 m0, s43
	s_nop 0
	global_load_lds_dwordx4 v79, s[50:51]
	s_waitcnt vmcnt(9)
	v_add_u32_e32 v54, s98, v59
	v_add_u32_e32 v55, s98, v60
	v_add_u32_e32 v56, s98, v61
	v_add_u32_e32 v57, s98, v62
	ds_read_b64_tr_b4 v[46:47], v160 offset:256
	ds_read_b64_tr_b4 v[48:49], v160 offset:1280
	ds_read_b64_tr_b4 v[122:123], v54
	ds_read_b64_tr_b4 v[124:125], v55
	ds_read_b64_tr_b4 v[126:127], v56
	ds_read_b64_tr_b4 v[128:129], v57
	s_waitcnt lgkmcnt(6)
	v_dot8c_i32_i4_e32 v38, v130, v52
	v_dot8c_i32_i4_e32 v39, v130, v50
	v_dot8c_i32_i4_e32 v40, v132, v52
	v_dot8c_i32_i4_e32 v41, v132, v50
	v_dot8c_i32_i4_e32 v42, v134, v52
	v_dot8c_i32_i4_e32 v43, v134, v50
	v_dot8c_i32_i4_e32 v44, v136, v52
	v_dot8c_i32_i4_e32 v45, v136, v50
	v_dot8c_i32_i4_e32 v38, v131, v53
	v_dot8c_i32_i4_e32 v39, v131, v51
	v_dot8c_i32_i4_e32 v40, v133, v53
	v_dot8c_i32_i4_e32 v41, v133, v51
	v_dot8c_i32_i4_e32 v42, v135, v53
	v_dot8c_i32_i4_e32 v43, v135, v51
	v_dot8c_i32_i4_e32 v44, v137, v53
	v_dot8c_i32_i4_e32 v45, v137, v51
	ds_write_b16 v65, v178
	ds_write_b16_d16_hi v65, v178 offset:128
	ds_write_b16 v65, v179 offset:256
	ds_write_b16_d16_hi v65, v179 offset:384
	ds_write_b16 v65, v180 offset:512
	ds_write_b16_d16_hi v65, v180 offset:640
	ds_write_b16 v65, v181 offset:768
	ds_write_b16_d16_hi v65, v181 offset:896
	ds_write_b16 v65, v182 offset:1024
	ds_write_b16_d16_hi v65, v182 offset:1152
	ds_write_b16 v65, v183 offset:1280
	ds_write_b16_d16_hi v65, v183 offset:1408
	ds_write_b16 v65, v184 offset:1536
	ds_write_b16_d16_hi v65, v184 offset:1664
	ds_write_b16 v65, v185 offset:1792
	ds_write_b16_d16_hi v65, v185 offset:1920
	ds_read_b64 v[202:203], v154
	ds_read_b64 v[204:205], v154 offset:512
	ds_read_b64 v[206:207], v154 offset:1024
	ds_read_b64 v[208:209], v154 offset:1536
	v_and_b32_e32 v78, 0xffff, v25
	v_lshrrev_b32_e32 v79, 16, v25
	v_lshl_add_u32 v78, v78, 7, v150
	v_lshl_add_u32 v79, v79, 7, v151
	s_mov_b32 m0, s79
	s_add_i32 s43, s79, 0x400
	global_load_lds_dwordx4 v78, s[50:51]
	s_mov_b32 m0, s43
	s_nop 0
	global_load_lds_dwordx4 v79, s[50:51]
	s_waitcnt vmcnt(9)
	v_add_u32_e32 v54, s99, v59
	v_add_u32_e32 v55, s99, v60
	v_add_u32_e32 v56, s99, v61
	v_add_u32_e32 v57, s99, v62
	ds_read_b64_tr_b4 v[50:51], v160 offset:384
	ds_read_b64_tr_b4 v[52:53], v160 offset:1408
	ds_read_b64_tr_b4 v[130:131], v54
	ds_read_b64_tr_b4 v[132:133], v55
	ds_read_b64_tr_b4 v[134:135], v56
	ds_read_b64_tr_b4 v[136:137], v57
	s_waitcnt lgkmcnt(15)
; #define LAS __attribute__((address_space(3)))
; #define TR4(p_) __builtin_amdgcn_ds_read_tr4_b64_v2i32((LAS v2i*)(p_))
; __device__ __forceinline__ void peer_v_tokens(int j, const LAS unsigned short* EL, const LAS unsigned char* AL  , const LAS float* ASC  , const LAS int* SAL  , ...
;     ...
;         for (int m = 0; m < 2; ++m) {
;             const int idx = lane + 64 * m, tau = idx >> 4, sr = idx & 15, k = 16 * (sr & 7) + 2 * tau + (sr >> 3);
;             const int aq = (int)*(const LAS signed char*)(AL + tl * 128 + k); const int tq = aq + 8;
;             const unsigned lo = (((unsigned)tq & 15u) ^ 8u) * 0x11111111u, hi = ((unsigned)(tq >> 4) & 15u) * 0x11111111u;
;             typedef unsigned u2v __attribute__((ext_vector_type(2)));
;             u2v l2; l2.x = lo; l2.y = lo; u2v h2; h2.x = hi; h2.y = hi;
;             *(LAS u2v*)(ATL + 8 * idx) = l2; *(LAS u2v*)(ATL + 1024 + 8 * idx) = h2;
;         }
;     ...
;         for (int st = 0; st < 16; ++st) {
;             const int p = st >> 2, q = st & 3;
;             if (st < 14) VDMA(st + 2, (st + 2) % 3);
;             if (st < 14) asm volatile("s_waitcnt vmcnt(8)" ::: "memory");
;             else if (st == 14) asm volatile("s_waitcnt vmcnt(4)" ::: "memory");
;             else asm volatile("s_waitcnt vmcnt(0)" ::: "memory");
;             if (q == 0) {
; #pragma unroll
;                 for (int r = 0; r < 4; ++r) { accH[r] = 0; accL[r] = 0; } }
; #pragma unroll
;             for (int tp = 0; tp < 2; ++tp) {
;                 const v2i ao = TR4(ATL + (2 * q + tp) * 128 + 8 * s16), ah = TR4(ATL + 1024 + (2 * q + tp) * 128 + 8 * s16);
; #pragma unroll
;                 for (int r = 0; r < 4; ++r) {
;                     const v2i d = TR4(ldsb + BUF[st % 3] + 2048 * tp + roff[r]);
;                     accH[r] = __builtin_amdgcn_sdot8(d.x, ah.x, accH[r], false); accH[r] = __builtin_amdgcn_sdot8(d.y, ah.y, accH[r], false);
;                     accL[r] = __builtin_amdgcn_sdot8(d.x, ao.x, accL[r], false); accL[r] = __builtin_amdgcn_sdot8(d.y, ao.y, accL[r], false);
;                 }
;             }
	v_dot8c_i32_i4_e32 v38, v122, v48
	v_dot8c_i32_i4_e32 v39, v122, v46
	v_dot8c_i32_i4_e32 v40, v124, v48
	v_dot8c_i32_i4_e32 v41, v124, v46
	v_dot8c_i32_i4_e32 v42, v126, v48
	v_dot8c_i32_i4_e32 v43, v126, v46
	v_dot8c_i32_i4_e32 v44, v128, v48
	v_dot8c_i32_i4_e32 v45, v128, v46
	v_dot8c_i32_i4_e32 v38, v123, v49
	v_dot8c_i32_i4_e32 v39, v123, v47
	v_dot8c_i32_i4_e32 v40, v125, v49
	v_dot8c_i32_i4_e32 v41, v125, v47
	v_dot8c_i32_i4_e32 v42, v127, v49
	v_dot8c_i32_i4_e32 v43, v127, v47
	v_dot8c_i32_i4_e32 v44, v129, v49
	v_dot8c_i32_i4_e32 v45, v129, v47
	s_waitcnt lgkmcnt(15)
	v_and_b32_e32 v78, 0xffff, v26
	v_lshrrev_b32_e32 v79, 16, v26
	v_lshl_add_u32 v78, v78, 7, v150
	v_lshl_add_u32 v79, v79, 7, v151
	s_mov_b32 m0, s98
	s_add_i32 s43, s98, 0x400
	global_load_lds_dwordx4 v78, s[50:51]
	s_mov_b32 m0, s43
	s_nop 0
	global_load_lds_dwordx4 v79, s[50:51]
	s_waitcnt vmcnt(9)
	v_add_u32_e32 v54, s76, v59
	v_add_u32_e32 v55, s76, v60
	v_add_u32_e32 v56, s76, v61
	v_add_u32_e32 v57, s76, v62
	ds_read_b64_tr_b4 v[46:47], v160 offset:512
	ds_read_b64_tr_b4 v[48:49], v160 offset:1536
	ds_read_b64_tr_b4 v[122:123], v54
	ds_read_b64_tr_b4 v[124:125], v55
	ds_read_b64_tr_b4 v[126:127], v56
	ds_read_b64_tr_b4 v[128:129], v57
	s_waitcnt lgkmcnt(6)
	v_dot8c_i32_i4_e32 v38, v130, v52
	v_dot8c_i32_i4_e32 v39, v130, v50
	v_dot8c_i32_i4_e32 v40, v132, v52
	v_dot8c_i32_i4_e32 v41, v132, v50
	v_dot8c_i32_i4_e32 v42, v134, v52
	v_dot8c_i32_i4_e32 v43, v134, v50
	v_dot8c_i32_i4_e32 v44, v136, v52
	v_dot8c_i32_i4_e32 v45, v136, v50
	v_dot8c_i32_i4_e32 v38, v131, v53
	v_dot8c_i32_i4_e32 v39, v131, v51
	v_dot8c_i32_i4_e32 v40, v133, v53
	v_dot8c_i32_i4_e32 v41, v133, v51
	v_dot8c_i32_i4_e32 v42, v135, v53
	v_dot8c_i32_i4_e32 v43, v135, v51
	v_dot8c_i32_i4_e32 v44, v137, v53
	v_dot8c_i32_i4_e32 v45, v137, v51
	v_and_b32_e32 v78, 0xffff, v27
	v_lshrrev_b32_e32 v79, 16, v27
	v_lshl_add_u32 v78, v78, 7, v150
	v_lshl_add_u32 v79, v79, 7, v151
	s_mov_b32 m0, s99
	s_add_i32 s43, s99, 0x400
	global_load_lds_dwordx4 v78, s[50:51]
	s_mov_b32 m0, s43
	s_nop 0
	global_load_lds_dwordx4 v79, s[50:51]
	s_waitcnt vmcnt(8)
	v_add_u32_e32 v54, s77, v59
	v_add_u32_e32 v55, s77, v60
	v_add_u32_e32 v56, s77, v61
	v_add_u32_e32 v57, s77, v62
	ds_read_b64_tr_b4 v[50:51], v160 offset:640
	ds_read_b64_tr_b4 v[52:53], v160 offset:1664
	ds_read_b64_tr_b4 v[130:131], v54
	ds_read_b64_tr_b4 v[132:133], v55
	ds_read_b64_tr_b4 v[134:135], v56
	ds_read_b64_tr_b4 v[136:137], v57
	s_waitcnt lgkmcnt(6)
	v_dot8c_i32_i4_e32 v38, v122, v48
	v_dot8c_i32_i4_e32 v39, v122, v46
	v_dot8c_i32_i4_e32 v40, v124, v48
	v_dot8c_i32_i4_e32 v41, v124, v46
	v_dot8c_i32_i4_e32 v42, v126, v48
	v_dot8c_i32_i4_e32 v43, v126, v46
	v_dot8c_i32_i4_e32 v44, v128, v48
	v_dot8c_i32_i4_e32 v45, v128, v46
	v_dot8c_i32_i4_e32 v38, v123, v49
	v_dot8c_i32_i4_e32 v39, v123, v47
	v_dot8c_i32_i4_e32 v40, v125, v49
	v_dot8c_i32_i4_e32 v41, v125, v47
	v_dot8c_i32_i4_e32 v42, v127, v49
	v_dot8c_i32_i4_e32 v43, v127, v47
	v_dot8c_i32_i4_e32 v44, v129, v49
	v_dot8c_i32_i4_e32 v45, v129, v47
	s_waitcnt lgkmcnt(15)
	v_add_u32_e32 v143, 8, v139
	v_and_b32_e32 v142, 15, v143
	v_xor_b32_e32 v142, 8, v142
	v_bfe_u32 v144, v143, 4, 4
	v_mul_lo_u32 v142, v142, s92
	v_mul_lo_u32 v144, v144, s92
	v_mov_b32_e32 v143, v142
	v_mov_b32_e32 v145, v144
	ds_write2st64_b64 v159, v[142:143], v[144:145] offset1:2
	v_and_b32_e32 v78, 0xffff, v28
	v_lshrrev_b32_e32 v79, 16, v28
	v_lshl_add_u32 v78, v78, 7, v150
	v_lshl_add_u32 v79, v79, 7, v151
	s_mov_b32 m0, s76
	s_add_i32 s43, s76, 0x400
	global_load_lds_dwordx4 v78, s[50:51]
	s_mov_b32 m0, s43
	s_nop 0
	global_load_lds_dwordx4 v79, s[50:51]
	s_waitcnt vmcnt(8)
	v_add_u32_e32 v54, s78, v59
	v_add_u32_e32 v55, s78, v60
	v_add_u32_e32 v56, s78, v61
	v_add_u32_e32 v57, s78, v62
	ds_read_b64_tr_b4 v[46:47], v160 offset:768
	ds_read_b64_tr_b4 v[48:49], v160 offset:1792
	ds_read_b64_tr_b4 v[122:123], v54
	ds_read_b64_tr_b4 v[124:125], v55
	ds_read_b64_tr_b4 v[126:127], v56
	ds_read_b64_tr_b4 v[128:129], v57
	s_waitcnt lgkmcnt(7)
	v_dot8c_i32_i4_e32 v38, v130, v52
	v_dot8c_i32_i4_e32 v39, v130, v50
	v_dot8c_i32_i4_e32 v40, v132, v52
	v_dot8c_i32_i4_e32 v41, v132, v50
	v_dot8c_i32_i4_e32 v42, v134, v52
	v_dot8c_i32_i4_e32 v43, v134, v50
	v_dot8c_i32_i4_e32 v44, v136, v52
	v_dot8c_i32_i4_e32 v45, v136, v50
	v_dot8c_i32_i4_e32 v38, v131, v53
	v_dot8c_i32_i4_e32 v39, v131, v51
	v_dot8c_i32_i4_e32 v40, v133, v53
	v_dot8c_i32_i4_e32 v41, v133, v51
	v_dot8c_i32_i4_e32 v42, v135, v53
	v_dot8c_i32_i4_e32 v43, v135, v51
	v_dot8c_i32_i4_e32 v44, v137, v53
	v_dot8c_i32_i4_e32 v45, v137, v51
	v_and_b32_e32 v78, 0xffff, v29
	v_lshrrev_b32_e32 v79, 16, v29
	v_lshl_add_u32 v78, v78, 7, v150
	v_lshl_add_u32 v79, v79, 7, v151
	s_mov_b32 m0, s77
	s_add_i32 s43, s77, 0x400
	global_load_lds_dwordx4 v78, s[50:51]
	s_mov_b32 m0, s43
	s_nop 0
	global_load_lds_dwordx4 v79, s[50:51]
	s_waitcnt vmcnt(8)
	v_add_u32_e32 v54, s79, v59
	v_add_u32_e32 v55, s79, v60
	v_add_u32_e32 v56, s79, v61
	v_add_u32_e32 v57, s79, v62
	ds_read_b64_tr_b4 v[50:51], v160 offset:896
	ds_read_b64_tr_b4 v[52:53], v160 offset:1920
	ds_read_b64_tr_b4 v[130:131], v54
	ds_read_b64_tr_b4 v[132:133], v55
	ds_read_b64_tr_b4 v[134:135], v56
	ds_read_b64_tr_b4 v[136:137], v57
	s_waitcnt lgkmcnt(6)
; #define LAS __attribute__((address_space(3)))
; __device__ __forceinline__ bf16 f2bf(float f) { return (bf16)f2bfu(f); }
; __device__ __forceinline__ void peer_v_tokens(int j, const LAS unsigned short* EL, const LAS unsigned char* AL  , const LAS float* ASC  , const LAS int* SAL  , ...
;     ...
;         for (int m = 0; m < 2; ++m) {
;             const int idx = lane + 64 * m, tau = idx >> 4, sr = idx & 15, k = 16 * (sr & 7) + 2 * tau + (sr >> 3);
;             const int aq = (int)*(const LAS signed char*)(AL + tl * 128 + k); const int tq = aq + 8;
;             const unsigned lo = (((unsigned)tq & 15u) ^ 8u) * 0x11111111u, hi = ((unsigned)(tq >> 4) & 15u) * 0x11111111u;
;             typedef unsigned u2v __attribute__((ext_vector_type(2)));
;             u2v l2; l2.x = lo; l2.y = lo; u2v h2; h2.x = hi; h2.y = hi;
;             *(LAS u2v*)(ATL + 8 * idx) = l2; *(LAS u2v*)(ATL + 1024 + 8 * idx) = h2;
;         }
;     ...
;                 for (int r = 0; r < 4; ++r) STASH[256 * p + 16 * (grp + 4 * r) + pc] = f2bf(asc * (float)(2 * ((accH[r] << 4) + accL[r]) + sa));
;     ...
;         {
;             float4 v[4]; float ss = 0.f;
; #pragma unroll
;             for (int jq = 0; jq < 4; ++jq) { typedef unsigned u2v __attribute__((ext_vector_type(2))); const u2v pw = *(const LAS u2v*)(STASH + 4 * lane + 256 * jq); const uint2 hw = hv[jq];
;                 v[jq] = make_float4(__uint_as_float(hw.x << 16) + __uint_as_float(pw.x << 16), __uint_as_float(hw.x & 0xffff0000u) + __uint_as_float(pw.x & 0xffff0000u),
;                                     __uint_as_float(hw.y << 16) + __uint_as_float(pw.y << 16), __uint_as_float(hw.y & 0xffff0000u) + __uint_as_float(pw.y & 0xffff0000u));
;                 ss += v[jq].x * v[jq].x + v[jq].y * v[jq].y + v[jq].z * v[jq].z + v[jq].w * v[jq].w; }
;             ss = wave_sum(ss);
;             const float r3 = rsqrtf(ss * (1.f / D) + EPS);
	v_dot8c_i32_i4_e32 v38, v122, v48
	v_dot8c_i32_i4_e32 v39, v122, v46
	v_dot8c_i32_i4_e32 v40, v124, v48
	v_dot8c_i32_i4_e32 v41, v124, v46
	v_dot8c_i32_i4_e32 v42, v126, v48
	v_dot8c_i32_i4_e32 v43, v126, v46
	v_dot8c_i32_i4_e32 v44, v128, v48
	v_dot8c_i32_i4_e32 v45, v128, v46
	v_dot8c_i32_i4_e32 v38, v123, v49
	v_dot8c_i32_i4_e32 v39, v123, v47
	v_dot8c_i32_i4_e32 v40, v125, v49
	v_dot8c_i32_i4_e32 v41, v125, v47
	v_dot8c_i32_i4_e32 v42, v127, v49
	v_dot8c_i32_i4_e32 v43, v127, v47
	v_dot8c_i32_i4_e32 v44, v129, v49
	v_dot8c_i32_i4_e32 v45, v129, v47
	v_and_b32_e32 v78, 0xffff, v30
	v_lshrrev_b32_e32 v79, 16, v30
	v_lshl_add_u32 v78, v78, 7, v150
	v_lshl_add_u32 v79, v79, 7, v151
	s_mov_b32 m0, s78
	s_add_i32 s43, s78, 0x400
	global_load_lds_dwordx4 v78, s[50:51]
	s_mov_b32 m0, s43
	s_nop 0
	global_load_lds_dwordx4 v79, s[50:51]
	s_waitcnt vmcnt(8)
	v_add_u32_e32 v54, s98, v59
	v_add_u32_e32 v55, s98, v60
	v_add_u32_e32 v56, s98, v61
	v_add_u32_e32 v57, s98, v62
	ds_read_b64_tr_b4 v[46:47], v160
	ds_read_b64_tr_b4 v[48:49], v160 offset:1024
	ds_read_b64_tr_b4 v[122:123], v54
	ds_read_b64_tr_b4 v[124:125], v55
	ds_read_b64_tr_b4 v[126:127], v56
	ds_read_b64_tr_b4 v[128:129], v57
	s_waitcnt lgkmcnt(6)
	v_dot8c_i32_i4_e32 v38, v130, v52
	v_dot8c_i32_i4_e32 v39, v130, v50
	v_dot8c_i32_i4_e32 v40, v132, v52
	v_dot8c_i32_i4_e32 v41, v132, v50
	v_dot8c_i32_i4_e32 v42, v134, v52
	v_dot8c_i32_i4_e32 v43, v134, v50
	v_dot8c_i32_i4_e32 v44, v136, v52
	v_dot8c_i32_i4_e32 v45, v136, v50
	v_dot8c_i32_i4_e32 v38, v131, v53
	v_dot8c_i32_i4_e32 v39, v131, v51
	v_dot8c_i32_i4_e32 v40, v133, v53
	v_dot8c_i32_i4_e32 v41, v133, v51
	v_dot8c_i32_i4_e32 v42, v135, v53
	v_dot8c_i32_i4_e32 v43, v135, v51
	v_dot8c_i32_i4_e32 v44, v137, v53
	v_dot8c_i32_i4_e32 v45, v137, v51
	s_nop 3
	s_waitcnt lgkmcnt(15)
	v_lshlrev_b32_e32 v38, 5, v38
	v_lshlrev_b32_e32 v39, 1, v39
	v_add3_u32 v38, v39, v229, v38
	v_cvt_f32_i32_e32 v38, v38
	v_mul_f32_e32 v38, v228, v38
	v_lshlrev_b32_e32 v40, 5, v40
	v_lshlrev_b32_e32 v41, 1, v41
	v_add3_u32 v40, v41, v229, v40
	v_cvt_f32_i32_e32 v40, v40
	v_mul_f32_e32 v40, v228, v40
	v_lshlrev_b32_e32 v42, 5, v42
	v_lshlrev_b32_e32 v43, 1, v43
	v_add3_u32 v42, v43, v229, v42
	v_cvt_f32_i32_e32 v42, v42
	v_mul_f32_e32 v42, v228, v42
	v_lshlrev_b32_e32 v44, 5, v44
	v_lshlrev_b32_e32 v45, 1, v45
	v_add3_u32 v44, v45, v229, v44
	v_cvt_f32_i32_e32 v44, v44
	v_mul_f32_e32 v44, v228, v44
	v_cvt_pk_bf16_f32 v162, v38, v40
	v_cvt_pk_bf16_f32 v163, v42, v44
	v_add_u32_e32 v147, 8, v140
	v_and_b32_e32 v146, 15, v147
	v_xor_b32_e32 v146, 8, v146
	v_bfe_u32 v148, v147, 4, 4
	v_mul_lo_u32 v146, v146, s92
	v_mul_lo_u32 v148, v148, s92
	v_mov_b32_e32 v147, v146
	v_mov_b32_e32 v149, v148
	ds_write2st64_b64 v77, v[146:147], v[148:149] offset1:2
	v_add_u32_e32 v138, 0x1000, v74
	ds_read_u8 v139, v138
	v_add_u32_e32 v141, 0x1000, v73
	ds_read_u8 v140, v141
	s_add_i32 s43, s67, 160
	v_mov_b32_e32 v138, s43
	ds_read2st64_b32 v[228:229], v138 offset1:1
	ds_read_b128 v[18:21], v227 offset:8192
	ds_read_b128 v[22:25], v227 offset:8208
	v_add_u32_e32 v152, 0x200000, v63
	v_add_u32_e32 v153, 0x200000, v64
	v_mov_b32_e32 v38, 0
	v_mov_b32_e32 v39, 0
	v_mov_b32_e32 v40, 0
	v_mov_b32_e32 v41, 0
	v_mov_b32_e32 v42, 0
	v_mov_b32_e32 v43, 0
	v_mov_b32_e32 v44, 0
	v_mov_b32_e32 v45, 0
	v_and_b32_e32 v78, 0xffff, v31
	v_lshrrev_b32_e32 v79, 16, v31
	v_lshl_add_u32 v78, v78, 7, v150
	v_lshl_add_u32 v79, v79, 7, v151
	s_mov_b32 m0, s79
	s_add_i32 s43, s79, 0x400
	global_load_lds_dwordx4 v78, s[50:51]
	s_mov_b32 m0, s43
	s_nop 0
	global_load_lds_dwordx4 v79, s[50:51]
	s_waitcnt vmcnt(8)
	v_add_u32_e32 v54, s99, v59
	v_add_u32_e32 v55, s99, v60
	v_add_u32_e32 v56, s99, v61
	v_add_u32_e32 v57, s99, v62
	ds_read_b64_tr_b4 v[50:51], v160 offset:128
	ds_read_b64_tr_b4 v[52:53], v160 offset:1152
	ds_read_b64_tr_b4 v[130:131], v54
	ds_read_b64_tr_b4 v[132:133], v55
	ds_read_b64_tr_b4 v[134:135], v56
	ds_read_b64_tr_b4 v[136:137], v57
	s_waitcnt lgkmcnt(12)
	s_waitcnt vmcnt(35) lgkmcnt(15)
	v_lshlrev_b32_e32 v210, 16, v194
	v_and_b32_e32 v211, 0xffff0000, v194
	v_lshlrev_b32_e32 v142, 16, v202
	v_and_b32_e32 v143, 0xffff0000, v202
	v_add_f32_e32 v210, v210, v142
	v_add_f32_e32 v211, v211, v143
	v_lshlrev_b32_e32 v212, 16, v195
	v_and_b32_e32 v213, 0xffff0000, v195
	v_lshlrev_b32_e32 v142, 16, v203
	v_and_b32_e32 v143, 0xffff0000, v203
	v_add_f32_e32 v212, v212, v142
	v_add_f32_e32 v213, v213, v143
	v_lshlrev_b32_e32 v214, 16, v196
	v_and_b32_e32 v215, 0xffff0000, v196
	v_lshlrev_b32_e32 v142, 16, v204
	v_and_b32_e32 v143, 0xffff0000, v204
	v_add_f32_e32 v214, v214, v142
	v_add_f32_e32 v215, v215, v143
	v_lshlrev_b32_e32 v216, 16, v197
	v_and_b32_e32 v217, 0xffff0000, v197
	v_lshlrev_b32_e32 v142, 16, v205
	v_and_b32_e32 v143, 0xffff0000, v205
	v_add_f32_e32 v216, v216, v142
	v_add_f32_e32 v217, v217, v143
	v_lshlrev_b32_e32 v218, 16, v198
	v_and_b32_e32 v219, 0xffff0000, v198
	v_lshlrev_b32_e32 v142, 16, v206
	v_and_b32_e32 v143, 0xffff0000, v206
	v_add_f32_e32 v218, v218, v142
	v_add_f32_e32 v219, v219, v143
	v_lshlrev_b32_e32 v220, 16, v199
	v_and_b32_e32 v221, 0xffff0000, v199
	v_lshlrev_b32_e32 v142, 16, v207
	v_and_b32_e32 v143, 0xffff0000, v207
	v_add_f32_e32 v220, v220, v142
	v_add_f32_e32 v221, v221, v143
	v_lshlrev_b32_e32 v222, 16, v200
	v_and_b32_e32 v223, 0xffff0000, v200
	v_lshlrev_b32_e32 v142, 16, v208
	v_and_b32_e32 v143, 0xffff0000, v208
	v_add_f32_e32 v222, v222, v142
	v_add_f32_e32 v223, v223, v143
	v_lshlrev_b32_e32 v224, 16, v201
	v_and_b32_e32 v225, 0xffff0000, v201
	v_lshlrev_b32_e32 v142, 16, v209
	v_and_b32_e32 v143, 0xffff0000, v209
	v_add_f32_e32 v224, v224, v142
; #define TR4(p_) __builtin_amdgcn_ds_read_tr4_b64_v2i32((LAS v2i*)(p_))
; #define VDMA(st_, k_) do { _Pragma("unroll") for (int i_ = 0; i_ < 4; ++i_) { \
;         const unsigned off_ = (unsigned)((st_) >> 2) * (16384u * 128u) + (PE_ID(E, 4 * ((st_) & 3) + i_) << 7) + ((i_ & 1) ? cx1 : cx0); \
;         __builtin_amdgcn_global_load_lds((const unsigned*)(V4 + off_), (LAS unsigned*)(ldsb + BUF[k_] + 1024 * i_), 16, 0, 0); } } while (0)
; __device__ __forceinline__ void peer_v_tokens(int j, const LAS unsigned short* EL, const LAS unsigned char* AL  , const LAS float* ASC  , const LAS int* SAL  , ...
;     ...
;         for (int st = 0; st < 16; ++st) {
;             const int p = st >> 2, q = st & 3;
;             if (st < 14) VDMA(st + 2, (st + 2) % 3);
;             if (st < 14) asm volatile("s_waitcnt vmcnt(8)" ::: "memory");
;             else if (st == 14) asm volatile("s_waitcnt vmcnt(4)" ::: "memory");
;             else asm volatile("s_waitcnt vmcnt(0)" ::: "memory");
;             if (q == 0) {
; #pragma unroll
;                 for (int r = 0; r < 4; ++r) { accH[r] = 0; accL[r] = 0; } }
; #pragma unroll
;             for (int tp = 0; tp < 2; ++tp) {
;                 const v2i ao = TR4(ATL + (2 * q + tp) * 128 + 8 * s16), ah = TR4(ATL + 1024 + (2 * q + tp) * 128 + 8 * s16);
; #pragma unroll
;                 for (int r = 0; r < 4; ++r) {
;                     const v2i d = TR4(ldsb + BUF[st % 3] + 2048 * tp + roff[r]);
;                     accH[r] = __builtin_amdgcn_sdot8(d.x, ah.x, accH[r], false); accH[r] = __builtin_amdgcn_sdot8(d.y, ah.y, accH[r], false);
;                     accL[r] = __builtin_amdgcn_sdot8(d.x, ao.x, accL[r], false); accL[r] = __builtin_amdgcn_sdot8(d.y, ao.y, accL[r], false);
;                 }
;             }
;     ...
;                 ss += v[jq].x * v[jq].x + v[jq].y * v[jq].y + v[jq].z * v[jq].z + v[jq].w * v[jq].w; }
;             ss = wave_sum(ss);
;             const float r3 = rsqrtf(ss * (1.f / D) + EPS);
;             float4* op = (float4*)(outp + (size_t)t * D) + lane;
; #pragma unroll
;             for (int jq = 0; jq < 4; ++jq) { typedef float f4v __attribute__((ext_vector_type(4))); f4v o4; o4.x = v[jq].x * r3 * gv[jq].x; o4.y = v[jq].y * r3 * gv[jq].y; o4.z = v[jq].z * r3 * gv[jq].z; o4.w = v[jq].w * r3 * gv[jq].w;
	v_add_f32_e32 v225, v225, v143
	v_mov_b32_e32 v144, 0
	v_mul_f32_e32 v145, v210, v210
	v_fmac_f32_e32 v145, v211, v211
	v_fmac_f32_e32 v145, v212, v212
	v_fmac_f32_e32 v145, v213, v213
	v_add_f32_e32 v144, v144, v145
	v_mul_f32_e32 v145, v214, v214
	v_fmac_f32_e32 v145, v215, v215
	v_fmac_f32_e32 v145, v216, v216
	v_fmac_f32_e32 v145, v217, v217
	v_add_f32_e32 v144, v144, v145
	v_mul_f32_e32 v145, v218, v218
	v_fmac_f32_e32 v145, v219, v219
	v_fmac_f32_e32 v145, v220, v220
	v_fmac_f32_e32 v145, v221, v221
	v_add_f32_e32 v144, v144, v145
	v_mul_f32_e32 v145, v222, v222
	v_fmac_f32_e32 v145, v223, v223
	v_fmac_f32_e32 v145, v224, v224
	v_fmac_f32_e32 v145, v225, v225
	v_add_f32_e32 v144, v144, v145
	s_nop 1
	v_add_f32_dpp v144, v144, v144 quad_perm:[1,0,3,2] row_mask:0xf bank_mask:0xf bound_ctrl:1
	s_nop 1
	v_add_f32_dpp v144, v144, v144 quad_perm:[2,3,0,1] row_mask:0xf bank_mask:0xf bound_ctrl:1
	s_nop 1
	v_add_f32_dpp v144, v144, v144 row_half_mirror row_mask:0xf bank_mask:0xf bound_ctrl:1
	s_nop 1
	v_add_f32_dpp v144, v144, v144 row_mirror row_mask:0xf bank_mask:0xf bound_ctrl:1
	s_nop 1
	v_readlane_b32 s10, v144, 0
	v_readlane_b32 s11, v144, 16
	v_readlane_b32 s14, v144, 32
	v_readlane_b32 s15, v144, 48
	s_nop 3
	v_mov_b32_e32 v144, s11
	v_mov_b32_e32 v145, s15
	v_add_f32_e32 v144, s10, v144
	v_add_f32_e32 v145, s14, v145
	v_add_f32_e32 v144, v144, v145
	v_fmamk_f32 v144, v144, 0x3a800000, v111
	v_rsq_f32_e32 v144, v144
	s_nop 0
	v_mul_f32_e32 v210, v210, v144
	v_mul_f32_e32 v211, v211, v144
	v_mul_f32_e32 v212, v212, v144
	v_mul_f32_e32 v213, v213, v144
	v_mul_f32_e32 v214, v214, v144
	v_mul_f32_e32 v215, v215, v144
	v_mul_f32_e32 v216, v216, v144
	v_mul_f32_e32 v217, v217, v144
	v_mul_f32_e32 v218, v218, v144
	v_mul_f32_e32 v219, v219, v144
	v_mul_f32_e32 v220, v220, v144
	v_mul_f32_e32 v221, v221, v144
	v_mul_f32_e32 v222, v222, v144
	v_mul_f32_e32 v223, v223, v144
	v_mul_f32_e32 v224, v224, v144
	v_mul_f32_e32 v225, v225, v144
	v_dot8c_i32_i4_e32 v38, v122, v48
	v_dot8c_i32_i4_e32 v39, v122, v46
	v_dot8c_i32_i4_e32 v40, v124, v48
	v_dot8c_i32_i4_e32 v41, v124, v46
	v_dot8c_i32_i4_e32 v42, v126, v48
	v_dot8c_i32_i4_e32 v43, v126, v46
	v_dot8c_i32_i4_e32 v44, v128, v48
	v_dot8c_i32_i4_e32 v45, v128, v46
	v_dot8c_i32_i4_e32 v38, v123, v49
	v_dot8c_i32_i4_e32 v39, v123, v47
	v_dot8c_i32_i4_e32 v40, v125, v49
	v_dot8c_i32_i4_e32 v41, v125, v47
	v_dot8c_i32_i4_e32 v42, v127, v49
	v_dot8c_i32_i4_e32 v43, v127, v47
	v_dot8c_i32_i4_e32 v44, v129, v49
	v_dot8c_i32_i4_e32 v45, v129, v47
	v_and_b32_e32 v78, 0xffff, v32
	v_lshrrev_b32_e32 v79, 16, v32
	v_lshl_add_u32 v78, v78, 7, v150
	v_lshl_add_u32 v79, v79, 7, v151
	s_mov_b32 m0, s98
	s_add_i32 s43, s98, 0x400
	global_load_lds_dwordx4 v78, s[50:51]
	s_mov_b32 m0, s43
	s_nop 0
	global_load_lds_dwordx4 v79, s[50:51]
	s_waitcnt vmcnt(8)
	v_add_u32_e32 v54, s76, v59
	v_add_u32_e32 v55, s76, v60
	v_add_u32_e32 v56, s76, v61
	v_add_u32_e32 v57, s76, v62
	ds_read_b64_tr_b4 v[46:47], v160 offset:256
	ds_read_b64_tr_b4 v[48:49], v160 offset:1280
	ds_read_b64_tr_b4 v[122:123], v54
	ds_read_b64_tr_b4 v[124:125], v55
	ds_read_b64_tr_b4 v[126:127], v56
	ds_read_b64_tr_b4 v[128:129], v57
	s_waitcnt lgkmcnt(6)
	v_dot8c_i32_i4_e32 v38, v130, v52
	v_dot8c_i32_i4_e32 v39, v130, v50
	v_dot8c_i32_i4_e32 v40, v132, v52
	v_dot8c_i32_i4_e32 v41, v132, v50
	v_dot8c_i32_i4_e32 v42, v134, v52
	v_dot8c_i32_i4_e32 v43, v134, v50
	v_dot8c_i32_i4_e32 v44, v136, v52
	v_dot8c_i32_i4_e32 v45, v136, v50
	v_dot8c_i32_i4_e32 v38, v131, v53
	v_dot8c_i32_i4_e32 v39, v131, v51
	v_dot8c_i32_i4_e32 v40, v133, v53
	v_dot8c_i32_i4_e32 v41, v133, v51
	v_dot8c_i32_i4_e32 v42, v135, v53
	v_dot8c_i32_i4_e32 v43, v135, v51
	v_dot8c_i32_i4_e32 v44, v137, v53
	v_dot8c_i32_i4_e32 v45, v137, v51
	v_and_b32_e32 v78, 0xffff, v33
	v_lshrrev_b32_e32 v79, 16, v33
	v_lshl_add_u32 v78, v78, 7, v150
	v_lshl_add_u32 v79, v79, 7, v151
	s_mov_b32 m0, s99
	s_add_i32 s43, s99, 0x400
	global_load_lds_dwordx4 v78, s[50:51]
	s_mov_b32 m0, s43
	s_nop 0
	global_load_lds_dwordx4 v79, s[50:51]
	s_waitcnt vmcnt(8)
	v_add_u32_e32 v54, s77, v59
	v_add_u32_e32 v55, s77, v60
	v_add_u32_e32 v56, s77, v61
	v_add_u32_e32 v57, s77, v62
	ds_read_b64_tr_b4 v[50:51], v160 offset:384
	ds_read_b64_tr_b4 v[52:53], v160 offset:1408
	ds_read_b64_tr_b4 v[130:131], v54
	ds_read_b64_tr_b4 v[132:133], v55
	ds_read_b64_tr_b4 v[134:135], v56
	ds_read_b64_tr_b4 v[136:137], v57
	s_waitcnt lgkmcnt(6)
	v_dot8c_i32_i4_e32 v38, v122, v48
	v_dot8c_i32_i4_e32 v39, v122, v46
	v_dot8c_i32_i4_e32 v40, v124, v48
	v_dot8c_i32_i4_e32 v41, v124, v46
	v_dot8c_i32_i4_e32 v42, v126, v48
	v_dot8c_i32_i4_e32 v43, v126, v46
	v_dot8c_i32_i4_e32 v44, v128, v48
	v_dot8c_i32_i4_e32 v45, v128, v46
	v_dot8c_i32_i4_e32 v38, v123, v49
	v_dot8c_i32_i4_e32 v39, v123, v47
	v_dot8c_i32_i4_e32 v40, v125, v49
	v_dot8c_i32_i4_e32 v41, v125, v47
	v_dot8c_i32_i4_e32 v42, v127, v49
	v_dot8c_i32_i4_e32 v43, v127, v47
	v_dot8c_i32_i4_e32 v44, v129, v49
	v_dot8c_i32_i4_e32 v45, v129, v47
	s_waitcnt lgkmcnt(15)
	v_and_b32_e32 v78, 0xffff, v18
	v_lshrrev_b32_e32 v79, 16, v18
	v_lshl_add_u32 v78, v78, 7, v152
	v_lshl_add_u32 v79, v79, 7, v153
	s_mov_b32 m0, s76
	s_add_i32 s43, s76, 0x400
	global_load_lds_dwordx4 v78, s[50:51]
	s_mov_b32 m0, s43
	s_nop 0
	global_load_lds_dwordx4 v79, s[50:51]
	s_waitcnt vmcnt(8)
	v_add_u32_e32 v54, s78, v59
	v_add_u32_e32 v55, s78, v60
	v_add_u32_e32 v56, s78, v61
	v_add_u32_e32 v57, s78, v62
	ds_read_b64_tr_b4 v[46:47], v160 offset:512
	ds_read_b64_tr_b4 v[48:49], v160 offset:1536
	ds_read_b64_tr_b4 v[122:123], v54
	ds_read_b64_tr_b4 v[124:125], v55
	ds_read_b64_tr_b4 v[126:127], v56
	ds_read_b64_tr_b4 v[128:129], v57
	s_waitcnt lgkmcnt(6)
; #define LAS __attribute__((address_space(3)))
; #define TR4(p_) __builtin_amdgcn_ds_read_tr4_b64_v2i32((LAS v2i*)(p_))
; __device__ __forceinline__ void peer_v_tokens(int j, const LAS unsigned short* EL, const LAS unsigned char* AL  , const LAS float* ASC  , const LAS int* SAL  , ...
;     ...
;         for (int m = 0; m < 2; ++m) {
;             const int idx = lane + 64 * m, tau = idx >> 4, sr = idx & 15, k = 16 * (sr & 7) + 2 * tau + (sr >> 3);
;             const int aq = (int)*(const LAS signed char*)(AL + tl * 128 + k); const int tq = aq + 8;
;             const unsigned lo = (((unsigned)tq & 15u) ^ 8u) * 0x11111111u, hi = ((unsigned)(tq >> 4) & 15u) * 0x11111111u;
;             typedef unsigned u2v __attribute__((ext_vector_type(2)));
;             u2v l2; l2.x = lo; l2.y = lo; u2v h2; h2.x = hi; h2.y = hi;
;             *(LAS u2v*)(ATL + 8 * idx) = l2; *(LAS u2v*)(ATL + 1024 + 8 * idx) = h2;
;         }
;     ...
;         for (int st = 0; st < 16; ++st) {
;             const int p = st >> 2, q = st & 3;
;             if (st < 14) VDMA(st + 2, (st + 2) % 3);
;             if (st < 14) asm volatile("s_waitcnt vmcnt(8)" ::: "memory");
;             else if (st == 14) asm volatile("s_waitcnt vmcnt(4)" ::: "memory");
;             else asm volatile("s_waitcnt vmcnt(0)" ::: "memory");
;             if (q == 0) {
; #pragma unroll
;                 for (int r = 0; r < 4; ++r) { accH[r] = 0; accL[r] = 0; } }
; #pragma unroll
;             for (int tp = 0; tp < 2; ++tp) {
;                 const v2i ao = TR4(ATL + (2 * q + tp) * 128 + 8 * s16), ah = TR4(ATL + 1024 + (2 * q + tp) * 128 + 8 * s16);
; #pragma unroll
;                 for (int r = 0; r < 4; ++r) {
;                     const v2i d = TR4(ldsb + BUF[st % 3] + 2048 * tp + roff[r]);
;                     accH[r] = __builtin_amdgcn_sdot8(d.x, ah.x, accH[r], false); accH[r] = __builtin_amdgcn_sdot8(d.y, ah.y, accH[r], false);
;                     accL[r] = __builtin_amdgcn_sdot8(d.x, ao.x, accL[r], false); accL[r] = __builtin_amdgcn_sdot8(d.y, ao.y, accL[r], false);
;                 }
;             }
	v_dot8c_i32_i4_e32 v38, v130, v52
	v_dot8c_i32_i4_e32 v39, v130, v50
	v_dot8c_i32_i4_e32 v40, v132, v52
	v_dot8c_i32_i4_e32 v41, v132, v50
	v_dot8c_i32_i4_e32 v42, v134, v52
	v_dot8c_i32_i4_e32 v43, v134, v50
	v_dot8c_i32_i4_e32 v44, v136, v52
	v_dot8c_i32_i4_e32 v45, v136, v50
	v_dot8c_i32_i4_e32 v38, v131, v53
	v_dot8c_i32_i4_e32 v39, v131, v51
	v_dot8c_i32_i4_e32 v40, v133, v53
	v_dot8c_i32_i4_e32 v41, v133, v51
	v_dot8c_i32_i4_e32 v42, v135, v53
	v_dot8c_i32_i4_e32 v43, v135, v51
	v_dot8c_i32_i4_e32 v44, v137, v53
	v_dot8c_i32_i4_e32 v45, v137, v51
	v_and_b32_e32 v78, 0xffff, v19
	v_lshrrev_b32_e32 v79, 16, v19
	v_lshl_add_u32 v78, v78, 7, v152
	v_lshl_add_u32 v79, v79, 7, v153
	s_mov_b32 m0, s77
	s_add_i32 s43, s77, 0x400
	global_load_lds_dwordx4 v78, s[50:51]
	s_mov_b32 m0, s43
	s_nop 0
	global_load_lds_dwordx4 v79, s[50:51]
	s_waitcnt vmcnt(8)
	v_add_u32_e32 v54, s79, v59
	v_add_u32_e32 v55, s79, v60
	v_add_u32_e32 v56, s79, v61
	v_add_u32_e32 v57, s79, v62
	ds_read_b64_tr_b4 v[50:51], v160 offset:640
	ds_read_b64_tr_b4 v[52:53], v160 offset:1664
	ds_read_b64_tr_b4 v[130:131], v54
	ds_read_b64_tr_b4 v[132:133], v55
	ds_read_b64_tr_b4 v[134:135], v56
	ds_read_b64_tr_b4 v[136:137], v57
	s_waitcnt lgkmcnt(6)
	v_dot8c_i32_i4_e32 v38, v122, v48
	v_dot8c_i32_i4_e32 v39, v122, v46
	v_dot8c_i32_i4_e32 v40, v124, v48
	v_dot8c_i32_i4_e32 v41, v124, v46
	v_dot8c_i32_i4_e32 v42, v126, v48
	v_dot8c_i32_i4_e32 v43, v126, v46
	v_dot8c_i32_i4_e32 v44, v128, v48
	v_dot8c_i32_i4_e32 v45, v128, v46
	v_dot8c_i32_i4_e32 v38, v123, v49
	v_dot8c_i32_i4_e32 v39, v123, v47
	v_dot8c_i32_i4_e32 v40, v125, v49
	v_dot8c_i32_i4_e32 v41, v125, v47
	v_dot8c_i32_i4_e32 v42, v127, v49
	v_dot8c_i32_i4_e32 v43, v127, v47
	v_dot8c_i32_i4_e32 v44, v129, v49
	v_dot8c_i32_i4_e32 v45, v129, v47
	s_waitcnt lgkmcnt(15)
	v_add_u32_e32 v143, 8, v139
	v_and_b32_e32 v142, 15, v143
	v_xor_b32_e32 v142, 8, v142
	v_bfe_u32 v144, v143, 4, 4
	v_mul_lo_u32 v142, v142, s92
	v_mul_lo_u32 v144, v144, s92
	v_mov_b32_e32 v143, v142
	v_mov_b32_e32 v145, v144
	ds_write2st64_b64 v159, v[142:143], v[144:145] offset1:2
	v_and_b32_e32 v78, 0xffff, v20
	v_lshrrev_b32_e32 v79, 16, v20
	v_lshl_add_u32 v78, v78, 7, v152
	v_lshl_add_u32 v79, v79, 7, v153
	s_mov_b32 m0, s78
	s_add_i32 s43, s78, 0x400
	global_load_lds_dwordx4 v78, s[50:51]
	s_mov_b32 m0, s43
	s_nop 0
	global_load_lds_dwordx4 v79, s[50:51]
	s_waitcnt vmcnt(8)
	v_add_u32_e32 v54, s98, v59
	v_add_u32_e32 v55, s98, v60
	v_add_u32_e32 v56, s98, v61
	v_add_u32_e32 v57, s98, v62
	ds_read_b64_tr_b4 v[46:47], v160 offset:768
	ds_read_b64_tr_b4 v[48:49], v160 offset:1792
	ds_read_b64_tr_b4 v[122:123], v54
	ds_read_b64_tr_b4 v[124:125], v55
	ds_read_b64_tr_b4 v[126:127], v56
	ds_read_b64_tr_b4 v[128:129], v57
	s_waitcnt lgkmcnt(7)
	v_dot8c_i32_i4_e32 v38, v130, v52
	v_dot8c_i32_i4_e32 v39, v130, v50
	v_dot8c_i32_i4_e32 v40, v132, v52
	v_dot8c_i32_i4_e32 v41, v132, v50
	v_dot8c_i32_i4_e32 v42, v134, v52
	v_dot8c_i32_i4_e32 v43, v134, v50
	v_dot8c_i32_i4_e32 v44, v136, v52
	v_dot8c_i32_i4_e32 v45, v136, v50
	v_dot8c_i32_i4_e32 v38, v131, v53
	v_dot8c_i32_i4_e32 v39, v131, v51
	v_dot8c_i32_i4_e32 v40, v133, v53
	v_dot8c_i32_i4_e32 v41, v133, v51
	v_dot8c_i32_i4_e32 v42, v135, v53
	v_dot8c_i32_i4_e32 v43, v135, v51
	v_dot8c_i32_i4_e32 v44, v137, v53
	v_dot8c_i32_i4_e32 v45, v137, v51
	v_and_b32_e32 v78, 0xffff, v21
	v_lshrrev_b32_e32 v79, 16, v21
	v_lshl_add_u32 v78, v78, 7, v152
	v_lshl_add_u32 v79, v79, 7, v153
	s_mov_b32 m0, s79
	s_add_i32 s43, s79, 0x400
	global_load_lds_dwordx4 v78, s[50:51]
	s_mov_b32 m0, s43
	s_nop 0
	global_load_lds_dwordx4 v79, s[50:51]
	s_waitcnt vmcnt(8)
	v_add_u32_e32 v54, s99, v59
	v_add_u32_e32 v55, s99, v60
	v_add_u32_e32 v56, s99, v61
	v_add_u32_e32 v57, s99, v62
	ds_read_b64_tr_b4 v[50:51], v160 offset:896
	ds_read_b64_tr_b4 v[52:53], v160 offset:1920
	ds_read_b64_tr_b4 v[130:131], v54
	ds_read_b64_tr_b4 v[132:133], v55
	ds_read_b64_tr_b4 v[134:135], v56
	ds_read_b64_tr_b4 v[136:137], v57
	s_waitcnt lgkmcnt(6)
	v_dot8c_i32_i4_e32 v38, v122, v48
	v_dot8c_i32_i4_e32 v39, v122, v46
	v_dot8c_i32_i4_e32 v40, v124, v48
	v_dot8c_i32_i4_e32 v41, v124, v46
	v_dot8c_i32_i4_e32 v42, v126, v48
	v_dot8c_i32_i4_e32 v43, v126, v46
	v_dot8c_i32_i4_e32 v44, v128, v48
	v_dot8c_i32_i4_e32 v45, v128, v46
	v_dot8c_i32_i4_e32 v38, v123, v49
	v_dot8c_i32_i4_e32 v39, v123, v47
	v_dot8c_i32_i4_e32 v40, v125, v49
	v_dot8c_i32_i4_e32 v41, v125, v47
	v_dot8c_i32_i4_e32 v42, v127, v49
	v_dot8c_i32_i4_e32 v43, v127, v47
	v_dot8c_i32_i4_e32 v44, v129, v49
	v_dot8c_i32_i4_e32 v45, v129, v47
	v_and_b32_e32 v78, 0xffff, v22
	v_lshrrev_b32_e32 v79, 16, v22
	v_lshl_add_u32 v78, v78, 7, v152
	v_lshl_add_u32 v79, v79, 7, v153
	s_mov_b32 m0, s98
	s_add_i32 s43, s98, 0x400
	global_load_lds_dwordx4 v78, s[50:51]
	s_mov_b32 m0, s43
	s_nop 0
	global_load_lds_dwordx4 v79, s[50:51]
	s_waitcnt vmcnt(8)
	v_add_u32_e32 v54, s76, v59
	v_add_u32_e32 v55, s76, v60
	v_add_u32_e32 v56, s76, v61
	v_add_u32_e32 v57, s76, v62
	ds_read_b64_tr_b4 v[46:47], v160
	ds_read_b64_tr_b4 v[48:49], v160 offset:1024
	ds_read_b64_tr_b4 v[122:123], v54
	ds_read_b64_tr_b4 v[124:125], v55
	ds_read_b64_tr_b4 v[126:127], v56
	ds_read_b64_tr_b4 v[128:129], v57
	s_waitcnt lgkmcnt(6)
	v_dot8c_i32_i4_e32 v38, v130, v52
	v_dot8c_i32_i4_e32 v39, v130, v50
	v_dot8c_i32_i4_e32 v40, v132, v52
	v_dot8c_i32_i4_e32 v41, v132, v50
	v_dot8c_i32_i4_e32 v42, v134, v52
	v_dot8c_i32_i4_e32 v43, v134, v50
	v_dot8c_i32_i4_e32 v44, v136, v52
	v_dot8c_i32_i4_e32 v45, v136, v50
	v_dot8c_i32_i4_e32 v38, v131, v53
	v_dot8c_i32_i4_e32 v39, v131, v51
	v_dot8c_i32_i4_e32 v40, v133, v53
	v_dot8c_i32_i4_e32 v41, v133, v51
	v_dot8c_i32_i4_e32 v42, v135, v53
	v_dot8c_i32_i4_e32 v43, v135, v51
	v_dot8c_i32_i4_e32 v44, v137, v53
	v_dot8c_i32_i4_e32 v45, v137, v51
	s_nop 3
	s_waitcnt lgkmcnt(15)
; #define LAS __attribute__((address_space(3)))
; __device__ __forceinline__ bf16 f2bf(float f) { return (bf16)f2bfu(f); }
; __device__ __forceinline__ void peer_v_tokens(int j, const LAS unsigned short* EL, const LAS unsigned char* AL  , const LAS float* ASC  , const LAS int* SAL  , ...
;     ...
;         uint2 hv[4]; float4 gv[4];
;         { unsigned ho = (unsigned)t * (D / 4) + (unsigned)lane; asm volatile("" : "+v"(ho)); const uint2* hp = (const uint2*)HB + ho; const float4* gp = (const float4*)fng + lane;
; #pragma unroll
;           for (int jq = 0; jq < 4; ++jq) { hv[jq] = hp[64 * jq]; gv[jq] = gp[64 * jq]; } }
;     ...
;                 for (int r = 0; r < 4; ++r) STASH[256 * p + 16 * (grp + 4 * r) + pc] = f2bf(asc * (float)(2 * ((accH[r] << 4) + accL[r]) + sa));
;     ...
;         {
;             float4 v[4]; float ss = 0.f;
; #pragma unroll
;             for (int jq = 0; jq < 4; ++jq) { typedef unsigned u2v __attribute__((ext_vector_type(2))); const u2v pw = *(const LAS u2v*)(STASH + 4 * lane + 256 * jq); const uint2 hw = hv[jq];
;                 v[jq] = make_float4(__uint_as_float(hw.x << 16) + __uint_as_float(pw.x << 16), __uint_as_float(hw.x & 0xffff0000u) + __uint_as_float(pw.x & 0xffff0000u),
;                                     __uint_as_float(hw.y << 16) + __uint_as_float(pw.y << 16), __uint_as_float(hw.y & 0xffff0000u) + __uint_as_float(pw.y & 0xffff0000u));
;                 ss += v[jq].x * v[jq].x + v[jq].y * v[jq].y + v[jq].z * v[jq].z + v[jq].w * v[jq].w; }
;             ss = wave_sum(ss);
;             const float r3 = rsqrtf(ss * (1.f / D) + EPS);
;             float4* op = (float4*)(outp + (size_t)t * D) + lane;
; #pragma unroll
;             for (int jq = 0; jq < 4; ++jq) { typedef float f4v __attribute__((ext_vector_type(4))); f4v o4; o4.x = v[jq].x * r3 * gv[jq].x; o4.y = v[jq].y * r3 * gv[jq].y; o4.z = v[jq].z * r3 * gv[jq].z; o4.w = v[jq].w * r3 * gv[jq].w;
;                 __builtin_nontemporal_store(o4, (f4v*)op + 64 * jq); }
;         }
	v_lshlrev_b32_e32 v38, 5, v38
	v_lshlrev_b32_e32 v39, 1, v39
	v_add3_u32 v38, v39, v229, v38
	v_cvt_f32_i32_e32 v38, v38
	v_mul_f32_e32 v38, v228, v38
	v_lshlrev_b32_e32 v40, 5, v40
	v_lshlrev_b32_e32 v41, 1, v41
	v_add3_u32 v40, v41, v229, v40
	v_cvt_f32_i32_e32 v40, v40
	v_mul_f32_e32 v40, v228, v40
	v_lshlrev_b32_e32 v42, 5, v42
	v_lshlrev_b32_e32 v43, 1, v43
	v_add3_u32 v42, v43, v229, v42
	v_cvt_f32_i32_e32 v42, v42
	v_mul_f32_e32 v42, v228, v42
	v_lshlrev_b32_e32 v44, 5, v44
	v_lshlrev_b32_e32 v45, 1, v45
	v_add3_u32 v44, v45, v229, v44
	v_cvt_f32_i32_e32 v44, v44
	v_mul_f32_e32 v44, v228, v44
	v_cvt_pk_bf16_f32 v170, v38, v40
	v_cvt_pk_bf16_f32 v171, v42, v44
	ds_read_b128 v[252:255], v155
	s_add_i32 s44, s40, 16
	s_ashr_i32 s45, s44, 31
	s_lshl_b64 s[44:45], s[44:45], 12
	v_lshl_add_u64 v[80:81], v[36:37], 0, s[44:45]
	s_waitcnt lgkmcnt(0)
	v_mul_f32_e32 v210, v210, v252
	v_mul_f32_e32 v211, v211, v253
	v_mul_f32_e32 v212, v212, v254
	v_mul_f32_e32 v213, v213, v255
	global_store_dwordx4 v[80:81], v[210:213], off sc1
	s_add_i32 s43, s40, 24
	s_lshl_b32 s43, s43, 11
	v_add_u32_e32 v138, s43, v66
	global_load_dwordx2 v[194:195], v138, s[70:71]
	global_load_dwordx2 v[196:197], v138, s[70:71] offset:512
	global_load_dwordx2 v[198:199], v138, s[70:71] offset:1024
	global_load_dwordx2 v[200:201], v138, s[70:71] offset:1536
	v_add_u32_e32 v147, 8, v140
	v_and_b32_e32 v146, 15, v147
	v_xor_b32_e32 v146, 8, v146
	v_bfe_u32 v148, v147, 4, 4
	v_mul_lo_u32 v146, v146, s92
	v_mul_lo_u32 v148, v148, s92
	v_mov_b32_e32 v147, v146
	v_mov_b32_e32 v149, v148
	ds_write2st64_b64 v77, v[146:147], v[148:149] offset1:2
	v_add_u32_e32 v138, 0x1400, v74
	ds_read_u8 v139, v138
	v_add_u32_e32 v141, 0x1400, v73
	ds_read_u8 v140, v141
	s_add_i32 s43, s67, 128
	v_mov_b32_e32 v138, s43
	ds_read2st64_b32 v[228:229], v138 offset1:1
	ds_read_b128 v[26:29], v227 offset:10240
	ds_read_b128 v[30:33], v227 offset:10256
	v_mov_b32_e32 v38, 0
	v_mov_b32_e32 v39, 0
	v_mov_b32_e32 v40, 0
	v_mov_b32_e32 v41, 0
	v_mov_b32_e32 v42, 0
	v_mov_b32_e32 v43, 0
	v_mov_b32_e32 v44, 0
	v_mov_b32_e32 v45, 0
	v_and_b32_e32 v78, 0xffff, v23
	v_lshrrev_b32_e32 v79, 16, v23
	v_lshl_add_u32 v78, v78, 7, v152
	v_lshl_add_u32 v79, v79, 7, v153
	s_mov_b32 m0, s99
	s_add_i32 s43, s99, 0x400
	global_load_lds_dwordx4 v78, s[50:51]
	s_mov_b32 m0, s43
	s_nop 0
	global_load_lds_dwordx4 v79, s[50:51]
	s_waitcnt vmcnt(13)
	v_add_u32_e32 v54, s77, v59
	v_add_u32_e32 v55, s77, v60
	v_add_u32_e32 v56, s77, v61
	v_add_u32_e32 v57, s77, v62
	ds_read_b64_tr_b4 v[50:51], v160 offset:128
	ds_read_b64_tr_b4 v[52:53], v160 offset:1152
	ds_read_b64_tr_b4 v[130:131], v54
	ds_read_b64_tr_b4 v[132:133], v55
	ds_read_b64_tr_b4 v[134:135], v56
	ds_read_b64_tr_b4 v[136:137], v57
	s_waitcnt lgkmcnt(13)
	v_dot8c_i32_i4_e32 v38, v122, v48
	v_dot8c_i32_i4_e32 v39, v122, v46
	v_dot8c_i32_i4_e32 v40, v124, v48
	v_dot8c_i32_i4_e32 v41, v124, v46
	v_dot8c_i32_i4_e32 v42, v126, v48
	v_dot8c_i32_i4_e32 v43, v126, v46
	v_dot8c_i32_i4_e32 v44, v128, v48
	v_dot8c_i32_i4_e32 v45, v128, v46
	v_dot8c_i32_i4_e32 v38, v123, v49
	v_dot8c_i32_i4_e32 v39, v123, v47
	v_dot8c_i32_i4_e32 v40, v125, v49
	v_dot8c_i32_i4_e32 v41, v125, v47
	v_dot8c_i32_i4_e32 v42, v127, v49
	v_dot8c_i32_i4_e32 v43, v127, v47
	v_dot8c_i32_i4_e32 v44, v129, v49
	v_dot8c_i32_i4_e32 v45, v129, v47
	v_and_b32_e32 v78, 0xffff, v24
	v_lshrrev_b32_e32 v79, 16, v24
	v_lshl_add_u32 v78, v78, 7, v152
	v_lshl_add_u32 v79, v79, 7, v153
	s_mov_b32 m0, s76
	s_add_i32 s43, s76, 0x400
	global_load_lds_dwordx4 v78, s[50:51]
	s_mov_b32 m0, s43
	s_nop 0
	global_load_lds_dwordx4 v79, s[50:51]
	s_waitcnt vmcnt(13)
	v_add_u32_e32 v54, s78, v59
	v_add_u32_e32 v55, s78, v60
	v_add_u32_e32 v56, s78, v61
	v_add_u32_e32 v57, s78, v62
	ds_read_b64_tr_b4 v[46:47], v160 offset:256
	ds_read_b64_tr_b4 v[48:49], v160 offset:1280
	ds_read_b64_tr_b4 v[122:123], v54
	ds_read_b64_tr_b4 v[124:125], v55
	ds_read_b64_tr_b4 v[126:127], v56
	ds_read_b64_tr_b4 v[128:129], v57
	s_waitcnt lgkmcnt(6)
	v_dot8c_i32_i4_e32 v38, v130, v52
	v_dot8c_i32_i4_e32 v39, v130, v50
	v_dot8c_i32_i4_e32 v40, v132, v52
	v_dot8c_i32_i4_e32 v41, v132, v50
	v_dot8c_i32_i4_e32 v42, v134, v52
	v_dot8c_i32_i4_e32 v43, v134, v50
	v_dot8c_i32_i4_e32 v44, v136, v52
	v_dot8c_i32_i4_e32 v45, v136, v50
	v_dot8c_i32_i4_e32 v38, v131, v53
	v_dot8c_i32_i4_e32 v39, v131, v51
	v_dot8c_i32_i4_e32 v40, v133, v53
	v_dot8c_i32_i4_e32 v41, v133, v51
	v_dot8c_i32_i4_e32 v42, v135, v53
	v_dot8c_i32_i4_e32 v43, v135, v51
	v_dot8c_i32_i4_e32 v44, v137, v53
	v_dot8c_i32_i4_e32 v45, v137, v51
	v_and_b32_e32 v78, 0xffff, v25
	v_lshrrev_b32_e32 v79, 16, v25
	v_lshl_add_u32 v78, v78, 7, v152
	v_lshl_add_u32 v79, v79, 7, v153
	s_mov_b32 m0, s77
	s_add_i32 s43, s77, 0x400
	global_load_lds_dwordx4 v78, s[50:51]
	s_mov_b32 m0, s43
	s_nop 0
	global_load_lds_dwordx4 v79, s[50:51]
	s_waitcnt vmcnt(13)
	v_add_u32_e32 v54, s79, v59
	v_add_u32_e32 v55, s79, v60
	v_add_u32_e32 v56, s79, v61
	v_add_u32_e32 v57, s79, v62
	ds_read_b64_tr_b4 v[50:51], v160 offset:384
	ds_read_b64_tr_b4 v[52:53], v160 offset:1408
	ds_read_b64_tr_b4 v[130:131], v54
	ds_read_b64_tr_b4 v[132:133], v55
	ds_read_b64_tr_b4 v[134:135], v56
	ds_read_b64_tr_b4 v[136:137], v57
	s_waitcnt lgkmcnt(6)
	v_dot8c_i32_i4_e32 v38, v122, v48
	v_dot8c_i32_i4_e32 v39, v122, v46
	v_dot8c_i32_i4_e32 v40, v124, v48
	v_dot8c_i32_i4_e32 v41, v124, v46
	v_dot8c_i32_i4_e32 v42, v126, v48
	v_dot8c_i32_i4_e32 v43, v126, v46
	v_dot8c_i32_i4_e32 v44, v128, v48
	v_dot8c_i32_i4_e32 v45, v128, v46
	v_dot8c_i32_i4_e32 v38, v123, v49
	v_dot8c_i32_i4_e32 v39, v123, v47
	v_dot8c_i32_i4_e32 v40, v125, v49
	v_dot8c_i32_i4_e32 v41, v125, v47
	v_dot8c_i32_i4_e32 v42, v127, v49
	v_dot8c_i32_i4_e32 v43, v127, v47
	v_dot8c_i32_i4_e32 v44, v129, v49
	v_dot8c_i32_i4_e32 v45, v129, v47
	s_waitcnt lgkmcnt(15)
; __device__ __forceinline__ void peer_v_tokens(int j, const LAS unsigned short* EL, const LAS unsigned char* AL  , const LAS float* ASC  , const LAS int* SAL  , ...
;     ...
; #pragma unroll 1
;     for (int it = 0; it < 8; ++it) {
;         const int tl = it * 8 + wave, t = j * 64 + tl;
;         unsigned E[8];
;         { const LAS v4u* ep = (const LAS v4u*)(EL + tl * 128 + 16 * g); const v4u e0 = ep[0], e1 = ep[1];
;           E[0] = e0.x; E[1] = e0.y; E[2] = e0.z; E[3] = e0.w; E[4] = e1.x; E[5] = e1.y; E[6] = e1.z; E[7] = e1.w; }
;         uint2 hv[4]; float4 gv[4];
;         { unsigned ho = (unsigned)t * (D / 4) + (unsigned)lane; asm volatile("" : "+v"(ho)); const uint2* hp = (const uint2*)HB + ho; const float4* gp = (const float4*)fng + lane;
; #pragma unroll
;           for (int jq = 0; jq < 4; ++jq) { hv[jq] = hp[64 * jq]; gv[jq] = gp[64 * jq]; } }
;         VDMA(0, 0); VDMA(1, 1);
; #pragma unroll
;         for (int m = 0; m < 2; ++m) {
;             const int idx = lane + 64 * m, tau = idx >> 4, sr = idx & 15, k = 16 * (sr & 7) + 2 * tau + (sr >> 3);
;             const int aq = (int)*(const LAS signed char*)(AL + tl * 128 + k); const int tq = aq + 8;
;             const unsigned lo = (((unsigned)tq & 15u) ^ 8u) * 0x11111111u, hi = ((unsigned)(tq >> 4) & 15u) * 0x11111111u;
;             typedef unsigned u2v __attribute__((ext_vector_type(2)));
;             u2v l2; l2.x = lo; l2.y = lo; u2v h2; h2.x = hi; h2.y = hi;
;             *(LAS u2v*)(ATL + 8 * idx) = l2; *(LAS u2v*)(ATL + 1024 + 8 * idx) = h2;
;         }
;         const float asc = ASC[tl]; const int sa = SAL[tl];
;         CFENCE();
;         int accH[4], accL[4];
; #pragma unroll
;         for (int st = 0; st < 16; ++st) {
;             const int p = st >> 2, q = st & 3;
;             if (st < 14) VDMA(st + 2, (st + 2) % 3);
;             if (st < 14) asm volatile("s_waitcnt vmcnt(8)" ::: "memory");
;             else if (st == 14) asm volatile("s_waitcnt vmcnt(4)" ::: "memory");
;             else asm volatile("s_waitcnt vmcnt(0)" ::: "memory");
;             if (q == 0) {
; #pragma unroll
;                 for (int r = 0; r < 4; ++r) { accH[r] = 0; accL[r] = 0; } }
; #pragma unroll
;             for (int tp = 0; tp < 2; ++tp) {
;                 const v2i ao = TR4(ATL + (2 * q + tp) * 128 + 8 * s16), ah = TR4(ATL + 1024 + (2 * q + tp) * 128 + 8 * s16);
; #pragma unroll
	v_and_b32_e32 v78, 0xffff, v26
	v_lshrrev_b32_e32 v79, 16, v26
	v_lshl_add_u32 v78, v78, 7, v152
	v_lshl_add_u32 v79, v79, 7, v153
	s_mov_b32 m0, s78
	s_add_i32 s43, s78, 0x400
	global_load_lds_dwordx4 v78, s[50:51]
	s_mov_b32 m0, s43
	s_nop 0
	global_load_lds_dwordx4 v79, s[50:51]
	s_waitcnt vmcnt(13)
	v_add_u32_e32 v54, s98, v59
	v_add_u32_e32 v55, s98, v60
	v_add_u32_e32 v56, s98, v61
	v_add_u32_e32 v57, s98, v62
	ds_read_b64_tr_b4 v[46:47], v160 offset:512
	ds_read_b64_tr_b4 v[48:49], v160 offset:1536
	ds_read_b64_tr_b4 v[122:123], v54
	ds_read_b64_tr_b4 v[124:125], v55
	ds_read_b64_tr_b4 v[126:127], v56
	ds_read_b64_tr_b4 v[128:129], v57
	s_waitcnt lgkmcnt(6)
	v_dot8c_i32_i4_e32 v38, v130, v52
	v_dot8c_i32_i4_e32 v39, v130, v50
	v_dot8c_i32_i4_e32 v40, v132, v52
	v_dot8c_i32_i4_e32 v41, v132, v50
	v_dot8c_i32_i4_e32 v42, v134, v52
	v_dot8c_i32_i4_e32 v43, v134, v50
	v_dot8c_i32_i4_e32 v44, v136, v52
	v_dot8c_i32_i4_e32 v45, v136, v50
	v_dot8c_i32_i4_e32 v38, v131, v53
	v_dot8c_i32_i4_e32 v39, v131, v51
	v_dot8c_i32_i4_e32 v40, v133, v53
	v_dot8c_i32_i4_e32 v41, v133, v51
	v_dot8c_i32_i4_e32 v42, v135, v53
	v_dot8c_i32_i4_e32 v43, v135, v51
	v_dot8c_i32_i4_e32 v44, v137, v53
	v_dot8c_i32_i4_e32 v45, v137, v51
	v_and_b32_e32 v78, 0xffff, v27
	v_lshrrev_b32_e32 v79, 16, v27
	v_lshl_add_u32 v78, v78, 7, v152
	v_lshl_add_u32 v79, v79, 7, v153
	s_mov_b32 m0, s79
	s_add_i32 s43, s79, 0x400
	global_load_lds_dwordx4 v78, s[50:51]
	s_mov_b32 m0, s43
	s_nop 0
	global_load_lds_dwordx4 v79, s[50:51]
	s_waitcnt vmcnt(8)
	v_add_u32_e32 v54, s99, v59
	v_add_u32_e32 v55, s99, v60
	v_add_u32_e32 v56, s99, v61
	v_add_u32_e32 v57, s99, v62
	ds_read_b64_tr_b4 v[50:51], v160 offset:640
	ds_read_b64_tr_b4 v[52:53], v160 offset:1664
	ds_read_b64_tr_b4 v[130:131], v54
	ds_read_b64_tr_b4 v[132:133], v55
	ds_read_b64_tr_b4 v[134:135], v56
	ds_read_b64_tr_b4 v[136:137], v57
	s_waitcnt lgkmcnt(6)
	v_dot8c_i32_i4_e32 v38, v122, v48
	v_dot8c_i32_i4_e32 v39, v122, v46
	v_dot8c_i32_i4_e32 v40, v124, v48
	v_dot8c_i32_i4_e32 v41, v124, v46
	v_dot8c_i32_i4_e32 v42, v126, v48
	v_dot8c_i32_i4_e32 v43, v126, v46
	v_dot8c_i32_i4_e32 v44, v128, v48
	v_dot8c_i32_i4_e32 v45, v128, v46
	v_dot8c_i32_i4_e32 v38, v123, v49
	v_dot8c_i32_i4_e32 v39, v123, v47
	v_dot8c_i32_i4_e32 v40, v125, v49
	v_dot8c_i32_i4_e32 v41, v125, v47
	v_dot8c_i32_i4_e32 v42, v127, v49
	v_dot8c_i32_i4_e32 v43, v127, v47
	v_dot8c_i32_i4_e32 v44, v129, v49
	v_dot8c_i32_i4_e32 v45, v129, v47
	s_waitcnt lgkmcnt(15)
	v_add_u32_e32 v143, 8, v139
	v_and_b32_e32 v142, 15, v143
	v_xor_b32_e32 v142, 8, v142
	v_bfe_u32 v144, v143, 4, 4
	v_mul_lo_u32 v142, v142, s92
	v_mul_lo_u32 v144, v144, s92
	v_mov_b32_e32 v143, v142
	v_mov_b32_e32 v145, v144
	ds_write2st64_b64 v159, v[142:143], v[144:145] offset1:2
	v_and_b32_e32 v78, 0xffff, v28
	v_lshrrev_b32_e32 v79, 16, v28
	v_lshl_add_u32 v78, v78, 7, v152
	v_lshl_add_u32 v79, v79, 7, v153
	s_mov_b32 m0, s98
	s_add_i32 s43, s98, 0x400
	global_load_lds_dwordx4 v78, s[50:51]
	s_mov_b32 m0, s43
	s_nop 0
	global_load_lds_dwordx4 v79, s[50:51]
	s_waitcnt vmcnt(8)
	v_add_u32_e32 v54, s76, v59
	v_add_u32_e32 v55, s76, v60
	v_add_u32_e32 v56, s76, v61
	v_add_u32_e32 v57, s76, v62
	ds_read_b64_tr_b4 v[46:47], v160 offset:768
	ds_read_b64_tr_b4 v[48:49], v160 offset:1792
	ds_read_b64_tr_b4 v[122:123], v54
	ds_read_b64_tr_b4 v[124:125], v55
	ds_read_b64_tr_b4 v[126:127], v56
	ds_read_b64_tr_b4 v[128:129], v57
	s_waitcnt lgkmcnt(7)
	v_dot8c_i32_i4_e32 v38, v130, v52
	v_dot8c_i32_i4_e32 v39, v130, v50
	v_dot8c_i32_i4_e32 v40, v132, v52
	v_dot8c_i32_i4_e32 v41, v132, v50
	v_dot8c_i32_i4_e32 v42, v134, v52
	v_dot8c_i32_i4_e32 v43, v134, v50
	v_dot8c_i32_i4_e32 v44, v136, v52
	v_dot8c_i32_i4_e32 v45, v136, v50
	v_dot8c_i32_i4_e32 v38, v131, v53
	v_dot8c_i32_i4_e32 v39, v131, v51
	v_dot8c_i32_i4_e32 v40, v133, v53
	v_dot8c_i32_i4_e32 v41, v133, v51
	v_dot8c_i32_i4_e32 v42, v135, v53
	v_dot8c_i32_i4_e32 v43, v135, v51
	v_dot8c_i32_i4_e32 v44, v137, v53
	v_dot8c_i32_i4_e32 v45, v137, v51
	v_and_b32_e32 v78, 0xffff, v29
	v_lshrrev_b32_e32 v79, 16, v29
	v_lshl_add_u32 v78, v78, 7, v152
	v_lshl_add_u32 v79, v79, 7, v153
	s_mov_b32 m0, s99
	s_add_i32 s43, s99, 0x400
	global_load_lds_dwordx4 v78, s[50:51]
	s_mov_b32 m0, s43
	s_nop 0
	global_load_lds_dwordx4 v79, s[50:51]
	s_waitcnt vmcnt(8)
	v_add_u32_e32 v54, s77, v59
	v_add_u32_e32 v55, s77, v60
	v_add_u32_e32 v56, s77, v61
	v_add_u32_e32 v57, s77, v62
	ds_read_b64_tr_b4 v[50:51], v160 offset:896
	ds_read_b64_tr_b4 v[52:53], v160 offset:1920
	ds_read_b64_tr_b4 v[130:131], v54
	ds_read_b64_tr_b4 v[132:133], v55
	ds_read_b64_tr_b4 v[134:135], v56
	ds_read_b64_tr_b4 v[136:137], v57
	s_waitcnt lgkmcnt(6)
	v_dot8c_i32_i4_e32 v38, v122, v48
	v_dot8c_i32_i4_e32 v39, v122, v46
	v_dot8c_i32_i4_e32 v40, v124, v48
	v_dot8c_i32_i4_e32 v41, v124, v46
	v_dot8c_i32_i4_e32 v42, v126, v48
	v_dot8c_i32_i4_e32 v43, v126, v46
	v_dot8c_i32_i4_e32 v44, v128, v48
	v_dot8c_i32_i4_e32 v45, v128, v46
	v_dot8c_i32_i4_e32 v38, v123, v49
	v_dot8c_i32_i4_e32 v39, v123, v47
	v_dot8c_i32_i4_e32 v40, v125, v49
	v_dot8c_i32_i4_e32 v41, v125, v47
	v_dot8c_i32_i4_e32 v42, v127, v49
	v_dot8c_i32_i4_e32 v43, v127, v47
	v_dot8c_i32_i4_e32 v44, v129, v49
	v_dot8c_i32_i4_e32 v45, v129, v47
	v_and_b32_e32 v78, 0xffff, v30
	v_lshrrev_b32_e32 v79, 16, v30
	v_lshl_add_u32 v78, v78, 7, v152
	v_lshl_add_u32 v79, v79, 7, v153
	s_mov_b32 m0, s76
	s_add_i32 s43, s76, 0x400
	global_load_lds_dwordx4 v78, s[50:51]
	s_mov_b32 m0, s43
	s_nop 0
	global_load_lds_dwordx4 v79, s[50:51]
	s_waitcnt vmcnt(8)
; __device__ __forceinline__ void peer_v_tokens(int j, const LAS unsigned short* EL, const LAS unsigned char* AL  , const LAS float* ASC  , const LAS int* SAL  , ...
;     ...
;         for (int st = 0; st < 16; ++st) {
;             const int p = st >> 2, q = st & 3;
;             if (st < 14) VDMA(st + 2, (st + 2) % 3);
;             if (st < 14) asm volatile("s_waitcnt vmcnt(8)" ::: "memory");
;             else if (st == 14) asm volatile("s_waitcnt vmcnt(4)" ::: "memory");
;             else asm volatile("s_waitcnt vmcnt(0)" ::: "memory");
;             if (q == 0) {
; #pragma unroll
;                 for (int r = 0; r < 4; ++r) { accH[r] = 0; accL[r] = 0; } }
; #pragma unroll
;             for (int tp = 0; tp < 2; ++tp) {
;                 const v2i ao = TR4(ATL + (2 * q + tp) * 128 + 8 * s16), ah = TR4(ATL + 1024 + (2 * q + tp) * 128 + 8 * s16);
; #pragma unroll
;                 for (int r = 0; r < 4; ++r) {
;                     const v2i d = TR4(ldsb + BUF[st % 3] + 2048 * tp + roff[r]);
;                     accH[r] = __builtin_amdgcn_sdot8(d.x, ah.x, accH[r], false); accH[r] = __builtin_amdgcn_sdot8(d.y, ah.y, accH[r], false);
;                     accL[r] = __builtin_amdgcn_sdot8(d.x, ao.x, accL[r], false); accL[r] = __builtin_amdgcn_sdot8(d.y, ao.y, accL[r], false);
;                 }
;             }
;             asm volatile("s_waitcnt lgkmcnt(0)" ::: "memory");
;             if (q == 3) {
; #pragma unroll
;                 for (int r = 0; r < 4; ++r) STASH[256 * p + 16 * (grp + 4 * r) + pc] = f2bf(asc * (float)(2 * ((accH[r] << 4) + accL[r]) + sa));
;             }
;         }
;         CFENCE();
;         {
;             float4 v[4]; float ss = 0.f;
; #pragma unroll
;             for (int jq = 0; jq < 4; ++jq) { typedef unsigned u2v __attribute__((ext_vector_type(2))); const u2v pw = *(const LAS u2v*)(STASH + 4 * lane + 256 * jq); const uint2 hw = hv[jq];
;                 v[jq] = make_float4(__uint_as_float(hw.x << 16) + __uint_as_float(pw.x << 16), __uint_as_float(hw.x & 0xffff0000u) + __uint_as_float(pw.x & 0xffff0000u),
;                                     __uint_as_float(hw.y << 16) + __uint_as_float(pw.y << 16), __uint_as_float(hw.y & 0xffff0000u) + __uint_as_float(pw.y & 0xffff0000u));
;                 ss += v[jq].x * v[jq].x + v[jq].y * v[jq].y + v[jq].z * v[jq].z + v[jq].w * v[jq].w; }
;             ss = wave_sum(ss);
	v_add_u32_e32 v54, s78, v59
	v_add_u32_e32 v55, s78, v60
	v_add_u32_e32 v56, s78, v61
	v_add_u32_e32 v57, s78, v62
	ds_read_b64_tr_b4 v[46:47], v160
	ds_read_b64_tr_b4 v[48:49], v160 offset:1024
	ds_read_b64_tr_b4 v[122:123], v54
	ds_read_b64_tr_b4 v[124:125], v55
	ds_read_b64_tr_b4 v[126:127], v56
	ds_read_b64_tr_b4 v[128:129], v57
	s_waitcnt lgkmcnt(6)
	v_dot8c_i32_i4_e32 v38, v130, v52
	v_dot8c_i32_i4_e32 v39, v130, v50
	v_dot8c_i32_i4_e32 v40, v132, v52
	v_dot8c_i32_i4_e32 v41, v132, v50
	v_dot8c_i32_i4_e32 v42, v134, v52
	v_dot8c_i32_i4_e32 v43, v134, v50
	v_dot8c_i32_i4_e32 v44, v136, v52
	v_dot8c_i32_i4_e32 v45, v136, v50
	v_dot8c_i32_i4_e32 v38, v131, v53
	v_dot8c_i32_i4_e32 v39, v131, v51
	v_dot8c_i32_i4_e32 v40, v133, v53
	v_dot8c_i32_i4_e32 v41, v133, v51
	v_dot8c_i32_i4_e32 v42, v135, v53
	v_dot8c_i32_i4_e32 v43, v135, v51
	v_dot8c_i32_i4_e32 v44, v137, v53
	v_dot8c_i32_i4_e32 v45, v137, v51
	s_nop 3
	s_waitcnt lgkmcnt(15)
	v_lshlrev_b32_e32 v38, 5, v38
	v_lshlrev_b32_e32 v39, 1, v39
	v_add3_u32 v38, v39, v229, v38
	v_cvt_f32_i32_e32 v38, v38
	v_mul_f32_e32 v38, v228, v38
	v_lshlrev_b32_e32 v40, 5, v40
	v_lshlrev_b32_e32 v41, 1, v41
	v_add3_u32 v40, v41, v229, v40
	v_cvt_f32_i32_e32 v40, v40
	v_mul_f32_e32 v40, v228, v40
	v_lshlrev_b32_e32 v42, 5, v42
	v_lshlrev_b32_e32 v43, 1, v43
	v_add3_u32 v42, v43, v229, v42
	v_cvt_f32_i32_e32 v42, v42
	v_mul_f32_e32 v42, v228, v42
	v_lshlrev_b32_e32 v44, 5, v44
	v_lshlrev_b32_e32 v45, 1, v45
	v_add3_u32 v44, v45, v229, v44
	v_cvt_f32_i32_e32 v44, v44
	v_mul_f32_e32 v44, v228, v44
	v_cvt_pk_bf16_f32 v164, v38, v40
	v_cvt_pk_bf16_f32 v165, v42, v44
	ds_read_b128 v[252:255], v155 offset:1024
	s_add_i32 s44, s40, 16
	s_ashr_i32 s45, s44, 31
	s_lshl_b64 s[44:45], s[44:45], 12
	v_lshl_add_u64 v[80:81], v[36:37], 0, s[44:45]
	s_waitcnt lgkmcnt(0)
	v_mul_f32_e32 v214, v214, v252
	v_mul_f32_e32 v215, v215, v253
	v_mul_f32_e32 v216, v216, v254
	v_mul_f32_e32 v217, v217, v255
	global_store_dwordx4 v[80:81], v[214:217], off offset:1024 sc1
	v_add_u32_e32 v147, 8, v140
	v_and_b32_e32 v146, 15, v147
	v_xor_b32_e32 v146, 8, v146
	v_bfe_u32 v148, v147, 4, 4
	v_mul_lo_u32 v146, v146, s92
	v_mul_lo_u32 v148, v148, s92
	v_mov_b32_e32 v147, v146
	v_mov_b32_e32 v149, v148
	ds_write2st64_b64 v77, v[146:147], v[148:149] offset1:2
	v_add_u32_e32 v138, 0x1000, v74
	ds_read_u8 v139, v138
	v_add_u32_e32 v141, 0x1000, v73
	ds_read_u8 v140, v141
	s_add_i32 s43, s67, 160
	v_mov_b32_e32 v138, s43
	ds_read2st64_b32 v[228:229], v138 offset1:1
	ds_read_b128 v[18:21], v227 offset:8192
	ds_read_b128 v[22:25], v227 offset:8208
	v_add_u32_e32 v150, 0x400000, v63
	v_add_u32_e32 v151, 0x400000, v64
	v_mov_b32_e32 v38, 0
	v_mov_b32_e32 v39, 0
	v_mov_b32_e32 v40, 0
	v_mov_b32_e32 v41, 0
	v_mov_b32_e32 v42, 0
	v_mov_b32_e32 v43, 0
	v_mov_b32_e32 v44, 0
	v_mov_b32_e32 v45, 0
	v_and_b32_e32 v78, 0xffff, v31
	v_lshrrev_b32_e32 v79, 16, v31
	v_lshl_add_u32 v78, v78, 7, v152
	v_lshl_add_u32 v79, v79, 7, v153
	s_mov_b32 m0, s77
	s_add_i32 s43, s77, 0x400
	global_load_lds_dwordx4 v78, s[50:51]
	s_mov_b32 m0, s43
	s_nop 0
	global_load_lds_dwordx4 v79, s[50:51]
	s_waitcnt vmcnt(9)
	v_add_u32_e32 v54, s79, v59
	v_add_u32_e32 v55, s79, v60
	v_add_u32_e32 v56, s79, v61
	v_add_u32_e32 v57, s79, v62
	ds_read_b64_tr_b4 v[50:51], v160 offset:128
	ds_read_b64_tr_b4 v[52:53], v160 offset:1152
	ds_read_b64_tr_b4 v[130:131], v54
	ds_read_b64_tr_b4 v[132:133], v55
	ds_read_b64_tr_b4 v[134:135], v56
	ds_read_b64_tr_b4 v[136:137], v57
	s_waitcnt lgkmcnt(13)
	v_dot8c_i32_i4_e32 v38, v122, v48
	v_dot8c_i32_i4_e32 v39, v122, v46
	v_dot8c_i32_i4_e32 v40, v124, v48
	v_dot8c_i32_i4_e32 v41, v124, v46
	v_dot8c_i32_i4_e32 v42, v126, v48
	v_dot8c_i32_i4_e32 v43, v126, v46
	v_dot8c_i32_i4_e32 v44, v128, v48
	v_dot8c_i32_i4_e32 v45, v128, v46
	v_dot8c_i32_i4_e32 v38, v123, v49
	v_dot8c_i32_i4_e32 v39, v123, v47
	v_dot8c_i32_i4_e32 v40, v125, v49
	v_dot8c_i32_i4_e32 v41, v125, v47
	v_dot8c_i32_i4_e32 v42, v127, v49
	v_dot8c_i32_i4_e32 v43, v127, v47
	v_dot8c_i32_i4_e32 v44, v129, v49
	v_dot8c_i32_i4_e32 v45, v129, v47
	v_and_b32_e32 v78, 0xffff, v32
	v_lshrrev_b32_e32 v79, 16, v32
	v_lshl_add_u32 v78, v78, 7, v152
	v_lshl_add_u32 v79, v79, 7, v153
	s_mov_b32 m0, s78
	s_add_i32 s43, s78, 0x400
	global_load_lds_dwordx4 v78, s[50:51]
	s_mov_b32 m0, s43
	s_nop 0
	global_load_lds_dwordx4 v79, s[50:51]
	s_waitcnt vmcnt(9)
	v_add_u32_e32 v54, s98, v59
	v_add_u32_e32 v55, s98, v60
	v_add_u32_e32 v56, s98, v61
	v_add_u32_e32 v57, s98, v62
	ds_read_b64_tr_b4 v[46:47], v160 offset:256
	ds_read_b64_tr_b4 v[48:49], v160 offset:1280
	ds_read_b64_tr_b4 v[122:123], v54
	ds_read_b64_tr_b4 v[124:125], v55
	ds_read_b64_tr_b4 v[126:127], v56
	ds_read_b64_tr_b4 v[128:129], v57
	s_waitcnt lgkmcnt(6)
	v_dot8c_i32_i4_e32 v38, v130, v52
	v_dot8c_i32_i4_e32 v39, v130, v50
	v_dot8c_i32_i4_e32 v40, v132, v52
	v_dot8c_i32_i4_e32 v41, v132, v50
	v_dot8c_i32_i4_e32 v42, v134, v52
	v_dot8c_i32_i4_e32 v43, v134, v50
	v_dot8c_i32_i4_e32 v44, v136, v52
	v_dot8c_i32_i4_e32 v45, v136, v50
	v_dot8c_i32_i4_e32 v38, v131, v53
	v_dot8c_i32_i4_e32 v39, v131, v51
	v_dot8c_i32_i4_e32 v40, v133, v53
	v_dot8c_i32_i4_e32 v41, v133, v51
	v_dot8c_i32_i4_e32 v42, v135, v53
	v_dot8c_i32_i4_e32 v43, v135, v51
	v_dot8c_i32_i4_e32 v44, v137, v53
	v_dot8c_i32_i4_e32 v45, v137, v51
	ds_write_b16 v65, v186
	ds_write_b16_d16_hi v65, v186 offset:128
	ds_write_b16 v65, v187 offset:256
	ds_write_b16_d16_hi v65, v187 offset:384
	ds_write_b16 v65, v188 offset:512
	ds_write_b16_d16_hi v65, v188 offset:640
	ds_write_b16 v65, v189 offset:768
	ds_write_b16_d16_hi v65, v189 offset:896
	ds_write_b16 v65, v190 offset:1024
	ds_write_b16_d16_hi v65, v190 offset:1152
	ds_write_b16 v65, v191 offset:1280
	ds_write_b16_d16_hi v65, v191 offset:1408
	ds_write_b16 v65, v192 offset:1536
	ds_write_b16_d16_hi v65, v192 offset:1664
	ds_write_b16 v65, v193 offset:1792
	ds_write_b16_d16_hi v65, v193 offset:1920
	ds_read_b64 v[202:203], v154
	ds_read_b64 v[204:205], v154 offset:512
	ds_read_b64 v[206:207], v154 offset:1024
	ds_read_b64 v[208:209], v154 offset:1536
	v_and_b32_e32 v78, 0xffff, v33
	v_lshrrev_b32_e32 v79, 16, v33
	v_lshl_add_u32 v78, v78, 7, v152
	v_lshl_add_u32 v79, v79, 7, v153
	s_mov_b32 m0, s79
	s_add_i32 s43, s79, 0x400
	global_load_lds_dwordx4 v78, s[50:51]
	s_mov_b32 m0, s43
	s_nop 0
	global_load_lds_dwordx4 v79, s[50:51]
	s_waitcnt vmcnt(9)
; __device__ __forceinline__ void peer_v_tokens(int j, const LAS unsigned short* EL, const LAS unsigned char* AL  , const LAS float* ASC  , const LAS int* SAL  , ...
;     ...
; #pragma unroll 1
;     for (int it = 0; it < 8; ++it) {
;         const int tl = it * 8 + wave, t = j * 64 + tl;
;         unsigned E[8];
;         { const LAS v4u* ep = (const LAS v4u*)(EL + tl * 128 + 16 * g); const v4u e0 = ep[0], e1 = ep[1];
;           E[0] = e0.x; E[1] = e0.y; E[2] = e0.z; E[3] = e0.w; E[4] = e1.x; E[5] = e1.y; E[6] = e1.z; E[7] = e1.w; }
;         uint2 hv[4]; float4 gv[4];
;         { unsigned ho = (unsigned)t * (D / 4) + (unsigned)lane; asm volatile("" : "+v"(ho)); const uint2* hp = (const uint2*)HB + ho; const float4* gp = (const float4*)fng + lane;
; #pragma unroll
;           for (int jq = 0; jq < 4; ++jq) { hv[jq] = hp[64 * jq]; gv[jq] = gp[64 * jq]; } }
;         VDMA(0, 0); VDMA(1, 1);
; #pragma unroll
;         for (int m = 0; m < 2; ++m) {
;             const int idx = lane + 64 * m, tau = idx >> 4, sr = idx & 15, k = 16 * (sr & 7) + 2 * tau + (sr >> 3);
;             const int aq = (int)*(const LAS signed char*)(AL + tl * 128 + k); const int tq = aq + 8;
;             const unsigned lo = (((unsigned)tq & 15u) ^ 8u) * 0x11111111u, hi = ((unsigned)(tq >> 4) & 15u) * 0x11111111u;
;             typedef unsigned u2v __attribute__((ext_vector_type(2)));
;             u2v l2; l2.x = lo; l2.y = lo; u2v h2; h2.x = hi; h2.y = hi;
;             *(LAS u2v*)(ATL + 8 * idx) = l2; *(LAS u2v*)(ATL + 1024 + 8 * idx) = h2;
;         }
;         const float asc = ASC[tl]; const int sa = SAL[tl];
;         CFENCE();
;         int accH[4], accL[4];
; #pragma unroll
;         for (int st = 0; st < 16; ++st) {
;             const int p = st >> 2, q = st & 3;
;             if (st < 14) VDMA(st + 2, (st + 2) % 3);
;             if (st < 14) asm volatile("s_waitcnt vmcnt(8)" ::: "memory");
;             else if (st == 14) asm volatile("s_waitcnt vmcnt(4)" ::: "memory");
;             else asm volatile("s_waitcnt vmcnt(0)" ::: "memory");
;             if (q == 0) {
; #pragma unroll
;                 for (int r = 0; r < 4; ++r) { accH[r] = 0; accL[r] = 0; } }
; #pragma unroll
;             for (int tp = 0; tp < 2; ++tp) {
;                 const v2i ao = TR4(ATL + (2 * q + tp) * 128 + 8 * s16), ah = TR4(ATL + 1024 + (2 * q + tp) * 128 + 8 * s16);
; #pragma unroll
	v_add_u32_e32 v54, s99, v59
	v_add_u32_e32 v55, s99, v60
	v_add_u32_e32 v56, s99, v61
	v_add_u32_e32 v57, s99, v62
	ds_read_b64_tr_b4 v[50:51], v160 offset:384
	ds_read_b64_tr_b4 v[52:53], v160 offset:1408
	ds_read_b64_tr_b4 v[130:131], v54
	ds_read_b64_tr_b4 v[132:133], v55
	ds_read_b64_tr_b4 v[134:135], v56
	ds_read_b64_tr_b4 v[136:137], v57
	s_waitcnt lgkmcnt(15)
	v_dot8c_i32_i4_e32 v38, v122, v48
	v_dot8c_i32_i4_e32 v39, v122, v46
	v_dot8c_i32_i4_e32 v40, v124, v48
	v_dot8c_i32_i4_e32 v41, v124, v46
	v_dot8c_i32_i4_e32 v42, v126, v48
	v_dot8c_i32_i4_e32 v43, v126, v46
	v_dot8c_i32_i4_e32 v44, v128, v48
	v_dot8c_i32_i4_e32 v45, v128, v46
	v_dot8c_i32_i4_e32 v38, v123, v49
	v_dot8c_i32_i4_e32 v39, v123, v47
	v_dot8c_i32_i4_e32 v40, v125, v49
	v_dot8c_i32_i4_e32 v41, v125, v47
	v_dot8c_i32_i4_e32 v42, v127, v49
	v_dot8c_i32_i4_e32 v43, v127, v47
	v_dot8c_i32_i4_e32 v44, v129, v49
	v_dot8c_i32_i4_e32 v45, v129, v47
	s_waitcnt lgkmcnt(15)
	v_and_b32_e32 v78, 0xffff, v18
	v_lshrrev_b32_e32 v79, 16, v18
	v_lshl_add_u32 v78, v78, 7, v150
	v_lshl_add_u32 v79, v79, 7, v151
	s_mov_b32 m0, s98
	s_add_i32 s43, s98, 0x400
	global_load_lds_dwordx4 v78, s[50:51]
	s_mov_b32 m0, s43
	s_nop 0
	global_load_lds_dwordx4 v79, s[50:51]
	s_waitcnt vmcnt(9)
	v_add_u32_e32 v54, s76, v59
	v_add_u32_e32 v55, s76, v60
	v_add_u32_e32 v56, s76, v61
	v_add_u32_e32 v57, s76, v62
	ds_read_b64_tr_b4 v[46:47], v160 offset:512
	ds_read_b64_tr_b4 v[48:49], v160 offset:1536
	ds_read_b64_tr_b4 v[122:123], v54
	ds_read_b64_tr_b4 v[124:125], v55
	ds_read_b64_tr_b4 v[126:127], v56
	ds_read_b64_tr_b4 v[128:129], v57
	s_waitcnt lgkmcnt(6)
	v_dot8c_i32_i4_e32 v38, v130, v52
	v_dot8c_i32_i4_e32 v39, v130, v50
	v_dot8c_i32_i4_e32 v40, v132, v52
	v_dot8c_i32_i4_e32 v41, v132, v50
	v_dot8c_i32_i4_e32 v42, v134, v52
	v_dot8c_i32_i4_e32 v43, v134, v50
	v_dot8c_i32_i4_e32 v44, v136, v52
	v_dot8c_i32_i4_e32 v45, v136, v50
	v_dot8c_i32_i4_e32 v38, v131, v53
	v_dot8c_i32_i4_e32 v39, v131, v51
	v_dot8c_i32_i4_e32 v40, v133, v53
	v_dot8c_i32_i4_e32 v41, v133, v51
	v_dot8c_i32_i4_e32 v42, v135, v53
	v_dot8c_i32_i4_e32 v43, v135, v51
	v_dot8c_i32_i4_e32 v44, v137, v53
	v_dot8c_i32_i4_e32 v45, v137, v51
	v_and_b32_e32 v78, 0xffff, v19
	v_lshrrev_b32_e32 v79, 16, v19
	v_lshl_add_u32 v78, v78, 7, v150
	v_lshl_add_u32 v79, v79, 7, v151
	s_mov_b32 m0, s99
	s_add_i32 s43, s99, 0x400
	global_load_lds_dwordx4 v78, s[50:51]
	s_mov_b32 m0, s43
	s_nop 0
	global_load_lds_dwordx4 v79, s[50:51]
	s_waitcnt vmcnt(8)
	v_add_u32_e32 v54, s77, v59
	v_add_u32_e32 v55, s77, v60
	v_add_u32_e32 v56, s77, v61
	v_add_u32_e32 v57, s77, v62
	ds_read_b64_tr_b4 v[50:51], v160 offset:640
	ds_read_b64_tr_b4 v[52:53], v160 offset:1664
	ds_read_b64_tr_b4 v[130:131], v54
	ds_read_b64_tr_b4 v[132:133], v55
	ds_read_b64_tr_b4 v[134:135], v56
	ds_read_b64_tr_b4 v[136:137], v57
	s_waitcnt lgkmcnt(6)
	v_dot8c_i32_i4_e32 v38, v122, v48
	v_dot8c_i32_i4_e32 v39, v122, v46
	v_dot8c_i32_i4_e32 v40, v124, v48
	v_dot8c_i32_i4_e32 v41, v124, v46
	v_dot8c_i32_i4_e32 v42, v126, v48
	v_dot8c_i32_i4_e32 v43, v126, v46
	v_dot8c_i32_i4_e32 v44, v128, v48
	v_dot8c_i32_i4_e32 v45, v128, v46
	v_dot8c_i32_i4_e32 v38, v123, v49
	v_dot8c_i32_i4_e32 v39, v123, v47
	v_dot8c_i32_i4_e32 v40, v125, v49
	v_dot8c_i32_i4_e32 v41, v125, v47
	v_dot8c_i32_i4_e32 v42, v127, v49
	v_dot8c_i32_i4_e32 v43, v127, v47
	v_dot8c_i32_i4_e32 v44, v129, v49
	v_dot8c_i32_i4_e32 v45, v129, v47
	s_waitcnt lgkmcnt(15)
	v_add_u32_e32 v143, 8, v139
	v_and_b32_e32 v142, 15, v143
	v_xor_b32_e32 v142, 8, v142
	v_bfe_u32 v144, v143, 4, 4
	v_mul_lo_u32 v142, v142, s92
	v_mul_lo_u32 v144, v144, s92
	v_mov_b32_e32 v143, v142
	v_mov_b32_e32 v145, v144
	ds_write2st64_b64 v159, v[142:143], v[144:145] offset1:2
	v_and_b32_e32 v78, 0xffff, v20
	v_lshrrev_b32_e32 v79, 16, v20
	v_lshl_add_u32 v78, v78, 7, v150
	v_lshl_add_u32 v79, v79, 7, v151
	s_mov_b32 m0, s76
	s_add_i32 s43, s76, 0x400
	global_load_lds_dwordx4 v78, s[50:51]
	s_mov_b32 m0, s43
	s_nop 0
	global_load_lds_dwordx4 v79, s[50:51]
	s_waitcnt vmcnt(8)
	v_add_u32_e32 v54, s78, v59
	v_add_u32_e32 v55, s78, v60
	v_add_u32_e32 v56, s78, v61
	v_add_u32_e32 v57, s78, v62
	ds_read_b64_tr_b4 v[46:47], v160 offset:768
	ds_read_b64_tr_b4 v[48:49], v160 offset:1792
	ds_read_b64_tr_b4 v[122:123], v54
	ds_read_b64_tr_b4 v[124:125], v55
	ds_read_b64_tr_b4 v[126:127], v56
	ds_read_b64_tr_b4 v[128:129], v57
	s_waitcnt lgkmcnt(7)
	v_dot8c_i32_i4_e32 v38, v130, v52
	v_dot8c_i32_i4_e32 v39, v130, v50
	v_dot8c_i32_i4_e32 v40, v132, v52
	v_dot8c_i32_i4_e32 v41, v132, v50
	v_dot8c_i32_i4_e32 v42, v134, v52
	v_dot8c_i32_i4_e32 v43, v134, v50
	v_dot8c_i32_i4_e32 v44, v136, v52
	v_dot8c_i32_i4_e32 v45, v136, v50
	v_dot8c_i32_i4_e32 v38, v131, v53
	v_dot8c_i32_i4_e32 v39, v131, v51
	v_dot8c_i32_i4_e32 v40, v133, v53
	v_dot8c_i32_i4_e32 v41, v133, v51
	v_dot8c_i32_i4_e32 v42, v135, v53
	v_dot8c_i32_i4_e32 v43, v135, v51
	v_dot8c_i32_i4_e32 v44, v137, v53
	v_dot8c_i32_i4_e32 v45, v137, v51
	v_and_b32_e32 v78, 0xffff, v21
	v_lshrrev_b32_e32 v79, 16, v21
	v_lshl_add_u32 v78, v78, 7, v150
	v_lshl_add_u32 v79, v79, 7, v151
	s_mov_b32 m0, s77
	s_add_i32 s43, s77, 0x400
	global_load_lds_dwordx4 v78, s[50:51]
	s_mov_b32 m0, s43
	s_nop 0
	global_load_lds_dwordx4 v79, s[50:51]
	s_waitcnt vmcnt(8)
	v_add_u32_e32 v54, s79, v59
	v_add_u32_e32 v55, s79, v60
	v_add_u32_e32 v56, s79, v61
	v_add_u32_e32 v57, s79, v62
	ds_read_b64_tr_b4 v[50:51], v160 offset:896
	ds_read_b64_tr_b4 v[52:53], v160 offset:1920
	ds_read_b64_tr_b4 v[130:131], v54
	ds_read_b64_tr_b4 v[132:133], v55
	ds_read_b64_tr_b4 v[134:135], v56
	ds_read_b64_tr_b4 v[136:137], v57
	s_waitcnt lgkmcnt(6)
; __device__ __forceinline__ void peer_v_tokens(int j, const LAS unsigned short* EL, const LAS unsigned char* AL  , const LAS float* ASC  , const LAS int* SAL  , ...
;     ...
;         for (int st = 0; st < 16; ++st) {
;             const int p = st >> 2, q = st & 3;
;             if (st < 14) VDMA(st + 2, (st + 2) % 3);
;             if (st < 14) asm volatile("s_waitcnt vmcnt(8)" ::: "memory");
;             else if (st == 14) asm volatile("s_waitcnt vmcnt(4)" ::: "memory");
;             else asm volatile("s_waitcnt vmcnt(0)" ::: "memory");
;             if (q == 0) {
; #pragma unroll
;                 for (int r = 0; r < 4; ++r) { accH[r] = 0; accL[r] = 0; } }
; #pragma unroll
;             for (int tp = 0; tp < 2; ++tp) {
;                 const v2i ao = TR4(ATL + (2 * q + tp) * 128 + 8 * s16), ah = TR4(ATL + 1024 + (2 * q + tp) * 128 + 8 * s16);
; #pragma unroll
;                 for (int r = 0; r < 4; ++r) {
;                     const v2i d = TR4(ldsb + BUF[st % 3] + 2048 * tp + roff[r]);
;                     accH[r] = __builtin_amdgcn_sdot8(d.x, ah.x, accH[r], false); accH[r] = __builtin_amdgcn_sdot8(d.y, ah.y, accH[r], false);
;                     accL[r] = __builtin_amdgcn_sdot8(d.x, ao.x, accL[r], false); accL[r] = __builtin_amdgcn_sdot8(d.y, ao.y, accL[r], false);
;                 }
;             }
;             asm volatile("s_waitcnt lgkmcnt(0)" ::: "memory");
;             if (q == 3) {
; #pragma unroll
;                 for (int r = 0; r < 4; ++r) STASH[256 * p + 16 * (grp + 4 * r) + pc] = f2bf(asc * (float)(2 * ((accH[r] << 4) + accL[r]) + sa));
;             }
;         }
;         CFENCE();
;         {
;             float4 v[4]; float ss = 0.f;
; #pragma unroll
;             for (int jq = 0; jq < 4; ++jq) { typedef unsigned u2v __attribute__((ext_vector_type(2))); const u2v pw = *(const LAS u2v*)(STASH + 4 * lane + 256 * jq); const uint2 hw = hv[jq];
;                 v[jq] = make_float4(__uint_as_float(hw.x << 16) + __uint_as_float(pw.x << 16), __uint_as_float(hw.x & 0xffff0000u) + __uint_as_float(pw.x & 0xffff0000u),
;                                     __uint_as_float(hw.y << 16) + __uint_as_float(pw.y << 16), __uint_as_float(hw.y & 0xffff0000u) + __uint_as_float(pw.y & 0xffff0000u));
;                 ss += v[jq].x * v[jq].x + v[jq].y * v[jq].y + v[jq].z * v[jq].z + v[jq].w * v[jq].w; }
;             ss = wave_sum(ss);
	v_dot8c_i32_i4_e32 v38, v122, v48
	v_dot8c_i32_i4_e32 v39, v122, v46
	v_dot8c_i32_i4_e32 v40, v124, v48
	v_dot8c_i32_i4_e32 v41, v124, v46
	v_dot8c_i32_i4_e32 v42, v126, v48
	v_dot8c_i32_i4_e32 v43, v126, v46
	v_dot8c_i32_i4_e32 v44, v128, v48
	v_dot8c_i32_i4_e32 v45, v128, v46
	v_dot8c_i32_i4_e32 v38, v123, v49
	v_dot8c_i32_i4_e32 v39, v123, v47
	v_dot8c_i32_i4_e32 v40, v125, v49
	v_dot8c_i32_i4_e32 v41, v125, v47
	v_dot8c_i32_i4_e32 v42, v127, v49
	v_dot8c_i32_i4_e32 v43, v127, v47
	v_dot8c_i32_i4_e32 v44, v129, v49
	v_dot8c_i32_i4_e32 v45, v129, v47
	v_and_b32_e32 v78, 0xffff, v22
	v_lshrrev_b32_e32 v79, 16, v22
	v_lshl_add_u32 v78, v78, 7, v150
	v_lshl_add_u32 v79, v79, 7, v151
	s_mov_b32 m0, s78
	s_add_i32 s43, s78, 0x400
	global_load_lds_dwordx4 v78, s[50:51]
	s_mov_b32 m0, s43
	s_nop 0
	global_load_lds_dwordx4 v79, s[50:51]
	s_waitcnt vmcnt(8)
	v_add_u32_e32 v54, s98, v59
	v_add_u32_e32 v55, s98, v60
	v_add_u32_e32 v56, s98, v61
	v_add_u32_e32 v57, s98, v62
	ds_read_b64_tr_b4 v[46:47], v160
	ds_read_b64_tr_b4 v[48:49], v160 offset:1024
	ds_read_b64_tr_b4 v[122:123], v54
	ds_read_b64_tr_b4 v[124:125], v55
	ds_read_b64_tr_b4 v[126:127], v56
	ds_read_b64_tr_b4 v[128:129], v57
	s_waitcnt lgkmcnt(6)
	v_dot8c_i32_i4_e32 v38, v130, v52
	v_dot8c_i32_i4_e32 v39, v130, v50
	v_dot8c_i32_i4_e32 v40, v132, v52
	v_dot8c_i32_i4_e32 v41, v132, v50
	v_dot8c_i32_i4_e32 v42, v134, v52
	v_dot8c_i32_i4_e32 v43, v134, v50
	v_dot8c_i32_i4_e32 v44, v136, v52
	v_dot8c_i32_i4_e32 v45, v136, v50
	v_dot8c_i32_i4_e32 v38, v131, v53
	v_dot8c_i32_i4_e32 v39, v131, v51
	v_dot8c_i32_i4_e32 v40, v133, v53
	v_dot8c_i32_i4_e32 v41, v133, v51
	v_dot8c_i32_i4_e32 v42, v135, v53
	v_dot8c_i32_i4_e32 v43, v135, v51
	v_dot8c_i32_i4_e32 v44, v137, v53
	v_dot8c_i32_i4_e32 v45, v137, v51
	s_nop 3
	s_waitcnt lgkmcnt(15)
	v_lshlrev_b32_e32 v38, 5, v38
	v_lshlrev_b32_e32 v39, 1, v39
	v_add3_u32 v38, v39, v229, v38
	v_cvt_f32_i32_e32 v38, v38
	v_mul_f32_e32 v38, v228, v38
	v_lshlrev_b32_e32 v40, 5, v40
	v_lshlrev_b32_e32 v41, 1, v41
	v_add3_u32 v40, v41, v229, v40
	v_cvt_f32_i32_e32 v40, v40
	v_mul_f32_e32 v40, v228, v40
	v_lshlrev_b32_e32 v42, 5, v42
	v_lshlrev_b32_e32 v43, 1, v43
	v_add3_u32 v42, v43, v229, v42
	v_cvt_f32_i32_e32 v42, v42
	v_mul_f32_e32 v42, v228, v42
	v_lshlrev_b32_e32 v44, 5, v44
	v_lshlrev_b32_e32 v45, 1, v45
	v_add3_u32 v44, v45, v229, v44
	v_cvt_f32_i32_e32 v44, v44
	v_mul_f32_e32 v44, v228, v44
	v_cvt_pk_bf16_f32 v172, v38, v40
	v_cvt_pk_bf16_f32 v173, v42, v44
	ds_read_b128 v[252:255], v156
	s_add_i32 s44, s40, 16
	s_ashr_i32 s45, s44, 31
	s_lshl_b64 s[44:45], s[44:45], 12
	v_lshl_add_u64 v[80:81], v[36:37], 0, s[44:45]
	s_waitcnt lgkmcnt(0)
	v_mul_f32_e32 v218, v218, v252
	v_mul_f32_e32 v219, v219, v253
	v_mul_f32_e32 v220, v220, v254
	v_mul_f32_e32 v221, v221, v255
	global_store_dwordx4 v[80:81], v[218:221], off offset:2048 sc1
	v_add_u32_e32 v147, 8, v140
	v_and_b32_e32 v146, 15, v147
	v_xor_b32_e32 v146, 8, v146
	v_bfe_u32 v148, v147, 4, 4
	v_mul_lo_u32 v146, v146, s92
	v_mul_lo_u32 v148, v148, s92
	v_mov_b32_e32 v147, v146
	v_mov_b32_e32 v149, v148
	ds_write2st64_b64 v77, v[146:147], v[148:149] offset1:2
	v_add_u32_e32 v138, 0x1400, v74
	ds_read_u8 v139, v138
	v_add_u32_e32 v141, 0x1400, v73
	ds_read_u8 v140, v141
	s_add_i32 s43, s67, 128
	v_mov_b32_e32 v138, s43
	ds_read2st64_b32 v[228:229], v138 offset1:1
	ds_read_b128 v[26:29], v227 offset:10240
	ds_read_b128 v[30:33], v227 offset:10256
	v_mov_b32_e32 v38, 0
	v_mov_b32_e32 v39, 0
	v_mov_b32_e32 v40, 0
	v_mov_b32_e32 v41, 0
	v_mov_b32_e32 v42, 0
	v_mov_b32_e32 v43, 0
	v_mov_b32_e32 v44, 0
	v_mov_b32_e32 v45, 0
	v_and_b32_e32 v78, 0xffff, v23
	v_lshrrev_b32_e32 v79, 16, v23
	v_lshl_add_u32 v78, v78, 7, v150
	v_lshl_add_u32 v79, v79, 7, v151
	s_mov_b32 m0, s79
	s_add_i32 s43, s79, 0x400
	global_load_lds_dwordx4 v78, s[50:51]
	s_mov_b32 m0, s43
	s_nop 0
	global_load_lds_dwordx4 v79, s[50:51]
	s_waitcnt vmcnt(9)
	v_add_u32_e32 v54, s99, v59
	v_add_u32_e32 v55, s99, v60
	v_add_u32_e32 v56, s99, v61
	v_add_u32_e32 v57, s99, v62
	ds_read_b64_tr_b4 v[50:51], v160 offset:128
	ds_read_b64_tr_b4 v[52:53], v160 offset:1152
	ds_read_b64_tr_b4 v[130:131], v54
	ds_read_b64_tr_b4 v[132:133], v55
	ds_read_b64_tr_b4 v[134:135], v56
	ds_read_b64_tr_b4 v[136:137], v57
	s_waitcnt lgkmcnt(13)
	s_waitcnt vmcnt(36) lgkmcnt(15)
; #define LAS __attribute__((address_space(3)))
; #define TR4(p_) __builtin_amdgcn_ds_read_tr4_b64_v2i32((LAS v2i*)(p_))
; __device__ __forceinline__ void peer_v_tokens(int j, const LAS unsigned short* EL, const LAS unsigned char* AL  , const LAS float* ASC  , const LAS int* SAL  , ...
;     ...
; #pragma unroll
;             for (int tp = 0; tp < 2; ++tp) {
;                 const v2i ao = TR4(ATL + (2 * q + tp) * 128 + 8 * s16), ah = TR4(ATL + 1024 + (2 * q + tp) * 128 + 8 * s16);
; #pragma unroll
;                 for (int r = 0; r < 4; ++r) {
;                     const v2i d = TR4(ldsb + BUF[st % 3] + 2048 * tp + roff[r]);
;                     accH[r] = __builtin_amdgcn_sdot8(d.x, ah.x, accH[r], false); accH[r] = __builtin_amdgcn_sdot8(d.y, ah.y, accH[r], false);
;                     accL[r] = __builtin_amdgcn_sdot8(d.x, ao.x, accL[r], false); accL[r] = __builtin_amdgcn_sdot8(d.y, ao.y, accL[r], false);
;                 }
;     ...
;         {
;             float4 v[4]; float ss = 0.f;
; #pragma unroll
;             for (int jq = 0; jq < 4; ++jq) { typedef unsigned u2v __attribute__((ext_vector_type(2))); const u2v pw = *(const LAS u2v*)(STASH + 4 * lane + 256 * jq); const uint2 hw = hv[jq];
;                 v[jq] = make_float4(__uint_as_float(hw.x << 16) + __uint_as_float(pw.x << 16), __uint_as_float(hw.x & 0xffff0000u) + __uint_as_float(pw.x & 0xffff0000u),
;                                     __uint_as_float(hw.y << 16) + __uint_as_float(pw.y << 16), __uint_as_float(hw.y & 0xffff0000u) + __uint_as_float(pw.y & 0xffff0000u));
;                 ss += v[jq].x * v[jq].x + v[jq].y * v[jq].y + v[jq].z * v[jq].z + v[jq].w * v[jq].w; }
;             ss = wave_sum(ss);
;             const float r3 = rsqrtf(ss * (1.f / D) + EPS);
	v_lshlrev_b32_e32 v236, 16, v194
	v_and_b32_e32 v237, 0xffff0000, v194
	v_lshlrev_b32_e32 v142, 16, v202
	v_and_b32_e32 v143, 0xffff0000, v202
	v_add_f32_e32 v236, v236, v142
	v_add_f32_e32 v237, v237, v143
	v_lshlrev_b32_e32 v238, 16, v195
	v_and_b32_e32 v239, 0xffff0000, v195
	v_lshlrev_b32_e32 v142, 16, v203
	v_and_b32_e32 v143, 0xffff0000, v203
	v_add_f32_e32 v238, v238, v142
	v_add_f32_e32 v239, v239, v143
	v_lshlrev_b32_e32 v240, 16, v196
	v_and_b32_e32 v241, 0xffff0000, v196
	v_lshlrev_b32_e32 v142, 16, v204
	v_and_b32_e32 v143, 0xffff0000, v204
	v_add_f32_e32 v240, v240, v142
	v_add_f32_e32 v241, v241, v143
	v_lshlrev_b32_e32 v242, 16, v197
	v_and_b32_e32 v243, 0xffff0000, v197
	v_lshlrev_b32_e32 v142, 16, v205
	v_and_b32_e32 v143, 0xffff0000, v205
	v_add_f32_e32 v242, v242, v142
	v_add_f32_e32 v243, v243, v143
	v_lshlrev_b32_e32 v244, 16, v198
	v_and_b32_e32 v245, 0xffff0000, v198
	v_lshlrev_b32_e32 v142, 16, v206
	v_and_b32_e32 v143, 0xffff0000, v206
	v_add_f32_e32 v244, v244, v142
	v_add_f32_e32 v245, v245, v143
	v_lshlrev_b32_e32 v246, 16, v199
	v_and_b32_e32 v247, 0xffff0000, v199
	v_lshlrev_b32_e32 v142, 16, v207
	v_and_b32_e32 v143, 0xffff0000, v207
	v_add_f32_e32 v246, v246, v142
	v_add_f32_e32 v247, v247, v143
	v_lshlrev_b32_e32 v248, 16, v200
	v_and_b32_e32 v249, 0xffff0000, v200
	v_lshlrev_b32_e32 v142, 16, v208
	v_and_b32_e32 v143, 0xffff0000, v208
	v_add_f32_e32 v248, v248, v142
	v_add_f32_e32 v249, v249, v143
	v_lshlrev_b32_e32 v250, 16, v201
	v_and_b32_e32 v251, 0xffff0000, v201
	v_lshlrev_b32_e32 v142, 16, v209
	v_and_b32_e32 v143, 0xffff0000, v209
	v_add_f32_e32 v250, v250, v142
	v_add_f32_e32 v251, v251, v143
	v_mov_b32_e32 v144, 0
	v_mul_f32_e32 v145, v236, v236
	v_fmac_f32_e32 v145, v237, v237
	v_fmac_f32_e32 v145, v238, v238
	v_fmac_f32_e32 v145, v239, v239
	v_add_f32_e32 v144, v144, v145
	v_mul_f32_e32 v145, v240, v240
	v_fmac_f32_e32 v145, v241, v241
	v_fmac_f32_e32 v145, v242, v242
	v_fmac_f32_e32 v145, v243, v243
	v_add_f32_e32 v144, v144, v145
	v_mul_f32_e32 v145, v244, v244
	v_fmac_f32_e32 v145, v245, v245
	v_fmac_f32_e32 v145, v246, v246
	v_fmac_f32_e32 v145, v247, v247
	v_add_f32_e32 v144, v144, v145
	v_mul_f32_e32 v145, v248, v248
	v_fmac_f32_e32 v145, v249, v249
	v_fmac_f32_e32 v145, v250, v250
	v_fmac_f32_e32 v145, v251, v251
	v_add_f32_e32 v144, v144, v145
	s_nop 1
	v_add_f32_dpp v144, v144, v144 quad_perm:[1,0,3,2] row_mask:0xf bank_mask:0xf bound_ctrl:1
	s_nop 1
	v_add_f32_dpp v144, v144, v144 quad_perm:[2,3,0,1] row_mask:0xf bank_mask:0xf bound_ctrl:1
	s_nop 1
	v_add_f32_dpp v144, v144, v144 row_half_mirror row_mask:0xf bank_mask:0xf bound_ctrl:1
	s_nop 1
	v_add_f32_dpp v144, v144, v144 row_mirror row_mask:0xf bank_mask:0xf bound_ctrl:1
	s_nop 1
	v_readlane_b32 s10, v144, 0
	v_readlane_b32 s11, v144, 16
	v_readlane_b32 s14, v144, 32
	v_readlane_b32 s15, v144, 48
	s_nop 3
	v_mov_b32_e32 v144, s11
	v_mov_b32_e32 v145, s15
	v_add_f32_e32 v144, s10, v144
	v_add_f32_e32 v145, s14, v145
	v_add_f32_e32 v144, v144, v145
	v_fmamk_f32 v144, v144, 0x3a800000, v111
	v_rsq_f32_e32 v144, v144
	s_nop 0
	v_mul_f32_e32 v236, v236, v144
	v_mul_f32_e32 v237, v237, v144
	v_mul_f32_e32 v238, v238, v144
	v_mul_f32_e32 v239, v239, v144
	v_mul_f32_e32 v240, v240, v144
	v_mul_f32_e32 v241, v241, v144
	v_mul_f32_e32 v242, v242, v144
	v_mul_f32_e32 v243, v243, v144
	v_mul_f32_e32 v244, v244, v144
	v_mul_f32_e32 v245, v245, v144
	v_mul_f32_e32 v246, v246, v144
	v_mul_f32_e32 v247, v247, v144
	v_mul_f32_e32 v248, v248, v144
	v_mul_f32_e32 v249, v249, v144
	v_mul_f32_e32 v250, v250, v144
	v_mul_f32_e32 v251, v251, v144
	v_dot8c_i32_i4_e32 v38, v122, v48
	v_dot8c_i32_i4_e32 v39, v122, v46
	v_dot8c_i32_i4_e32 v40, v124, v48
	v_dot8c_i32_i4_e32 v41, v124, v46
	v_dot8c_i32_i4_e32 v42, v126, v48
	v_dot8c_i32_i4_e32 v43, v126, v46
	v_dot8c_i32_i4_e32 v44, v128, v48
	v_dot8c_i32_i4_e32 v45, v128, v46
	v_dot8c_i32_i4_e32 v38, v123, v49
	v_dot8c_i32_i4_e32 v39, v123, v47
	v_dot8c_i32_i4_e32 v40, v125, v49
	v_dot8c_i32_i4_e32 v41, v125, v47
	v_dot8c_i32_i4_e32 v42, v127, v49
	v_dot8c_i32_i4_e32 v43, v127, v47
	v_dot8c_i32_i4_e32 v44, v129, v49
	v_dot8c_i32_i4_e32 v45, v129, v47
	v_and_b32_e32 v78, 0xffff, v24
	v_lshrrev_b32_e32 v79, 16, v24
	v_lshl_add_u32 v78, v78, 7, v150
	v_lshl_add_u32 v79, v79, 7, v151
	s_mov_b32 m0, s98
	s_add_i32 s43, s98, 0x400
	global_load_lds_dwordx4 v78, s[50:51]
	s_mov_b32 m0, s43
	s_nop 0
	global_load_lds_dwordx4 v79, s[50:51]
	s_waitcnt vmcnt(9)
	v_add_u32_e32 v54, s76, v59
	v_add_u32_e32 v55, s76, v60
	v_add_u32_e32 v56, s76, v61
	v_add_u32_e32 v57, s76, v62
	ds_read_b64_tr_b4 v[46:47], v160 offset:256
	ds_read_b64_tr_b4 v[48:49], v160 offset:1280
	ds_read_b64_tr_b4 v[122:123], v54
	ds_read_b64_tr_b4 v[124:125], v55
	ds_read_b64_tr_b4 v[126:127], v56
	ds_read_b64_tr_b4 v[128:129], v57
	s_waitcnt lgkmcnt(6)
	v_dot8c_i32_i4_e32 v38, v130, v52
	v_dot8c_i32_i4_e32 v39, v130, v50
	v_dot8c_i32_i4_e32 v40, v132, v52
	v_dot8c_i32_i4_e32 v41, v132, v50
	v_dot8c_i32_i4_e32 v42, v134, v52
	v_dot8c_i32_i4_e32 v43, v134, v50
	v_dot8c_i32_i4_e32 v44, v136, v52
	v_dot8c_i32_i4_e32 v45, v136, v50
	v_dot8c_i32_i4_e32 v38, v131, v53
	v_dot8c_i32_i4_e32 v39, v131, v51
	v_dot8c_i32_i4_e32 v40, v133, v53
	v_dot8c_i32_i4_e32 v41, v133, v51
	v_dot8c_i32_i4_e32 v42, v135, v53
	v_dot8c_i32_i4_e32 v43, v135, v51
	v_dot8c_i32_i4_e32 v44, v137, v53
	v_dot8c_i32_i4_e32 v45, v137, v51
	v_and_b32_e32 v78, 0xffff, v25
	v_lshrrev_b32_e32 v79, 16, v25
	v_lshl_add_u32 v78, v78, 7, v150
	v_lshl_add_u32 v79, v79, 7, v151
	s_mov_b32 m0, s99
	s_add_i32 s43, s99, 0x400
	global_load_lds_dwordx4 v78, s[50:51]
	s_mov_b32 m0, s43
	s_nop 0
	global_load_lds_dwordx4 v79, s[50:51]
	s_waitcnt vmcnt(9)
; __device__ __forceinline__ void peer_v_tokens(int j, const LAS unsigned short* EL, const LAS unsigned char* AL  , const LAS float* ASC  , const LAS int* SAL  , ...
;     ...
; #pragma unroll 1
;     for (int it = 0; it < 8; ++it) {
;         const int tl = it * 8 + wave, t = j * 64 + tl;
;         unsigned E[8];
;         { const LAS v4u* ep = (const LAS v4u*)(EL + tl * 128 + 16 * g); const v4u e0 = ep[0], e1 = ep[1];
;           E[0] = e0.x; E[1] = e0.y; E[2] = e0.z; E[3] = e0.w; E[4] = e1.x; E[5] = e1.y; E[6] = e1.z; E[7] = e1.w; }
;         uint2 hv[4]; float4 gv[4];
;         { unsigned ho = (unsigned)t * (D / 4) + (unsigned)lane; asm volatile("" : "+v"(ho)); const uint2* hp = (const uint2*)HB + ho; const float4* gp = (const float4*)fng + lane;
; #pragma unroll
;           for (int jq = 0; jq < 4; ++jq) { hv[jq] = hp[64 * jq]; gv[jq] = gp[64 * jq]; } }
;         VDMA(0, 0); VDMA(1, 1);
; #pragma unroll
;         for (int m = 0; m < 2; ++m) {
;             const int idx = lane + 64 * m, tau = idx >> 4, sr = idx & 15, k = 16 * (sr & 7) + 2 * tau + (sr >> 3);
;             const int aq = (int)*(const LAS signed char*)(AL + tl * 128 + k); const int tq = aq + 8;
;             const unsigned lo = (((unsigned)tq & 15u) ^ 8u) * 0x11111111u, hi = ((unsigned)(tq >> 4) & 15u) * 0x11111111u;
;             typedef unsigned u2v __attribute__((ext_vector_type(2)));
;             u2v l2; l2.x = lo; l2.y = lo; u2v h2; h2.x = hi; h2.y = hi;
;             *(LAS u2v*)(ATL + 8 * idx) = l2; *(LAS u2v*)(ATL + 1024 + 8 * idx) = h2;
;         }
;         const float asc = ASC[tl]; const int sa = SAL[tl];
;         CFENCE();
;         int accH[4], accL[4];
; #pragma unroll
;         for (int st = 0; st < 16; ++st) {
;             const int p = st >> 2, q = st & 3;
;             if (st < 14) VDMA(st + 2, (st + 2) % 3);
;             if (st < 14) asm volatile("s_waitcnt vmcnt(8)" ::: "memory");
;             else if (st == 14) asm volatile("s_waitcnt vmcnt(4)" ::: "memory");
;             else asm volatile("s_waitcnt vmcnt(0)" ::: "memory");
;             if (q == 0) {
; #pragma unroll
;                 for (int r = 0; r < 4; ++r) { accH[r] = 0; accL[r] = 0; } }
; #pragma unroll
;             for (int tp = 0; tp < 2; ++tp) {
;                 const v2i ao = TR4(ATL + (2 * q + tp) * 128 + 8 * s16), ah = TR4(ATL + 1024 + (2 * q + tp) * 128 + 8 * s16);
; #pragma unroll
	v_add_u32_e32 v54, s77, v59
	v_add_u32_e32 v55, s77, v60
	v_add_u32_e32 v56, s77, v61
	v_add_u32_e32 v57, s77, v62
	ds_read_b64_tr_b4 v[50:51], v160 offset:384
	ds_read_b64_tr_b4 v[52:53], v160 offset:1408
	ds_read_b64_tr_b4 v[130:131], v54
	ds_read_b64_tr_b4 v[132:133], v55
	ds_read_b64_tr_b4 v[134:135], v56
	ds_read_b64_tr_b4 v[136:137], v57
	s_waitcnt lgkmcnt(6)
	v_dot8c_i32_i4_e32 v38, v122, v48
	v_dot8c_i32_i4_e32 v39, v122, v46
	v_dot8c_i32_i4_e32 v40, v124, v48
	v_dot8c_i32_i4_e32 v41, v124, v46
	v_dot8c_i32_i4_e32 v42, v126, v48
	v_dot8c_i32_i4_e32 v43, v126, v46
	v_dot8c_i32_i4_e32 v44, v128, v48
	v_dot8c_i32_i4_e32 v45, v128, v46
	v_dot8c_i32_i4_e32 v38, v123, v49
	v_dot8c_i32_i4_e32 v39, v123, v47
	v_dot8c_i32_i4_e32 v40, v125, v49
	v_dot8c_i32_i4_e32 v41, v125, v47
	v_dot8c_i32_i4_e32 v42, v127, v49
	v_dot8c_i32_i4_e32 v43, v127, v47
	v_dot8c_i32_i4_e32 v44, v129, v49
	v_dot8c_i32_i4_e32 v45, v129, v47
	s_waitcnt lgkmcnt(15)
	v_and_b32_e32 v78, 0xffff, v26
	v_lshrrev_b32_e32 v79, 16, v26
	v_lshl_add_u32 v78, v78, 7, v150
	v_lshl_add_u32 v79, v79, 7, v151
	s_mov_b32 m0, s76
	s_add_i32 s43, s76, 0x400
	global_load_lds_dwordx4 v78, s[50:51]
	s_mov_b32 m0, s43
	s_nop 0
	global_load_lds_dwordx4 v79, s[50:51]
	s_waitcnt vmcnt(9)
	v_add_u32_e32 v54, s78, v59
	v_add_u32_e32 v55, s78, v60
	v_add_u32_e32 v56, s78, v61
	v_add_u32_e32 v57, s78, v62
	ds_read_b64_tr_b4 v[46:47], v160 offset:512
	ds_read_b64_tr_b4 v[48:49], v160 offset:1536
	ds_read_b64_tr_b4 v[122:123], v54
	ds_read_b64_tr_b4 v[124:125], v55
	ds_read_b64_tr_b4 v[126:127], v56
	ds_read_b64_tr_b4 v[128:129], v57
	s_waitcnt lgkmcnt(6)
	v_dot8c_i32_i4_e32 v38, v130, v52
	v_dot8c_i32_i4_e32 v39, v130, v50
	v_dot8c_i32_i4_e32 v40, v132, v52
	v_dot8c_i32_i4_e32 v41, v132, v50
	v_dot8c_i32_i4_e32 v42, v134, v52
	v_dot8c_i32_i4_e32 v43, v134, v50
	v_dot8c_i32_i4_e32 v44, v136, v52
	v_dot8c_i32_i4_e32 v45, v136, v50
	v_dot8c_i32_i4_e32 v38, v131, v53
	v_dot8c_i32_i4_e32 v39, v131, v51
	v_dot8c_i32_i4_e32 v40, v133, v53
	v_dot8c_i32_i4_e32 v41, v133, v51
	v_dot8c_i32_i4_e32 v42, v135, v53
	v_dot8c_i32_i4_e32 v43, v135, v51
	v_dot8c_i32_i4_e32 v44, v137, v53
	v_dot8c_i32_i4_e32 v45, v137, v51
	v_and_b32_e32 v78, 0xffff, v27
	v_lshrrev_b32_e32 v79, 16, v27
	v_lshl_add_u32 v78, v78, 7, v150
	v_lshl_add_u32 v79, v79, 7, v151
	s_mov_b32 m0, s77
	s_add_i32 s43, s77, 0x400
	global_load_lds_dwordx4 v78, s[50:51]
	s_mov_b32 m0, s43
	s_nop 0
	global_load_lds_dwordx4 v79, s[50:51]
	s_waitcnt vmcnt(8)
	v_add_u32_e32 v54, s79, v59
	v_add_u32_e32 v55, s79, v60
	v_add_u32_e32 v56, s79, v61
	v_add_u32_e32 v57, s79, v62
	ds_read_b64_tr_b4 v[50:51], v160 offset:640
	ds_read_b64_tr_b4 v[52:53], v160 offset:1664
	ds_read_b64_tr_b4 v[130:131], v54
	ds_read_b64_tr_b4 v[132:133], v55
	ds_read_b64_tr_b4 v[134:135], v56
	ds_read_b64_tr_b4 v[136:137], v57
	s_waitcnt lgkmcnt(6)
	v_dot8c_i32_i4_e32 v38, v122, v48
	v_dot8c_i32_i4_e32 v39, v122, v46
	v_dot8c_i32_i4_e32 v40, v124, v48
	v_dot8c_i32_i4_e32 v41, v124, v46
	v_dot8c_i32_i4_e32 v42, v126, v48
	v_dot8c_i32_i4_e32 v43, v126, v46
	v_dot8c_i32_i4_e32 v44, v128, v48
	v_dot8c_i32_i4_e32 v45, v128, v46
	v_dot8c_i32_i4_e32 v38, v123, v49
	v_dot8c_i32_i4_e32 v39, v123, v47
	v_dot8c_i32_i4_e32 v40, v125, v49
	v_dot8c_i32_i4_e32 v41, v125, v47
	v_dot8c_i32_i4_e32 v42, v127, v49
	v_dot8c_i32_i4_e32 v43, v127, v47
	v_dot8c_i32_i4_e32 v44, v129, v49
	v_dot8c_i32_i4_e32 v45, v129, v47
	s_waitcnt lgkmcnt(15)
	v_add_u32_e32 v143, 8, v139
	v_and_b32_e32 v142, 15, v143
	v_xor_b32_e32 v142, 8, v142
	v_bfe_u32 v144, v143, 4, 4
	v_mul_lo_u32 v142, v142, s92
	v_mul_lo_u32 v144, v144, s92
	v_mov_b32_e32 v143, v142
	v_mov_b32_e32 v145, v144
	ds_write2st64_b64 v159, v[142:143], v[144:145] offset1:2
	v_and_b32_e32 v78, 0xffff, v28
	v_lshrrev_b32_e32 v79, 16, v28
	v_lshl_add_u32 v78, v78, 7, v150
	v_lshl_add_u32 v79, v79, 7, v151
	s_mov_b32 m0, s78
	s_add_i32 s43, s78, 0x400
	global_load_lds_dwordx4 v78, s[50:51]
	s_mov_b32 m0, s43
	s_nop 0
	global_load_lds_dwordx4 v79, s[50:51]
	s_waitcnt vmcnt(8)
	v_add_u32_e32 v54, s98, v59
	v_add_u32_e32 v55, s98, v60
	v_add_u32_e32 v56, s98, v61
	v_add_u32_e32 v57, s98, v62
	ds_read_b64_tr_b4 v[46:47], v160 offset:768
	ds_read_b64_tr_b4 v[48:49], v160 offset:1792
	ds_read_b64_tr_b4 v[122:123], v54
	ds_read_b64_tr_b4 v[124:125], v55
	ds_read_b64_tr_b4 v[126:127], v56
	ds_read_b64_tr_b4 v[128:129], v57
	s_waitcnt lgkmcnt(7)
	v_dot8c_i32_i4_e32 v38, v130, v52
	v_dot8c_i32_i4_e32 v39, v130, v50
	v_dot8c_i32_i4_e32 v40, v132, v52
	v_dot8c_i32_i4_e32 v41, v132, v50
	v_dot8c_i32_i4_e32 v42, v134, v52
	v_dot8c_i32_i4_e32 v43, v134, v50
	v_dot8c_i32_i4_e32 v44, v136, v52
	v_dot8c_i32_i4_e32 v45, v136, v50
	v_dot8c_i32_i4_e32 v38, v131, v53
	v_dot8c_i32_i4_e32 v39, v131, v51
	v_dot8c_i32_i4_e32 v40, v133, v53
	v_dot8c_i32_i4_e32 v41, v133, v51
	v_dot8c_i32_i4_e32 v42, v135, v53
	v_dot8c_i32_i4_e32 v43, v135, v51
	v_dot8c_i32_i4_e32 v44, v137, v53
	v_dot8c_i32_i4_e32 v45, v137, v51
	v_and_b32_e32 v78, 0xffff, v29
	v_lshrrev_b32_e32 v79, 16, v29
	v_lshl_add_u32 v78, v78, 7, v150
	v_lshl_add_u32 v79, v79, 7, v151
	s_mov_b32 m0, s79
	s_add_i32 s43, s79, 0x400
	global_load_lds_dwordx4 v78, s[50:51]
	s_mov_b32 m0, s43
	s_nop 0
	global_load_lds_dwordx4 v79, s[50:51]
	s_waitcnt vmcnt(8)
	v_add_u32_e32 v54, s99, v59
	v_add_u32_e32 v55, s99, v60
	v_add_u32_e32 v56, s99, v61
	v_add_u32_e32 v57, s99, v62
	ds_read_b64_tr_b4 v[50:51], v160 offset:896
	ds_read_b64_tr_b4 v[52:53], v160 offset:1920
	ds_read_b64_tr_b4 v[130:131], v54
	ds_read_b64_tr_b4 v[132:133], v55
	ds_read_b64_tr_b4 v[134:135], v56
	ds_read_b64_tr_b4 v[136:137], v57
	s_waitcnt lgkmcnt(6)
; __device__ __forceinline__ void peer_v_tokens(int j, const LAS unsigned short* EL, const LAS unsigned char* AL  , const LAS float* ASC  , const LAS int* SAL  , ...
;     ...
;         for (int st = 0; st < 16; ++st) {
;             const int p = st >> 2, q = st & 3;
;             if (st < 14) VDMA(st + 2, (st + 2) % 3);
;             if (st < 14) asm volatile("s_waitcnt vmcnt(8)" ::: "memory");
;             else if (st == 14) asm volatile("s_waitcnt vmcnt(4)" ::: "memory");
;             else asm volatile("s_waitcnt vmcnt(0)" ::: "memory");
;             if (q == 0) {
; #pragma unroll
;                 for (int r = 0; r < 4; ++r) { accH[r] = 0; accL[r] = 0; } }
; #pragma unroll
;             for (int tp = 0; tp < 2; ++tp) {
;                 const v2i ao = TR4(ATL + (2 * q + tp) * 128 + 8 * s16), ah = TR4(ATL + 1024 + (2 * q + tp) * 128 + 8 * s16);
; #pragma unroll
;                 for (int r = 0; r < 4; ++r) {
;                     const v2i d = TR4(ldsb + BUF[st % 3] + 2048 * tp + roff[r]);
;                     accH[r] = __builtin_amdgcn_sdot8(d.x, ah.x, accH[r], false); accH[r] = __builtin_amdgcn_sdot8(d.y, ah.y, accH[r], false);
;                     accL[r] = __builtin_amdgcn_sdot8(d.x, ao.x, accL[r], false); accL[r] = __builtin_amdgcn_sdot8(d.y, ao.y, accL[r], false);
;                 }
;             }
;             asm volatile("s_waitcnt lgkmcnt(0)" ::: "memory");
;             if (q == 3) {
; #pragma unroll
;                 for (int r = 0; r < 4; ++r) STASH[256 * p + 16 * (grp + 4 * r) + pc] = f2bf(asc * (float)(2 * ((accH[r] << 4) + accL[r]) + sa));
;             }
;         }
;         CFENCE();
;         {
;             float4 v[4]; float ss = 0.f;
; #pragma unroll
;             for (int jq = 0; jq < 4; ++jq) { typedef unsigned u2v __attribute__((ext_vector_type(2))); const u2v pw = *(const LAS u2v*)(STASH + 4 * lane + 256 * jq); const uint2 hw = hv[jq];
;                 v[jq] = make_float4(__uint_as_float(hw.x << 16) + __uint_as_float(pw.x << 16), __uint_as_float(hw.x & 0xffff0000u) + __uint_as_float(pw.x & 0xffff0000u),
;                                     __uint_as_float(hw.y << 16) + __uint_as_float(pw.y << 16), __uint_as_float(hw.y & 0xffff0000u) + __uint_as_float(pw.y & 0xffff0000u));
;                 ss += v[jq].x * v[jq].x + v[jq].y * v[jq].y + v[jq].z * v[jq].z + v[jq].w * v[jq].w; }
;             ss = wave_sum(ss);
	v_dot8c_i32_i4_e32 v38, v122, v48
	v_dot8c_i32_i4_e32 v39, v122, v46
	v_dot8c_i32_i4_e32 v40, v124, v48
	v_dot8c_i32_i4_e32 v41, v124, v46
	v_dot8c_i32_i4_e32 v42, v126, v48
	v_dot8c_i32_i4_e32 v43, v126, v46
	v_dot8c_i32_i4_e32 v44, v128, v48
	v_dot8c_i32_i4_e32 v45, v128, v46
	v_dot8c_i32_i4_e32 v38, v123, v49
	v_dot8c_i32_i4_e32 v39, v123, v47
	v_dot8c_i32_i4_e32 v40, v125, v49
	v_dot8c_i32_i4_e32 v41, v125, v47
	v_dot8c_i32_i4_e32 v42, v127, v49
	v_dot8c_i32_i4_e32 v43, v127, v47
	v_dot8c_i32_i4_e32 v44, v129, v49
	v_dot8c_i32_i4_e32 v45, v129, v47
	v_and_b32_e32 v78, 0xffff, v30
	v_lshrrev_b32_e32 v79, 16, v30
	v_lshl_add_u32 v78, v78, 7, v150
	v_lshl_add_u32 v79, v79, 7, v151
	s_mov_b32 m0, s98
	s_add_i32 s43, s98, 0x400
	global_load_lds_dwordx4 v78, s[50:51]
	s_mov_b32 m0, s43
	s_nop 0
	global_load_lds_dwordx4 v79, s[50:51]
	s_waitcnt vmcnt(8)
	v_add_u32_e32 v54, s76, v59
	v_add_u32_e32 v55, s76, v60
	v_add_u32_e32 v56, s76, v61
	v_add_u32_e32 v57, s76, v62
	ds_read_b64_tr_b4 v[46:47], v160
	ds_read_b64_tr_b4 v[48:49], v160 offset:1024
	ds_read_b64_tr_b4 v[122:123], v54
	ds_read_b64_tr_b4 v[124:125], v55
	ds_read_b64_tr_b4 v[126:127], v56
	ds_read_b64_tr_b4 v[128:129], v57
	s_waitcnt lgkmcnt(6)
	v_dot8c_i32_i4_e32 v38, v130, v52
	v_dot8c_i32_i4_e32 v39, v130, v50
	v_dot8c_i32_i4_e32 v40, v132, v52
	v_dot8c_i32_i4_e32 v41, v132, v50
	v_dot8c_i32_i4_e32 v42, v134, v52
	v_dot8c_i32_i4_e32 v43, v134, v50
	v_dot8c_i32_i4_e32 v44, v136, v52
	v_dot8c_i32_i4_e32 v45, v136, v50
	v_dot8c_i32_i4_e32 v38, v131, v53
	v_dot8c_i32_i4_e32 v39, v131, v51
	v_dot8c_i32_i4_e32 v40, v133, v53
	v_dot8c_i32_i4_e32 v41, v133, v51
	v_dot8c_i32_i4_e32 v42, v135, v53
	v_dot8c_i32_i4_e32 v43, v135, v51
	v_dot8c_i32_i4_e32 v44, v137, v53
	v_dot8c_i32_i4_e32 v45, v137, v51
	s_nop 3
	s_waitcnt lgkmcnt(15)
	v_lshlrev_b32_e32 v38, 5, v38
	v_lshlrev_b32_e32 v39, 1, v39
	v_add3_u32 v38, v39, v229, v38
	v_cvt_f32_i32_e32 v38, v38
	v_mul_f32_e32 v38, v228, v38
	v_lshlrev_b32_e32 v40, 5, v40
	v_lshlrev_b32_e32 v41, 1, v41
	v_add3_u32 v40, v41, v229, v40
	v_cvt_f32_i32_e32 v40, v40
	v_mul_f32_e32 v40, v228, v40
	v_lshlrev_b32_e32 v42, 5, v42
	v_lshlrev_b32_e32 v43, 1, v43
	v_add3_u32 v42, v43, v229, v42
	v_cvt_f32_i32_e32 v42, v42
	v_mul_f32_e32 v42, v228, v42
	v_lshlrev_b32_e32 v44, 5, v44
	v_lshlrev_b32_e32 v45, 1, v45
	v_add3_u32 v44, v45, v229, v44
	v_cvt_f32_i32_e32 v44, v44
	v_mul_f32_e32 v44, v228, v44
	v_cvt_pk_bf16_f32 v166, v38, v40
	v_cvt_pk_bf16_f32 v167, v42, v44
	ds_read_b128 v[252:255], v156 offset:1024
	s_add_i32 s44, s40, 16
	s_ashr_i32 s45, s44, 31
	s_lshl_b64 s[44:45], s[44:45], 12
	v_lshl_add_u64 v[80:81], v[36:37], 0, s[44:45]
	s_waitcnt lgkmcnt(0)
	v_mul_f32_e32 v222, v222, v252
	v_mul_f32_e32 v223, v223, v253
	v_mul_f32_e32 v224, v224, v254
	v_mul_f32_e32 v225, v225, v255
	global_store_dwordx4 v[80:81], v[222:225], off offset:3072 sc1
	ds_read_b128 v[252:255], v155
	s_add_i32 s44, s40, 24
	s_ashr_i32 s45, s44, 31
	s_lshl_b64 s[44:45], s[44:45], 12
	v_lshl_add_u64 v[80:81], v[36:37], 0, s[44:45]
	s_waitcnt lgkmcnt(0)
	v_mul_f32_e32 v236, v236, v252
	v_mul_f32_e32 v237, v237, v253
	v_mul_f32_e32 v238, v238, v254
	v_mul_f32_e32 v239, v239, v255
	global_store_dwordx4 v[80:81], v[236:239], off sc1
	v_add_u32_e32 v147, 8, v140
	v_and_b32_e32 v146, 15, v147
	v_xor_b32_e32 v146, 8, v146
	v_bfe_u32 v148, v147, 4, 4
	v_mul_lo_u32 v146, v146, s92
	v_mul_lo_u32 v148, v148, s92
	v_mov_b32_e32 v147, v146
	v_mov_b32_e32 v149, v148
	ds_write2st64_b64 v77, v[146:147], v[148:149] offset1:2
	v_add_u32_e32 v138, 0x1000, v74
	ds_read_u8 v139, v138
	v_add_u32_e32 v141, 0x1000, v73
	ds_read_u8 v140, v141
	s_add_i32 s43, s67, 160
	v_mov_b32_e32 v138, s43
	ds_read2st64_b32 v[228:229], v138 offset1:1
	ds_read_b128 v[18:21], v227 offset:8192
	ds_read_b128 v[22:25], v227 offset:8208
	v_add_u32_e32 v152, 0x600000, v63
	v_add_u32_e32 v153, 0x600000, v64
	v_mov_b32_e32 v38, 0
	v_mov_b32_e32 v39, 0
	v_mov_b32_e32 v40, 0
	v_mov_b32_e32 v41, 0
	v_mov_b32_e32 v42, 0
	v_mov_b32_e32 v43, 0
	v_mov_b32_e32 v44, 0
	v_mov_b32_e32 v45, 0
	v_and_b32_e32 v78, 0xffff, v31
	v_lshrrev_b32_e32 v79, 16, v31
	v_lshl_add_u32 v78, v78, 7, v150
	v_lshl_add_u32 v79, v79, 7, v151
	s_mov_b32 m0, s99
	s_add_i32 s43, s99, 0x400
	global_load_lds_dwordx4 v78, s[50:51]
	s_mov_b32 m0, s43
	s_nop 0
	global_load_lds_dwordx4 v79, s[50:51]
	s_waitcnt vmcnt(10)
	v_add_u32_e32 v54, s77, v59
	v_add_u32_e32 v55, s77, v60
	v_add_u32_e32 v56, s77, v61
	v_add_u32_e32 v57, s77, v62
	ds_read_b64_tr_b4 v[50:51], v160 offset:128
	ds_read_b64_tr_b4 v[52:53], v160 offset:1152
	ds_read_b64_tr_b4 v[130:131], v54
	ds_read_b64_tr_b4 v[132:133], v55
	ds_read_b64_tr_b4 v[134:135], v56
	ds_read_b64_tr_b4 v[136:137], v57
	s_waitcnt lgkmcnt(14)
	v_dot8c_i32_i4_e32 v38, v122, v48
	v_dot8c_i32_i4_e32 v39, v122, v46
	v_dot8c_i32_i4_e32 v40, v124, v48
	v_dot8c_i32_i4_e32 v41, v124, v46
	v_dot8c_i32_i4_e32 v42, v126, v48
	v_dot8c_i32_i4_e32 v43, v126, v46
	v_dot8c_i32_i4_e32 v44, v128, v48
	v_dot8c_i32_i4_e32 v45, v128, v46
	v_dot8c_i32_i4_e32 v38, v123, v49
	v_dot8c_i32_i4_e32 v39, v123, v47
	v_dot8c_i32_i4_e32 v40, v125, v49
	v_dot8c_i32_i4_e32 v41, v125, v47
	v_dot8c_i32_i4_e32 v42, v127, v49
	v_dot8c_i32_i4_e32 v43, v127, v47
	v_dot8c_i32_i4_e32 v44, v129, v49
	v_dot8c_i32_i4_e32 v45, v129, v47
	v_and_b32_e32 v78, 0xffff, v32
	v_lshrrev_b32_e32 v79, 16, v32
	v_lshl_add_u32 v78, v78, 7, v150
	v_lshl_add_u32 v79, v79, 7, v151
	s_mov_b32 m0, s76
	s_add_i32 s43, s76, 0x400
	global_load_lds_dwordx4 v78, s[50:51]
	s_mov_b32 m0, s43
	s_nop 0
	global_load_lds_dwordx4 v79, s[50:51]
	s_waitcnt vmcnt(10)
; __device__ __forceinline__ void peer_v_tokens(int j, const LAS unsigned short* EL, const LAS unsigned char* AL  , const LAS float* ASC  , const LAS int* SAL  , ...
;     ...
; #pragma unroll 1
;     for (int it = 0; it < 8; ++it) {
;         const int tl = it * 8 + wave, t = j * 64 + tl;
;         unsigned E[8];
;         { const LAS v4u* ep = (const LAS v4u*)(EL + tl * 128 + 16 * g); const v4u e0 = ep[0], e1 = ep[1];
;           E[0] = e0.x; E[1] = e0.y; E[2] = e0.z; E[3] = e0.w; E[4] = e1.x; E[5] = e1.y; E[6] = e1.z; E[7] = e1.w; }
;         uint2 hv[4]; float4 gv[4];
;         { unsigned ho = (unsigned)t * (D / 4) + (unsigned)lane; asm volatile("" : "+v"(ho)); const uint2* hp = (const uint2*)HB + ho; const float4* gp = (const float4*)fng + lane;
; #pragma unroll
;           for (int jq = 0; jq < 4; ++jq) { hv[jq] = hp[64 * jq]; gv[jq] = gp[64 * jq]; } }
;         VDMA(0, 0); VDMA(1, 1);
; #pragma unroll
;         for (int m = 0; m < 2; ++m) {
;             const int idx = lane + 64 * m, tau = idx >> 4, sr = idx & 15, k = 16 * (sr & 7) + 2 * tau + (sr >> 3);
;             const int aq = (int)*(const LAS signed char*)(AL + tl * 128 + k); const int tq = aq + 8;
;             const unsigned lo = (((unsigned)tq & 15u) ^ 8u) * 0x11111111u, hi = ((unsigned)(tq >> 4) & 15u) * 0x11111111u;
;             typedef unsigned u2v __attribute__((ext_vector_type(2)));
;             u2v l2; l2.x = lo; l2.y = lo; u2v h2; h2.x = hi; h2.y = hi;
;             *(LAS u2v*)(ATL + 8 * idx) = l2; *(LAS u2v*)(ATL + 1024 + 8 * idx) = h2;
;         }
;         const float asc = ASC[tl]; const int sa = SAL[tl];
;         CFENCE();
;         int accH[4], accL[4];
; #pragma unroll
;         for (int st = 0; st < 16; ++st) {
;             const int p = st >> 2, q = st & 3;
;             if (st < 14) VDMA(st + 2, (st + 2) % 3);
;             if (st < 14) asm volatile("s_waitcnt vmcnt(8)" ::: "memory");
;             else if (st == 14) asm volatile("s_waitcnt vmcnt(4)" ::: "memory");
;             else asm volatile("s_waitcnt vmcnt(0)" ::: "memory");
;             if (q == 0) {
; #pragma unroll
;                 for (int r = 0; r < 4; ++r) { accH[r] = 0; accL[r] = 0; } }
; #pragma unroll
;             for (int tp = 0; tp < 2; ++tp) {
;                 const v2i ao = TR4(ATL + (2 * q + tp) * 128 + 8 * s16), ah = TR4(ATL + 1024 + (2 * q + tp) * 128 + 8 * s16);
; #pragma unroll
	v_add_u32_e32 v54, s78, v59
	v_add_u32_e32 v55, s78, v60
	v_add_u32_e32 v56, s78, v61
	v_add_u32_e32 v57, s78, v62
	ds_read_b64_tr_b4 v[46:47], v160 offset:256
	ds_read_b64_tr_b4 v[48:49], v160 offset:1280
	ds_read_b64_tr_b4 v[122:123], v54
	ds_read_b64_tr_b4 v[124:125], v55
	ds_read_b64_tr_b4 v[126:127], v56
	ds_read_b64_tr_b4 v[128:129], v57
	s_waitcnt lgkmcnt(6)
	v_dot8c_i32_i4_e32 v38, v130, v52
	v_dot8c_i32_i4_e32 v39, v130, v50
	v_dot8c_i32_i4_e32 v40, v132, v52
	v_dot8c_i32_i4_e32 v41, v132, v50
	v_dot8c_i32_i4_e32 v42, v134, v52
	v_dot8c_i32_i4_e32 v43, v134, v50
	v_dot8c_i32_i4_e32 v44, v136, v52
	v_dot8c_i32_i4_e32 v45, v136, v50
	v_dot8c_i32_i4_e32 v38, v131, v53
	v_dot8c_i32_i4_e32 v39, v131, v51
	v_dot8c_i32_i4_e32 v40, v133, v53
	v_dot8c_i32_i4_e32 v41, v133, v51
	v_dot8c_i32_i4_e32 v42, v135, v53
	v_dot8c_i32_i4_e32 v43, v135, v51
	v_dot8c_i32_i4_e32 v44, v137, v53
	v_dot8c_i32_i4_e32 v45, v137, v51
	v_and_b32_e32 v78, 0xffff, v33
	v_lshrrev_b32_e32 v79, 16, v33
	v_lshl_add_u32 v78, v78, 7, v150
	v_lshl_add_u32 v79, v79, 7, v151
	s_mov_b32 m0, s77
	s_add_i32 s43, s77, 0x400
	global_load_lds_dwordx4 v78, s[50:51]
	s_mov_b32 m0, s43
	s_nop 0
	global_load_lds_dwordx4 v79, s[50:51]
	s_waitcnt vmcnt(10)
	v_add_u32_e32 v54, s79, v59
	v_add_u32_e32 v55, s79, v60
	v_add_u32_e32 v56, s79, v61
	v_add_u32_e32 v57, s79, v62
	ds_read_b64_tr_b4 v[50:51], v160 offset:384
	ds_read_b64_tr_b4 v[52:53], v160 offset:1408
	ds_read_b64_tr_b4 v[130:131], v54
	ds_read_b64_tr_b4 v[132:133], v55
	ds_read_b64_tr_b4 v[134:135], v56
	ds_read_b64_tr_b4 v[136:137], v57
	s_waitcnt lgkmcnt(6)
	v_dot8c_i32_i4_e32 v38, v122, v48
	v_dot8c_i32_i4_e32 v39, v122, v46
	v_dot8c_i32_i4_e32 v40, v124, v48
	v_dot8c_i32_i4_e32 v41, v124, v46
	v_dot8c_i32_i4_e32 v42, v126, v48
	v_dot8c_i32_i4_e32 v43, v126, v46
	v_dot8c_i32_i4_e32 v44, v128, v48
	v_dot8c_i32_i4_e32 v45, v128, v46
	v_dot8c_i32_i4_e32 v38, v123, v49
	v_dot8c_i32_i4_e32 v39, v123, v47
	v_dot8c_i32_i4_e32 v40, v125, v49
	v_dot8c_i32_i4_e32 v41, v125, v47
	v_dot8c_i32_i4_e32 v42, v127, v49
	v_dot8c_i32_i4_e32 v43, v127, v47
	v_dot8c_i32_i4_e32 v44, v129, v49
	v_dot8c_i32_i4_e32 v45, v129, v47
	s_waitcnt lgkmcnt(15)
	v_and_b32_e32 v78, 0xffff, v18
	v_lshrrev_b32_e32 v79, 16, v18
	v_lshl_add_u32 v78, v78, 7, v152
	v_lshl_add_u32 v79, v79, 7, v153
	s_mov_b32 m0, s78
	s_add_i32 s43, s78, 0x400
	global_load_lds_dwordx4 v78, s[50:51]
	s_mov_b32 m0, s43
	s_nop 0
	global_load_lds_dwordx4 v79, s[50:51]
	s_waitcnt vmcnt(10)
	v_add_u32_e32 v54, s98, v59
	v_add_u32_e32 v55, s98, v60
	v_add_u32_e32 v56, s98, v61
	v_add_u32_e32 v57, s98, v62
	ds_read_b64_tr_b4 v[46:47], v160 offset:512
	ds_read_b64_tr_b4 v[48:49], v160 offset:1536
	ds_read_b64_tr_b4 v[122:123], v54
	ds_read_b64_tr_b4 v[124:125], v55
	ds_read_b64_tr_b4 v[126:127], v56
	ds_read_b64_tr_b4 v[128:129], v57
	s_waitcnt lgkmcnt(6)
	v_dot8c_i32_i4_e32 v38, v130, v52
	v_dot8c_i32_i4_e32 v39, v130, v50
	v_dot8c_i32_i4_e32 v40, v132, v52
	v_dot8c_i32_i4_e32 v41, v132, v50
	v_dot8c_i32_i4_e32 v42, v134, v52
	v_dot8c_i32_i4_e32 v43, v134, v50
	v_dot8c_i32_i4_e32 v44, v136, v52
	v_dot8c_i32_i4_e32 v45, v136, v50
	v_dot8c_i32_i4_e32 v38, v131, v53
	v_dot8c_i32_i4_e32 v39, v131, v51
	v_dot8c_i32_i4_e32 v40, v133, v53
	v_dot8c_i32_i4_e32 v41, v133, v51
	v_dot8c_i32_i4_e32 v42, v135, v53
	v_dot8c_i32_i4_e32 v43, v135, v51
	v_dot8c_i32_i4_e32 v44, v137, v53
	v_dot8c_i32_i4_e32 v45, v137, v51
	v_and_b32_e32 v78, 0xffff, v19
	v_lshrrev_b32_e32 v79, 16, v19
	v_lshl_add_u32 v78, v78, 7, v152
	v_lshl_add_u32 v79, v79, 7, v153
	s_mov_b32 m0, s79
	s_add_i32 s43, s79, 0x400
	global_load_lds_dwordx4 v78, s[50:51]
	s_mov_b32 m0, s43
	s_nop 0
	global_load_lds_dwordx4 v79, s[50:51]
	s_waitcnt vmcnt(8)
	v_add_u32_e32 v54, s99, v59
	v_add_u32_e32 v55, s99, v60
	v_add_u32_e32 v56, s99, v61
	v_add_u32_e32 v57, s99, v62
	ds_read_b64_tr_b4 v[50:51], v160 offset:640
	ds_read_b64_tr_b4 v[52:53], v160 offset:1664
	ds_read_b64_tr_b4 v[130:131], v54
	ds_read_b64_tr_b4 v[132:133], v55
	ds_read_b64_tr_b4 v[134:135], v56
	ds_read_b64_tr_b4 v[136:137], v57
	s_waitcnt lgkmcnt(6)
	v_dot8c_i32_i4_e32 v38, v122, v48
	v_dot8c_i32_i4_e32 v39, v122, v46
	v_dot8c_i32_i4_e32 v40, v124, v48
	v_dot8c_i32_i4_e32 v41, v124, v46
	v_dot8c_i32_i4_e32 v42, v126, v48
	v_dot8c_i32_i4_e32 v43, v126, v46
	v_dot8c_i32_i4_e32 v44, v128, v48
	v_dot8c_i32_i4_e32 v45, v128, v46
	v_dot8c_i32_i4_e32 v38, v123, v49
	v_dot8c_i32_i4_e32 v39, v123, v47
	v_dot8c_i32_i4_e32 v40, v125, v49
	v_dot8c_i32_i4_e32 v41, v125, v47
	v_dot8c_i32_i4_e32 v42, v127, v49
	v_dot8c_i32_i4_e32 v43, v127, v47
	v_dot8c_i32_i4_e32 v44, v129, v49
	v_dot8c_i32_i4_e32 v45, v129, v47
	s_waitcnt lgkmcnt(15)
	v_add_u32_e32 v143, 8, v139
	v_and_b32_e32 v142, 15, v143
	v_xor_b32_e32 v142, 8, v142
	v_bfe_u32 v144, v143, 4, 4
	v_mul_lo_u32 v142, v142, s92
	v_mul_lo_u32 v144, v144, s92
	v_mov_b32_e32 v143, v142
	v_mov_b32_e32 v145, v144
	ds_write2st64_b64 v159, v[142:143], v[144:145] offset1:2
	v_and_b32_e32 v78, 0xffff, v20
	v_lshrrev_b32_e32 v79, 16, v20
	v_lshl_add_u32 v78, v78, 7, v152
	v_lshl_add_u32 v79, v79, 7, v153
	s_mov_b32 m0, s98
	s_add_i32 s43, s98, 0x400
	global_load_lds_dwordx4 v78, s[50:51]
	s_mov_b32 m0, s43
	s_nop 0
	global_load_lds_dwordx4 v79, s[50:51]
	s_waitcnt vmcnt(8)
	v_add_u32_e32 v54, s76, v59
	v_add_u32_e32 v55, s76, v60
	v_add_u32_e32 v56, s76, v61
	v_add_u32_e32 v57, s76, v62
	ds_read_b64_tr_b4 v[46:47], v160 offset:768
	ds_read_b64_tr_b4 v[48:49], v160 offset:1792
	ds_read_b64_tr_b4 v[122:123], v54
	ds_read_b64_tr_b4 v[124:125], v55
	ds_read_b64_tr_b4 v[126:127], v56
	ds_read_b64_tr_b4 v[128:129], v57
	s_waitcnt lgkmcnt(7)
; __device__ __forceinline__ void peer_v_tokens(int j, const LAS unsigned short* EL, const LAS unsigned char* AL  , const LAS float* ASC  , const LAS int* SAL  , ...
;     ...
;         for (int st = 0; st < 16; ++st) {
;             const int p = st >> 2, q = st & 3;
;             if (st < 14) VDMA(st + 2, (st + 2) % 3);
;             if (st < 14) asm volatile("s_waitcnt vmcnt(8)" ::: "memory");
;             else if (st == 14) asm volatile("s_waitcnt vmcnt(4)" ::: "memory");
;             else asm volatile("s_waitcnt vmcnt(0)" ::: "memory");
;             if (q == 0) {
; #pragma unroll
;                 for (int r = 0; r < 4; ++r) { accH[r] = 0; accL[r] = 0; } }
; #pragma unroll
;             for (int tp = 0; tp < 2; ++tp) {
;                 const v2i ao = TR4(ATL + (2 * q + tp) * 128 + 8 * s16), ah = TR4(ATL + 1024 + (2 * q + tp) * 128 + 8 * s16);
; #pragma unroll
;                 for (int r = 0; r < 4; ++r) {
;                     const v2i d = TR4(ldsb + BUF[st % 3] + 2048 * tp + roff[r]);
;                     accH[r] = __builtin_amdgcn_sdot8(d.x, ah.x, accH[r], false); accH[r] = __builtin_amdgcn_sdot8(d.y, ah.y, accH[r], false);
;                     accL[r] = __builtin_amdgcn_sdot8(d.x, ao.x, accL[r], false); accL[r] = __builtin_amdgcn_sdot8(d.y, ao.y, accL[r], false);
;                 }
;             }
;             asm volatile("s_waitcnt lgkmcnt(0)" ::: "memory");
;             if (q == 3) {
; #pragma unroll
;                 for (int r = 0; r < 4; ++r) STASH[256 * p + 16 * (grp + 4 * r) + pc] = f2bf(asc * (float)(2 * ((accH[r] << 4) + accL[r]) + sa));
;             }
;         }
;         CFENCE();
;         {
;             float4 v[4]; float ss = 0.f;
; #pragma unroll
;             for (int jq = 0; jq < 4; ++jq) { typedef unsigned u2v __attribute__((ext_vector_type(2))); const u2v pw = *(const LAS u2v*)(STASH + 4 * lane + 256 * jq); const uint2 hw = hv[jq];
;                 v[jq] = make_float4(__uint_as_float(hw.x << 16) + __uint_as_float(pw.x << 16), __uint_as_float(hw.x & 0xffff0000u) + __uint_as_float(pw.x & 0xffff0000u),
;                                     __uint_as_float(hw.y << 16) + __uint_as_float(pw.y << 16), __uint_as_float(hw.y & 0xffff0000u) + __uint_as_float(pw.y & 0xffff0000u));
;                 ss += v[jq].x * v[jq].x + v[jq].y * v[jq].y + v[jq].z * v[jq].z + v[jq].w * v[jq].w; }
;             ss = wave_sum(ss);
	v_dot8c_i32_i4_e32 v38, v130, v52
	v_dot8c_i32_i4_e32 v39, v130, v50
	v_dot8c_i32_i4_e32 v40, v132, v52
	v_dot8c_i32_i4_e32 v41, v132, v50
	v_dot8c_i32_i4_e32 v42, v134, v52
	v_dot8c_i32_i4_e32 v43, v134, v50
	v_dot8c_i32_i4_e32 v44, v136, v52
	v_dot8c_i32_i4_e32 v45, v136, v50
	v_dot8c_i32_i4_e32 v38, v131, v53
	v_dot8c_i32_i4_e32 v39, v131, v51
	v_dot8c_i32_i4_e32 v40, v133, v53
	v_dot8c_i32_i4_e32 v41, v133, v51
	v_dot8c_i32_i4_e32 v42, v135, v53
	v_dot8c_i32_i4_e32 v43, v135, v51
	v_dot8c_i32_i4_e32 v44, v137, v53
	v_dot8c_i32_i4_e32 v45, v137, v51
	v_and_b32_e32 v78, 0xffff, v21
	v_lshrrev_b32_e32 v79, 16, v21
	v_lshl_add_u32 v78, v78, 7, v152
	v_lshl_add_u32 v79, v79, 7, v153
	s_mov_b32 m0, s99
	s_add_i32 s43, s99, 0x400
	global_load_lds_dwordx4 v78, s[50:51]
	s_mov_b32 m0, s43
	s_nop 0
	global_load_lds_dwordx4 v79, s[50:51]
	s_waitcnt vmcnt(8)
	v_add_u32_e32 v54, s77, v59
	v_add_u32_e32 v55, s77, v60
	v_add_u32_e32 v56, s77, v61
	v_add_u32_e32 v57, s77, v62
	ds_read_b64_tr_b4 v[50:51], v160 offset:896
	ds_read_b64_tr_b4 v[52:53], v160 offset:1920
	ds_read_b64_tr_b4 v[130:131], v54
	ds_read_b64_tr_b4 v[132:133], v55
	ds_read_b64_tr_b4 v[134:135], v56
	ds_read_b64_tr_b4 v[136:137], v57
	s_waitcnt lgkmcnt(6)
	v_dot8c_i32_i4_e32 v38, v122, v48
	v_dot8c_i32_i4_e32 v39, v122, v46
	v_dot8c_i32_i4_e32 v40, v124, v48
	v_dot8c_i32_i4_e32 v41, v124, v46
	v_dot8c_i32_i4_e32 v42, v126, v48
	v_dot8c_i32_i4_e32 v43, v126, v46
	v_dot8c_i32_i4_e32 v44, v128, v48
	v_dot8c_i32_i4_e32 v45, v128, v46
	v_dot8c_i32_i4_e32 v38, v123, v49
	v_dot8c_i32_i4_e32 v39, v123, v47
	v_dot8c_i32_i4_e32 v40, v125, v49
	v_dot8c_i32_i4_e32 v41, v125, v47
	v_dot8c_i32_i4_e32 v42, v127, v49
	v_dot8c_i32_i4_e32 v43, v127, v47
	v_dot8c_i32_i4_e32 v44, v129, v49
	v_dot8c_i32_i4_e32 v45, v129, v47
	v_and_b32_e32 v78, 0xffff, v22
	v_lshrrev_b32_e32 v79, 16, v22
	v_lshl_add_u32 v78, v78, 7, v152
	v_lshl_add_u32 v79, v79, 7, v153
	s_mov_b32 m0, s76
	s_add_i32 s43, s76, 0x400
	global_load_lds_dwordx4 v78, s[50:51]
	s_mov_b32 m0, s43
	s_nop 0
	global_load_lds_dwordx4 v79, s[50:51]
	s_waitcnt vmcnt(8)
	v_add_u32_e32 v54, s78, v59
	v_add_u32_e32 v55, s78, v60
	v_add_u32_e32 v56, s78, v61
	v_add_u32_e32 v57, s78, v62
	ds_read_b64_tr_b4 v[46:47], v160
	ds_read_b64_tr_b4 v[48:49], v160 offset:1024
	ds_read_b64_tr_b4 v[122:123], v54
	ds_read_b64_tr_b4 v[124:125], v55
	ds_read_b64_tr_b4 v[126:127], v56
	ds_read_b64_tr_b4 v[128:129], v57
	s_waitcnt lgkmcnt(6)
	v_dot8c_i32_i4_e32 v38, v130, v52
	v_dot8c_i32_i4_e32 v39, v130, v50
	v_dot8c_i32_i4_e32 v40, v132, v52
	v_dot8c_i32_i4_e32 v41, v132, v50
	v_dot8c_i32_i4_e32 v42, v134, v52
	v_dot8c_i32_i4_e32 v43, v134, v50
	v_dot8c_i32_i4_e32 v44, v136, v52
	v_dot8c_i32_i4_e32 v45, v136, v50
	v_dot8c_i32_i4_e32 v38, v131, v53
	v_dot8c_i32_i4_e32 v39, v131, v51
	v_dot8c_i32_i4_e32 v40, v133, v53
	v_dot8c_i32_i4_e32 v41, v133, v51
	v_dot8c_i32_i4_e32 v42, v135, v53
	v_dot8c_i32_i4_e32 v43, v135, v51
	v_dot8c_i32_i4_e32 v44, v137, v53
	v_dot8c_i32_i4_e32 v45, v137, v51
	s_nop 3
	s_waitcnt lgkmcnt(15)
	v_lshlrev_b32_e32 v38, 5, v38
	v_lshlrev_b32_e32 v39, 1, v39
	v_add3_u32 v38, v39, v229, v38
	v_cvt_f32_i32_e32 v38, v38
	v_mul_f32_e32 v38, v228, v38
	v_lshlrev_b32_e32 v40, 5, v40
	v_lshlrev_b32_e32 v41, 1, v41
	v_add3_u32 v40, v41, v229, v40
	v_cvt_f32_i32_e32 v40, v40
	v_mul_f32_e32 v40, v228, v40
	v_lshlrev_b32_e32 v42, 5, v42
	v_lshlrev_b32_e32 v43, 1, v43
	v_add3_u32 v42, v43, v229, v42
	v_cvt_f32_i32_e32 v42, v42
	v_mul_f32_e32 v42, v228, v42
	v_lshlrev_b32_e32 v44, 5, v44
	v_lshlrev_b32_e32 v45, 1, v45
	v_add3_u32 v44, v45, v229, v44
	v_cvt_f32_i32_e32 v44, v44
	v_mul_f32_e32 v44, v228, v44
	v_cvt_pk_bf16_f32 v174, v38, v40
	v_cvt_pk_bf16_f32 v175, v42, v44
	ds_read_b128 v[252:255], v155 offset:1024
	s_add_i32 s44, s40, 24
	s_ashr_i32 s45, s44, 31
	s_lshl_b64 s[44:45], s[44:45], 12
	v_lshl_add_u64 v[80:81], v[36:37], 0, s[44:45]
	s_waitcnt lgkmcnt(0)
	v_mul_f32_e32 v240, v240, v252
	v_mul_f32_e32 v241, v241, v253
	v_mul_f32_e32 v242, v242, v254
	v_mul_f32_e32 v243, v243, v255
	global_store_dwordx4 v[80:81], v[240:243], off offset:1024 sc1
	v_add_u32_e32 v147, 8, v140
	v_and_b32_e32 v146, 15, v147
	v_xor_b32_e32 v146, 8, v146
	v_bfe_u32 v148, v147, 4, 4
	v_mul_lo_u32 v146, v146, s92
	v_mul_lo_u32 v148, v148, s92
	v_mov_b32_e32 v147, v146
	v_mov_b32_e32 v149, v148
	ds_write2st64_b64 v77, v[146:147], v[148:149] offset1:2
	v_add_u32_e32 v138, 0x1400, v74
	ds_read_u8 v139, v138
	v_add_u32_e32 v141, 0x1400, v73
	ds_read_u8 v140, v141
	s_add_i32 s43, s67, 128
	v_mov_b32_e32 v138, s43
	ds_read2st64_b32 v[228:229], v138 offset1:1
	ds_read_b128 v[26:29], v227 offset:10240
	ds_read_b128 v[30:33], v227 offset:10256
	v_mov_b32_e32 v38, 0
	v_mov_b32_e32 v39, 0
	v_mov_b32_e32 v40, 0
	v_mov_b32_e32 v41, 0
	v_mov_b32_e32 v42, 0
	v_mov_b32_e32 v43, 0
	v_mov_b32_e32 v44, 0
	v_mov_b32_e32 v45, 0
	v_and_b32_e32 v78, 0xffff, v23
	v_lshrrev_b32_e32 v79, 16, v23
	v_lshl_add_u32 v78, v78, 7, v152
	v_lshl_add_u32 v79, v79, 7, v153
	s_mov_b32 m0, s77
	s_add_i32 s43, s77, 0x400
	global_load_lds_dwordx4 v78, s[50:51]
	s_mov_b32 m0, s43
	s_nop 0
	global_load_lds_dwordx4 v79, s[50:51]
	s_waitcnt vmcnt(9)
	v_add_u32_e32 v54, s79, v59
	v_add_u32_e32 v55, s79, v60
	v_add_u32_e32 v56, s79, v61
	v_add_u32_e32 v57, s79, v62
	ds_read_b64_tr_b4 v[50:51], v160 offset:128
	ds_read_b64_tr_b4 v[52:53], v160 offset:1152
	ds_read_b64_tr_b4 v[130:131], v54
	ds_read_b64_tr_b4 v[132:133], v55
	ds_read_b64_tr_b4 v[134:135], v56
	ds_read_b64_tr_b4 v[136:137], v57
	s_waitcnt lgkmcnt(13)
; __device__ __forceinline__ void peer_v_tokens(int j, const LAS unsigned short* EL, const LAS unsigned char* AL  , const LAS float* ASC  , const LAS int* SAL  , ...
;     ...
; #pragma unroll 1
;     for (int it = 0; it < 8; ++it) {
;         const int tl = it * 8 + wave, t = j * 64 + tl;
;         unsigned E[8];
;         { const LAS v4u* ep = (const LAS v4u*)(EL + tl * 128 + 16 * g); const v4u e0 = ep[0], e1 = ep[1];
;           E[0] = e0.x; E[1] = e0.y; E[2] = e0.z; E[3] = e0.w; E[4] = e1.x; E[5] = e1.y; E[6] = e1.z; E[7] = e1.w; }
;         uint2 hv[4]; float4 gv[4];
;         { unsigned ho = (unsigned)t * (D / 4) + (unsigned)lane; asm volatile("" : "+v"(ho)); const uint2* hp = (const uint2*)HB + ho; const float4* gp = (const float4*)fng + lane;
; #pragma unroll
;           for (int jq = 0; jq < 4; ++jq) { hv[jq] = hp[64 * jq]; gv[jq] = gp[64 * jq]; } }
;         VDMA(0, 0); VDMA(1, 1);
; #pragma unroll
;         for (int m = 0; m < 2; ++m) {
;             const int idx = lane + 64 * m, tau = idx >> 4, sr = idx & 15, k = 16 * (sr & 7) + 2 * tau + (sr >> 3);
;             const int aq = (int)*(const LAS signed char*)(AL + tl * 128 + k); const int tq = aq + 8;
;             const unsigned lo = (((unsigned)tq & 15u) ^ 8u) * 0x11111111u, hi = ((unsigned)(tq >> 4) & 15u) * 0x11111111u;
;             typedef unsigned u2v __attribute__((ext_vector_type(2)));
;             u2v l2; l2.x = lo; l2.y = lo; u2v h2; h2.x = hi; h2.y = hi;
;             *(LAS u2v*)(ATL + 8 * idx) = l2; *(LAS u2v*)(ATL + 1024 + 8 * idx) = h2;
;         }
;         const float asc = ASC[tl]; const int sa = SAL[tl];
;         CFENCE();
;         int accH[4], accL[4];
; #pragma unroll
;         for (int st = 0; st < 16; ++st) {
;             const int p = st >> 2, q = st & 3;
;             if (st < 14) VDMA(st + 2, (st + 2) % 3);
;             if (st < 14) asm volatile("s_waitcnt vmcnt(8)" ::: "memory");
;             else if (st == 14) asm volatile("s_waitcnt vmcnt(4)" ::: "memory");
;             else asm volatile("s_waitcnt vmcnt(0)" ::: "memory");
;             if (q == 0) {
; #pragma unroll
;                 for (int r = 0; r < 4; ++r) { accH[r] = 0; accL[r] = 0; } }
; #pragma unroll
;             for (int tp = 0; tp < 2; ++tp) {
;                 const v2i ao = TR4(ATL + (2 * q + tp) * 128 + 8 * s16), ah = TR4(ATL + 1024 + (2 * q + tp) * 128 + 8 * s16);
; #pragma unroll
	v_dot8c_i32_i4_e32 v38, v122, v48
	v_dot8c_i32_i4_e32 v39, v122, v46
	v_dot8c_i32_i4_e32 v40, v124, v48
	v_dot8c_i32_i4_e32 v41, v124, v46
	v_dot8c_i32_i4_e32 v42, v126, v48
	v_dot8c_i32_i4_e32 v43, v126, v46
	v_dot8c_i32_i4_e32 v44, v128, v48
	v_dot8c_i32_i4_e32 v45, v128, v46
	v_dot8c_i32_i4_e32 v38, v123, v49
	v_dot8c_i32_i4_e32 v39, v123, v47
	v_dot8c_i32_i4_e32 v40, v125, v49
	v_dot8c_i32_i4_e32 v41, v125, v47
	v_dot8c_i32_i4_e32 v42, v127, v49
	v_dot8c_i32_i4_e32 v43, v127, v47
	v_dot8c_i32_i4_e32 v44, v129, v49
	v_dot8c_i32_i4_e32 v45, v129, v47
	v_and_b32_e32 v78, 0xffff, v24
	v_lshrrev_b32_e32 v79, 16, v24
	v_lshl_add_u32 v78, v78, 7, v152
	v_lshl_add_u32 v79, v79, 7, v153
	s_mov_b32 m0, s78
	s_add_i32 s43, s78, 0x400
	global_load_lds_dwordx4 v78, s[50:51]
	s_mov_b32 m0, s43
	s_nop 0
	global_load_lds_dwordx4 v79, s[50:51]
	s_waitcnt vmcnt(9)
	v_add_u32_e32 v54, s98, v59
	v_add_u32_e32 v55, s98, v60
	v_add_u32_e32 v56, s98, v61
	v_add_u32_e32 v57, s98, v62
	ds_read_b64_tr_b4 v[46:47], v160 offset:256
	ds_read_b64_tr_b4 v[48:49], v160 offset:1280
	ds_read_b64_tr_b4 v[122:123], v54
	ds_read_b64_tr_b4 v[124:125], v55
	ds_read_b64_tr_b4 v[126:127], v56
	ds_read_b64_tr_b4 v[128:129], v57
	s_waitcnt lgkmcnt(6)
	v_dot8c_i32_i4_e32 v38, v130, v52
	v_dot8c_i32_i4_e32 v39, v130, v50
	v_dot8c_i32_i4_e32 v40, v132, v52
	v_dot8c_i32_i4_e32 v41, v132, v50
	v_dot8c_i32_i4_e32 v42, v134, v52
	v_dot8c_i32_i4_e32 v43, v134, v50
	v_dot8c_i32_i4_e32 v44, v136, v52
	v_dot8c_i32_i4_e32 v45, v136, v50
	v_dot8c_i32_i4_e32 v38, v131, v53
	v_dot8c_i32_i4_e32 v39, v131, v51
	v_dot8c_i32_i4_e32 v40, v133, v53
	v_dot8c_i32_i4_e32 v41, v133, v51
	v_dot8c_i32_i4_e32 v42, v135, v53
	v_dot8c_i32_i4_e32 v43, v135, v51
	v_dot8c_i32_i4_e32 v44, v137, v53
	v_dot8c_i32_i4_e32 v45, v137, v51
	v_and_b32_e32 v78, 0xffff, v25
	v_lshrrev_b32_e32 v79, 16, v25
	v_lshl_add_u32 v78, v78, 7, v152
	v_lshl_add_u32 v79, v79, 7, v153
	s_mov_b32 m0, s79
	s_add_i32 s43, s79, 0x400
	global_load_lds_dwordx4 v78, s[50:51]
	s_mov_b32 m0, s43
	s_nop 0
	global_load_lds_dwordx4 v79, s[50:51]
	s_waitcnt vmcnt(9)
	v_add_u32_e32 v54, s99, v59
	v_add_u32_e32 v55, s99, v60
	v_add_u32_e32 v56, s99, v61
	v_add_u32_e32 v57, s99, v62
	ds_read_b64_tr_b4 v[50:51], v160 offset:384
	ds_read_b64_tr_b4 v[52:53], v160 offset:1408
	ds_read_b64_tr_b4 v[130:131], v54
	ds_read_b64_tr_b4 v[132:133], v55
	ds_read_b64_tr_b4 v[134:135], v56
	ds_read_b64_tr_b4 v[136:137], v57
	s_waitcnt lgkmcnt(6)
	v_dot8c_i32_i4_e32 v38, v122, v48
	v_dot8c_i32_i4_e32 v39, v122, v46
	v_dot8c_i32_i4_e32 v40, v124, v48
	v_dot8c_i32_i4_e32 v41, v124, v46
	v_dot8c_i32_i4_e32 v42, v126, v48
	v_dot8c_i32_i4_e32 v43, v126, v46
	v_dot8c_i32_i4_e32 v44, v128, v48
	v_dot8c_i32_i4_e32 v45, v128, v46
	v_dot8c_i32_i4_e32 v38, v123, v49
	v_dot8c_i32_i4_e32 v39, v123, v47
	v_dot8c_i32_i4_e32 v40, v125, v49
	v_dot8c_i32_i4_e32 v41, v125, v47
	v_dot8c_i32_i4_e32 v42, v127, v49
	v_dot8c_i32_i4_e32 v43, v127, v47
	v_dot8c_i32_i4_e32 v44, v129, v49
	v_dot8c_i32_i4_e32 v45, v129, v47
	s_waitcnt lgkmcnt(15)
	v_and_b32_e32 v78, 0xffff, v26
	v_lshrrev_b32_e32 v79, 16, v26
	v_lshl_add_u32 v78, v78, 7, v152
	v_lshl_add_u32 v79, v79, 7, v153
	s_mov_b32 m0, s98
	s_add_i32 s43, s98, 0x400
	global_load_lds_dwordx4 v78, s[50:51]
	s_mov_b32 m0, s43
	s_nop 0
	global_load_lds_dwordx4 v79, s[50:51]
	s_waitcnt vmcnt(9)
	v_add_u32_e32 v54, s76, v59
	v_add_u32_e32 v55, s76, v60
	v_add_u32_e32 v56, s76, v61
	v_add_u32_e32 v57, s76, v62
	ds_read_b64_tr_b4 v[46:47], v160 offset:512
	ds_read_b64_tr_b4 v[48:49], v160 offset:1536
	ds_read_b64_tr_b4 v[122:123], v54
	ds_read_b64_tr_b4 v[124:125], v55
	ds_read_b64_tr_b4 v[126:127], v56
	ds_read_b64_tr_b4 v[128:129], v57
	s_waitcnt lgkmcnt(6)
	v_dot8c_i32_i4_e32 v38, v130, v52
	v_dot8c_i32_i4_e32 v39, v130, v50
	v_dot8c_i32_i4_e32 v40, v132, v52
	v_dot8c_i32_i4_e32 v41, v132, v50
	v_dot8c_i32_i4_e32 v42, v134, v52
	v_dot8c_i32_i4_e32 v43, v134, v50
	v_dot8c_i32_i4_e32 v44, v136, v52
	v_dot8c_i32_i4_e32 v45, v136, v50
	v_dot8c_i32_i4_e32 v38, v131, v53
	v_dot8c_i32_i4_e32 v39, v131, v51
	v_dot8c_i32_i4_e32 v40, v133, v53
	v_dot8c_i32_i4_e32 v41, v133, v51
	v_dot8c_i32_i4_e32 v42, v135, v53
	v_dot8c_i32_i4_e32 v43, v135, v51
	v_dot8c_i32_i4_e32 v44, v137, v53
	v_dot8c_i32_i4_e32 v45, v137, v51
	v_and_b32_e32 v78, 0xffff, v27
	v_lshrrev_b32_e32 v79, 16, v27
	v_lshl_add_u32 v78, v78, 7, v152
	v_lshl_add_u32 v79, v79, 7, v153
	s_mov_b32 m0, s99
	s_add_i32 s43, s99, 0x400
	global_load_lds_dwordx4 v78, s[50:51]
	s_mov_b32 m0, s43
	s_nop 0
	global_load_lds_dwordx4 v79, s[50:51]
	s_waitcnt vmcnt(8)
	v_add_u32_e32 v54, s77, v59
	v_add_u32_e32 v55, s77, v60
	v_add_u32_e32 v56, s77, v61
	v_add_u32_e32 v57, s77, v62
	ds_read_b64_tr_b4 v[50:51], v160 offset:640
	ds_read_b64_tr_b4 v[52:53], v160 offset:1664
	ds_read_b64_tr_b4 v[130:131], v54
	ds_read_b64_tr_b4 v[132:133], v55
	ds_read_b64_tr_b4 v[134:135], v56
	ds_read_b64_tr_b4 v[136:137], v57
	s_waitcnt lgkmcnt(6)
	v_dot8c_i32_i4_e32 v38, v122, v48
	v_dot8c_i32_i4_e32 v39, v122, v46
	v_dot8c_i32_i4_e32 v40, v124, v48
	v_dot8c_i32_i4_e32 v41, v124, v46
	v_dot8c_i32_i4_e32 v42, v126, v48
	v_dot8c_i32_i4_e32 v43, v126, v46
	v_dot8c_i32_i4_e32 v44, v128, v48
	v_dot8c_i32_i4_e32 v45, v128, v46
	v_dot8c_i32_i4_e32 v38, v123, v49
	v_dot8c_i32_i4_e32 v39, v123, v47
	v_dot8c_i32_i4_e32 v40, v125, v49
	v_dot8c_i32_i4_e32 v41, v125, v47
	v_dot8c_i32_i4_e32 v42, v127, v49
	v_dot8c_i32_i4_e32 v43, v127, v47
	v_dot8c_i32_i4_e32 v44, v129, v49
	v_dot8c_i32_i4_e32 v45, v129, v47
	s_waitcnt lgkmcnt(15)
; __device__ __forceinline__ void peer_v_tokens(int j, const LAS unsigned short* EL, const LAS unsigned char* AL  , const LAS float* ASC  , const LAS int* SAL  , ...
;     ...
; #pragma unroll 1
;     for (int it = 0; it < 8; ++it) {
;         const int tl = it * 8 + wave, t = j * 64 + tl;
;         unsigned E[8];
;         { const LAS v4u* ep = (const LAS v4u*)(EL + tl * 128 + 16 * g); const v4u e0 = ep[0], e1 = ep[1];
;           E[0] = e0.x; E[1] = e0.y; E[2] = e0.z; E[3] = e0.w; E[4] = e1.x; E[5] = e1.y; E[6] = e1.z; E[7] = e1.w; }
;         uint2 hv[4]; float4 gv[4];
;         { unsigned ho = (unsigned)t * (D / 4) + (unsigned)lane; asm volatile("" : "+v"(ho)); const uint2* hp = (const uint2*)HB + ho; const float4* gp = (const float4*)fng + lane;
; #pragma unroll
;           for (int jq = 0; jq < 4; ++jq) { hv[jq] = hp[64 * jq]; gv[jq] = gp[64 * jq]; } }
;         VDMA(0, 0); VDMA(1, 1);
; #pragma unroll
;         for (int m = 0; m < 2; ++m) {
;     ...
;         for (int st = 0; st < 16; ++st) {
;             const int p = st >> 2, q = st & 3;
;             if (st < 14) VDMA(st + 2, (st + 2) % 3);
;             if (st < 14) asm volatile("s_waitcnt vmcnt(8)" ::: "memory");
;             else if (st == 14) asm volatile("s_waitcnt vmcnt(4)" ::: "memory");
;             else asm volatile("s_waitcnt vmcnt(0)" ::: "memory");
;             if (q == 0) {
; #pragma unroll
;                 for (int r = 0; r < 4; ++r) { accH[r] = 0; accL[r] = 0; } }
; #pragma unroll
;             for (int tp = 0; tp < 2; ++tp) {
;                 const v2i ao = TR4(ATL + (2 * q + tp) * 128 + 8 * s16), ah = TR4(ATL + 1024 + (2 * q + tp) * 128 + 8 * s16);
; #pragma unroll
;                 for (int r = 0; r < 4; ++r) {
;                     const v2i d = TR4(ldsb + BUF[st % 3] + 2048 * tp + roff[r]);
;                     accH[r] = __builtin_amdgcn_sdot8(d.x, ah.x, accH[r], false); accH[r] = __builtin_amdgcn_sdot8(d.y, ah.y, accH[r], false);
;                     accL[r] = __builtin_amdgcn_sdot8(d.x, ao.x, accL[r], false); accL[r] = __builtin_amdgcn_sdot8(d.y, ao.y, accL[r], false);
;                 }
;             }
;             asm volatile("s_waitcnt lgkmcnt(0)" ::: "memory");
;             if (q == 3) {
; #pragma unroll
;                 for (int r = 0; r < 4; ++r) STASH[256 * p + 16 * (grp + 4 * r) + pc] = f2bf(asc * (float)(2 * ((accH[r] << 4) + accL[r]) + sa));
;             }
	v_add_u32_e32 v143, 8, v139
	v_and_b32_e32 v142, 15, v143
	v_xor_b32_e32 v142, 8, v142
	v_bfe_u32 v144, v143, 4, 4
	v_mul_lo_u32 v142, v142, s92
	v_mul_lo_u32 v144, v144, s92
	v_mov_b32_e32 v143, v142
	v_mov_b32_e32 v145, v144
	ds_write2st64_b64 v159, v[142:143], v[144:145] offset1:2
	v_and_b32_e32 v78, 0xffff, v28
	v_lshrrev_b32_e32 v79, 16, v28
	v_lshl_add_u32 v78, v78, 7, v152
	v_lshl_add_u32 v79, v79, 7, v153
	s_mov_b32 m0, s76
	s_add_i32 s43, s76, 0x400
	global_load_lds_dwordx4 v78, s[50:51]
	s_mov_b32 m0, s43
	s_nop 0
	global_load_lds_dwordx4 v79, s[50:51]
	s_waitcnt vmcnt(8)
	v_add_u32_e32 v54, s78, v59
	v_add_u32_e32 v55, s78, v60
	v_add_u32_e32 v56, s78, v61
	v_add_u32_e32 v57, s78, v62
	ds_read_b64_tr_b4 v[46:47], v160 offset:768
	ds_read_b64_tr_b4 v[48:49], v160 offset:1792
	ds_read_b64_tr_b4 v[122:123], v54
	ds_read_b64_tr_b4 v[124:125], v55
	ds_read_b64_tr_b4 v[126:127], v56
	ds_read_b64_tr_b4 v[128:129], v57
	s_waitcnt lgkmcnt(7)
	v_dot8c_i32_i4_e32 v38, v130, v52
	v_dot8c_i32_i4_e32 v39, v130, v50
	v_dot8c_i32_i4_e32 v40, v132, v52
	v_dot8c_i32_i4_e32 v41, v132, v50
	v_dot8c_i32_i4_e32 v42, v134, v52
	v_dot8c_i32_i4_e32 v43, v134, v50
	v_dot8c_i32_i4_e32 v44, v136, v52
	v_dot8c_i32_i4_e32 v45, v136, v50
	v_dot8c_i32_i4_e32 v38, v131, v53
	v_dot8c_i32_i4_e32 v39, v131, v51
	v_dot8c_i32_i4_e32 v40, v133, v53
	v_dot8c_i32_i4_e32 v41, v133, v51
	v_dot8c_i32_i4_e32 v42, v135, v53
	v_dot8c_i32_i4_e32 v43, v135, v51
	v_dot8c_i32_i4_e32 v44, v137, v53
	v_dot8c_i32_i4_e32 v45, v137, v51
	v_and_b32_e32 v78, 0xffff, v29
	v_lshrrev_b32_e32 v79, 16, v29
	v_lshl_add_u32 v78, v78, 7, v152
	v_lshl_add_u32 v79, v79, 7, v153
	s_mov_b32 m0, s77
	s_add_i32 s43, s77, 0x400
	global_load_lds_dwordx4 v78, s[50:51]
	s_mov_b32 m0, s43
	s_nop 0
	global_load_lds_dwordx4 v79, s[50:51]
	s_waitcnt vmcnt(8)
	v_add_u32_e32 v54, s79, v59
	v_add_u32_e32 v55, s79, v60
	v_add_u32_e32 v56, s79, v61
	v_add_u32_e32 v57, s79, v62
	ds_read_b64_tr_b4 v[50:51], v160 offset:896
	ds_read_b64_tr_b4 v[52:53], v160 offset:1920
	ds_read_b64_tr_b4 v[130:131], v54
	ds_read_b64_tr_b4 v[132:133], v55
	ds_read_b64_tr_b4 v[134:135], v56
	ds_read_b64_tr_b4 v[136:137], v57
	s_waitcnt lgkmcnt(6)
	v_dot8c_i32_i4_e32 v38, v122, v48
	v_dot8c_i32_i4_e32 v39, v122, v46
	v_dot8c_i32_i4_e32 v40, v124, v48
	v_dot8c_i32_i4_e32 v41, v124, v46
	v_dot8c_i32_i4_e32 v42, v126, v48
	v_dot8c_i32_i4_e32 v43, v126, v46
	v_dot8c_i32_i4_e32 v44, v128, v48
	v_dot8c_i32_i4_e32 v45, v128, v46
	v_dot8c_i32_i4_e32 v38, v123, v49
	v_dot8c_i32_i4_e32 v39, v123, v47
	v_dot8c_i32_i4_e32 v40, v125, v49
	v_dot8c_i32_i4_e32 v41, v125, v47
	v_dot8c_i32_i4_e32 v42, v127, v49
	v_dot8c_i32_i4_e32 v43, v127, v47
	v_dot8c_i32_i4_e32 v44, v129, v49
	v_dot8c_i32_i4_e32 v45, v129, v47
	v_and_b32_e32 v78, 0xffff, v30
	v_lshrrev_b32_e32 v79, 16, v30
	v_lshl_add_u32 v78, v78, 7, v152
	v_lshl_add_u32 v79, v79, 7, v153
	s_mov_b32 m0, s78
	s_add_i32 s43, s78, 0x400
	global_load_lds_dwordx4 v78, s[50:51]
	s_mov_b32 m0, s43
	s_nop 0
	global_load_lds_dwordx4 v79, s[50:51]
	s_waitcnt vmcnt(8)
	v_add_u32_e32 v54, s98, v59
	v_add_u32_e32 v55, s98, v60
	v_add_u32_e32 v56, s98, v61
	v_add_u32_e32 v57, s98, v62
	ds_read_b64_tr_b4 v[46:47], v160
	ds_read_b64_tr_b4 v[48:49], v160 offset:1024
	ds_read_b64_tr_b4 v[122:123], v54
	ds_read_b64_tr_b4 v[124:125], v55
	ds_read_b64_tr_b4 v[126:127], v56
	ds_read_b64_tr_b4 v[128:129], v57
	s_waitcnt lgkmcnt(6)
	v_dot8c_i32_i4_e32 v38, v130, v52
	v_dot8c_i32_i4_e32 v39, v130, v50
	v_dot8c_i32_i4_e32 v40, v132, v52
	v_dot8c_i32_i4_e32 v41, v132, v50
	v_dot8c_i32_i4_e32 v42, v134, v52
	v_dot8c_i32_i4_e32 v43, v134, v50
	v_dot8c_i32_i4_e32 v44, v136, v52
	v_dot8c_i32_i4_e32 v45, v136, v50
	v_dot8c_i32_i4_e32 v38, v131, v53
	v_dot8c_i32_i4_e32 v39, v131, v51
	v_dot8c_i32_i4_e32 v40, v133, v53
	v_dot8c_i32_i4_e32 v41, v133, v51
	v_dot8c_i32_i4_e32 v42, v135, v53
	v_dot8c_i32_i4_e32 v43, v135, v51
	v_dot8c_i32_i4_e32 v44, v137, v53
	v_dot8c_i32_i4_e32 v45, v137, v51
	s_nop 3
	s_waitcnt lgkmcnt(15)
	v_lshlrev_b32_e32 v38, 5, v38
	v_lshlrev_b32_e32 v39, 1, v39
	v_add3_u32 v38, v39, v229, v38
	v_cvt_f32_i32_e32 v38, v38
	v_mul_f32_e32 v38, v228, v38
	v_lshlrev_b32_e32 v40, 5, v40
	v_lshlrev_b32_e32 v41, 1, v41
	v_add3_u32 v40, v41, v229, v40
	v_cvt_f32_i32_e32 v40, v40
	v_mul_f32_e32 v40, v228, v40
	v_lshlrev_b32_e32 v42, 5, v42
	v_lshlrev_b32_e32 v43, 1, v43
	v_add3_u32 v42, v43, v229, v42
	v_cvt_f32_i32_e32 v42, v42
	v_mul_f32_e32 v42, v228, v42
	v_lshlrev_b32_e32 v44, 5, v44
	v_lshlrev_b32_e32 v45, 1, v45
	v_add3_u32 v44, v45, v229, v44
	v_cvt_f32_i32_e32 v44, v44
	v_mul_f32_e32 v44, v228, v44
	v_cvt_pk_bf16_f32 v168, v38, v40
	v_cvt_pk_bf16_f32 v169, v42, v44
	ds_read_b128 v[252:255], v156
	s_add_i32 s44, s40, 24
	s_ashr_i32 s45, s44, 31
	s_lshl_b64 s[44:45], s[44:45], 12
	v_lshl_add_u64 v[80:81], v[36:37], 0, s[44:45]
	s_waitcnt lgkmcnt(0)
; #define LAS __attribute__((address_space(3)))
; #define VDMA(st_, k_) do { _Pragma("unroll") for (int i_ = 0; i_ < 4; ++i_) { \
;         const unsigned off_ = (unsigned)((st_) >> 2) * (16384u * 128u) + (PE_ID(E, 4 * ((st_) & 3) + i_) << 7) + ((i_ & 1) ? cx1 : cx0); \
;         __builtin_amdgcn_global_load_lds((const unsigned*)(V4 + off_), (LAS unsigned*)(ldsb + BUF[k_] + 1024 * i_), 16, 0, 0); } } while (0)
; __device__ __forceinline__ void peer_v_tokens(int j, const LAS unsigned short* EL, const LAS unsigned char* AL  , const LAS float* ASC  , const LAS int* SAL  , ...
;     ...
;         const int tl = it * 8 + wave, t = j * 64 + tl;
;         unsigned E[8];
;         { const LAS v4u* ep = (const LAS v4u*)(EL + tl * 128 + 16 * g); const v4u e0 = ep[0], e1 = ep[1];
;           E[0] = e0.x; E[1] = e0.y; E[2] = e0.z; E[3] = e0.w; E[4] = e1.x; E[5] = e1.y; E[6] = e1.z; E[7] = e1.w; }
;         uint2 hv[4]; float4 gv[4];
;         { unsigned ho = (unsigned)t * (D / 4) + (unsigned)lane; asm volatile("" : "+v"(ho)); const uint2* hp = (const uint2*)HB + ho; const float4* gp = (const float4*)fng + lane;
; #pragma unroll
;           for (int jq = 0; jq < 4; ++jq) { hv[jq] = hp[64 * jq]; gv[jq] = gp[64 * jq]; } }
;         VDMA(0, 0); VDMA(1, 1);
; #pragma unroll
;         for (int m = 0; m < 2; ++m) {
;             const int idx = lane + 64 * m, tau = idx >> 4, sr = idx & 15, k = 16 * (sr & 7) + 2 * tau + (sr >> 3);
;             const int aq = (int)*(const LAS signed char*)(AL + tl * 128 + k); const int tq = aq + 8;
;             const unsigned lo = (((unsigned)tq & 15u) ^ 8u) * 0x11111111u, hi = ((unsigned)(tq >> 4) & 15u) * 0x11111111u;
;             typedef unsigned u2v __attribute__((ext_vector_type(2)));
;             u2v l2; l2.x = lo; l2.y = lo; u2v h2; h2.x = hi; h2.y = hi;
;             *(LAS u2v*)(ATL + 8 * idx) = l2; *(LAS u2v*)(ATL + 1024 + 8 * idx) = h2;
;         }
;         const float asc = ASC[tl]; const int sa = SAL[tl];
;     ...
;             float4* op = (float4*)(outp + (size_t)t * D) + lane;
; #pragma unroll
;             for (int jq = 0; jq < 4; ++jq) { typedef float f4v __attribute__((ext_vector_type(4))); f4v o4; o4.x = v[jq].x * r3 * gv[jq].x; o4.y = v[jq].y * r3 * gv[jq].y; o4.z = v[jq].z * r3 * gv[jq].z; o4.w = v[jq].w * r3 * gv[jq].w;
;                 __builtin_nontemporal_store(o4, (f4v*)op + 64 * jq); }
	v_mul_f32_e32 v244, v244, v252
	v_mul_f32_e32 v245, v245, v253
	v_mul_f32_e32 v246, v246, v254
	v_mul_f32_e32 v247, v247, v255
	global_store_dwordx4 v[80:81], v[244:247], off offset:2048 sc1
	s_add_i32 s43, s40, 32
	s_lshl_b32 s43, s43, 11
	v_add_u32_e32 v138, s43, v66
	global_load_dwordx2 v[194:195], v138, s[70:71]
	global_load_dwordx2 v[196:197], v138, s[70:71] offset:512
	global_load_dwordx2 v[198:199], v138, s[70:71] offset:1024
	global_load_dwordx2 v[200:201], v138, s[70:71] offset:1536
	v_add_u32_e32 v147, 8, v140
	v_and_b32_e32 v146, 15, v147
	v_xor_b32_e32 v146, 8, v146
	v_bfe_u32 v148, v147, 4, 4
	v_mul_lo_u32 v146, v146, s92
	v_mul_lo_u32 v148, v148, s92
	v_mov_b32_e32 v147, v146
	v_mov_b32_e32 v149, v148
	ds_write2st64_b64 v77, v[146:147], v[148:149] offset1:2
	v_add_u32_e32 v138, 0x1800, v74
	ds_read_u8 v139, v138
	v_add_u32_e32 v141, 0x1800, v73
	ds_read_u8 v140, v141
	s_add_i32 s43, s67, 160
	v_mov_b32_e32 v138, s43
	ds_read2st64_b32 v[228:229], v138 offset1:1
	ds_read_b128 v[18:21], v227 offset:12288
	ds_read_b128 v[22:25], v227 offset:12304
	v_mov_b32_e32 v150, v63
	v_mov_b32_e32 v151, v64
	v_mov_b32_e32 v38, 0
	v_mov_b32_e32 v39, 0
	v_mov_b32_e32 v40, 0
	v_mov_b32_e32 v41, 0
	v_mov_b32_e32 v42, 0
	v_mov_b32_e32 v43, 0
	v_mov_b32_e32 v44, 0
	v_mov_b32_e32 v45, 0
	v_and_b32_e32 v78, 0xffff, v31
	v_lshrrev_b32_e32 v79, 16, v31
	v_lshl_add_u32 v78, v78, 7, v152
	v_lshl_add_u32 v79, v79, 7, v153
	s_mov_b32 m0, s79
	s_add_i32 s43, s79, 0x400
	global_load_lds_dwordx4 v78, s[50:51]
	s_mov_b32 m0, s43
	s_nop 0
	global_load_lds_dwordx4 v79, s[50:51]
	s_waitcnt vmcnt(13)
	v_add_u32_e32 v54, s99, v59
	v_add_u32_e32 v55, s99, v60
	v_add_u32_e32 v56, s99, v61
	v_add_u32_e32 v57, s99, v62
	ds_read_b64_tr_b4 v[50:51], v160 offset:128
	ds_read_b64_tr_b4 v[52:53], v160 offset:1152
	ds_read_b64_tr_b4 v[130:131], v54
	ds_read_b64_tr_b4 v[132:133], v55
	ds_read_b64_tr_b4 v[134:135], v56
	ds_read_b64_tr_b4 v[136:137], v57
	s_waitcnt lgkmcnt(13)
	v_dot8c_i32_i4_e32 v38, v122, v48
	v_dot8c_i32_i4_e32 v39, v122, v46
	v_dot8c_i32_i4_e32 v40, v124, v48
	v_dot8c_i32_i4_e32 v41, v124, v46
	v_dot8c_i32_i4_e32 v42, v126, v48
	v_dot8c_i32_i4_e32 v43, v126, v46
	v_dot8c_i32_i4_e32 v44, v128, v48
	v_dot8c_i32_i4_e32 v45, v128, v46
	v_dot8c_i32_i4_e32 v38, v123, v49
	v_dot8c_i32_i4_e32 v39, v123, v47
	v_dot8c_i32_i4_e32 v40, v125, v49
	v_dot8c_i32_i4_e32 v41, v125, v47
	v_dot8c_i32_i4_e32 v42, v127, v49
	v_dot8c_i32_i4_e32 v43, v127, v47
	v_dot8c_i32_i4_e32 v44, v129, v49
	v_dot8c_i32_i4_e32 v45, v129, v47
	v_and_b32_e32 v78, 0xffff, v32
	v_lshrrev_b32_e32 v79, 16, v32
	v_lshl_add_u32 v78, v78, 7, v152
	v_lshl_add_u32 v79, v79, 7, v153
	s_mov_b32 m0, s98
	s_add_i32 s43, s98, 0x400
	global_load_lds_dwordx4 v78, s[50:51]
	s_mov_b32 m0, s43
	s_nop 0
	global_load_lds_dwordx4 v79, s[50:51]
	s_waitcnt vmcnt(13)
	v_add_u32_e32 v54, s76, v59
	v_add_u32_e32 v55, s76, v60
	v_add_u32_e32 v56, s76, v61
	v_add_u32_e32 v57, s76, v62
	ds_read_b64_tr_b4 v[46:47], v160 offset:256
	ds_read_b64_tr_b4 v[48:49], v160 offset:1280
	ds_read_b64_tr_b4 v[122:123], v54
	ds_read_b64_tr_b4 v[124:125], v55
	ds_read_b64_tr_b4 v[126:127], v56
	ds_read_b64_tr_b4 v[128:129], v57
	s_waitcnt lgkmcnt(6)
	v_dot8c_i32_i4_e32 v38, v130, v52
	v_dot8c_i32_i4_e32 v39, v130, v50
	v_dot8c_i32_i4_e32 v40, v132, v52
	v_dot8c_i32_i4_e32 v41, v132, v50
	v_dot8c_i32_i4_e32 v42, v134, v52
	v_dot8c_i32_i4_e32 v43, v134, v50
	v_dot8c_i32_i4_e32 v44, v136, v52
	v_dot8c_i32_i4_e32 v45, v136, v50
	v_dot8c_i32_i4_e32 v38, v131, v53
	v_dot8c_i32_i4_e32 v39, v131, v51
	v_dot8c_i32_i4_e32 v40, v133, v53
	v_dot8c_i32_i4_e32 v41, v133, v51
	v_dot8c_i32_i4_e32 v42, v135, v53
	v_dot8c_i32_i4_e32 v43, v135, v51
	v_dot8c_i32_i4_e32 v44, v137, v53
	v_dot8c_i32_i4_e32 v45, v137, v51
	v_and_b32_e32 v78, 0xffff, v33
	v_lshrrev_b32_e32 v79, 16, v33
	v_lshl_add_u32 v78, v78, 7, v152
	v_lshl_add_u32 v79, v79, 7, v153
	s_mov_b32 m0, s99
	s_add_i32 s43, s99, 0x400
	global_load_lds_dwordx4 v78, s[50:51]
	s_mov_b32 m0, s43
	s_nop 0
	global_load_lds_dwordx4 v79, s[50:51]
	s_waitcnt vmcnt(13)
	v_add_u32_e32 v54, s77, v59
	v_add_u32_e32 v55, s77, v60
	v_add_u32_e32 v56, s77, v61
	v_add_u32_e32 v57, s77, v62
	ds_read_b64_tr_b4 v[50:51], v160 offset:384
	ds_read_b64_tr_b4 v[52:53], v160 offset:1408
	ds_read_b64_tr_b4 v[130:131], v54
	ds_read_b64_tr_b4 v[132:133], v55
	ds_read_b64_tr_b4 v[134:135], v56
	ds_read_b64_tr_b4 v[136:137], v57
	s_waitcnt lgkmcnt(6)
	v_dot8c_i32_i4_e32 v38, v122, v48
	v_dot8c_i32_i4_e32 v39, v122, v46
	v_dot8c_i32_i4_e32 v40, v124, v48
	v_dot8c_i32_i4_e32 v41, v124, v46
	v_dot8c_i32_i4_e32 v42, v126, v48
	v_dot8c_i32_i4_e32 v43, v126, v46
	v_dot8c_i32_i4_e32 v44, v128, v48
	v_dot8c_i32_i4_e32 v45, v128, v46
	v_dot8c_i32_i4_e32 v38, v123, v49
	v_dot8c_i32_i4_e32 v39, v123, v47
	v_dot8c_i32_i4_e32 v40, v125, v49
	v_dot8c_i32_i4_e32 v41, v125, v47
	v_dot8c_i32_i4_e32 v42, v127, v49
	v_dot8c_i32_i4_e32 v43, v127, v47
	v_dot8c_i32_i4_e32 v44, v129, v49
	v_dot8c_i32_i4_e32 v45, v129, v47
	s_waitcnt lgkmcnt(15)
	v_and_b32_e32 v78, 0xffff, v18
	v_lshrrev_b32_e32 v79, 16, v18
	v_lshl_add_u32 v78, v78, 7, v150
	v_lshl_add_u32 v79, v79, 7, v151
	s_mov_b32 m0, s76
	s_add_i32 s43, s76, 0x400
	global_load_lds_dwordx4 v78, s[50:51]
	s_mov_b32 m0, s43
	s_nop 0
	global_load_lds_dwordx4 v79, s[50:51]
	s_waitcnt vmcnt(13)
	v_add_u32_e32 v54, s78, v59
	v_add_u32_e32 v55, s78, v60
	v_add_u32_e32 v56, s78, v61
	v_add_u32_e32 v57, s78, v62
	ds_read_b64_tr_b4 v[46:47], v160 offset:512
	ds_read_b64_tr_b4 v[48:49], v160 offset:1536
	ds_read_b64_tr_b4 v[122:123], v54
	ds_read_b64_tr_b4 v[124:125], v55
	ds_read_b64_tr_b4 v[126:127], v56
	ds_read_b64_tr_b4 v[128:129], v57
	s_waitcnt lgkmcnt(6)
; __device__ __forceinline__ void peer_v_tokens(int j, const LAS unsigned short* EL, const LAS unsigned char* AL  , const LAS float* ASC  , const LAS int* SAL  , ...
;     ...
; #pragma unroll 1
;     for (int it = 0; it < 8; ++it) {
;         const int tl = it * 8 + wave, t = j * 64 + tl;
;         unsigned E[8];
;         { const LAS v4u* ep = (const LAS v4u*)(EL + tl * 128 + 16 * g); const v4u e0 = ep[0], e1 = ep[1];
;           E[0] = e0.x; E[1] = e0.y; E[2] = e0.z; E[3] = e0.w; E[4] = e1.x; E[5] = e1.y; E[6] = e1.z; E[7] = e1.w; }
;         uint2 hv[4]; float4 gv[4];
;         { unsigned ho = (unsigned)t * (D / 4) + (unsigned)lane; asm volatile("" : "+v"(ho)); const uint2* hp = (const uint2*)HB + ho; const float4* gp = (const float4*)fng + lane;
; #pragma unroll
;           for (int jq = 0; jq < 4; ++jq) { hv[jq] = hp[64 * jq]; gv[jq] = gp[64 * jq]; } }
;         VDMA(0, 0); VDMA(1, 1);
; #pragma unroll
;         for (int m = 0; m < 2; ++m) {
;             const int idx = lane + 64 * m, tau = idx >> 4, sr = idx & 15, k = 16 * (sr & 7) + 2 * tau + (sr >> 3);
;             const int aq = (int)*(const LAS signed char*)(AL + tl * 128 + k); const int tq = aq + 8;
;             const unsigned lo = (((unsigned)tq & 15u) ^ 8u) * 0x11111111u, hi = ((unsigned)(tq >> 4) & 15u) * 0x11111111u;
;             typedef unsigned u2v __attribute__((ext_vector_type(2)));
;             u2v l2; l2.x = lo; l2.y = lo; u2v h2; h2.x = hi; h2.y = hi;
;             *(LAS u2v*)(ATL + 8 * idx) = l2; *(LAS u2v*)(ATL + 1024 + 8 * idx) = h2;
;         }
;         const float asc = ASC[tl]; const int sa = SAL[tl];
;         CFENCE();
;         int accH[4], accL[4];
; #pragma unroll
;         for (int st = 0; st < 16; ++st) {
;             const int p = st >> 2, q = st & 3;
;             if (st < 14) VDMA(st + 2, (st + 2) % 3);
;             if (st < 14) asm volatile("s_waitcnt vmcnt(8)" ::: "memory");
;             else if (st == 14) asm volatile("s_waitcnt vmcnt(4)" ::: "memory");
;             else asm volatile("s_waitcnt vmcnt(0)" ::: "memory");
;             if (q == 0) {
; #pragma unroll
;                 for (int r = 0; r < 4; ++r) { accH[r] = 0; accL[r] = 0; } }
; #pragma unroll
;             for (int tp = 0; tp < 2; ++tp) {
;                 const v2i ao = TR4(ATL + (2 * q + tp) * 128 + 8 * s16), ah = TR4(ATL + 1024 + (2 * q + tp) * 128 + 8 * s16);
; #pragma unroll
	v_dot8c_i32_i4_e32 v38, v130, v52
	v_dot8c_i32_i4_e32 v39, v130, v50
	v_dot8c_i32_i4_e32 v40, v132, v52
	v_dot8c_i32_i4_e32 v41, v132, v50
	v_dot8c_i32_i4_e32 v42, v134, v52
	v_dot8c_i32_i4_e32 v43, v134, v50
	v_dot8c_i32_i4_e32 v44, v136, v52
	v_dot8c_i32_i4_e32 v45, v136, v50
	v_dot8c_i32_i4_e32 v38, v131, v53
	v_dot8c_i32_i4_e32 v39, v131, v51
	v_dot8c_i32_i4_e32 v40, v133, v53
	v_dot8c_i32_i4_e32 v41, v133, v51
	v_dot8c_i32_i4_e32 v42, v135, v53
	v_dot8c_i32_i4_e32 v43, v135, v51
	v_dot8c_i32_i4_e32 v44, v137, v53
	v_dot8c_i32_i4_e32 v45, v137, v51
	v_and_b32_e32 v78, 0xffff, v19
	v_lshrrev_b32_e32 v79, 16, v19
	v_lshl_add_u32 v78, v78, 7, v150
	v_lshl_add_u32 v79, v79, 7, v151
	s_mov_b32 m0, s77
	s_add_i32 s43, s77, 0x400
	global_load_lds_dwordx4 v78, s[50:51]
	s_mov_b32 m0, s43
	s_nop 0
	global_load_lds_dwordx4 v79, s[50:51]
	s_waitcnt vmcnt(8)
	v_add_u32_e32 v54, s79, v59
	v_add_u32_e32 v55, s79, v60
	v_add_u32_e32 v56, s79, v61
	v_add_u32_e32 v57, s79, v62
	ds_read_b64_tr_b4 v[50:51], v160 offset:640
	ds_read_b64_tr_b4 v[52:53], v160 offset:1664
	ds_read_b64_tr_b4 v[130:131], v54
	ds_read_b64_tr_b4 v[132:133], v55
	ds_read_b64_tr_b4 v[134:135], v56
	ds_read_b64_tr_b4 v[136:137], v57
	s_waitcnt lgkmcnt(6)
	v_dot8c_i32_i4_e32 v38, v122, v48
	v_dot8c_i32_i4_e32 v39, v122, v46
	v_dot8c_i32_i4_e32 v40, v124, v48
	v_dot8c_i32_i4_e32 v41, v124, v46
	v_dot8c_i32_i4_e32 v42, v126, v48
	v_dot8c_i32_i4_e32 v43, v126, v46
	v_dot8c_i32_i4_e32 v44, v128, v48
	v_dot8c_i32_i4_e32 v45, v128, v46
	v_dot8c_i32_i4_e32 v38, v123, v49
	v_dot8c_i32_i4_e32 v39, v123, v47
	v_dot8c_i32_i4_e32 v40, v125, v49
	v_dot8c_i32_i4_e32 v41, v125, v47
	v_dot8c_i32_i4_e32 v42, v127, v49
	v_dot8c_i32_i4_e32 v43, v127, v47
	v_dot8c_i32_i4_e32 v44, v129, v49
	v_dot8c_i32_i4_e32 v45, v129, v47
	s_waitcnt lgkmcnt(15)
	v_add_u32_e32 v143, 8, v139
	v_and_b32_e32 v142, 15, v143
	v_xor_b32_e32 v142, 8, v142
	v_bfe_u32 v144, v143, 4, 4
	v_mul_lo_u32 v142, v142, s92
	v_mul_lo_u32 v144, v144, s92
	v_mov_b32_e32 v143, v142
	v_mov_b32_e32 v145, v144
	ds_write2st64_b64 v159, v[142:143], v[144:145] offset1:2
	v_and_b32_e32 v78, 0xffff, v20
	v_lshrrev_b32_e32 v79, 16, v20
	v_lshl_add_u32 v78, v78, 7, v150
	v_lshl_add_u32 v79, v79, 7, v151
	s_mov_b32 m0, s78
	s_add_i32 s43, s78, 0x400
	global_load_lds_dwordx4 v78, s[50:51]
	s_mov_b32 m0, s43
	s_nop 0
	global_load_lds_dwordx4 v79, s[50:51]
	s_waitcnt vmcnt(8)
	v_add_u32_e32 v54, s98, v59
	v_add_u32_e32 v55, s98, v60
	v_add_u32_e32 v56, s98, v61
	v_add_u32_e32 v57, s98, v62
	ds_read_b64_tr_b4 v[46:47], v160 offset:768
	ds_read_b64_tr_b4 v[48:49], v160 offset:1792
	ds_read_b64_tr_b4 v[122:123], v54
	ds_read_b64_tr_b4 v[124:125], v55
	ds_read_b64_tr_b4 v[126:127], v56
	ds_read_b64_tr_b4 v[128:129], v57
	s_waitcnt lgkmcnt(7)
	v_dot8c_i32_i4_e32 v38, v130, v52
	v_dot8c_i32_i4_e32 v39, v130, v50
	v_dot8c_i32_i4_e32 v40, v132, v52
	v_dot8c_i32_i4_e32 v41, v132, v50
	v_dot8c_i32_i4_e32 v42, v134, v52
	v_dot8c_i32_i4_e32 v43, v134, v50
	v_dot8c_i32_i4_e32 v44, v136, v52
	v_dot8c_i32_i4_e32 v45, v136, v50
	v_dot8c_i32_i4_e32 v38, v131, v53
	v_dot8c_i32_i4_e32 v39, v131, v51
	v_dot8c_i32_i4_e32 v40, v133, v53
	v_dot8c_i32_i4_e32 v41, v133, v51
	v_dot8c_i32_i4_e32 v42, v135, v53
	v_dot8c_i32_i4_e32 v43, v135, v51
	v_dot8c_i32_i4_e32 v44, v137, v53
	v_dot8c_i32_i4_e32 v45, v137, v51
	v_and_b32_e32 v78, 0xffff, v21
	v_lshrrev_b32_e32 v79, 16, v21
	v_lshl_add_u32 v78, v78, 7, v150
	v_lshl_add_u32 v79, v79, 7, v151
	s_mov_b32 m0, s79
	s_add_i32 s43, s79, 0x400
	global_load_lds_dwordx4 v78, s[50:51]
	s_mov_b32 m0, s43
	s_nop 0
	global_load_lds_dwordx4 v79, s[50:51]
	s_waitcnt vmcnt(8)
	v_add_u32_e32 v54, s99, v59
	v_add_u32_e32 v55, s99, v60
	v_add_u32_e32 v56, s99, v61
	v_add_u32_e32 v57, s99, v62
	ds_read_b64_tr_b4 v[50:51], v160 offset:896
	ds_read_b64_tr_b4 v[52:53], v160 offset:1920
	ds_read_b64_tr_b4 v[130:131], v54
	ds_read_b64_tr_b4 v[132:133], v55
	ds_read_b64_tr_b4 v[134:135], v56
	ds_read_b64_tr_b4 v[136:137], v57
	s_waitcnt lgkmcnt(6)
	v_dot8c_i32_i4_e32 v38, v122, v48
	v_dot8c_i32_i4_e32 v39, v122, v46
	v_dot8c_i32_i4_e32 v40, v124, v48
	v_dot8c_i32_i4_e32 v41, v124, v46
	v_dot8c_i32_i4_e32 v42, v126, v48
	v_dot8c_i32_i4_e32 v43, v126, v46
	v_dot8c_i32_i4_e32 v44, v128, v48
	v_dot8c_i32_i4_e32 v45, v128, v46
	v_dot8c_i32_i4_e32 v38, v123, v49
	v_dot8c_i32_i4_e32 v39, v123, v47
	v_dot8c_i32_i4_e32 v40, v125, v49
	v_dot8c_i32_i4_e32 v41, v125, v47
	v_dot8c_i32_i4_e32 v42, v127, v49
	v_dot8c_i32_i4_e32 v43, v127, v47
	v_dot8c_i32_i4_e32 v44, v129, v49
	v_dot8c_i32_i4_e32 v45, v129, v47
	v_and_b32_e32 v78, 0xffff, v22
	v_lshrrev_b32_e32 v79, 16, v22
	v_lshl_add_u32 v78, v78, 7, v150
	v_lshl_add_u32 v79, v79, 7, v151
	s_mov_b32 m0, s98
	s_add_i32 s43, s98, 0x400
	global_load_lds_dwordx4 v78, s[50:51]
	s_mov_b32 m0, s43
	s_nop 0
	global_load_lds_dwordx4 v79, s[50:51]
	s_waitcnt vmcnt(8)
	v_add_u32_e32 v54, s76, v59
	v_add_u32_e32 v55, s76, v60
	v_add_u32_e32 v56, s76, v61
	v_add_u32_e32 v57, s76, v62
	ds_read_b64_tr_b4 v[46:47], v160
	ds_read_b64_tr_b4 v[48:49], v160 offset:1024
	ds_read_b64_tr_b4 v[122:123], v54
	ds_read_b64_tr_b4 v[124:125], v55
	ds_read_b64_tr_b4 v[126:127], v56
	ds_read_b64_tr_b4 v[128:129], v57
	s_waitcnt lgkmcnt(6)
	v_dot8c_i32_i4_e32 v38, v130, v52
	v_dot8c_i32_i4_e32 v39, v130, v50
	v_dot8c_i32_i4_e32 v40, v132, v52
	v_dot8c_i32_i4_e32 v41, v132, v50
	v_dot8c_i32_i4_e32 v42, v134, v52
	v_dot8c_i32_i4_e32 v43, v134, v50
	v_dot8c_i32_i4_e32 v44, v136, v52
	v_dot8c_i32_i4_e32 v45, v136, v50
	v_dot8c_i32_i4_e32 v38, v131, v53
	v_dot8c_i32_i4_e32 v39, v131, v51
	v_dot8c_i32_i4_e32 v40, v133, v53
	v_dot8c_i32_i4_e32 v41, v133, v51
	v_dot8c_i32_i4_e32 v42, v135, v53
	v_dot8c_i32_i4_e32 v43, v135, v51
	v_dot8c_i32_i4_e32 v44, v137, v53
	v_dot8c_i32_i4_e32 v45, v137, v51
	s_nop 3
	s_waitcnt lgkmcnt(15)
; __device__ __forceinline__ void peer_v_tokens(int j, const LAS unsigned short* EL, const LAS unsigned char* AL  , const LAS float* ASC  , const LAS int* SAL  , ...
;     ...
;         for (int st = 0; st < 16; ++st) {
;             const int p = st >> 2, q = st & 3;
;             if (st < 14) VDMA(st + 2, (st + 2) % 3);
;             if (st < 14) asm volatile("s_waitcnt vmcnt(8)" ::: "memory");
;             else if (st == 14) asm volatile("s_waitcnt vmcnt(4)" ::: "memory");
;             else asm volatile("s_waitcnt vmcnt(0)" ::: "memory");
;             if (q == 0) {
; #pragma unroll
;                 for (int r = 0; r < 4; ++r) { accH[r] = 0; accL[r] = 0; } }
; #pragma unroll
;             for (int tp = 0; tp < 2; ++tp) {
;                 const v2i ao = TR4(ATL + (2 * q + tp) * 128 + 8 * s16), ah = TR4(ATL + 1024 + (2 * q + tp) * 128 + 8 * s16);
; #pragma unroll
;                 for (int r = 0; r < 4; ++r) {
;                     const v2i d = TR4(ldsb + BUF[st % 3] + 2048 * tp + roff[r]);
;                     accH[r] = __builtin_amdgcn_sdot8(d.x, ah.x, accH[r], false); accH[r] = __builtin_amdgcn_sdot8(d.y, ah.y, accH[r], false);
;                     accL[r] = __builtin_amdgcn_sdot8(d.x, ao.x, accL[r], false); accL[r] = __builtin_amdgcn_sdot8(d.y, ao.y, accL[r], false);
;                 }
;             }
;             asm volatile("s_waitcnt lgkmcnt(0)" ::: "memory");
;             if (q == 3) {
; #pragma unroll
;                 for (int r = 0; r < 4; ++r) STASH[256 * p + 16 * (grp + 4 * r) + pc] = f2bf(asc * (float)(2 * ((accH[r] << 4) + accL[r]) + sa));
;             }
;         }
;         CFENCE();
;         {
;             float4 v[4]; float ss = 0.f;
; #pragma unroll
;             for (int jq = 0; jq < 4; ++jq) { typedef unsigned u2v __attribute__((ext_vector_type(2))); const u2v pw = *(const LAS u2v*)(STASH + 4 * lane + 256 * jq); const uint2 hw = hv[jq];
;                 v[jq] = make_float4(__uint_as_float(hw.x << 16) + __uint_as_float(pw.x << 16), __uint_as_float(hw.x & 0xffff0000u) + __uint_as_float(pw.x & 0xffff0000u),
;                                     __uint_as_float(hw.y << 16) + __uint_as_float(pw.y << 16), __uint_as_float(hw.y & 0xffff0000u) + __uint_as_float(pw.y & 0xffff0000u));
;                 ss += v[jq].x * v[jq].x + v[jq].y * v[jq].y + v[jq].z * v[jq].z + v[jq].w * v[jq].w; }
;             ss = wave_sum(ss);
	v_lshlrev_b32_e32 v38, 5, v38
	v_lshlrev_b32_e32 v39, 1, v39
	v_add3_u32 v38, v39, v229, v38
	v_cvt_f32_i32_e32 v38, v38
	v_mul_f32_e32 v38, v228, v38
	v_lshlrev_b32_e32 v40, 5, v40
	v_lshlrev_b32_e32 v41, 1, v41
	v_add3_u32 v40, v41, v229, v40
	v_cvt_f32_i32_e32 v40, v40
	v_mul_f32_e32 v40, v228, v40
	v_lshlrev_b32_e32 v42, 5, v42
	v_lshlrev_b32_e32 v43, 1, v43
	v_add3_u32 v42, v43, v229, v42
	v_cvt_f32_i32_e32 v42, v42
	v_mul_f32_e32 v42, v228, v42
	v_lshlrev_b32_e32 v44, 5, v44
	v_lshlrev_b32_e32 v45, 1, v45
	v_add3_u32 v44, v45, v229, v44
	v_cvt_f32_i32_e32 v44, v44
	v_mul_f32_e32 v44, v228, v44
	v_cvt_pk_bf16_f32 v176, v38, v40
	v_cvt_pk_bf16_f32 v177, v42, v44
	ds_read_b128 v[252:255], v156 offset:1024
	s_add_i32 s44, s40, 24
	s_ashr_i32 s45, s44, 31
	s_lshl_b64 s[44:45], s[44:45], 12
	v_lshl_add_u64 v[80:81], v[36:37], 0, s[44:45]
	s_waitcnt lgkmcnt(0)
	v_mul_f32_e32 v248, v248, v252
	v_mul_f32_e32 v249, v249, v253
	v_mul_f32_e32 v250, v250, v254
	v_mul_f32_e32 v251, v251, v255
	global_store_dwordx4 v[80:81], v[248:251], off offset:3072 sc1
	v_add_u32_e32 v147, 8, v140
	v_and_b32_e32 v146, 15, v147
	v_xor_b32_e32 v146, 8, v146
	v_bfe_u32 v148, v147, 4, 4
	v_mul_lo_u32 v146, v146, s92
	v_mul_lo_u32 v148, v148, s92
	v_mov_b32_e32 v147, v146
	v_mov_b32_e32 v149, v148
	ds_write2st64_b64 v77, v[146:147], v[148:149] offset1:2
	v_add_u32_e32 v138, 0x1c00, v74
	ds_read_u8 v139, v138
	v_add_u32_e32 v141, 0x1c00, v73
	ds_read_u8 v140, v141
	s_add_i32 s43, s67, 192
	v_mov_b32_e32 v138, s43
	ds_read2st64_b32 v[228:229], v138 offset1:1
	ds_read_b128 v[26:29], v227 offset:14336
	ds_read_b128 v[30:33], v227 offset:14352
	v_mov_b32_e32 v38, 0
	v_mov_b32_e32 v39, 0
	v_mov_b32_e32 v40, 0
	v_mov_b32_e32 v41, 0
	v_mov_b32_e32 v42, 0
	v_mov_b32_e32 v43, 0
	v_mov_b32_e32 v44, 0
	v_mov_b32_e32 v45, 0
	v_and_b32_e32 v78, 0xffff, v23
	v_lshrrev_b32_e32 v79, 16, v23
	v_lshl_add_u32 v78, v78, 7, v150
	v_lshl_add_u32 v79, v79, 7, v151
	s_mov_b32 m0, s99
	s_add_i32 s43, s99, 0x400
	global_load_lds_dwordx4 v78, s[50:51]
	s_mov_b32 m0, s43
	s_nop 0
	global_load_lds_dwordx4 v79, s[50:51]
	s_waitcnt vmcnt(9)
	v_add_u32_e32 v54, s77, v59
	v_add_u32_e32 v55, s77, v60
	v_add_u32_e32 v56, s77, v61
	v_add_u32_e32 v57, s77, v62
	ds_read_b64_tr_b4 v[50:51], v160 offset:128
	ds_read_b64_tr_b4 v[52:53], v160 offset:1152
	ds_read_b64_tr_b4 v[130:131], v54
	ds_read_b64_tr_b4 v[132:133], v55
	ds_read_b64_tr_b4 v[134:135], v56
	ds_read_b64_tr_b4 v[136:137], v57
	s_waitcnt lgkmcnt(13)
	v_dot8c_i32_i4_e32 v38, v122, v48
	v_dot8c_i32_i4_e32 v39, v122, v46
	v_dot8c_i32_i4_e32 v40, v124, v48
	v_dot8c_i32_i4_e32 v41, v124, v46
	v_dot8c_i32_i4_e32 v42, v126, v48
	v_dot8c_i32_i4_e32 v43, v126, v46
	v_dot8c_i32_i4_e32 v44, v128, v48
	v_dot8c_i32_i4_e32 v45, v128, v46
	v_dot8c_i32_i4_e32 v38, v123, v49
	v_dot8c_i32_i4_e32 v39, v123, v47
	v_dot8c_i32_i4_e32 v40, v125, v49
	v_dot8c_i32_i4_e32 v41, v125, v47
	v_dot8c_i32_i4_e32 v42, v127, v49
	v_dot8c_i32_i4_e32 v43, v127, v47
	v_dot8c_i32_i4_e32 v44, v129, v49
	v_dot8c_i32_i4_e32 v45, v129, v47
	v_and_b32_e32 v78, 0xffff, v24
	v_lshrrev_b32_e32 v79, 16, v24
	v_lshl_add_u32 v78, v78, 7, v150
	v_lshl_add_u32 v79, v79, 7, v151
	s_mov_b32 m0, s76
	s_add_i32 s43, s76, 0x400
	global_load_lds_dwordx4 v78, s[50:51]
	s_mov_b32 m0, s43
	s_nop 0
	global_load_lds_dwordx4 v79, s[50:51]
	s_waitcnt vmcnt(9)
	v_add_u32_e32 v54, s78, v59
	v_add_u32_e32 v55, s78, v60
	v_add_u32_e32 v56, s78, v61
	v_add_u32_e32 v57, s78, v62
	ds_read_b64_tr_b4 v[46:47], v160 offset:256
	ds_read_b64_tr_b4 v[48:49], v160 offset:1280
	ds_read_b64_tr_b4 v[122:123], v54
	ds_read_b64_tr_b4 v[124:125], v55
	ds_read_b64_tr_b4 v[126:127], v56
	ds_read_b64_tr_b4 v[128:129], v57
	s_waitcnt lgkmcnt(6)
	v_dot8c_i32_i4_e32 v38, v130, v52
	v_dot8c_i32_i4_e32 v39, v130, v50
	v_dot8c_i32_i4_e32 v40, v132, v52
	v_dot8c_i32_i4_e32 v41, v132, v50
	v_dot8c_i32_i4_e32 v42, v134, v52
	v_dot8c_i32_i4_e32 v43, v134, v50
	v_dot8c_i32_i4_e32 v44, v136, v52
	v_dot8c_i32_i4_e32 v45, v136, v50
	v_dot8c_i32_i4_e32 v38, v131, v53
	v_dot8c_i32_i4_e32 v39, v131, v51
	v_dot8c_i32_i4_e32 v40, v133, v53
	v_dot8c_i32_i4_e32 v41, v133, v51
	v_dot8c_i32_i4_e32 v42, v135, v53
	v_dot8c_i32_i4_e32 v43, v135, v51
	v_dot8c_i32_i4_e32 v44, v137, v53
	v_dot8c_i32_i4_e32 v45, v137, v51
	ds_write_b16 v65, v162
	ds_write_b16_d16_hi v65, v162 offset:128
	ds_write_b16 v65, v163 offset:256
	ds_write_b16_d16_hi v65, v163 offset:384
	ds_write_b16 v65, v164 offset:512
	ds_write_b16_d16_hi v65, v164 offset:640
	ds_write_b16 v65, v165 offset:768
	ds_write_b16_d16_hi v65, v165 offset:896
	ds_write_b16 v65, v166 offset:1024
	ds_write_b16_d16_hi v65, v166 offset:1152
	ds_write_b16 v65, v167 offset:1280
	ds_write_b16_d16_hi v65, v167 offset:1408
	ds_write_b16 v65, v168 offset:1536
	ds_write_b16_d16_hi v65, v168 offset:1664
	ds_write_b16 v65, v169 offset:1792
	ds_write_b16_d16_hi v65, v169 offset:1920
	ds_read_b64 v[202:203], v154
	ds_read_b64 v[204:205], v154 offset:512
	ds_read_b64 v[206:207], v154 offset:1024
	ds_read_b64 v[208:209], v154 offset:1536
	v_and_b32_e32 v78, 0xffff, v25
	v_lshrrev_b32_e32 v79, 16, v25
	v_lshl_add_u32 v78, v78, 7, v150
	v_lshl_add_u32 v79, v79, 7, v151
	s_mov_b32 m0, s77
	s_add_i32 s43, s77, 0x400
	global_load_lds_dwordx4 v78, s[50:51]
	s_mov_b32 m0, s43
	s_nop 0
	global_load_lds_dwordx4 v79, s[50:51]
	s_waitcnt vmcnt(9)
	v_add_u32_e32 v54, s79, v59
	v_add_u32_e32 v55, s79, v60
	v_add_u32_e32 v56, s79, v61
	v_add_u32_e32 v57, s79, v62
	ds_read_b64_tr_b4 v[50:51], v160 offset:384
	ds_read_b64_tr_b4 v[52:53], v160 offset:1408
	ds_read_b64_tr_b4 v[130:131], v54
	ds_read_b64_tr_b4 v[132:133], v55
	ds_read_b64_tr_b4 v[134:135], v56
	ds_read_b64_tr_b4 v[136:137], v57
	s_waitcnt lgkmcnt(15)
; __device__ __forceinline__ void peer_v_tokens(int j, const LAS unsigned short* EL, const LAS unsigned char* AL  , const LAS float* ASC  , const LAS int* SAL  , ...
;     ...
; #pragma unroll 1
;     for (int it = 0; it < 8; ++it) {
;         const int tl = it * 8 + wave, t = j * 64 + tl;
;         unsigned E[8];
;         { const LAS v4u* ep = (const LAS v4u*)(EL + tl * 128 + 16 * g); const v4u e0 = ep[0], e1 = ep[1];
;           E[0] = e0.x; E[1] = e0.y; E[2] = e0.z; E[3] = e0.w; E[4] = e1.x; E[5] = e1.y; E[6] = e1.z; E[7] = e1.w; }
;         uint2 hv[4]; float4 gv[4];
;         { unsigned ho = (unsigned)t * (D / 4) + (unsigned)lane; asm volatile("" : "+v"(ho)); const uint2* hp = (const uint2*)HB + ho; const float4* gp = (const float4*)fng + lane;
; #pragma unroll
;           for (int jq = 0; jq < 4; ++jq) { hv[jq] = hp[64 * jq]; gv[jq] = gp[64 * jq]; } }
;         VDMA(0, 0); VDMA(1, 1);
; #pragma unroll
;         for (int m = 0; m < 2; ++m) {
;             const int idx = lane + 64 * m, tau = idx >> 4, sr = idx & 15, k = 16 * (sr & 7) + 2 * tau + (sr >> 3);
;             const int aq = (int)*(const LAS signed char*)(AL + tl * 128 + k); const int tq = aq + 8;
;             const unsigned lo = (((unsigned)tq & 15u) ^ 8u) * 0x11111111u, hi = ((unsigned)(tq >> 4) & 15u) * 0x11111111u;
;             typedef unsigned u2v __attribute__((ext_vector_type(2)));
;             u2v l2; l2.x = lo; l2.y = lo; u2v h2; h2.x = hi; h2.y = hi;
;             *(LAS u2v*)(ATL + 8 * idx) = l2; *(LAS u2v*)(ATL + 1024 + 8 * idx) = h2;
;         }
;         const float asc = ASC[tl]; const int sa = SAL[tl];
;         CFENCE();
;         int accH[4], accL[4];
; #pragma unroll
;         for (int st = 0; st < 16; ++st) {
;             const int p = st >> 2, q = st & 3;
;             if (st < 14) VDMA(st + 2, (st + 2) % 3);
;             if (st < 14) asm volatile("s_waitcnt vmcnt(8)" ::: "memory");
;             else if (st == 14) asm volatile("s_waitcnt vmcnt(4)" ::: "memory");
;             else asm volatile("s_waitcnt vmcnt(0)" ::: "memory");
;             if (q == 0) {
; #pragma unroll
;                 for (int r = 0; r < 4; ++r) { accH[r] = 0; accL[r] = 0; } }
; #pragma unroll
;             for (int tp = 0; tp < 2; ++tp) {
;                 const v2i ao = TR4(ATL + (2 * q + tp) * 128 + 8 * s16), ah = TR4(ATL + 1024 + (2 * q + tp) * 128 + 8 * s16);
; #pragma unroll
	v_dot8c_i32_i4_e32 v38, v122, v48
	v_dot8c_i32_i4_e32 v39, v122, v46
	v_dot8c_i32_i4_e32 v40, v124, v48
	v_dot8c_i32_i4_e32 v41, v124, v46
	v_dot8c_i32_i4_e32 v42, v126, v48
	v_dot8c_i32_i4_e32 v43, v126, v46
	v_dot8c_i32_i4_e32 v44, v128, v48
	v_dot8c_i32_i4_e32 v45, v128, v46
	v_dot8c_i32_i4_e32 v38, v123, v49
	v_dot8c_i32_i4_e32 v39, v123, v47
	v_dot8c_i32_i4_e32 v40, v125, v49
	v_dot8c_i32_i4_e32 v41, v125, v47
	v_dot8c_i32_i4_e32 v42, v127, v49
	v_dot8c_i32_i4_e32 v43, v127, v47
	v_dot8c_i32_i4_e32 v44, v129, v49
	v_dot8c_i32_i4_e32 v45, v129, v47
	s_waitcnt lgkmcnt(15)
	v_and_b32_e32 v78, 0xffff, v26
	v_lshrrev_b32_e32 v79, 16, v26
	v_lshl_add_u32 v78, v78, 7, v150
	v_lshl_add_u32 v79, v79, 7, v151
	s_mov_b32 m0, s78
	s_add_i32 s43, s78, 0x400
	global_load_lds_dwordx4 v78, s[50:51]
	s_mov_b32 m0, s43
	s_nop 0
	global_load_lds_dwordx4 v79, s[50:51]
	s_waitcnt vmcnt(9)
	v_add_u32_e32 v54, s98, v59
	v_add_u32_e32 v55, s98, v60
	v_add_u32_e32 v56, s98, v61
	v_add_u32_e32 v57, s98, v62
	ds_read_b64_tr_b4 v[46:47], v160 offset:512
	ds_read_b64_tr_b4 v[48:49], v160 offset:1536
	ds_read_b64_tr_b4 v[122:123], v54
	ds_read_b64_tr_b4 v[124:125], v55
	ds_read_b64_tr_b4 v[126:127], v56
	ds_read_b64_tr_b4 v[128:129], v57
	s_waitcnt lgkmcnt(6)
	v_dot8c_i32_i4_e32 v38, v130, v52
	v_dot8c_i32_i4_e32 v39, v130, v50
	v_dot8c_i32_i4_e32 v40, v132, v52
	v_dot8c_i32_i4_e32 v41, v132, v50
	v_dot8c_i32_i4_e32 v42, v134, v52
	v_dot8c_i32_i4_e32 v43, v134, v50
	v_dot8c_i32_i4_e32 v44, v136, v52
	v_dot8c_i32_i4_e32 v45, v136, v50
	v_dot8c_i32_i4_e32 v38, v131, v53
	v_dot8c_i32_i4_e32 v39, v131, v51
	v_dot8c_i32_i4_e32 v40, v133, v53
	v_dot8c_i32_i4_e32 v41, v133, v51
	v_dot8c_i32_i4_e32 v42, v135, v53
	v_dot8c_i32_i4_e32 v43, v135, v51
	v_dot8c_i32_i4_e32 v44, v137, v53
	v_dot8c_i32_i4_e32 v45, v137, v51
	v_and_b32_e32 v78, 0xffff, v27
	v_lshrrev_b32_e32 v79, 16, v27
	v_lshl_add_u32 v78, v78, 7, v150
	v_lshl_add_u32 v79, v79, 7, v151
	s_mov_b32 m0, s79
	s_add_i32 s43, s79, 0x400
	global_load_lds_dwordx4 v78, s[50:51]
	s_mov_b32 m0, s43
	s_nop 0
	global_load_lds_dwordx4 v79, s[50:51]
	s_waitcnt vmcnt(8)
	v_add_u32_e32 v54, s99, v59
	v_add_u32_e32 v55, s99, v60
	v_add_u32_e32 v56, s99, v61
	v_add_u32_e32 v57, s99, v62
	ds_read_b64_tr_b4 v[50:51], v160 offset:640
	ds_read_b64_tr_b4 v[52:53], v160 offset:1664
	ds_read_b64_tr_b4 v[130:131], v54
	ds_read_b64_tr_b4 v[132:133], v55
	ds_read_b64_tr_b4 v[134:135], v56
	ds_read_b64_tr_b4 v[136:137], v57
	s_waitcnt lgkmcnt(6)
	v_dot8c_i32_i4_e32 v38, v122, v48
	v_dot8c_i32_i4_e32 v39, v122, v46
	v_dot8c_i32_i4_e32 v40, v124, v48
	v_dot8c_i32_i4_e32 v41, v124, v46
	v_dot8c_i32_i4_e32 v42, v126, v48
	v_dot8c_i32_i4_e32 v43, v126, v46
	v_dot8c_i32_i4_e32 v44, v128, v48
	v_dot8c_i32_i4_e32 v45, v128, v46
	v_dot8c_i32_i4_e32 v38, v123, v49
	v_dot8c_i32_i4_e32 v39, v123, v47
	v_dot8c_i32_i4_e32 v40, v125, v49
	v_dot8c_i32_i4_e32 v41, v125, v47
	v_dot8c_i32_i4_e32 v42, v127, v49
	v_dot8c_i32_i4_e32 v43, v127, v47
	v_dot8c_i32_i4_e32 v44, v129, v49
	v_dot8c_i32_i4_e32 v45, v129, v47
	s_waitcnt lgkmcnt(15)
	v_add_u32_e32 v143, 8, v139
	v_and_b32_e32 v142, 15, v143
	v_xor_b32_e32 v142, 8, v142
	v_bfe_u32 v144, v143, 4, 4
	v_mul_lo_u32 v142, v142, s92
	v_mul_lo_u32 v144, v144, s92
	v_mov_b32_e32 v143, v142
	v_mov_b32_e32 v145, v144
	ds_write2st64_b64 v159, v[142:143], v[144:145] offset1:2
	v_and_b32_e32 v78, 0xffff, v28
	v_lshrrev_b32_e32 v79, 16, v28
	v_lshl_add_u32 v78, v78, 7, v150
	v_lshl_add_u32 v79, v79, 7, v151
	s_mov_b32 m0, s98
	s_add_i32 s43, s98, 0x400
	global_load_lds_dwordx4 v78, s[50:51]
	s_mov_b32 m0, s43
	s_nop 0
	global_load_lds_dwordx4 v79, s[50:51]
	s_waitcnt vmcnt(8)
	v_add_u32_e32 v54, s76, v59
	v_add_u32_e32 v55, s76, v60
	v_add_u32_e32 v56, s76, v61
	v_add_u32_e32 v57, s76, v62
	ds_read_b64_tr_b4 v[46:47], v160 offset:768
	ds_read_b64_tr_b4 v[48:49], v160 offset:1792
	ds_read_b64_tr_b4 v[122:123], v54
	ds_read_b64_tr_b4 v[124:125], v55
	ds_read_b64_tr_b4 v[126:127], v56
	ds_read_b64_tr_b4 v[128:129], v57
	s_waitcnt lgkmcnt(7)
	v_dot8c_i32_i4_e32 v38, v130, v52
	v_dot8c_i32_i4_e32 v39, v130, v50
	v_dot8c_i32_i4_e32 v40, v132, v52
	v_dot8c_i32_i4_e32 v41, v132, v50
	v_dot8c_i32_i4_e32 v42, v134, v52
	v_dot8c_i32_i4_e32 v43, v134, v50
	v_dot8c_i32_i4_e32 v44, v136, v52
	v_dot8c_i32_i4_e32 v45, v136, v50
	v_dot8c_i32_i4_e32 v38, v131, v53
	v_dot8c_i32_i4_e32 v39, v131, v51
	v_dot8c_i32_i4_e32 v40, v133, v53
	v_dot8c_i32_i4_e32 v41, v133, v51
	v_dot8c_i32_i4_e32 v42, v135, v53
	v_dot8c_i32_i4_e32 v43, v135, v51
	v_dot8c_i32_i4_e32 v44, v137, v53
	v_dot8c_i32_i4_e32 v45, v137, v51
	v_and_b32_e32 v78, 0xffff, v29
	v_lshrrev_b32_e32 v79, 16, v29
	v_lshl_add_u32 v78, v78, 7, v150
	v_lshl_add_u32 v79, v79, 7, v151
	s_mov_b32 m0, s99
	s_add_i32 s43, s99, 0x400
	global_load_lds_dwordx4 v78, s[50:51]
	s_mov_b32 m0, s43
	s_nop 0
	global_load_lds_dwordx4 v79, s[50:51]
	s_waitcnt vmcnt(8)
	v_add_u32_e32 v54, s77, v59
	v_add_u32_e32 v55, s77, v60
	v_add_u32_e32 v56, s77, v61
	v_add_u32_e32 v57, s77, v62
	ds_read_b64_tr_b4 v[50:51], v160 offset:896
	ds_read_b64_tr_b4 v[52:53], v160 offset:1920
	ds_read_b64_tr_b4 v[130:131], v54
	ds_read_b64_tr_b4 v[132:133], v55
	ds_read_b64_tr_b4 v[134:135], v56
	ds_read_b64_tr_b4 v[136:137], v57
	s_waitcnt lgkmcnt(6)
; __device__ __forceinline__ void peer_v_tokens(int j, const LAS unsigned short* EL, const LAS unsigned char* AL  , const LAS float* ASC  , const LAS int* SAL  , ...
;     ...
;         for (int st = 0; st < 16; ++st) {
;             const int p = st >> 2, q = st & 3;
;             if (st < 14) VDMA(st + 2, (st + 2) % 3);
;             if (st < 14) asm volatile("s_waitcnt vmcnt(8)" ::: "memory");
;             else if (st == 14) asm volatile("s_waitcnt vmcnt(4)" ::: "memory");
;             else asm volatile("s_waitcnt vmcnt(0)" ::: "memory");
;             if (q == 0) {
; #pragma unroll
;                 for (int r = 0; r < 4; ++r) { accH[r] = 0; accL[r] = 0; } }
; #pragma unroll
;             for (int tp = 0; tp < 2; ++tp) {
;                 const v2i ao = TR4(ATL + (2 * q + tp) * 128 + 8 * s16), ah = TR4(ATL + 1024 + (2 * q + tp) * 128 + 8 * s16);
; #pragma unroll
;                 for (int r = 0; r < 4; ++r) {
;                     const v2i d = TR4(ldsb + BUF[st % 3] + 2048 * tp + roff[r]);
;                     accH[r] = __builtin_amdgcn_sdot8(d.x, ah.x, accH[r], false); accH[r] = __builtin_amdgcn_sdot8(d.y, ah.y, accH[r], false);
;                     accL[r] = __builtin_amdgcn_sdot8(d.x, ao.x, accL[r], false); accL[r] = __builtin_amdgcn_sdot8(d.y, ao.y, accL[r], false);
;                 }
;             }
;             asm volatile("s_waitcnt lgkmcnt(0)" ::: "memory");
;             if (q == 3) {
; #pragma unroll
;                 for (int r = 0; r < 4; ++r) STASH[256 * p + 16 * (grp + 4 * r) + pc] = f2bf(asc * (float)(2 * ((accH[r] << 4) + accL[r]) + sa));
;             }
;         }
;         CFENCE();
;         {
;             float4 v[4]; float ss = 0.f;
; #pragma unroll
;             for (int jq = 0; jq < 4; ++jq) { typedef unsigned u2v __attribute__((ext_vector_type(2))); const u2v pw = *(const LAS u2v*)(STASH + 4 * lane + 256 * jq); const uint2 hw = hv[jq];
;                 v[jq] = make_float4(__uint_as_float(hw.x << 16) + __uint_as_float(pw.x << 16), __uint_as_float(hw.x & 0xffff0000u) + __uint_as_float(pw.x & 0xffff0000u),
;                                     __uint_as_float(hw.y << 16) + __uint_as_float(pw.y << 16), __uint_as_float(hw.y & 0xffff0000u) + __uint_as_float(pw.y & 0xffff0000u));
;                 ss += v[jq].x * v[jq].x + v[jq].y * v[jq].y + v[jq].z * v[jq].z + v[jq].w * v[jq].w; }
;             ss = wave_sum(ss);
	v_dot8c_i32_i4_e32 v38, v122, v48
	v_dot8c_i32_i4_e32 v39, v122, v46
	v_dot8c_i32_i4_e32 v40, v124, v48
	v_dot8c_i32_i4_e32 v41, v124, v46
	v_dot8c_i32_i4_e32 v42, v126, v48
	v_dot8c_i32_i4_e32 v43, v126, v46
	v_dot8c_i32_i4_e32 v44, v128, v48
	v_dot8c_i32_i4_e32 v45, v128, v46
	v_dot8c_i32_i4_e32 v38, v123, v49
	v_dot8c_i32_i4_e32 v39, v123, v47
	v_dot8c_i32_i4_e32 v40, v125, v49
	v_dot8c_i32_i4_e32 v41, v125, v47
	v_dot8c_i32_i4_e32 v42, v127, v49
	v_dot8c_i32_i4_e32 v43, v127, v47
	v_dot8c_i32_i4_e32 v44, v129, v49
	v_dot8c_i32_i4_e32 v45, v129, v47
	v_and_b32_e32 v78, 0xffff, v30
	v_lshrrev_b32_e32 v79, 16, v30
	v_lshl_add_u32 v78, v78, 7, v150
	v_lshl_add_u32 v79, v79, 7, v151
	s_mov_b32 m0, s76
	s_add_i32 s43, s76, 0x400
	global_load_lds_dwordx4 v78, s[50:51]
	s_mov_b32 m0, s43
	s_nop 0
	global_load_lds_dwordx4 v79, s[50:51]
	s_waitcnt vmcnt(8)
	v_add_u32_e32 v54, s78, v59
	v_add_u32_e32 v55, s78, v60
	v_add_u32_e32 v56, s78, v61
	v_add_u32_e32 v57, s78, v62
	ds_read_b64_tr_b4 v[46:47], v160
	ds_read_b64_tr_b4 v[48:49], v160 offset:1024
	ds_read_b64_tr_b4 v[122:123], v54
	ds_read_b64_tr_b4 v[124:125], v55
	ds_read_b64_tr_b4 v[126:127], v56
	ds_read_b64_tr_b4 v[128:129], v57
	s_waitcnt lgkmcnt(6)
	v_dot8c_i32_i4_e32 v38, v130, v52
	v_dot8c_i32_i4_e32 v39, v130, v50
	v_dot8c_i32_i4_e32 v40, v132, v52
	v_dot8c_i32_i4_e32 v41, v132, v50
	v_dot8c_i32_i4_e32 v42, v134, v52
	v_dot8c_i32_i4_e32 v43, v134, v50
	v_dot8c_i32_i4_e32 v44, v136, v52
	v_dot8c_i32_i4_e32 v45, v136, v50
	v_dot8c_i32_i4_e32 v38, v131, v53
	v_dot8c_i32_i4_e32 v39, v131, v51
	v_dot8c_i32_i4_e32 v40, v133, v53
	v_dot8c_i32_i4_e32 v41, v133, v51
	v_dot8c_i32_i4_e32 v42, v135, v53
	v_dot8c_i32_i4_e32 v43, v135, v51
	v_dot8c_i32_i4_e32 v44, v137, v53
	v_dot8c_i32_i4_e32 v45, v137, v51
	s_nop 3
	s_waitcnt lgkmcnt(15)
	v_lshlrev_b32_e32 v38, 5, v38
	v_lshlrev_b32_e32 v39, 1, v39
	v_add3_u32 v38, v39, v229, v38
	v_cvt_f32_i32_e32 v38, v38
	v_mul_f32_e32 v38, v228, v38
	v_lshlrev_b32_e32 v40, 5, v40
	v_lshlrev_b32_e32 v41, 1, v41
	v_add3_u32 v40, v41, v229, v40
	v_cvt_f32_i32_e32 v40, v40
	v_mul_f32_e32 v40, v228, v40
	v_lshlrev_b32_e32 v42, 5, v42
	v_lshlrev_b32_e32 v43, 1, v43
	v_add3_u32 v42, v43, v229, v42
	v_cvt_f32_i32_e32 v42, v42
	v_mul_f32_e32 v42, v228, v42
	v_lshlrev_b32_e32 v44, 5, v44
	v_lshlrev_b32_e32 v45, 1, v45
	v_add3_u32 v44, v45, v229, v44
	v_cvt_f32_i32_e32 v44, v44
	v_mul_f32_e32 v44, v228, v44
	v_cvt_pk_bf16_f32 v178, v38, v40
	v_cvt_pk_bf16_f32 v179, v42, v44
	v_add_u32_e32 v147, 8, v140
	v_and_b32_e32 v146, 15, v147
	v_xor_b32_e32 v146, 8, v146
	v_bfe_u32 v148, v147, 4, 4
	v_mul_lo_u32 v146, v146, s92
	v_mul_lo_u32 v148, v148, s92
	v_mov_b32_e32 v147, v146
	v_mov_b32_e32 v149, v148
	ds_write2st64_b64 v77, v[146:147], v[148:149] offset1:2
	v_add_u32_e32 v138, 0x1800, v74
	ds_read_u8 v139, v138
	v_add_u32_e32 v141, 0x1800, v73
	ds_read_u8 v140, v141
	s_add_i32 s43, s67, 224
	v_mov_b32_e32 v138, s43
	ds_read2st64_b32 v[228:229], v138 offset1:1
	ds_read_b128 v[18:21], v227 offset:12288
	ds_read_b128 v[22:25], v227 offset:12304
	v_add_u32_e32 v152, 0x200000, v63
	v_add_u32_e32 v153, 0x200000, v64
	v_mov_b32_e32 v38, 0
	v_mov_b32_e32 v39, 0
	v_mov_b32_e32 v40, 0
	v_mov_b32_e32 v41, 0
	v_mov_b32_e32 v42, 0
	v_mov_b32_e32 v43, 0
	v_mov_b32_e32 v44, 0
	v_mov_b32_e32 v45, 0
	v_and_b32_e32 v78, 0xffff, v31
	v_lshrrev_b32_e32 v79, 16, v31
	v_lshl_add_u32 v78, v78, 7, v150
	v_lshl_add_u32 v79, v79, 7, v151
	s_mov_b32 m0, s77
	s_add_i32 s43, s77, 0x400
	global_load_lds_dwordx4 v78, s[50:51]
	s_mov_b32 m0, s43
	s_nop 0
	global_load_lds_dwordx4 v79, s[50:51]
	s_waitcnt vmcnt(8)
	v_add_u32_e32 v54, s79, v59
	v_add_u32_e32 v55, s79, v60
	v_add_u32_e32 v56, s79, v61
	v_add_u32_e32 v57, s79, v62
	ds_read_b64_tr_b4 v[50:51], v160 offset:128
	ds_read_b64_tr_b4 v[52:53], v160 offset:1152
	ds_read_b64_tr_b4 v[130:131], v54
	ds_read_b64_tr_b4 v[132:133], v55
	ds_read_b64_tr_b4 v[134:135], v56
	ds_read_b64_tr_b4 v[136:137], v57
	s_waitcnt lgkmcnt(12)
	s_waitcnt vmcnt(35) lgkmcnt(15)
	v_lshlrev_b32_e32 v210, 16, v194
	v_and_b32_e32 v211, 0xffff0000, v194
	v_lshlrev_b32_e32 v142, 16, v202
	v_and_b32_e32 v143, 0xffff0000, v202
	v_add_f32_e32 v210, v210, v142
	v_add_f32_e32 v211, v211, v143
	v_lshlrev_b32_e32 v212, 16, v195
	v_and_b32_e32 v213, 0xffff0000, v195
	v_lshlrev_b32_e32 v142, 16, v203
	v_and_b32_e32 v143, 0xffff0000, v203
	v_add_f32_e32 v212, v212, v142
	v_add_f32_e32 v213, v213, v143
	v_lshlrev_b32_e32 v214, 16, v196
	v_and_b32_e32 v215, 0xffff0000, v196
	v_lshlrev_b32_e32 v142, 16, v204
	v_and_b32_e32 v143, 0xffff0000, v204
	v_add_f32_e32 v214, v214, v142
	v_add_f32_e32 v215, v215, v143
	v_lshlrev_b32_e32 v216, 16, v197
	v_and_b32_e32 v217, 0xffff0000, v197
	v_lshlrev_b32_e32 v142, 16, v205
	v_and_b32_e32 v143, 0xffff0000, v205
	v_add_f32_e32 v216, v216, v142
	v_add_f32_e32 v217, v217, v143
	v_lshlrev_b32_e32 v218, 16, v198
	v_and_b32_e32 v219, 0xffff0000, v198
	v_lshlrev_b32_e32 v142, 16, v206
	v_and_b32_e32 v143, 0xffff0000, v206
	v_add_f32_e32 v218, v218, v142
	v_add_f32_e32 v219, v219, v143
	v_lshlrev_b32_e32 v220, 16, v199
	v_and_b32_e32 v221, 0xffff0000, v199
	v_lshlrev_b32_e32 v142, 16, v207
	v_and_b32_e32 v143, 0xffff0000, v207
	v_add_f32_e32 v220, v220, v142
	v_add_f32_e32 v221, v221, v143
	v_lshlrev_b32_e32 v222, 16, v200
	v_and_b32_e32 v223, 0xffff0000, v200
	v_lshlrev_b32_e32 v142, 16, v208
	v_and_b32_e32 v143, 0xffff0000, v208
	v_add_f32_e32 v222, v222, v142
	v_add_f32_e32 v223, v223, v143
	v_lshlrev_b32_e32 v224, 16, v201
	v_and_b32_e32 v225, 0xffff0000, v201
	v_lshlrev_b32_e32 v142, 16, v209
	v_and_b32_e32 v143, 0xffff0000, v209
	v_add_f32_e32 v224, v224, v142
; #define TR4(p_) __builtin_amdgcn_ds_read_tr4_b64_v2i32((LAS v2i*)(p_))
; __device__ __forceinline__ void peer_v_tokens(int j, const LAS unsigned short* EL, const LAS unsigned char* AL  , const LAS float* ASC  , const LAS int* SAL  , ...
;     ...
; #pragma unroll
;             for (int tp = 0; tp < 2; ++tp) {
;                 const v2i ao = TR4(ATL + (2 * q + tp) * 128 + 8 * s16), ah = TR4(ATL + 1024 + (2 * q + tp) * 128 + 8 * s16);
; #pragma unroll
;                 for (int r = 0; r < 4; ++r) {
;                     const v2i d = TR4(ldsb + BUF[st % 3] + 2048 * tp + roff[r]);
;                     accH[r] = __builtin_amdgcn_sdot8(d.x, ah.x, accH[r], false); accH[r] = __builtin_amdgcn_sdot8(d.y, ah.y, accH[r], false);
;                     accL[r] = __builtin_amdgcn_sdot8(d.x, ao.x, accL[r], false); accL[r] = __builtin_amdgcn_sdot8(d.y, ao.y, accL[r], false);
;                 }
;     ...
;                 ss += v[jq].x * v[jq].x + v[jq].y * v[jq].y + v[jq].z * v[jq].z + v[jq].w * v[jq].w; }
;             ss = wave_sum(ss);
;             const float r3 = rsqrtf(ss * (1.f / D) + EPS);
	v_add_f32_e32 v225, v225, v143
	v_mov_b32_e32 v144, 0
	v_mul_f32_e32 v145, v210, v210
	v_fmac_f32_e32 v145, v211, v211
	v_fmac_f32_e32 v145, v212, v212
	v_fmac_f32_e32 v145, v213, v213
	v_add_f32_e32 v144, v144, v145
	v_mul_f32_e32 v145, v214, v214
	v_fmac_f32_e32 v145, v215, v215
	v_fmac_f32_e32 v145, v216, v216
	v_fmac_f32_e32 v145, v217, v217
	v_add_f32_e32 v144, v144, v145
	v_mul_f32_e32 v145, v218, v218
	v_fmac_f32_e32 v145, v219, v219
	v_fmac_f32_e32 v145, v220, v220
	v_fmac_f32_e32 v145, v221, v221
	v_add_f32_e32 v144, v144, v145
	v_mul_f32_e32 v145, v222, v222
	v_fmac_f32_e32 v145, v223, v223
	v_fmac_f32_e32 v145, v224, v224
	v_fmac_f32_e32 v145, v225, v225
	v_add_f32_e32 v144, v144, v145
	s_nop 1
	v_add_f32_dpp v144, v144, v144 quad_perm:[1,0,3,2] row_mask:0xf bank_mask:0xf bound_ctrl:1
	s_nop 1
	v_add_f32_dpp v144, v144, v144 quad_perm:[2,3,0,1] row_mask:0xf bank_mask:0xf bound_ctrl:1
	s_nop 1
	v_add_f32_dpp v144, v144, v144 row_half_mirror row_mask:0xf bank_mask:0xf bound_ctrl:1
	s_nop 1
	v_add_f32_dpp v144, v144, v144 row_mirror row_mask:0xf bank_mask:0xf bound_ctrl:1
	s_nop 1
	v_readlane_b32 s10, v144, 0
	v_readlane_b32 s11, v144, 16
	v_readlane_b32 s14, v144, 32
	v_readlane_b32 s15, v144, 48
	s_nop 3
	v_mov_b32_e32 v144, s11
	v_mov_b32_e32 v145, s15
	v_add_f32_e32 v144, s10, v144
	v_add_f32_e32 v145, s14, v145
	v_add_f32_e32 v144, v144, v145
	v_fmamk_f32 v144, v144, 0x3a800000, v111
	v_rsq_f32_e32 v144, v144
	s_nop 0
	v_mul_f32_e32 v210, v210, v144
	v_mul_f32_e32 v211, v211, v144
	v_mul_f32_e32 v212, v212, v144
	v_mul_f32_e32 v213, v213, v144
	v_mul_f32_e32 v214, v214, v144
	v_mul_f32_e32 v215, v215, v144
	v_mul_f32_e32 v216, v216, v144
	v_mul_f32_e32 v217, v217, v144
	v_mul_f32_e32 v218, v218, v144
	v_mul_f32_e32 v219, v219, v144
	v_mul_f32_e32 v220, v220, v144
	v_mul_f32_e32 v221, v221, v144
	v_mul_f32_e32 v222, v222, v144
	v_mul_f32_e32 v223, v223, v144
	v_mul_f32_e32 v224, v224, v144
	v_mul_f32_e32 v225, v225, v144
	v_dot8c_i32_i4_e32 v38, v122, v48
	v_dot8c_i32_i4_e32 v39, v122, v46
	v_dot8c_i32_i4_e32 v40, v124, v48
	v_dot8c_i32_i4_e32 v41, v124, v46
	v_dot8c_i32_i4_e32 v42, v126, v48
	v_dot8c_i32_i4_e32 v43, v126, v46
	v_dot8c_i32_i4_e32 v44, v128, v48
	v_dot8c_i32_i4_e32 v45, v128, v46
	v_dot8c_i32_i4_e32 v38, v123, v49
	v_dot8c_i32_i4_e32 v39, v123, v47
	v_dot8c_i32_i4_e32 v40, v125, v49
	v_dot8c_i32_i4_e32 v41, v125, v47
	v_dot8c_i32_i4_e32 v42, v127, v49
	v_dot8c_i32_i4_e32 v43, v127, v47
	v_dot8c_i32_i4_e32 v44, v129, v49
	v_dot8c_i32_i4_e32 v45, v129, v47
	v_and_b32_e32 v78, 0xffff, v32
	v_lshrrev_b32_e32 v79, 16, v32
	v_lshl_add_u32 v78, v78, 7, v150
	v_lshl_add_u32 v79, v79, 7, v151
	s_mov_b32 m0, s78
	s_add_i32 s43, s78, 0x400
	global_load_lds_dwordx4 v78, s[50:51]
	s_mov_b32 m0, s43
	s_nop 0
	global_load_lds_dwordx4 v79, s[50:51]
	s_waitcnt vmcnt(8)
	v_add_u32_e32 v54, s98, v59
	v_add_u32_e32 v55, s98, v60
	v_add_u32_e32 v56, s98, v61
	v_add_u32_e32 v57, s98, v62
	ds_read_b64_tr_b4 v[46:47], v160 offset:256
	ds_read_b64_tr_b4 v[48:49], v160 offset:1280
	ds_read_b64_tr_b4 v[122:123], v54
	ds_read_b64_tr_b4 v[124:125], v55
	ds_read_b64_tr_b4 v[126:127], v56
	ds_read_b64_tr_b4 v[128:129], v57
	s_waitcnt lgkmcnt(6)
	v_dot8c_i32_i4_e32 v38, v130, v52
	v_dot8c_i32_i4_e32 v39, v130, v50
	v_dot8c_i32_i4_e32 v40, v132, v52
	v_dot8c_i32_i4_e32 v41, v132, v50
	v_dot8c_i32_i4_e32 v42, v134, v52
	v_dot8c_i32_i4_e32 v43, v134, v50
	v_dot8c_i32_i4_e32 v44, v136, v52
	v_dot8c_i32_i4_e32 v45, v136, v50
	v_dot8c_i32_i4_e32 v38, v131, v53
	v_dot8c_i32_i4_e32 v39, v131, v51
	v_dot8c_i32_i4_e32 v40, v133, v53
	v_dot8c_i32_i4_e32 v41, v133, v51
	v_dot8c_i32_i4_e32 v42, v135, v53
	v_dot8c_i32_i4_e32 v43, v135, v51
	v_dot8c_i32_i4_e32 v44, v137, v53
	v_dot8c_i32_i4_e32 v45, v137, v51
	v_and_b32_e32 v78, 0xffff, v33
	v_lshrrev_b32_e32 v79, 16, v33
	v_lshl_add_u32 v78, v78, 7, v150
	v_lshl_add_u32 v79, v79, 7, v151
	s_mov_b32 m0, s79
	s_add_i32 s43, s79, 0x400
	global_load_lds_dwordx4 v78, s[50:51]
	s_mov_b32 m0, s43
	s_nop 0
	global_load_lds_dwordx4 v79, s[50:51]
	s_waitcnt vmcnt(8)
	v_add_u32_e32 v54, s99, v59
	v_add_u32_e32 v55, s99, v60
	v_add_u32_e32 v56, s99, v61
	v_add_u32_e32 v57, s99, v62
	ds_read_b64_tr_b4 v[50:51], v160 offset:384
	ds_read_b64_tr_b4 v[52:53], v160 offset:1408
	ds_read_b64_tr_b4 v[130:131], v54
	ds_read_b64_tr_b4 v[132:133], v55
	ds_read_b64_tr_b4 v[134:135], v56
	ds_read_b64_tr_b4 v[136:137], v57
	s_waitcnt lgkmcnt(6)
	v_dot8c_i32_i4_e32 v38, v122, v48
	v_dot8c_i32_i4_e32 v39, v122, v46
	v_dot8c_i32_i4_e32 v40, v124, v48
	v_dot8c_i32_i4_e32 v41, v124, v46
	v_dot8c_i32_i4_e32 v42, v126, v48
	v_dot8c_i32_i4_e32 v43, v126, v46
	v_dot8c_i32_i4_e32 v44, v128, v48
	v_dot8c_i32_i4_e32 v45, v128, v46
	v_dot8c_i32_i4_e32 v38, v123, v49
	v_dot8c_i32_i4_e32 v39, v123, v47
	v_dot8c_i32_i4_e32 v40, v125, v49
	v_dot8c_i32_i4_e32 v41, v125, v47
	v_dot8c_i32_i4_e32 v42, v127, v49
	v_dot8c_i32_i4_e32 v43, v127, v47
	v_dot8c_i32_i4_e32 v44, v129, v49
	v_dot8c_i32_i4_e32 v45, v129, v47
	s_waitcnt lgkmcnt(15)
	v_and_b32_e32 v78, 0xffff, v18
	v_lshrrev_b32_e32 v79, 16, v18
	v_lshl_add_u32 v78, v78, 7, v152
	v_lshl_add_u32 v79, v79, 7, v153
	s_mov_b32 m0, s98
	s_add_i32 s43, s98, 0x400
	global_load_lds_dwordx4 v78, s[50:51]
	s_mov_b32 m0, s43
	s_nop 0
	global_load_lds_dwordx4 v79, s[50:51]
	s_waitcnt vmcnt(8)
	v_add_u32_e32 v54, s76, v59
	v_add_u32_e32 v55, s76, v60
	v_add_u32_e32 v56, s76, v61
	v_add_u32_e32 v57, s76, v62
	ds_read_b64_tr_b4 v[46:47], v160 offset:512
	ds_read_b64_tr_b4 v[48:49], v160 offset:1536
	ds_read_b64_tr_b4 v[122:123], v54
	ds_read_b64_tr_b4 v[124:125], v55
	ds_read_b64_tr_b4 v[126:127], v56
	ds_read_b64_tr_b4 v[128:129], v57
	s_waitcnt lgkmcnt(6)
; __device__ __forceinline__ void peer_v_tokens(int j, const LAS unsigned short* EL, const LAS unsigned char* AL  , const LAS float* ASC  , const LAS int* SAL  , ...
;     ...
; #pragma unroll 1
;     for (int it = 0; it < 8; ++it) {
;         const int tl = it * 8 + wave, t = j * 64 + tl;
;         unsigned E[8];
;         { const LAS v4u* ep = (const LAS v4u*)(EL + tl * 128 + 16 * g); const v4u e0 = ep[0], e1 = ep[1];
;           E[0] = e0.x; E[1] = e0.y; E[2] = e0.z; E[3] = e0.w; E[4] = e1.x; E[5] = e1.y; E[6] = e1.z; E[7] = e1.w; }
;         uint2 hv[4]; float4 gv[4];
;         { unsigned ho = (unsigned)t * (D / 4) + (unsigned)lane; asm volatile("" : "+v"(ho)); const uint2* hp = (const uint2*)HB + ho; const float4* gp = (const float4*)fng + lane;
; #pragma unroll
;           for (int jq = 0; jq < 4; ++jq) { hv[jq] = hp[64 * jq]; gv[jq] = gp[64 * jq]; } }
;         VDMA(0, 0); VDMA(1, 1);
; #pragma unroll
;         for (int m = 0; m < 2; ++m) {
;             const int idx = lane + 64 * m, tau = idx >> 4, sr = idx & 15, k = 16 * (sr & 7) + 2 * tau + (sr >> 3);
;             const int aq = (int)*(const LAS signed char*)(AL + tl * 128 + k); const int tq = aq + 8;
;             const unsigned lo = (((unsigned)tq & 15u) ^ 8u) * 0x11111111u, hi = ((unsigned)(tq >> 4) & 15u) * 0x11111111u;
;             typedef unsigned u2v __attribute__((ext_vector_type(2)));
;             u2v l2; l2.x = lo; l2.y = lo; u2v h2; h2.x = hi; h2.y = hi;
;             *(LAS u2v*)(ATL + 8 * idx) = l2; *(LAS u2v*)(ATL + 1024 + 8 * idx) = h2;
;         }
;         const float asc = ASC[tl]; const int sa = SAL[tl];
;         CFENCE();
;         int accH[4], accL[4];
; #pragma unroll
;         for (int st = 0; st < 16; ++st) {
;             const int p = st >> 2, q = st & 3;
;             if (st < 14) VDMA(st + 2, (st + 2) % 3);
;             if (st < 14) asm volatile("s_waitcnt vmcnt(8)" ::: "memory");
;             else if (st == 14) asm volatile("s_waitcnt vmcnt(4)" ::: "memory");
;             else asm volatile("s_waitcnt vmcnt(0)" ::: "memory");
;             if (q == 0) {
; #pragma unroll
;                 for (int r = 0; r < 4; ++r) { accH[r] = 0; accL[r] = 0; } }
; #pragma unroll
;             for (int tp = 0; tp < 2; ++tp) {
;                 const v2i ao = TR4(ATL + (2 * q + tp) * 128 + 8 * s16), ah = TR4(ATL + 1024 + (2 * q + tp) * 128 + 8 * s16);
; #pragma unroll
	v_dot8c_i32_i4_e32 v38, v130, v52
	v_dot8c_i32_i4_e32 v39, v130, v50
	v_dot8c_i32_i4_e32 v40, v132, v52
	v_dot8c_i32_i4_e32 v41, v132, v50
	v_dot8c_i32_i4_e32 v42, v134, v52
	v_dot8c_i32_i4_e32 v43, v134, v50
	v_dot8c_i32_i4_e32 v44, v136, v52
	v_dot8c_i32_i4_e32 v45, v136, v50
	v_dot8c_i32_i4_e32 v38, v131, v53
	v_dot8c_i32_i4_e32 v39, v131, v51
	v_dot8c_i32_i4_e32 v40, v133, v53
	v_dot8c_i32_i4_e32 v41, v133, v51
	v_dot8c_i32_i4_e32 v42, v135, v53
	v_dot8c_i32_i4_e32 v43, v135, v51
	v_dot8c_i32_i4_e32 v44, v137, v53
	v_dot8c_i32_i4_e32 v45, v137, v51
	v_and_b32_e32 v78, 0xffff, v19
	v_lshrrev_b32_e32 v79, 16, v19
	v_lshl_add_u32 v78, v78, 7, v152
	v_lshl_add_u32 v79, v79, 7, v153
	s_mov_b32 m0, s99
	s_add_i32 s43, s99, 0x400
	global_load_lds_dwordx4 v78, s[50:51]
	s_mov_b32 m0, s43
	s_nop 0
	global_load_lds_dwordx4 v79, s[50:51]
	s_waitcnt vmcnt(8)
	v_add_u32_e32 v54, s77, v59
	v_add_u32_e32 v55, s77, v60
	v_add_u32_e32 v56, s77, v61
	v_add_u32_e32 v57, s77, v62
	ds_read_b64_tr_b4 v[50:51], v160 offset:640
	ds_read_b64_tr_b4 v[52:53], v160 offset:1664
	ds_read_b64_tr_b4 v[130:131], v54
	ds_read_b64_tr_b4 v[132:133], v55
	ds_read_b64_tr_b4 v[134:135], v56
	ds_read_b64_tr_b4 v[136:137], v57
	s_waitcnt lgkmcnt(6)
	v_dot8c_i32_i4_e32 v38, v122, v48
	v_dot8c_i32_i4_e32 v39, v122, v46
	v_dot8c_i32_i4_e32 v40, v124, v48
	v_dot8c_i32_i4_e32 v41, v124, v46
	v_dot8c_i32_i4_e32 v42, v126, v48
	v_dot8c_i32_i4_e32 v43, v126, v46
	v_dot8c_i32_i4_e32 v44, v128, v48
	v_dot8c_i32_i4_e32 v45, v128, v46
	v_dot8c_i32_i4_e32 v38, v123, v49
	v_dot8c_i32_i4_e32 v39, v123, v47
	v_dot8c_i32_i4_e32 v40, v125, v49
	v_dot8c_i32_i4_e32 v41, v125, v47
	v_dot8c_i32_i4_e32 v42, v127, v49
	v_dot8c_i32_i4_e32 v43, v127, v47
	v_dot8c_i32_i4_e32 v44, v129, v49
	v_dot8c_i32_i4_e32 v45, v129, v47
	s_waitcnt lgkmcnt(15)
	v_add_u32_e32 v143, 8, v139
	v_and_b32_e32 v142, 15, v143
	v_xor_b32_e32 v142, 8, v142
	v_bfe_u32 v144, v143, 4, 4
	v_mul_lo_u32 v142, v142, s92
	v_mul_lo_u32 v144, v144, s92
	v_mov_b32_e32 v143, v142
	v_mov_b32_e32 v145, v144
	ds_write2st64_b64 v159, v[142:143], v[144:145] offset1:2
	v_and_b32_e32 v78, 0xffff, v20
	v_lshrrev_b32_e32 v79, 16, v20
	v_lshl_add_u32 v78, v78, 7, v152
	v_lshl_add_u32 v79, v79, 7, v153
	s_mov_b32 m0, s76
	s_add_i32 s43, s76, 0x400
	global_load_lds_dwordx4 v78, s[50:51]
	s_mov_b32 m0, s43
	s_nop 0
	global_load_lds_dwordx4 v79, s[50:51]
	s_waitcnt vmcnt(8)
	v_add_u32_e32 v54, s78, v59
	v_add_u32_e32 v55, s78, v60
	v_add_u32_e32 v56, s78, v61
	v_add_u32_e32 v57, s78, v62
	ds_read_b64_tr_b4 v[46:47], v160 offset:768
	ds_read_b64_tr_b4 v[48:49], v160 offset:1792
	ds_read_b64_tr_b4 v[122:123], v54
	ds_read_b64_tr_b4 v[124:125], v55
	ds_read_b64_tr_b4 v[126:127], v56
	ds_read_b64_tr_b4 v[128:129], v57
	s_waitcnt lgkmcnt(7)
	v_dot8c_i32_i4_e32 v38, v130, v52
	v_dot8c_i32_i4_e32 v39, v130, v50
	v_dot8c_i32_i4_e32 v40, v132, v52
	v_dot8c_i32_i4_e32 v41, v132, v50
	v_dot8c_i32_i4_e32 v42, v134, v52
	v_dot8c_i32_i4_e32 v43, v134, v50
	v_dot8c_i32_i4_e32 v44, v136, v52
	v_dot8c_i32_i4_e32 v45, v136, v50
	v_dot8c_i32_i4_e32 v38, v131, v53
	v_dot8c_i32_i4_e32 v39, v131, v51
	v_dot8c_i32_i4_e32 v40, v133, v53
	v_dot8c_i32_i4_e32 v41, v133, v51
	v_dot8c_i32_i4_e32 v42, v135, v53
	v_dot8c_i32_i4_e32 v43, v135, v51
	v_dot8c_i32_i4_e32 v44, v137, v53
	v_dot8c_i32_i4_e32 v45, v137, v51
	v_and_b32_e32 v78, 0xffff, v21
	v_lshrrev_b32_e32 v79, 16, v21
	v_lshl_add_u32 v78, v78, 7, v152
	v_lshl_add_u32 v79, v79, 7, v153
	s_mov_b32 m0, s77
	s_add_i32 s43, s77, 0x400
	global_load_lds_dwordx4 v78, s[50:51]
	s_mov_b32 m0, s43
	s_nop 0
	global_load_lds_dwordx4 v79, s[50:51]
	s_waitcnt vmcnt(8)
	v_add_u32_e32 v54, s79, v59
	v_add_u32_e32 v55, s79, v60
	v_add_u32_e32 v56, s79, v61
	v_add_u32_e32 v57, s79, v62
	ds_read_b64_tr_b4 v[50:51], v160 offset:896
	ds_read_b64_tr_b4 v[52:53], v160 offset:1920
	ds_read_b64_tr_b4 v[130:131], v54
	ds_read_b64_tr_b4 v[132:133], v55
	ds_read_b64_tr_b4 v[134:135], v56
	ds_read_b64_tr_b4 v[136:137], v57
	s_waitcnt lgkmcnt(6)
	v_dot8c_i32_i4_e32 v38, v122, v48
	v_dot8c_i32_i4_e32 v39, v122, v46
	v_dot8c_i32_i4_e32 v40, v124, v48
	v_dot8c_i32_i4_e32 v41, v124, v46
	v_dot8c_i32_i4_e32 v42, v126, v48
	v_dot8c_i32_i4_e32 v43, v126, v46
	v_dot8c_i32_i4_e32 v44, v128, v48
	v_dot8c_i32_i4_e32 v45, v128, v46
	v_dot8c_i32_i4_e32 v38, v123, v49
	v_dot8c_i32_i4_e32 v39, v123, v47
	v_dot8c_i32_i4_e32 v40, v125, v49
	v_dot8c_i32_i4_e32 v41, v125, v47
	v_dot8c_i32_i4_e32 v42, v127, v49
	v_dot8c_i32_i4_e32 v43, v127, v47
	v_dot8c_i32_i4_e32 v44, v129, v49
	v_dot8c_i32_i4_e32 v45, v129, v47
	v_and_b32_e32 v78, 0xffff, v22
	v_lshrrev_b32_e32 v79, 16, v22
	v_lshl_add_u32 v78, v78, 7, v152
	v_lshl_add_u32 v79, v79, 7, v153
	s_mov_b32 m0, s78
	s_add_i32 s43, s78, 0x400
	global_load_lds_dwordx4 v78, s[50:51]
	s_mov_b32 m0, s43
	s_nop 0
	global_load_lds_dwordx4 v79, s[50:51]
	s_waitcnt vmcnt(8)
	v_add_u32_e32 v54, s98, v59
	v_add_u32_e32 v55, s98, v60
	v_add_u32_e32 v56, s98, v61
	v_add_u32_e32 v57, s98, v62
	ds_read_b64_tr_b4 v[46:47], v160
	ds_read_b64_tr_b4 v[48:49], v160 offset:1024
	ds_read_b64_tr_b4 v[122:123], v54
	ds_read_b64_tr_b4 v[124:125], v55
	ds_read_b64_tr_b4 v[126:127], v56
	ds_read_b64_tr_b4 v[128:129], v57
	s_waitcnt lgkmcnt(6)
	v_dot8c_i32_i4_e32 v38, v130, v52
	v_dot8c_i32_i4_e32 v39, v130, v50
	v_dot8c_i32_i4_e32 v40, v132, v52
	v_dot8c_i32_i4_e32 v41, v132, v50
	v_dot8c_i32_i4_e32 v42, v134, v52
	v_dot8c_i32_i4_e32 v43, v134, v50
	v_dot8c_i32_i4_e32 v44, v136, v52
	v_dot8c_i32_i4_e32 v45, v136, v50
	v_dot8c_i32_i4_e32 v38, v131, v53
	v_dot8c_i32_i4_e32 v39, v131, v51
	v_dot8c_i32_i4_e32 v40, v133, v53
	v_dot8c_i32_i4_e32 v41, v133, v51
	v_dot8c_i32_i4_e32 v42, v135, v53
	v_dot8c_i32_i4_e32 v43, v135, v51
	v_dot8c_i32_i4_e32 v44, v137, v53
	v_dot8c_i32_i4_e32 v45, v137, v51
	s_nop 3
	s_waitcnt lgkmcnt(15)
; __device__ __forceinline__ void peer_v_tokens(int j, const LAS unsigned short* EL, const LAS unsigned char* AL  , const LAS float* ASC  , const LAS int* SAL  , ...
;     ...
;         for (int st = 0; st < 16; ++st) {
;             const int p = st >> 2, q = st & 3;
;             if (st < 14) VDMA(st + 2, (st + 2) % 3);
;             if (st < 14) asm volatile("s_waitcnt vmcnt(8)" ::: "memory");
;             else if (st == 14) asm volatile("s_waitcnt vmcnt(4)" ::: "memory");
;             else asm volatile("s_waitcnt vmcnt(0)" ::: "memory");
;             if (q == 0) {
; #pragma unroll
;                 for (int r = 0; r < 4; ++r) { accH[r] = 0; accL[r] = 0; } }
; #pragma unroll
;             for (int tp = 0; tp < 2; ++tp) {
;                 const v2i ao = TR4(ATL + (2 * q + tp) * 128 + 8 * s16), ah = TR4(ATL + 1024 + (2 * q + tp) * 128 + 8 * s16);
; #pragma unroll
;                 for (int r = 0; r < 4; ++r) {
;                     const v2i d = TR4(ldsb + BUF[st % 3] + 2048 * tp + roff[r]);
;                     accH[r] = __builtin_amdgcn_sdot8(d.x, ah.x, accH[r], false); accH[r] = __builtin_amdgcn_sdot8(d.y, ah.y, accH[r], false);
;                     accL[r] = __builtin_amdgcn_sdot8(d.x, ao.x, accL[r], false); accL[r] = __builtin_amdgcn_sdot8(d.y, ao.y, accL[r], false);
;                 }
;             }
;             asm volatile("s_waitcnt lgkmcnt(0)" ::: "memory");
;             if (q == 3) {
; #pragma unroll
;                 for (int r = 0; r < 4; ++r) STASH[256 * p + 16 * (grp + 4 * r) + pc] = f2bf(asc * (float)(2 * ((accH[r] << 4) + accL[r]) + sa));
;             }
;         }
;         CFENCE();
;         {
;             float4 v[4]; float ss = 0.f;
; #pragma unroll
;             for (int jq = 0; jq < 4; ++jq) { typedef unsigned u2v __attribute__((ext_vector_type(2))); const u2v pw = *(const LAS u2v*)(STASH + 4 * lane + 256 * jq); const uint2 hw = hv[jq];
;                 v[jq] = make_float4(__uint_as_float(hw.x << 16) + __uint_as_float(pw.x << 16), __uint_as_float(hw.x & 0xffff0000u) + __uint_as_float(pw.x & 0xffff0000u),
;                                     __uint_as_float(hw.y << 16) + __uint_as_float(pw.y << 16), __uint_as_float(hw.y & 0xffff0000u) + __uint_as_float(pw.y & 0xffff0000u));
;                 ss += v[jq].x * v[jq].x + v[jq].y * v[jq].y + v[jq].z * v[jq].z + v[jq].w * v[jq].w; }
;             ss = wave_sum(ss);
	v_lshlrev_b32_e32 v38, 5, v38
	v_lshlrev_b32_e32 v39, 1, v39
	v_add3_u32 v38, v39, v229, v38
	v_cvt_f32_i32_e32 v38, v38
	v_mul_f32_e32 v38, v228, v38
	v_lshlrev_b32_e32 v40, 5, v40
	v_lshlrev_b32_e32 v41, 1, v41
	v_add3_u32 v40, v41, v229, v40
	v_cvt_f32_i32_e32 v40, v40
	v_mul_f32_e32 v40, v228, v40
	v_lshlrev_b32_e32 v42, 5, v42
	v_lshlrev_b32_e32 v43, 1, v43
	v_add3_u32 v42, v43, v229, v42
	v_cvt_f32_i32_e32 v42, v42
	v_mul_f32_e32 v42, v228, v42
	v_lshlrev_b32_e32 v44, 5, v44
	v_lshlrev_b32_e32 v45, 1, v45
	v_add3_u32 v44, v45, v229, v44
	v_cvt_f32_i32_e32 v44, v44
	v_mul_f32_e32 v44, v228, v44
	v_cvt_pk_bf16_f32 v186, v38, v40
	v_cvt_pk_bf16_f32 v187, v42, v44
	ds_read_b128 v[252:255], v155
	s_add_i32 s44, s40, 32
	s_ashr_i32 s45, s44, 31
	s_lshl_b64 s[44:45], s[44:45], 12
	v_lshl_add_u64 v[80:81], v[36:37], 0, s[44:45]
	s_waitcnt lgkmcnt(0)
	v_mul_f32_e32 v210, v210, v252
	v_mul_f32_e32 v211, v211, v253
	v_mul_f32_e32 v212, v212, v254
	v_mul_f32_e32 v213, v213, v255
	global_store_dwordx4 v[80:81], v[210:213], off sc1
	s_add_i32 s43, s40, 40
	s_lshl_b32 s43, s43, 11
	v_add_u32_e32 v138, s43, v66
	global_load_dwordx2 v[194:195], v138, s[70:71]
	global_load_dwordx2 v[196:197], v138, s[70:71] offset:512
	global_load_dwordx2 v[198:199], v138, s[70:71] offset:1024
	global_load_dwordx2 v[200:201], v138, s[70:71] offset:1536
	v_add_u32_e32 v147, 8, v140
	v_and_b32_e32 v146, 15, v147
	v_xor_b32_e32 v146, 8, v146
	v_bfe_u32 v148, v147, 4, 4
	v_mul_lo_u32 v146, v146, s92
	v_mul_lo_u32 v148, v148, s92
	v_mov_b32_e32 v147, v146
	v_mov_b32_e32 v149, v148
	ds_write2st64_b64 v77, v[146:147], v[148:149] offset1:2
	v_add_u32_e32 v138, 0x1c00, v74
	ds_read_u8 v139, v138
	v_add_u32_e32 v141, 0x1c00, v73
	ds_read_u8 v140, v141
	s_add_i32 s43, s67, 192
	v_mov_b32_e32 v138, s43
	ds_read2st64_b32 v[228:229], v138 offset1:1
	ds_read_b128 v[26:29], v227 offset:14336
	ds_read_b128 v[30:33], v227 offset:14352
	v_mov_b32_e32 v38, 0
	v_mov_b32_e32 v39, 0
	v_mov_b32_e32 v40, 0
	v_mov_b32_e32 v41, 0
	v_mov_b32_e32 v42, 0
	v_mov_b32_e32 v43, 0
	v_mov_b32_e32 v44, 0
	v_mov_b32_e32 v45, 0
	v_and_b32_e32 v78, 0xffff, v23
	v_lshrrev_b32_e32 v79, 16, v23
	v_lshl_add_u32 v78, v78, 7, v152
	v_lshl_add_u32 v79, v79, 7, v153
	s_mov_b32 m0, s79
	s_add_i32 s43, s79, 0x400
	global_load_lds_dwordx4 v78, s[50:51]
	s_mov_b32 m0, s43
	s_nop 0
	global_load_lds_dwordx4 v79, s[50:51]
	s_waitcnt vmcnt(13)
	v_add_u32_e32 v54, s99, v59
	v_add_u32_e32 v55, s99, v60
	v_add_u32_e32 v56, s99, v61
	v_add_u32_e32 v57, s99, v62
	ds_read_b64_tr_b4 v[50:51], v160 offset:128
	ds_read_b64_tr_b4 v[52:53], v160 offset:1152
	ds_read_b64_tr_b4 v[130:131], v54
	ds_read_b64_tr_b4 v[132:133], v55
	ds_read_b64_tr_b4 v[134:135], v56
	ds_read_b64_tr_b4 v[136:137], v57
	s_waitcnt lgkmcnt(13)
	v_dot8c_i32_i4_e32 v38, v122, v48
	v_dot8c_i32_i4_e32 v39, v122, v46
	v_dot8c_i32_i4_e32 v40, v124, v48
	v_dot8c_i32_i4_e32 v41, v124, v46
	v_dot8c_i32_i4_e32 v42, v126, v48
	v_dot8c_i32_i4_e32 v43, v126, v46
	v_dot8c_i32_i4_e32 v44, v128, v48
	v_dot8c_i32_i4_e32 v45, v128, v46
	v_dot8c_i32_i4_e32 v38, v123, v49
	v_dot8c_i32_i4_e32 v39, v123, v47
	v_dot8c_i32_i4_e32 v40, v125, v49
	v_dot8c_i32_i4_e32 v41, v125, v47
	v_dot8c_i32_i4_e32 v42, v127, v49
	v_dot8c_i32_i4_e32 v43, v127, v47
	v_dot8c_i32_i4_e32 v44, v129, v49
	v_dot8c_i32_i4_e32 v45, v129, v47
	v_and_b32_e32 v78, 0xffff, v24
	v_lshrrev_b32_e32 v79, 16, v24
	v_lshl_add_u32 v78, v78, 7, v152
	v_lshl_add_u32 v79, v79, 7, v153
	s_mov_b32 m0, s98
	s_add_i32 s43, s98, 0x400
	global_load_lds_dwordx4 v78, s[50:51]
	s_mov_b32 m0, s43
	s_nop 0
	global_load_lds_dwordx4 v79, s[50:51]
	s_waitcnt vmcnt(13)
	v_add_u32_e32 v54, s76, v59
	v_add_u32_e32 v55, s76, v60
	v_add_u32_e32 v56, s76, v61
	v_add_u32_e32 v57, s76, v62
	ds_read_b64_tr_b4 v[46:47], v160 offset:256
	ds_read_b64_tr_b4 v[48:49], v160 offset:1280
	ds_read_b64_tr_b4 v[122:123], v54
	ds_read_b64_tr_b4 v[124:125], v55
	ds_read_b64_tr_b4 v[126:127], v56
	ds_read_b64_tr_b4 v[128:129], v57
	s_waitcnt lgkmcnt(6)
	v_dot8c_i32_i4_e32 v38, v130, v52
	v_dot8c_i32_i4_e32 v39, v130, v50
	v_dot8c_i32_i4_e32 v40, v132, v52
	v_dot8c_i32_i4_e32 v41, v132, v50
	v_dot8c_i32_i4_e32 v42, v134, v52
	v_dot8c_i32_i4_e32 v43, v134, v50
	v_dot8c_i32_i4_e32 v44, v136, v52
	v_dot8c_i32_i4_e32 v45, v136, v50
	v_dot8c_i32_i4_e32 v38, v131, v53
	v_dot8c_i32_i4_e32 v39, v131, v51
	v_dot8c_i32_i4_e32 v40, v133, v53
	v_dot8c_i32_i4_e32 v41, v133, v51
	v_dot8c_i32_i4_e32 v42, v135, v53
	v_dot8c_i32_i4_e32 v43, v135, v51
	v_dot8c_i32_i4_e32 v44, v137, v53
	v_dot8c_i32_i4_e32 v45, v137, v51
	v_and_b32_e32 v78, 0xffff, v25
	v_lshrrev_b32_e32 v79, 16, v25
	v_lshl_add_u32 v78, v78, 7, v152
	v_lshl_add_u32 v79, v79, 7, v153
	s_mov_b32 m0, s99
	s_add_i32 s43, s99, 0x400
	global_load_lds_dwordx4 v78, s[50:51]
	s_mov_b32 m0, s43
	s_nop 0
	global_load_lds_dwordx4 v79, s[50:51]
	s_waitcnt vmcnt(13)
	v_add_u32_e32 v54, s77, v59
	v_add_u32_e32 v55, s77, v60
	v_add_u32_e32 v56, s77, v61
	v_add_u32_e32 v57, s77, v62
	ds_read_b64_tr_b4 v[50:51], v160 offset:384
	ds_read_b64_tr_b4 v[52:53], v160 offset:1408
	ds_read_b64_tr_b4 v[130:131], v54
	ds_read_b64_tr_b4 v[132:133], v55
	ds_read_b64_tr_b4 v[134:135], v56
	ds_read_b64_tr_b4 v[136:137], v57
	s_waitcnt lgkmcnt(6)
	v_dot8c_i32_i4_e32 v38, v122, v48
	v_dot8c_i32_i4_e32 v39, v122, v46
	v_dot8c_i32_i4_e32 v40, v124, v48
	v_dot8c_i32_i4_e32 v41, v124, v46
	v_dot8c_i32_i4_e32 v42, v126, v48
	v_dot8c_i32_i4_e32 v43, v126, v46
	v_dot8c_i32_i4_e32 v44, v128, v48
	v_dot8c_i32_i4_e32 v45, v128, v46
	v_dot8c_i32_i4_e32 v38, v123, v49
	v_dot8c_i32_i4_e32 v39, v123, v47
	v_dot8c_i32_i4_e32 v40, v125, v49
	v_dot8c_i32_i4_e32 v41, v125, v47
	v_dot8c_i32_i4_e32 v42, v127, v49
	v_dot8c_i32_i4_e32 v43, v127, v47
	v_dot8c_i32_i4_e32 v44, v129, v49
	v_dot8c_i32_i4_e32 v45, v129, v47
	s_waitcnt lgkmcnt(15)
; __device__ __forceinline__ void peer_v_tokens(int j, const LAS unsigned short* EL, const LAS unsigned char* AL  , const LAS float* ASC  , const LAS int* SAL  , ...
;     ...
; #pragma unroll 1
;     for (int it = 0; it < 8; ++it) {
;         const int tl = it * 8 + wave, t = j * 64 + tl;
;         unsigned E[8];
;         { const LAS v4u* ep = (const LAS v4u*)(EL + tl * 128 + 16 * g); const v4u e0 = ep[0], e1 = ep[1];
;           E[0] = e0.x; E[1] = e0.y; E[2] = e0.z; E[3] = e0.w; E[4] = e1.x; E[5] = e1.y; E[6] = e1.z; E[7] = e1.w; }
;         uint2 hv[4]; float4 gv[4];
;         { unsigned ho = (unsigned)t * (D / 4) + (unsigned)lane; asm volatile("" : "+v"(ho)); const uint2* hp = (const uint2*)HB + ho; const float4* gp = (const float4*)fng + lane;
; #pragma unroll
;           for (int jq = 0; jq < 4; ++jq) { hv[jq] = hp[64 * jq]; gv[jq] = gp[64 * jq]; } }
;         VDMA(0, 0); VDMA(1, 1);
; #pragma unroll
;         for (int m = 0; m < 2; ++m) {
;             const int idx = lane + 64 * m, tau = idx >> 4, sr = idx & 15, k = 16 * (sr & 7) + 2 * tau + (sr >> 3);
;             const int aq = (int)*(const LAS signed char*)(AL + tl * 128 + k); const int tq = aq + 8;
;             const unsigned lo = (((unsigned)tq & 15u) ^ 8u) * 0x11111111u, hi = ((unsigned)(tq >> 4) & 15u) * 0x11111111u;
;             typedef unsigned u2v __attribute__((ext_vector_type(2)));
;             u2v l2; l2.x = lo; l2.y = lo; u2v h2; h2.x = hi; h2.y = hi;
;             *(LAS u2v*)(ATL + 8 * idx) = l2; *(LAS u2v*)(ATL + 1024 + 8 * idx) = h2;
;         }
;         const float asc = ASC[tl]; const int sa = SAL[tl];
;         CFENCE();
;         int accH[4], accL[4];
; #pragma unroll
;         for (int st = 0; st < 16; ++st) {
;             const int p = st >> 2, q = st & 3;
;             if (st < 14) VDMA(st + 2, (st + 2) % 3);
;             if (st < 14) asm volatile("s_waitcnt vmcnt(8)" ::: "memory");
;             else if (st == 14) asm volatile("s_waitcnt vmcnt(4)" ::: "memory");
;             else asm volatile("s_waitcnt vmcnt(0)" ::: "memory");
;             if (q == 0) {
; #pragma unroll
;                 for (int r = 0; r < 4; ++r) { accH[r] = 0; accL[r] = 0; } }
; #pragma unroll
;             for (int tp = 0; tp < 2; ++tp) {
;                 const v2i ao = TR4(ATL + (2 * q + tp) * 128 + 8 * s16), ah = TR4(ATL + 1024 + (2 * q + tp) * 128 + 8 * s16);
; #pragma unroll
	v_and_b32_e32 v78, 0xffff, v26
	v_lshrrev_b32_e32 v79, 16, v26
	v_lshl_add_u32 v78, v78, 7, v152
	v_lshl_add_u32 v79, v79, 7, v153
	s_mov_b32 m0, s76
	s_add_i32 s43, s76, 0x400
	global_load_lds_dwordx4 v78, s[50:51]
	s_mov_b32 m0, s43
	s_nop 0
	global_load_lds_dwordx4 v79, s[50:51]
	s_waitcnt vmcnt(13)
	v_add_u32_e32 v54, s78, v59
	v_add_u32_e32 v55, s78, v60
	v_add_u32_e32 v56, s78, v61
	v_add_u32_e32 v57, s78, v62
	ds_read_b64_tr_b4 v[46:47], v160 offset:512
	ds_read_b64_tr_b4 v[48:49], v160 offset:1536
	ds_read_b64_tr_b4 v[122:123], v54
	ds_read_b64_tr_b4 v[124:125], v55
	ds_read_b64_tr_b4 v[126:127], v56
	ds_read_b64_tr_b4 v[128:129], v57
	s_waitcnt lgkmcnt(6)
	v_dot8c_i32_i4_e32 v38, v130, v52
	v_dot8c_i32_i4_e32 v39, v130, v50
	v_dot8c_i32_i4_e32 v40, v132, v52
	v_dot8c_i32_i4_e32 v41, v132, v50
	v_dot8c_i32_i4_e32 v42, v134, v52
	v_dot8c_i32_i4_e32 v43, v134, v50
	v_dot8c_i32_i4_e32 v44, v136, v52
	v_dot8c_i32_i4_e32 v45, v136, v50
	v_dot8c_i32_i4_e32 v38, v131, v53
	v_dot8c_i32_i4_e32 v39, v131, v51
	v_dot8c_i32_i4_e32 v40, v133, v53
	v_dot8c_i32_i4_e32 v41, v133, v51
	v_dot8c_i32_i4_e32 v42, v135, v53
	v_dot8c_i32_i4_e32 v43, v135, v51
	v_dot8c_i32_i4_e32 v44, v137, v53
	v_dot8c_i32_i4_e32 v45, v137, v51
	v_and_b32_e32 v78, 0xffff, v27
	v_lshrrev_b32_e32 v79, 16, v27
	v_lshl_add_u32 v78, v78, 7, v152
	v_lshl_add_u32 v79, v79, 7, v153
	s_mov_b32 m0, s77
	s_add_i32 s43, s77, 0x400
	global_load_lds_dwordx4 v78, s[50:51]
	s_mov_b32 m0, s43
	s_nop 0
	global_load_lds_dwordx4 v79, s[50:51]
	s_waitcnt vmcnt(8)
	v_add_u32_e32 v54, s79, v59
	v_add_u32_e32 v55, s79, v60
	v_add_u32_e32 v56, s79, v61
	v_add_u32_e32 v57, s79, v62
	ds_read_b64_tr_b4 v[50:51], v160 offset:640
	ds_read_b64_tr_b4 v[52:53], v160 offset:1664
	ds_read_b64_tr_b4 v[130:131], v54
	ds_read_b64_tr_b4 v[132:133], v55
	ds_read_b64_tr_b4 v[134:135], v56
	ds_read_b64_tr_b4 v[136:137], v57
	s_waitcnt lgkmcnt(6)
	v_dot8c_i32_i4_e32 v38, v122, v48
	v_dot8c_i32_i4_e32 v39, v122, v46
	v_dot8c_i32_i4_e32 v40, v124, v48
	v_dot8c_i32_i4_e32 v41, v124, v46
	v_dot8c_i32_i4_e32 v42, v126, v48
	v_dot8c_i32_i4_e32 v43, v126, v46
	v_dot8c_i32_i4_e32 v44, v128, v48
	v_dot8c_i32_i4_e32 v45, v128, v46
	v_dot8c_i32_i4_e32 v38, v123, v49
	v_dot8c_i32_i4_e32 v39, v123, v47
	v_dot8c_i32_i4_e32 v40, v125, v49
	v_dot8c_i32_i4_e32 v41, v125, v47
	v_dot8c_i32_i4_e32 v42, v127, v49
	v_dot8c_i32_i4_e32 v43, v127, v47
	v_dot8c_i32_i4_e32 v44, v129, v49
	v_dot8c_i32_i4_e32 v45, v129, v47
	s_waitcnt lgkmcnt(15)
	v_add_u32_e32 v143, 8, v139
	v_and_b32_e32 v142, 15, v143
	v_xor_b32_e32 v142, 8, v142
	v_bfe_u32 v144, v143, 4, 4
	v_mul_lo_u32 v142, v142, s92
	v_mul_lo_u32 v144, v144, s92
	v_mov_b32_e32 v143, v142
	v_mov_b32_e32 v145, v144
	ds_write2st64_b64 v159, v[142:143], v[144:145] offset1:2
	v_and_b32_e32 v78, 0xffff, v28
	v_lshrrev_b32_e32 v79, 16, v28
	v_lshl_add_u32 v78, v78, 7, v152
	v_lshl_add_u32 v79, v79, 7, v153
	s_mov_b32 m0, s78
	s_add_i32 s43, s78, 0x400
	global_load_lds_dwordx4 v78, s[50:51]
	s_mov_b32 m0, s43
	s_nop 0
	global_load_lds_dwordx4 v79, s[50:51]
	s_waitcnt vmcnt(8)
	v_add_u32_e32 v54, s98, v59
	v_add_u32_e32 v55, s98, v60
	v_add_u32_e32 v56, s98, v61
	v_add_u32_e32 v57, s98, v62
	ds_read_b64_tr_b4 v[46:47], v160 offset:768
	ds_read_b64_tr_b4 v[48:49], v160 offset:1792
	ds_read_b64_tr_b4 v[122:123], v54
	ds_read_b64_tr_b4 v[124:125], v55
	ds_read_b64_tr_b4 v[126:127], v56
	ds_read_b64_tr_b4 v[128:129], v57
	s_waitcnt lgkmcnt(7)
	v_dot8c_i32_i4_e32 v38, v130, v52
	v_dot8c_i32_i4_e32 v39, v130, v50
	v_dot8c_i32_i4_e32 v40, v132, v52
	v_dot8c_i32_i4_e32 v41, v132, v50
	v_dot8c_i32_i4_e32 v42, v134, v52
	v_dot8c_i32_i4_e32 v43, v134, v50
	v_dot8c_i32_i4_e32 v44, v136, v52
	v_dot8c_i32_i4_e32 v45, v136, v50
	v_dot8c_i32_i4_e32 v38, v131, v53
	v_dot8c_i32_i4_e32 v39, v131, v51
	v_dot8c_i32_i4_e32 v40, v133, v53
	v_dot8c_i32_i4_e32 v41, v133, v51
	v_dot8c_i32_i4_e32 v42, v135, v53
	v_dot8c_i32_i4_e32 v43, v135, v51
	v_dot8c_i32_i4_e32 v44, v137, v53
	v_dot8c_i32_i4_e32 v45, v137, v51
	v_and_b32_e32 v78, 0xffff, v29
	v_lshrrev_b32_e32 v79, 16, v29
	v_lshl_add_u32 v78, v78, 7, v152
	v_lshl_add_u32 v79, v79, 7, v153
	s_mov_b32 m0, s79
	s_add_i32 s43, s79, 0x400
	global_load_lds_dwordx4 v78, s[50:51]
	s_mov_b32 m0, s43
	s_nop 0
	global_load_lds_dwordx4 v79, s[50:51]
	s_waitcnt vmcnt(8)
	v_add_u32_e32 v54, s99, v59
	v_add_u32_e32 v55, s99, v60
	v_add_u32_e32 v56, s99, v61
	v_add_u32_e32 v57, s99, v62
	ds_read_b64_tr_b4 v[50:51], v160 offset:896
	ds_read_b64_tr_b4 v[52:53], v160 offset:1920
	ds_read_b64_tr_b4 v[130:131], v54
	ds_read_b64_tr_b4 v[132:133], v55
	ds_read_b64_tr_b4 v[134:135], v56
	ds_read_b64_tr_b4 v[136:137], v57
	s_waitcnt lgkmcnt(6)
	v_dot8c_i32_i4_e32 v38, v122, v48
	v_dot8c_i32_i4_e32 v39, v122, v46
	v_dot8c_i32_i4_e32 v40, v124, v48
	v_dot8c_i32_i4_e32 v41, v124, v46
	v_dot8c_i32_i4_e32 v42, v126, v48
	v_dot8c_i32_i4_e32 v43, v126, v46
	v_dot8c_i32_i4_e32 v44, v128, v48
	v_dot8c_i32_i4_e32 v45, v128, v46
	v_dot8c_i32_i4_e32 v38, v123, v49
	v_dot8c_i32_i4_e32 v39, v123, v47
	v_dot8c_i32_i4_e32 v40, v125, v49
	v_dot8c_i32_i4_e32 v41, v125, v47
	v_dot8c_i32_i4_e32 v42, v127, v49
	v_dot8c_i32_i4_e32 v43, v127, v47
	v_dot8c_i32_i4_e32 v44, v129, v49
	v_dot8c_i32_i4_e32 v45, v129, v47
	v_and_b32_e32 v78, 0xffff, v30
	v_lshrrev_b32_e32 v79, 16, v30
	v_lshl_add_u32 v78, v78, 7, v152
	v_lshl_add_u32 v79, v79, 7, v153
	s_mov_b32 m0, s98
	s_add_i32 s43, s98, 0x400
	global_load_lds_dwordx4 v78, s[50:51]
	s_mov_b32 m0, s43
	s_nop 0
	global_load_lds_dwordx4 v79, s[50:51]
	s_waitcnt vmcnt(8)
; __device__ __forceinline__ void peer_v_tokens(int j, const LAS unsigned short* EL, const LAS unsigned char* AL  , const LAS float* ASC  , const LAS int* SAL  , ...
;     ...
;         for (int st = 0; st < 16; ++st) {
;             const int p = st >> 2, q = st & 3;
;             if (st < 14) VDMA(st + 2, (st + 2) % 3);
;             if (st < 14) asm volatile("s_waitcnt vmcnt(8)" ::: "memory");
;             else if (st == 14) asm volatile("s_waitcnt vmcnt(4)" ::: "memory");
;             else asm volatile("s_waitcnt vmcnt(0)" ::: "memory");
;             if (q == 0) {
; #pragma unroll
;                 for (int r = 0; r < 4; ++r) { accH[r] = 0; accL[r] = 0; } }
; #pragma unroll
;             for (int tp = 0; tp < 2; ++tp) {
;                 const v2i ao = TR4(ATL + (2 * q + tp) * 128 + 8 * s16), ah = TR4(ATL + 1024 + (2 * q + tp) * 128 + 8 * s16);
; #pragma unroll
;                 for (int r = 0; r < 4; ++r) {
;                     const v2i d = TR4(ldsb + BUF[st % 3] + 2048 * tp + roff[r]);
;                     accH[r] = __builtin_amdgcn_sdot8(d.x, ah.x, accH[r], false); accH[r] = __builtin_amdgcn_sdot8(d.y, ah.y, accH[r], false);
;                     accL[r] = __builtin_amdgcn_sdot8(d.x, ao.x, accL[r], false); accL[r] = __builtin_amdgcn_sdot8(d.y, ao.y, accL[r], false);
;                 }
;             }
;             asm volatile("s_waitcnt lgkmcnt(0)" ::: "memory");
;             if (q == 3) {
; #pragma unroll
;                 for (int r = 0; r < 4; ++r) STASH[256 * p + 16 * (grp + 4 * r) + pc] = f2bf(asc * (float)(2 * ((accH[r] << 4) + accL[r]) + sa));
;             }
;         }
;         CFENCE();
;         {
;             float4 v[4]; float ss = 0.f;
; #pragma unroll
;             for (int jq = 0; jq < 4; ++jq) { typedef unsigned u2v __attribute__((ext_vector_type(2))); const u2v pw = *(const LAS u2v*)(STASH + 4 * lane + 256 * jq); const uint2 hw = hv[jq];
;                 v[jq] = make_float4(__uint_as_float(hw.x << 16) + __uint_as_float(pw.x << 16), __uint_as_float(hw.x & 0xffff0000u) + __uint_as_float(pw.x & 0xffff0000u),
;                                     __uint_as_float(hw.y << 16) + __uint_as_float(pw.y << 16), __uint_as_float(hw.y & 0xffff0000u) + __uint_as_float(pw.y & 0xffff0000u));
;                 ss += v[jq].x * v[jq].x + v[jq].y * v[jq].y + v[jq].z * v[jq].z + v[jq].w * v[jq].w; }
;             ss = wave_sum(ss);
	v_add_u32_e32 v54, s76, v59
	v_add_u32_e32 v55, s76, v60
	v_add_u32_e32 v56, s76, v61
	v_add_u32_e32 v57, s76, v62
	ds_read_b64_tr_b4 v[46:47], v160
	ds_read_b64_tr_b4 v[48:49], v160 offset:1024
	ds_read_b64_tr_b4 v[122:123], v54
	ds_read_b64_tr_b4 v[124:125], v55
	ds_read_b64_tr_b4 v[126:127], v56
	ds_read_b64_tr_b4 v[128:129], v57
	s_waitcnt lgkmcnt(6)
	v_dot8c_i32_i4_e32 v38, v130, v52
	v_dot8c_i32_i4_e32 v39, v130, v50
	v_dot8c_i32_i4_e32 v40, v132, v52
	v_dot8c_i32_i4_e32 v41, v132, v50
	v_dot8c_i32_i4_e32 v42, v134, v52
	v_dot8c_i32_i4_e32 v43, v134, v50
	v_dot8c_i32_i4_e32 v44, v136, v52
	v_dot8c_i32_i4_e32 v45, v136, v50
	v_dot8c_i32_i4_e32 v38, v131, v53
	v_dot8c_i32_i4_e32 v39, v131, v51
	v_dot8c_i32_i4_e32 v40, v133, v53
	v_dot8c_i32_i4_e32 v41, v133, v51
	v_dot8c_i32_i4_e32 v42, v135, v53
	v_dot8c_i32_i4_e32 v43, v135, v51
	v_dot8c_i32_i4_e32 v44, v137, v53
	v_dot8c_i32_i4_e32 v45, v137, v51
	s_nop 3
	s_waitcnt lgkmcnt(15)
	v_lshlrev_b32_e32 v38, 5, v38
	v_lshlrev_b32_e32 v39, 1, v39
	v_add3_u32 v38, v39, v229, v38
	v_cvt_f32_i32_e32 v38, v38
	v_mul_f32_e32 v38, v228, v38
	v_lshlrev_b32_e32 v40, 5, v40
	v_lshlrev_b32_e32 v41, 1, v41
	v_add3_u32 v40, v41, v229, v40
	v_cvt_f32_i32_e32 v40, v40
	v_mul_f32_e32 v40, v228, v40
	v_lshlrev_b32_e32 v42, 5, v42
	v_lshlrev_b32_e32 v43, 1, v43
	v_add3_u32 v42, v43, v229, v42
	v_cvt_f32_i32_e32 v42, v42
	v_mul_f32_e32 v42, v228, v42
	v_lshlrev_b32_e32 v44, 5, v44
	v_lshlrev_b32_e32 v45, 1, v45
	v_add3_u32 v44, v45, v229, v44
	v_cvt_f32_i32_e32 v44, v44
	v_mul_f32_e32 v44, v228, v44
	v_cvt_pk_bf16_f32 v180, v38, v40
	v_cvt_pk_bf16_f32 v181, v42, v44
	ds_read_b128 v[252:255], v155 offset:1024
	s_add_i32 s44, s40, 32
	s_ashr_i32 s45, s44, 31
	s_lshl_b64 s[44:45], s[44:45], 12
	v_lshl_add_u64 v[80:81], v[36:37], 0, s[44:45]
	s_waitcnt lgkmcnt(0)
	v_mul_f32_e32 v214, v214, v252
	v_mul_f32_e32 v215, v215, v253
	v_mul_f32_e32 v216, v216, v254
	v_mul_f32_e32 v217, v217, v255
	global_store_dwordx4 v[80:81], v[214:217], off offset:1024 sc1
	v_add_u32_e32 v147, 8, v140
	v_and_b32_e32 v146, 15, v147
	v_xor_b32_e32 v146, 8, v146
	v_bfe_u32 v148, v147, 4, 4
	v_mul_lo_u32 v146, v146, s92
	v_mul_lo_u32 v148, v148, s92
	v_mov_b32_e32 v147, v146
	v_mov_b32_e32 v149, v148
	ds_write2st64_b64 v77, v[146:147], v[148:149] offset1:2
	v_add_u32_e32 v138, 0x1800, v74
	ds_read_u8 v139, v138
	v_add_u32_e32 v141, 0x1800, v73
	ds_read_u8 v140, v141
	s_add_i32 s43, s67, 224
	v_mov_b32_e32 v138, s43
	ds_read2st64_b32 v[228:229], v138 offset1:1
	ds_read_b128 v[18:21], v227 offset:12288
	ds_read_b128 v[22:25], v227 offset:12304
	v_add_u32_e32 v150, 0x400000, v63
	v_add_u32_e32 v151, 0x400000, v64
	v_mov_b32_e32 v38, 0
	v_mov_b32_e32 v39, 0
	v_mov_b32_e32 v40, 0
	v_mov_b32_e32 v41, 0
	v_mov_b32_e32 v42, 0
	v_mov_b32_e32 v43, 0
	v_mov_b32_e32 v44, 0
	v_mov_b32_e32 v45, 0
	v_and_b32_e32 v78, 0xffff, v31
	v_lshrrev_b32_e32 v79, 16, v31
	v_lshl_add_u32 v78, v78, 7, v152
	v_lshl_add_u32 v79, v79, 7, v153
	s_mov_b32 m0, s99
	s_add_i32 s43, s99, 0x400
	global_load_lds_dwordx4 v78, s[50:51]
	s_mov_b32 m0, s43
	s_nop 0
	global_load_lds_dwordx4 v79, s[50:51]
	s_waitcnt vmcnt(9)
	v_add_u32_e32 v54, s77, v59
	v_add_u32_e32 v55, s77, v60
	v_add_u32_e32 v56, s77, v61
	v_add_u32_e32 v57, s77, v62
	ds_read_b64_tr_b4 v[50:51], v160 offset:128
	ds_read_b64_tr_b4 v[52:53], v160 offset:1152
	ds_read_b64_tr_b4 v[130:131], v54
	ds_read_b64_tr_b4 v[132:133], v55
	ds_read_b64_tr_b4 v[134:135], v56
	ds_read_b64_tr_b4 v[136:137], v57
	s_waitcnt lgkmcnt(13)
	v_dot8c_i32_i4_e32 v38, v122, v48
	v_dot8c_i32_i4_e32 v39, v122, v46
	v_dot8c_i32_i4_e32 v40, v124, v48
	v_dot8c_i32_i4_e32 v41, v124, v46
	v_dot8c_i32_i4_e32 v42, v126, v48
	v_dot8c_i32_i4_e32 v43, v126, v46
	v_dot8c_i32_i4_e32 v44, v128, v48
	v_dot8c_i32_i4_e32 v45, v128, v46
	v_dot8c_i32_i4_e32 v38, v123, v49
	v_dot8c_i32_i4_e32 v39, v123, v47
	v_dot8c_i32_i4_e32 v40, v125, v49
	v_dot8c_i32_i4_e32 v41, v125, v47
	v_dot8c_i32_i4_e32 v42, v127, v49
	v_dot8c_i32_i4_e32 v43, v127, v47
	v_dot8c_i32_i4_e32 v44, v129, v49
	v_dot8c_i32_i4_e32 v45, v129, v47
	v_and_b32_e32 v78, 0xffff, v32
	v_lshrrev_b32_e32 v79, 16, v32
	v_lshl_add_u32 v78, v78, 7, v152
	v_lshl_add_u32 v79, v79, 7, v153
	s_mov_b32 m0, s76
	s_add_i32 s43, s76, 0x400
	global_load_lds_dwordx4 v78, s[50:51]
	s_mov_b32 m0, s43
	s_nop 0
	global_load_lds_dwordx4 v79, s[50:51]
	s_waitcnt vmcnt(9)
	v_add_u32_e32 v54, s78, v59
	v_add_u32_e32 v55, s78, v60
	v_add_u32_e32 v56, s78, v61
	v_add_u32_e32 v57, s78, v62
	ds_read_b64_tr_b4 v[46:47], v160 offset:256
	ds_read_b64_tr_b4 v[48:49], v160 offset:1280
	ds_read_b64_tr_b4 v[122:123], v54
	ds_read_b64_tr_b4 v[124:125], v55
	ds_read_b64_tr_b4 v[126:127], v56
	ds_read_b64_tr_b4 v[128:129], v57
	s_waitcnt lgkmcnt(6)
	v_dot8c_i32_i4_e32 v38, v130, v52
	v_dot8c_i32_i4_e32 v39, v130, v50
	v_dot8c_i32_i4_e32 v40, v132, v52
	v_dot8c_i32_i4_e32 v41, v132, v50
	v_dot8c_i32_i4_e32 v42, v134, v52
	v_dot8c_i32_i4_e32 v43, v134, v50
	v_dot8c_i32_i4_e32 v44, v136, v52
	v_dot8c_i32_i4_e32 v45, v136, v50
	v_dot8c_i32_i4_e32 v38, v131, v53
	v_dot8c_i32_i4_e32 v39, v131, v51
	v_dot8c_i32_i4_e32 v40, v133, v53
	v_dot8c_i32_i4_e32 v41, v133, v51
	v_dot8c_i32_i4_e32 v42, v135, v53
	v_dot8c_i32_i4_e32 v43, v135, v51
	v_dot8c_i32_i4_e32 v44, v137, v53
	v_dot8c_i32_i4_e32 v45, v137, v51
	ds_write_b16 v65, v170
	ds_write_b16_d16_hi v65, v170 offset:128
	ds_write_b16 v65, v171 offset:256
	ds_write_b16_d16_hi v65, v171 offset:384
	ds_write_b16 v65, v172 offset:512
	ds_write_b16_d16_hi v65, v172 offset:640
	ds_write_b16 v65, v173 offset:768
	ds_write_b16_d16_hi v65, v173 offset:896
	ds_write_b16 v65, v174 offset:1024
	ds_write_b16_d16_hi v65, v174 offset:1152
	ds_write_b16 v65, v175 offset:1280
	ds_write_b16_d16_hi v65, v175 offset:1408
	ds_write_b16 v65, v176 offset:1536
	ds_write_b16_d16_hi v65, v176 offset:1664
	ds_write_b16 v65, v177 offset:1792
	ds_write_b16_d16_hi v65, v177 offset:1920
	ds_read_b64 v[202:203], v154
	ds_read_b64 v[204:205], v154 offset:512
	ds_read_b64 v[206:207], v154 offset:1024
	ds_read_b64 v[208:209], v154 offset:1536
	v_and_b32_e32 v78, 0xffff, v33
	v_lshrrev_b32_e32 v79, 16, v33
	v_lshl_add_u32 v78, v78, 7, v152
	v_lshl_add_u32 v79, v79, 7, v153
	s_mov_b32 m0, s77
	s_add_i32 s43, s77, 0x400
	global_load_lds_dwordx4 v78, s[50:51]
	s_mov_b32 m0, s43
	s_nop 0
	global_load_lds_dwordx4 v79, s[50:51]
	s_waitcnt vmcnt(9)
; __device__ __forceinline__ void peer_v_tokens(int j, const LAS unsigned short* EL, const LAS unsigned char* AL  , const LAS float* ASC  , const LAS int* SAL  , ...
;     ...
; #pragma unroll 1
;     for (int it = 0; it < 8; ++it) {
;         const int tl = it * 8 + wave, t = j * 64 + tl;
;         unsigned E[8];
;         { const LAS v4u* ep = (const LAS v4u*)(EL + tl * 128 + 16 * g); const v4u e0 = ep[0], e1 = ep[1];
;           E[0] = e0.x; E[1] = e0.y; E[2] = e0.z; E[3] = e0.w; E[4] = e1.x; E[5] = e1.y; E[6] = e1.z; E[7] = e1.w; }
;         uint2 hv[4]; float4 gv[4];
;         { unsigned ho = (unsigned)t * (D / 4) + (unsigned)lane; asm volatile("" : "+v"(ho)); const uint2* hp = (const uint2*)HB + ho; const float4* gp = (const float4*)fng + lane;
; #pragma unroll
;           for (int jq = 0; jq < 4; ++jq) { hv[jq] = hp[64 * jq]; gv[jq] = gp[64 * jq]; } }
;         VDMA(0, 0); VDMA(1, 1);
; #pragma unroll
;         for (int m = 0; m < 2; ++m) {
;             const int idx = lane + 64 * m, tau = idx >> 4, sr = idx & 15, k = 16 * (sr & 7) + 2 * tau + (sr >> 3);
;             const int aq = (int)*(const LAS signed char*)(AL + tl * 128 + k); const int tq = aq + 8;
;             const unsigned lo = (((unsigned)tq & 15u) ^ 8u) * 0x11111111u, hi = ((unsigned)(tq >> 4) & 15u) * 0x11111111u;
;             typedef unsigned u2v __attribute__((ext_vector_type(2)));
;             u2v l2; l2.x = lo; l2.y = lo; u2v h2; h2.x = hi; h2.y = hi;
;             *(LAS u2v*)(ATL + 8 * idx) = l2; *(LAS u2v*)(ATL + 1024 + 8 * idx) = h2;
;         }
;         const float asc = ASC[tl]; const int sa = SAL[tl];
;         CFENCE();
;         int accH[4], accL[4];
; #pragma unroll
;         for (int st = 0; st < 16; ++st) {
;             const int p = st >> 2, q = st & 3;
;             if (st < 14) VDMA(st + 2, (st + 2) % 3);
;             if (st < 14) asm volatile("s_waitcnt vmcnt(8)" ::: "memory");
;             else if (st == 14) asm volatile("s_waitcnt vmcnt(4)" ::: "memory");
;             else asm volatile("s_waitcnt vmcnt(0)" ::: "memory");
;             if (q == 0) {
; #pragma unroll
;                 for (int r = 0; r < 4; ++r) { accH[r] = 0; accL[r] = 0; } }
; #pragma unroll
;             for (int tp = 0; tp < 2; ++tp) {
;                 const v2i ao = TR4(ATL + (2 * q + tp) * 128 + 8 * s16), ah = TR4(ATL + 1024 + (2 * q + tp) * 128 + 8 * s16);
; #pragma unroll
	v_add_u32_e32 v54, s79, v59
	v_add_u32_e32 v55, s79, v60
	v_add_u32_e32 v56, s79, v61
	v_add_u32_e32 v57, s79, v62
	ds_read_b64_tr_b4 v[50:51], v160 offset:384
	ds_read_b64_tr_b4 v[52:53], v160 offset:1408
	ds_read_b64_tr_b4 v[130:131], v54
	ds_read_b64_tr_b4 v[132:133], v55
	ds_read_b64_tr_b4 v[134:135], v56
	ds_read_b64_tr_b4 v[136:137], v57
	s_waitcnt lgkmcnt(15)
	v_dot8c_i32_i4_e32 v38, v122, v48
	v_dot8c_i32_i4_e32 v39, v122, v46
	v_dot8c_i32_i4_e32 v40, v124, v48
	v_dot8c_i32_i4_e32 v41, v124, v46
	v_dot8c_i32_i4_e32 v42, v126, v48
	v_dot8c_i32_i4_e32 v43, v126, v46
	v_dot8c_i32_i4_e32 v44, v128, v48
	v_dot8c_i32_i4_e32 v45, v128, v46
	v_dot8c_i32_i4_e32 v38, v123, v49
	v_dot8c_i32_i4_e32 v39, v123, v47
	v_dot8c_i32_i4_e32 v40, v125, v49
	v_dot8c_i32_i4_e32 v41, v125, v47
	v_dot8c_i32_i4_e32 v42, v127, v49
	v_dot8c_i32_i4_e32 v43, v127, v47
	v_dot8c_i32_i4_e32 v44, v129, v49
	v_dot8c_i32_i4_e32 v45, v129, v47
	s_waitcnt lgkmcnt(15)
	v_and_b32_e32 v78, 0xffff, v18
	v_lshrrev_b32_e32 v79, 16, v18
	v_lshl_add_u32 v78, v78, 7, v150
	v_lshl_add_u32 v79, v79, 7, v151
	s_mov_b32 m0, s78
	s_add_i32 s43, s78, 0x400
	global_load_lds_dwordx4 v78, s[50:51]
	s_mov_b32 m0, s43
	s_nop 0
	global_load_lds_dwordx4 v79, s[50:51]
	s_waitcnt vmcnt(9)
	v_add_u32_e32 v54, s98, v59
	v_add_u32_e32 v55, s98, v60
	v_add_u32_e32 v56, s98, v61
	v_add_u32_e32 v57, s98, v62
	ds_read_b64_tr_b4 v[46:47], v160 offset:512
	ds_read_b64_tr_b4 v[48:49], v160 offset:1536
	ds_read_b64_tr_b4 v[122:123], v54
	ds_read_b64_tr_b4 v[124:125], v55
	ds_read_b64_tr_b4 v[126:127], v56
	ds_read_b64_tr_b4 v[128:129], v57
	s_waitcnt lgkmcnt(6)
	v_dot8c_i32_i4_e32 v38, v130, v52
	v_dot8c_i32_i4_e32 v39, v130, v50
	v_dot8c_i32_i4_e32 v40, v132, v52
	v_dot8c_i32_i4_e32 v41, v132, v50
	v_dot8c_i32_i4_e32 v42, v134, v52
	v_dot8c_i32_i4_e32 v43, v134, v50
	v_dot8c_i32_i4_e32 v44, v136, v52
	v_dot8c_i32_i4_e32 v45, v136, v50
	v_dot8c_i32_i4_e32 v38, v131, v53
	v_dot8c_i32_i4_e32 v39, v131, v51
	v_dot8c_i32_i4_e32 v40, v133, v53
	v_dot8c_i32_i4_e32 v41, v133, v51
	v_dot8c_i32_i4_e32 v42, v135, v53
	v_dot8c_i32_i4_e32 v43, v135, v51
	v_dot8c_i32_i4_e32 v44, v137, v53
	v_dot8c_i32_i4_e32 v45, v137, v51
	v_and_b32_e32 v78, 0xffff, v19
	v_lshrrev_b32_e32 v79, 16, v19
	v_lshl_add_u32 v78, v78, 7, v150
	v_lshl_add_u32 v79, v79, 7, v151
	s_mov_b32 m0, s79
	s_add_i32 s43, s79, 0x400
	global_load_lds_dwordx4 v78, s[50:51]
	s_mov_b32 m0, s43
	s_nop 0
	global_load_lds_dwordx4 v79, s[50:51]
	s_waitcnt vmcnt(8)
	v_add_u32_e32 v54, s99, v59
	v_add_u32_e32 v55, s99, v60
	v_add_u32_e32 v56, s99, v61
	v_add_u32_e32 v57, s99, v62
	ds_read_b64_tr_b4 v[50:51], v160 offset:640
	ds_read_b64_tr_b4 v[52:53], v160 offset:1664
	ds_read_b64_tr_b4 v[130:131], v54
	ds_read_b64_tr_b4 v[132:133], v55
	ds_read_b64_tr_b4 v[134:135], v56
	ds_read_b64_tr_b4 v[136:137], v57
	s_waitcnt lgkmcnt(6)
	v_dot8c_i32_i4_e32 v38, v122, v48
	v_dot8c_i32_i4_e32 v39, v122, v46
	v_dot8c_i32_i4_e32 v40, v124, v48
	v_dot8c_i32_i4_e32 v41, v124, v46
	v_dot8c_i32_i4_e32 v42, v126, v48
	v_dot8c_i32_i4_e32 v43, v126, v46
	v_dot8c_i32_i4_e32 v44, v128, v48
	v_dot8c_i32_i4_e32 v45, v128, v46
	v_dot8c_i32_i4_e32 v38, v123, v49
	v_dot8c_i32_i4_e32 v39, v123, v47
	v_dot8c_i32_i4_e32 v40, v125, v49
	v_dot8c_i32_i4_e32 v41, v125, v47
	v_dot8c_i32_i4_e32 v42, v127, v49
	v_dot8c_i32_i4_e32 v43, v127, v47
	v_dot8c_i32_i4_e32 v44, v129, v49
	v_dot8c_i32_i4_e32 v45, v129, v47
	s_waitcnt lgkmcnt(15)
	v_add_u32_e32 v143, 8, v139
	v_and_b32_e32 v142, 15, v143
	v_xor_b32_e32 v142, 8, v142
	v_bfe_u32 v144, v143, 4, 4
	v_mul_lo_u32 v142, v142, s92
	v_mul_lo_u32 v144, v144, s92
	v_mov_b32_e32 v143, v142
	v_mov_b32_e32 v145, v144
	ds_write2st64_b64 v159, v[142:143], v[144:145] offset1:2
	v_and_b32_e32 v78, 0xffff, v20
	v_lshrrev_b32_e32 v79, 16, v20
	v_lshl_add_u32 v78, v78, 7, v150
	v_lshl_add_u32 v79, v79, 7, v151
	s_mov_b32 m0, s98
	s_add_i32 s43, s98, 0x400
	global_load_lds_dwordx4 v78, s[50:51]
	s_mov_b32 m0, s43
	s_nop 0
	global_load_lds_dwordx4 v79, s[50:51]
	s_waitcnt vmcnt(8)
	v_add_u32_e32 v54, s76, v59
	v_add_u32_e32 v55, s76, v60
	v_add_u32_e32 v56, s76, v61
	v_add_u32_e32 v57, s76, v62
	ds_read_b64_tr_b4 v[46:47], v160 offset:768
	ds_read_b64_tr_b4 v[48:49], v160 offset:1792
	ds_read_b64_tr_b4 v[122:123], v54
	ds_read_b64_tr_b4 v[124:125], v55
	ds_read_b64_tr_b4 v[126:127], v56
	ds_read_b64_tr_b4 v[128:129], v57
	s_waitcnt lgkmcnt(7)
	v_dot8c_i32_i4_e32 v38, v130, v52
	v_dot8c_i32_i4_e32 v39, v130, v50
	v_dot8c_i32_i4_e32 v40, v132, v52
	v_dot8c_i32_i4_e32 v41, v132, v50
	v_dot8c_i32_i4_e32 v42, v134, v52
	v_dot8c_i32_i4_e32 v43, v134, v50
	v_dot8c_i32_i4_e32 v44, v136, v52
	v_dot8c_i32_i4_e32 v45, v136, v50
	v_dot8c_i32_i4_e32 v38, v131, v53
	v_dot8c_i32_i4_e32 v39, v131, v51
	v_dot8c_i32_i4_e32 v40, v133, v53
	v_dot8c_i32_i4_e32 v41, v133, v51
	v_dot8c_i32_i4_e32 v42, v135, v53
	v_dot8c_i32_i4_e32 v43, v135, v51
	v_dot8c_i32_i4_e32 v44, v137, v53
	v_dot8c_i32_i4_e32 v45, v137, v51
	v_and_b32_e32 v78, 0xffff, v21
	v_lshrrev_b32_e32 v79, 16, v21
	v_lshl_add_u32 v78, v78, 7, v150
	v_lshl_add_u32 v79, v79, 7, v151
	s_mov_b32 m0, s99
	s_add_i32 s43, s99, 0x400
	global_load_lds_dwordx4 v78, s[50:51]
	s_mov_b32 m0, s43
	s_nop 0
	global_load_lds_dwordx4 v79, s[50:51]
	s_waitcnt vmcnt(8)
	v_add_u32_e32 v54, s77, v59
	v_add_u32_e32 v55, s77, v60
	v_add_u32_e32 v56, s77, v61
	v_add_u32_e32 v57, s77, v62
	ds_read_b64_tr_b4 v[50:51], v160 offset:896
	ds_read_b64_tr_b4 v[52:53], v160 offset:1920
	ds_read_b64_tr_b4 v[130:131], v54
	ds_read_b64_tr_b4 v[132:133], v55
	ds_read_b64_tr_b4 v[134:135], v56
	ds_read_b64_tr_b4 v[136:137], v57
	s_waitcnt lgkmcnt(6)
; #define LAS __attribute__((address_space(3)))
; __device__ __forceinline__ void peer_v_tokens(int j, const LAS unsigned short* EL, const LAS unsigned char* AL  , const LAS float* ASC  , const LAS int* SAL  , ...
;     ...
;         const int tl = it * 8 + wave, t = j * 64 + tl;
;         unsigned E[8];
;         { const LAS v4u* ep = (const LAS v4u*)(EL + tl * 128 + 16 * g); const v4u e0 = ep[0], e1 = ep[1];
;           E[0] = e0.x; E[1] = e0.y; E[2] = e0.z; E[3] = e0.w; E[4] = e1.x; E[5] = e1.y; E[6] = e1.z; E[7] = e1.w; }
;         uint2 hv[4]; float4 gv[4];
;         { unsigned ho = (unsigned)t * (D / 4) + (unsigned)lane; asm volatile("" : "+v"(ho)); const uint2* hp = (const uint2*)HB + ho; const float4* gp = (const float4*)fng + lane;
; #pragma unroll
;           for (int jq = 0; jq < 4; ++jq) { hv[jq] = hp[64 * jq]; gv[jq] = gp[64 * jq]; } }
;         VDMA(0, 0); VDMA(1, 1);
; #pragma unroll
;         for (int m = 0; m < 2; ++m) {
;     ...
;         for (int st = 0; st < 16; ++st) {
;             const int p = st >> 2, q = st & 3;
;             if (st < 14) VDMA(st + 2, (st + 2) % 3);
;             if (st < 14) asm volatile("s_waitcnt vmcnt(8)" ::: "memory");
;             else if (st == 14) asm volatile("s_waitcnt vmcnt(4)" ::: "memory");
;             else asm volatile("s_waitcnt vmcnt(0)" ::: "memory");
;             if (q == 0) {
; #pragma unroll
;                 for (int r = 0; r < 4; ++r) { accH[r] = 0; accL[r] = 0; } }
; #pragma unroll
;             for (int tp = 0; tp < 2; ++tp) {
;                 const v2i ao = TR4(ATL + (2 * q + tp) * 128 + 8 * s16), ah = TR4(ATL + 1024 + (2 * q + tp) * 128 + 8 * s16);
; #pragma unroll
;                 for (int r = 0; r < 4; ++r) {
;                     const v2i d = TR4(ldsb + BUF[st % 3] + 2048 * tp + roff[r]);
;                     accH[r] = __builtin_amdgcn_sdot8(d.x, ah.x, accH[r], false); accH[r] = __builtin_amdgcn_sdot8(d.y, ah.y, accH[r], false);
;                     accL[r] = __builtin_amdgcn_sdot8(d.x, ao.x, accL[r], false); accL[r] = __builtin_amdgcn_sdot8(d.y, ao.y, accL[r], false);
;                 }
;             }
;             asm volatile("s_waitcnt lgkmcnt(0)" ::: "memory");
;             if (q == 3) {
; #pragma unroll
;                 for (int r = 0; r < 4; ++r) STASH[256 * p + 16 * (grp + 4 * r) + pc] = f2bf(asc * (float)(2 * ((accH[r] << 4) + accL[r]) + sa));
;             }
;         }
	v_dot8c_i32_i4_e32 v38, v122, v48
	v_dot8c_i32_i4_e32 v39, v122, v46
	v_dot8c_i32_i4_e32 v40, v124, v48
	v_dot8c_i32_i4_e32 v41, v124, v46
	v_dot8c_i32_i4_e32 v42, v126, v48
	v_dot8c_i32_i4_e32 v43, v126, v46
	v_dot8c_i32_i4_e32 v44, v128, v48
	v_dot8c_i32_i4_e32 v45, v128, v46
	v_dot8c_i32_i4_e32 v38, v123, v49
	v_dot8c_i32_i4_e32 v39, v123, v47
	v_dot8c_i32_i4_e32 v40, v125, v49
	v_dot8c_i32_i4_e32 v41, v125, v47
	v_dot8c_i32_i4_e32 v42, v127, v49
	v_dot8c_i32_i4_e32 v43, v127, v47
	v_dot8c_i32_i4_e32 v44, v129, v49
	v_dot8c_i32_i4_e32 v45, v129, v47
	v_and_b32_e32 v78, 0xffff, v22
	v_lshrrev_b32_e32 v79, 16, v22
	v_lshl_add_u32 v78, v78, 7, v150
	v_lshl_add_u32 v79, v79, 7, v151
	s_mov_b32 m0, s76
	s_add_i32 s43, s76, 0x400
	global_load_lds_dwordx4 v78, s[50:51]
	s_mov_b32 m0, s43
	s_nop 0
	global_load_lds_dwordx4 v79, s[50:51]
	s_waitcnt vmcnt(8)
	v_add_u32_e32 v54, s78, v59
	v_add_u32_e32 v55, s78, v60
	v_add_u32_e32 v56, s78, v61
	v_add_u32_e32 v57, s78, v62
	ds_read_b64_tr_b4 v[46:47], v160
	ds_read_b64_tr_b4 v[48:49], v160 offset:1024
	ds_read_b64_tr_b4 v[122:123], v54
	ds_read_b64_tr_b4 v[124:125], v55
	ds_read_b64_tr_b4 v[126:127], v56
	ds_read_b64_tr_b4 v[128:129], v57
	s_waitcnt lgkmcnt(6)
	v_dot8c_i32_i4_e32 v38, v130, v52
	v_dot8c_i32_i4_e32 v39, v130, v50
	v_dot8c_i32_i4_e32 v40, v132, v52
	v_dot8c_i32_i4_e32 v41, v132, v50
	v_dot8c_i32_i4_e32 v42, v134, v52
	v_dot8c_i32_i4_e32 v43, v134, v50
	v_dot8c_i32_i4_e32 v44, v136, v52
	v_dot8c_i32_i4_e32 v45, v136, v50
	v_dot8c_i32_i4_e32 v38, v131, v53
	v_dot8c_i32_i4_e32 v39, v131, v51
	v_dot8c_i32_i4_e32 v40, v133, v53
	v_dot8c_i32_i4_e32 v41, v133, v51
	v_dot8c_i32_i4_e32 v42, v135, v53
	v_dot8c_i32_i4_e32 v43, v135, v51
	v_dot8c_i32_i4_e32 v44, v137, v53
	v_dot8c_i32_i4_e32 v45, v137, v51
	s_nop 3
	s_waitcnt lgkmcnt(15)
	v_lshlrev_b32_e32 v38, 5, v38
	v_lshlrev_b32_e32 v39, 1, v39
	v_add3_u32 v38, v39, v229, v38
	v_cvt_f32_i32_e32 v38, v38
	v_mul_f32_e32 v38, v228, v38
	v_lshlrev_b32_e32 v40, 5, v40
	v_lshlrev_b32_e32 v41, 1, v41
	v_add3_u32 v40, v41, v229, v40
	v_cvt_f32_i32_e32 v40, v40
	v_mul_f32_e32 v40, v228, v40
	v_lshlrev_b32_e32 v42, 5, v42
	v_lshlrev_b32_e32 v43, 1, v43
	v_add3_u32 v42, v43, v229, v42
	v_cvt_f32_i32_e32 v42, v42
	v_mul_f32_e32 v42, v228, v42
	v_lshlrev_b32_e32 v44, 5, v44
	v_lshlrev_b32_e32 v45, 1, v45
	v_add3_u32 v44, v45, v229, v44
	v_cvt_f32_i32_e32 v44, v44
	v_mul_f32_e32 v44, v228, v44
	v_cvt_pk_bf16_f32 v188, v38, v40
	v_cvt_pk_bf16_f32 v189, v42, v44
	ds_read_b128 v[252:255], v156
	s_add_i32 s44, s40, 32
	s_ashr_i32 s45, s44, 31
	s_lshl_b64 s[44:45], s[44:45], 12
	v_lshl_add_u64 v[80:81], v[36:37], 0, s[44:45]
	s_waitcnt lgkmcnt(0)
	v_mul_f32_e32 v218, v218, v252
	v_mul_f32_e32 v219, v219, v253
	v_mul_f32_e32 v220, v220, v254
	v_mul_f32_e32 v221, v221, v255
	global_store_dwordx4 v[80:81], v[218:221], off offset:2048 sc1
	v_add_u32_e32 v147, 8, v140
	v_and_b32_e32 v146, 15, v147
	v_xor_b32_e32 v146, 8, v146
	v_bfe_u32 v148, v147, 4, 4
	v_mul_lo_u32 v146, v146, s92
	v_mul_lo_u32 v148, v148, s92
	v_mov_b32_e32 v147, v146
	v_mov_b32_e32 v149, v148
	ds_write2st64_b64 v77, v[146:147], v[148:149] offset1:2
	v_add_u32_e32 v138, 0x1c00, v74
	ds_read_u8 v139, v138
	v_add_u32_e32 v141, 0x1c00, v73
	ds_read_u8 v140, v141
	s_add_i32 s43, s67, 192
	v_mov_b32_e32 v138, s43
	ds_read2st64_b32 v[228:229], v138 offset1:1
	ds_read_b128 v[26:29], v227 offset:14336
	ds_read_b128 v[30:33], v227 offset:14352
	v_mov_b32_e32 v38, 0
	v_mov_b32_e32 v39, 0
	v_mov_b32_e32 v40, 0
	v_mov_b32_e32 v41, 0
	v_mov_b32_e32 v42, 0
	v_mov_b32_e32 v43, 0
	v_mov_b32_e32 v44, 0
	v_mov_b32_e32 v45, 0
	v_and_b32_e32 v78, 0xffff, v23
	v_lshrrev_b32_e32 v79, 16, v23
	v_lshl_add_u32 v78, v78, 7, v150
	v_lshl_add_u32 v79, v79, 7, v151
	s_mov_b32 m0, s77
	s_add_i32 s43, s77, 0x400
	global_load_lds_dwordx4 v78, s[50:51]
	s_mov_b32 m0, s43
	s_nop 0
	global_load_lds_dwordx4 v79, s[50:51]
	s_waitcnt vmcnt(9)
	v_add_u32_e32 v54, s79, v59
	v_add_u32_e32 v55, s79, v60
	v_add_u32_e32 v56, s79, v61
	v_add_u32_e32 v57, s79, v62
	ds_read_b64_tr_b4 v[50:51], v160 offset:128
	ds_read_b64_tr_b4 v[52:53], v160 offset:1152
	ds_read_b64_tr_b4 v[130:131], v54
	ds_read_b64_tr_b4 v[132:133], v55
	ds_read_b64_tr_b4 v[134:135], v56
	ds_read_b64_tr_b4 v[136:137], v57
	s_waitcnt lgkmcnt(13)
	s_waitcnt vmcnt(36) lgkmcnt(15)
; #define LAS __attribute__((address_space(3)))
; __device__ __forceinline__ void peer_v_tokens(int j, const LAS unsigned short* EL, const LAS unsigned char* AL  , const LAS float* ASC  , const LAS int* SAL  , ...
;     ...
;         for (int st = 0; st < 16; ++st) {
;             const int p = st >> 2, q = st & 3;
;             if (st < 14) VDMA(st + 2, (st + 2) % 3);
;             if (st < 14) asm volatile("s_waitcnt vmcnt(8)" ::: "memory");
;             else if (st == 14) asm volatile("s_waitcnt vmcnt(4)" ::: "memory");
;             else asm volatile("s_waitcnt vmcnt(0)" ::: "memory");
;             if (q == 0) {
; #pragma unroll
;                 for (int r = 0; r < 4; ++r) { accH[r] = 0; accL[r] = 0; } }
; #pragma unroll
;             for (int tp = 0; tp < 2; ++tp) {
;                 const v2i ao = TR4(ATL + (2 * q + tp) * 128 + 8 * s16), ah = TR4(ATL + 1024 + (2 * q + tp) * 128 + 8 * s16);
; #pragma unroll
;                 for (int r = 0; r < 4; ++r) {
;                     const v2i d = TR4(ldsb + BUF[st % 3] + 2048 * tp + roff[r]);
;                     accH[r] = __builtin_amdgcn_sdot8(d.x, ah.x, accH[r], false); accH[r] = __builtin_amdgcn_sdot8(d.y, ah.y, accH[r], false);
;     ...
;         {
;             float4 v[4]; float ss = 0.f;
; #pragma unroll
;             for (int jq = 0; jq < 4; ++jq) { typedef unsigned u2v __attribute__((ext_vector_type(2))); const u2v pw = *(const LAS u2v*)(STASH + 4 * lane + 256 * jq); const uint2 hw = hv[jq];
;                 v[jq] = make_float4(__uint_as_float(hw.x << 16) + __uint_as_float(pw.x << 16), __uint_as_float(hw.x & 0xffff0000u) + __uint_as_float(pw.x & 0xffff0000u),
;                                     __uint_as_float(hw.y << 16) + __uint_as_float(pw.y << 16), __uint_as_float(hw.y & 0xffff0000u) + __uint_as_float(pw.y & 0xffff0000u));
;                 ss += v[jq].x * v[jq].x + v[jq].y * v[jq].y + v[jq].z * v[jq].z + v[jq].w * v[jq].w; }
;             ss = wave_sum(ss);
;             const float r3 = rsqrtf(ss * (1.f / D) + EPS);
;             float4* op = (float4*)(outp + (size_t)t * D) + lane;
; #pragma unroll
;             for (int jq = 0; jq < 4; ++jq) { typedef float f4v __attribute__((ext_vector_type(4))); f4v o4; o4.x = v[jq].x * r3 * gv[jq].x; o4.y = v[jq].y * r3 * gv[jq].y; o4.z = v[jq].z * r3 * gv[jq].z; o4.w = v[jq].w * r3 * gv[jq].w;
;                 __builtin_nontemporal_store(o4, (f4v*)op + 64 * jq); }
	v_lshlrev_b32_e32 v236, 16, v194
	v_and_b32_e32 v237, 0xffff0000, v194
	v_lshlrev_b32_e32 v142, 16, v202
	v_and_b32_e32 v143, 0xffff0000, v202
	v_add_f32_e32 v236, v236, v142
	v_add_f32_e32 v237, v237, v143
	v_lshlrev_b32_e32 v238, 16, v195
	v_and_b32_e32 v239, 0xffff0000, v195
	v_lshlrev_b32_e32 v142, 16, v203
	v_and_b32_e32 v143, 0xffff0000, v203
	v_add_f32_e32 v238, v238, v142
	v_add_f32_e32 v239, v239, v143
	v_lshlrev_b32_e32 v240, 16, v196
	v_and_b32_e32 v241, 0xffff0000, v196
	v_lshlrev_b32_e32 v142, 16, v204
	v_and_b32_e32 v143, 0xffff0000, v204
	v_add_f32_e32 v240, v240, v142
	v_add_f32_e32 v241, v241, v143
	v_lshlrev_b32_e32 v242, 16, v197
	v_and_b32_e32 v243, 0xffff0000, v197
	v_lshlrev_b32_e32 v142, 16, v205
	v_and_b32_e32 v143, 0xffff0000, v205
	v_add_f32_e32 v242, v242, v142
	v_add_f32_e32 v243, v243, v143
	v_lshlrev_b32_e32 v244, 16, v198
	v_and_b32_e32 v245, 0xffff0000, v198
	v_lshlrev_b32_e32 v142, 16, v206
	v_and_b32_e32 v143, 0xffff0000, v206
	v_add_f32_e32 v244, v244, v142
	v_add_f32_e32 v245, v245, v143
	v_lshlrev_b32_e32 v246, 16, v199
	v_and_b32_e32 v247, 0xffff0000, v199
	v_lshlrev_b32_e32 v142, 16, v207
	v_and_b32_e32 v143, 0xffff0000, v207
	v_add_f32_e32 v246, v246, v142
	v_add_f32_e32 v247, v247, v143
	v_lshlrev_b32_e32 v248, 16, v200
	v_and_b32_e32 v249, 0xffff0000, v200
	v_lshlrev_b32_e32 v142, 16, v208
	v_and_b32_e32 v143, 0xffff0000, v208
	v_add_f32_e32 v248, v248, v142
	v_add_f32_e32 v249, v249, v143
	v_lshlrev_b32_e32 v250, 16, v201
	v_and_b32_e32 v251, 0xffff0000, v201
	v_lshlrev_b32_e32 v142, 16, v209
	v_and_b32_e32 v143, 0xffff0000, v209
	v_add_f32_e32 v250, v250, v142
	v_add_f32_e32 v251, v251, v143
	v_mov_b32_e32 v144, 0
	v_mul_f32_e32 v145, v236, v236
	v_fmac_f32_e32 v145, v237, v237
	v_fmac_f32_e32 v145, v238, v238
	v_fmac_f32_e32 v145, v239, v239
	v_add_f32_e32 v144, v144, v145
	v_mul_f32_e32 v145, v240, v240
	v_fmac_f32_e32 v145, v241, v241
	v_fmac_f32_e32 v145, v242, v242
	v_fmac_f32_e32 v145, v243, v243
	v_add_f32_e32 v144, v144, v145
	v_mul_f32_e32 v145, v244, v244
	v_fmac_f32_e32 v145, v245, v245
	v_fmac_f32_e32 v145, v246, v246
	v_fmac_f32_e32 v145, v247, v247
	v_add_f32_e32 v144, v144, v145
	v_mul_f32_e32 v145, v248, v248
	v_fmac_f32_e32 v145, v249, v249
	v_fmac_f32_e32 v145, v250, v250
	v_fmac_f32_e32 v145, v251, v251
	v_add_f32_e32 v144, v144, v145
	s_nop 1
	v_add_f32_dpp v144, v144, v144 quad_perm:[1,0,3,2] row_mask:0xf bank_mask:0xf bound_ctrl:1
	s_nop 1
	v_add_f32_dpp v144, v144, v144 quad_perm:[2,3,0,1] row_mask:0xf bank_mask:0xf bound_ctrl:1
	s_nop 1
	v_add_f32_dpp v144, v144, v144 row_half_mirror row_mask:0xf bank_mask:0xf bound_ctrl:1
	s_nop 1
	v_add_f32_dpp v144, v144, v144 row_mirror row_mask:0xf bank_mask:0xf bound_ctrl:1
	s_nop 1
	v_readlane_b32 s10, v144, 0
	v_readlane_b32 s11, v144, 16
	v_readlane_b32 s14, v144, 32
	v_readlane_b32 s15, v144, 48
	s_nop 3
	v_mov_b32_e32 v144, s11
	v_mov_b32_e32 v145, s15
	v_add_f32_e32 v144, s10, v144
	v_add_f32_e32 v145, s14, v145
	v_add_f32_e32 v144, v144, v145
	v_fmamk_f32 v144, v144, 0x3a800000, v111
	v_rsq_f32_e32 v144, v144
	s_nop 0
	v_mul_f32_e32 v236, v236, v144
	v_mul_f32_e32 v237, v237, v144
	v_mul_f32_e32 v238, v238, v144
	v_mul_f32_e32 v239, v239, v144
	v_mul_f32_e32 v240, v240, v144
	v_mul_f32_e32 v241, v241, v144
	v_mul_f32_e32 v242, v242, v144
	v_mul_f32_e32 v243, v243, v144
	v_mul_f32_e32 v244, v244, v144
	v_mul_f32_e32 v245, v245, v144
	v_mul_f32_e32 v246, v246, v144
	v_mul_f32_e32 v247, v247, v144
	v_mul_f32_e32 v248, v248, v144
	v_mul_f32_e32 v249, v249, v144
	v_mul_f32_e32 v250, v250, v144
	v_mul_f32_e32 v251, v251, v144
	v_dot8c_i32_i4_e32 v38, v122, v48
	v_dot8c_i32_i4_e32 v39, v122, v46
	v_dot8c_i32_i4_e32 v40, v124, v48
	v_dot8c_i32_i4_e32 v41, v124, v46
	v_dot8c_i32_i4_e32 v42, v126, v48
	v_dot8c_i32_i4_e32 v43, v126, v46
	v_dot8c_i32_i4_e32 v44, v128, v48
	v_dot8c_i32_i4_e32 v45, v128, v46
	v_dot8c_i32_i4_e32 v38, v123, v49
	v_dot8c_i32_i4_e32 v39, v123, v47
	v_dot8c_i32_i4_e32 v40, v125, v49
	v_dot8c_i32_i4_e32 v41, v125, v47
	v_dot8c_i32_i4_e32 v42, v127, v49
	v_dot8c_i32_i4_e32 v43, v127, v47
	v_dot8c_i32_i4_e32 v44, v129, v49
	v_dot8c_i32_i4_e32 v45, v129, v47
	v_and_b32_e32 v78, 0xffff, v24
	v_lshrrev_b32_e32 v79, 16, v24
	v_lshl_add_u32 v78, v78, 7, v150
	v_lshl_add_u32 v79, v79, 7, v151
	s_mov_b32 m0, s78
	s_add_i32 s43, s78, 0x400
	global_load_lds_dwordx4 v78, s[50:51]
	s_mov_b32 m0, s43
	s_nop 0
	global_load_lds_dwordx4 v79, s[50:51]
	s_waitcnt vmcnt(9)
	v_add_u32_e32 v54, s98, v59
	v_add_u32_e32 v55, s98, v60
	v_add_u32_e32 v56, s98, v61
	v_add_u32_e32 v57, s98, v62
	ds_read_b64_tr_b4 v[46:47], v160 offset:256
	ds_read_b64_tr_b4 v[48:49], v160 offset:1280
	ds_read_b64_tr_b4 v[122:123], v54
	ds_read_b64_tr_b4 v[124:125], v55
	ds_read_b64_tr_b4 v[126:127], v56
	ds_read_b64_tr_b4 v[128:129], v57
	s_waitcnt lgkmcnt(6)
	v_dot8c_i32_i4_e32 v38, v130, v52
	v_dot8c_i32_i4_e32 v39, v130, v50
	v_dot8c_i32_i4_e32 v40, v132, v52
	v_dot8c_i32_i4_e32 v41, v132, v50
	v_dot8c_i32_i4_e32 v42, v134, v52
	v_dot8c_i32_i4_e32 v43, v134, v50
	v_dot8c_i32_i4_e32 v44, v136, v52
	v_dot8c_i32_i4_e32 v45, v136, v50
	v_dot8c_i32_i4_e32 v38, v131, v53
	v_dot8c_i32_i4_e32 v39, v131, v51
	v_dot8c_i32_i4_e32 v40, v133, v53
	v_dot8c_i32_i4_e32 v41, v133, v51
	v_dot8c_i32_i4_e32 v42, v135, v53
	v_dot8c_i32_i4_e32 v43, v135, v51
	v_dot8c_i32_i4_e32 v44, v137, v53
	v_dot8c_i32_i4_e32 v45, v137, v51
	v_and_b32_e32 v78, 0xffff, v25
	v_lshrrev_b32_e32 v79, 16, v25
	v_lshl_add_u32 v78, v78, 7, v150
	v_lshl_add_u32 v79, v79, 7, v151
	s_mov_b32 m0, s79
	s_add_i32 s43, s79, 0x400
	global_load_lds_dwordx4 v78, s[50:51]
	s_mov_b32 m0, s43
	s_nop 0
	global_load_lds_dwordx4 v79, s[50:51]
	s_waitcnt vmcnt(9)
; #define LAS __attribute__((address_space(3)))
; #define TR4(p_) __builtin_amdgcn_ds_read_tr4_b64_v2i32((LAS v2i*)(p_))
; __device__ __forceinline__ void peer_v_tokens(int j, const LAS unsigned short* EL, const LAS unsigned char* AL  , const LAS float* ASC  , const LAS int* SAL  , ...
;     ...
;         for (int m = 0; m < 2; ++m) {
;             const int idx = lane + 64 * m, tau = idx >> 4, sr = idx & 15, k = 16 * (sr & 7) + 2 * tau + (sr >> 3);
;             const int aq = (int)*(const LAS signed char*)(AL + tl * 128 + k); const int tq = aq + 8;
;             const unsigned lo = (((unsigned)tq & 15u) ^ 8u) * 0x11111111u, hi = ((unsigned)(tq >> 4) & 15u) * 0x11111111u;
;             typedef unsigned u2v __attribute__((ext_vector_type(2)));
;             u2v l2; l2.x = lo; l2.y = lo; u2v h2; h2.x = hi; h2.y = hi;
;             *(LAS u2v*)(ATL + 8 * idx) = l2; *(LAS u2v*)(ATL + 1024 + 8 * idx) = h2;
;         }
;     ...
;         for (int st = 0; st < 16; ++st) {
;             const int p = st >> 2, q = st & 3;
;             if (st < 14) VDMA(st + 2, (st + 2) % 3);
;             if (st < 14) asm volatile("s_waitcnt vmcnt(8)" ::: "memory");
;             else if (st == 14) asm volatile("s_waitcnt vmcnt(4)" ::: "memory");
;             else asm volatile("s_waitcnt vmcnt(0)" ::: "memory");
;             if (q == 0) {
; #pragma unroll
;                 for (int r = 0; r < 4; ++r) { accH[r] = 0; accL[r] = 0; } }
; #pragma unroll
;             for (int tp = 0; tp < 2; ++tp) {
;                 const v2i ao = TR4(ATL + (2 * q + tp) * 128 + 8 * s16), ah = TR4(ATL + 1024 + (2 * q + tp) * 128 + 8 * s16);
; #pragma unroll
;                 for (int r = 0; r < 4; ++r) {
;                     const v2i d = TR4(ldsb + BUF[st % 3] + 2048 * tp + roff[r]);
;                     accH[r] = __builtin_amdgcn_sdot8(d.x, ah.x, accH[r], false); accH[r] = __builtin_amdgcn_sdot8(d.y, ah.y, accH[r], false);
;                     accL[r] = __builtin_amdgcn_sdot8(d.x, ao.x, accL[r], false); accL[r] = __builtin_amdgcn_sdot8(d.y, ao.y, accL[r], false);
;                 }
;             }
	v_add_u32_e32 v54, s99, v59
	v_add_u32_e32 v55, s99, v60
	v_add_u32_e32 v56, s99, v61
	v_add_u32_e32 v57, s99, v62
	ds_read_b64_tr_b4 v[50:51], v160 offset:384
	ds_read_b64_tr_b4 v[52:53], v160 offset:1408
	ds_read_b64_tr_b4 v[130:131], v54
	ds_read_b64_tr_b4 v[132:133], v55
	ds_read_b64_tr_b4 v[134:135], v56
	ds_read_b64_tr_b4 v[136:137], v57
	s_waitcnt lgkmcnt(6)
	v_dot8c_i32_i4_e32 v38, v122, v48
	v_dot8c_i32_i4_e32 v39, v122, v46
	v_dot8c_i32_i4_e32 v40, v124, v48
	v_dot8c_i32_i4_e32 v41, v124, v46
	v_dot8c_i32_i4_e32 v42, v126, v48
	v_dot8c_i32_i4_e32 v43, v126, v46
	v_dot8c_i32_i4_e32 v44, v128, v48
	v_dot8c_i32_i4_e32 v45, v128, v46
	v_dot8c_i32_i4_e32 v38, v123, v49
	v_dot8c_i32_i4_e32 v39, v123, v47
	v_dot8c_i32_i4_e32 v40, v125, v49
	v_dot8c_i32_i4_e32 v41, v125, v47
	v_dot8c_i32_i4_e32 v42, v127, v49
	v_dot8c_i32_i4_e32 v43, v127, v47
	v_dot8c_i32_i4_e32 v44, v129, v49
	v_dot8c_i32_i4_e32 v45, v129, v47
	s_waitcnt lgkmcnt(15)
	v_and_b32_e32 v78, 0xffff, v26
	v_lshrrev_b32_e32 v79, 16, v26
	v_lshl_add_u32 v78, v78, 7, v150
	v_lshl_add_u32 v79, v79, 7, v151
	s_mov_b32 m0, s98
	s_add_i32 s43, s98, 0x400
	global_load_lds_dwordx4 v78, s[50:51]
	s_mov_b32 m0, s43
	s_nop 0
	global_load_lds_dwordx4 v79, s[50:51]
	s_waitcnt vmcnt(9)
	v_add_u32_e32 v54, s76, v59
	v_add_u32_e32 v55, s76, v60
	v_add_u32_e32 v56, s76, v61
	v_add_u32_e32 v57, s76, v62
	ds_read_b64_tr_b4 v[46:47], v160 offset:512
	ds_read_b64_tr_b4 v[48:49], v160 offset:1536
	ds_read_b64_tr_b4 v[122:123], v54
	ds_read_b64_tr_b4 v[124:125], v55
	ds_read_b64_tr_b4 v[126:127], v56
	ds_read_b64_tr_b4 v[128:129], v57
	s_waitcnt lgkmcnt(6)
	v_dot8c_i32_i4_e32 v38, v130, v52
	v_dot8c_i32_i4_e32 v39, v130, v50
	v_dot8c_i32_i4_e32 v40, v132, v52
	v_dot8c_i32_i4_e32 v41, v132, v50
	v_dot8c_i32_i4_e32 v42, v134, v52
	v_dot8c_i32_i4_e32 v43, v134, v50
	v_dot8c_i32_i4_e32 v44, v136, v52
	v_dot8c_i32_i4_e32 v45, v136, v50
	v_dot8c_i32_i4_e32 v38, v131, v53
	v_dot8c_i32_i4_e32 v39, v131, v51
	v_dot8c_i32_i4_e32 v40, v133, v53
	v_dot8c_i32_i4_e32 v41, v133, v51
	v_dot8c_i32_i4_e32 v42, v135, v53
	v_dot8c_i32_i4_e32 v43, v135, v51
	v_dot8c_i32_i4_e32 v44, v137, v53
	v_dot8c_i32_i4_e32 v45, v137, v51
	v_and_b32_e32 v78, 0xffff, v27
	v_lshrrev_b32_e32 v79, 16, v27
	v_lshl_add_u32 v78, v78, 7, v150
	v_lshl_add_u32 v79, v79, 7, v151
	s_mov_b32 m0, s99
	s_add_i32 s43, s99, 0x400
	global_load_lds_dwordx4 v78, s[50:51]
	s_mov_b32 m0, s43
	s_nop 0
	global_load_lds_dwordx4 v79, s[50:51]
	s_waitcnt vmcnt(8)
	v_add_u32_e32 v54, s77, v59
	v_add_u32_e32 v55, s77, v60
	v_add_u32_e32 v56, s77, v61
	v_add_u32_e32 v57, s77, v62
	ds_read_b64_tr_b4 v[50:51], v160 offset:640
	ds_read_b64_tr_b4 v[52:53], v160 offset:1664
	ds_read_b64_tr_b4 v[130:131], v54
	ds_read_b64_tr_b4 v[132:133], v55
	ds_read_b64_tr_b4 v[134:135], v56
	ds_read_b64_tr_b4 v[136:137], v57
	s_waitcnt lgkmcnt(6)
	v_dot8c_i32_i4_e32 v38, v122, v48
	v_dot8c_i32_i4_e32 v39, v122, v46
	v_dot8c_i32_i4_e32 v40, v124, v48
	v_dot8c_i32_i4_e32 v41, v124, v46
	v_dot8c_i32_i4_e32 v42, v126, v48
	v_dot8c_i32_i4_e32 v43, v126, v46
	v_dot8c_i32_i4_e32 v44, v128, v48
	v_dot8c_i32_i4_e32 v45, v128, v46
	v_dot8c_i32_i4_e32 v38, v123, v49
	v_dot8c_i32_i4_e32 v39, v123, v47
	v_dot8c_i32_i4_e32 v40, v125, v49
	v_dot8c_i32_i4_e32 v41, v125, v47
	v_dot8c_i32_i4_e32 v42, v127, v49
	v_dot8c_i32_i4_e32 v43, v127, v47
	v_dot8c_i32_i4_e32 v44, v129, v49
	v_dot8c_i32_i4_e32 v45, v129, v47
	s_waitcnt lgkmcnt(15)
	v_add_u32_e32 v143, 8, v139
	v_and_b32_e32 v142, 15, v143
	v_xor_b32_e32 v142, 8, v142
	v_bfe_u32 v144, v143, 4, 4
	v_mul_lo_u32 v142, v142, s92
	v_mul_lo_u32 v144, v144, s92
	v_mov_b32_e32 v143, v142
	v_mov_b32_e32 v145, v144
	ds_write2st64_b64 v159, v[142:143], v[144:145] offset1:2
	v_and_b32_e32 v78, 0xffff, v28
	v_lshrrev_b32_e32 v79, 16, v28
	v_lshl_add_u32 v78, v78, 7, v150
	v_lshl_add_u32 v79, v79, 7, v151
	s_mov_b32 m0, s76
	s_add_i32 s43, s76, 0x400
	global_load_lds_dwordx4 v78, s[50:51]
	s_mov_b32 m0, s43
	s_nop 0
	global_load_lds_dwordx4 v79, s[50:51]
	s_waitcnt vmcnt(8)
	v_add_u32_e32 v54, s78, v59
	v_add_u32_e32 v55, s78, v60
	v_add_u32_e32 v56, s78, v61
	v_add_u32_e32 v57, s78, v62
	ds_read_b64_tr_b4 v[46:47], v160 offset:768
	ds_read_b64_tr_b4 v[48:49], v160 offset:1792
	ds_read_b64_tr_b4 v[122:123], v54
	ds_read_b64_tr_b4 v[124:125], v55
	ds_read_b64_tr_b4 v[126:127], v56
	ds_read_b64_tr_b4 v[128:129], v57
	s_waitcnt lgkmcnt(7)
	v_dot8c_i32_i4_e32 v38, v130, v52
	v_dot8c_i32_i4_e32 v39, v130, v50
	v_dot8c_i32_i4_e32 v40, v132, v52
	v_dot8c_i32_i4_e32 v41, v132, v50
	v_dot8c_i32_i4_e32 v42, v134, v52
	v_dot8c_i32_i4_e32 v43, v134, v50
	v_dot8c_i32_i4_e32 v44, v136, v52
	v_dot8c_i32_i4_e32 v45, v136, v50
	v_dot8c_i32_i4_e32 v38, v131, v53
	v_dot8c_i32_i4_e32 v39, v131, v51
	v_dot8c_i32_i4_e32 v40, v133, v53
	v_dot8c_i32_i4_e32 v41, v133, v51
	v_dot8c_i32_i4_e32 v42, v135, v53
	v_dot8c_i32_i4_e32 v43, v135, v51
	v_dot8c_i32_i4_e32 v44, v137, v53
	v_dot8c_i32_i4_e32 v45, v137, v51
	v_and_b32_e32 v78, 0xffff, v29
	v_lshrrev_b32_e32 v79, 16, v29
	v_lshl_add_u32 v78, v78, 7, v150
	v_lshl_add_u32 v79, v79, 7, v151
	s_mov_b32 m0, s77
	s_add_i32 s43, s77, 0x400
	global_load_lds_dwordx4 v78, s[50:51]
	s_mov_b32 m0, s43
	s_nop 0
	global_load_lds_dwordx4 v79, s[50:51]
	s_waitcnt vmcnt(8)
	v_add_u32_e32 v54, s79, v59
	v_add_u32_e32 v55, s79, v60
	v_add_u32_e32 v56, s79, v61
	v_add_u32_e32 v57, s79, v62
	ds_read_b64_tr_b4 v[50:51], v160 offset:896
	ds_read_b64_tr_b4 v[52:53], v160 offset:1920
	ds_read_b64_tr_b4 v[130:131], v54
	ds_read_b64_tr_b4 v[132:133], v55
	ds_read_b64_tr_b4 v[134:135], v56
	ds_read_b64_tr_b4 v[136:137], v57
	s_waitcnt lgkmcnt(6)
; __device__ __forceinline__ bf16 f2bf(float f) { return (bf16)f2bfu(f); }
; #define TR4(p_) __builtin_amdgcn_ds_read_tr4_b64_v2i32((LAS v2i*)(p_))
; __device__ __forceinline__ void peer_v_tokens(int j, const LAS unsigned short* EL, const LAS unsigned char* AL  , const LAS float* ASC  , const LAS int* SAL  , ...
;     ...
;         for (int st = 0; st < 16; ++st) {
;             const int p = st >> 2, q = st & 3;
;             if (st < 14) VDMA(st + 2, (st + 2) % 3);
;             if (st < 14) asm volatile("s_waitcnt vmcnt(8)" ::: "memory");
;             else if (st == 14) asm volatile("s_waitcnt vmcnt(4)" ::: "memory");
;             else asm volatile("s_waitcnt vmcnt(0)" ::: "memory");
;             if (q == 0) {
; #pragma unroll
;                 for (int r = 0; r < 4; ++r) { accH[r] = 0; accL[r] = 0; } }
; #pragma unroll
;             for (int tp = 0; tp < 2; ++tp) {
;                 const v2i ao = TR4(ATL + (2 * q + tp) * 128 + 8 * s16), ah = TR4(ATL + 1024 + (2 * q + tp) * 128 + 8 * s16);
; #pragma unroll
;                 for (int r = 0; r < 4; ++r) {
;                     const v2i d = TR4(ldsb + BUF[st % 3] + 2048 * tp + roff[r]);
;                     accH[r] = __builtin_amdgcn_sdot8(d.x, ah.x, accH[r], false); accH[r] = __builtin_amdgcn_sdot8(d.y, ah.y, accH[r], false);
;                     accL[r] = __builtin_amdgcn_sdot8(d.x, ao.x, accL[r], false); accL[r] = __builtin_amdgcn_sdot8(d.y, ao.y, accL[r], false);
;                 }
;             }
;             asm volatile("s_waitcnt lgkmcnt(0)" ::: "memory");
;             if (q == 3) {
; #pragma unroll
;                 for (int r = 0; r < 4; ++r) STASH[256 * p + 16 * (grp + 4 * r) + pc] = f2bf(asc * (float)(2 * ((accH[r] << 4) + accL[r]) + sa));
;             }
;         }
;     ...
;             float4* op = (float4*)(outp + (size_t)t * D) + lane;
; #pragma unroll
;             for (int jq = 0; jq < 4; ++jq) { typedef float f4v __attribute__((ext_vector_type(4))); f4v o4; o4.x = v[jq].x * r3 * gv[jq].x; o4.y = v[jq].y * r3 * gv[jq].y; o4.z = v[jq].z * r3 * gv[jq].z; o4.w = v[jq].w * r3 * gv[jq].w;
;                 __builtin_nontemporal_store(o4, (f4v*)op + 64 * jq); }
	v_dot8c_i32_i4_e32 v38, v122, v48
	v_dot8c_i32_i4_e32 v39, v122, v46
	v_dot8c_i32_i4_e32 v40, v124, v48
	v_dot8c_i32_i4_e32 v41, v124, v46
	v_dot8c_i32_i4_e32 v42, v126, v48
	v_dot8c_i32_i4_e32 v43, v126, v46
	v_dot8c_i32_i4_e32 v44, v128, v48
	v_dot8c_i32_i4_e32 v45, v128, v46
	v_dot8c_i32_i4_e32 v38, v123, v49
	v_dot8c_i32_i4_e32 v39, v123, v47
	v_dot8c_i32_i4_e32 v40, v125, v49
	v_dot8c_i32_i4_e32 v41, v125, v47
	v_dot8c_i32_i4_e32 v42, v127, v49
	v_dot8c_i32_i4_e32 v43, v127, v47
	v_dot8c_i32_i4_e32 v44, v129, v49
	v_dot8c_i32_i4_e32 v45, v129, v47
	v_and_b32_e32 v78, 0xffff, v30
	v_lshrrev_b32_e32 v79, 16, v30
	v_lshl_add_u32 v78, v78, 7, v150
	v_lshl_add_u32 v79, v79, 7, v151
	s_mov_b32 m0, s78
	s_add_i32 s43, s78, 0x400
	global_load_lds_dwordx4 v78, s[50:51]
	s_mov_b32 m0, s43
	s_nop 0
	global_load_lds_dwordx4 v79, s[50:51]
	s_waitcnt vmcnt(8)
	v_add_u32_e32 v54, s98, v59
	v_add_u32_e32 v55, s98, v60
	v_add_u32_e32 v56, s98, v61
	v_add_u32_e32 v57, s98, v62
	ds_read_b64_tr_b4 v[46:47], v160
	ds_read_b64_tr_b4 v[48:49], v160 offset:1024
	ds_read_b64_tr_b4 v[122:123], v54
	ds_read_b64_tr_b4 v[124:125], v55
	ds_read_b64_tr_b4 v[126:127], v56
	ds_read_b64_tr_b4 v[128:129], v57
	s_waitcnt lgkmcnt(6)
	v_dot8c_i32_i4_e32 v38, v130, v52
	v_dot8c_i32_i4_e32 v39, v130, v50
	v_dot8c_i32_i4_e32 v40, v132, v52
	v_dot8c_i32_i4_e32 v41, v132, v50
	v_dot8c_i32_i4_e32 v42, v134, v52
	v_dot8c_i32_i4_e32 v43, v134, v50
	v_dot8c_i32_i4_e32 v44, v136, v52
	v_dot8c_i32_i4_e32 v45, v136, v50
	v_dot8c_i32_i4_e32 v38, v131, v53
	v_dot8c_i32_i4_e32 v39, v131, v51
	v_dot8c_i32_i4_e32 v40, v133, v53
	v_dot8c_i32_i4_e32 v41, v133, v51
	v_dot8c_i32_i4_e32 v42, v135, v53
	v_dot8c_i32_i4_e32 v43, v135, v51
	v_dot8c_i32_i4_e32 v44, v137, v53
	v_dot8c_i32_i4_e32 v45, v137, v51
	s_nop 3
	s_waitcnt lgkmcnt(15)
	v_lshlrev_b32_e32 v38, 5, v38
	v_lshlrev_b32_e32 v39, 1, v39
	v_add3_u32 v38, v39, v229, v38
	v_cvt_f32_i32_e32 v38, v38
	v_mul_f32_e32 v38, v228, v38
	v_lshlrev_b32_e32 v40, 5, v40
	v_lshlrev_b32_e32 v41, 1, v41
	v_add3_u32 v40, v41, v229, v40
	v_cvt_f32_i32_e32 v40, v40
	v_mul_f32_e32 v40, v228, v40
	v_lshlrev_b32_e32 v42, 5, v42
	v_lshlrev_b32_e32 v43, 1, v43
	v_add3_u32 v42, v43, v229, v42
	v_cvt_f32_i32_e32 v42, v42
	v_mul_f32_e32 v42, v228, v42
	v_lshlrev_b32_e32 v44, 5, v44
	v_lshlrev_b32_e32 v45, 1, v45
	v_add3_u32 v44, v45, v229, v44
	v_cvt_f32_i32_e32 v44, v44
	v_mul_f32_e32 v44, v228, v44
	v_cvt_pk_bf16_f32 v182, v38, v40
	v_cvt_pk_bf16_f32 v183, v42, v44
	ds_read_b128 v[252:255], v156 offset:1024
	s_add_i32 s44, s40, 32
	s_ashr_i32 s45, s44, 31
	s_lshl_b64 s[44:45], s[44:45], 12
	v_lshl_add_u64 v[80:81], v[36:37], 0, s[44:45]
	s_waitcnt lgkmcnt(0)
	v_mul_f32_e32 v222, v222, v252
	v_mul_f32_e32 v223, v223, v253
	v_mul_f32_e32 v224, v224, v254
	v_mul_f32_e32 v225, v225, v255
	global_store_dwordx4 v[80:81], v[222:225], off offset:3072 sc1
	ds_read_b128 v[252:255], v155
	s_add_i32 s44, s40, 40
	s_ashr_i32 s45, s44, 31
	s_lshl_b64 s[44:45], s[44:45], 12
	v_lshl_add_u64 v[80:81], v[36:37], 0, s[44:45]
	s_waitcnt lgkmcnt(0)
	v_mul_f32_e32 v236, v236, v252
	v_mul_f32_e32 v237, v237, v253
	v_mul_f32_e32 v238, v238, v254
	v_mul_f32_e32 v239, v239, v255
	global_store_dwordx4 v[80:81], v[236:239], off sc1
	v_add_u32_e32 v147, 8, v140
	v_and_b32_e32 v146, 15, v147
	v_xor_b32_e32 v146, 8, v146
	v_bfe_u32 v148, v147, 4, 4
	v_mul_lo_u32 v146, v146, s92
	v_mul_lo_u32 v148, v148, s92
	v_mov_b32_e32 v147, v146
	v_mov_b32_e32 v149, v148
	ds_write2st64_b64 v77, v[146:147], v[148:149] offset1:2
	v_add_u32_e32 v138, 0x1800, v74
	ds_read_u8 v139, v138
	v_add_u32_e32 v141, 0x1800, v73
	ds_read_u8 v140, v141
	s_add_i32 s43, s67, 224
	v_mov_b32_e32 v138, s43
	ds_read2st64_b32 v[228:229], v138 offset1:1
	ds_read_b128 v[18:21], v227 offset:12288
	ds_read_b128 v[22:25], v227 offset:12304
	v_add_u32_e32 v152, 0x600000, v63
	v_add_u32_e32 v153, 0x600000, v64
	v_mov_b32_e32 v38, 0
	v_mov_b32_e32 v39, 0
	v_mov_b32_e32 v40, 0
	v_mov_b32_e32 v41, 0
	v_mov_b32_e32 v42, 0
	v_mov_b32_e32 v43, 0
	v_mov_b32_e32 v44, 0
	v_mov_b32_e32 v45, 0
	v_and_b32_e32 v78, 0xffff, v31
	v_lshrrev_b32_e32 v79, 16, v31
	v_lshl_add_u32 v78, v78, 7, v150
	v_lshl_add_u32 v79, v79, 7, v151
	s_mov_b32 m0, s79
	s_add_i32 s43, s79, 0x400
	global_load_lds_dwordx4 v78, s[50:51]
	s_mov_b32 m0, s43
	s_nop 0
	global_load_lds_dwordx4 v79, s[50:51]
	s_waitcnt vmcnt(10)
	v_add_u32_e32 v54, s99, v59
	v_add_u32_e32 v55, s99, v60
	v_add_u32_e32 v56, s99, v61
	v_add_u32_e32 v57, s99, v62
	ds_read_b64_tr_b4 v[50:51], v160 offset:128
	ds_read_b64_tr_b4 v[52:53], v160 offset:1152
	ds_read_b64_tr_b4 v[130:131], v54
	ds_read_b64_tr_b4 v[132:133], v55
	ds_read_b64_tr_b4 v[134:135], v56
	ds_read_b64_tr_b4 v[136:137], v57
	s_waitcnt lgkmcnt(14)
	v_dot8c_i32_i4_e32 v38, v122, v48
	v_dot8c_i32_i4_e32 v39, v122, v46
	v_dot8c_i32_i4_e32 v40, v124, v48
	v_dot8c_i32_i4_e32 v41, v124, v46
	v_dot8c_i32_i4_e32 v42, v126, v48
	v_dot8c_i32_i4_e32 v43, v126, v46
	v_dot8c_i32_i4_e32 v44, v128, v48
	v_dot8c_i32_i4_e32 v45, v128, v46
	v_dot8c_i32_i4_e32 v38, v123, v49
	v_dot8c_i32_i4_e32 v39, v123, v47
	v_dot8c_i32_i4_e32 v40, v125, v49
	v_dot8c_i32_i4_e32 v41, v125, v47
	v_dot8c_i32_i4_e32 v42, v127, v49
	v_dot8c_i32_i4_e32 v43, v127, v47
	v_dot8c_i32_i4_e32 v44, v129, v49
	v_dot8c_i32_i4_e32 v45, v129, v47
	v_and_b32_e32 v78, 0xffff, v32
	v_lshrrev_b32_e32 v79, 16, v32
	v_lshl_add_u32 v78, v78, 7, v150
	v_lshl_add_u32 v79, v79, 7, v151
	s_mov_b32 m0, s98
	s_add_i32 s43, s98, 0x400
	global_load_lds_dwordx4 v78, s[50:51]
	s_mov_b32 m0, s43
	s_nop 0
	global_load_lds_dwordx4 v79, s[50:51]
	s_waitcnt vmcnt(10)
; #define LAS __attribute__((address_space(3)))
; #define TR4(p_) __builtin_amdgcn_ds_read_tr4_b64_v2i32((LAS v2i*)(p_))
; __device__ __forceinline__ void peer_v_tokens(int j, const LAS unsigned short* EL, const LAS unsigned char* AL  , const LAS float* ASC  , const LAS int* SAL  , ...
;     ...
;         for (int m = 0; m < 2; ++m) {
;             const int idx = lane + 64 * m, tau = idx >> 4, sr = idx & 15, k = 16 * (sr & 7) + 2 * tau + (sr >> 3);
;             const int aq = (int)*(const LAS signed char*)(AL + tl * 128 + k); const int tq = aq + 8;
;             const unsigned lo = (((unsigned)tq & 15u) ^ 8u) * 0x11111111u, hi = ((unsigned)(tq >> 4) & 15u) * 0x11111111u;
;             typedef unsigned u2v __attribute__((ext_vector_type(2)));
;             u2v l2; l2.x = lo; l2.y = lo; u2v h2; h2.x = hi; h2.y = hi;
;             *(LAS u2v*)(ATL + 8 * idx) = l2; *(LAS u2v*)(ATL + 1024 + 8 * idx) = h2;
;         }
;     ...
;         for (int st = 0; st < 16; ++st) {
;             const int p = st >> 2, q = st & 3;
;             if (st < 14) VDMA(st + 2, (st + 2) % 3);
;             if (st < 14) asm volatile("s_waitcnt vmcnt(8)" ::: "memory");
;             else if (st == 14) asm volatile("s_waitcnt vmcnt(4)" ::: "memory");
;             else asm volatile("s_waitcnt vmcnt(0)" ::: "memory");
;             if (q == 0) {
; #pragma unroll
;                 for (int r = 0; r < 4; ++r) { accH[r] = 0; accL[r] = 0; } }
; #pragma unroll
;             for (int tp = 0; tp < 2; ++tp) {
;                 const v2i ao = TR4(ATL + (2 * q + tp) * 128 + 8 * s16), ah = TR4(ATL + 1024 + (2 * q + tp) * 128 + 8 * s16);
; #pragma unroll
;                 for (int r = 0; r < 4; ++r) {
;                     const v2i d = TR4(ldsb + BUF[st % 3] + 2048 * tp + roff[r]);
;                     accH[r] = __builtin_amdgcn_sdot8(d.x, ah.x, accH[r], false); accH[r] = __builtin_amdgcn_sdot8(d.y, ah.y, accH[r], false);
;                     accL[r] = __builtin_amdgcn_sdot8(d.x, ao.x, accL[r], false); accL[r] = __builtin_amdgcn_sdot8(d.y, ao.y, accL[r], false);
;                 }
;             }
	v_add_u32_e32 v54, s76, v59
	v_add_u32_e32 v55, s76, v60
	v_add_u32_e32 v56, s76, v61
	v_add_u32_e32 v57, s76, v62
	ds_read_b64_tr_b4 v[46:47], v160 offset:256
	ds_read_b64_tr_b4 v[48:49], v160 offset:1280
	ds_read_b64_tr_b4 v[122:123], v54
	ds_read_b64_tr_b4 v[124:125], v55
	ds_read_b64_tr_b4 v[126:127], v56
	ds_read_b64_tr_b4 v[128:129], v57
	s_waitcnt lgkmcnt(6)
	v_dot8c_i32_i4_e32 v38, v130, v52
	v_dot8c_i32_i4_e32 v39, v130, v50
	v_dot8c_i32_i4_e32 v40, v132, v52
	v_dot8c_i32_i4_e32 v41, v132, v50
	v_dot8c_i32_i4_e32 v42, v134, v52
	v_dot8c_i32_i4_e32 v43, v134, v50
	v_dot8c_i32_i4_e32 v44, v136, v52
	v_dot8c_i32_i4_e32 v45, v136, v50
	v_dot8c_i32_i4_e32 v38, v131, v53
	v_dot8c_i32_i4_e32 v39, v131, v51
	v_dot8c_i32_i4_e32 v40, v133, v53
	v_dot8c_i32_i4_e32 v41, v133, v51
	v_dot8c_i32_i4_e32 v42, v135, v53
	v_dot8c_i32_i4_e32 v43, v135, v51
	v_dot8c_i32_i4_e32 v44, v137, v53
	v_dot8c_i32_i4_e32 v45, v137, v51
	v_and_b32_e32 v78, 0xffff, v33
	v_lshrrev_b32_e32 v79, 16, v33
	v_lshl_add_u32 v78, v78, 7, v150
	v_lshl_add_u32 v79, v79, 7, v151
	s_mov_b32 m0, s99
	s_add_i32 s43, s99, 0x400
	global_load_lds_dwordx4 v78, s[50:51]
	s_mov_b32 m0, s43
	s_nop 0
	global_load_lds_dwordx4 v79, s[50:51]
	s_waitcnt vmcnt(10)
	v_add_u32_e32 v54, s77, v59
	v_add_u32_e32 v55, s77, v60
	v_add_u32_e32 v56, s77, v61
	v_add_u32_e32 v57, s77, v62
	ds_read_b64_tr_b4 v[50:51], v160 offset:384
	ds_read_b64_tr_b4 v[52:53], v160 offset:1408
	ds_read_b64_tr_b4 v[130:131], v54
	ds_read_b64_tr_b4 v[132:133], v55
	ds_read_b64_tr_b4 v[134:135], v56
	ds_read_b64_tr_b4 v[136:137], v57
	s_waitcnt lgkmcnt(6)
	v_dot8c_i32_i4_e32 v38, v122, v48
	v_dot8c_i32_i4_e32 v39, v122, v46
	v_dot8c_i32_i4_e32 v40, v124, v48
	v_dot8c_i32_i4_e32 v41, v124, v46
	v_dot8c_i32_i4_e32 v42, v126, v48
	v_dot8c_i32_i4_e32 v43, v126, v46
	v_dot8c_i32_i4_e32 v44, v128, v48
	v_dot8c_i32_i4_e32 v45, v128, v46
	v_dot8c_i32_i4_e32 v38, v123, v49
	v_dot8c_i32_i4_e32 v39, v123, v47
	v_dot8c_i32_i4_e32 v40, v125, v49
	v_dot8c_i32_i4_e32 v41, v125, v47
	v_dot8c_i32_i4_e32 v42, v127, v49
	v_dot8c_i32_i4_e32 v43, v127, v47
	v_dot8c_i32_i4_e32 v44, v129, v49
	v_dot8c_i32_i4_e32 v45, v129, v47
	s_waitcnt lgkmcnt(15)
	v_and_b32_e32 v78, 0xffff, v18
	v_lshrrev_b32_e32 v79, 16, v18
	v_lshl_add_u32 v78, v78, 7, v152
	v_lshl_add_u32 v79, v79, 7, v153
	s_mov_b32 m0, s76
	s_add_i32 s43, s76, 0x400
	global_load_lds_dwordx4 v78, s[50:51]
	s_mov_b32 m0, s43
	s_nop 0
	global_load_lds_dwordx4 v79, s[50:51]
	s_waitcnt vmcnt(10)
	v_add_u32_e32 v54, s78, v59
	v_add_u32_e32 v55, s78, v60
	v_add_u32_e32 v56, s78, v61
	v_add_u32_e32 v57, s78, v62
	ds_read_b64_tr_b4 v[46:47], v160 offset:512
	ds_read_b64_tr_b4 v[48:49], v160 offset:1536
	ds_read_b64_tr_b4 v[122:123], v54
	ds_read_b64_tr_b4 v[124:125], v55
	ds_read_b64_tr_b4 v[126:127], v56
	ds_read_b64_tr_b4 v[128:129], v57
	s_waitcnt lgkmcnt(6)
	v_dot8c_i32_i4_e32 v38, v130, v52
	v_dot8c_i32_i4_e32 v39, v130, v50
	v_dot8c_i32_i4_e32 v40, v132, v52
	v_dot8c_i32_i4_e32 v41, v132, v50
	v_dot8c_i32_i4_e32 v42, v134, v52
	v_dot8c_i32_i4_e32 v43, v134, v50
	v_dot8c_i32_i4_e32 v44, v136, v52
	v_dot8c_i32_i4_e32 v45, v136, v50
	v_dot8c_i32_i4_e32 v38, v131, v53
	v_dot8c_i32_i4_e32 v39, v131, v51
	v_dot8c_i32_i4_e32 v40, v133, v53
	v_dot8c_i32_i4_e32 v41, v133, v51
	v_dot8c_i32_i4_e32 v42, v135, v53
	v_dot8c_i32_i4_e32 v43, v135, v51
	v_dot8c_i32_i4_e32 v44, v137, v53
	v_dot8c_i32_i4_e32 v45, v137, v51
	v_and_b32_e32 v78, 0xffff, v19
	v_lshrrev_b32_e32 v79, 16, v19
	v_lshl_add_u32 v78, v78, 7, v152
	v_lshl_add_u32 v79, v79, 7, v153
	s_mov_b32 m0, s77
	s_add_i32 s43, s77, 0x400
	global_load_lds_dwordx4 v78, s[50:51]
	s_mov_b32 m0, s43
	s_nop 0
	global_load_lds_dwordx4 v79, s[50:51]
	s_waitcnt vmcnt(8)
	v_add_u32_e32 v54, s79, v59
	v_add_u32_e32 v55, s79, v60
	v_add_u32_e32 v56, s79, v61
	v_add_u32_e32 v57, s79, v62
	ds_read_b64_tr_b4 v[50:51], v160 offset:640
	ds_read_b64_tr_b4 v[52:53], v160 offset:1664
	ds_read_b64_tr_b4 v[130:131], v54
	ds_read_b64_tr_b4 v[132:133], v55
	ds_read_b64_tr_b4 v[134:135], v56
	ds_read_b64_tr_b4 v[136:137], v57
	s_waitcnt lgkmcnt(6)
	v_dot8c_i32_i4_e32 v38, v122, v48
	v_dot8c_i32_i4_e32 v39, v122, v46
	v_dot8c_i32_i4_e32 v40, v124, v48
	v_dot8c_i32_i4_e32 v41, v124, v46
	v_dot8c_i32_i4_e32 v42, v126, v48
	v_dot8c_i32_i4_e32 v43, v126, v46
	v_dot8c_i32_i4_e32 v44, v128, v48
	v_dot8c_i32_i4_e32 v45, v128, v46
	v_dot8c_i32_i4_e32 v38, v123, v49
	v_dot8c_i32_i4_e32 v39, v123, v47
	v_dot8c_i32_i4_e32 v40, v125, v49
	v_dot8c_i32_i4_e32 v41, v125, v47
	v_dot8c_i32_i4_e32 v42, v127, v49
	v_dot8c_i32_i4_e32 v43, v127, v47
	v_dot8c_i32_i4_e32 v44, v129, v49
	v_dot8c_i32_i4_e32 v45, v129, v47
	s_waitcnt lgkmcnt(15)
	v_add_u32_e32 v143, 8, v139
	v_and_b32_e32 v142, 15, v143
	v_xor_b32_e32 v142, 8, v142
	v_bfe_u32 v144, v143, 4, 4
	v_mul_lo_u32 v142, v142, s92
	v_mul_lo_u32 v144, v144, s92
	v_mov_b32_e32 v143, v142
	v_mov_b32_e32 v145, v144
	ds_write2st64_b64 v159, v[142:143], v[144:145] offset1:2
	v_and_b32_e32 v78, 0xffff, v20
	v_lshrrev_b32_e32 v79, 16, v20
	v_lshl_add_u32 v78, v78, 7, v152
	v_lshl_add_u32 v79, v79, 7, v153
	s_mov_b32 m0, s78
	s_add_i32 s43, s78, 0x400
	global_load_lds_dwordx4 v78, s[50:51]
	s_mov_b32 m0, s43
	s_nop 0
	global_load_lds_dwordx4 v79, s[50:51]
	s_waitcnt vmcnt(8)
	v_add_u32_e32 v54, s98, v59
	v_add_u32_e32 v55, s98, v60
	v_add_u32_e32 v56, s98, v61
	v_add_u32_e32 v57, s98, v62
	ds_read_b64_tr_b4 v[46:47], v160 offset:768
	ds_read_b64_tr_b4 v[48:49], v160 offset:1792
	ds_read_b64_tr_b4 v[122:123], v54
	ds_read_b64_tr_b4 v[124:125], v55
	ds_read_b64_tr_b4 v[126:127], v56
	ds_read_b64_tr_b4 v[128:129], v57
	s_waitcnt lgkmcnt(7)
; __device__ __forceinline__ bf16 f2bf(float f) { return (bf16)f2bfu(f); }
; #define TR4(p_) __builtin_amdgcn_ds_read_tr4_b64_v2i32((LAS v2i*)(p_))
; __device__ __forceinline__ void peer_v_tokens(int j, const LAS unsigned short* EL, const LAS unsigned char* AL  , const LAS float* ASC  , const LAS int* SAL  , ...
;     ...
;         for (int st = 0; st < 16; ++st) {
;             const int p = st >> 2, q = st & 3;
;             if (st < 14) VDMA(st + 2, (st + 2) % 3);
;             if (st < 14) asm volatile("s_waitcnt vmcnt(8)" ::: "memory");
;             else if (st == 14) asm volatile("s_waitcnt vmcnt(4)" ::: "memory");
;             else asm volatile("s_waitcnt vmcnt(0)" ::: "memory");
;             if (q == 0) {
; #pragma unroll
;                 for (int r = 0; r < 4; ++r) { accH[r] = 0; accL[r] = 0; } }
; #pragma unroll
;             for (int tp = 0; tp < 2; ++tp) {
;                 const v2i ao = TR4(ATL + (2 * q + tp) * 128 + 8 * s16), ah = TR4(ATL + 1024 + (2 * q + tp) * 128 + 8 * s16);
; #pragma unroll
;                 for (int r = 0; r < 4; ++r) {
;                     const v2i d = TR4(ldsb + BUF[st % 3] + 2048 * tp + roff[r]);
;                     accH[r] = __builtin_amdgcn_sdot8(d.x, ah.x, accH[r], false); accH[r] = __builtin_amdgcn_sdot8(d.y, ah.y, accH[r], false);
;                     accL[r] = __builtin_amdgcn_sdot8(d.x, ao.x, accL[r], false); accL[r] = __builtin_amdgcn_sdot8(d.y, ao.y, accL[r], false);
;                 }
;             }
;             asm volatile("s_waitcnt lgkmcnt(0)" ::: "memory");
;             if (q == 3) {
; #pragma unroll
;                 for (int r = 0; r < 4; ++r) STASH[256 * p + 16 * (grp + 4 * r) + pc] = f2bf(asc * (float)(2 * ((accH[r] << 4) + accL[r]) + sa));
;             }
;         }
;     ...
;             float4* op = (float4*)(outp + (size_t)t * D) + lane;
; #pragma unroll
;             for (int jq = 0; jq < 4; ++jq) { typedef float f4v __attribute__((ext_vector_type(4))); f4v o4; o4.x = v[jq].x * r3 * gv[jq].x; o4.y = v[jq].y * r3 * gv[jq].y; o4.z = v[jq].z * r3 * gv[jq].z; o4.w = v[jq].w * r3 * gv[jq].w;
;                 __builtin_nontemporal_store(o4, (f4v*)op + 64 * jq); }
	v_dot8c_i32_i4_e32 v38, v130, v52
	v_dot8c_i32_i4_e32 v39, v130, v50
	v_dot8c_i32_i4_e32 v40, v132, v52
	v_dot8c_i32_i4_e32 v41, v132, v50
	v_dot8c_i32_i4_e32 v42, v134, v52
	v_dot8c_i32_i4_e32 v43, v134, v50
	v_dot8c_i32_i4_e32 v44, v136, v52
	v_dot8c_i32_i4_e32 v45, v136, v50
	v_dot8c_i32_i4_e32 v38, v131, v53
	v_dot8c_i32_i4_e32 v39, v131, v51
	v_dot8c_i32_i4_e32 v40, v133, v53
	v_dot8c_i32_i4_e32 v41, v133, v51
	v_dot8c_i32_i4_e32 v42, v135, v53
	v_dot8c_i32_i4_e32 v43, v135, v51
	v_dot8c_i32_i4_e32 v44, v137, v53
	v_dot8c_i32_i4_e32 v45, v137, v51
	v_and_b32_e32 v78, 0xffff, v21
	v_lshrrev_b32_e32 v79, 16, v21
	v_lshl_add_u32 v78, v78, 7, v152
	v_lshl_add_u32 v79, v79, 7, v153
	s_mov_b32 m0, s79
	s_add_i32 s43, s79, 0x400
	global_load_lds_dwordx4 v78, s[50:51]
	s_mov_b32 m0, s43
	s_nop 0
	global_load_lds_dwordx4 v79, s[50:51]
	s_waitcnt vmcnt(8)
	v_add_u32_e32 v54, s99, v59
	v_add_u32_e32 v55, s99, v60
	v_add_u32_e32 v56, s99, v61
	v_add_u32_e32 v57, s99, v62
	ds_read_b64_tr_b4 v[50:51], v160 offset:896
	ds_read_b64_tr_b4 v[52:53], v160 offset:1920
	ds_read_b64_tr_b4 v[130:131], v54
	ds_read_b64_tr_b4 v[132:133], v55
	ds_read_b64_tr_b4 v[134:135], v56
	ds_read_b64_tr_b4 v[136:137], v57
	s_waitcnt lgkmcnt(6)
	v_dot8c_i32_i4_e32 v38, v122, v48
	v_dot8c_i32_i4_e32 v39, v122, v46
	v_dot8c_i32_i4_e32 v40, v124, v48
	v_dot8c_i32_i4_e32 v41, v124, v46
	v_dot8c_i32_i4_e32 v42, v126, v48
	v_dot8c_i32_i4_e32 v43, v126, v46
	v_dot8c_i32_i4_e32 v44, v128, v48
	v_dot8c_i32_i4_e32 v45, v128, v46
	v_dot8c_i32_i4_e32 v38, v123, v49
	v_dot8c_i32_i4_e32 v39, v123, v47
	v_dot8c_i32_i4_e32 v40, v125, v49
	v_dot8c_i32_i4_e32 v41, v125, v47
	v_dot8c_i32_i4_e32 v42, v127, v49
	v_dot8c_i32_i4_e32 v43, v127, v47
	v_dot8c_i32_i4_e32 v44, v129, v49
	v_dot8c_i32_i4_e32 v45, v129, v47
	v_and_b32_e32 v78, 0xffff, v22
	v_lshrrev_b32_e32 v79, 16, v22
	v_lshl_add_u32 v78, v78, 7, v152
	v_lshl_add_u32 v79, v79, 7, v153
	s_mov_b32 m0, s98
	s_add_i32 s43, s98, 0x400
	global_load_lds_dwordx4 v78, s[50:51]
	s_mov_b32 m0, s43
	s_nop 0
	global_load_lds_dwordx4 v79, s[50:51]
	s_waitcnt vmcnt(8)
	v_add_u32_e32 v54, s76, v59
	v_add_u32_e32 v55, s76, v60
	v_add_u32_e32 v56, s76, v61
	v_add_u32_e32 v57, s76, v62
	ds_read_b64_tr_b4 v[46:47], v160
	ds_read_b64_tr_b4 v[48:49], v160 offset:1024
	ds_read_b64_tr_b4 v[122:123], v54
	ds_read_b64_tr_b4 v[124:125], v55
	ds_read_b64_tr_b4 v[126:127], v56
	ds_read_b64_tr_b4 v[128:129], v57
	s_waitcnt lgkmcnt(6)
	v_dot8c_i32_i4_e32 v38, v130, v52
	v_dot8c_i32_i4_e32 v39, v130, v50
	v_dot8c_i32_i4_e32 v40, v132, v52
	v_dot8c_i32_i4_e32 v41, v132, v50
	v_dot8c_i32_i4_e32 v42, v134, v52
	v_dot8c_i32_i4_e32 v43, v134, v50
	v_dot8c_i32_i4_e32 v44, v136, v52
	v_dot8c_i32_i4_e32 v45, v136, v50
	v_dot8c_i32_i4_e32 v38, v131, v53
	v_dot8c_i32_i4_e32 v39, v131, v51
	v_dot8c_i32_i4_e32 v40, v133, v53
	v_dot8c_i32_i4_e32 v41, v133, v51
	v_dot8c_i32_i4_e32 v42, v135, v53
	v_dot8c_i32_i4_e32 v43, v135, v51
	v_dot8c_i32_i4_e32 v44, v137, v53
	v_dot8c_i32_i4_e32 v45, v137, v51
	s_nop 3
	s_waitcnt lgkmcnt(15)
	v_lshlrev_b32_e32 v38, 5, v38
	v_lshlrev_b32_e32 v39, 1, v39
	v_add3_u32 v38, v39, v229, v38
	v_cvt_f32_i32_e32 v38, v38
	v_mul_f32_e32 v38, v228, v38
	v_lshlrev_b32_e32 v40, 5, v40
	v_lshlrev_b32_e32 v41, 1, v41
	v_add3_u32 v40, v41, v229, v40
	v_cvt_f32_i32_e32 v40, v40
	v_mul_f32_e32 v40, v228, v40
	v_lshlrev_b32_e32 v42, 5, v42
	v_lshlrev_b32_e32 v43, 1, v43
	v_add3_u32 v42, v43, v229, v42
	v_cvt_f32_i32_e32 v42, v42
	v_mul_f32_e32 v42, v228, v42
	v_lshlrev_b32_e32 v44, 5, v44
	v_lshlrev_b32_e32 v45, 1, v45
	v_add3_u32 v44, v45, v229, v44
	v_cvt_f32_i32_e32 v44, v44
	v_mul_f32_e32 v44, v228, v44
	v_cvt_pk_bf16_f32 v190, v38, v40
	v_cvt_pk_bf16_f32 v191, v42, v44
	ds_read_b128 v[252:255], v155 offset:1024
	s_add_i32 s44, s40, 40
	s_ashr_i32 s45, s44, 31
	s_lshl_b64 s[44:45], s[44:45], 12
	v_lshl_add_u64 v[80:81], v[36:37], 0, s[44:45]
	s_waitcnt lgkmcnt(0)
	v_mul_f32_e32 v240, v240, v252
	v_mul_f32_e32 v241, v241, v253
	v_mul_f32_e32 v242, v242, v254
	v_mul_f32_e32 v243, v243, v255
	global_store_dwordx4 v[80:81], v[240:243], off offset:1024 sc1
	v_add_u32_e32 v147, 8, v140
	v_and_b32_e32 v146, 15, v147
	v_xor_b32_e32 v146, 8, v146
	v_bfe_u32 v148, v147, 4, 4
	v_mul_lo_u32 v146, v146, s92
	v_mul_lo_u32 v148, v148, s92
	v_mov_b32_e32 v147, v146
	v_mov_b32_e32 v149, v148
	ds_write2st64_b64 v77, v[146:147], v[148:149] offset1:2
	v_add_u32_e32 v138, 0x1c00, v74
	ds_read_u8 v139, v138
	v_add_u32_e32 v141, 0x1c00, v73
	ds_read_u8 v140, v141
	s_add_i32 s43, s67, 192
	v_mov_b32_e32 v138, s43
	ds_read2st64_b32 v[228:229], v138 offset1:1
	ds_read_b128 v[26:29], v227 offset:14336
	ds_read_b128 v[30:33], v227 offset:14352
	v_mov_b32_e32 v38, 0
	v_mov_b32_e32 v39, 0
	v_mov_b32_e32 v40, 0
	v_mov_b32_e32 v41, 0
	v_mov_b32_e32 v42, 0
	v_mov_b32_e32 v43, 0
	v_mov_b32_e32 v44, 0
	v_mov_b32_e32 v45, 0
	v_and_b32_e32 v78, 0xffff, v23
	v_lshrrev_b32_e32 v79, 16, v23
	v_lshl_add_u32 v78, v78, 7, v152
	v_lshl_add_u32 v79, v79, 7, v153
	s_mov_b32 m0, s99
	s_add_i32 s43, s99, 0x400
	global_load_lds_dwordx4 v78, s[50:51]
	s_mov_b32 m0, s43
	s_nop 0
	global_load_lds_dwordx4 v79, s[50:51]
	s_waitcnt vmcnt(9)
	v_add_u32_e32 v54, s77, v59
	v_add_u32_e32 v55, s77, v60
	v_add_u32_e32 v56, s77, v61
	v_add_u32_e32 v57, s77, v62
	ds_read_b64_tr_b4 v[50:51], v160 offset:128
	ds_read_b64_tr_b4 v[52:53], v160 offset:1152
	ds_read_b64_tr_b4 v[130:131], v54
	ds_read_b64_tr_b4 v[132:133], v55
	ds_read_b64_tr_b4 v[134:135], v56
	ds_read_b64_tr_b4 v[136:137], v57
	s_waitcnt lgkmcnt(13)
; #define TR4(p_) __builtin_amdgcn_ds_read_tr4_b64_v2i32((LAS v2i*)(p_))
; #define VDMA(st_, k_) do { _Pragma("unroll") for (int i_ = 0; i_ < 4; ++i_) { \
;         const unsigned off_ = (unsigned)((st_) >> 2) * (16384u * 128u) + (PE_ID(E, 4 * ((st_) & 3) + i_) << 7) + ((i_ & 1) ? cx1 : cx0); \
;         __builtin_amdgcn_global_load_lds((const unsigned*)(V4 + off_), (LAS unsigned*)(ldsb + BUF[k_] + 1024 * i_), 16, 0, 0); } } while (0)
; __device__ __forceinline__ void peer_v_tokens(int j, const LAS unsigned short* EL, const LAS unsigned char* AL  , const LAS float* ASC  , const LAS int* SAL  , ...
;     ...
;         for (int st = 0; st < 16; ++st) {
;             const int p = st >> 2, q = st & 3;
;             if (st < 14) VDMA(st + 2, (st + 2) % 3);
;             if (st < 14) asm volatile("s_waitcnt vmcnt(8)" ::: "memory");
;             else if (st == 14) asm volatile("s_waitcnt vmcnt(4)" ::: "memory");
;             else asm volatile("s_waitcnt vmcnt(0)" ::: "memory");
;             if (q == 0) {
; #pragma unroll
;                 for (int r = 0; r < 4; ++r) { accH[r] = 0; accL[r] = 0; } }
; #pragma unroll
;             for (int tp = 0; tp < 2; ++tp) {
;                 const v2i ao = TR4(ATL + (2 * q + tp) * 128 + 8 * s16), ah = TR4(ATL + 1024 + (2 * q + tp) * 128 + 8 * s16);
; #pragma unroll
;                 for (int r = 0; r < 4; ++r) {
;                     const v2i d = TR4(ldsb + BUF[st % 3] + 2048 * tp + roff[r]);
;                     accH[r] = __builtin_amdgcn_sdot8(d.x, ah.x, accH[r], false); accH[r] = __builtin_amdgcn_sdot8(d.y, ah.y, accH[r], false);
;                     accL[r] = __builtin_amdgcn_sdot8(d.x, ao.x, accL[r], false); accL[r] = __builtin_amdgcn_sdot8(d.y, ao.y, accL[r], false);
;                 }
;             }
	v_dot8c_i32_i4_e32 v38, v122, v48
	v_dot8c_i32_i4_e32 v39, v122, v46
	v_dot8c_i32_i4_e32 v40, v124, v48
	v_dot8c_i32_i4_e32 v41, v124, v46
	v_dot8c_i32_i4_e32 v42, v126, v48
	v_dot8c_i32_i4_e32 v43, v126, v46
	v_dot8c_i32_i4_e32 v44, v128, v48
	v_dot8c_i32_i4_e32 v45, v128, v46
	v_dot8c_i32_i4_e32 v38, v123, v49
	v_dot8c_i32_i4_e32 v39, v123, v47
	v_dot8c_i32_i4_e32 v40, v125, v49
	v_dot8c_i32_i4_e32 v41, v125, v47
	v_dot8c_i32_i4_e32 v42, v127, v49
	v_dot8c_i32_i4_e32 v43, v127, v47
	v_dot8c_i32_i4_e32 v44, v129, v49
	v_dot8c_i32_i4_e32 v45, v129, v47
	v_and_b32_e32 v78, 0xffff, v24
	v_lshrrev_b32_e32 v79, 16, v24
	v_lshl_add_u32 v78, v78, 7, v152
	v_lshl_add_u32 v79, v79, 7, v153
	s_mov_b32 m0, s76
	s_add_i32 s43, s76, 0x400
	global_load_lds_dwordx4 v78, s[50:51]
	s_mov_b32 m0, s43
	s_nop 0
	global_load_lds_dwordx4 v79, s[50:51]
	s_waitcnt vmcnt(9)
	v_add_u32_e32 v54, s78, v59
	v_add_u32_e32 v55, s78, v60
	v_add_u32_e32 v56, s78, v61
	v_add_u32_e32 v57, s78, v62
	ds_read_b64_tr_b4 v[46:47], v160 offset:256
	ds_read_b64_tr_b4 v[48:49], v160 offset:1280
	ds_read_b64_tr_b4 v[122:123], v54
	ds_read_b64_tr_b4 v[124:125], v55
	ds_read_b64_tr_b4 v[126:127], v56
	ds_read_b64_tr_b4 v[128:129], v57
	s_waitcnt lgkmcnt(6)
	v_dot8c_i32_i4_e32 v38, v130, v52
	v_dot8c_i32_i4_e32 v39, v130, v50
	v_dot8c_i32_i4_e32 v40, v132, v52
	v_dot8c_i32_i4_e32 v41, v132, v50
	v_dot8c_i32_i4_e32 v42, v134, v52
	v_dot8c_i32_i4_e32 v43, v134, v50
	v_dot8c_i32_i4_e32 v44, v136, v52
	v_dot8c_i32_i4_e32 v45, v136, v50
	v_dot8c_i32_i4_e32 v38, v131, v53
	v_dot8c_i32_i4_e32 v39, v131, v51
	v_dot8c_i32_i4_e32 v40, v133, v53
	v_dot8c_i32_i4_e32 v41, v133, v51
	v_dot8c_i32_i4_e32 v42, v135, v53
	v_dot8c_i32_i4_e32 v43, v135, v51
	v_dot8c_i32_i4_e32 v44, v137, v53
	v_dot8c_i32_i4_e32 v45, v137, v51
	v_and_b32_e32 v78, 0xffff, v25
	v_lshrrev_b32_e32 v79, 16, v25
	v_lshl_add_u32 v78, v78, 7, v152
	v_lshl_add_u32 v79, v79, 7, v153
	s_mov_b32 m0, s77
	s_add_i32 s43, s77, 0x400
	global_load_lds_dwordx4 v78, s[50:51]
	s_mov_b32 m0, s43
	s_nop 0
	global_load_lds_dwordx4 v79, s[50:51]
	s_waitcnt vmcnt(9)
	v_add_u32_e32 v54, s79, v59
	v_add_u32_e32 v55, s79, v60
	v_add_u32_e32 v56, s79, v61
	v_add_u32_e32 v57, s79, v62
	ds_read_b64_tr_b4 v[50:51], v160 offset:384
	ds_read_b64_tr_b4 v[52:53], v160 offset:1408
	ds_read_b64_tr_b4 v[130:131], v54
	ds_read_b64_tr_b4 v[132:133], v55
	ds_read_b64_tr_b4 v[134:135], v56
	ds_read_b64_tr_b4 v[136:137], v57
	s_waitcnt lgkmcnt(6)
	v_dot8c_i32_i4_e32 v38, v122, v48
	v_dot8c_i32_i4_e32 v39, v122, v46
	v_dot8c_i32_i4_e32 v40, v124, v48
	v_dot8c_i32_i4_e32 v41, v124, v46
	v_dot8c_i32_i4_e32 v42, v126, v48
	v_dot8c_i32_i4_e32 v43, v126, v46
	v_dot8c_i32_i4_e32 v44, v128, v48
	v_dot8c_i32_i4_e32 v45, v128, v46
	v_dot8c_i32_i4_e32 v38, v123, v49
	v_dot8c_i32_i4_e32 v39, v123, v47
	v_dot8c_i32_i4_e32 v40, v125, v49
	v_dot8c_i32_i4_e32 v41, v125, v47
	v_dot8c_i32_i4_e32 v42, v127, v49
	v_dot8c_i32_i4_e32 v43, v127, v47
	v_dot8c_i32_i4_e32 v44, v129, v49
	v_dot8c_i32_i4_e32 v45, v129, v47
	s_waitcnt lgkmcnt(15)
	v_and_b32_e32 v78, 0xffff, v26
	v_lshrrev_b32_e32 v79, 16, v26
	v_lshl_add_u32 v78, v78, 7, v152
	v_lshl_add_u32 v79, v79, 7, v153
	s_mov_b32 m0, s78
	s_add_i32 s43, s78, 0x400
	global_load_lds_dwordx4 v78, s[50:51]
	s_mov_b32 m0, s43
	s_nop 0
	global_load_lds_dwordx4 v79, s[50:51]
	s_waitcnt vmcnt(9)
	v_add_u32_e32 v54, s98, v59
	v_add_u32_e32 v55, s98, v60
	v_add_u32_e32 v56, s98, v61
	v_add_u32_e32 v57, s98, v62
	ds_read_b64_tr_b4 v[46:47], v160 offset:512
	ds_read_b64_tr_b4 v[48:49], v160 offset:1536
	ds_read_b64_tr_b4 v[122:123], v54
	ds_read_b64_tr_b4 v[124:125], v55
	ds_read_b64_tr_b4 v[126:127], v56
	ds_read_b64_tr_b4 v[128:129], v57
	s_waitcnt lgkmcnt(6)
	v_dot8c_i32_i4_e32 v38, v130, v52
	v_dot8c_i32_i4_e32 v39, v130, v50
	v_dot8c_i32_i4_e32 v40, v132, v52
	v_dot8c_i32_i4_e32 v41, v132, v50
	v_dot8c_i32_i4_e32 v42, v134, v52
	v_dot8c_i32_i4_e32 v43, v134, v50
	v_dot8c_i32_i4_e32 v44, v136, v52
	v_dot8c_i32_i4_e32 v45, v136, v50
	v_dot8c_i32_i4_e32 v38, v131, v53
	v_dot8c_i32_i4_e32 v39, v131, v51
	v_dot8c_i32_i4_e32 v40, v133, v53
	v_dot8c_i32_i4_e32 v41, v133, v51
	v_dot8c_i32_i4_e32 v42, v135, v53
	v_dot8c_i32_i4_e32 v43, v135, v51
	v_dot8c_i32_i4_e32 v44, v137, v53
	v_dot8c_i32_i4_e32 v45, v137, v51
	v_and_b32_e32 v78, 0xffff, v27
	v_lshrrev_b32_e32 v79, 16, v27
	v_lshl_add_u32 v78, v78, 7, v152
	v_lshl_add_u32 v79, v79, 7, v153
	s_mov_b32 m0, s79
	s_add_i32 s43, s79, 0x400
	global_load_lds_dwordx4 v78, s[50:51]
	s_mov_b32 m0, s43
	s_nop 0
	global_load_lds_dwordx4 v79, s[50:51]
	s_waitcnt vmcnt(8)
	v_add_u32_e32 v54, s99, v59
	v_add_u32_e32 v55, s99, v60
	v_add_u32_e32 v56, s99, v61
	v_add_u32_e32 v57, s99, v62
	ds_read_b64_tr_b4 v[50:51], v160 offset:640
	ds_read_b64_tr_b4 v[52:53], v160 offset:1664
	ds_read_b64_tr_b4 v[130:131], v54
	ds_read_b64_tr_b4 v[132:133], v55
	ds_read_b64_tr_b4 v[134:135], v56
	ds_read_b64_tr_b4 v[136:137], v57
	s_waitcnt lgkmcnt(6)
	v_dot8c_i32_i4_e32 v38, v122, v48
	v_dot8c_i32_i4_e32 v39, v122, v46
	v_dot8c_i32_i4_e32 v40, v124, v48
	v_dot8c_i32_i4_e32 v41, v124, v46
	v_dot8c_i32_i4_e32 v42, v126, v48
	v_dot8c_i32_i4_e32 v43, v126, v46
	v_dot8c_i32_i4_e32 v44, v128, v48
	v_dot8c_i32_i4_e32 v45, v128, v46
	v_dot8c_i32_i4_e32 v38, v123, v49
	v_dot8c_i32_i4_e32 v39, v123, v47
	v_dot8c_i32_i4_e32 v40, v125, v49
	v_dot8c_i32_i4_e32 v41, v125, v47
	v_dot8c_i32_i4_e32 v42, v127, v49
	v_dot8c_i32_i4_e32 v43, v127, v47
	v_dot8c_i32_i4_e32 v44, v129, v49
	v_dot8c_i32_i4_e32 v45, v129, v47
	s_waitcnt lgkmcnt(15)
; #define LAS __attribute__((address_space(3)))
; __device__ __forceinline__ bf16 f2bf(float f) { return (bf16)f2bfu(f); }
; __device__ __forceinline__ void peer_v_tokens(int j, const LAS unsigned short* EL, const LAS unsigned char* AL  , const LAS float* ASC  , const LAS int* SAL  , ...
;     ...
;         for (int m = 0; m < 2; ++m) {
;             const int idx = lane + 64 * m, tau = idx >> 4, sr = idx & 15, k = 16 * (sr & 7) + 2 * tau + (sr >> 3);
;             const int aq = (int)*(const LAS signed char*)(AL + tl * 128 + k); const int tq = aq + 8;
;             const unsigned lo = (((unsigned)tq & 15u) ^ 8u) * 0x11111111u, hi = ((unsigned)(tq >> 4) & 15u) * 0x11111111u;
;             typedef unsigned u2v __attribute__((ext_vector_type(2)));
;             u2v l2; l2.x = lo; l2.y = lo; u2v h2; h2.x = hi; h2.y = hi;
;             *(LAS u2v*)(ATL + 8 * idx) = l2; *(LAS u2v*)(ATL + 1024 + 8 * idx) = h2;
;         }
;     ...
;         for (int st = 0; st < 16; ++st) {
;             const int p = st >> 2, q = st & 3;
;             if (st < 14) VDMA(st + 2, (st + 2) % 3);
;             if (st < 14) asm volatile("s_waitcnt vmcnt(8)" ::: "memory");
;             else if (st == 14) asm volatile("s_waitcnt vmcnt(4)" ::: "memory");
;             else asm volatile("s_waitcnt vmcnt(0)" ::: "memory");
;             if (q == 0) {
; #pragma unroll
;                 for (int r = 0; r < 4; ++r) { accH[r] = 0; accL[r] = 0; } }
; #pragma unroll
;             for (int tp = 0; tp < 2; ++tp) {
;                 const v2i ao = TR4(ATL + (2 * q + tp) * 128 + 8 * s16), ah = TR4(ATL + 1024 + (2 * q + tp) * 128 + 8 * s16);
; #pragma unroll
;                 for (int r = 0; r < 4; ++r) {
;                     const v2i d = TR4(ldsb + BUF[st % 3] + 2048 * tp + roff[r]);
;                     accH[r] = __builtin_amdgcn_sdot8(d.x, ah.x, accH[r], false); accH[r] = __builtin_amdgcn_sdot8(d.y, ah.y, accH[r], false);
;                     accL[r] = __builtin_amdgcn_sdot8(d.x, ao.x, accL[r], false); accL[r] = __builtin_amdgcn_sdot8(d.y, ao.y, accL[r], false);
;                 }
;             }
;             asm volatile("s_waitcnt lgkmcnt(0)" ::: "memory");
;             if (q == 3) {
; #pragma unroll
;                 for (int r = 0; r < 4; ++r) STASH[256 * p + 16 * (grp + 4 * r) + pc] = f2bf(asc * (float)(2 * ((accH[r] << 4) + accL[r]) + sa));
;             }
;         }
	v_add_u32_e32 v143, 8, v139
	v_and_b32_e32 v142, 15, v143
	v_xor_b32_e32 v142, 8, v142
	v_bfe_u32 v144, v143, 4, 4
	v_mul_lo_u32 v142, v142, s92
	v_mul_lo_u32 v144, v144, s92
	v_mov_b32_e32 v143, v142
	v_mov_b32_e32 v145, v144
	ds_write2st64_b64 v159, v[142:143], v[144:145] offset1:2
	v_and_b32_e32 v78, 0xffff, v28
	v_lshrrev_b32_e32 v79, 16, v28
	v_lshl_add_u32 v78, v78, 7, v152
	v_lshl_add_u32 v79, v79, 7, v153
	s_mov_b32 m0, s98
	s_add_i32 s43, s98, 0x400
	global_load_lds_dwordx4 v78, s[50:51]
	s_mov_b32 m0, s43
	s_nop 0
	global_load_lds_dwordx4 v79, s[50:51]
	s_waitcnt vmcnt(8)
	v_add_u32_e32 v54, s76, v59
	v_add_u32_e32 v55, s76, v60
	v_add_u32_e32 v56, s76, v61
	v_add_u32_e32 v57, s76, v62
	ds_read_b64_tr_b4 v[46:47], v160 offset:768
	ds_read_b64_tr_b4 v[48:49], v160 offset:1792
	ds_read_b64_tr_b4 v[122:123], v54
	ds_read_b64_tr_b4 v[124:125], v55
	ds_read_b64_tr_b4 v[126:127], v56
	ds_read_b64_tr_b4 v[128:129], v57
	s_waitcnt lgkmcnt(7)
	v_dot8c_i32_i4_e32 v38, v130, v52
	v_dot8c_i32_i4_e32 v39, v130, v50
	v_dot8c_i32_i4_e32 v40, v132, v52
	v_dot8c_i32_i4_e32 v41, v132, v50
	v_dot8c_i32_i4_e32 v42, v134, v52
	v_dot8c_i32_i4_e32 v43, v134, v50
	v_dot8c_i32_i4_e32 v44, v136, v52
	v_dot8c_i32_i4_e32 v45, v136, v50
	v_dot8c_i32_i4_e32 v38, v131, v53
	v_dot8c_i32_i4_e32 v39, v131, v51
	v_dot8c_i32_i4_e32 v40, v133, v53
	v_dot8c_i32_i4_e32 v41, v133, v51
	v_dot8c_i32_i4_e32 v42, v135, v53
	v_dot8c_i32_i4_e32 v43, v135, v51
	v_dot8c_i32_i4_e32 v44, v137, v53
	v_dot8c_i32_i4_e32 v45, v137, v51
	v_and_b32_e32 v78, 0xffff, v29
	v_lshrrev_b32_e32 v79, 16, v29
	v_lshl_add_u32 v78, v78, 7, v152
	v_lshl_add_u32 v79, v79, 7, v153
	s_mov_b32 m0, s99
	s_add_i32 s43, s99, 0x400
	global_load_lds_dwordx4 v78, s[50:51]
	s_mov_b32 m0, s43
	s_nop 0
	global_load_lds_dwordx4 v79, s[50:51]
	s_waitcnt vmcnt(8)
	v_add_u32_e32 v54, s77, v59
	v_add_u32_e32 v55, s77, v60
	v_add_u32_e32 v56, s77, v61
	v_add_u32_e32 v57, s77, v62
	ds_read_b64_tr_b4 v[50:51], v160 offset:896
	ds_read_b64_tr_b4 v[52:53], v160 offset:1920
	ds_read_b64_tr_b4 v[130:131], v54
	ds_read_b64_tr_b4 v[132:133], v55
	ds_read_b64_tr_b4 v[134:135], v56
	ds_read_b64_tr_b4 v[136:137], v57
	s_waitcnt lgkmcnt(6)
	v_dot8c_i32_i4_e32 v38, v122, v48
	v_dot8c_i32_i4_e32 v39, v122, v46
	v_dot8c_i32_i4_e32 v40, v124, v48
	v_dot8c_i32_i4_e32 v41, v124, v46
	v_dot8c_i32_i4_e32 v42, v126, v48
	v_dot8c_i32_i4_e32 v43, v126, v46
	v_dot8c_i32_i4_e32 v44, v128, v48
	v_dot8c_i32_i4_e32 v45, v128, v46
	v_dot8c_i32_i4_e32 v38, v123, v49
	v_dot8c_i32_i4_e32 v39, v123, v47
	v_dot8c_i32_i4_e32 v40, v125, v49
	v_dot8c_i32_i4_e32 v41, v125, v47
	v_dot8c_i32_i4_e32 v42, v127, v49
	v_dot8c_i32_i4_e32 v43, v127, v47
	v_dot8c_i32_i4_e32 v44, v129, v49
	v_dot8c_i32_i4_e32 v45, v129, v47
	v_and_b32_e32 v78, 0xffff, v30
	v_lshrrev_b32_e32 v79, 16, v30
	v_lshl_add_u32 v78, v78, 7, v152
	v_lshl_add_u32 v79, v79, 7, v153
	s_mov_b32 m0, s76
	s_add_i32 s43, s76, 0x400
	global_load_lds_dwordx4 v78, s[50:51]
	s_mov_b32 m0, s43
	s_nop 0
	global_load_lds_dwordx4 v79, s[50:51]
	s_waitcnt vmcnt(8)
	v_add_u32_e32 v54, s78, v59
	v_add_u32_e32 v55, s78, v60
	v_add_u32_e32 v56, s78, v61
	v_add_u32_e32 v57, s78, v62
	ds_read_b64_tr_b4 v[46:47], v160
	ds_read_b64_tr_b4 v[48:49], v160 offset:1024
	ds_read_b64_tr_b4 v[122:123], v54
	ds_read_b64_tr_b4 v[124:125], v55
	ds_read_b64_tr_b4 v[126:127], v56
	ds_read_b64_tr_b4 v[128:129], v57
	s_waitcnt lgkmcnt(6)
	v_dot8c_i32_i4_e32 v38, v130, v52
	v_dot8c_i32_i4_e32 v39, v130, v50
	v_dot8c_i32_i4_e32 v40, v132, v52
	v_dot8c_i32_i4_e32 v41, v132, v50
	v_dot8c_i32_i4_e32 v42, v134, v52
	v_dot8c_i32_i4_e32 v43, v134, v50
	v_dot8c_i32_i4_e32 v44, v136, v52
	v_dot8c_i32_i4_e32 v45, v136, v50
	v_dot8c_i32_i4_e32 v38, v131, v53
	v_dot8c_i32_i4_e32 v39, v131, v51
	v_dot8c_i32_i4_e32 v40, v133, v53
	v_dot8c_i32_i4_e32 v41, v133, v51
	v_dot8c_i32_i4_e32 v42, v135, v53
	v_dot8c_i32_i4_e32 v43, v135, v51
	v_dot8c_i32_i4_e32 v44, v137, v53
	v_dot8c_i32_i4_e32 v45, v137, v51
	s_nop 3
	s_waitcnt lgkmcnt(15)
	v_lshlrev_b32_e32 v38, 5, v38
	v_lshlrev_b32_e32 v39, 1, v39
	v_add3_u32 v38, v39, v229, v38
	v_cvt_f32_i32_e32 v38, v38
	v_mul_f32_e32 v38, v228, v38
	v_lshlrev_b32_e32 v40, 5, v40
	v_lshlrev_b32_e32 v41, 1, v41
	v_add3_u32 v40, v41, v229, v40
	v_cvt_f32_i32_e32 v40, v40
	v_mul_f32_e32 v40, v228, v40
	v_lshlrev_b32_e32 v42, 5, v42
	v_lshlrev_b32_e32 v43, 1, v43
	v_add3_u32 v42, v43, v229, v42
	v_cvt_f32_i32_e32 v42, v42
	v_mul_f32_e32 v42, v228, v42
	v_lshlrev_b32_e32 v44, 5, v44
	v_lshlrev_b32_e32 v45, 1, v45
	v_add3_u32 v44, v45, v229, v44
	v_cvt_f32_i32_e32 v44, v44
	v_mul_f32_e32 v44, v228, v44
	v_cvt_pk_bf16_f32 v184, v38, v40
	v_cvt_pk_bf16_f32 v185, v42, v44
	ds_read_b128 v[252:255], v156
	s_add_i32 s44, s40, 40
	s_ashr_i32 s45, s44, 31
	s_lshl_b64 s[44:45], s[44:45], 12
	v_lshl_add_u64 v[80:81], v[36:37], 0, s[44:45]
	s_waitcnt lgkmcnt(0)
; __device__ __forceinline__ void peer_v_tokens(int j, const LAS unsigned short* EL, const LAS unsigned char* AL  , const LAS float* ASC  , const LAS int* SAL  , ...
;     ...
;         const int tl = it * 8 + wave, t = j * 64 + tl;
;         unsigned E[8];
;         { const LAS v4u* ep = (const LAS v4u*)(EL + tl * 128 + 16 * g); const v4u e0 = ep[0], e1 = ep[1];
;           E[0] = e0.x; E[1] = e0.y; E[2] = e0.z; E[3] = e0.w; E[4] = e1.x; E[5] = e1.y; E[6] = e1.z; E[7] = e1.w; }
;         uint2 hv[4]; float4 gv[4];
;         { unsigned ho = (unsigned)t * (D / 4) + (unsigned)lane; asm volatile("" : "+v"(ho)); const uint2* hp = (const uint2*)HB + ho; const float4* gp = (const float4*)fng + lane;
; #pragma unroll
;           for (int jq = 0; jq < 4; ++jq) { hv[jq] = hp[64 * jq]; gv[jq] = gp[64 * jq]; } }
;         VDMA(0, 0); VDMA(1, 1);
; #pragma unroll
;         for (int m = 0; m < 2; ++m) {
;             const int idx = lane + 64 * m, tau = idx >> 4, sr = idx & 15, k = 16 * (sr & 7) + 2 * tau + (sr >> 3);
;             const int aq = (int)*(const LAS signed char*)(AL + tl * 128 + k); const int tq = aq + 8;
;             const unsigned lo = (((unsigned)tq & 15u) ^ 8u) * 0x11111111u, hi = ((unsigned)(tq >> 4) & 15u) * 0x11111111u;
;             typedef unsigned u2v __attribute__((ext_vector_type(2)));
;             u2v l2; l2.x = lo; l2.y = lo; u2v h2; h2.x = hi; h2.y = hi;
;             *(LAS u2v*)(ATL + 8 * idx) = l2; *(LAS u2v*)(ATL + 1024 + 8 * idx) = h2;
;         }
;         const float asc = ASC[tl]; const int sa = SAL[tl];
;         CFENCE();
;         int accH[4], accL[4];
; #pragma unroll
;         for (int st = 0; st < 16; ++st) {
;             const int p = st >> 2, q = st & 3;
;             if (st < 14) VDMA(st + 2, (st + 2) % 3);
;             if (st < 14) asm volatile("s_waitcnt vmcnt(8)" ::: "memory");
;             else if (st == 14) asm volatile("s_waitcnt vmcnt(4)" ::: "memory");
;             else asm volatile("s_waitcnt vmcnt(0)" ::: "memory");
;             if (q == 0) {
; #pragma unroll
;                 for (int r = 0; r < 4; ++r) { accH[r] = 0; accL[r] = 0; } }
; #pragma unroll
;             for (int tp = 0; tp < 2; ++tp) {
;                 const v2i ao = TR4(ATL + (2 * q + tp) * 128 + 8 * s16), ah = TR4(ATL + 1024 + (2 * q + tp) * 128 + 8 * s16);
; #pragma unroll
;                 for (int r = 0; r < 4; ++r) {
	v_mul_f32_e32 v244, v244, v252
	v_mul_f32_e32 v245, v245, v253
	v_mul_f32_e32 v246, v246, v254
	v_mul_f32_e32 v247, v247, v255
	global_store_dwordx4 v[80:81], v[244:247], off offset:2048 sc1
	s_add_i32 s43, s40, 48
	s_lshl_b32 s43, s43, 11
	v_add_u32_e32 v138, s43, v66
	global_load_dwordx2 v[194:195], v138, s[70:71]
	global_load_dwordx2 v[196:197], v138, s[70:71] offset:512
	global_load_dwordx2 v[198:199], v138, s[70:71] offset:1024
	global_load_dwordx2 v[200:201], v138, s[70:71] offset:1536
	s_add_i32 s43, s40, 56
	s_lshl_b32 s43, s43, 11
	v_add_u32_e32 v138, s43, v66
	global_load_dwordx2 v[18:19], v138, s[70:71]
	global_load_dwordx2 v[20:21], v138, s[70:71] offset:512
	global_load_dwordx2 v[22:23], v138, s[70:71] offset:1024
	global_load_dwordx2 v[24:25], v138, s[70:71] offset:1536
	v_add_u32_e32 v147, 8, v140
	v_and_b32_e32 v146, 15, v147
	v_xor_b32_e32 v146, 8, v146
	v_bfe_u32 v148, v147, 4, 4
	v_mul_lo_u32 v146, v146, s92
	v_mul_lo_u32 v148, v148, s92
	v_mov_b32_e32 v147, v146
	v_mov_b32_e32 v149, v148
	ds_write2st64_b64 v77, v[146:147], v[148:149] offset1:2
	s_add_i32 s43, s67, 224
	v_mov_b32_e32 v138, s43
	ds_read2st64_b32 v[228:229], v138 offset1:1
	v_mov_b32_e32 v38, 0
	v_mov_b32_e32 v39, 0
	v_mov_b32_e32 v40, 0
	v_mov_b32_e32 v41, 0
	v_mov_b32_e32 v42, 0
	v_mov_b32_e32 v43, 0
	v_mov_b32_e32 v44, 0
	v_mov_b32_e32 v45, 0
	v_and_b32_e32 v78, 0xffff, v31
	v_lshrrev_b32_e32 v79, 16, v31
	v_lshl_add_u32 v78, v78, 7, v152
	v_lshl_add_u32 v79, v79, 7, v153
	s_mov_b32 m0, s77
	s_add_i32 s43, s77, 0x400
	global_load_lds_dwordx4 v78, s[50:51]
	s_mov_b32 m0, s43
	s_nop 0
	global_load_lds_dwordx4 v79, s[50:51]
	s_waitcnt vmcnt(17)
	v_add_u32_e32 v54, s79, v59
	v_add_u32_e32 v55, s79, v60
	v_add_u32_e32 v56, s79, v61
	v_add_u32_e32 v57, s79, v62
	ds_read_b64_tr_b4 v[50:51], v160 offset:128
	ds_read_b64_tr_b4 v[52:53], v160 offset:1152
	ds_read_b64_tr_b4 v[130:131], v54
	ds_read_b64_tr_b4 v[132:133], v55
	ds_read_b64_tr_b4 v[134:135], v56
	ds_read_b64_tr_b4 v[136:137], v57
	s_waitcnt lgkmcnt(9)
	v_dot8c_i32_i4_e32 v38, v122, v48
	v_dot8c_i32_i4_e32 v39, v122, v46
	v_dot8c_i32_i4_e32 v40, v124, v48
	v_dot8c_i32_i4_e32 v41, v124, v46
	v_dot8c_i32_i4_e32 v42, v126, v48
	v_dot8c_i32_i4_e32 v43, v126, v46
	v_dot8c_i32_i4_e32 v44, v128, v48
	v_dot8c_i32_i4_e32 v45, v128, v46
	v_dot8c_i32_i4_e32 v38, v123, v49
	v_dot8c_i32_i4_e32 v39, v123, v47
	v_dot8c_i32_i4_e32 v40, v125, v49
	v_dot8c_i32_i4_e32 v41, v125, v47
	v_dot8c_i32_i4_e32 v42, v127, v49
	v_dot8c_i32_i4_e32 v43, v127, v47
	v_dot8c_i32_i4_e32 v44, v129, v49
	v_dot8c_i32_i4_e32 v45, v129, v47
	v_and_b32_e32 v78, 0xffff, v32
	v_lshrrev_b32_e32 v79, 16, v32
	v_lshl_add_u32 v78, v78, 7, v152
	v_lshl_add_u32 v79, v79, 7, v153
	s_mov_b32 m0, s78
	s_add_i32 s43, s78, 0x400
	global_load_lds_dwordx4 v78, s[50:51]
	s_mov_b32 m0, s43
	s_nop 0
	global_load_lds_dwordx4 v79, s[50:51]
	s_waitcnt vmcnt(17)
	v_add_u32_e32 v54, s98, v59
	v_add_u32_e32 v55, s98, v60
	v_add_u32_e32 v56, s98, v61
	v_add_u32_e32 v57, s98, v62
	ds_read_b64_tr_b4 v[46:47], v160 offset:256
	ds_read_b64_tr_b4 v[48:49], v160 offset:1280
	ds_read_b64_tr_b4 v[122:123], v54
	ds_read_b64_tr_b4 v[124:125], v55
	ds_read_b64_tr_b4 v[126:127], v56
	ds_read_b64_tr_b4 v[128:129], v57
	s_waitcnt lgkmcnt(6)
	v_dot8c_i32_i4_e32 v38, v130, v52
	v_dot8c_i32_i4_e32 v39, v130, v50
	v_dot8c_i32_i4_e32 v40, v132, v52
	v_dot8c_i32_i4_e32 v41, v132, v50
	v_dot8c_i32_i4_e32 v42, v134, v52
	v_dot8c_i32_i4_e32 v43, v134, v50
	v_dot8c_i32_i4_e32 v44, v136, v52
	v_dot8c_i32_i4_e32 v45, v136, v50
	v_dot8c_i32_i4_e32 v38, v131, v53
	v_dot8c_i32_i4_e32 v39, v131, v51
	v_dot8c_i32_i4_e32 v40, v133, v53
	v_dot8c_i32_i4_e32 v41, v133, v51
	v_dot8c_i32_i4_e32 v42, v135, v53
	v_dot8c_i32_i4_e32 v43, v135, v51
	v_dot8c_i32_i4_e32 v44, v137, v53
	v_dot8c_i32_i4_e32 v45, v137, v51
	v_and_b32_e32 v78, 0xffff, v33
	v_lshrrev_b32_e32 v79, 16, v33
	v_lshl_add_u32 v78, v78, 7, v152
	v_lshl_add_u32 v79, v79, 7, v153
	s_mov_b32 m0, s79
	s_add_i32 s43, s79, 0x400
	global_load_lds_dwordx4 v78, s[50:51]
	s_mov_b32 m0, s43
	s_nop 0
	global_load_lds_dwordx4 v79, s[50:51]
	s_waitcnt vmcnt(17)
	v_add_u32_e32 v54, s99, v59
	v_add_u32_e32 v55, s99, v60
	v_add_u32_e32 v56, s99, v61
	v_add_u32_e32 v57, s99, v62
	ds_read_b64_tr_b4 v[50:51], v160 offset:384
	ds_read_b64_tr_b4 v[52:53], v160 offset:1408
	ds_read_b64_tr_b4 v[130:131], v54
	ds_read_b64_tr_b4 v[132:133], v55
	ds_read_b64_tr_b4 v[134:135], v56
	ds_read_b64_tr_b4 v[136:137], v57
	s_waitcnt lgkmcnt(6)
	v_dot8c_i32_i4_e32 v38, v122, v48
	v_dot8c_i32_i4_e32 v39, v122, v46
	v_dot8c_i32_i4_e32 v40, v124, v48
	v_dot8c_i32_i4_e32 v41, v124, v46
	v_dot8c_i32_i4_e32 v42, v126, v48
	v_dot8c_i32_i4_e32 v43, v126, v46
	v_dot8c_i32_i4_e32 v44, v128, v48
	v_dot8c_i32_i4_e32 v45, v128, v46
	v_dot8c_i32_i4_e32 v38, v123, v49
	v_dot8c_i32_i4_e32 v39, v123, v47
	v_dot8c_i32_i4_e32 v40, v125, v49
	v_dot8c_i32_i4_e32 v41, v125, v47
	v_dot8c_i32_i4_e32 v42, v127, v49
	v_dot8c_i32_i4_e32 v43, v127, v47
	v_dot8c_i32_i4_e32 v44, v129, v49
	v_dot8c_i32_i4_e32 v45, v129, v47
	s_waitcnt vmcnt(15)
	v_add_u32_e32 v54, s76, v59
	v_add_u32_e32 v55, s76, v60
	v_add_u32_e32 v56, s76, v61
	v_add_u32_e32 v57, s76, v62
	ds_read_b64_tr_b4 v[46:47], v160 offset:512
	ds_read_b64_tr_b4 v[48:49], v160 offset:1536
	ds_read_b64_tr_b4 v[122:123], v54
	ds_read_b64_tr_b4 v[124:125], v55
	ds_read_b64_tr_b4 v[126:127], v56
	ds_read_b64_tr_b4 v[128:129], v57
	s_waitcnt lgkmcnt(6)
; #define LAS __attribute__((address_space(3)))
; __device__ __forceinline__ bf16 f2bf(float f) { return (bf16)f2bfu(f); }
; #define TR4(p_) __builtin_amdgcn_ds_read_tr4_b64_v2i32((LAS v2i*)(p_))
; #define CFENCE() asm volatile("" ::: "memory")
; __device__ __forceinline__ void peer_v_tokens(int j, const LAS unsigned short* EL, const LAS unsigned char* AL  , const LAS float* ASC  , const LAS int* SAL  , ...
;     ...
;         for (int st = 0; st < 16; ++st) {
;             const int p = st >> 2, q = st & 3;
;             if (st < 14) VDMA(st + 2, (st + 2) % 3);
;             if (st < 14) asm volatile("s_waitcnt vmcnt(8)" ::: "memory");
;             else if (st == 14) asm volatile("s_waitcnt vmcnt(4)" ::: "memory");
;             else asm volatile("s_waitcnt vmcnt(0)" ::: "memory");
;             if (q == 0) {
; #pragma unroll
;                 for (int r = 0; r < 4; ++r) { accH[r] = 0; accL[r] = 0; } }
; #pragma unroll
;             for (int tp = 0; tp < 2; ++tp) {
;                 const v2i ao = TR4(ATL + (2 * q + tp) * 128 + 8 * s16), ah = TR4(ATL + 1024 + (2 * q + tp) * 128 + 8 * s16);
; #pragma unroll
;                 for (int r = 0; r < 4; ++r) {
;                     const v2i d = TR4(ldsb + BUF[st % 3] + 2048 * tp + roff[r]);
;                     accH[r] = __builtin_amdgcn_sdot8(d.x, ah.x, accH[r], false); accH[r] = __builtin_amdgcn_sdot8(d.y, ah.y, accH[r], false);
;                     accL[r] = __builtin_amdgcn_sdot8(d.x, ao.x, accL[r], false); accL[r] = __builtin_amdgcn_sdot8(d.y, ao.y, accL[r], false);
;                 }
;             }
;             asm volatile("s_waitcnt lgkmcnt(0)" ::: "memory");
;             if (q == 3) {
; #pragma unroll
;                 for (int r = 0; r < 4; ++r) STASH[256 * p + 16 * (grp + 4 * r) + pc] = f2bf(asc * (float)(2 * ((accH[r] << 4) + accL[r]) + sa));
;             }
;         }
;         CFENCE();
;         {
;             float4 v[4]; float ss = 0.f;
; #pragma unroll
;             for (int jq = 0; jq < 4; ++jq) { typedef unsigned u2v __attribute__((ext_vector_type(2))); const u2v pw = *(const LAS u2v*)(STASH + 4 * lane + 256 * jq); const uint2 hw = hv[jq];
;                 v[jq] = make_float4(__uint_as_float(hw.x << 16) + __uint_as_float(pw.x << 16), __uint_as_float(hw.x & 0xffff0000u) + __uint_as_float(pw.x & 0xffff0000u),
	v_dot8c_i32_i4_e32 v38, v130, v52
	v_dot8c_i32_i4_e32 v39, v130, v50
	v_dot8c_i32_i4_e32 v40, v132, v52
	v_dot8c_i32_i4_e32 v41, v132, v50
	v_dot8c_i32_i4_e32 v42, v134, v52
	v_dot8c_i32_i4_e32 v43, v134, v50
	v_dot8c_i32_i4_e32 v44, v136, v52
	v_dot8c_i32_i4_e32 v45, v136, v50
	v_dot8c_i32_i4_e32 v38, v131, v53
	v_dot8c_i32_i4_e32 v39, v131, v51
	v_dot8c_i32_i4_e32 v40, v133, v53
	v_dot8c_i32_i4_e32 v41, v133, v51
	v_dot8c_i32_i4_e32 v42, v135, v53
	v_dot8c_i32_i4_e32 v43, v135, v51
	v_dot8c_i32_i4_e32 v44, v137, v53
	v_dot8c_i32_i4_e32 v45, v137, v51
	s_waitcnt vmcnt(4)
	v_add_u32_e32 v54, s77, v59
	v_add_u32_e32 v55, s77, v60
	v_add_u32_e32 v56, s77, v61
	v_add_u32_e32 v57, s77, v62
	ds_read_b64_tr_b4 v[50:51], v160 offset:640
	ds_read_b64_tr_b4 v[52:53], v160 offset:1664
	ds_read_b64_tr_b4 v[130:131], v54
	ds_read_b64_tr_b4 v[132:133], v55
	ds_read_b64_tr_b4 v[134:135], v56
	ds_read_b64_tr_b4 v[136:137], v57
	s_waitcnt lgkmcnt(6)
	v_dot8c_i32_i4_e32 v38, v122, v48
	v_dot8c_i32_i4_e32 v39, v122, v46
	v_dot8c_i32_i4_e32 v40, v124, v48
	v_dot8c_i32_i4_e32 v41, v124, v46
	v_dot8c_i32_i4_e32 v42, v126, v48
	v_dot8c_i32_i4_e32 v43, v126, v46
	v_dot8c_i32_i4_e32 v44, v128, v48
	v_dot8c_i32_i4_e32 v45, v128, v46
	v_dot8c_i32_i4_e32 v38, v123, v49
	v_dot8c_i32_i4_e32 v39, v123, v47
	v_dot8c_i32_i4_e32 v40, v125, v49
	v_dot8c_i32_i4_e32 v41, v125, v47
	v_dot8c_i32_i4_e32 v42, v127, v49
	v_dot8c_i32_i4_e32 v43, v127, v47
	v_dot8c_i32_i4_e32 v44, v129, v49
	v_dot8c_i32_i4_e32 v45, v129, v47
	s_waitcnt vmcnt(2)
	v_add_u32_e32 v54, s78, v59
	v_add_u32_e32 v55, s78, v60
	v_add_u32_e32 v56, s78, v61
	v_add_u32_e32 v57, s78, v62
	ds_read_b64_tr_b4 v[46:47], v160 offset:768
	ds_read_b64_tr_b4 v[48:49], v160 offset:1792
	ds_read_b64_tr_b4 v[122:123], v54
	ds_read_b64_tr_b4 v[124:125], v55
	ds_read_b64_tr_b4 v[126:127], v56
	ds_read_b64_tr_b4 v[128:129], v57
	s_waitcnt lgkmcnt(6)
	v_dot8c_i32_i4_e32 v38, v130, v52
	v_dot8c_i32_i4_e32 v39, v130, v50
	v_dot8c_i32_i4_e32 v40, v132, v52
	v_dot8c_i32_i4_e32 v41, v132, v50
	v_dot8c_i32_i4_e32 v42, v134, v52
	v_dot8c_i32_i4_e32 v43, v134, v50
	v_dot8c_i32_i4_e32 v44, v136, v52
	v_dot8c_i32_i4_e32 v45, v136, v50
	v_dot8c_i32_i4_e32 v38, v131, v53
	v_dot8c_i32_i4_e32 v39, v131, v51
	v_dot8c_i32_i4_e32 v40, v133, v53
	v_dot8c_i32_i4_e32 v41, v133, v51
	v_dot8c_i32_i4_e32 v42, v135, v53
	v_dot8c_i32_i4_e32 v43, v135, v51
	v_dot8c_i32_i4_e32 v44, v137, v53
	v_dot8c_i32_i4_e32 v45, v137, v51
	s_waitcnt vmcnt(0)
	v_add_u32_e32 v54, s79, v59
	v_add_u32_e32 v55, s79, v60
	v_add_u32_e32 v56, s79, v61
	v_add_u32_e32 v57, s79, v62
	ds_read_b64_tr_b4 v[50:51], v160 offset:896
	ds_read_b64_tr_b4 v[52:53], v160 offset:1920
	ds_read_b64_tr_b4 v[130:131], v54
	ds_read_b64_tr_b4 v[132:133], v55
	ds_read_b64_tr_b4 v[134:135], v56
	ds_read_b64_tr_b4 v[136:137], v57
	s_waitcnt lgkmcnt(6)
	v_dot8c_i32_i4_e32 v38, v122, v48
	v_dot8c_i32_i4_e32 v39, v122, v46
	v_dot8c_i32_i4_e32 v40, v124, v48
	v_dot8c_i32_i4_e32 v41, v124, v46
	v_dot8c_i32_i4_e32 v42, v126, v48
	v_dot8c_i32_i4_e32 v43, v126, v46
	v_dot8c_i32_i4_e32 v44, v128, v48
	v_dot8c_i32_i4_e32 v45, v128, v46
	v_dot8c_i32_i4_e32 v38, v123, v49
	v_dot8c_i32_i4_e32 v39, v123, v47
	v_dot8c_i32_i4_e32 v40, v125, v49
	v_dot8c_i32_i4_e32 v41, v125, v47
	v_dot8c_i32_i4_e32 v42, v127, v49
	v_dot8c_i32_i4_e32 v43, v127, v47
	v_dot8c_i32_i4_e32 v44, v129, v49
	v_dot8c_i32_i4_e32 v45, v129, v47
	s_waitcnt lgkmcnt(0)
	v_dot8c_i32_i4_e32 v38, v130, v52
	v_dot8c_i32_i4_e32 v39, v130, v50
	v_dot8c_i32_i4_e32 v40, v132, v52
	v_dot8c_i32_i4_e32 v41, v132, v50
	v_dot8c_i32_i4_e32 v42, v134, v52
	v_dot8c_i32_i4_e32 v43, v134, v50
	v_dot8c_i32_i4_e32 v44, v136, v52
	v_dot8c_i32_i4_e32 v45, v136, v50
	v_dot8c_i32_i4_e32 v38, v131, v53
	v_dot8c_i32_i4_e32 v39, v131, v51
	v_dot8c_i32_i4_e32 v40, v133, v53
	v_dot8c_i32_i4_e32 v41, v133, v51
	v_dot8c_i32_i4_e32 v42, v135, v53
	v_dot8c_i32_i4_e32 v43, v135, v51
	v_dot8c_i32_i4_e32 v44, v137, v53
	v_dot8c_i32_i4_e32 v45, v137, v51
	s_nop 3
	s_waitcnt lgkmcnt(15)
	v_lshlrev_b32_e32 v38, 5, v38
	v_lshlrev_b32_e32 v39, 1, v39
	v_add3_u32 v38, v39, v229, v38
	v_cvt_f32_i32_e32 v38, v38
	v_mul_f32_e32 v38, v228, v38
	v_lshlrev_b32_e32 v40, 5, v40
	v_lshlrev_b32_e32 v41, 1, v41
	v_add3_u32 v40, v41, v229, v40
	v_cvt_f32_i32_e32 v40, v40
	v_mul_f32_e32 v40, v228, v40
	v_lshlrev_b32_e32 v42, 5, v42
	v_lshlrev_b32_e32 v43, 1, v43
	v_add3_u32 v42, v43, v229, v42
	v_cvt_f32_i32_e32 v42, v42
	v_mul_f32_e32 v42, v228, v42
	v_lshlrev_b32_e32 v44, 5, v44
	v_lshlrev_b32_e32 v45, 1, v45
	v_add3_u32 v44, v45, v229, v44
	v_cvt_f32_i32_e32 v44, v44
	v_mul_f32_e32 v44, v228, v44
	v_cvt_pk_bf16_f32 v192, v38, v40
	v_cvt_pk_bf16_f32 v193, v42, v44
	ds_read_b128 v[252:255], v156 offset:1024
	s_add_i32 s44, s40, 40
	s_ashr_i32 s45, s44, 31
	s_lshl_b64 s[44:45], s[44:45], 12
	v_lshl_add_u64 v[80:81], v[36:37], 0, s[44:45]
	s_waitcnt lgkmcnt(0)
	v_mul_f32_e32 v248, v248, v252
	v_mul_f32_e32 v249, v249, v253
	v_mul_f32_e32 v250, v250, v254
	v_mul_f32_e32 v251, v251, v255
	global_store_dwordx4 v[80:81], v[248:251], off offset:3072 sc1
	ds_write_b16 v65, v178
	ds_write_b16_d16_hi v65, v178 offset:128
	ds_write_b16 v65, v179 offset:256
	ds_write_b16_d16_hi v65, v179 offset:384
	ds_write_b16 v65, v180 offset:512
	ds_write_b16_d16_hi v65, v180 offset:640
	ds_write_b16 v65, v181 offset:768
	ds_write_b16_d16_hi v65, v181 offset:896
	ds_write_b16 v65, v182 offset:1024
	ds_write_b16_d16_hi v65, v182 offset:1152
	ds_write_b16 v65, v183 offset:1280
	ds_write_b16_d16_hi v65, v183 offset:1408
	ds_write_b16 v65, v184 offset:1536
	ds_write_b16_d16_hi v65, v184 offset:1664
	ds_write_b16 v65, v185 offset:1792
	ds_write_b16_d16_hi v65, v185 offset:1920
	ds_read_b64 v[202:203], v154
	ds_read_b64 v[204:205], v154 offset:512
	ds_read_b64 v[206:207], v154 offset:1024
	ds_read_b64 v[208:209], v154 offset:1536
	s_waitcnt vmcnt(11) lgkmcnt(0)
; #define LAS __attribute__((address_space(3)))
; __device__ __forceinline__ void peer_v_tokens(int j, const LAS unsigned short* EL, const LAS unsigned char* AL  , const LAS float* ASC  , const LAS int* SAL  , ...
;     ...
;         {
;             float4 v[4]; float ss = 0.f;
; #pragma unroll
;             for (int jq = 0; jq < 4; ++jq) { typedef unsigned u2v __attribute__((ext_vector_type(2))); const u2v pw = *(const LAS u2v*)(STASH + 4 * lane + 256 * jq); const uint2 hw = hv[jq];
;                 v[jq] = make_float4(__uint_as_float(hw.x << 16) + __uint_as_float(pw.x << 16), __uint_as_float(hw.x & 0xffff0000u) + __uint_as_float(pw.x & 0xffff0000u),
;                                     __uint_as_float(hw.y << 16) + __uint_as_float(pw.y << 16), __uint_as_float(hw.y & 0xffff0000u) + __uint_as_float(pw.y & 0xffff0000u));
;                 ss += v[jq].x * v[jq].x + v[jq].y * v[jq].y + v[jq].z * v[jq].z + v[jq].w * v[jq].w; }
;             ss = wave_sum(ss);
;             const float r3 = rsqrtf(ss * (1.f / D) + EPS);
;             float4* op = (float4*)(outp + (size_t)t * D) + lane;
; #pragma unroll
;             for (int jq = 0; jq < 4; ++jq) { typedef float f4v __attribute__((ext_vector_type(4))); f4v o4; o4.x = v[jq].x * r3 * gv[jq].x; o4.y = v[jq].y * r3 * gv[jq].y; o4.z = v[jq].z * r3 * gv[jq].z; o4.w = v[jq].w * r3 * gv[jq].w;
;                 __builtin_nontemporal_store(o4, (f4v*)op + 64 * jq); }
	v_lshlrev_b32_e32 v210, 16, v194
	v_and_b32_e32 v211, 0xffff0000, v194
	v_lshlrev_b32_e32 v142, 16, v202
	v_and_b32_e32 v143, 0xffff0000, v202
	v_add_f32_e32 v210, v210, v142
	v_add_f32_e32 v211, v211, v143
	v_lshlrev_b32_e32 v212, 16, v195
	v_and_b32_e32 v213, 0xffff0000, v195
	v_lshlrev_b32_e32 v142, 16, v203
	v_and_b32_e32 v143, 0xffff0000, v203
	v_add_f32_e32 v212, v212, v142
	v_add_f32_e32 v213, v213, v143
	v_lshlrev_b32_e32 v214, 16, v196
	v_and_b32_e32 v215, 0xffff0000, v196
	v_lshlrev_b32_e32 v142, 16, v204
	v_and_b32_e32 v143, 0xffff0000, v204
	v_add_f32_e32 v214, v214, v142
	v_add_f32_e32 v215, v215, v143
	v_lshlrev_b32_e32 v216, 16, v197
	v_and_b32_e32 v217, 0xffff0000, v197
	v_lshlrev_b32_e32 v142, 16, v205
	v_and_b32_e32 v143, 0xffff0000, v205
	v_add_f32_e32 v216, v216, v142
	v_add_f32_e32 v217, v217, v143
	v_lshlrev_b32_e32 v218, 16, v198
	v_and_b32_e32 v219, 0xffff0000, v198
	v_lshlrev_b32_e32 v142, 16, v206
	v_and_b32_e32 v143, 0xffff0000, v206
	v_add_f32_e32 v218, v218, v142
	v_add_f32_e32 v219, v219, v143
	v_lshlrev_b32_e32 v220, 16, v199
	v_and_b32_e32 v221, 0xffff0000, v199
	v_lshlrev_b32_e32 v142, 16, v207
	v_and_b32_e32 v143, 0xffff0000, v207
	v_add_f32_e32 v220, v220, v142
	v_add_f32_e32 v221, v221, v143
	v_lshlrev_b32_e32 v222, 16, v200
	v_and_b32_e32 v223, 0xffff0000, v200
	v_lshlrev_b32_e32 v142, 16, v208
	v_and_b32_e32 v143, 0xffff0000, v208
	v_add_f32_e32 v222, v222, v142
	v_add_f32_e32 v223, v223, v143
	v_lshlrev_b32_e32 v224, 16, v201
	v_and_b32_e32 v225, 0xffff0000, v201
	v_lshlrev_b32_e32 v142, 16, v209
	v_and_b32_e32 v143, 0xffff0000, v209
	v_add_f32_e32 v224, v224, v142
	v_add_f32_e32 v225, v225, v143
	v_mov_b32_e32 v144, 0
	v_mul_f32_e32 v145, v210, v210
	v_fmac_f32_e32 v145, v211, v211
	v_fmac_f32_e32 v145, v212, v212
	v_fmac_f32_e32 v145, v213, v213
	v_add_f32_e32 v144, v144, v145
	v_mul_f32_e32 v145, v214, v214
	v_fmac_f32_e32 v145, v215, v215
	v_fmac_f32_e32 v145, v216, v216
	v_fmac_f32_e32 v145, v217, v217
	v_add_f32_e32 v144, v144, v145
	v_mul_f32_e32 v145, v218, v218
	v_fmac_f32_e32 v145, v219, v219
	v_fmac_f32_e32 v145, v220, v220
	v_fmac_f32_e32 v145, v221, v221
	v_add_f32_e32 v144, v144, v145
	v_mul_f32_e32 v145, v222, v222
	v_fmac_f32_e32 v145, v223, v223
	v_fmac_f32_e32 v145, v224, v224
	v_fmac_f32_e32 v145, v225, v225
	v_add_f32_e32 v144, v144, v145
	s_nop 1
	v_add_f32_dpp v144, v144, v144 quad_perm:[1,0,3,2] row_mask:0xf bank_mask:0xf bound_ctrl:1
	s_nop 1
	v_add_f32_dpp v144, v144, v144 quad_perm:[2,3,0,1] row_mask:0xf bank_mask:0xf bound_ctrl:1
	s_nop 1
	v_add_f32_dpp v144, v144, v144 row_half_mirror row_mask:0xf bank_mask:0xf bound_ctrl:1
	s_nop 1
	v_add_f32_dpp v144, v144, v144 row_mirror row_mask:0xf bank_mask:0xf bound_ctrl:1
	s_nop 1
	v_readlane_b32 s10, v144, 0
	v_readlane_b32 s11, v144, 16
	v_readlane_b32 s14, v144, 32
	v_readlane_b32 s15, v144, 48
	s_nop 3
	v_mov_b32_e32 v144, s11
	v_mov_b32_e32 v145, s15
	v_add_f32_e32 v144, s10, v144
	v_add_f32_e32 v145, s14, v145
	v_add_f32_e32 v144, v144, v145
	v_fmamk_f32 v144, v144, 0x3a800000, v111
	v_rsq_f32_e32 v144, v144
	s_nop 0
	v_mul_f32_e32 v210, v210, v144
	v_mul_f32_e32 v211, v211, v144
	v_mul_f32_e32 v212, v212, v144
	v_mul_f32_e32 v213, v213, v144
	v_mul_f32_e32 v214, v214, v144
	v_mul_f32_e32 v215, v215, v144
	v_mul_f32_e32 v216, v216, v144
	v_mul_f32_e32 v217, v217, v144
	v_mul_f32_e32 v218, v218, v144
	v_mul_f32_e32 v219, v219, v144
	v_mul_f32_e32 v220, v220, v144
	v_mul_f32_e32 v221, v221, v144
	v_mul_f32_e32 v222, v222, v144
	v_mul_f32_e32 v223, v223, v144
	v_mul_f32_e32 v224, v224, v144
	v_mul_f32_e32 v225, v225, v144
	ds_read_b128 v[252:255], v155
	s_add_i32 s44, s40, 48
	s_ashr_i32 s45, s44, 31
	s_lshl_b64 s[44:45], s[44:45], 12
	v_lshl_add_u64 v[80:81], v[36:37], 0, s[44:45]
	s_waitcnt lgkmcnt(0)
	v_mul_f32_e32 v210, v210, v252
	v_mul_f32_e32 v211, v211, v253
	v_mul_f32_e32 v212, v212, v254
	v_mul_f32_e32 v213, v213, v255
	global_store_dwordx4 v[80:81], v[210:213], off sc1
	ds_read_b128 v[252:255], v155 offset:1024
	s_add_i32 s44, s40, 48
	s_ashr_i32 s45, s44, 31
	s_lshl_b64 s[44:45], s[44:45], 12
	v_lshl_add_u64 v[80:81], v[36:37], 0, s[44:45]
	s_waitcnt lgkmcnt(0)
	v_mul_f32_e32 v214, v214, v252
	v_mul_f32_e32 v215, v215, v253
	v_mul_f32_e32 v216, v216, v254
	v_mul_f32_e32 v217, v217, v255
	global_store_dwordx4 v[80:81], v[214:217], off offset:1024 sc1
	ds_read_b128 v[252:255], v156
	s_add_i32 s44, s40, 48
	s_ashr_i32 s45, s44, 31
	s_lshl_b64 s[44:45], s[44:45], 12
	v_lshl_add_u64 v[80:81], v[36:37], 0, s[44:45]
	s_waitcnt lgkmcnt(0)
	v_mul_f32_e32 v218, v218, v252
	v_mul_f32_e32 v219, v219, v253
	v_mul_f32_e32 v220, v220, v254
	v_mul_f32_e32 v221, v221, v255
	global_store_dwordx4 v[80:81], v[218:221], off offset:2048 sc1
	ds_read_b128 v[252:255], v156 offset:1024
	s_add_i32 s44, s40, 48
	s_ashr_i32 s45, s44, 31
	s_lshl_b64 s[44:45], s[44:45], 12
	v_lshl_add_u64 v[80:81], v[36:37], 0, s[44:45]
	s_waitcnt lgkmcnt(0)
	v_mul_f32_e32 v222, v222, v252
	v_mul_f32_e32 v223, v223, v253
	v_mul_f32_e32 v224, v224, v254
	v_mul_f32_e32 v225, v225, v255
	global_store_dwordx4 v[80:81], v[222:225], off offset:3072 sc1
	ds_write_b16 v65, v186
	ds_write_b16_d16_hi v65, v186 offset:128
	ds_write_b16 v65, v187 offset:256
	ds_write_b16_d16_hi v65, v187 offset:384
	ds_write_b16 v65, v188 offset:512
	ds_write_b16_d16_hi v65, v188 offset:640
	ds_write_b16 v65, v189 offset:768
	ds_write_b16_d16_hi v65, v189 offset:896
	ds_write_b16 v65, v190 offset:1024
	ds_write_b16_d16_hi v65, v190 offset:1152
	ds_write_b16 v65, v191 offset:1280
	ds_write_b16_d16_hi v65, v191 offset:1408
	ds_write_b16 v65, v192 offset:1536
	ds_write_b16_d16_hi v65, v192 offset:1664
	ds_write_b16 v65, v193 offset:1792
	ds_write_b16_d16_hi v65, v193 offset:1920
	ds_read_b64 v[202:203], v154
	ds_read_b64 v[204:205], v154 offset:512
	ds_read_b64 v[206:207], v154 offset:1024
	ds_read_b64 v[208:209], v154 offset:1536
	s_waitcnt vmcnt(11) lgkmcnt(0)
; #define LAS __attribute__((address_space(3)))
; __device__ __forceinline__ void peer_v_tokens(int j, const LAS unsigned short* EL, const LAS unsigned char* AL  , const LAS float* ASC  , const LAS int* SAL  , ...
;     ...
;         {
;             float4 v[4]; float ss = 0.f;
; #pragma unroll
;             for (int jq = 0; jq < 4; ++jq) { typedef unsigned u2v __attribute__((ext_vector_type(2))); const u2v pw = *(const LAS u2v*)(STASH + 4 * lane + 256 * jq); const uint2 hw = hv[jq];
;                 v[jq] = make_float4(__uint_as_float(hw.x << 16) + __uint_as_float(pw.x << 16), __uint_as_float(hw.x & 0xffff0000u) + __uint_as_float(pw.x & 0xffff0000u),
;                                     __uint_as_float(hw.y << 16) + __uint_as_float(pw.y << 16), __uint_as_float(hw.y & 0xffff0000u) + __uint_as_float(pw.y & 0xffff0000u));
;                 ss += v[jq].x * v[jq].x + v[jq].y * v[jq].y + v[jq].z * v[jq].z + v[jq].w * v[jq].w; }
;             ss = wave_sum(ss);
;             const float r3 = rsqrtf(ss * (1.f / D) + EPS);
;             float4* op = (float4*)(outp + (size_t)t * D) + lane;
; #pragma unroll
;             for (int jq = 0; jq < 4; ++jq) { typedef float f4v __attribute__((ext_vector_type(4))); f4v o4; o4.x = v[jq].x * r3 * gv[jq].x; o4.y = v[jq].y * r3 * gv[jq].y; o4.z = v[jq].z * r3 * gv[jq].z; o4.w = v[jq].w * r3 * gv[jq].w;
;                 __builtin_nontemporal_store(o4, (f4v*)op + 64 * jq); }
	v_lshlrev_b32_e32 v236, 16, v18
	v_and_b32_e32 v237, 0xffff0000, v18
	v_lshlrev_b32_e32 v142, 16, v202
	v_and_b32_e32 v143, 0xffff0000, v202
	v_add_f32_e32 v236, v236, v142
	v_add_f32_e32 v237, v237, v143
	v_lshlrev_b32_e32 v238, 16, v19
	v_and_b32_e32 v239, 0xffff0000, v19
	v_lshlrev_b32_e32 v142, 16, v203
	v_and_b32_e32 v143, 0xffff0000, v203
	v_add_f32_e32 v238, v238, v142
	v_add_f32_e32 v239, v239, v143
	v_lshlrev_b32_e32 v240, 16, v20
	v_and_b32_e32 v241, 0xffff0000, v20
	v_lshlrev_b32_e32 v142, 16, v204
	v_and_b32_e32 v143, 0xffff0000, v204
	v_add_f32_e32 v240, v240, v142
	v_add_f32_e32 v241, v241, v143
	v_lshlrev_b32_e32 v242, 16, v21
	v_and_b32_e32 v243, 0xffff0000, v21
	v_lshlrev_b32_e32 v142, 16, v205
	v_and_b32_e32 v143, 0xffff0000, v205
	v_add_f32_e32 v242, v242, v142
	v_add_f32_e32 v243, v243, v143
	v_lshlrev_b32_e32 v244, 16, v22
	v_and_b32_e32 v245, 0xffff0000, v22
	v_lshlrev_b32_e32 v142, 16, v206
	v_and_b32_e32 v143, 0xffff0000, v206
	v_add_f32_e32 v244, v244, v142
	v_add_f32_e32 v245, v245, v143
	v_lshlrev_b32_e32 v246, 16, v23
	v_and_b32_e32 v247, 0xffff0000, v23
	v_lshlrev_b32_e32 v142, 16, v207
	v_and_b32_e32 v143, 0xffff0000, v207
	v_add_f32_e32 v246, v246, v142
	v_add_f32_e32 v247, v247, v143
	v_lshlrev_b32_e32 v248, 16, v24
	v_and_b32_e32 v249, 0xffff0000, v24
	v_lshlrev_b32_e32 v142, 16, v208
	v_and_b32_e32 v143, 0xffff0000, v208
	v_add_f32_e32 v248, v248, v142
	v_add_f32_e32 v249, v249, v143
	v_lshlrev_b32_e32 v250, 16, v25
	v_and_b32_e32 v251, 0xffff0000, v25
	v_lshlrev_b32_e32 v142, 16, v209
	v_and_b32_e32 v143, 0xffff0000, v209
	v_add_f32_e32 v250, v250, v142
	v_add_f32_e32 v251, v251, v143
	v_mov_b32_e32 v144, 0
	v_mul_f32_e32 v145, v236, v236
	v_fmac_f32_e32 v145, v237, v237
	v_fmac_f32_e32 v145, v238, v238
	v_fmac_f32_e32 v145, v239, v239
	v_add_f32_e32 v144, v144, v145
	v_mul_f32_e32 v145, v240, v240
	v_fmac_f32_e32 v145, v241, v241
	v_fmac_f32_e32 v145, v242, v242
	v_fmac_f32_e32 v145, v243, v243
	v_add_f32_e32 v144, v144, v145
	v_mul_f32_e32 v145, v244, v244
	v_fmac_f32_e32 v145, v245, v245
	v_fmac_f32_e32 v145, v246, v246
	v_fmac_f32_e32 v145, v247, v247
	v_add_f32_e32 v144, v144, v145
	v_mul_f32_e32 v145, v248, v248
	v_fmac_f32_e32 v145, v249, v249
	v_fmac_f32_e32 v145, v250, v250
	v_fmac_f32_e32 v145, v251, v251
	v_add_f32_e32 v144, v144, v145
	s_nop 1
	v_add_f32_dpp v144, v144, v144 quad_perm:[1,0,3,2] row_mask:0xf bank_mask:0xf bound_ctrl:1
	s_nop 1
	v_add_f32_dpp v144, v144, v144 quad_perm:[2,3,0,1] row_mask:0xf bank_mask:0xf bound_ctrl:1
	s_nop 1
	v_add_f32_dpp v144, v144, v144 row_half_mirror row_mask:0xf bank_mask:0xf bound_ctrl:1
	s_nop 1
	v_add_f32_dpp v144, v144, v144 row_mirror row_mask:0xf bank_mask:0xf bound_ctrl:1
	s_nop 1
	v_readlane_b32 s10, v144, 0
	v_readlane_b32 s11, v144, 16
	v_readlane_b32 s14, v144, 32
	v_readlane_b32 s15, v144, 48
	s_nop 3
	v_mov_b32_e32 v144, s11
	v_mov_b32_e32 v145, s15
	v_add_f32_e32 v144, s10, v144
	v_add_f32_e32 v145, s14, v145
	v_add_f32_e32 v144, v144, v145
	v_fmamk_f32 v144, v144, 0x3a800000, v111
	v_rsq_f32_e32 v144, v144
	s_nop 0
	v_mul_f32_e32 v236, v236, v144
	v_mul_f32_e32 v237, v237, v144
	v_mul_f32_e32 v238, v238, v144
	v_mul_f32_e32 v239, v239, v144
	v_mul_f32_e32 v240, v240, v144
	v_mul_f32_e32 v241, v241, v144
	v_mul_f32_e32 v242, v242, v144
	v_mul_f32_e32 v243, v243, v144
	v_mul_f32_e32 v244, v244, v144
	v_mul_f32_e32 v245, v245, v144
	v_mul_f32_e32 v246, v246, v144
	v_mul_f32_e32 v247, v247, v144
	v_mul_f32_e32 v248, v248, v144
	v_mul_f32_e32 v249, v249, v144
	v_mul_f32_e32 v250, v250, v144
	v_mul_f32_e32 v251, v251, v144
	ds_read_b128 v[252:255], v155
	s_add_i32 s44, s40, 56
	s_ashr_i32 s45, s44, 31
	s_lshl_b64 s[44:45], s[44:45], 12
	v_lshl_add_u64 v[80:81], v[36:37], 0, s[44:45]
	s_waitcnt lgkmcnt(0)
	v_mul_f32_e32 v236, v236, v252
	v_mul_f32_e32 v237, v237, v253
	v_mul_f32_e32 v238, v238, v254
	v_mul_f32_e32 v239, v239, v255
	global_store_dwordx4 v[80:81], v[236:239], off sc1
	ds_read_b128 v[252:255], v155 offset:1024
	s_add_i32 s44, s40, 56
	s_ashr_i32 s45, s44, 31
	s_lshl_b64 s[44:45], s[44:45], 12
	v_lshl_add_u64 v[80:81], v[36:37], 0, s[44:45]
	s_waitcnt lgkmcnt(0)
	v_mul_f32_e32 v240, v240, v252
	v_mul_f32_e32 v241, v241, v253
	v_mul_f32_e32 v242, v242, v254
	v_mul_f32_e32 v243, v243, v255
	global_store_dwordx4 v[80:81], v[240:243], off offset:1024 sc1
	ds_read_b128 v[252:255], v156
	s_add_i32 s44, s40, 56
	s_ashr_i32 s45, s44, 31
	s_lshl_b64 s[44:45], s[44:45], 12
	v_lshl_add_u64 v[80:81], v[36:37], 0, s[44:45]
	s_waitcnt lgkmcnt(0)
	v_mul_f32_e32 v244, v244, v252
	v_mul_f32_e32 v245, v245, v253
	v_mul_f32_e32 v246, v246, v254
	v_mul_f32_e32 v247, v247, v255
	global_store_dwordx4 v[80:81], v[244:247], off offset:2048 sc1
	ds_read_b128 v[252:255], v156 offset:1024
	s_add_i32 s44, s40, 56
	s_ashr_i32 s45, s44, 31
	s_lshl_b64 s[44:45], s[44:45], 12
	v_lshl_add_u64 v[80:81], v[36:37], 0, s[44:45]
	s_waitcnt lgkmcnt(0)
	v_mul_f32_e32 v248, v248, v252
	v_mul_f32_e32 v249, v249, v253
	v_mul_f32_e32 v250, v250, v254
	v_mul_f32_e32 v251, v251, v255
	global_store_dwordx4 v[80:81], v[248:251], off offset:3072 sc1
	s_add_i32 s2, s2, s33
	s_add_i32 s40, s40, s63
	s_add_i32 s73, s73, s74
	s_cmpk_lt_i32 s2, 0x100
	s_cbranch_scc1 .LBB0_648
